# v10 + background weight-conversion items de-serialised: 8 row-group loads issued together into phase-dead registers, one wait, then the LDS writes
# speedup vs baseline: 1.0049x; 1.0029x over previous
; #define LAS __attribute__((address_space(3)))
; __device__ __forceinline__ void atomic_addq(i64* p, float v, float scale) { (void)__hip_atomic_fetch_add((unsigned long long*)p, (unsigned long long)(i64)__builtin_rintf(v * scale), __ATOMIC_RELAXED, __HIP_MEMORY_SCOPE_AGENT); }
; template <class Map>
; __device__ __forceinline__ void conv_item(const Frame& F, int it, const float* W, int K, int N, bf16_t* WT, const float* gk, int gmask, float gmul, const float* bk, i64* cs, i64* bw, Map map) {
;     ...
;         const int kb = it / nblk, nb = it % nblk, k0 = 64 * kb, n0 = 32 * nb, v0 = map(n0);
; #pragma unroll
;         for (int i = 0; i < 8; ++i) { const int kk = 8 * i + (lane >> 3), c4 = (lane & 7) * 4;
;             const f32x4 w4 = __builtin_nontemporal_load((const f32x4*)(W + (size_t)(k0 + kk) * N + n0 + c4)); LAS float* d = scr + kk * 33 + c4; d[0] = w4[0]; d[1] = w4[1]; d[2] = w4[2]; d[3] = w4[3]; }
;         LDS_WAIT(); asm volatile("" ::: "memory");
;         if (bk) {
;             const int n = lane & 31, kh = lane >> 5; float sb = 0.f, sc = 0.f;
; #pragma unroll 8
;             for (int j = 0; j < 32; ++j) { const int kk = kh * 32 + j; const float w = scr[kk * 33 + n]; sb += bk[k0 + kk] * w; sc += bf_round(gk[(k0 + kk) & gmask] * gmul * w); }
;             { auto r = __builtin_amdgcn_permlane32_swap(__float_as_uint(sb), __float_as_uint(sb), false, false); sb = __uint_as_float(r[0]) + __uint_as_float(r[1]); }
;             { auto r = __builtin_amdgcn_permlane32_swap(__float_as_uint(sc), __float_as_uint(sc), false, false); sc = __uint_as_float(r[0]) + __uint_as_float(r[1]); }
;             if (lane < 32) { atomic_addq(bw + v0 + n, sb, FX_COL); atomic_addq(cs + v0 + n, sc, FX_COL); }
;         }
;         const int c = lane & 7; float gl[8];
; #pragma unroll
;         for (int i = 0; i < 8; ++i) gl[i] = gk ? gk[(k0 + 8 * c + i) & gmask] * gmul : 1.0f;
; #pragma unroll
;         for (int j = 0; j < 4; ++j) { const int n = (lane >> 3) + 8 * j; const LAS float* s = scr + (8 * c) * 33 + n;
;             u32x4 o; o.x = pk2(s[0 * 33] * gl[0], s[1 * 33] * gl[1]); o.y = pk2(s[2 * 33] * gl[2], s[3 * 33] * gl[3]); o.z = pk2(s[4 * 33] * gl[4], s[5 * 33] * gl[5]); o.w = pk2(s[6 * 33] * gl[6], s[7 * 33] * gl[7]);
;             __builtin_nontemporal_store(o, (u32x4*)(WT + (size_t)(v0 + n) * K + k0 + 8 * c)); }
.LBB0_237:
	v_readlane_b32 s6, v252, 14
	v_readlane_b32 s7, v252, 15
	s_load_dwordx2 s[6:7], s[6:7], 0x10
	v_mov_b32_e32 v13, v220
	v_mov_b32_e32 v1, v185
	s_waitcnt lgkmcnt(0)
	s_add_u32 s24, s6, s83
	s_addc_u32 s25, s7, s82
	s_and_b32 s12, s91, 0xffff
	s_mul_i32 s13, s12, 0xf0f1
	s_lshr_b32 s12, s13, 21
	s_mul_i32 s12, s12, 34
	s_sub_i32 s12, s91, s12
	s_lshl_b32 s16, s12, 5
	v_readlane_b32 s6, v252, 12
	s_lshr_b32 s13, s13, 15
	s_and_b32 s16, s16, 0xffe0
	v_readlane_b32 s7, v252, 13
	s_and_b32 s13, s13, 0xffc0
	s_add_i32 s17, s16, 0x60
	s_lshl_b32 s26, s16, 2
	s_add_u32 s24, s24, s26
	v_bfe_u32 v5, v13, 3, 3
	v_lshlrev_b32_e32 v0, 4, v13
	s_addc_u32 s25, s25, 0
	v_and_b32_e32 v184, 0x70, v0
	v_or_b32_e32 v14, s13, v5
	v_lshl_add_u64 v[10:11], s[24:25], 0, v[184:185]
	v_mul_u32_u24_e32 v0, 0x1100, v14
	v_lshl_add_u64 v[0:1], v[10:11], 0, v[0:1]
	global_load_dwordx4 v[132:135], v[0:1], off nt
	v_mul_u32_u24_e32 v4, 0x84, v5
	v_add3_u32 v15, s79, v184, v4
	v_or_b32_e32 v4, 8, v5
	v_add_u32_e32 v6, 0x420, v15
	s_and_b32 s12, s12, 0xffff
	s_cmp_lt_u32 s12, 33
	s_cselect_b32 s12, s16, s17
	v_or_b32_e32 v0, s13, v4
	v_mul_u32_u24_e32 v184, 0x1100, v0
	v_lshl_add_u64 v[0:1], v[10:11], 0, v[184:185]
	global_load_dwordx4 v[136:139], v[0:1], off nt
	v_or_b32_e32 v4, s12, v4
	v_add_u32_e32 v0, 0x428, v15
	v_or_b32_e32 v3, 16, v5
	v_or_b32_e32 v0, s13, v3
	v_mul_u32_u24_e32 v184, 0x1100, v0
	v_lshl_add_u64 v[0:1], v[10:11], 0, v[184:185]
	global_load_dwordx4 v[140:143], v[0:1], off nt
	v_add_u32_e32 v0, 0x840, v15
	v_or_b32_e32 v2, 24, v5
	v_or_b32_e32 v3, s12, v3
	v_add_u32_e32 v0, 0x848, v15
	v_or_b32_e32 v0, s13, v2
	v_mul_u32_u24_e32 v184, 0x1100, v0
	v_lshl_add_u64 v[0:1], v[10:11], 0, v[184:185]
	global_load_dwordx4 v[144:147], v[0:1], off nt
	v_add_u32_e32 v0, 0xc60, v15
	s_lshl_b32 s13, s13, 1
	s_add_u32 s6, s6, s13
	s_addc_u32 s7, s7, 0
	v_or_b32_e32 v2, s12, v2
	v_add_u32_e32 v0, 0xc68, v15
	v_or_b32_e32 v0, 32, v14
	v_mul_u32_u24_e32 v184, 0x1100, v0
	v_lshl_add_u64 v[0:1], v[10:11], 0, v[184:185]
	global_load_dwordx4 v[148:151], v[0:1], off nt
	v_add_u32_e32 v0, 0x1080, v15
	v_add_u32_e32 v0, 0x1088, v15
	v_or_b32_e32 v0, 40, v14
	v_mul_u32_u24_e32 v184, 0x1100, v0
	v_lshl_add_u64 v[0:1], v[10:11], 0, v[184:185]
	global_load_dwordx4 v[152:155], v[0:1], off nt
	v_add_u32_e32 v0, 0x14a0, v15
	v_add_u32_e32 v0, 0x14a8, v15
	v_or_b32_e32 v0, 48, v14
	v_mul_u32_u24_e32 v184, 0x1100, v0
	v_lshl_add_u64 v[0:1], v[10:11], 0, v[184:185]
	global_load_dwordx4 v[156:159], v[0:1], off nt
	v_add_u32_e32 v0, 0x18c0, v15
	v_add_u32_e32 v0, 0x18c8, v15
	v_or_b32_e32 v0, 56, v14
	v_mul_u32_u24_e32 v184, 0x1100, v0
	v_lshl_add_u64 v[0:1], v[10:11], 0, v[184:185]
	global_load_dwordx4 v[160:163], v[0:1], off nt
	v_add_u32_e32 v0, 0x1ce0, v15
	v_add_u32_e32 v0, 0x1ce8, v15
	s_waitcnt vmcnt(0)
	v_add_u32_e32 v164, 0x0, v15
	ds_write2_b32 v164, v132, v133 offset1:1
	ds_write2_b32 v164, v134, v135 offset0:2 offset1:3
	v_add_u32_e32 v164, 0x420, v15
	ds_write2_b32 v164, v136, v137 offset1:1
	ds_write2_b32 v164, v138, v139 offset0:2 offset1:3
	v_add_u32_e32 v164, 0x840, v15
	ds_write2_b32 v164, v140, v141 offset1:1
	ds_write2_b32 v164, v142, v143 offset0:2 offset1:3
	v_add_u32_e32 v164, 0xc60, v15
	ds_write2_b32 v164, v144, v145 offset1:1
	ds_write2_b32 v164, v146, v147 offset0:2 offset1:3
	v_add_u32_e32 v164, 0x1080, v15
	ds_write2_b32 v164, v148, v149 offset1:1
	ds_write2_b32 v164, v150, v151 offset0:2 offset1:3
	v_add_u32_e32 v164, 0x14a0, v15
	ds_write2_b32 v164, v152, v153 offset1:1
	ds_write2_b32 v164, v154, v155 offset0:2 offset1:3
	v_add_u32_e32 v164, 0x18c0, v15
	ds_write2_b32 v164, v156, v157 offset1:1
	ds_write2_b32 v164, v158, v159 offset0:2 offset1:3
	v_add_u32_e32 v164, 0x1ce0, v15
	ds_write2_b32 v164, v160, v161 offset1:1
	ds_write2_b32 v164, v162, v163 offset0:2 offset1:3
	v_lshlrev_b32_e32 v0, 3, v13
	v_and_b32_e32 v0, 56, v0
	s_waitcnt lgkmcnt(0)
	v_mul_u32_u24_e32 v6, 0x84, v0
	v_lshlrev_b32_e32 v7, 2, v5
	v_add3_u32 v6, s79, v6, v7
	ds_read_b32 v7, v6
	ds_read_b32 v8, v6 offset:132
	v_lshlrev_b32_e32 v184, 1, v0
	v_lshl_add_u64 v[0:1], s[6:7], 0, v[184:185]
	s_mov_b64 s[6:7], 0x800000
	s_waitcnt lgkmcnt(1)
	v_bfe_u32 v9, v7, 16, 1
	v_add3_u32 v7, v7, v9, s73
	s_waitcnt lgkmcnt(0)
; #define LAS __attribute__((address_space(3)))
; #define LDS_WAIT() asm volatile("s_waitcnt lgkmcnt(0)" ::: "memory")
; __device__ __forceinline__ unsigned pk2(float lo, float hi) { return f2bf(lo) | (f2bf(hi) << 16); }
; template <class Map>
; __device__ __forceinline__ void conv_item(const Frame& F, int it, const float* W, int K, int N, bf16_t* WT, const float* gk, int gmask, float gmul, const float* bk, i64* cs, i64* bw, Map map) {
;     ...
;         const int c = lane & 7; float gl[8];
; #pragma unroll
;         for (int i = 0; i < 8; ++i) gl[i] = gk ? gk[(k0 + 8 * c + i) & gmask] * gmul : 1.0f;
; #pragma unroll
;         for (int j = 0; j < 4; ++j) { const int n = (lane >> 3) + 8 * j; const LAS float* s = scr + (8 * c) * 33 + n;
;             u32x4 o; o.x = pk2(s[0 * 33] * gl[0], s[1 * 33] * gl[1]); o.y = pk2(s[2 * 33] * gl[2], s[3 * 33] * gl[3]); o.z = pk2(s[4 * 33] * gl[4], s[5 * 33] * gl[5]); o.w = pk2(s[6 * 33] * gl[6], s[7 * 33] * gl[7]);
;             __builtin_nontemporal_store(o, (u32x4*)(WT + (size_t)(v0 + n) * K + k0 + 8 * c)); }
;         LDS_WAIT(); asm volatile("" ::: "memory");
	v_bfe_u32 v9, v8, 16, 1
	v_lshrrev_b32_e32 v7, 16, v7
	v_add3_u32 v8, v8, v9, s73
	v_and_or_b32 v8, v8, s72, v7
	ds_read_b32 v7, v6 offset:264
	ds_read_b32 v9, v6 offset:396
	v_or_b32_e32 v5, s12, v5
	v_lshl_add_u64 v[0:1], v[0:1], 0, s[6:7]
	v_lshlrev_b32_e32 v184, 12, v5
	s_waitcnt lgkmcnt(1)
	v_bfe_u32 v10, v7, 16, 1
	v_add3_u32 v7, v7, v10, s73
	s_waitcnt lgkmcnt(0)
	v_bfe_u32 v10, v9, 16, 1
	v_lshrrev_b32_e32 v7, 16, v7
	v_add3_u32 v9, v9, v10, s73
	v_and_or_b32 v9, v9, s72, v7
	ds_read_b32 v7, v6 offset:528
	ds_read_b32 v10, v6 offset:660
	v_lshl_add_u64 v[14:15], v[0:1], 0, v[184:185]
	v_lshlrev_b32_e32 v184, 12, v4
	s_waitcnt lgkmcnt(1)
	v_bfe_u32 v11, v7, 16, 1
	v_add3_u32 v7, v7, v11, s73
	s_waitcnt lgkmcnt(0)
	v_bfe_u32 v11, v10, 16, 1
	v_lshrrev_b32_e32 v7, 16, v7
	v_add3_u32 v10, v10, v11, s73
	v_and_or_b32 v10, v10, s72, v7
	ds_read_b32 v7, v6 offset:792
	ds_read_b32 v11, v6 offset:924
	s_waitcnt lgkmcnt(1)
	v_bfe_u32 v13, v7, 16, 1
	v_add3_u32 v7, v7, v13, s73
	s_waitcnt lgkmcnt(0)
	v_bfe_u32 v13, v11, 16, 1
	v_lshrrev_b32_e32 v7, 16, v7
	v_add3_u32 v11, v11, v13, s73
	v_and_or_b32 v11, v11, s72, v7
	flat_store_dwordx4 v[14:15], v[8:11] nt
	ds_read_b32 v5, v6 offset:32
	ds_read_b32 v7, v6 offset:164
	s_waitcnt lgkmcnt(0)
	v_bfe_u32 v8, v5, 16, 1
	v_add3_u32 v5, v5, v8, s73
	v_bfe_u32 v8, v7, 16, 1
	v_lshrrev_b32_e32 v5, 16, v5
	v_add3_u32 v7, v7, v8, s73
	v_and_or_b32 v8, v7, s72, v5
	ds_read_b32 v5, v6 offset:296
	ds_read_b32 v7, v6 offset:428
	s_waitcnt lgkmcnt(0)
	v_bfe_u32 v9, v5, 16, 1
	v_add3_u32 v5, v5, v9, s73
	v_bfe_u32 v9, v7, 16, 1
	v_lshrrev_b32_e32 v5, 16, v5
	v_add3_u32 v7, v7, v9, s73
	v_and_or_b32 v9, v7, s72, v5
	ds_read_b32 v5, v6 offset:560
	ds_read_b32 v7, v6 offset:692
	s_waitcnt lgkmcnt(0)
	v_bfe_u32 v10, v5, 16, 1
	v_add3_u32 v5, v5, v10, s73
	v_bfe_u32 v10, v7, 16, 1
	v_lshrrev_b32_e32 v5, 16, v5
	v_add3_u32 v7, v7, v10, s73
	v_and_or_b32 v10, v7, s72, v5
	ds_read_b32 v5, v6 offset:824
	ds_read_b32 v7, v6 offset:956
	s_waitcnt lgkmcnt(0)
	v_bfe_u32 v11, v5, 16, 1
	v_add3_u32 v5, v5, v11, s73
	v_bfe_u32 v11, v7, 16, 1
	v_lshrrev_b32_e32 v5, 16, v5
	v_add3_u32 v7, v7, v11, s73
	v_and_or_b32 v11, v7, s72, v5
	v_lshl_add_u64 v[4:5], v[0:1], 0, v[184:185]
	flat_store_dwordx4 v[4:5], v[8:11] nt
	ds_read_b32 v4, v6 offset:64
	ds_read_b32 v5, v6 offset:196
	v_lshlrev_b32_e32 v184, 12, v3
	s_waitcnt lgkmcnt(0)
	v_bfe_u32 v7, v4, 16, 1
	v_add3_u32 v4, v4, v7, s73
	v_bfe_u32 v7, v5, 16, 1
	v_lshrrev_b32_e32 v4, 16, v4
	v_add3_u32 v5, v5, v7, s73
	v_and_or_b32 v8, v5, s72, v4
	ds_read_b32 v4, v6 offset:328
	ds_read_b32 v5, v6 offset:460
	s_waitcnt lgkmcnt(0)
	v_bfe_u32 v7, v4, 16, 1
	v_add3_u32 v4, v4, v7, s73
	v_bfe_u32 v7, v5, 16, 1
	v_lshrrev_b32_e32 v4, 16, v4
	v_add3_u32 v5, v5, v7, s73
	v_and_or_b32 v9, v5, s72, v4
	ds_read_b32 v4, v6 offset:592
	ds_read_b32 v5, v6 offset:724
	s_waitcnt lgkmcnt(0)
	v_bfe_u32 v7, v4, 16, 1
	v_add3_u32 v4, v4, v7, s73
	v_bfe_u32 v7, v5, 16, 1
	v_lshrrev_b32_e32 v4, 16, v4
	v_add3_u32 v5, v5, v7, s73
	v_and_or_b32 v10, v5, s72, v4
	ds_read_b32 v4, v6 offset:856
	ds_read_b32 v5, v6 offset:988
	s_waitcnt lgkmcnt(0)
	v_bfe_u32 v7, v4, 16, 1
	v_add3_u32 v4, v4, v7, s73
	v_bfe_u32 v7, v5, 16, 1
	v_lshrrev_b32_e32 v4, 16, v4
	v_add3_u32 v5, v5, v7, s73
	v_and_or_b32 v11, v5, s72, v4
	v_lshl_add_u64 v[4:5], v[0:1], 0, v[184:185]
	flat_store_dwordx4 v[4:5], v[8:11] nt
	ds_read_b32 v3, v6 offset:96
	ds_read_b32 v4, v6 offset:228
	v_lshlrev_b32_e32 v184, 12, v2
	v_lshl_add_u64 v[0:1], v[0:1], 0, v[184:185]
	s_waitcnt lgkmcnt(0)
	v_bfe_u32 v5, v3, 16, 1
	v_add3_u32 v3, v3, v5, s73
	v_bfe_u32 v5, v4, 16, 1
	v_lshrrev_b32_e32 v3, 16, v3
	v_add3_u32 v4, v4, v5, s73
	v_and_or_b32 v8, v4, s72, v3
	ds_read_b32 v3, v6 offset:360
	ds_read_b32 v4, v6 offset:492
	s_waitcnt lgkmcnt(0)
	v_bfe_u32 v5, v3, 16, 1
	v_add3_u32 v3, v3, v5, s73
	v_bfe_u32 v5, v4, 16, 1
	v_lshrrev_b32_e32 v3, 16, v3
	v_add3_u32 v4, v4, v5, s73
	v_and_or_b32 v9, v4, s72, v3
	ds_read_b32 v3, v6 offset:624
	ds_read_b32 v4, v6 offset:756
	s_waitcnt lgkmcnt(0)
	v_bfe_u32 v5, v3, 16, 1
	v_add3_u32 v3, v3, v5, s73
	v_bfe_u32 v5, v4, 16, 1
	v_lshrrev_b32_e32 v3, 16, v3
	v_add3_u32 v4, v4, v5, s73
	v_and_or_b32 v10, v4, s72, v3
	ds_read_b32 v3, v6 offset:888
	ds_read_b32 v4, v6 offset:1020
	s_waitcnt lgkmcnt(0)
	v_bfe_u32 v5, v3, 16, 1
	v_add3_u32 v3, v3, v5, s73
	v_bfe_u32 v5, v4, 16, 1
	v_lshrrev_b32_e32 v3, 16, v3
	v_add3_u32 v4, v4, v5, s73
	v_and_or_b32 v11, v4, s72, v3
	flat_store_dwordx4 v[0:1], v[8:11] nt
	s_waitcnt lgkmcnt(0)

; #define LAS __attribute__((address_space(3)))
; __device__ __forceinline__ void atomic_addq(i64* p, float v, float scale) { (void)__hip_atomic_fetch_add((unsigned long long*)p, (unsigned long long)(i64)__builtin_rintf(v * scale), __ATOMIC_RELAXED, __HIP_MEMORY_SCOPE_AGENT); }
; template <class Map>
; __device__ __forceinline__ void conv_item(const Frame& F, int it, const float* W, int K, int N, bf16_t* WT, const float* gk, int gmask, float gmul, const float* bk, i64* cs, i64* bw, Map map) {
;     ...
;         const int kb = it / nblk, nb = it % nblk, k0 = 64 * kb, n0 = 32 * nb, v0 = map(n0);
; #pragma unroll
;         for (int i = 0; i < 8; ++i) { const int kk = 8 * i + (lane >> 3), c4 = (lane & 7) * 4;
;             const f32x4 w4 = __builtin_nontemporal_load((const f32x4*)(W + (size_t)(k0 + kk) * N + n0 + c4)); LAS float* d = scr + kk * 33 + c4; d[0] = w4[0]; d[1] = w4[1]; d[2] = w4[2]; d[3] = w4[3]; }
;         LDS_WAIT(); asm volatile("" ::: "memory");
;         if (bk) {
;             const int n = lane & 31, kh = lane >> 5; float sb = 0.f, sc = 0.f;
; #pragma unroll 8
;             for (int j = 0; j < 32; ++j) { const int kk = kh * 32 + j; const float w = scr[kk * 33 + n]; sb += bk[k0 + kk] * w; sc += bf_round(gk[(k0 + kk) & gmask] * gmul * w); }
;             { auto r = __builtin_amdgcn_permlane32_swap(__float_as_uint(sb), __float_as_uint(sb), false, false); sb = __uint_as_float(r[0]) + __uint_as_float(r[1]); }
;             { auto r = __builtin_amdgcn_permlane32_swap(__float_as_uint(sc), __float_as_uint(sc), false, false); sc = __uint_as_float(r[0]) + __uint_as_float(r[1]); }
;             if (lane < 32) { atomic_addq(bw + v0 + n, sb, FX_COL); atomic_addq(cs + v0 + n, sc, FX_COL); }
;         }
;         const int c = lane & 7; float gl[8];
; #pragma unroll
;         for (int i = 0; i < 8; ++i) gl[i] = gk ? gk[(k0 + 8 * c + i) & gmask] * gmul : 1.0f;
; #pragma unroll
;         for (int j = 0; j < 4; ++j) { const int n = (lane >> 3) + 8 * j; const LAS float* s = scr + (8 * c) * 33 + n;
;             u32x4 o; o.x = pk2(s[0 * 33] * gl[0], s[1 * 33] * gl[1]); o.y = pk2(s[2 * 33] * gl[2], s[3 * 33] * gl[3]); o.z = pk2(s[4 * 33] * gl[4], s[5 * 33] * gl[5]); o.w = pk2(s[6 * 33] * gl[6], s[7 * 33] * gl[7]);
;             __builtin_nontemporal_store(o, (u32x4*)(WT + (size_t)(v0 + n) * K + k0 + 8 * c)); }
.LBB0_251:
	s_andn2_b64 vcc, exec, s[6:7]
	s_cbranch_vccnz .LBB0_253
	v_readlane_b32 s6, v252, 14
	v_readlane_b32 s7, v252, 15
	s_load_dwordx2 s[6:7], s[6:7], 0x90
	v_mov_b32_e32 v7, v220
	v_mov_b32_e32 v5, v185
	s_waitcnt lgkmcnt(0)
	s_add_u32 s17, s6, s46
	s_addc_u32 s25, s7, s47
	s_lshl_b32 s12, s16, 5
	v_readlane_b32 s6, v252, 12
	s_and_b32 s12, s12, 0x7e0
	v_readlane_b32 s7, v252, 13
	s_and_b32 s13, s16, 0xc0
	s_lshl_b32 s24, s12, 2
	s_add_u32 s24, s17, s24
	v_bfe_u32 v6, v7, 3, 3
	v_lshlrev_b32_e32 v0, 4, v7
	s_addc_u32 s25, s25, 0
	v_and_b32_e32 v184, 0x70, v0
	v_or_b32_e32 v0, s13, v6
	v_lshl_add_u64 v[14:15], s[24:25], 0, v[184:185]
	v_lshlrev_b32_e32 v4, 13, v0
	v_lshl_add_u64 v[0:1], v[14:15], 0, v[4:5]
	global_load_dwordx4 v[132:135], v[0:1], off nt
	v_mul_u32_u24_e32 v5, 0x84, v6
	v_add3_u32 v13, s79, v184, v5
	v_or_b32_e32 v5, 8, v6
	v_add_u32_e32 v8, 0x420, v13
	v_or_b32_e32 v0, s13, v5
	v_lshlrev_b32_e32 v184, 13, v0
	v_lshl_add_u64 v[0:1], v[14:15], 0, v[184:185]
	global_load_dwordx4 v[136:139], v[0:1], off nt
	v_or_b32_e32 v5, s12, v5
	v_add_u32_e32 v0, 0x428, v13
	v_or_b32_e32 v3, 16, v6
	v_or_b32_e32 v0, s13, v3
	v_lshlrev_b32_e32 v184, 13, v0
	v_lshl_add_u64 v[0:1], v[14:15], 0, v[184:185]
	global_load_dwordx4 v[140:143], v[0:1], off nt
	v_add_u32_e32 v0, 0x840, v13
	v_or_b32_e32 v2, 24, v6
	v_or_b32_e32 v3, s12, v3
	v_add_u32_e32 v0, 0x848, v13
	v_or_b32_e32 v0, s13, v2
	v_lshlrev_b32_e32 v184, 13, v0
	v_lshl_add_u64 v[0:1], v[14:15], 0, v[184:185]
	global_load_dwordx4 v[144:147], v[0:1], off nt
	v_add_u32_e32 v0, 0xc60, v13
	v_or_b32_e32 v184, 0x40000, v4
	s_lshl_b32 s13, s13, 1
	s_add_u32 s6, s6, s13
	s_addc_u32 s7, s7, 0
	v_or_b32_e32 v2, s12, v2
	v_add_u32_e32 v0, 0xc68, v13
	v_lshl_add_u64 v[0:1], v[14:15], 0, v[184:185]
	global_load_dwordx4 v[148:151], v[0:1], off nt
	v_add_u32_e32 v0, 0x1080, v13
	v_or_b32_e32 v184, 0x50000, v4
	v_add_u32_e32 v0, 0x1088, v13
	v_lshl_add_u64 v[0:1], v[14:15], 0, v[184:185]
	global_load_dwordx4 v[152:155], v[0:1], off nt
	v_add_u32_e32 v0, 0x14a0, v13
	v_or_b32_e32 v184, 0x60000, v4
	v_add_u32_e32 v0, 0x14a8, v13
	v_lshl_add_u64 v[0:1], v[14:15], 0, v[184:185]
	global_load_dwordx4 v[156:159], v[0:1], off nt
	v_add_u32_e32 v0, 0x18c0, v13
	v_or_b32_e32 v184, 0x70000, v4
	v_add_u32_e32 v0, 0x18c8, v13
	v_lshl_add_u64 v[0:1], v[14:15], 0, v[184:185]
	global_load_dwordx4 v[160:163], v[0:1], off nt
	v_add_u32_e32 v0, 0x1ce0, v13
	v_add_u32_e32 v0, 0x1ce8, v13
	s_waitcnt vmcnt(0)
	v_add_u32_e32 v164, 0x0, v13
	ds_write2_b32 v164, v132, v133 offset1:1
	ds_write2_b32 v164, v134, v135 offset0:2 offset1:3
	v_add_u32_e32 v164, 0x420, v13
	ds_write2_b32 v164, v136, v137 offset1:1
	ds_write2_b32 v164, v138, v139 offset0:2 offset1:3
	v_add_u32_e32 v164, 0x840, v13
	ds_write2_b32 v164, v140, v141 offset1:1
	ds_write2_b32 v164, v142, v143 offset0:2 offset1:3
	v_add_u32_e32 v164, 0xc60, v13
	ds_write2_b32 v164, v144, v145 offset1:1
	ds_write2_b32 v164, v146, v147 offset0:2 offset1:3
	v_add_u32_e32 v164, 0x1080, v13
	ds_write2_b32 v164, v148, v149 offset1:1
	ds_write2_b32 v164, v150, v151 offset0:2 offset1:3
	v_add_u32_e32 v164, 0x14a0, v13
	ds_write2_b32 v164, v152, v153 offset1:1
	ds_write2_b32 v164, v154, v155 offset0:2 offset1:3
	v_add_u32_e32 v164, 0x18c0, v13
	ds_write2_b32 v164, v156, v157 offset1:1
	ds_write2_b32 v164, v158, v159 offset0:2 offset1:3
	v_add_u32_e32 v164, 0x1ce0, v13
	ds_write2_b32 v164, v160, v161 offset1:1
	ds_write2_b32 v164, v162, v163 offset0:2 offset1:3
	v_and_b32_e32 v0, 7, v7
	s_waitcnt lgkmcnt(0)
	v_mul_u32_u24_e32 v4, 0x420, v0
	v_lshlrev_b32_e32 v7, 2, v6
	v_add3_u32 v4, s79, v4, v7
	ds_read_b32 v7, v4
	ds_read_b32 v8, v4 offset:132
	v_lshlrev_b32_e32 v184, 4, v0
	v_lshl_add_u64 v[0:1], s[6:7], 0, v[184:185]
	s_mov_b64 s[6:7], 0x7a00000
	s_waitcnt lgkmcnt(1)
	v_bfe_u32 v9, v7, 16, 1
	v_add3_u32 v7, v7, v9, s73
	s_waitcnt lgkmcnt(0)
	v_bfe_u32 v9, v8, 16, 1
	v_lshrrev_b32_e32 v7, 16, v7
	v_add3_u32 v8, v8, v9, s73
	v_and_or_b32 v8, v8, s72, v7
	ds_read_b32 v7, v4 offset:264
	ds_read_b32 v9, v4 offset:396
	v_or_b32_e32 v6, s12, v6
	v_lshl_add_u64 v[0:1], v[0:1], 0, s[6:7]
	v_lshlrev_b32_e32 v184, 9, v6
	s_waitcnt lgkmcnt(1)
; #define LAS __attribute__((address_space(3)))
; #define LDS_WAIT() asm volatile("s_waitcnt lgkmcnt(0)" ::: "memory")
; __device__ __forceinline__ unsigned pk2(float lo, float hi) { return f2bf(lo) | (f2bf(hi) << 16); }
; template <class Map>
; __device__ __forceinline__ void conv_item(const Frame& F, int it, const float* W, int K, int N, bf16_t* WT, const float* gk, int gmask, float gmul, const float* bk, i64* cs, i64* bw, Map map) {
;     ...
;         const int c = lane & 7; float gl[8];
; #pragma unroll
;         for (int i = 0; i < 8; ++i) gl[i] = gk ? gk[(k0 + 8 * c + i) & gmask] * gmul : 1.0f;
; #pragma unroll
;         for (int j = 0; j < 4; ++j) { const int n = (lane >> 3) + 8 * j; const LAS float* s = scr + (8 * c) * 33 + n;
;             u32x4 o; o.x = pk2(s[0 * 33] * gl[0], s[1 * 33] * gl[1]); o.y = pk2(s[2 * 33] * gl[2], s[3 * 33] * gl[3]); o.z = pk2(s[4 * 33] * gl[4], s[5 * 33] * gl[5]); o.w = pk2(s[6 * 33] * gl[6], s[7 * 33] * gl[7]);
;             __builtin_nontemporal_store(o, (u32x4*)(WT + (size_t)(v0 + n) * K + k0 + 8 * c)); }
;         LDS_WAIT(); asm volatile("" ::: "memory");
	v_bfe_u32 v10, v7, 16, 1
	v_add3_u32 v7, v7, v10, s73
	s_waitcnt lgkmcnt(0)
	v_bfe_u32 v10, v9, 16, 1
	v_lshrrev_b32_e32 v7, 16, v7
	v_add3_u32 v9, v9, v10, s73
	v_and_or_b32 v9, v9, s72, v7
	ds_read_b32 v7, v4 offset:528
	ds_read_b32 v10, v4 offset:660
	s_waitcnt lgkmcnt(1)
	v_bfe_u32 v11, v7, 16, 1
	v_add3_u32 v7, v7, v11, s73
	s_waitcnt lgkmcnt(0)
	v_bfe_u32 v11, v10, 16, 1
	v_lshrrev_b32_e32 v7, 16, v7
	v_add3_u32 v10, v10, v11, s73
	v_and_or_b32 v10, v10, s72, v7
	ds_read_b32 v7, v4 offset:792
	ds_read_b32 v11, v4 offset:924
	s_waitcnt lgkmcnt(1)
	v_bfe_u32 v13, v7, 16, 1
	v_add3_u32 v7, v7, v13, s73
	s_waitcnt lgkmcnt(0)
	v_bfe_u32 v13, v11, 16, 1
	v_lshrrev_b32_e32 v7, 16, v7
	v_add3_u32 v11, v11, v13, s73
	v_and_or_b32 v11, v11, s72, v7
	v_lshl_add_u64 v[6:7], v[0:1], 0, v[184:185]
	flat_store_dwordx4 v[6:7], v[8:11] nt
	ds_read_b32 v6, v4 offset:32
	ds_read_b32 v7, v4 offset:164
	v_lshlrev_b32_e32 v184, 9, v5
	s_waitcnt lgkmcnt(0)
	v_bfe_u32 v8, v6, 16, 1
	v_add3_u32 v6, v6, v8, s73
	v_bfe_u32 v8, v7, 16, 1
	v_lshrrev_b32_e32 v6, 16, v6
	v_add3_u32 v7, v7, v8, s73
	v_and_or_b32 v6, v7, s72, v6
	ds_read_b32 v7, v4 offset:296
	ds_read_b32 v8, v4 offset:428
	s_waitcnt lgkmcnt(0)
	v_bfe_u32 v9, v7, 16, 1
	v_add3_u32 v7, v7, v9, s73
	v_bfe_u32 v9, v8, 16, 1
	v_lshrrev_b32_e32 v7, 16, v7
	v_add3_u32 v8, v8, v9, s73
	v_and_or_b32 v7, v8, s72, v7
	ds_read_b32 v8, v4 offset:560
	ds_read_b32 v9, v4 offset:692
	s_waitcnt lgkmcnt(0)
	v_bfe_u32 v10, v8, 16, 1
	v_add3_u32 v8, v8, v10, s73
	v_bfe_u32 v10, v9, 16, 1
	v_lshrrev_b32_e32 v8, 16, v8
	v_add3_u32 v9, v9, v10, s73
	v_and_or_b32 v8, v9, s72, v8
	ds_read_b32 v9, v4 offset:824
	ds_read_b32 v10, v4 offset:956
	s_waitcnt lgkmcnt(0)
	v_bfe_u32 v11, v9, 16, 1
	v_add3_u32 v9, v9, v11, s73
	v_bfe_u32 v11, v10, 16, 1
	v_lshrrev_b32_e32 v9, 16, v9
	v_add3_u32 v10, v10, v11, s73
	v_and_or_b32 v9, v10, s72, v9
	v_lshl_add_u64 v[10:11], v[0:1], 0, v[184:185]
	flat_store_dwordx4 v[10:11], v[6:9] nt
	ds_read_b32 v5, v4 offset:64
	ds_read_b32 v6, v4 offset:196
	v_lshlrev_b32_e32 v184, 9, v3
	s_waitcnt lgkmcnt(0)
	v_bfe_u32 v7, v5, 16, 1
	v_add3_u32 v5, v5, v7, s73
	v_bfe_u32 v7, v6, 16, 1
	v_lshrrev_b32_e32 v5, 16, v5
	v_add3_u32 v6, v6, v7, s73
	v_and_or_b32 v6, v6, s72, v5
	ds_read_b32 v5, v4 offset:328
	ds_read_b32 v7, v4 offset:460
	s_waitcnt lgkmcnt(0)
	v_bfe_u32 v8, v5, 16, 1
	v_add3_u32 v5, v5, v8, s73
	v_bfe_u32 v8, v7, 16, 1
	v_lshrrev_b32_e32 v5, 16, v5
	v_add3_u32 v7, v7, v8, s73
	v_and_or_b32 v7, v7, s72, v5
	ds_read_b32 v5, v4 offset:592
	ds_read_b32 v8, v4 offset:724
	s_waitcnt lgkmcnt(0)
	v_bfe_u32 v9, v5, 16, 1
	v_add3_u32 v5, v5, v9, s73
	v_bfe_u32 v9, v8, 16, 1
	v_lshrrev_b32_e32 v5, 16, v5
	v_add3_u32 v8, v8, v9, s73
	v_and_or_b32 v8, v8, s72, v5
	ds_read_b32 v5, v4 offset:856
	ds_read_b32 v9, v4 offset:988
	s_waitcnt lgkmcnt(0)
	v_bfe_u32 v10, v5, 16, 1
	v_add3_u32 v5, v5, v10, s73
	v_bfe_u32 v10, v9, 16, 1
	v_lshrrev_b32_e32 v5, 16, v5
	v_add3_u32 v9, v9, v10, s73
	v_and_or_b32 v9, v9, s72, v5
	v_lshl_add_u64 v[10:11], v[0:1], 0, v[184:185]
	flat_store_dwordx4 v[10:11], v[6:9] nt
	ds_read_b32 v3, v4 offset:96
	ds_read_b32 v5, v4 offset:228
	v_lshlrev_b32_e32 v184, 9, v2
	v_lshl_add_u64 v[0:1], v[0:1], 0, v[184:185]
	s_waitcnt lgkmcnt(0)
	v_bfe_u32 v6, v3, 16, 1
	v_add3_u32 v3, v3, v6, s73
	v_bfe_u32 v6, v5, 16, 1
	v_lshrrev_b32_e32 v3, 16, v3
	v_add3_u32 v5, v5, v6, s73
	v_and_or_b32 v6, v5, s72, v3
	ds_read_b32 v3, v4 offset:360
	ds_read_b32 v5, v4 offset:492
	s_waitcnt lgkmcnt(0)
	v_bfe_u32 v7, v3, 16, 1
	v_add3_u32 v3, v3, v7, s73
	v_bfe_u32 v7, v5, 16, 1
	v_lshrrev_b32_e32 v3, 16, v3
	v_add3_u32 v5, v5, v7, s73
	v_and_or_b32 v7, v5, s72, v3
	ds_read_b32 v3, v4 offset:624
	ds_read_b32 v5, v4 offset:756
	s_waitcnt lgkmcnt(0)
	v_bfe_u32 v8, v3, 16, 1
	v_add3_u32 v3, v3, v8, s73
	v_bfe_u32 v8, v5, 16, 1
	v_lshrrev_b32_e32 v3, 16, v3
	v_add3_u32 v5, v5, v8, s73
	v_and_or_b32 v8, v5, s72, v3
	ds_read_b32 v3, v4 offset:888
	ds_read_b32 v4, v4 offset:1020
	s_waitcnt lgkmcnt(0)
	v_bfe_u32 v5, v3, 16, 1
	v_add3_u32 v3, v3, v5, s73
	v_bfe_u32 v5, v4, 16, 1
	v_lshrrev_b32_e32 v3, 16, v3
	v_add3_u32 v4, v4, v5, s73
	v_and_or_b32 v9, v4, s72, v3
	flat_store_dwordx4 v[0:1], v[6:9] nt
	s_waitcnt lgkmcnt(0)

; #define LAS __attribute__((address_space(3)))
; __device__ __forceinline__ void atomic_addq(i64* p, float v, float scale) { (void)__hip_atomic_fetch_add((unsigned long long*)p, (unsigned long long)(i64)__builtin_rintf(v * scale), __ATOMIC_RELAXED, __HIP_MEMORY_SCOPE_AGENT); }
; #define LDS_WAIT() asm volatile("s_waitcnt lgkmcnt(0)" ::: "memory")
; __device__ __forceinline__ float bf_round(float f) { return __uint_as_float(f2bf(f) << 16); }
; template <class Map>
; __device__ __forceinline__ void conv_item(const Frame& F, int it, const float* W, int K, int N, bf16_t* WT, const float* gk, int gmask, float gmul, const float* bk, i64* cs, i64* bw, Map map) {
;     ...
;         const int kb = it / nblk, nb = it % nblk, k0 = 64 * kb, n0 = 32 * nb, v0 = map(n0);
; #pragma unroll
;         for (int i = 0; i < 8; ++i) { const int kk = 8 * i + (lane >> 3), c4 = (lane & 7) * 4;
;             const f32x4 w4 = __builtin_nontemporal_load((const f32x4*)(W + (size_t)(k0 + kk) * N + n0 + c4)); LAS float* d = scr + kk * 33 + c4; d[0] = w4[0]; d[1] = w4[1]; d[2] = w4[2]; d[3] = w4[3]; }
;         LDS_WAIT(); asm volatile("" ::: "memory");
;         if (bk) {
;             const int n = lane & 31, kh = lane >> 5; float sb = 0.f, sc = 0.f;
; #pragma unroll 8
;             for (int j = 0; j < 32; ++j) { const int kk = kh * 32 + j; const float w = scr[kk * 33 + n]; sb += bk[k0 + kk] * w; sc += bf_round(gk[(k0 + kk) & gmask] * gmul * w); }
;             { auto r = __builtin_amdgcn_permlane32_swap(__float_as_uint(sb), __float_as_uint(sb), false, false); sb = __uint_as_float(r[0]) + __uint_as_float(r[1]); }
;             { auto r = __builtin_amdgcn_permlane32_swap(__float_as_uint(sc), __float_as_uint(sc), false, false); sc = __uint_as_float(r[0]) + __uint_as_float(r[1]); }
;             if (lane < 32) { atomic_addq(bw + v0 + n, sb, FX_COL); atomic_addq(cs + v0 + n, sc, FX_COL); }
.LBB0_254:
	s_andn2_b64 vcc, exec, s[6:7]
	s_cbranch_vccnz .LBB0_260
	v_readlane_b32 s26, v252, 14
	v_readlane_b32 s27, v252, 15
	s_mov_b64 s[6:7], s[26:27]
	s_load_dwordx2 s[6:7], s[6:7], 0x88
	s_add_i32 s78, s91, 0xaac0
	v_readlane_b32 s40, v252, 12
	v_readlane_b32 s41, v252, 13
	s_mov_b64 s[12:13], s[26:27]
	s_waitcnt lgkmcnt(0)
	s_add_u32 s79, s6, s54
	s_addc_u32 s93, s7, s55
	s_mov_b64 s[6:7], s[40:41]
	s_load_dwordx2 s[48:49], s[12:13], 0x68
	s_lshl_b64 s[12:13], s[56:57], 2
	v_mov_b32_e32 v15, v220
	v_mov_b32_e32 v7, v185
	s_waitcnt lgkmcnt(0)
	s_add_u32 s12, s48, s12
	s_addc_u32 s13, s49, s13
	s_add_u32 s24, s12, 0x2000
	s_addc_u32 s25, s13, 0
	s_lshl_b32 s17, s16, 5
	s_mov_b64 s[12:13], s[26:27]
	s_and_b32 s17, s17, 0x7e0
	s_mov_b64 s[26:27], s[40:41]
	s_and_b32 s52, s78, 0xffc0
	s_lshl_b32 s92, s17, 2
	s_load_dwordx2 s[12:13], s[12:13], 0x70
	s_add_u32 s92, s79, s92
	v_bfe_u32 v11, v15, 3, 3
	v_lshlrev_b32_e32 v0, 4, v15
	s_addc_u32 s93, s93, 0
	v_and_b32_e32 v184, 0x70, v0
	v_or_b32_e32 v0, s52, v11
	v_lshl_add_u64 v[4:5], s[92:93], 0, v[184:185]
	v_lshlrev_b32_e32 v6, 13, v0
	v_lshl_add_u64 v[0:1], v[4:5], 0, v[6:7]
	global_load_dwordx4 v[132:135], v[0:1], off nt
	v_readlane_b32 s79, v255, 17
	v_mul_u32_u24_e32 v7, 0x84, v11
	v_or_b32_e32 v10, 8, v11
	v_add3_u32 v7, s79, v184, v7
	v_add_u32_e32 v8, 0x420, v7
	v_or_b32_e32 v14, 16, v11
	v_or_b32_e32 v13, 24, v11
	v_readlane_b32 s92, v255, 25
	v_readlane_b32 s93, v255, 26
	s_add_u32 s48, s48, s92
	s_addc_u32 s49, s49, s93
	s_and_b32 s78, s78, 0x7c0
	v_and_b32_e32 v17, 31, v15
	s_waitcnt lgkmcnt(0)
	s_add_u32 s12, s12, s92
	v_and_or_b32 v18, v15, 32, s52
	s_addc_u32 s13, s13, s93
	v_and_b32_e32 v16, 63, v15
	s_mov_b64 s[92:93], 0x2000
	v_or_b32_e32 v0, s52, v10
	v_lshlrev_b32_e32 v184, 13, v0
	v_lshl_add_u64 v[0:1], v[4:5], 0, v[184:185]
	global_load_dwordx4 v[136:139], v[0:1], off nt
	v_add_u32_e32 v0, 0x428, v7
	v_or_b32_e32 v0, s52, v14
	v_lshlrev_b32_e32 v184, 13, v0
	v_lshl_add_u64 v[0:1], v[4:5], 0, v[184:185]
	global_load_dwordx4 v[140:143], v[0:1], off nt
	v_add_u32_e32 v8, 0x840, v7
	v_add_u32_e32 v0, 0x848, v7
	v_or_b32_e32 v0, s52, v13
	v_lshlrev_b32_e32 v184, 13, v0
	v_lshl_add_u64 v[0:1], v[4:5], 0, v[184:185]
	global_load_dwordx4 v[144:147], v[0:1], off nt
	v_add_u32_e32 v8, 0xc60, v7
	v_or_b32_e32 v184, 0x40000, v6
	v_add_u32_e32 v0, 0xc68, v7
	v_lshl_add_u64 v[0:1], v[4:5], 0, v[184:185]
	global_load_dwordx4 v[148:151], v[0:1], off nt
	v_add_u32_e32 v8, 0x1080, v7
	v_or_b32_e32 v184, 0x50000, v6
	v_add_u32_e32 v0, 0x1088, v7
	v_lshl_add_u64 v[0:1], v[4:5], 0, v[184:185]
	global_load_dwordx4 v[152:155], v[0:1], off nt
	v_add_u32_e32 v8, 0x14a0, v7
	v_or_b32_e32 v184, 0x60000, v6
	v_add_u32_e32 v0, 0x14a8, v7
	v_lshl_add_u64 v[0:1], v[4:5], 0, v[184:185]
	global_load_dwordx4 v[156:159], v[0:1], off nt
	v_add_u32_e32 v8, 0x18c0, v7
	v_or_b32_e32 v184, 0x70000, v6
	v_add_u32_e32 v0, 0x18c8, v7
	v_lshl_add_u64 v[0:1], v[4:5], 0, v[184:185]
	global_load_dwordx4 v[160:163], v[0:1], off nt
	v_add_u32_e32 v4, 0x1ce0, v7
	v_mov_b32_e32 v8, 0
	v_mov_b32_e32 v9, v8
	v_add_u32_e32 v0, 0x1ce8, v7
	s_waitcnt vmcnt(0)
	v_add_u32_e32 v164, 0x0, v7
	ds_write2_b32 v164, v132, v133 offset1:1
	ds_write2_b32 v164, v134, v135 offset0:2 offset1:3
	v_add_u32_e32 v164, 0x420, v7
	ds_write2_b32 v164, v136, v137 offset1:1
	ds_write2_b32 v164, v138, v139 offset0:2 offset1:3
	v_add_u32_e32 v164, 0x840, v7
	ds_write2_b32 v164, v140, v141 offset1:1
	ds_write2_b32 v164, v142, v143 offset0:2 offset1:3
	v_add_u32_e32 v164, 0xc60, v7
	ds_write2_b32 v164, v144, v145 offset1:1
	ds_write2_b32 v164, v146, v147 offset0:2 offset1:3
	v_add_u32_e32 v164, 0x1080, v7
	ds_write2_b32 v164, v148, v149 offset1:1
	ds_write2_b32 v164, v150, v151 offset0:2 offset1:3
	v_add_u32_e32 v164, 0x14a0, v7
	ds_write2_b32 v164, v152, v153 offset1:1
	ds_write2_b32 v164, v154, v155 offset0:2 offset1:3
	v_add_u32_e32 v164, 0x18c0, v7
	ds_write2_b32 v164, v156, v157 offset1:1
	ds_write2_b32 v164, v158, v159 offset0:2 offset1:3
	v_add_u32_e32 v164, 0x1ce0, v7
	ds_write2_b32 v164, v160, v161 offset1:1
	ds_write2_b32 v164, v162, v163 offset0:2 offset1:3
	v_lshrrev_b32_e32 v0, 5, v15
	v_and_b32_e32 v0, 1, v0
	v_lshlrev_b16_e32 v0, 5, v0
	v_or_b32_e32 v0, s78, v0
	s_waitcnt lgkmcnt(0)
	v_lshlrev_b32_sdwa v184, v227, v0 dst_sel:DWORD dst_unused:UNUSED_PAD src0_sel:DWORD src1_sel:WORD_0
	v_bfe_u32 v0, v15, 5, 1
	v_mul_u32_u24_e32 v0, 0x1080, v0
	v_lshl_add_u64 v[4:5], s[48:49], 0, v[184:185]
	v_lshlrev_b32_e32 v184, 2, v18
	v_lshl_or_b32 v0, v17, 2, v0
	v_lshl_add_u64 v[6:7], s[12:13], 0, v[184:185]
	v_add_u32_e32 v19, s79, v0
	s_mov_b64 s[12:13], 0
	s_movk_i32 s48, 0x2000

; #define LAS __attribute__((address_space(3)))
; __device__ __forceinline__ void atomic_addq(i64* p, float v, float scale) { (void)__hip_atomic_fetch_add((unsigned long long*)p, (unsigned long long)(i64)__builtin_rintf(v * scale), __ATOMIC_RELAXED, __HIP_MEMORY_SCOPE_AGENT); }
; template <class Map>
; __device__ __forceinline__ void conv_item(const Frame& F, int it, const float* W, int K, int N, bf16_t* WT, const float* gk, int gmask, float gmul, const float* bk, i64* cs, i64* bw, Map map) {
;     ...
;         const int kb = it / nblk, nb = it % nblk, k0 = 64 * kb, n0 = 32 * nb, v0 = map(n0);
; #pragma unroll
;         for (int i = 0; i < 8; ++i) { const int kk = 8 * i + (lane >> 3), c4 = (lane & 7) * 4;
;             const f32x4 w4 = __builtin_nontemporal_load((const f32x4*)(W + (size_t)(k0 + kk) * N + n0 + c4)); LAS float* d = scr + kk * 33 + c4; d[0] = w4[0]; d[1] = w4[1]; d[2] = w4[2]; d[3] = w4[3]; }
;         LDS_WAIT(); asm volatile("" ::: "memory");
;         if (bk) {
;             const int n = lane & 31, kh = lane >> 5; float sb = 0.f, sc = 0.f;
; #pragma unroll 8
;             for (int j = 0; j < 32; ++j) { const int kk = kh * 32 + j; const float w = scr[kk * 33 + n]; sb += bk[k0 + kk] * w; sc += bf_round(gk[(k0 + kk) & gmask] * gmul * w); }
;             { auto r = __builtin_amdgcn_permlane32_swap(__float_as_uint(sb), __float_as_uint(sb), false, false); sb = __uint_as_float(r[0]) + __uint_as_float(r[1]); }
;             { auto r = __builtin_amdgcn_permlane32_swap(__float_as_uint(sc), __float_as_uint(sc), false, false); sc = __uint_as_float(r[0]) + __uint_as_float(r[1]); }
;             if (lane < 32) { atomic_addq(bw + v0 + n, sb, FX_COL); atomic_addq(cs + v0 + n, sc, FX_COL); }
;         }
;         const int c = lane & 7; float gl[8];
; #pragma unroll
;         for (int i = 0; i < 8; ++i) gl[i] = gk ? gk[(k0 + 8 * c + i) & gmask] * gmul : 1.0f;
; #pragma unroll
;         for (int j = 0; j < 4; ++j) { const int n = (lane >> 3) + 8 * j; const LAS float* s = scr + (8 * c) * 33 + n;
;             u32x4 o; o.x = pk2(s[0 * 33] * gl[0], s[1 * 33] * gl[1]); o.y = pk2(s[2 * 33] * gl[2], s[3 * 33] * gl[3]); o.z = pk2(s[4 * 33] * gl[4], s[5 * 33] * gl[5]); o.w = pk2(s[6 * 33] * gl[6], s[7 * 33] * gl[7]);
;             __builtin_nontemporal_store(o, (u32x4*)(WT + (size_t)(v0 + n) * K + k0 + 8 * c)); }
.LBB0_261:
	s_andn2_b64 vcc, exec, s[6:7]
	s_cbranch_vccnz .LBB0_263
	v_readlane_b32 s6, v252, 14
	v_readlane_b32 s7, v252, 15
	s_load_dwordx2 s[6:7], s[6:7], 0x80
	s_add_i32 s12, s91, 0xc0c0
	s_mul_i32 s13, s20, 0x2c00000
	v_mov_b32_e32 v7, v220
	v_mov_b32_e32 v5, v185
	s_waitcnt lgkmcnt(0)
	s_add_u32 s17, s6, s13
	s_mul_hi_i32 s6, s20, 0x2c00000
	s_addc_u32 s25, s7, s6
	s_and_b32 s13, s12, 0xffc0
	s_lshl_b32 s12, s16, 5
	v_readlane_b32 s6, v252, 12
	s_and_b32 s12, s12, 0x7e0
	v_readlane_b32 s7, v252, 13
	s_lshl_b32 s24, s12, 2
	s_add_u32 s24, s17, s24
	v_bfe_u32 v6, v7, 3, 3
	v_lshlrev_b32_e32 v0, 4, v7
	s_addc_u32 s25, s25, 0
	v_and_b32_e32 v184, 0x70, v0
	v_or_b32_e32 v0, s13, v6
	v_lshl_add_u64 v[14:15], s[24:25], 0, v[184:185]
	v_lshlrev_b32_e32 v4, 13, v0
	v_lshl_add_u64 v[0:1], v[14:15], 0, v[4:5]
	global_load_dwordx4 v[132:135], v[0:1], off nt
	v_mul_u32_u24_e32 v5, 0x84, v6
	v_add3_u32 v13, s79, v184, v5
	v_or_b32_e32 v5, 8, v6
	v_add_u32_e32 v8, 0x420, v13
	v_or_b32_e32 v0, s13, v5
	v_lshlrev_b32_e32 v184, 13, v0
	v_lshl_add_u64 v[0:1], v[14:15], 0, v[184:185]
	global_load_dwordx4 v[136:139], v[0:1], off nt
	v_or_b32_e32 v5, s12, v5
	v_mul_u32_u24_e32 v5, 0x1600, v5
	v_add_u32_e32 v0, 0x428, v13
	v_or_b32_e32 v3, 16, v6
	v_or_b32_e32 v0, s13, v3
	v_lshlrev_b32_e32 v184, 13, v0
	v_lshl_add_u64 v[0:1], v[14:15], 0, v[184:185]
	global_load_dwordx4 v[140:143], v[0:1], off nt
	v_add_u32_e32 v0, 0x840, v13
	v_or_b32_e32 v2, 24, v6
	v_or_b32_e32 v3, s12, v3
	v_mul_u32_u24_e32 v3, 0x1600, v3
	v_add_u32_e32 v0, 0x848, v13
	v_or_b32_e32 v0, s13, v2
	v_lshlrev_b32_e32 v184, 13, v0
	v_lshl_add_u64 v[0:1], v[14:15], 0, v[184:185]
	global_load_dwordx4 v[144:147], v[0:1], off nt
	v_add_u32_e32 v0, 0xc60, v13
	v_or_b32_e32 v184, 0x40000, v4
	s_lshl_b32 s13, s13, 1
	s_add_u32 s6, s6, s13
	s_addc_u32 s7, s7, 0
	v_or_b32_e32 v2, s12, v2
	v_mul_u32_u24_e32 v2, 0x1600, v2
	v_add_u32_e32 v0, 0xc68, v13
	v_lshl_add_u64 v[0:1], v[14:15], 0, v[184:185]
	global_load_dwordx4 v[148:151], v[0:1], off nt
	v_add_u32_e32 v0, 0x1080, v13
	v_or_b32_e32 v184, 0x50000, v4
	v_add_u32_e32 v0, 0x1088, v13
	v_lshl_add_u64 v[0:1], v[14:15], 0, v[184:185]
	global_load_dwordx4 v[152:155], v[0:1], off nt
	v_add_u32_e32 v0, 0x14a0, v13
	v_or_b32_e32 v184, 0x60000, v4
	v_add_u32_e32 v0, 0x14a8, v13
	v_lshl_add_u64 v[0:1], v[14:15], 0, v[184:185]
	global_load_dwordx4 v[156:159], v[0:1], off nt
	v_add_u32_e32 v0, 0x18c0, v13
	v_or_b32_e32 v184, 0x70000, v4
	v_add_u32_e32 v0, 0x18c8, v13
	v_lshl_add_u64 v[0:1], v[14:15], 0, v[184:185]
	global_load_dwordx4 v[160:163], v[0:1], off nt
	v_add_u32_e32 v0, 0x1ce0, v13
	v_add_u32_e32 v0, 0x1ce8, v13
	s_waitcnt vmcnt(0)
	v_add_u32_e32 v164, 0x0, v13
	ds_write2_b32 v164, v132, v133 offset1:1
	ds_write2_b32 v164, v134, v135 offset0:2 offset1:3
	v_add_u32_e32 v164, 0x420, v13
	ds_write2_b32 v164, v136, v137 offset1:1
	ds_write2_b32 v164, v138, v139 offset0:2 offset1:3
	v_add_u32_e32 v164, 0x840, v13
	ds_write2_b32 v164, v140, v141 offset1:1
	ds_write2_b32 v164, v142, v143 offset0:2 offset1:3
	v_add_u32_e32 v164, 0xc60, v13
	ds_write2_b32 v164, v144, v145 offset1:1
	ds_write2_b32 v164, v146, v147 offset0:2 offset1:3
	v_add_u32_e32 v164, 0x1080, v13
	ds_write2_b32 v164, v148, v149 offset1:1
	ds_write2_b32 v164, v150, v151 offset0:2 offset1:3
	v_add_u32_e32 v164, 0x14a0, v13
	ds_write2_b32 v164, v152, v153 offset1:1
	ds_write2_b32 v164, v154, v155 offset0:2 offset1:3
	v_add_u32_e32 v164, 0x18c0, v13
	ds_write2_b32 v164, v156, v157 offset1:1
	ds_write2_b32 v164, v158, v159 offset0:2 offset1:3
	v_add_u32_e32 v164, 0x1ce0, v13
	ds_write2_b32 v164, v160, v161 offset1:1
	ds_write2_b32 v164, v162, v163 offset0:2 offset1:3
	v_and_b32_e32 v0, 7, v7
	s_waitcnt lgkmcnt(0)
	v_mul_u32_u24_e32 v4, 0x420, v0
	v_lshlrev_b32_e32 v7, 2, v6
	v_add3_u32 v4, s79, v4, v7
	ds_read_b32 v7, v4
	ds_read_b32 v8, v4 offset:132
	v_lshlrev_b32_e32 v184, 4, v0
	v_or_b32_e32 v6, s12, v6
	v_lshl_add_u64 v[0:1], s[6:7], 0, v[184:185]
	s_waitcnt lgkmcnt(1)
	v_bfe_u32 v9, v7, 16, 1
	v_add3_u32 v7, v7, v9, s73
	s_waitcnt lgkmcnt(0)
	v_bfe_u32 v9, v8, 16, 1
	v_lshrrev_b32_e32 v7, 16, v7
	v_add3_u32 v8, v8, v9, s73
	v_and_or_b32 v8, v8, s72, v7
	ds_read_b32 v7, v4 offset:264
	ds_read_b32 v9, v4 offset:396
	s_mov_b64 s[6:7], 0x5c00000
	v_mul_u32_u24_e32 v6, 0x1600, v6
	v_lshl_add_u64 v[0:1], v[0:1], 0, s[6:7]
	s_waitcnt lgkmcnt(1)
; #define LAS __attribute__((address_space(3)))
; #define LDS_WAIT() asm volatile("s_waitcnt lgkmcnt(0)" ::: "memory")
; __device__ __forceinline__ unsigned pk2(float lo, float hi) { return f2bf(lo) | (f2bf(hi) << 16); }
; template <class Map>
; __device__ __forceinline__ void conv_item(const Frame& F, int it, const float* W, int K, int N, bf16_t* WT, const float* gk, int gmask, float gmul, const float* bk, i64* cs, i64* bw, Map map) {
;     ...
;         const int c = lane & 7; float gl[8];
; #pragma unroll
;         for (int i = 0; i < 8; ++i) gl[i] = gk ? gk[(k0 + 8 * c + i) & gmask] * gmul : 1.0f;
; #pragma unroll
;         for (int j = 0; j < 4; ++j) { const int n = (lane >> 3) + 8 * j; const LAS float* s = scr + (8 * c) * 33 + n;
;             u32x4 o; o.x = pk2(s[0 * 33] * gl[0], s[1 * 33] * gl[1]); o.y = pk2(s[2 * 33] * gl[2], s[3 * 33] * gl[3]); o.z = pk2(s[4 * 33] * gl[4], s[5 * 33] * gl[5]); o.w = pk2(s[6 * 33] * gl[6], s[7 * 33] * gl[7]);
;             __builtin_nontemporal_store(o, (u32x4*)(WT + (size_t)(v0 + n) * K + k0 + 8 * c)); }
;         LDS_WAIT(); asm volatile("" ::: "memory");
	v_bfe_u32 v10, v7, 16, 1
	v_add3_u32 v7, v7, v10, s73
	s_waitcnt lgkmcnt(0)
	v_bfe_u32 v10, v9, 16, 1
	v_lshrrev_b32_e32 v7, 16, v7
	v_add3_u32 v9, v9, v10, s73
	v_and_or_b32 v9, v9, s72, v7
	ds_read_b32 v7, v4 offset:528
	ds_read_b32 v10, v4 offset:660
	v_lshlrev_b32_e32 v184, 1, v6
	s_waitcnt lgkmcnt(1)
	v_bfe_u32 v11, v7, 16, 1
	v_add3_u32 v7, v7, v11, s73
	s_waitcnt lgkmcnt(0)
	v_bfe_u32 v11, v10, 16, 1
	v_lshrrev_b32_e32 v7, 16, v7
	v_add3_u32 v10, v10, v11, s73
	v_and_or_b32 v10, v10, s72, v7
	ds_read_b32 v7, v4 offset:792
	ds_read_b32 v11, v4 offset:924
	s_waitcnt lgkmcnt(1)
	v_bfe_u32 v13, v7, 16, 1
	v_add3_u32 v7, v7, v13, s73
	s_waitcnt lgkmcnt(0)
	v_bfe_u32 v13, v11, 16, 1
	v_lshrrev_b32_e32 v7, 16, v7
	v_add3_u32 v11, v11, v13, s73
	v_and_or_b32 v11, v11, s72, v7
	v_lshl_add_u64 v[6:7], v[0:1], 0, v[184:185]
	flat_store_dwordx4 v[6:7], v[8:11] nt
	ds_read_b32 v6, v4 offset:32
	ds_read_b32 v7, v4 offset:164
	v_lshlrev_b32_e32 v184, 1, v5
	s_waitcnt lgkmcnt(0)
	v_bfe_u32 v8, v6, 16, 1
	v_add3_u32 v6, v6, v8, s73
	v_bfe_u32 v8, v7, 16, 1
	v_lshrrev_b32_e32 v6, 16, v6
	v_add3_u32 v7, v7, v8, s73
	v_and_or_b32 v6, v7, s72, v6
	ds_read_b32 v7, v4 offset:296
	ds_read_b32 v8, v4 offset:428
	s_waitcnt lgkmcnt(0)
	v_bfe_u32 v9, v7, 16, 1
	v_add3_u32 v7, v7, v9, s73
	v_bfe_u32 v9, v8, 16, 1
	v_lshrrev_b32_e32 v7, 16, v7
	v_add3_u32 v8, v8, v9, s73
	v_and_or_b32 v7, v8, s72, v7
	ds_read_b32 v8, v4 offset:560
	ds_read_b32 v9, v4 offset:692
	s_waitcnt lgkmcnt(0)
	v_bfe_u32 v10, v8, 16, 1
	v_add3_u32 v8, v8, v10, s73
	v_bfe_u32 v10, v9, 16, 1
	v_lshrrev_b32_e32 v8, 16, v8
	v_add3_u32 v9, v9, v10, s73
	v_and_or_b32 v8, v9, s72, v8
	ds_read_b32 v9, v4 offset:824
	ds_read_b32 v10, v4 offset:956
	s_waitcnt lgkmcnt(0)
	v_bfe_u32 v11, v9, 16, 1
	v_add3_u32 v9, v9, v11, s73
	v_bfe_u32 v11, v10, 16, 1
	v_lshrrev_b32_e32 v9, 16, v9
	v_add3_u32 v10, v10, v11, s73
	v_and_or_b32 v9, v10, s72, v9
	v_lshl_add_u64 v[10:11], v[0:1], 0, v[184:185]
	flat_store_dwordx4 v[10:11], v[6:9] nt
	ds_read_b32 v5, v4 offset:64
	ds_read_b32 v6, v4 offset:196
	v_lshlrev_b32_e32 v184, 1, v3
	s_waitcnt lgkmcnt(0)
	v_bfe_u32 v7, v5, 16, 1
	v_add3_u32 v5, v5, v7, s73
	v_bfe_u32 v7, v6, 16, 1
	v_lshrrev_b32_e32 v5, 16, v5
	v_add3_u32 v6, v6, v7, s73
	v_and_or_b32 v6, v6, s72, v5
	ds_read_b32 v5, v4 offset:328
	ds_read_b32 v7, v4 offset:460
	s_waitcnt lgkmcnt(0)
	v_bfe_u32 v8, v5, 16, 1
	v_add3_u32 v5, v5, v8, s73
	v_bfe_u32 v8, v7, 16, 1
	v_lshrrev_b32_e32 v5, 16, v5
	v_add3_u32 v7, v7, v8, s73
	v_and_or_b32 v7, v7, s72, v5
	ds_read_b32 v5, v4 offset:592
	ds_read_b32 v8, v4 offset:724
	s_waitcnt lgkmcnt(0)
	v_bfe_u32 v9, v5, 16, 1
	v_add3_u32 v5, v5, v9, s73
	v_bfe_u32 v9, v8, 16, 1
	v_lshrrev_b32_e32 v5, 16, v5
	v_add3_u32 v8, v8, v9, s73
	v_and_or_b32 v8, v8, s72, v5
	ds_read_b32 v5, v4 offset:856
	ds_read_b32 v9, v4 offset:988
	s_waitcnt lgkmcnt(0)
	v_bfe_u32 v10, v5, 16, 1
	v_add3_u32 v5, v5, v10, s73
	v_bfe_u32 v10, v9, 16, 1
	v_lshrrev_b32_e32 v5, 16, v5
	v_add3_u32 v9, v9, v10, s73
	v_and_or_b32 v9, v9, s72, v5
	v_lshl_add_u64 v[10:11], v[0:1], 0, v[184:185]
	flat_store_dwordx4 v[10:11], v[6:9] nt
	ds_read_b32 v3, v4 offset:96
	ds_read_b32 v5, v4 offset:228
	v_lshlrev_b32_e32 v184, 1, v2
	v_lshl_add_u64 v[0:1], v[0:1], 0, v[184:185]
	s_waitcnt lgkmcnt(0)
	v_bfe_u32 v6, v3, 16, 1
	v_add3_u32 v3, v3, v6, s73
	v_bfe_u32 v6, v5, 16, 1
	v_lshrrev_b32_e32 v3, 16, v3
	v_add3_u32 v5, v5, v6, s73
	v_and_or_b32 v6, v5, s72, v3
	ds_read_b32 v3, v4 offset:360
	ds_read_b32 v5, v4 offset:492
	s_waitcnt lgkmcnt(0)
	v_bfe_u32 v7, v3, 16, 1
	v_add3_u32 v3, v3, v7, s73
	v_bfe_u32 v7, v5, 16, 1
	v_lshrrev_b32_e32 v3, 16, v3
	v_add3_u32 v5, v5, v7, s73
	v_and_or_b32 v7, v5, s72, v3
	ds_read_b32 v3, v4 offset:624
	ds_read_b32 v5, v4 offset:756
	s_waitcnt lgkmcnt(0)
	v_bfe_u32 v8, v3, 16, 1
	v_add3_u32 v3, v3, v8, s73
	v_bfe_u32 v8, v5, 16, 1
	v_lshrrev_b32_e32 v3, 16, v3
	v_add3_u32 v5, v5, v8, s73
	v_and_or_b32 v8, v5, s72, v3
	ds_read_b32 v3, v4 offset:888
	ds_read_b32 v4, v4 offset:1020
	s_waitcnt lgkmcnt(0)
	v_bfe_u32 v5, v3, 16, 1
	v_add3_u32 v3, v3, v5, s73
	v_bfe_u32 v5, v4, 16, 1
	v_lshrrev_b32_e32 v3, 16, v3
	v_add3_u32 v4, v4, v5, s73
	v_and_or_b32 v9, v4, s72, v3
	flat_store_dwordx4 v[0:1], v[6:9] nt
	s_waitcnt lgkmcnt(0)

; #define LAS __attribute__((address_space(3)))
; __device__ __forceinline__ void atomic_addq(i64* p, float v, float scale) { (void)__hip_atomic_fetch_add((unsigned long long*)p, (unsigned long long)(i64)__builtin_rintf(v * scale), __ATOMIC_RELAXED, __HIP_MEMORY_SCOPE_AGENT); }
; #define F_LANE() (tid_of(F.wave) & 63)
; #define LDS_WAIT() asm volatile("s_waitcnt lgkmcnt(0)" ::: "memory")
; __device__ __forceinline__ float bf_round(float f) { return __uint_as_float(f2bf(f) << 16); }
; #define INP(i) (kargs()->in[i])
; template <class Map>
; __device__ __forceinline__ void conv_item(const Frame& F, int it, const float* W, int K, int N, bf16_t* WT, const float* gk, int gmask, float gmul, const float* bk, i64* cs, i64* bw, Map map) {
;     LAS float* scr = (LAS float*)(F.lds + F.wave * 16384);
;     const int lane = F_LANE(), nblk = N / 32;
;     {
;         const int kb = it / nblk, nb = it % nblk, k0 = 64 * kb, n0 = 32 * nb, v0 = map(n0);
; #pragma unroll
;         for (int i = 0; i < 8; ++i) { const int kk = 8 * i + (lane >> 3), c4 = (lane & 7) * 4;
;             const f32x4 w4 = __builtin_nontemporal_load((const f32x4*)(W + (size_t)(k0 + kk) * N + n0 + c4)); LAS float* d = scr + kk * 33 + c4; d[0] = w4[0]; d[1] = w4[1]; d[2] = w4[2]; d[3] = w4[3]; }
;         LDS_WAIT(); asm volatile("" ::: "memory");
;         if (bk) {
;             const int n = lane & 31, kh = lane >> 5; float sb = 0.f, sc = 0.f;
; #pragma unroll 8
;             for (int j = 0; j < 32; ++j) { const int kk = kh * 32 + j; const float w = scr[kk * 33 + n]; sb += bk[k0 + kk] * w; sc += bf_round(gk[(k0 + kk) & gmask] * gmul * w); }
;             { auto r = __builtin_amdgcn_permlane32_swap(__float_as_uint(sb), __float_as_uint(sb), false, false); sb = __uint_as_float(r[0]) + __uint_as_float(r[1]); }
;             { auto r = __builtin_amdgcn_permlane32_swap(__float_as_uint(sc), __float_as_uint(sc), false, false); sc = __uint_as_float(r[0]) + __uint_as_float(r[1]); }
;             if (lane < 32) { atomic_addq(bw + v0 + n, sb, FX_COL); atomic_addq(cs + v0 + n, sc, FX_COL); }
;         }
; __device__ BG_ATTR void bg_item(const Frame& F, unsigned char* ws, const int L, int id) {
;     ...
;     if (id < NI_F1) { conv_item(F, id, INP(15) + (size_t)L * DM * 2 * DFF, DM, 2 * DFF, Wf1, g1, DM - 1, 1.f, b1, csFq, csFq + 11264, MapSwiglu()); return; } id -= NI_F1;
.LBB0_264:
	s_andn2_b64 vcc, exec, s[6:7]
	s_cbranch_vccnz .LBB0_288
	v_readlane_b32 s40, v252, 14
	v_readlane_b32 s41, v252, 15
	s_mov_b64 s[6:7], s[40:41]
	s_load_dwordx2 s[6:7], s[6:7], 0x78
	s_mul_i32 s12, s20, 0x5800000
	s_mov_b32 vcc_lo, s79
	v_readlane_b32 s78, v252, 12
	v_readlane_b32 s79, v252, 13
	s_waitcnt lgkmcnt(0)
	s_add_u32 s92, s6, s12
	s_mul_hi_i32 s6, s20, 0x5800000
	s_addc_u32 s93, s7, s6
	s_mov_b64 s[6:7], s[78:79]
	s_mov_b64 s[12:13], s[40:41]
	s_load_dwordx2 s[26:27], s[12:13], 0x68
	s_lshl_b64 s[12:13], s[56:57], 2
	v_mov_b32_e32 v3, v220
	v_mov_b32_e32 v5, v185
	s_waitcnt lgkmcnt(0)
	s_add_u32 s24, s26, s12
	s_addc_u32 s25, s27, s13
	s_and_b32 s17, s16, 0xffff
	s_mov_b64 s[12:13], s[40:41]
	s_mul_i32 s52, s17, 0xba2f
	s_lshr_b32 s52, s52, 24
	s_load_dwordx2 s[48:49], s[12:13], 0x70
	s_mov_b64 s[12:13], s[78:79]
	s_mov_b64 s[40:41], s[78:79]
	s_mul_i32 s78, s52, 0x160
	s_sub_i32 s96, s16, s78
	s_lshl_b32 s16, s96, 5
	s_lshl_b32 s52, s52, 6
	s_and_b32 s78, s96, 0xffff
	s_add_i32 s79, s16, 0xea00
	s_cmpk_lt_u32 s78, 0xb0
	s_cselect_b32 s16, s16, s79
	s_sext_i32_i16 s97, s16
	s_lshl_b32 s79, s97, 1
	s_cmpk_gt_u32 s78, 0xaf
	s_cselect_b32 s16, 0x80, 0
	s_lshl_b32 s96, s96, 7
	s_and_b32 s78, s97, 0x60
	s_and_b32 s96, s96, 0x3ff80
	s_add_u32 s92, s92, s96
	v_bfe_u32 v16, v3, 3, 3
	v_lshlrev_b32_e32 v0, 4, v3
	s_addc_u32 s93, s93, 0
	v_and_b32_e32 v184, 0x70, v0
	v_or_b32_e32 v2, s52, v16
	v_lshl_add_u64 v[0:1], s[92:93], 0, v[184:185]
	v_mul_u32_u24_e32 v4, 0xb000, v2
	v_lshl_add_u64 v[4:5], v[0:1], 0, v[4:5]
	global_load_dwordx4 v[132:135], v[4:5], off nt
	v_mul_u32_u24_e32 v8, 0x84, v16
	v_add3_u32 v8, vcc_lo, v184, v8
	v_or_b32_e32 v15, 8, v16
	v_add_u32_e32 v9, 0x420, v8
	v_or_b32_e32 v14, 16, v16
	v_or_b32_e32 v13, 24, v16
	s_and_b32 s79, s79, 0xffffff00
	s_or_b32 s16, s78, s16
	s_or_b32 s78, s16, s79
	s_waitcnt lgkmcnt(0)
	s_cmp_eq_u64 s[48:49], 0
	v_or_b32_e32 v4, s52, v15
	v_mul_u32_u24_e32 v184, 0xb000, v4
	v_lshl_add_u64 v[4:5], v[0:1], 0, v[184:185]
	global_load_dwordx4 v[136:139], v[4:5], off nt
	v_add_u32_e32 v4, 0x428, v8
	v_or_b32_e32 v4, s52, v14
	v_mul_u32_u24_e32 v184, 0xb000, v4
	v_lshl_add_u64 v[4:5], v[0:1], 0, v[184:185]
	global_load_dwordx4 v[140:143], v[4:5], off nt
	v_add_u32_e32 v9, 0x840, v8
	v_add_u32_e32 v4, 0x848, v8
	v_or_b32_e32 v4, s52, v13
	v_mul_u32_u24_e32 v184, 0xb000, v4
	v_lshl_add_u64 v[4:5], v[0:1], 0, v[184:185]
	global_load_dwordx4 v[144:147], v[4:5], off nt
	v_add_u32_e32 v9, 0xc60, v8
	v_add_u32_e32 v4, 0xc68, v8
	v_or_b32_e32 v4, 32, v2
	v_mul_u32_u24_e32 v184, 0xb000, v4
	v_lshl_add_u64 v[4:5], v[0:1], 0, v[184:185]
	global_load_dwordx4 v[148:151], v[4:5], off nt
	v_add_u32_e32 v9, 0x1080, v8
	v_add_u32_e32 v4, 0x1088, v8
	v_or_b32_e32 v4, 40, v2
	v_mul_u32_u24_e32 v184, 0xb000, v4
	v_lshl_add_u64 v[4:5], v[0:1], 0, v[184:185]
	global_load_dwordx4 v[152:155], v[4:5], off nt
	v_add_u32_e32 v9, 0x14a0, v8
	v_add_u32_e32 v4, 0x14a8, v8
	v_or_b32_e32 v4, 48, v2
	v_mul_u32_u24_e32 v184, 0xb000, v4
	v_lshl_add_u64 v[4:5], v[0:1], 0, v[184:185]
	global_load_dwordx4 v[156:159], v[4:5], off nt
	v_or_b32_e32 v2, 56, v2
	v_add_u32_e32 v9, 0x18c0, v8
	v_mul_u32_u24_e32 v184, 0xb000, v2
	v_lshl_add_u64 v[0:1], v[0:1], 0, v[184:185]
	v_add_u32_e32 v4, 0x18c8, v8
	global_load_dwordx4 v[160:163], v[0:1], off nt
	v_add_u32_e32 v0, 0x1ce0, v8
	v_add_u32_e32 v0, 0x1ce8, v8
	s_waitcnt vmcnt(0)
	v_add_u32_e32 v164, 0x0, v8
	ds_write2_b32 v164, v132, v133 offset1:1
	ds_write2_b32 v164, v134, v135 offset0:2 offset1:3
	v_add_u32_e32 v164, 0x420, v8
	ds_write2_b32 v164, v136, v137 offset1:1
	ds_write2_b32 v164, v138, v139 offset0:2 offset1:3
	v_add_u32_e32 v164, 0x840, v8
	ds_write2_b32 v164, v140, v141 offset1:1
	ds_write2_b32 v164, v142, v143 offset0:2 offset1:3
	v_add_u32_e32 v164, 0xc60, v8
	ds_write2_b32 v164, v144, v145 offset1:1
	ds_write2_b32 v164, v146, v147 offset0:2 offset1:3
	v_add_u32_e32 v164, 0x1080, v8
	ds_write2_b32 v164, v148, v149 offset1:1
	ds_write2_b32 v164, v150, v151 offset0:2 offset1:3
	v_add_u32_e32 v164, 0x14a0, v8
	ds_write2_b32 v164, v152, v153 offset1:1
	ds_write2_b32 v164, v154, v155 offset0:2 offset1:3
	v_add_u32_e32 v164, 0x18c0, v8
	ds_write2_b32 v164, v156, v157 offset1:1
	ds_write2_b32 v164, v158, v159 offset0:2 offset1:3
	v_add_u32_e32 v164, 0x1ce0, v8
	ds_write2_b32 v164, v160, v161 offset1:1
	ds_write2_b32 v164, v162, v163 offset0:2 offset1:3
	s_waitcnt lgkmcnt(0)
	s_cbranch_scc1 .LBB0_271
	v_readlane_b32 s92, v255, 25
	v_and_b32_e32 v0, 32, v3
	v_readlane_b32 s93, v255, 26
	s_add_u32 s48, s48, s92
	s_mul_hi_u32 s79, s17, 0xba2e8c
	s_addc_u32 s49, s49, s93
	v_add_u32_e32 v19, s52, v0
	s_lshl_b32 s16, s79, 8
	v_lshlrev_b32_e32 v184, 2, v19
	v_bfe_u32 v1, v3, 5, 1
	s_add_u32 s16, s48, s16
	v_lshl_add_u64 v[4:5], s[48:49], 0, v[184:185]
	v_lshrrev_b32_e32 v0, 5, v3
	v_lshlrev_b32_e32 v184, 7, v1
	s_addc_u32 s17, s49, 0
	v_lshl_add_u64 v[6:7], s[16:17], 0, v[184:185]
	s_add_u32 s16, s26, s92
	v_and_b32_e32 v0, 1, v0
	s_addc_u32 s17, s27, s93
	s_lshl_b32 s48, s79, 6
	v_lshlrev_b16_e32 v0, 5, v0
	v_or_b32_e32 v0, s48, v0
	v_and_b32_e32 v0, 0x7e0, v0
	v_and_b32_e32 v17, 31, v3
	v_lshlrev_b32_e32 v184, 2, v0
	v_mul_u32_u24_e32 v0, 0x1080, v1
	v_lshl_add_u64 v[8:9], s[16:17], 0, v[184:185]
	v_lshl_or_b32 v0, v17, 2, v0
	v_readlane_b32 s16, v255, 17
	v_and_b32_e32 v18, 63, v3
	s_mov_b64 s[48:49], 0
	v_add_u32_e32 v20, s16, v0
	v_mov_b32_e32 v0, 0
	v_mov_b32_e32 v1, v0

; #define LAS __attribute__((address_space(3)))
; #define INP(i) (kargs()->in[i])
; template <class Map>
; __device__ __forceinline__ void conv_item(const Frame& F, int it, const float* W, int K, int N, bf16_t* WT, const float* gk, int gmask, float gmul, const float* bk, i64* cs, i64* bw, Map map) {
;     ...
;         const int kb = it / nblk, nb = it % nblk, k0 = 64 * kb, n0 = 32 * nb, v0 = map(n0);
; #pragma unroll
;         for (int i = 0; i < 8; ++i) { const int kk = 8 * i + (lane >> 3), c4 = (lane & 7) * 4;
;             const f32x4 w4 = __builtin_nontemporal_load((const f32x4*)(W + (size_t)(k0 + kk) * N + n0 + c4)); LAS float* d = scr + kk * 33 + c4; d[0] = w4[0]; d[1] = w4[1]; d[2] = w4[2]; d[3] = w4[3]; }
;         LDS_WAIT(); asm volatile("" ::: "memory");
;         if (bk) {
;             const int n = lane & 31, kh = lane >> 5; float sb = 0.f, sc = 0.f;
; #pragma unroll 8
;             for (int j = 0; j < 32; ++j) { const int kk = kh * 32 + j; const float w = scr[kk * 33 + n]; sb += bk[k0 + kk] * w; sc += bf_round(gk[(k0 + kk) & gmask] * gmul * w); }
;             { auto r = __builtin_amdgcn_permlane32_swap(__float_as_uint(sb), __float_as_uint(sb), false, false); sb = __uint_as_float(r[0]) + __uint_as_float(r[1]); }
;             { auto r = __builtin_amdgcn_permlane32_swap(__float_as_uint(sc), __float_as_uint(sc), false, false); sc = __uint_as_float(r[0]) + __uint_as_float(r[1]); }
;             if (lane < 32) { atomic_addq(bw + v0 + n, sb, FX_COL); atomic_addq(cs + v0 + n, sc, FX_COL); }
;         }
;         const int c = lane & 7; float gl[8];
; #pragma unroll
;         for (int i = 0; i < 8; ++i) gl[i] = gk ? gk[(k0 + 8 * c + i) & gmask] * gmul : 1.0f;
; #pragma unroll
;         for (int j = 0; j < 4; ++j) { const int n = (lane >> 3) + 8 * j; const LAS float* s = scr + (8 * c) * 33 + n;
;             u32x4 o; o.x = pk2(s[0 * 33] * gl[0], s[1 * 33] * gl[1]); o.y = pk2(s[2 * 33] * gl[2], s[3 * 33] * gl[3]); o.z = pk2(s[4 * 33] * gl[4], s[5 * 33] * gl[5]); o.w = pk2(s[6 * 33] * gl[6], s[7 * 33] * gl[7]);
;             __builtin_nontemporal_store(o, (u32x4*)(WT + (size_t)(v0 + n) * K + k0 + 8 * c)); }
; __device__ BG_ATTR void bg_item(const Frame& F, unsigned char* ws, const int L, int id) {
;     ...
;         if (id < NI_O) { conv_item(F, id, INP(7) + (size_t)j * DM * DM, DM, DM, Wo, nullptr, 0, 1.f, nullptr, nullptr, nullptr, MapIdent()); return; } id -= NI_O;
.LBB0_289:
	s_andn2_b64 vcc, exec, s[6:7]
	s_cbranch_vccnz .LBB0_291
	v_readlane_b32 s6, v252, 14
	v_readlane_b32 s7, v252, 15
	s_load_dwordx2 s[6:7], s[6:7], 0x38
	s_add_i32 s12, s91, 0xf4c0
	v_mov_b32_e32 v7, v220
	v_mov_b32_e32 v5, v185
	s_waitcnt lgkmcnt(0)
	s_add_u32 s16, s6, s36
	s_addc_u32 s17, s7, s37
	s_and_b32 s13, s12, 0xffc0
	s_lshl_b32 s12, s91, 5
	v_readlane_b32 s6, v252, 12
	s_and_b32 s12, s12, 0x7e0
	v_readlane_b32 s7, v252, 13
	s_lshl_b32 s24, s12, 2
	s_add_u32 s16, s16, s24
	v_bfe_u32 v6, v7, 3, 3
	v_lshlrev_b32_e32 v0, 4, v7
	s_addc_u32 s17, s17, 0
	v_and_b32_e32 v184, 0x70, v0
	v_or_b32_e32 v0, s13, v6
	v_lshl_add_u64 v[14:15], s[16:17], 0, v[184:185]
	v_lshlrev_b32_e32 v4, 13, v0
	v_lshl_add_u64 v[0:1], v[14:15], 0, v[4:5]
	global_load_dwordx4 v[132:135], v[0:1], off nt
	v_mul_u32_u24_e32 v5, 0x84, v6
	v_add3_u32 v13, s79, v184, v5
	v_or_b32_e32 v5, 8, v6
	v_add_u32_e32 v8, 0x420, v13
	v_or_b32_e32 v0, s13, v5
	v_lshlrev_b32_e32 v184, 13, v0
	v_lshl_add_u64 v[0:1], v[14:15], 0, v[184:185]
	global_load_dwordx4 v[136:139], v[0:1], off nt
	v_or_b32_e32 v5, s12, v5
	v_add_u32_e32 v0, 0x428, v13
	v_or_b32_e32 v3, 16, v6
	v_or_b32_e32 v0, s13, v3
	v_lshlrev_b32_e32 v184, 13, v0
	v_lshl_add_u64 v[0:1], v[14:15], 0, v[184:185]
	global_load_dwordx4 v[140:143], v[0:1], off nt
	v_add_u32_e32 v0, 0x840, v13
	v_or_b32_e32 v2, 24, v6
	v_or_b32_e32 v3, s12, v3
	v_add_u32_e32 v0, 0x848, v13
	v_or_b32_e32 v0, s13, v2
	v_lshlrev_b32_e32 v184, 13, v0
	v_lshl_add_u64 v[0:1], v[14:15], 0, v[184:185]
	global_load_dwordx4 v[144:147], v[0:1], off nt
	v_add_u32_e32 v0, 0xc60, v13
	v_or_b32_e32 v184, 0x40000, v4
	s_lshl_b32 s13, s13, 1
	s_add_u32 s6, s6, s13
	s_addc_u32 s7, s7, 0
	v_or_b32_e32 v2, s12, v2
	v_add_u32_e32 v0, 0xc68, v13
	v_lshl_add_u64 v[0:1], v[14:15], 0, v[184:185]
	global_load_dwordx4 v[148:151], v[0:1], off nt
	v_add_u32_e32 v0, 0x1080, v13
	v_or_b32_e32 v184, 0x50000, v4
	v_add_u32_e32 v0, 0x1088, v13
	v_lshl_add_u64 v[0:1], v[14:15], 0, v[184:185]
	global_load_dwordx4 v[152:155], v[0:1], off nt
	v_add_u32_e32 v0, 0x14a0, v13
	v_or_b32_e32 v184, 0x60000, v4
	v_add_u32_e32 v0, 0x14a8, v13
	v_lshl_add_u64 v[0:1], v[14:15], 0, v[184:185]
	global_load_dwordx4 v[156:159], v[0:1], off nt
	v_add_u32_e32 v0, 0x18c0, v13
	v_or_b32_e32 v184, 0x70000, v4
	v_add_u32_e32 v0, 0x18c8, v13
	v_lshl_add_u64 v[0:1], v[14:15], 0, v[184:185]
	global_load_dwordx4 v[160:163], v[0:1], off nt
	v_add_u32_e32 v0, 0x1ce0, v13
	v_add_u32_e32 v0, 0x1ce8, v13
	s_waitcnt vmcnt(0)
	v_add_u32_e32 v164, 0x0, v13
	ds_write2_b32 v164, v132, v133 offset1:1
	ds_write2_b32 v164, v134, v135 offset0:2 offset1:3
	v_add_u32_e32 v164, 0x420, v13
	ds_write2_b32 v164, v136, v137 offset1:1
	ds_write2_b32 v164, v138, v139 offset0:2 offset1:3
	v_add_u32_e32 v164, 0x840, v13
	ds_write2_b32 v164, v140, v141 offset1:1
	ds_write2_b32 v164, v142, v143 offset0:2 offset1:3
	v_add_u32_e32 v164, 0xc60, v13
	ds_write2_b32 v164, v144, v145 offset1:1
	ds_write2_b32 v164, v146, v147 offset0:2 offset1:3
	v_add_u32_e32 v164, 0x1080, v13
	ds_write2_b32 v164, v148, v149 offset1:1
	ds_write2_b32 v164, v150, v151 offset0:2 offset1:3
	v_add_u32_e32 v164, 0x14a0, v13
	ds_write2_b32 v164, v152, v153 offset1:1
	ds_write2_b32 v164, v154, v155 offset0:2 offset1:3
	v_add_u32_e32 v164, 0x18c0, v13
	ds_write2_b32 v164, v156, v157 offset1:1
	ds_write2_b32 v164, v158, v159 offset0:2 offset1:3
	v_add_u32_e32 v164, 0x1ce0, v13
	ds_write2_b32 v164, v160, v161 offset1:1
	ds_write2_b32 v164, v162, v163 offset0:2 offset1:3
	v_and_b32_e32 v0, 7, v7
	s_waitcnt lgkmcnt(0)
	v_mul_u32_u24_e32 v4, 0x420, v0
	v_lshlrev_b32_e32 v7, 2, v6
	v_add3_u32 v4, s79, v4, v7
	ds_read_b32 v7, v4
	ds_read_b32 v8, v4 offset:132
	v_lshlrev_b32_e32 v184, 4, v0
	v_lshl_add_u64 v[0:1], s[6:7], 0, v[184:185]
	s_mov_b64 s[6:7], 0x2800000
	s_waitcnt lgkmcnt(1)
	v_bfe_u32 v9, v7, 16, 1
	v_add3_u32 v7, v7, v9, s73
	s_waitcnt lgkmcnt(0)
	v_bfe_u32 v9, v8, 16, 1
	v_lshrrev_b32_e32 v7, 16, v7
	v_add3_u32 v8, v8, v9, s73
	v_and_or_b32 v8, v8, s72, v7
	ds_read_b32 v7, v4 offset:264
	ds_read_b32 v9, v4 offset:396
	v_or_b32_e32 v6, s12, v6
	v_lshl_add_u64 v[0:1], v[0:1], 0, s[6:7]
	v_lshlrev_b32_e32 v184, 12, v6
	s_waitcnt lgkmcnt(1)
; #define LAS __attribute__((address_space(3)))
; #define LDS_WAIT() asm volatile("s_waitcnt lgkmcnt(0)" ::: "memory")
; __device__ __forceinline__ unsigned pk2(float lo, float hi) { return f2bf(lo) | (f2bf(hi) << 16); }
; template <class Map>
; __device__ __forceinline__ void conv_item(const Frame& F, int it, const float* W, int K, int N, bf16_t* WT, const float* gk, int gmask, float gmul, const float* bk, i64* cs, i64* bw, Map map) {
;     ...
;         const int c = lane & 7; float gl[8];
; #pragma unroll
;         for (int i = 0; i < 8; ++i) gl[i] = gk ? gk[(k0 + 8 * c + i) & gmask] * gmul : 1.0f;
; #pragma unroll
;         for (int j = 0; j < 4; ++j) { const int n = (lane >> 3) + 8 * j; const LAS float* s = scr + (8 * c) * 33 + n;
;             u32x4 o; o.x = pk2(s[0 * 33] * gl[0], s[1 * 33] * gl[1]); o.y = pk2(s[2 * 33] * gl[2], s[3 * 33] * gl[3]); o.z = pk2(s[4 * 33] * gl[4], s[5 * 33] * gl[5]); o.w = pk2(s[6 * 33] * gl[6], s[7 * 33] * gl[7]);
;             __builtin_nontemporal_store(o, (u32x4*)(WT + (size_t)(v0 + n) * K + k0 + 8 * c)); }
;         LDS_WAIT(); asm volatile("" ::: "memory");
	v_bfe_u32 v10, v7, 16, 1
	v_add3_u32 v7, v7, v10, s73
	s_waitcnt lgkmcnt(0)
	v_bfe_u32 v10, v9, 16, 1
	v_lshrrev_b32_e32 v7, 16, v7
	v_add3_u32 v9, v9, v10, s73
	v_and_or_b32 v9, v9, s72, v7
	ds_read_b32 v7, v4 offset:528
	ds_read_b32 v10, v4 offset:660
	s_waitcnt lgkmcnt(1)
	v_bfe_u32 v11, v7, 16, 1
	v_add3_u32 v7, v7, v11, s73
	s_waitcnt lgkmcnt(0)
	v_bfe_u32 v11, v10, 16, 1
	v_lshrrev_b32_e32 v7, 16, v7
	v_add3_u32 v10, v10, v11, s73
	v_and_or_b32 v10, v10, s72, v7
	ds_read_b32 v7, v4 offset:792
	ds_read_b32 v11, v4 offset:924
	s_waitcnt lgkmcnt(1)
	v_bfe_u32 v13, v7, 16, 1
	v_add3_u32 v7, v7, v13, s73
	s_waitcnt lgkmcnt(0)
	v_bfe_u32 v13, v11, 16, 1
	v_lshrrev_b32_e32 v7, 16, v7
	v_add3_u32 v11, v11, v13, s73
	v_and_or_b32 v11, v11, s72, v7
	v_lshl_add_u64 v[6:7], v[0:1], 0, v[184:185]
	flat_store_dwordx4 v[6:7], v[8:11] nt
	ds_read_b32 v6, v4 offset:32
	ds_read_b32 v7, v4 offset:164
	v_lshlrev_b32_e32 v184, 12, v5
	s_waitcnt lgkmcnt(0)
	v_bfe_u32 v8, v6, 16, 1
	v_add3_u32 v6, v6, v8, s73
	v_bfe_u32 v8, v7, 16, 1
	v_lshrrev_b32_e32 v6, 16, v6
	v_add3_u32 v7, v7, v8, s73
	v_and_or_b32 v6, v7, s72, v6
	ds_read_b32 v7, v4 offset:296
	ds_read_b32 v8, v4 offset:428
	s_waitcnt lgkmcnt(0)
	v_bfe_u32 v9, v7, 16, 1
	v_add3_u32 v7, v7, v9, s73
	v_bfe_u32 v9, v8, 16, 1
	v_lshrrev_b32_e32 v7, 16, v7
	v_add3_u32 v8, v8, v9, s73
	v_and_or_b32 v7, v8, s72, v7
	ds_read_b32 v8, v4 offset:560
	ds_read_b32 v9, v4 offset:692
	s_waitcnt lgkmcnt(0)
	v_bfe_u32 v10, v8, 16, 1
	v_add3_u32 v8, v8, v10, s73
	v_bfe_u32 v10, v9, 16, 1
	v_lshrrev_b32_e32 v8, 16, v8
	v_add3_u32 v9, v9, v10, s73
	v_and_or_b32 v8, v9, s72, v8
	ds_read_b32 v9, v4 offset:824
	ds_read_b32 v10, v4 offset:956
	s_waitcnt lgkmcnt(0)
	v_bfe_u32 v11, v9, 16, 1
	v_add3_u32 v9, v9, v11, s73
	v_bfe_u32 v11, v10, 16, 1
	v_lshrrev_b32_e32 v9, 16, v9
	v_add3_u32 v10, v10, v11, s73
	v_and_or_b32 v9, v10, s72, v9
	v_lshl_add_u64 v[10:11], v[0:1], 0, v[184:185]
	flat_store_dwordx4 v[10:11], v[6:9] nt
	ds_read_b32 v5, v4 offset:64
	ds_read_b32 v6, v4 offset:196
	v_lshlrev_b32_e32 v184, 12, v3
	s_waitcnt lgkmcnt(0)
	v_bfe_u32 v7, v5, 16, 1
	v_add3_u32 v5, v5, v7, s73
	v_bfe_u32 v7, v6, 16, 1
	v_lshrrev_b32_e32 v5, 16, v5
	v_add3_u32 v6, v6, v7, s73
	v_and_or_b32 v6, v6, s72, v5
	ds_read_b32 v5, v4 offset:328
	ds_read_b32 v7, v4 offset:460
	s_waitcnt lgkmcnt(0)
	v_bfe_u32 v8, v5, 16, 1
	v_add3_u32 v5, v5, v8, s73
	v_bfe_u32 v8, v7, 16, 1
	v_lshrrev_b32_e32 v5, 16, v5
	v_add3_u32 v7, v7, v8, s73
	v_and_or_b32 v7, v7, s72, v5
	ds_read_b32 v5, v4 offset:592
	ds_read_b32 v8, v4 offset:724
	s_waitcnt lgkmcnt(0)
	v_bfe_u32 v9, v5, 16, 1
	v_add3_u32 v5, v5, v9, s73
	v_bfe_u32 v9, v8, 16, 1
	v_lshrrev_b32_e32 v5, 16, v5
	v_add3_u32 v8, v8, v9, s73
	v_and_or_b32 v8, v8, s72, v5
	ds_read_b32 v5, v4 offset:856
	ds_read_b32 v9, v4 offset:988
	s_waitcnt lgkmcnt(0)
	v_bfe_u32 v10, v5, 16, 1
	v_add3_u32 v5, v5, v10, s73
	v_bfe_u32 v10, v9, 16, 1
	v_lshrrev_b32_e32 v5, 16, v5
	v_add3_u32 v9, v9, v10, s73
	v_and_or_b32 v9, v9, s72, v5
	v_lshl_add_u64 v[10:11], v[0:1], 0, v[184:185]
	flat_store_dwordx4 v[10:11], v[6:9] nt
	ds_read_b32 v3, v4 offset:96
	ds_read_b32 v5, v4 offset:228
	v_lshlrev_b32_e32 v184, 12, v2
	v_lshl_add_u64 v[0:1], v[0:1], 0, v[184:185]
	s_waitcnt lgkmcnt(0)
	v_bfe_u32 v6, v3, 16, 1
	v_add3_u32 v3, v3, v6, s73
	v_bfe_u32 v6, v5, 16, 1
	v_lshrrev_b32_e32 v3, 16, v3
	v_add3_u32 v5, v5, v6, s73
	v_and_or_b32 v6, v5, s72, v3
	ds_read_b32 v3, v4 offset:360
	ds_read_b32 v5, v4 offset:492
	s_waitcnt lgkmcnt(0)
	v_bfe_u32 v7, v3, 16, 1
	v_add3_u32 v3, v3, v7, s73
	v_bfe_u32 v7, v5, 16, 1
	v_lshrrev_b32_e32 v3, 16, v3
	v_add3_u32 v5, v5, v7, s73
	v_and_or_b32 v7, v5, s72, v3
	ds_read_b32 v3, v4 offset:624
	ds_read_b32 v5, v4 offset:756
	s_waitcnt lgkmcnt(0)
	v_bfe_u32 v8, v3, 16, 1
	v_add3_u32 v3, v3, v8, s73
	v_bfe_u32 v8, v5, 16, 1
	v_lshrrev_b32_e32 v3, 16, v3
	v_add3_u32 v5, v5, v8, s73
	v_and_or_b32 v8, v5, s72, v3
	ds_read_b32 v3, v4 offset:888
	ds_read_b32 v4, v4 offset:1020
	s_waitcnt lgkmcnt(0)
	v_bfe_u32 v5, v3, 16, 1
	v_add3_u32 v3, v3, v5, s73
	v_bfe_u32 v5, v4, 16, 1
	v_lshrrev_b32_e32 v3, 16, v3
	v_add3_u32 v4, v4, v5, s73
	v_and_or_b32 v9, v4, s72, v3
	flat_store_dwordx4 v[0:1], v[6:9] nt
	s_waitcnt lgkmcnt(0)

; #define LAS __attribute__((address_space(3)))
; __device__ __forceinline__ void atomic_addq(i64* p, float v, float scale) { (void)__hip_atomic_fetch_add((unsigned long long*)p, (unsigned long long)(i64)__builtin_rintf(v * scale), __ATOMIC_RELAXED, __HIP_MEMORY_SCOPE_AGENT); }
; #define LDS_WAIT() asm volatile("s_waitcnt lgkmcnt(0)" ::: "memory")
; __device__ __forceinline__ float bf_round(float f) { return __uint_as_float(f2bf(f) << 16); }
; #define INP(i) (kargs()->in[i])
; template <class Map>
; __device__ __forceinline__ void conv_item(const Frame& F, int it, const float* W, int K, int N, bf16_t* WT, const float* gk, int gmask, float gmul, const float* bk, i64* cs, i64* bw, Map map) {
;     ...
;         const int kb = it / nblk, nb = it % nblk, k0 = 64 * kb, n0 = 32 * nb, v0 = map(n0);
; #pragma unroll
;         for (int i = 0; i < 8; ++i) { const int kk = 8 * i + (lane >> 3), c4 = (lane & 7) * 4;
;             const f32x4 w4 = __builtin_nontemporal_load((const f32x4*)(W + (size_t)(k0 + kk) * N + n0 + c4)); LAS float* d = scr + kk * 33 + c4; d[0] = w4[0]; d[1] = w4[1]; d[2] = w4[2]; d[3] = w4[3]; }
;         LDS_WAIT(); asm volatile("" ::: "memory");
;         if (bk) {
;             const int n = lane & 31, kh = lane >> 5; float sb = 0.f, sc = 0.f;
; #pragma unroll 8
;             for (int j = 0; j < 32; ++j) { const int kk = kh * 32 + j; const float w = scr[kk * 33 + n]; sb += bk[k0 + kk] * w; sc += bf_round(gk[(k0 + kk) & gmask] * gmul * w); }
;             { auto r = __builtin_amdgcn_permlane32_swap(__float_as_uint(sb), __float_as_uint(sb), false, false); sb = __uint_as_float(r[0]) + __uint_as_float(r[1]); }
;             { auto r = __builtin_amdgcn_permlane32_swap(__float_as_uint(sc), __float_as_uint(sc), false, false); sc = __uint_as_float(r[0]) + __uint_as_float(r[1]); }
;             if (lane < 32) { atomic_addq(bw + v0 + n, sb, FX_COL); atomic_addq(cs + v0 + n, sc, FX_COL); }
;         }
;         const int c = lane & 7; float gl[8];
; #pragma unroll
;         for (int i = 0; i < 8; ++i) gl[i] = gk ? gk[(k0 + 8 * c + i) & gmask] * gmul : 1.0f;
; __device__ BG_ATTR void bg_item(const Frame& F, unsigned char* ws, const int L, int id) {
;     ...
;         if (id < NI_UKV) { conv_item(F, id, INP(6) + (size_t)j * MLA_RANK * 4096, MLA_RANK, 4096, Wukv, INP(4) + j * MLA_RANK, MLA_RANK - 1, 1.f, nullptr, nullptr, nullptr, MapIdent()); return; } id -= NI_UKV;
.LBB0_292:
	s_andn2_b64 vcc, exec, s[6:7]
	s_cbranch_vccnz .LBB0_310
	v_readlane_b32 s12, v252, 14
	v_readlane_b32 s13, v252, 15
	s_mov_b64 s[6:7], s[12:13]
	s_load_dwordx2 s[6:7], s[6:7], 0x30
	s_add_i32 s16, s91, 0xfffff8c0
	v_mov_b32_e32 v13, v220
	v_mov_b32_e32 v7, v185
	s_waitcnt lgkmcnt(0)
	s_add_u32 s26, s6, s60
	s_addc_u32 s27, s7, s61
	v_readlane_b32 s6, v252, 12
	v_readlane_b32 s7, v252, 13
	s_load_dwordx2 s[24:25], s[12:13], 0x20
	s_lshl_b64 s[12:13], s[62:63], 2
	s_waitcnt lgkmcnt(0)
	s_add_u32 s12, s24, s12
	s_addc_u32 s13, s25, s13
	s_lshr_b32 s17, s16, 1
	s_lshl_b32 s16, s16, 5
	s_and_b32 s16, s16, 0xfe0
	s_and_b32 s17, s17, 0x7fc0
	s_lshl_b32 s40, s16, 2
	v_bfe_u32 v11, v13, 3, 3
	s_add_u32 s26, s26, s40
	v_lshlrev_b32_e32 v0, 4, v13
	s_addc_u32 s27, s27, 0
	v_and_b32_e32 v184, 0x70, v0
	v_or_b32_e32 v0, s17, v11
	v_lshl_add_u64 v[4:5], s[26:27], 0, v[184:185]
	v_lshlrev_b32_e32 v6, 14, v0
	v_lshl_add_u64 v[0:1], v[4:5], 0, v[6:7]
	global_load_dwordx4 v[132:135], v[0:1], off nt
	v_mul_u32_u24_e32 v7, 0x84, v11
	v_add3_u32 v7, s79, v184, v7
	v_or_b32_e32 v10, 8, v11
	v_add_u32_e32 v8, 0x420, v7
	v_or_b32_e32 v9, 16, v11
	v_add_u32_e32 v14, 0xc60, v7
	v_and_b32_e32 v13, 7, v13
	s_cmp_lg_u64 s[24:25], 0
	s_cselect_b64 s[26:27], -1, 0
	s_cmp_eq_u64 s[24:25], 0
	v_or_b32_e32 v0, s17, v10
	v_lshlrev_b32_e32 v184, 14, v0
	v_lshl_add_u64 v[0:1], v[4:5], 0, v[184:185]
	global_load_dwordx4 v[136:139], v[0:1], off nt
	v_add_u32_e32 v0, 0x428, v7
	v_or_b32_e32 v0, s17, v9
	v_lshlrev_b32_e32 v184, 14, v0
	v_lshl_add_u64 v[0:1], v[4:5], 0, v[184:185]
	global_load_dwordx4 v[140:143], v[0:1], off nt
	v_add_u32_e32 v8, 0x840, v7
	v_add_u32_e32 v0, 0x848, v7
	v_or_b32_e32 v8, 24, v11
	v_or_b32_e32 v0, s17, v8
	v_lshlrev_b32_e32 v184, 14, v0
	v_lshl_add_u64 v[0:1], v[4:5], 0, v[184:185]
	global_load_dwordx4 v[144:147], v[0:1], off nt
	v_or_b32_e32 v184, 0x80000, v6
	v_add_u32_e32 v0, 0xc68, v7
	v_lshl_add_u64 v[0:1], v[4:5], 0, v[184:185]
	global_load_dwordx4 v[148:151], v[0:1], off nt
	v_add_u32_e32 v14, 0x1080, v7
	v_or_b32_e32 v184, 0xa0000, v6
	v_add_u32_e32 v0, 0x1088, v7
	v_lshl_add_u64 v[0:1], v[4:5], 0, v[184:185]
	global_load_dwordx4 v[152:155], v[0:1], off nt
	v_add_u32_e32 v14, 0x14a0, v7
	v_or_b32_e32 v184, 0xc0000, v6
	v_add_u32_e32 v0, 0x14a8, v7
	v_lshl_add_u64 v[0:1], v[4:5], 0, v[184:185]
	global_load_dwordx4 v[156:159], v[0:1], off nt
	v_add_u32_e32 v14, 0x18c0, v7
	v_or_b32_e32 v184, 0xe0000, v6
	v_add_u32_e32 v0, 0x18c8, v7
	v_lshl_add_u64 v[0:1], v[4:5], 0, v[184:185]
	global_load_dwordx4 v[160:163], v[0:1], off nt
	v_add_u32_e32 v4, 0x1ce0, v7
	v_lshlrev_b32_e32 v14, 3, v13
	v_add_u32_e32 v0, 0x1ce8, v7
	s_waitcnt vmcnt(0)
	v_add_u32_e32 v164, 0x0, v7
	ds_write2_b32 v164, v132, v133 offset1:1
	ds_write2_b32 v164, v134, v135 offset0:2 offset1:3
	v_add_u32_e32 v164, 0x420, v7
	ds_write2_b32 v164, v136, v137 offset1:1
	ds_write2_b32 v164, v138, v139 offset0:2 offset1:3
	v_add_u32_e32 v164, 0x840, v7
	ds_write2_b32 v164, v140, v141 offset1:1
	ds_write2_b32 v164, v142, v143 offset0:2 offset1:3
	v_add_u32_e32 v164, 0xc60, v7
	ds_write2_b32 v164, v144, v145 offset1:1
	ds_write2_b32 v164, v146, v147 offset0:2 offset1:3
	v_add_u32_e32 v164, 0x1080, v7
	ds_write2_b32 v164, v148, v149 offset1:1
	ds_write2_b32 v164, v150, v151 offset0:2 offset1:3
	v_add_u32_e32 v164, 0x14a0, v7
	ds_write2_b32 v164, v152, v153 offset1:1
	ds_write2_b32 v164, v154, v155 offset0:2 offset1:3
	v_add_u32_e32 v164, 0x18c0, v7
	ds_write2_b32 v164, v156, v157 offset1:1
	ds_write2_b32 v164, v158, v159 offset0:2 offset1:3
	v_add_u32_e32 v164, 0x1ce0, v7
	ds_write2_b32 v164, v160, v161 offset1:1
	ds_write2_b32 v164, v162, v163 offset0:2 offset1:3
	s_waitcnt lgkmcnt(0)
	v_or_b32_e32 v1, s17, v14
	v_mov_b32_e32 v0, 1.0
	v_lshlrev_b32_e32 v15, 2, v1
	v_mov_b32_e32 v2, 1.0
	s_cbranch_scc1 .LBB0_295
	global_load_dword v2, v15, s[12:13]

; #define LAS __attribute__((address_space(3)))
; __device__ __forceinline__ void atomic_addq(i64* p, float v, float scale) { (void)__hip_atomic_fetch_add((unsigned long long*)p, (unsigned long long)(i64)__builtin_rintf(v * scale), __ATOMIC_RELAXED, __HIP_MEMORY_SCOPE_AGENT); }
; #define LDS_WAIT() asm volatile("s_waitcnt lgkmcnt(0)" ::: "memory")
; __device__ __forceinline__ float bf_round(float f) { return __uint_as_float(f2bf(f) << 16); }
; #define INP(i) (kargs()->in[i])
; template <class Map>
; __device__ __forceinline__ void conv_item(const Frame& F, int it, const float* W, int K, int N, bf16_t* WT, const float* gk, int gmask, float gmul, const float* bk, i64* cs, i64* bw, Map map) {
;     ...
;         const int kb = it / nblk, nb = it % nblk, k0 = 64 * kb, n0 = 32 * nb, v0 = map(n0);
; #pragma unroll
;         for (int i = 0; i < 8; ++i) { const int kk = 8 * i + (lane >> 3), c4 = (lane & 7) * 4;
;             const f32x4 w4 = __builtin_nontemporal_load((const f32x4*)(W + (size_t)(k0 + kk) * N + n0 + c4)); LAS float* d = scr + kk * 33 + c4; d[0] = w4[0]; d[1] = w4[1]; d[2] = w4[2]; d[3] = w4[3]; }
;         LDS_WAIT(); asm volatile("" ::: "memory");
;         if (bk) {
;             const int n = lane & 31, kh = lane >> 5; float sb = 0.f, sc = 0.f;
; #pragma unroll 8
;             for (int j = 0; j < 32; ++j) { const int kk = kh * 32 + j; const float w = scr[kk * 33 + n]; sb += bk[k0 + kk] * w; sc += bf_round(gk[(k0 + kk) & gmask] * gmul * w); }
;             { auto r = __builtin_amdgcn_permlane32_swap(__float_as_uint(sb), __float_as_uint(sb), false, false); sb = __uint_as_float(r[0]) + __uint_as_float(r[1]); }
;             { auto r = __builtin_amdgcn_permlane32_swap(__float_as_uint(sc), __float_as_uint(sc), false, false); sc = __uint_as_float(r[0]) + __uint_as_float(r[1]); }
;             if (lane < 32) { atomic_addq(bw + v0 + n, sb, FX_COL); atomic_addq(cs + v0 + n, sc, FX_COL); }
;         }
;         const int c = lane & 7; float gl[8];
; #pragma unroll
;         for (int i = 0; i < 8; ++i) gl[i] = gk ? gk[(k0 + 8 * c + i) & gmask] * gmul : 1.0f;
; __device__ BG_ATTR void bg_item(const Frame& F, unsigned char* ws, const int L, int id) {
;     ...
;         if (id < NI_UQ) { conv_item(F, id, INP(5) + (size_t)j * MLA_RANK * 3072, MLA_RANK, 3072, Wuq, INP(3) + j * MLA_RANK, MLA_RANK - 1, 1.f, nullptr, nullptr, nullptr, MapMlaUq()); return; } id -= NI_UQ;
.LBB0_316:
	s_waitcnt lgkmcnt(0)
	s_add_u32 s26, s12, s43
	s_addc_u32 s27, s13, s21
	s_lshl_b64 s[12:13], s[62:63], 2
	s_add_u32 s12, s24, s12
	s_addc_u32 s13, s25, s13
	s_lshl_b32 s17, s40, 6
	s_and_b32 s40, 0xffff, s41
	s_and_b32 s16, s17, 0xffc0
	s_lshl_b32 s40, s40, 2
	v_bfe_u32 v11, v0, 3, 3
	s_add_u32 s26, s26, s40
	v_lshlrev_b32_e32 v1, 4, v0
	s_addc_u32 s27, s27, 0
	v_and_b32_e32 v184, 0x70, v1
	v_or_b32_e32 v1, s16, v11
	v_lshl_add_u64 v[6:7], s[26:27], 0, v[184:185]
	v_mul_u32_u24_e32 v2, 0x3000, v1
	v_mov_b32_e32 v3, v185
	v_lshl_add_u64 v[2:3], v[6:7], 0, v[2:3]
	global_load_dwordx4 v[132:135], v[2:3], off nt
	v_mul_u32_u24_e32 v8, 0x84, v11
	v_add3_u32 v13, s79, v184, v8
	v_or_b32_e32 v10, 8, v11
	v_add_u32_e32 v8, 0x420, v13
	v_or_b32_e32 v9, 16, v11
	v_add_u32_e32 v14, 0xc60, v13
	s_cmp_lg_u64 s[24:25], 0
	s_cselect_b64 s[26:27], -1, 0
	s_and_b32 s17, s17, 0x1c0
	s_cmp_eq_u64 s[24:25], 0
	v_or_b32_e32 v2, s16, v10
	v_mul_u32_u24_e32 v184, 0x3000, v2
	v_lshl_add_u64 v[2:3], v[6:7], 0, v[184:185]
	global_load_dwordx4 v[136:139], v[2:3], off nt
	v_add_u32_e32 v2, 0x428, v13
	v_or_b32_e32 v2, s16, v9
	v_mul_u32_u24_e32 v184, 0x3000, v2
	v_lshl_add_u64 v[2:3], v[6:7], 0, v[184:185]
	global_load_dwordx4 v[140:143], v[2:3], off nt
	v_add_u32_e32 v8, 0x840, v13
	v_add_u32_e32 v2, 0x848, v13
	v_or_b32_e32 v8, 24, v11
	v_or_b32_e32 v2, s16, v8
	v_mul_u32_u24_e32 v184, 0x3000, v2
	v_lshl_add_u64 v[2:3], v[6:7], 0, v[184:185]
	global_load_dwordx4 v[144:147], v[2:3], off nt
	v_add_u32_e32 v2, 0xc68, v13
	v_or_b32_e32 v2, 32, v1
	v_mul_u32_u24_e32 v184, 0x3000, v2
	v_lshl_add_u64 v[2:3], v[6:7], 0, v[184:185]
	global_load_dwordx4 v[148:151], v[2:3], off nt
	v_add_u32_e32 v14, 0x1080, v13
	v_add_u32_e32 v2, 0x1088, v13
	v_or_b32_e32 v2, 40, v1
	v_mul_u32_u24_e32 v184, 0x3000, v2
	v_lshl_add_u64 v[2:3], v[6:7], 0, v[184:185]
	global_load_dwordx4 v[152:155], v[2:3], off nt
	v_add_u32_e32 v14, 0x14a0, v13
	v_add_u32_e32 v2, 0x14a8, v13
	v_or_b32_e32 v2, 48, v1
	v_mul_u32_u24_e32 v184, 0x3000, v2
	v_lshl_add_u64 v[2:3], v[6:7], 0, v[184:185]
	global_load_dwordx4 v[156:159], v[2:3], off nt
	v_add_u32_e32 v14, 0x18c0, v13
	v_or_b32_e32 v1, 56, v1
	v_mul_u32_u24_e32 v184, 0x3000, v1
	v_add_u32_e32 v1, 0x1ce0, v13
	v_add_u32_e32 v2, 0x18c8, v13
	v_lshl_add_u64 v[2:3], v[6:7], 0, v[184:185]
	global_load_dwordx4 v[160:163], v[2:3], off nt
	v_add_u32_e32 v1, 0x1ce8, v13
	s_waitcnt vmcnt(0)
	v_add_u32_e32 v164, 0x0, v13
	ds_write2_b32 v164, v132, v133 offset1:1
	ds_write2_b32 v164, v134, v135 offset0:2 offset1:3
	v_add_u32_e32 v164, 0x420, v13
	ds_write2_b32 v164, v136, v137 offset1:1
	ds_write2_b32 v164, v138, v139 offset0:2 offset1:3
	v_add_u32_e32 v164, 0x840, v13
	ds_write2_b32 v164, v140, v141 offset1:1
	ds_write2_b32 v164, v142, v143 offset0:2 offset1:3
	v_add_u32_e32 v164, 0xc60, v13
	ds_write2_b32 v164, v144, v145 offset1:1
	ds_write2_b32 v164, v146, v147 offset0:2 offset1:3
	v_add_u32_e32 v164, 0x1080, v13
	ds_write2_b32 v164, v148, v149 offset1:1
	ds_write2_b32 v164, v150, v151 offset0:2 offset1:3
	v_add_u32_e32 v164, 0x14a0, v13
	ds_write2_b32 v164, v152, v153 offset1:1
	ds_write2_b32 v164, v154, v155 offset0:2 offset1:3
	v_add_u32_e32 v164, 0x18c0, v13
	ds_write2_b32 v164, v156, v157 offset1:1
	ds_write2_b32 v164, v158, v159 offset0:2 offset1:3
	v_add_u32_e32 v164, 0x1ce0, v13
	ds_write2_b32 v164, v160, v161 offset1:1
	ds_write2_b32 v164, v162, v163 offset0:2 offset1:3
	s_waitcnt lgkmcnt(0)
	v_and_b32_e32 v13, 7, v0
	v_lshlrev_b32_e32 v14, 3, v13
	v_or_b32_e32 v1, s17, v14
	v_mov_b32_e32 v0, 1.0
	v_lshlrev_b32_e32 v15, 2, v1
	v_mov_b32_e32 v2, 1.0
	s_cbranch_scc1 .LBB0_318
	global_load_dword v2, v15, s[12:13]

; #define LAS __attribute__((address_space(3)))
; #define INP(i) (kargs()->in[i])
; template <class Map>
; __device__ __forceinline__ void conv_item(const Frame& F, int it, const float* W, int K, int N, bf16_t* WT, const float* gk, int gmask, float gmul, const float* bk, i64* cs, i64* bw, Map map) {
;     ...
;         const int kb = it / nblk, nb = it % nblk, k0 = 64 * kb, n0 = 32 * nb, v0 = map(n0);
; #pragma unroll
;         for (int i = 0; i < 8; ++i) { const int kk = 8 * i + (lane >> 3), c4 = (lane & 7) * 4;
;             const f32x4 w4 = __builtin_nontemporal_load((const f32x4*)(W + (size_t)(k0 + kk) * N + n0 + c4)); LAS float* d = scr + kk * 33 + c4; d[0] = w4[0]; d[1] = w4[1]; d[2] = w4[2]; d[3] = w4[3]; }
;         LDS_WAIT(); asm volatile("" ::: "memory");
;         if (bk) {
;             const int n = lane & 31, kh = lane >> 5; float sb = 0.f, sc = 0.f;
; #pragma unroll 8
;             for (int j = 0; j < 32; ++j) { const int kk = kh * 32 + j; const float w = scr[kk * 33 + n]; sb += bk[k0 + kk] * w; sc += bf_round(gk[(k0 + kk) & gmask] * gmul * w); }
;             { auto r = __builtin_amdgcn_permlane32_swap(__float_as_uint(sb), __float_as_uint(sb), false, false); sb = __uint_as_float(r[0]) + __uint_as_float(r[1]); }
;             { auto r = __builtin_amdgcn_permlane32_swap(__float_as_uint(sc), __float_as_uint(sc), false, false); sc = __uint_as_float(r[0]) + __uint_as_float(r[1]); }
;             if (lane < 32) { atomic_addq(bw + v0 + n, sb, FX_COL); atomic_addq(cs + v0 + n, sc, FX_COL); }
;         }
;         const int c = lane & 7; float gl[8];
; #pragma unroll
;         for (int i = 0; i < 8; ++i) gl[i] = gk ? gk[(k0 + 8 * c + i) & gmask] * gmul : 1.0f;
; #pragma unroll
;         for (int j = 0; j < 4; ++j) { const int n = (lane >> 3) + 8 * j; const LAS float* s = scr + (8 * c) * 33 + n;
;             u32x4 o; o.x = pk2(s[0 * 33] * gl[0], s[1 * 33] * gl[1]); o.y = pk2(s[2 * 33] * gl[2], s[3 * 33] * gl[3]); o.z = pk2(s[4 * 33] * gl[4], s[5 * 33] * gl[5]); o.w = pk2(s[6 * 33] * gl[6], s[7 * 33] * gl[7]);
;             __builtin_nontemporal_store(o, (u32x4*)(WT + (size_t)(v0 + n) * K + k0 + 8 * c)); }
; __device__ BG_ATTR void bg_item(const Frame& F, unsigned char* ws, const int L, int id) {
;     ...
;     if (id < NI_P) { conv_item(F, id, INP(18) + (size_t)L * PLE * DM, PLE, DM, Wp, nullptr, 0, 1.f, nullptr, nullptr, nullptr, MapIdent()); return; } id -= NI_P;
.LBB0_450:
	s_andn2_saveexec_b64 s[86:87], s[12:13]
	s_cbranch_execz .LBB0_452
	v_readlane_b32 s12, v252, 14
	v_readlane_b32 s13, v252, 15
	s_load_dwordx2 s[12:13], s[12:13], 0x90
	v_readlane_b32 s16, v255, 35
	v_readlane_b32 s17, v255, 36
	v_and_b32_e32 v15, 0xc0, v0
	v_lshlrev_b32_e32 v0, 5, v0
	s_waitcnt lgkmcnt(0)
	s_add_u32 s16, s12, s16
	s_addc_u32 s17, s13, s17
	v_readlane_b32 s12, v252, 12
	v_readlane_b32 s13, v252, 13
	v_mov_b32_e32 v14, v220
	v_and_b32_e32 v2, 0x7e0, v0
	v_lshlrev_b32_e32 v184, 2, v2
	v_bfe_u32 v7, v14, 3, 3
	v_lshlrev_b32_e32 v3, 4, v14
	v_lshl_add_u64 v[0:1], s[16:17], 0, v[184:185]
	v_and_b32_e32 v184, 0x70, v3
	v_or_b32_e32 v3, v7, v15
	v_lshl_add_u64 v[0:1], v[0:1], 0, v[184:185]
	v_lshlrev_b32_e32 v12, 13, v3
	v_mov_b32_e32 v13, v185
	v_lshl_add_u64 v[4:5], v[0:1], 0, v[12:13]
	global_load_dwordx4 v[132:135], v[4:5], off nt
	v_mul_u32_u24_e32 v3, 0x84, v7
	v_or_b32_e32 v6, 8, v7
	v_add3_u32 v13, s79, v184, v3
	v_or_b32_e32 v3, v6, v15
	v_lshlrev_b32_e32 v184, 13, v3
	v_lshl_add_u64 v[4:5], v[0:1], 0, v[184:185]
	v_add_u32_e32 v3, 0x420, v13
	v_or_b32_e32 v6, v6, v2
	global_load_dwordx4 v[136:139], v[4:5], off nt
	v_or_b32_e32 v4, 16, v7
	v_add_u32_e32 v3, 0x428, v13
	v_or_b32_e32 v3, v4, v15
	v_lshlrev_b32_e32 v184, 13, v3
	v_lshl_add_u64 v[8:9], v[0:1], 0, v[184:185]
	global_load_dwordx4 v[140:143], v[8:9], off nt
	v_add_u32_e32 v3, 0x840, v13
	v_or_b32_e32 v4, v4, v2
	v_add_u32_e32 v3, 0x848, v13
	v_or_b32_e32 v3, 24, v7
	v_or_b32_e32 v5, v3, v15
	v_lshlrev_b32_e32 v184, 13, v5
	v_lshl_add_u64 v[8:9], v[0:1], 0, v[184:185]
	global_load_dwordx4 v[144:147], v[8:9], off nt
	v_add_u32_e32 v5, 0xc60, v13
	v_or_b32_e32 v184, 0x40000, v12
	v_add_u32_e32 v5, 0xc68, v13
	v_lshl_add_u64 v[8:9], v[0:1], 0, v[184:185]
	global_load_dwordx4 v[148:151], v[8:9], off nt
	v_add_u32_e32 v5, 0x1080, v13
	v_or_b32_e32 v184, 0x50000, v12
	v_add_u32_e32 v5, 0x1088, v13
	v_lshl_add_u64 v[8:9], v[0:1], 0, v[184:185]
	global_load_dwordx4 v[152:155], v[8:9], off nt
	v_add_u32_e32 v5, 0x14a0, v13
	v_or_b32_e32 v184, 0x60000, v12
	v_add_u32_e32 v5, 0x14a8, v13
	v_lshl_add_u64 v[8:9], v[0:1], 0, v[184:185]
	global_load_dwordx4 v[156:159], v[8:9], off nt
	v_add_u32_e32 v5, 0x18c0, v13
	v_or_b32_e32 v184, 0x70000, v12
	v_lshl_add_u64 v[0:1], v[0:1], 0, v[184:185]
	v_lshlrev_b32_e32 v184, 1, v15
	v_add_u32_e32 v5, 0x18c8, v13
	global_load_dwordx4 v[160:163], v[0:1], off nt
	v_add_u32_e32 v0, 0x1ce0, v13
	v_and_b32_e32 v5, 7, v14
	v_add_u32_e32 v0, 0x1ce8, v13
	s_waitcnt vmcnt(0)
	v_add_u32_e32 v164, 0x0, v13
	ds_write2_b32 v164, v132, v133 offset1:1
	ds_write2_b32 v164, v134, v135 offset0:2 offset1:3
	v_add_u32_e32 v164, 0x420, v13
	ds_write2_b32 v164, v136, v137 offset1:1
	ds_write2_b32 v164, v138, v139 offset0:2 offset1:3
	v_add_u32_e32 v164, 0x840, v13
	ds_write2_b32 v164, v140, v141 offset1:1
	ds_write2_b32 v164, v142, v143 offset0:2 offset1:3
	v_add_u32_e32 v164, 0xc60, v13
	ds_write2_b32 v164, v144, v145 offset1:1
	ds_write2_b32 v164, v146, v147 offset0:2 offset1:3
	v_add_u32_e32 v164, 0x1080, v13
	ds_write2_b32 v164, v148, v149 offset1:1
	ds_write2_b32 v164, v150, v151 offset0:2 offset1:3
	v_add_u32_e32 v164, 0x14a0, v13
	ds_write2_b32 v164, v152, v153 offset1:1
	ds_write2_b32 v164, v154, v155 offset0:2 offset1:3
	v_add_u32_e32 v164, 0x18c0, v13
	ds_write2_b32 v164, v156, v157 offset1:1
	ds_write2_b32 v164, v158, v159 offset0:2 offset1:3
	v_add_u32_e32 v164, 0x1ce0, v13
	ds_write2_b32 v164, v160, v161 offset1:1
	ds_write2_b32 v164, v162, v163 offset0:2 offset1:3
	s_waitcnt lgkmcnt(0)
	v_mul_u32_u24_e32 v8, 0x420, v5
	v_lshl_add_u64 v[0:1], s[12:13], 0, v[184:185]
	v_lshlrev_b32_e32 v184, 4, v5
	v_lshlrev_b32_e32 v5, 2, v7
	v_add3_u32 v5, s79, v8, v5
	ds_read_b32 v8, v5
	ds_read_b32 v9, v5 offset:132
	v_lshl_add_u64 v[0:1], v[0:1], 0, v[184:185]
	s_mov_b64 s[12:13], 0x7a00000
	v_or_b32_e32 v7, v7, v2
	s_waitcnt lgkmcnt(1)
	v_bfe_u32 v10, v8, 16, 1
	v_add3_u32 v8, v8, v10, s73
	s_waitcnt lgkmcnt(0)
	v_bfe_u32 v10, v9, 16, 1
	v_lshrrev_b32_e32 v8, 16, v8
	v_add3_u32 v9, v9, v10, s73
	v_and_or_b32 v8, v9, s72, v8
	ds_read_b32 v9, v5 offset:264
	ds_read_b32 v10, v5 offset:396
	v_lshl_add_u64 v[0:1], v[0:1], 0, s[12:13]
	v_lshlrev_b32_e32 v184, 9, v7
	v_or_b32_e32 v2, v3, v2
	s_waitcnt lgkmcnt(1)
; #define LAS __attribute__((address_space(3)))
; #define LDS_WAIT() asm volatile("s_waitcnt lgkmcnt(0)" ::: "memory")
; __device__ __forceinline__ unsigned pk2(float lo, float hi) { return f2bf(lo) | (f2bf(hi) << 16); }
; template <class Map>
; __device__ __forceinline__ void conv_item(const Frame& F, int it, const float* W, int K, int N, bf16_t* WT, const float* gk, int gmask, float gmul, const float* bk, i64* cs, i64* bw, Map map) {
;     ...
;         const int c = lane & 7; float gl[8];
; #pragma unroll
;         for (int i = 0; i < 8; ++i) gl[i] = gk ? gk[(k0 + 8 * c + i) & gmask] * gmul : 1.0f;
; #pragma unroll
;         for (int j = 0; j < 4; ++j) { const int n = (lane >> 3) + 8 * j; const LAS float* s = scr + (8 * c) * 33 + n;
;             u32x4 o; o.x = pk2(s[0 * 33] * gl[0], s[1 * 33] * gl[1]); o.y = pk2(s[2 * 33] * gl[2], s[3 * 33] * gl[3]); o.z = pk2(s[4 * 33] * gl[4], s[5 * 33] * gl[5]); o.w = pk2(s[6 * 33] * gl[6], s[7 * 33] * gl[7]);
;             __builtin_nontemporal_store(o, (u32x4*)(WT + (size_t)(v0 + n) * K + k0 + 8 * c)); }
;         LDS_WAIT(); asm volatile("" ::: "memory");
	v_bfe_u32 v11, v9, 16, 1
	v_add3_u32 v9, v9, v11, s73
	s_waitcnt lgkmcnt(0)
	v_bfe_u32 v11, v10, 16, 1
	v_lshrrev_b32_e32 v9, 16, v9
	v_add3_u32 v10, v10, v11, s73
	v_and_or_b32 v9, v10, s72, v9
	ds_read_b32 v10, v5 offset:528
	ds_read_b32 v11, v5 offset:660
	s_waitcnt lgkmcnt(1)
	v_bfe_u32 v12, v10, 16, 1
	v_add3_u32 v10, v10, v12, s73
	s_waitcnt lgkmcnt(0)
	v_bfe_u32 v12, v11, 16, 1
	v_lshrrev_b32_e32 v10, 16, v10
	v_add3_u32 v11, v11, v12, s73
	v_and_or_b32 v10, v11, s72, v10
	ds_read_b32 v11, v5 offset:792
	ds_read_b32 v12, v5 offset:924
	s_waitcnt lgkmcnt(1)
	v_bfe_u32 v13, v11, 16, 1
	v_add3_u32 v11, v11, v13, s73
	s_waitcnt lgkmcnt(0)
	v_bfe_u32 v13, v12, 16, 1
	v_lshrrev_b32_e32 v11, 16, v11
	v_add3_u32 v12, v12, v13, s73
	v_and_or_b32 v11, v12, s72, v11
	v_lshl_add_u64 v[12:13], v[0:1], 0, v[184:185]
	flat_store_dwordx4 v[12:13], v[8:11] nt
	ds_read_b32 v7, v5 offset:32
	ds_read_b32 v8, v5 offset:164
	v_lshlrev_b32_e32 v184, 9, v6
	s_waitcnt lgkmcnt(0)
	v_bfe_u32 v9, v7, 16, 1
	v_add3_u32 v7, v7, v9, s73
	v_bfe_u32 v9, v8, 16, 1
	v_lshrrev_b32_e32 v7, 16, v7
	v_add3_u32 v8, v8, v9, s73
	v_and_or_b32 v8, v8, s72, v7
	ds_read_b32 v7, v5 offset:296
	ds_read_b32 v9, v5 offset:428
	s_waitcnt lgkmcnt(0)
	v_bfe_u32 v10, v7, 16, 1
	v_add3_u32 v7, v7, v10, s73
	v_bfe_u32 v10, v9, 16, 1
	v_lshrrev_b32_e32 v7, 16, v7
	v_add3_u32 v9, v9, v10, s73
	v_and_or_b32 v9, v9, s72, v7
	ds_read_b32 v7, v5 offset:560
	ds_read_b32 v10, v5 offset:692
	s_waitcnt lgkmcnt(0)
	v_bfe_u32 v11, v7, 16, 1
	v_add3_u32 v7, v7, v11, s73
	v_bfe_u32 v11, v10, 16, 1
	v_lshrrev_b32_e32 v7, 16, v7
	v_add3_u32 v10, v10, v11, s73
	v_and_or_b32 v10, v10, s72, v7
	ds_read_b32 v7, v5 offset:824
	ds_read_b32 v11, v5 offset:956
	s_waitcnt lgkmcnt(0)
	v_bfe_u32 v12, v7, 16, 1
	v_add3_u32 v7, v7, v12, s73
	v_bfe_u32 v12, v11, 16, 1
	v_lshrrev_b32_e32 v7, 16, v7
	v_add3_u32 v11, v11, v12, s73
	v_and_or_b32 v11, v11, s72, v7
	v_lshl_add_u64 v[6:7], v[0:1], 0, v[184:185]
	flat_store_dwordx4 v[6:7], v[8:11] nt
	ds_read_b32 v6, v5 offset:64
	ds_read_b32 v7, v5 offset:196
	v_lshlrev_b32_e32 v184, 9, v4
	s_waitcnt lgkmcnt(0)
	v_bfe_u32 v8, v6, 16, 1
	v_add3_u32 v6, v6, v8, s73
	v_bfe_u32 v8, v7, 16, 1
	v_lshrrev_b32_e32 v6, 16, v6
	v_add3_u32 v7, v7, v8, s73
	v_and_or_b32 v6, v7, s72, v6
	ds_read_b32 v7, v5 offset:328
	ds_read_b32 v8, v5 offset:460
	s_waitcnt lgkmcnt(0)
	v_bfe_u32 v9, v7, 16, 1
	v_add3_u32 v7, v7, v9, s73
	v_bfe_u32 v9, v8, 16, 1
	v_lshrrev_b32_e32 v7, 16, v7
	v_add3_u32 v8, v8, v9, s73
	v_and_or_b32 v7, v8, s72, v7
	ds_read_b32 v8, v5 offset:592
	ds_read_b32 v9, v5 offset:724
	s_waitcnt lgkmcnt(0)
	v_bfe_u32 v10, v8, 16, 1
	v_add3_u32 v8, v8, v10, s73
	v_bfe_u32 v10, v9, 16, 1
	v_lshrrev_b32_e32 v8, 16, v8
	v_add3_u32 v9, v9, v10, s73
	v_and_or_b32 v8, v9, s72, v8
	ds_read_b32 v9, v5 offset:856
	ds_read_b32 v10, v5 offset:988
	s_waitcnt lgkmcnt(0)
	v_bfe_u32 v11, v9, 16, 1
	v_add3_u32 v9, v9, v11, s73
	v_bfe_u32 v11, v10, 16, 1
	v_lshrrev_b32_e32 v9, 16, v9
	v_add3_u32 v10, v10, v11, s73
	v_and_or_b32 v9, v10, s72, v9
	v_lshl_add_u64 v[10:11], v[0:1], 0, v[184:185]
	flat_store_dwordx4 v[10:11], v[6:9] nt
	ds_read_b32 v4, v5 offset:96
	ds_read_b32 v6, v5 offset:228
	v_lshlrev_b32_e32 v184, 9, v2
	v_lshl_add_u64 v[0:1], v[0:1], 0, v[184:185]
	s_waitcnt lgkmcnt(0)
	v_bfe_u32 v7, v4, 16, 1
	v_add3_u32 v4, v4, v7, s73
	v_bfe_u32 v7, v6, 16, 1
	v_lshrrev_b32_e32 v4, 16, v4
	v_add3_u32 v6, v6, v7, s73
	v_and_or_b32 v6, v6, s72, v4
	ds_read_b32 v4, v5 offset:360
	ds_read_b32 v7, v5 offset:492
	s_waitcnt lgkmcnt(0)
	v_bfe_u32 v8, v4, 16, 1
	v_add3_u32 v4, v4, v8, s73
	v_bfe_u32 v8, v7, 16, 1
	v_lshrrev_b32_e32 v4, 16, v4
	v_add3_u32 v7, v7, v8, s73
	v_and_or_b32 v7, v7, s72, v4
	ds_read_b32 v4, v5 offset:624
	ds_read_b32 v8, v5 offset:756
	s_waitcnt lgkmcnt(0)
	v_bfe_u32 v9, v4, 16, 1
	v_add3_u32 v4, v4, v9, s73
	v_bfe_u32 v9, v8, 16, 1
	v_lshrrev_b32_e32 v4, 16, v4
	v_add3_u32 v8, v8, v9, s73
	v_and_or_b32 v8, v8, s72, v4
	ds_read_b32 v4, v5 offset:888
	ds_read_b32 v5, v5 offset:1020
	s_waitcnt lgkmcnt(0)
	v_bfe_u32 v9, v4, 16, 1
	v_add3_u32 v4, v4, v9, s73
	v_bfe_u32 v9, v5, 16, 1
	v_lshrrev_b32_e32 v4, 16, v4
	v_add3_u32 v5, v5, v9, s73
	v_and_or_b32 v9, v5, s72, v4
	flat_store_dwordx4 v[0:1], v[6:9] nt
	s_waitcnt lgkmcnt(0)

; #define LAS __attribute__((address_space(3)))
; __device__ __forceinline__ void atomic_addq(i64* p, float v, float scale) { (void)__hip_atomic_fetch_add((unsigned long long*)p, (unsigned long long)(i64)__builtin_rintf(v * scale), __ATOMIC_RELAXED, __HIP_MEMORY_SCOPE_AGENT); }
; #define LDS_WAIT() asm volatile("s_waitcnt lgkmcnt(0)" ::: "memory")
; __device__ __forceinline__ float bf_round(float f) { return __uint_as_float(f2bf(f) << 16); }
; #define INP(i) (kargs()->in[i])
; template <class Map>
; __device__ __forceinline__ void conv_item(const Frame& F, int it, const float* W, int K, int N, bf16_t* WT, const float* gk, int gmask, float gmul, const float* bk, i64* cs, i64* bw, Map map) {
;     ...
;         const int kb = it / nblk, nb = it % nblk, k0 = 64 * kb, n0 = 32 * nb, v0 = map(n0);
; #pragma unroll
;         for (int i = 0; i < 8; ++i) { const int kk = 8 * i + (lane >> 3), c4 = (lane & 7) * 4;
;             const f32x4 w4 = __builtin_nontemporal_load((const f32x4*)(W + (size_t)(k0 + kk) * N + n0 + c4)); LAS float* d = scr + kk * 33 + c4; d[0] = w4[0]; d[1] = w4[1]; d[2] = w4[2]; d[3] = w4[3]; }
;         LDS_WAIT(); asm volatile("" ::: "memory");
;         if (bk) {
;             const int n = lane & 31, kh = lane >> 5; float sb = 0.f, sc = 0.f;
; #pragma unroll 8
;             for (int j = 0; j < 32; ++j) { const int kk = kh * 32 + j; const float w = scr[kk * 33 + n]; sb += bk[k0 + kk] * w; sc += bf_round(gk[(k0 + kk) & gmask] * gmul * w); }
;             { auto r = __builtin_amdgcn_permlane32_swap(__float_as_uint(sb), __float_as_uint(sb), false, false); sb = __uint_as_float(r[0]) + __uint_as_float(r[1]); }
;             { auto r = __builtin_amdgcn_permlane32_swap(__float_as_uint(sc), __float_as_uint(sc), false, false); sc = __uint_as_float(r[0]) + __uint_as_float(r[1]); }
;             if (lane < 32) { atomic_addq(bw + v0 + n, sb, FX_COL); atomic_addq(cs + v0 + n, sc, FX_COL); }
;         }
;         const int c = lane & 7; float gl[8];
; #pragma unroll
;         for (int i = 0; i < 8; ++i) gl[i] = gk ? gk[(k0 + 8 * c + i) & gmask] * gmul : 1.0f;
; __device__ BG_ATTR void bg_item(const Frame& F, unsigned char* ws, const int L, int id) {
;     ...
;     if (id < NI_G) { conv_item(F, id, INP(17) + (size_t)L * DM * DM, DM, DM, Wg, g2, DM - 1, 1.f, b2, csFq + 22528, csFq + 24576, MapIdent()); return; } id -= NI_G;
.LBB0_453:
	s_andn2_saveexec_b64 s[96:97], s[84:85]
	s_cbranch_execz .LBB0_459
	v_readlane_b32 s40, v252, 14
	v_readlane_b32 s41, v252, 15
	s_mov_b64 s[12:13], s[40:41]
	s_load_dwordx2 s[12:13], s[12:13], 0x88
	v_writelane_b32 v255, s36, 39
	v_readlane_b32 s86, v252, 12
	v_readlane_b32 s87, v252, 13
	v_writelane_b32 v255, s37, 40
	s_mov_b64 s[38:39], s[86:87]
	v_readlane_b32 s16, v255, 37
	v_readlane_b32 s17, v255, 38
	s_waitcnt lgkmcnt(0)
	s_add_u32 s16, s12, s16
	s_addc_u32 s17, s13, s17
	s_mov_b64 s[12:13], s[40:41]
	s_mov_b64 s[36:37], s[48:49]
	s_load_dwordx2 s[48:49], s[12:13], 0x68
	v_writelane_b32 v255, s36, 41
	s_lshl_b64 s[12:13], s[36:37], 2
	v_lshlrev_b32_e32 v0, 5, v0
	v_mov_b32_e32 v11, v220
	s_waitcnt lgkmcnt(0)
	s_add_u32 s12, s48, s12
	s_addc_u32 s13, s49, s13
	s_add_u32 s84, s12, 0x2000
	s_addc_u32 s85, s13, 0
	s_mov_b64 s[12:13], s[40:41]
	s_load_dwordx2 s[78:79], s[12:13], 0x70
	s_mov_b64 s[12:13], s[86:87]
	s_mov_b64 s[40:41], s[86:87]
	v_and_b32_e32 v12, 0x7e0, v0
	v_add_u32_e32 v8, 0xaac0, v1
	v_lshlrev_b32_e32 v184, 2, v12
	v_lshlrev_b32_e32 v2, 4, v11
	v_and_b32_e32 v14, 0xffc0, v8
	v_bfe_u32 v10, v11, 3, 3
	v_lshl_add_u64 v[0:1], s[16:17], 0, v[184:185]
	v_and_b32_e32 v184, 0x70, v2
	v_lshl_add_u64 v[4:5], v[0:1], 0, v[184:185]
	v_or_b32_e32 v0, v10, v14
	v_lshlrev_b32_e32 v6, 13, v0
	v_mov_b32_e32 v7, v185
	v_lshl_add_u64 v[0:1], v[4:5], 0, v[6:7]
	global_load_dwordx4 v[132:135], v[0:1], off nt
	v_writelane_b32 v255, s37, 42
	v_mul_u32_u24_e32 v7, 0x84, v10
	v_readlane_b32 s16, v255, 17
	v_or_b32_e32 v25, 8, v10
	v_or_b32_e32 v24, 16, v10
	v_add3_u32 v7, s16, v184, v7
	v_add_u32_e32 v9, 0x420, v7
	v_or_b32_e32 v13, 24, v10
	v_readlane_b32 s86, v255, 25
	s_add_u32 s16, s48, s86
	s_movk_i32 s48, 0x7c0
	v_readlane_b32 s87, v255, 26
	s_addc_u32 s17, s49, s87
	v_and_b32_e32 v16, 31, v11
	v_and_or_b32 v17, v11, 32, v14
	v_and_b32_e32 v15, 63, v11
	v_or_b32_e32 v0, v25, v14
	v_lshlrev_b32_e32 v184, 13, v0
	v_lshl_add_u64 v[0:1], v[4:5], 0, v[184:185]
	global_load_dwordx4 v[136:139], v[0:1], off nt
	v_add_u32_e32 v0, 0x428, v7
	v_or_b32_e32 v0, v24, v14
	v_lshlrev_b32_e32 v184, 13, v0
	v_lshl_add_u64 v[0:1], v[4:5], 0, v[184:185]
	global_load_dwordx4 v[140:143], v[0:1], off nt
	v_add_u32_e32 v9, 0x840, v7
	v_add_u32_e32 v0, 0x848, v7
	v_or_b32_e32 v0, v13, v14
	v_lshlrev_b32_e32 v184, 13, v0
	v_lshl_add_u64 v[0:1], v[4:5], 0, v[184:185]
	global_load_dwordx4 v[144:147], v[0:1], off nt
	v_add_u32_e32 v9, 0xc60, v7
	v_or_b32_e32 v184, 0x40000, v6
	v_add_u32_e32 v0, 0xc68, v7
	v_lshl_add_u64 v[0:1], v[4:5], 0, v[184:185]
	global_load_dwordx4 v[148:151], v[0:1], off nt
	v_add_u32_e32 v9, 0x1080, v7
	v_or_b32_e32 v184, 0x50000, v6
	v_add_u32_e32 v0, 0x1088, v7
	v_lshl_add_u64 v[0:1], v[4:5], 0, v[184:185]
	global_load_dwordx4 v[152:155], v[0:1], off nt
	v_add_u32_e32 v9, 0x14a0, v7
	v_or_b32_e32 v184, 0x60000, v6
	v_add_u32_e32 v0, 0x14a8, v7
	v_lshl_add_u64 v[0:1], v[4:5], 0, v[184:185]
	global_load_dwordx4 v[156:159], v[0:1], off nt
	v_add_u32_e32 v9, 0x18c0, v7
	v_or_b32_e32 v184, 0x70000, v6
	v_add_u32_e32 v0, 0x18c8, v7
	v_lshl_add_u64 v[0:1], v[4:5], 0, v[184:185]
	global_load_dwordx4 v[160:163], v[0:1], off nt
	v_add_u32_e32 v4, 0x1ce0, v7
	v_add_u32_e32 v0, 0x1ce8, v7
	s_waitcnt vmcnt(0)
	v_add_u32_e32 v164, 0x0, v7
	ds_write2_b32 v164, v132, v133 offset1:1
	ds_write2_b32 v164, v134, v135 offset0:2 offset1:3
	v_add_u32_e32 v164, 0x420, v7
	ds_write2_b32 v164, v136, v137 offset1:1
	ds_write2_b32 v164, v138, v139 offset0:2 offset1:3
	v_add_u32_e32 v164, 0x840, v7
	ds_write2_b32 v164, v140, v141 offset1:1
	ds_write2_b32 v164, v142, v143 offset0:2 offset1:3
	v_add_u32_e32 v164, 0xc60, v7
	ds_write2_b32 v164, v144, v145 offset1:1
	ds_write2_b32 v164, v146, v147 offset0:2 offset1:3
	v_add_u32_e32 v164, 0x1080, v7
	ds_write2_b32 v164, v148, v149 offset1:1
	ds_write2_b32 v164, v150, v151 offset0:2 offset1:3
	v_add_u32_e32 v164, 0x14a0, v7
	ds_write2_b32 v164, v152, v153 offset1:1
	ds_write2_b32 v164, v154, v155 offset0:2 offset1:3
	v_add_u32_e32 v164, 0x18c0, v7
	ds_write2_b32 v164, v156, v157 offset1:1
	ds_write2_b32 v164, v158, v159 offset0:2 offset1:3
	v_add_u32_e32 v164, 0x1ce0, v7
	ds_write2_b32 v164, v160, v161 offset1:1
	ds_write2_b32 v164, v162, v163 offset0:2 offset1:3
	v_lshrrev_b32_e32 v0, 5, v11
	v_and_b32_e32 v0, 1, v0
	v_lshlrev_b16_e32 v0, 5, v0
	v_bitop3_b16 v0, v8, v0, s48 bitop3:0xec
	s_waitcnt lgkmcnt(0)
	v_lshlrev_b32_sdwa v184, v227, v0 dst_sel:DWORD dst_unused:UNUSED_PAD src0_sel:DWORD src1_sel:WORD_0
	v_bfe_u32 v0, v11, 5, 1
	v_lshl_add_u64 v[4:5], s[16:17], 0, v[184:185]
	s_waitcnt lgkmcnt(0)
	s_add_u32 s16, s78, s86
	v_mul_u32_u24_e32 v0, 0x1080, v0
	s_addc_u32 s17, s79, s87
	v_readlane_b32 s79, v255, 17
	v_lshlrev_b32_e32 v184, 2, v17
	v_lshl_or_b32 v0, v16, 2, v0
	v_mov_b32_e32 v8, 0
	v_lshl_add_u64 v[6:7], s[16:17], 0, v[184:185]
	v_add_u32_e32 v26, s79, v0
	s_mov_b64 s[48:49], 0
	v_mov_b32_e32 v9, v8
	s_movk_i32 s16, 0x2000
	s_mov_b64 s[86:87], 0x2000

; #define LAS __attribute__((address_space(3)))
; #define INP(i) (kargs()->in[i])
; template <class Map>
; __device__ __forceinline__ void conv_item(const Frame& F, int it, const float* W, int K, int N, bf16_t* WT, const float* gk, int gmask, float gmul, const float* bk, i64* cs, i64* bw, Map map) {
;     ...
;         const int kb = it / nblk, nb = it % nblk, k0 = 64 * kb, n0 = 32 * nb, v0 = map(n0);
; #pragma unroll
;         for (int i = 0; i < 8; ++i) { const int kk = 8 * i + (lane >> 3), c4 = (lane & 7) * 4;
;             const f32x4 w4 = __builtin_nontemporal_load((const f32x4*)(W + (size_t)(k0 + kk) * N + n0 + c4)); LAS float* d = scr + kk * 33 + c4; d[0] = w4[0]; d[1] = w4[1]; d[2] = w4[2]; d[3] = w4[3]; }
;         LDS_WAIT(); asm volatile("" ::: "memory");
;         if (bk) {
;             const int n = lane & 31, kh = lane >> 5; float sb = 0.f, sc = 0.f;
; #pragma unroll 8
;             for (int j = 0; j < 32; ++j) { const int kk = kh * 32 + j; const float w = scr[kk * 33 + n]; sb += bk[k0 + kk] * w; sc += bf_round(gk[(k0 + kk) & gmask] * gmul * w); }
;             { auto r = __builtin_amdgcn_permlane32_swap(__float_as_uint(sb), __float_as_uint(sb), false, false); sb = __uint_as_float(r[0]) + __uint_as_float(r[1]); }
;             { auto r = __builtin_amdgcn_permlane32_swap(__float_as_uint(sc), __float_as_uint(sc), false, false); sc = __uint_as_float(r[0]) + __uint_as_float(r[1]); }
;             if (lane < 32) { atomic_addq(bw + v0 + n, sb, FX_COL); atomic_addq(cs + v0 + n, sc, FX_COL); }
;         }
;         const int c = lane & 7; float gl[8];
; #pragma unroll
;         for (int i = 0; i < 8; ++i) gl[i] = gk ? gk[(k0 + 8 * c + i) & gmask] * gmul : 1.0f;
; #pragma unroll
;         for (int j = 0; j < 4; ++j) { const int n = (lane >> 3) + 8 * j; const LAS float* s = scr + (8 * c) * 33 + n;
;             u32x4 o; o.x = pk2(s[0 * 33] * gl[0], s[1 * 33] * gl[1]); o.y = pk2(s[2 * 33] * gl[2], s[3 * 33] * gl[3]); o.z = pk2(s[4 * 33] * gl[4], s[5 * 33] * gl[5]); o.w = pk2(s[6 * 33] * gl[6], s[7 * 33] * gl[7]);
;             __builtin_nontemporal_store(o, (u32x4*)(WT + (size_t)(v0 + n) * K + k0 + 8 * c)); }
; __device__ BG_ATTR void bg_item(const Frame& F, unsigned char* ws, const int L, int id) {
;     ...
;     if (id < NI_F2) { conv_item(F, id, INP(16) + (size_t)L * DFF * DM, DFF, DM, Wf2, nullptr, 0, 1.f, nullptr, nullptr, nullptr, MapIdent()); return; } id -= NI_F2;
.LBB0_460:
	s_andn2_saveexec_b64 s[38:39], s[36:37]
	s_cbranch_execz .LBB0_462
	v_readlane_b32 s12, v252, 14
	v_readlane_b32 s13, v252, 15
	s_load_dwordx2 s[12:13], s[12:13], 0x80
	s_mul_i32 s16, s20, 0x2c00000
	v_lshlrev_b32_e32 v0, 5, v0
	v_add_u32_e32 v1, 0xc0c0, v1
	v_mov_b32_e32 v14, v220
	s_waitcnt lgkmcnt(0)
	s_add_u32 s16, s12, s16
	s_mul_hi_i32 s12, s20, 0x2c00000
	s_addc_u32 s17, s13, s12
	v_readlane_b32 s12, v252, 12
	v_readlane_b32 s13, v252, 13
	v_and_b32_e32 v2, 0x7e0, v0
	v_and_b32_e32 v15, 0xffc0, v1
	v_bfe_u32 v7, v14, 3, 3
	v_lshlrev_b32_e32 v184, 2, v2
	v_lshlrev_b32_e32 v3, 4, v14
	v_lshl_add_u64 v[0:1], s[16:17], 0, v[184:185]
	v_and_b32_e32 v184, 0x70, v3
	v_or_b32_e32 v3, v7, v15
	v_lshl_add_u64 v[0:1], v[0:1], 0, v[184:185]
	v_lshlrev_b32_e32 v12, 13, v3
	v_mov_b32_e32 v13, v185
	v_lshl_add_u64 v[4:5], v[0:1], 0, v[12:13]
	global_load_dwordx4 v[132:135], v[4:5], off nt
	v_mul_u32_u24_e32 v3, 0x84, v7
	v_or_b32_e32 v6, 8, v7
	v_add3_u32 v13, s79, v184, v3
	v_or_b32_e32 v3, v6, v15
	v_lshlrev_b32_e32 v184, 13, v3
	v_lshl_add_u64 v[4:5], v[0:1], 0, v[184:185]
	v_add_u32_e32 v3, 0x420, v13
	v_or_b32_e32 v6, v6, v2
	v_mul_u32_u24_e32 v6, 0x1600, v6
	global_load_dwordx4 v[136:139], v[4:5], off nt
	v_or_b32_e32 v4, 16, v7
	v_add_u32_e32 v3, 0x428, v13
	v_or_b32_e32 v3, v4, v15
	v_lshlrev_b32_e32 v184, 13, v3
	v_lshl_add_u64 v[8:9], v[0:1], 0, v[184:185]
	global_load_dwordx4 v[140:143], v[8:9], off nt
	v_add_u32_e32 v3, 0x840, v13
	v_or_b32_e32 v4, v4, v2
	v_mul_u32_u24_e32 v4, 0x1600, v4
	v_add_u32_e32 v3, 0x848, v13
	v_or_b32_e32 v3, 24, v7
	v_or_b32_e32 v5, v3, v15
	v_lshlrev_b32_e32 v184, 13, v5
	v_lshl_add_u64 v[8:9], v[0:1], 0, v[184:185]
	global_load_dwordx4 v[144:147], v[8:9], off nt
	v_add_u32_e32 v5, 0xc60, v13
	v_or_b32_e32 v184, 0x40000, v12
	v_add_u32_e32 v5, 0xc68, v13
	v_lshl_add_u64 v[8:9], v[0:1], 0, v[184:185]
	global_load_dwordx4 v[148:151], v[8:9], off nt
	v_add_u32_e32 v5, 0x1080, v13
	v_or_b32_e32 v184, 0x50000, v12
	v_add_u32_e32 v5, 0x1088, v13
	v_lshl_add_u64 v[8:9], v[0:1], 0, v[184:185]
	global_load_dwordx4 v[152:155], v[8:9], off nt
	v_add_u32_e32 v5, 0x14a0, v13
	v_or_b32_e32 v184, 0x60000, v12
	v_add_u32_e32 v5, 0x14a8, v13
	v_lshl_add_u64 v[8:9], v[0:1], 0, v[184:185]
	global_load_dwordx4 v[156:159], v[8:9], off nt
	v_add_u32_e32 v5, 0x18c0, v13
	v_or_b32_e32 v184, 0x70000, v12
	v_lshl_add_u64 v[0:1], v[0:1], 0, v[184:185]
	v_lshlrev_b32_e32 v184, 1, v15
	v_add_u32_e32 v5, 0x18c8, v13
	global_load_dwordx4 v[160:163], v[0:1], off nt
	v_add_u32_e32 v0, 0x1ce0, v13
	v_and_b32_e32 v5, 7, v14
	v_add_u32_e32 v0, 0x1ce8, v13
	s_waitcnt vmcnt(0)
	v_add_u32_e32 v164, 0x0, v13
	ds_write2_b32 v164, v132, v133 offset1:1
	ds_write2_b32 v164, v134, v135 offset0:2 offset1:3
	v_add_u32_e32 v164, 0x420, v13
	ds_write2_b32 v164, v136, v137 offset1:1
	ds_write2_b32 v164, v138, v139 offset0:2 offset1:3
	v_add_u32_e32 v164, 0x840, v13
	ds_write2_b32 v164, v140, v141 offset1:1
	ds_write2_b32 v164, v142, v143 offset0:2 offset1:3
	v_add_u32_e32 v164, 0xc60, v13
	ds_write2_b32 v164, v144, v145 offset1:1
	ds_write2_b32 v164, v146, v147 offset0:2 offset1:3
	v_add_u32_e32 v164, 0x1080, v13
	ds_write2_b32 v164, v148, v149 offset1:1
	ds_write2_b32 v164, v150, v151 offset0:2 offset1:3
	v_add_u32_e32 v164, 0x14a0, v13
	ds_write2_b32 v164, v152, v153 offset1:1
	ds_write2_b32 v164, v154, v155 offset0:2 offset1:3
	v_add_u32_e32 v164, 0x18c0, v13
	ds_write2_b32 v164, v156, v157 offset1:1
	ds_write2_b32 v164, v158, v159 offset0:2 offset1:3
	v_add_u32_e32 v164, 0x1ce0, v13
	ds_write2_b32 v164, v160, v161 offset1:1
	ds_write2_b32 v164, v162, v163 offset0:2 offset1:3
	s_waitcnt lgkmcnt(0)
	v_mul_u32_u24_e32 v8, 0x420, v5
	v_lshl_add_u64 v[0:1], s[12:13], 0, v[184:185]
	v_lshlrev_b32_e32 v184, 4, v5
	v_lshlrev_b32_e32 v5, 2, v7
	v_add3_u32 v5, s79, v8, v5
	ds_read_b32 v8, v5
	ds_read_b32 v9, v5 offset:132
	v_or_b32_e32 v7, v7, v2
	v_lshl_add_u64 v[0:1], v[0:1], 0, v[184:185]
	s_mov_b64 s[12:13], 0x5c00000
	s_waitcnt lgkmcnt(1)
	v_bfe_u32 v10, v8, 16, 1
	v_add3_u32 v8, v8, v10, s73
	s_waitcnt lgkmcnt(0)
	v_bfe_u32 v10, v9, 16, 1
	v_lshrrev_b32_e32 v8, 16, v8
	v_add3_u32 v9, v9, v10, s73
	v_and_or_b32 v8, v9, s72, v8
	ds_read_b32 v9, v5 offset:264
	ds_read_b32 v10, v5 offset:396
	v_mul_u32_u24_e32 v7, 0x1600, v7
	v_lshl_add_u64 v[0:1], v[0:1], 0, s[12:13]
	v_lshlrev_b32_e32 v184, 1, v7
	s_waitcnt lgkmcnt(1)
; #define LAS __attribute__((address_space(3)))
; #define LDS_WAIT() asm volatile("s_waitcnt lgkmcnt(0)" ::: "memory")
; __device__ __forceinline__ unsigned pk2(float lo, float hi) { return f2bf(lo) | (f2bf(hi) << 16); }
; template <class Map>
; __device__ __forceinline__ void conv_item(const Frame& F, int it, const float* W, int K, int N, bf16_t* WT, const float* gk, int gmask, float gmul, const float* bk, i64* cs, i64* bw, Map map) {
;     ...
;         const int c = lane & 7; float gl[8];
; #pragma unroll
;         for (int i = 0; i < 8; ++i) gl[i] = gk ? gk[(k0 + 8 * c + i) & gmask] * gmul : 1.0f;
; #pragma unroll
;         for (int j = 0; j < 4; ++j) { const int n = (lane >> 3) + 8 * j; const LAS float* s = scr + (8 * c) * 33 + n;
;             u32x4 o; o.x = pk2(s[0 * 33] * gl[0], s[1 * 33] * gl[1]); o.y = pk2(s[2 * 33] * gl[2], s[3 * 33] * gl[3]); o.z = pk2(s[4 * 33] * gl[4], s[5 * 33] * gl[5]); o.w = pk2(s[6 * 33] * gl[6], s[7 * 33] * gl[7]);
;             __builtin_nontemporal_store(o, (u32x4*)(WT + (size_t)(v0 + n) * K + k0 + 8 * c)); }
;         LDS_WAIT(); asm volatile("" ::: "memory");
	v_bfe_u32 v11, v9, 16, 1
	v_add3_u32 v9, v9, v11, s73
	s_waitcnt lgkmcnt(0)
	v_bfe_u32 v11, v10, 16, 1
	v_lshrrev_b32_e32 v9, 16, v9
	v_add3_u32 v10, v10, v11, s73
	v_and_or_b32 v9, v10, s72, v9
	ds_read_b32 v10, v5 offset:528
	ds_read_b32 v11, v5 offset:660
	v_or_b32_e32 v2, v3, v2
	v_mul_u32_u24_e32 v2, 0x1600, v2
	s_waitcnt lgkmcnt(1)
	v_bfe_u32 v12, v10, 16, 1
	v_add3_u32 v10, v10, v12, s73
	s_waitcnt lgkmcnt(0)
	v_bfe_u32 v12, v11, 16, 1
	v_lshrrev_b32_e32 v10, 16, v10
	v_add3_u32 v11, v11, v12, s73
	v_and_or_b32 v10, v11, s72, v10
	ds_read_b32 v11, v5 offset:792
	ds_read_b32 v12, v5 offset:924
	s_waitcnt lgkmcnt(1)
	v_bfe_u32 v13, v11, 16, 1
	v_add3_u32 v11, v11, v13, s73
	s_waitcnt lgkmcnt(0)
	v_bfe_u32 v13, v12, 16, 1
	v_lshrrev_b32_e32 v11, 16, v11
	v_add3_u32 v12, v12, v13, s73
	v_and_or_b32 v11, v12, s72, v11
	v_lshl_add_u64 v[12:13], v[0:1], 0, v[184:185]
	flat_store_dwordx4 v[12:13], v[8:11] nt
	ds_read_b32 v7, v5 offset:32
	ds_read_b32 v8, v5 offset:164
	v_lshlrev_b32_e32 v184, 1, v6
	s_waitcnt lgkmcnt(0)
	v_bfe_u32 v9, v7, 16, 1
	v_add3_u32 v7, v7, v9, s73
	v_bfe_u32 v9, v8, 16, 1
	v_lshrrev_b32_e32 v7, 16, v7
	v_add3_u32 v8, v8, v9, s73
	v_and_or_b32 v8, v8, s72, v7
	ds_read_b32 v7, v5 offset:296
	ds_read_b32 v9, v5 offset:428
	s_waitcnt lgkmcnt(0)
	v_bfe_u32 v10, v7, 16, 1
	v_add3_u32 v7, v7, v10, s73
	v_bfe_u32 v10, v9, 16, 1
	v_lshrrev_b32_e32 v7, 16, v7
	v_add3_u32 v9, v9, v10, s73
	v_and_or_b32 v9, v9, s72, v7
	ds_read_b32 v7, v5 offset:560
	ds_read_b32 v10, v5 offset:692
	s_waitcnt lgkmcnt(0)
	v_bfe_u32 v11, v7, 16, 1
	v_add3_u32 v7, v7, v11, s73
	v_bfe_u32 v11, v10, 16, 1
	v_lshrrev_b32_e32 v7, 16, v7
	v_add3_u32 v10, v10, v11, s73
	v_and_or_b32 v10, v10, s72, v7
	ds_read_b32 v7, v5 offset:824
	ds_read_b32 v11, v5 offset:956
	s_waitcnt lgkmcnt(0)
	v_bfe_u32 v12, v7, 16, 1
	v_add3_u32 v7, v7, v12, s73
	v_bfe_u32 v12, v11, 16, 1
	v_lshrrev_b32_e32 v7, 16, v7
	v_add3_u32 v11, v11, v12, s73
	v_and_or_b32 v11, v11, s72, v7
	v_lshl_add_u64 v[6:7], v[0:1], 0, v[184:185]
	flat_store_dwordx4 v[6:7], v[8:11] nt
	ds_read_b32 v6, v5 offset:64
	ds_read_b32 v7, v5 offset:196
	v_lshlrev_b32_e32 v184, 1, v4
	s_waitcnt lgkmcnt(0)
	v_bfe_u32 v8, v6, 16, 1
	v_add3_u32 v6, v6, v8, s73
	v_bfe_u32 v8, v7, 16, 1
	v_lshrrev_b32_e32 v6, 16, v6
	v_add3_u32 v7, v7, v8, s73
	v_and_or_b32 v6, v7, s72, v6
	ds_read_b32 v7, v5 offset:328
	ds_read_b32 v8, v5 offset:460
	s_waitcnt lgkmcnt(0)
	v_bfe_u32 v9, v7, 16, 1
	v_add3_u32 v7, v7, v9, s73
	v_bfe_u32 v9, v8, 16, 1
	v_lshrrev_b32_e32 v7, 16, v7
	v_add3_u32 v8, v8, v9, s73
	v_and_or_b32 v7, v8, s72, v7
	ds_read_b32 v8, v5 offset:592
	ds_read_b32 v9, v5 offset:724
	s_waitcnt lgkmcnt(0)
	v_bfe_u32 v10, v8, 16, 1
	v_add3_u32 v8, v8, v10, s73
	v_bfe_u32 v10, v9, 16, 1
	v_lshrrev_b32_e32 v8, 16, v8
	v_add3_u32 v9, v9, v10, s73
	v_and_or_b32 v8, v9, s72, v8
	ds_read_b32 v9, v5 offset:856
	ds_read_b32 v10, v5 offset:988
	s_waitcnt lgkmcnt(0)
	v_bfe_u32 v11, v9, 16, 1
	v_add3_u32 v9, v9, v11, s73
	v_bfe_u32 v11, v10, 16, 1
	v_lshrrev_b32_e32 v9, 16, v9
	v_add3_u32 v10, v10, v11, s73
	v_and_or_b32 v9, v10, s72, v9
	v_lshl_add_u64 v[10:11], v[0:1], 0, v[184:185]
	flat_store_dwordx4 v[10:11], v[6:9] nt
	ds_read_b32 v4, v5 offset:96
	ds_read_b32 v6, v5 offset:228
	v_lshlrev_b32_e32 v184, 1, v2
	v_lshl_add_u64 v[0:1], v[0:1], 0, v[184:185]
	s_waitcnt lgkmcnt(0)
	v_bfe_u32 v7, v4, 16, 1
	v_add3_u32 v4, v4, v7, s73
	v_bfe_u32 v7, v6, 16, 1
	v_lshrrev_b32_e32 v4, 16, v4
	v_add3_u32 v6, v6, v7, s73
	v_and_or_b32 v6, v6, s72, v4
	ds_read_b32 v4, v5 offset:360
	ds_read_b32 v7, v5 offset:492
	s_waitcnt lgkmcnt(0)
	v_bfe_u32 v8, v4, 16, 1
	v_add3_u32 v4, v4, v8, s73
	v_bfe_u32 v8, v7, 16, 1
	v_lshrrev_b32_e32 v4, 16, v4
	v_add3_u32 v7, v7, v8, s73
	v_and_or_b32 v7, v7, s72, v4
	ds_read_b32 v4, v5 offset:624
	ds_read_b32 v8, v5 offset:756
	s_waitcnt lgkmcnt(0)
	v_bfe_u32 v9, v4, 16, 1
	v_add3_u32 v4, v4, v9, s73
	v_bfe_u32 v9, v8, 16, 1
	v_lshrrev_b32_e32 v4, 16, v4
	v_add3_u32 v8, v8, v9, s73
	v_and_or_b32 v8, v8, s72, v4
	ds_read_b32 v4, v5 offset:888
	ds_read_b32 v5, v5 offset:1020
	s_waitcnt lgkmcnt(0)
	v_bfe_u32 v9, v4, 16, 1
	v_add3_u32 v4, v4, v9, s73
	v_bfe_u32 v9, v5, 16, 1
	v_lshrrev_b32_e32 v4, 16, v4
	v_add3_u32 v5, v5, v9, s73
	v_and_or_b32 v9, v5, s72, v4
	flat_store_dwordx4 v[0:1], v[6:9] nt
	s_waitcnt lgkmcnt(0)

; #define LAS __attribute__((address_space(3)))
; __device__ __forceinline__ void atomic_addq(i64* p, float v, float scale) { (void)__hip_atomic_fetch_add((unsigned long long*)p, (unsigned long long)(i64)__builtin_rintf(v * scale), __ATOMIC_RELAXED, __HIP_MEMORY_SCOPE_AGENT); }
; #define F_LANE() (tid_of(F.wave) & 63)
; #define LDS_WAIT() asm volatile("s_waitcnt lgkmcnt(0)" ::: "memory")
; __device__ __forceinline__ float bf_round(float f) { return __uint_as_float(f2bf(f) << 16); }
; #define INP(i) (kargs()->in[i])
; template <class Map>
; __device__ __forceinline__ void conv_item(const Frame& F, int it, const float* W, int K, int N, bf16_t* WT, const float* gk, int gmask, float gmul, const float* bk, i64* cs, i64* bw, Map map) {
;     LAS float* scr = (LAS float*)(F.lds + F.wave * 16384);
;     const int lane = F_LANE(), nblk = N / 32;
;     {
;         const int kb = it / nblk, nb = it % nblk, k0 = 64 * kb, n0 = 32 * nb, v0 = map(n0);
; #pragma unroll
;         for (int i = 0; i < 8; ++i) { const int kk = 8 * i + (lane >> 3), c4 = (lane & 7) * 4;
;             const f32x4 w4 = __builtin_nontemporal_load((const f32x4*)(W + (size_t)(k0 + kk) * N + n0 + c4)); LAS float* d = scr + kk * 33 + c4; d[0] = w4[0]; d[1] = w4[1]; d[2] = w4[2]; d[3] = w4[3]; }
;         LDS_WAIT(); asm volatile("" ::: "memory");
;         if (bk) {
;             const int n = lane & 31, kh = lane >> 5; float sb = 0.f, sc = 0.f;
; #pragma unroll 8
;             for (int j = 0; j < 32; ++j) { const int kk = kh * 32 + j; const float w = scr[kk * 33 + n]; sb += bk[k0 + kk] * w; sc += bf_round(gk[(k0 + kk) & gmask] * gmul * w); }
;             { auto r = __builtin_amdgcn_permlane32_swap(__float_as_uint(sb), __float_as_uint(sb), false, false); sb = __uint_as_float(r[0]) + __uint_as_float(r[1]); }
;             { auto r = __builtin_amdgcn_permlane32_swap(__float_as_uint(sc), __float_as_uint(sc), false, false); sc = __uint_as_float(r[0]) + __uint_as_float(r[1]); }
;             if (lane < 32) { atomic_addq(bw + v0 + n, sb, FX_COL); atomic_addq(cs + v0 + n, sc, FX_COL); }
;         }
; __device__ BG_ATTR void bg_item(const Frame& F, unsigned char* ws, const int L, int id) {
;     ...
;     if (id < NI_F1) { conv_item(F, id, INP(15) + (size_t)L * DM * 2 * DFF, DM, 2 * DFF, Wf1, g1, DM - 1, 1.f, b1, csFq, csFq + 11264, MapSwiglu()); return; } id -= NI_F1;
.LBB0_463:
	s_andn2_saveexec_b64 s[24:25], s[24:25]
	s_cbranch_execz .LBB0_487
	v_readlane_b32 s38, v252, 14
	v_readlane_b32 s39, v252, 15
	s_mov_b64 s[12:13], s[38:39]
	s_load_dwordx2 s[12:13], s[12:13], 0x78
	s_mul_i32 s16, s20, 0x5800000
	v_readlane_b32 s40, v252, 12
	v_readlane_b32 s41, v252, 13
	s_mov_b64 s[84:85], s[40:41]
	s_waitcnt lgkmcnt(0)
	s_add_u32 s78, s12, s16
	s_mul_hi_i32 s12, s20, 0x5800000
	s_addc_u32 s79, s13, s12
	s_mov_b64 s[12:13], s[38:39]
	s_load_dwordx2 s[96:97], s[12:13], 0x68
	s_mov_b32 s16, 0xba2f
	v_mul_u32_u24_sdwa v1, v0, s16 dst_sel:DWORD dst_unused:UNUSED_PAD src0_sel:WORD_0 src1_sel:DWORD
	s_movk_i32 s16, 0x160
	s_lshl_b64 s[12:13], s[48:49], 2
	v_mul_lo_u16_sdwa v2, v1, s16 dst_sel:DWORD dst_unused:UNUSED_PAD src0_sel:BYTE_3 src1_sel:DWORD
	s_waitcnt lgkmcnt(0)
	s_add_u32 s86, s96, s12
	v_sub_u16_e32 v2, v0, v2
	v_mov_b32_e32 v4, 6
	s_movk_i32 s16, 0xaf
	s_addc_u32 s87, s97, s13
	s_mov_b64 s[12:13], s[38:39]
	v_lshlrev_b16_sdwa v24, v4, v1 dst_sel:DWORD dst_unused:UNUSED_PAD src0_sel:DWORD src1_sel:BYTE_3
	v_lshlrev_b16_e32 v1, 5, v2
	v_cmp_lt_u16_e32 vcc, s16, v2
	s_movk_i32 s16, 0xb0
	s_mov_b64 s[36:37], s[48:49]
	s_mov_b64 s[48:49], s[40:41]
	v_mov_b32_e32 v3, v220
	v_add_u16_e32 v4, 0xea00, v1
	v_cmp_gt_u16_e64 s[38:39], s16, v2
	s_load_dwordx2 s[12:13], s[12:13], 0x70
	v_lshlrev_b32_e32 v184, 2, v1
	v_cndmask_b32_e64 v2, v4, v1, s[38:39]
	v_mov_b32_e32 v4, 1
	v_bfe_u32 v17, v3, 3, 3
	v_lshlrev_b32_e32 v1, 4, v3
	v_lshlrev_b32_sdwa v10, v4, sext(v2) dst_sel:DWORD dst_unused:UNUSED_PAD src0_sel:DWORD src1_sel:WORD_0
	v_lshl_add_u64 v[4:5], s[78:79], 0, v[184:185]
	v_and_b32_e32 v184, 0x70, v1
	v_or_b32_e32 v1, v17, v24
	v_lshl_add_u64 v[8:9], v[4:5], 0, v[184:185]
	v_mul_u32_u24_e32 v4, 0xb000, v1
	v_mov_b32_e32 v5, v185
	v_lshl_add_u64 v[4:5], v[8:9], 0, v[4:5]
	global_load_dwordx4 v[132:135], v[4:5], off nt
	v_readlane_b32 s79, v255, 17
	v_mul_u32_u24_e32 v12, 0x84, v17
	v_or_b32_e32 v16, 8, v17
	v_add3_u32 v12, s79, v184, v12
	v_add_u32_e32 v13, 0x420, v12
	v_or_b32_e32 v15, 16, v17
	v_or_b32_e32 v14, 24, v17
	s_movk_i32 s16, 0x60
	v_cndmask_b32_e32 v11, 0, v228, vcc
	v_and_b32_sdwa v2, sext(v2), s16 dst_sel:DWORD dst_unused:UNUSED_PAD src0_sel:WORD_0 src1_sel:DWORD
	s_waitcnt lgkmcnt(0)
	s_cmp_eq_u64 s[12:13], 0
	v_or_b32_e32 v4, v16, v24
	v_mul_u32_u24_e32 v184, 0xb000, v4
	v_lshl_add_u64 v[4:5], v[8:9], 0, v[184:185]
	global_load_dwordx4 v[136:139], v[4:5], off nt
	v_add_u32_e32 v4, 0x428, v12
	v_or_b32_e32 v4, v15, v24
	v_mul_u32_u24_e32 v184, 0xb000, v4
	v_lshl_add_u64 v[4:5], v[8:9], 0, v[184:185]
	global_load_dwordx4 v[140:143], v[4:5], off nt
	v_add_u32_e32 v13, 0x840, v12
	v_add_u32_e32 v4, 0x848, v12
	v_or_b32_e32 v4, v14, v24
	v_mul_u32_u24_e32 v184, 0xb000, v4
	v_lshl_add_u64 v[4:5], v[8:9], 0, v[184:185]
	global_load_dwordx4 v[144:147], v[4:5], off nt
	v_add_u32_e32 v13, 0xc60, v12
	v_add_u32_e32 v4, 0xc68, v12
	v_or_b32_e32 v4, 32, v1
	v_mul_u32_u24_e32 v184, 0xb000, v4
	v_lshl_add_u64 v[4:5], v[8:9], 0, v[184:185]
	global_load_dwordx4 v[148:151], v[4:5], off nt
	v_add_u32_e32 v13, 0x1080, v12
	v_add_u32_e32 v4, 0x1088, v12
	v_or_b32_e32 v4, 40, v1
	v_mul_u32_u24_e32 v184, 0xb000, v4
	v_lshl_add_u64 v[4:5], v[8:9], 0, v[184:185]
	global_load_dwordx4 v[152:155], v[4:5], off nt
	v_add_u32_e32 v13, 0x14a0, v12
	v_add_u32_e32 v4, 0x14a8, v12
	v_or_b32_e32 v4, 48, v1
	v_mul_u32_u24_e32 v184, 0xb000, v4
	v_lshl_add_u64 v[4:5], v[8:9], 0, v[184:185]
	global_load_dwordx4 v[156:159], v[4:5], off nt
	v_add_u32_e32 v13, 0x18c0, v12
	v_or_b32_e32 v1, 56, v1
	v_mul_u32_u24_e32 v184, 0xb000, v1
	v_add_u32_e32 v1, 0x1ce0, v12
	v_add_u32_e32 v4, 0x18c8, v12
	v_lshl_add_u64 v[4:5], v[8:9], 0, v[184:185]
	global_load_dwordx4 v[160:163], v[4:5], off nt
	v_add_u32_e32 v1, 0x1ce8, v12
	s_waitcnt vmcnt(0)
	v_add_u32_e32 v164, 0x0, v12
	ds_write2_b32 v164, v132, v133 offset1:1
	ds_write2_b32 v164, v134, v135 offset0:2 offset1:3
	v_add_u32_e32 v164, 0x420, v12
	ds_write2_b32 v164, v136, v137 offset1:1
	ds_write2_b32 v164, v138, v139 offset0:2 offset1:3
	v_add_u32_e32 v164, 0x840, v12
	ds_write2_b32 v164, v140, v141 offset1:1
	ds_write2_b32 v164, v142, v143 offset0:2 offset1:3
	v_add_u32_e32 v164, 0xc60, v12
	ds_write2_b32 v164, v144, v145 offset1:1
	ds_write2_b32 v164, v146, v147 offset0:2 offset1:3
	v_add_u32_e32 v164, 0x1080, v12
	ds_write2_b32 v164, v148, v149 offset1:1
	ds_write2_b32 v164, v150, v151 offset0:2 offset1:3
	v_add_u32_e32 v164, 0x14a0, v12
	ds_write2_b32 v164, v152, v153 offset1:1
	ds_write2_b32 v164, v154, v155 offset0:2 offset1:3
	v_add_u32_e32 v164, 0x18c0, v12
	ds_write2_b32 v164, v156, v157 offset1:1
	ds_write2_b32 v164, v158, v159 offset0:2 offset1:3
	v_add_u32_e32 v164, 0x1ce0, v12
	ds_write2_b32 v164, v160, v161 offset1:1
	ds_write2_b32 v164, v162, v163 offset0:2 offset1:3
	s_waitcnt lgkmcnt(0)
	v_and_b32_e32 v1, 0xffffff00, v10
	v_or3_b32 v4, v2, v11, v1
	s_cbranch_scc1 .LBB0_470
	v_and_b32_e32 v1, 32, v3
	v_readlane_b32 s38, v255, 25
	v_readlane_b32 s39, v255, 26
	s_add_u32 s12, s12, s38
	v_add_u32_e32 v26, v24, v1
	s_mov_b32 s16, 0xba2e8c
	v_lshrrev_b32_e32 v1, 5, v3
	v_bfe_u32 v2, v3, 5, 1
	s_addc_u32 s13, s13, s39
	v_lshlrev_b32_e32 v184, 2, v26
	v_mul_hi_u32_u24_sdwa v0, v0, s16 dst_sel:DWORD dst_unused:UNUSED_PAD src0_sel:WORD_0 src1_sel:DWORD
	v_lshlrev_b32_e32 v8, 7, v2
	v_and_b32_e32 v1, 1, v1
	v_lshl_add_u64 v[6:7], s[12:13], 0, v[184:185]
	v_lshl_or_b32 v184, v0, 8, v8
	v_lshlrev_b16_e32 v0, 6, v0
	v_lshlrev_b16_e32 v1, 5, v1
	v_or_b32_e32 v0, v0, v1
	v_and_b32_e32 v0, 0x7e0, v0
	v_and_b32_e32 v25, 31, v3
	v_lshl_add_u64 v[8:9], s[12:13], 0, v[184:185]
	v_lshlrev_b32_e32 v184, 2, v0
	v_mul_u32_u24_e32 v0, 0x1080, v2
	s_add_u32 s12, s96, s38
	v_lshl_or_b32 v0, v25, 2, v0
	s_addc_u32 s13, s97, s39
	v_add_u32_e32 v27, s79, v0
	v_mov_b32_e32 v0, 0
	v_and_b32_e32 v5, 63, v3
	v_lshl_add_u64 v[10:11], s[12:13], 0, v[184:185]
	s_mov_b64 s[12:13], 0
	v_mov_b32_e32 v1, v0

; #define LAS __attribute__((address_space(3)))
; #define INP(i) (kargs()->in[i])
; template <class Map>
; __device__ __forceinline__ void conv_item(const Frame& F, int it, const float* W, int K, int N, bf16_t* WT, const float* gk, int gmask, float gmul, const float* bk, i64* cs, i64* bw, Map map) {
;     ...
;         const int kb = it / nblk, nb = it % nblk, k0 = 64 * kb, n0 = 32 * nb, v0 = map(n0);
; #pragma unroll
;         for (int i = 0; i < 8; ++i) { const int kk = 8 * i + (lane >> 3), c4 = (lane & 7) * 4;
;             const f32x4 w4 = __builtin_nontemporal_load((const f32x4*)(W + (size_t)(k0 + kk) * N + n0 + c4)); LAS float* d = scr + kk * 33 + c4; d[0] = w4[0]; d[1] = w4[1]; d[2] = w4[2]; d[3] = w4[3]; }
;         LDS_WAIT(); asm volatile("" ::: "memory");
;         if (bk) {
;             const int n = lane & 31, kh = lane >> 5; float sb = 0.f, sc = 0.f;
; #pragma unroll 8
;             for (int j = 0; j < 32; ++j) { const int kk = kh * 32 + j; const float w = scr[kk * 33 + n]; sb += bk[k0 + kk] * w; sc += bf_round(gk[(k0 + kk) & gmask] * gmul * w); }
;             { auto r = __builtin_amdgcn_permlane32_swap(__float_as_uint(sb), __float_as_uint(sb), false, false); sb = __uint_as_float(r[0]) + __uint_as_float(r[1]); }
;             { auto r = __builtin_amdgcn_permlane32_swap(__float_as_uint(sc), __float_as_uint(sc), false, false); sc = __uint_as_float(r[0]) + __uint_as_float(r[1]); }
;             if (lane < 32) { atomic_addq(bw + v0 + n, sb, FX_COL); atomic_addq(cs + v0 + n, sc, FX_COL); }
;         }
;         const int c = lane & 7; float gl[8];
; #pragma unroll
;         for (int i = 0; i < 8; ++i) gl[i] = gk ? gk[(k0 + 8 * c + i) & gmask] * gmul : 1.0f;
; #pragma unroll
;         for (int j = 0; j < 4; ++j) { const int n = (lane >> 3) + 8 * j; const LAS float* s = scr + (8 * c) * 33 + n;
;             u32x4 o; o.x = pk2(s[0 * 33] * gl[0], s[1 * 33] * gl[1]); o.y = pk2(s[2 * 33] * gl[2], s[3 * 33] * gl[3]); o.z = pk2(s[4 * 33] * gl[4], s[5 * 33] * gl[5]); o.w = pk2(s[6 * 33] * gl[6], s[7 * 33] * gl[7]);
;             __builtin_nontemporal_store(o, (u32x4*)(WT + (size_t)(v0 + n) * K + k0 + 8 * c)); }
; __device__ BG_ATTR void bg_item(const Frame& F, unsigned char* ws, const int L, int id) {
;     ...
;         if (id < NI_O) { conv_item(F, id, INP(7) + (size_t)j * DM * DM, DM, DM, Wo, nullptr, 0, 1.f, nullptr, nullptr, nullptr, MapIdent()); return; } id -= NI_O;
.LBB0_488:
	s_andn2_saveexec_b64 s[24:25], s[26:27]
	s_cbranch_execz .LBB0_490
	v_readlane_b32 s12, v252, 14
	v_readlane_b32 s13, v252, 15
	s_load_dwordx2 s[12:13], s[12:13], 0x38
	v_readlane_b32 s16, v255, 31
	v_add_u32_e32 v0, 0xf4c0, v1
	v_readlane_b32 s17, v255, 32
	v_and_b32_e32 v15, 0xffc0, v0
	s_waitcnt lgkmcnt(0)
	s_add_u32 s16, s12, s16
	s_addc_u32 s17, s13, s17
	v_readlane_b32 s12, v252, 12
	v_lshlrev_b32_e32 v0, 5, v1
	v_readlane_b32 s13, v252, 13
	v_mov_b32_e32 v14, v220
	v_and_b32_e32 v2, 0x7e0, v0
	v_lshlrev_b32_e32 v184, 2, v2
	v_bfe_u32 v7, v14, 3, 3
	v_lshlrev_b32_e32 v3, 4, v14
	v_lshl_add_u64 v[0:1], s[16:17], 0, v[184:185]
	v_and_b32_e32 v184, 0x70, v3
	v_or_b32_e32 v3, v7, v15
	v_lshl_add_u64 v[0:1], v[0:1], 0, v[184:185]
	v_lshlrev_b32_e32 v12, 13, v3
	v_mov_b32_e32 v13, v185
	v_lshl_add_u64 v[4:5], v[0:1], 0, v[12:13]
	global_load_dwordx4 v[132:135], v[4:5], off nt
	v_mul_u32_u24_e32 v3, 0x84, v7
	v_or_b32_e32 v6, 8, v7
	v_add3_u32 v13, s79, v184, v3
	v_or_b32_e32 v3, v6, v15
	v_lshlrev_b32_e32 v184, 13, v3
	v_lshl_add_u64 v[4:5], v[0:1], 0, v[184:185]
	v_add_u32_e32 v3, 0x420, v13
	v_or_b32_e32 v6, v6, v2
	global_load_dwordx4 v[136:139], v[4:5], off nt
	v_or_b32_e32 v4, 16, v7
	v_add_u32_e32 v3, 0x428, v13
	v_or_b32_e32 v3, v4, v15
	v_lshlrev_b32_e32 v184, 13, v3
	v_lshl_add_u64 v[8:9], v[0:1], 0, v[184:185]
	global_load_dwordx4 v[140:143], v[8:9], off nt
	v_add_u32_e32 v3, 0x840, v13
	v_or_b32_e32 v4, v4, v2
	v_add_u32_e32 v3, 0x848, v13
	v_or_b32_e32 v3, 24, v7
	v_or_b32_e32 v5, v3, v15
	v_lshlrev_b32_e32 v184, 13, v5
	v_lshl_add_u64 v[8:9], v[0:1], 0, v[184:185]
	global_load_dwordx4 v[144:147], v[8:9], off nt
	v_add_u32_e32 v5, 0xc60, v13
	v_or_b32_e32 v184, 0x40000, v12
	v_add_u32_e32 v5, 0xc68, v13
	v_lshl_add_u64 v[8:9], v[0:1], 0, v[184:185]
	global_load_dwordx4 v[148:151], v[8:9], off nt
	v_add_u32_e32 v5, 0x1080, v13
	v_or_b32_e32 v184, 0x50000, v12
	v_add_u32_e32 v5, 0x1088, v13
	v_lshl_add_u64 v[8:9], v[0:1], 0, v[184:185]
	global_load_dwordx4 v[152:155], v[8:9], off nt
	v_add_u32_e32 v5, 0x14a0, v13
	v_or_b32_e32 v184, 0x60000, v12
	v_add_u32_e32 v5, 0x14a8, v13
	v_lshl_add_u64 v[8:9], v[0:1], 0, v[184:185]
	global_load_dwordx4 v[156:159], v[8:9], off nt
	v_add_u32_e32 v5, 0x18c0, v13
	v_or_b32_e32 v184, 0x70000, v12
	v_lshl_add_u64 v[0:1], v[0:1], 0, v[184:185]
	v_lshlrev_b32_e32 v184, 1, v15
	v_add_u32_e32 v5, 0x18c8, v13
	global_load_dwordx4 v[160:163], v[0:1], off nt
	v_add_u32_e32 v0, 0x1ce0, v13
	v_and_b32_e32 v5, 7, v14
	v_add_u32_e32 v0, 0x1ce8, v13
	s_waitcnt vmcnt(0)
	v_add_u32_e32 v164, 0x0, v13
	ds_write2_b32 v164, v132, v133 offset1:1
	ds_write2_b32 v164, v134, v135 offset0:2 offset1:3
	v_add_u32_e32 v164, 0x420, v13
	ds_write2_b32 v164, v136, v137 offset1:1
	ds_write2_b32 v164, v138, v139 offset0:2 offset1:3
	v_add_u32_e32 v164, 0x840, v13
	ds_write2_b32 v164, v140, v141 offset1:1
	ds_write2_b32 v164, v142, v143 offset0:2 offset1:3
	v_add_u32_e32 v164, 0xc60, v13
	ds_write2_b32 v164, v144, v145 offset1:1
	ds_write2_b32 v164, v146, v147 offset0:2 offset1:3
	v_add_u32_e32 v164, 0x1080, v13
	ds_write2_b32 v164, v148, v149 offset1:1
	ds_write2_b32 v164, v150, v151 offset0:2 offset1:3
	v_add_u32_e32 v164, 0x14a0, v13
	ds_write2_b32 v164, v152, v153 offset1:1
	ds_write2_b32 v164, v154, v155 offset0:2 offset1:3
	v_add_u32_e32 v164, 0x18c0, v13
	ds_write2_b32 v164, v156, v157 offset1:1
	ds_write2_b32 v164, v158, v159 offset0:2 offset1:3
	v_add_u32_e32 v164, 0x1ce0, v13
	ds_write2_b32 v164, v160, v161 offset1:1
	ds_write2_b32 v164, v162, v163 offset0:2 offset1:3
	s_waitcnt lgkmcnt(0)
	v_mul_u32_u24_e32 v8, 0x420, v5
	v_lshl_add_u64 v[0:1], s[12:13], 0, v[184:185]
	v_lshlrev_b32_e32 v184, 4, v5
	v_lshlrev_b32_e32 v5, 2, v7
	v_add3_u32 v5, s79, v8, v5
	ds_read_b32 v8, v5
	ds_read_b32 v9, v5 offset:132
	v_lshl_add_u64 v[0:1], v[0:1], 0, v[184:185]
	s_mov_b64 s[12:13], 0x2800000
	v_or_b32_e32 v7, v7, v2
	s_waitcnt lgkmcnt(1)
	v_bfe_u32 v10, v8, 16, 1
	v_add3_u32 v8, v8, v10, s73
	s_waitcnt lgkmcnt(0)
	v_bfe_u32 v10, v9, 16, 1
	v_lshrrev_b32_e32 v8, 16, v8
	v_add3_u32 v9, v9, v10, s73
	v_and_or_b32 v8, v9, s72, v8
	ds_read_b32 v9, v5 offset:264
	ds_read_b32 v10, v5 offset:396
	v_lshl_add_u64 v[0:1], v[0:1], 0, s[12:13]
	v_lshlrev_b32_e32 v184, 12, v7
	v_or_b32_e32 v2, v3, v2
	s_waitcnt lgkmcnt(1)
; #define LAS __attribute__((address_space(3)))
; #define LDS_WAIT() asm volatile("s_waitcnt lgkmcnt(0)" ::: "memory")
; __device__ __forceinline__ unsigned pk2(float lo, float hi) { return f2bf(lo) | (f2bf(hi) << 16); }
; template <class Map>
; __device__ __forceinline__ void conv_item(const Frame& F, int it, const float* W, int K, int N, bf16_t* WT, const float* gk, int gmask, float gmul, const float* bk, i64* cs, i64* bw, Map map) {
;     ...
;         const int c = lane & 7; float gl[8];
; #pragma unroll
;         for (int i = 0; i < 8; ++i) gl[i] = gk ? gk[(k0 + 8 * c + i) & gmask] * gmul : 1.0f;
; #pragma unroll
;         for (int j = 0; j < 4; ++j) { const int n = (lane >> 3) + 8 * j; const LAS float* s = scr + (8 * c) * 33 + n;
;             u32x4 o; o.x = pk2(s[0 * 33] * gl[0], s[1 * 33] * gl[1]); o.y = pk2(s[2 * 33] * gl[2], s[3 * 33] * gl[3]); o.z = pk2(s[4 * 33] * gl[4], s[5 * 33] * gl[5]); o.w = pk2(s[6 * 33] * gl[6], s[7 * 33] * gl[7]);
;             __builtin_nontemporal_store(o, (u32x4*)(WT + (size_t)(v0 + n) * K + k0 + 8 * c)); }
;         LDS_WAIT(); asm volatile("" ::: "memory");
	v_bfe_u32 v11, v9, 16, 1
	v_add3_u32 v9, v9, v11, s73
	s_waitcnt lgkmcnt(0)
	v_bfe_u32 v11, v10, 16, 1
	v_lshrrev_b32_e32 v9, 16, v9
	v_add3_u32 v10, v10, v11, s73
	v_and_or_b32 v9, v10, s72, v9
	ds_read_b32 v10, v5 offset:528
	ds_read_b32 v11, v5 offset:660
	s_waitcnt lgkmcnt(1)
	v_bfe_u32 v12, v10, 16, 1
	v_add3_u32 v10, v10, v12, s73
	s_waitcnt lgkmcnt(0)
	v_bfe_u32 v12, v11, 16, 1
	v_lshrrev_b32_e32 v10, 16, v10
	v_add3_u32 v11, v11, v12, s73
	v_and_or_b32 v10, v11, s72, v10
	ds_read_b32 v11, v5 offset:792
	ds_read_b32 v12, v5 offset:924
	s_waitcnt lgkmcnt(1)
	v_bfe_u32 v13, v11, 16, 1
	v_add3_u32 v11, v11, v13, s73
	s_waitcnt lgkmcnt(0)
	v_bfe_u32 v13, v12, 16, 1
	v_lshrrev_b32_e32 v11, 16, v11
	v_add3_u32 v12, v12, v13, s73
	v_and_or_b32 v11, v12, s72, v11
	v_lshl_add_u64 v[12:13], v[0:1], 0, v[184:185]
	flat_store_dwordx4 v[12:13], v[8:11] nt
	ds_read_b32 v7, v5 offset:32
	ds_read_b32 v8, v5 offset:164
	v_lshlrev_b32_e32 v184, 12, v6
	s_waitcnt lgkmcnt(0)
	v_bfe_u32 v9, v7, 16, 1
	v_add3_u32 v7, v7, v9, s73
	v_bfe_u32 v9, v8, 16, 1
	v_lshrrev_b32_e32 v7, 16, v7
	v_add3_u32 v8, v8, v9, s73
	v_and_or_b32 v8, v8, s72, v7
	ds_read_b32 v7, v5 offset:296
	ds_read_b32 v9, v5 offset:428
	s_waitcnt lgkmcnt(0)
	v_bfe_u32 v10, v7, 16, 1
	v_add3_u32 v7, v7, v10, s73
	v_bfe_u32 v10, v9, 16, 1
	v_lshrrev_b32_e32 v7, 16, v7
	v_add3_u32 v9, v9, v10, s73
	v_and_or_b32 v9, v9, s72, v7
	ds_read_b32 v7, v5 offset:560
	ds_read_b32 v10, v5 offset:692
	s_waitcnt lgkmcnt(0)
	v_bfe_u32 v11, v7, 16, 1
	v_add3_u32 v7, v7, v11, s73
	v_bfe_u32 v11, v10, 16, 1
	v_lshrrev_b32_e32 v7, 16, v7
	v_add3_u32 v10, v10, v11, s73
	v_and_or_b32 v10, v10, s72, v7
	ds_read_b32 v7, v5 offset:824
	ds_read_b32 v11, v5 offset:956
	s_waitcnt lgkmcnt(0)
	v_bfe_u32 v12, v7, 16, 1
	v_add3_u32 v7, v7, v12, s73
	v_bfe_u32 v12, v11, 16, 1
	v_lshrrev_b32_e32 v7, 16, v7
	v_add3_u32 v11, v11, v12, s73
	v_and_or_b32 v11, v11, s72, v7
	v_lshl_add_u64 v[6:7], v[0:1], 0, v[184:185]
	flat_store_dwordx4 v[6:7], v[8:11] nt
	ds_read_b32 v6, v5 offset:64
	ds_read_b32 v7, v5 offset:196
	v_lshlrev_b32_e32 v184, 12, v4
	s_waitcnt lgkmcnt(0)
	v_bfe_u32 v8, v6, 16, 1
	v_add3_u32 v6, v6, v8, s73
	v_bfe_u32 v8, v7, 16, 1
	v_lshrrev_b32_e32 v6, 16, v6
	v_add3_u32 v7, v7, v8, s73
	v_and_or_b32 v6, v7, s72, v6
	ds_read_b32 v7, v5 offset:328
	ds_read_b32 v8, v5 offset:460
	s_waitcnt lgkmcnt(0)
	v_bfe_u32 v9, v7, 16, 1
	v_add3_u32 v7, v7, v9, s73
	v_bfe_u32 v9, v8, 16, 1
	v_lshrrev_b32_e32 v7, 16, v7
	v_add3_u32 v8, v8, v9, s73
	v_and_or_b32 v7, v8, s72, v7
	ds_read_b32 v8, v5 offset:592
	ds_read_b32 v9, v5 offset:724
	s_waitcnt lgkmcnt(0)
	v_bfe_u32 v10, v8, 16, 1
	v_add3_u32 v8, v8, v10, s73
	v_bfe_u32 v10, v9, 16, 1
	v_lshrrev_b32_e32 v8, 16, v8
	v_add3_u32 v9, v9, v10, s73
	v_and_or_b32 v8, v9, s72, v8
	ds_read_b32 v9, v5 offset:856
	ds_read_b32 v10, v5 offset:988
	s_waitcnt lgkmcnt(0)
	v_bfe_u32 v11, v9, 16, 1
	v_add3_u32 v9, v9, v11, s73
	v_bfe_u32 v11, v10, 16, 1
	v_lshrrev_b32_e32 v9, 16, v9
	v_add3_u32 v10, v10, v11, s73
	v_and_or_b32 v9, v10, s72, v9
	v_lshl_add_u64 v[10:11], v[0:1], 0, v[184:185]
	flat_store_dwordx4 v[10:11], v[6:9] nt
	ds_read_b32 v4, v5 offset:96
	ds_read_b32 v6, v5 offset:228
	v_lshlrev_b32_e32 v184, 12, v2
	v_lshl_add_u64 v[0:1], v[0:1], 0, v[184:185]
	s_waitcnt lgkmcnt(0)
	v_bfe_u32 v7, v4, 16, 1
	v_add3_u32 v4, v4, v7, s73
	v_bfe_u32 v7, v6, 16, 1
	v_lshrrev_b32_e32 v4, 16, v4
	v_add3_u32 v6, v6, v7, s73
	v_and_or_b32 v6, v6, s72, v4
	ds_read_b32 v4, v5 offset:360
	ds_read_b32 v7, v5 offset:492
	s_waitcnt lgkmcnt(0)
	v_bfe_u32 v8, v4, 16, 1
	v_add3_u32 v4, v4, v8, s73
	v_bfe_u32 v8, v7, 16, 1
	v_lshrrev_b32_e32 v4, 16, v4
	v_add3_u32 v7, v7, v8, s73
	v_and_or_b32 v7, v7, s72, v4
	ds_read_b32 v4, v5 offset:624
	ds_read_b32 v8, v5 offset:756
	s_waitcnt lgkmcnt(0)
	v_bfe_u32 v9, v4, 16, 1
	v_add3_u32 v4, v4, v9, s73
	v_bfe_u32 v9, v8, 16, 1
	v_lshrrev_b32_e32 v4, 16, v4
	v_add3_u32 v8, v8, v9, s73
	v_and_or_b32 v8, v8, s72, v4
	ds_read_b32 v4, v5 offset:888
	ds_read_b32 v5, v5 offset:1020
	s_waitcnt lgkmcnt(0)
	v_bfe_u32 v9, v4, 16, 1
	v_add3_u32 v4, v4, v9, s73
	v_bfe_u32 v9, v5, 16, 1
	v_lshrrev_b32_e32 v4, 16, v4
	v_add3_u32 v5, v5, v9, s73
	v_and_or_b32 v9, v5, s72, v4
	flat_store_dwordx4 v[0:1], v[6:9] nt
	s_waitcnt lgkmcnt(0)

; #define LAS __attribute__((address_space(3)))
; __device__ __forceinline__ void atomic_addq(i64* p, float v, float scale) { (void)__hip_atomic_fetch_add((unsigned long long*)p, (unsigned long long)(i64)__builtin_rintf(v * scale), __ATOMIC_RELAXED, __HIP_MEMORY_SCOPE_AGENT); }
; #define LDS_WAIT() asm volatile("s_waitcnt lgkmcnt(0)" ::: "memory")
; __device__ __forceinline__ float bf_round(float f) { return __uint_as_float(f2bf(f) << 16); }
; #define INP(i) (kargs()->in[i])
; template <class Map>
; __device__ __forceinline__ void conv_item(const Frame& F, int it, const float* W, int K, int N, bf16_t* WT, const float* gk, int gmask, float gmul, const float* bk, i64* cs, i64* bw, Map map) {
;     ...
;         const int kb = it / nblk, nb = it % nblk, k0 = 64 * kb, n0 = 32 * nb, v0 = map(n0);
; #pragma unroll
;         for (int i = 0; i < 8; ++i) { const int kk = 8 * i + (lane >> 3), c4 = (lane & 7) * 4;
;             const f32x4 w4 = __builtin_nontemporal_load((const f32x4*)(W + (size_t)(k0 + kk) * N + n0 + c4)); LAS float* d = scr + kk * 33 + c4; d[0] = w4[0]; d[1] = w4[1]; d[2] = w4[2]; d[3] = w4[3]; }
;         LDS_WAIT(); asm volatile("" ::: "memory");
;         if (bk) {
;             const int n = lane & 31, kh = lane >> 5; float sb = 0.f, sc = 0.f;
; #pragma unroll 8
;             for (int j = 0; j < 32; ++j) { const int kk = kh * 32 + j; const float w = scr[kk * 33 + n]; sb += bk[k0 + kk] * w; sc += bf_round(gk[(k0 + kk) & gmask] * gmul * w); }
;             { auto r = __builtin_amdgcn_permlane32_swap(__float_as_uint(sb), __float_as_uint(sb), false, false); sb = __uint_as_float(r[0]) + __uint_as_float(r[1]); }
;             { auto r = __builtin_amdgcn_permlane32_swap(__float_as_uint(sc), __float_as_uint(sc), false, false); sc = __uint_as_float(r[0]) + __uint_as_float(r[1]); }
;             if (lane < 32) { atomic_addq(bw + v0 + n, sb, FX_COL); atomic_addq(cs + v0 + n, sc, FX_COL); }
;         }
;         const int c = lane & 7; float gl[8];
; #pragma unroll
;         for (int i = 0; i < 8; ++i) gl[i] = gk ? gk[(k0 + 8 * c + i) & gmask] * gmul : 1.0f;
; __device__ BG_ATTR void bg_item(const Frame& F, unsigned char* ws, const int L, int id) {
;     ...
;         if (id < NI_UKV) { conv_item(F, id, INP(6) + (size_t)j * MLA_RANK * 4096, MLA_RANK, 4096, Wukv, INP(4) + j * MLA_RANK, MLA_RANK - 1, 1.f, nullptr, nullptr, nullptr, MapIdent()); return; } id -= NI_UKV;
.LBB0_491:
	s_andn2_saveexec_b64 s[12:13], s[46:47]
	s_cbranch_execz .LBB0_509
	v_readlane_b32 s26, v252, 14
	v_readlane_b32 s27, v252, 15
	s_mov_b64 s[16:17], s[26:27]
	s_load_dwordx2 s[16:17], s[16:17], 0x30
	v_add_u32_e32 v0, 0xfffff8c0, v1
	v_readlane_b32 s24, v252, 12
	v_lshrrev_b32_e32 v1, 1, v0
	v_lshlrev_b32_e32 v0, 5, v0
	s_waitcnt lgkmcnt(0)
	s_add_u32 s16, s16, s58
	v_readlane_b32 s25, v252, 13
	v_mov_b32_e32 v14, v220
	v_and_b32_e32 v8, 0xfe0, v0
	s_addc_u32 s17, s17, s59
	s_load_dwordx2 s[38:39], s[26:27], 0x20
	v_lshlrev_b32_e32 v184, 2, v8
	v_lshlrev_b32_e32 v2, 4, v14
	v_and_b32_e32 v13, 0x7fc0, v1
	v_bfe_u32 v12, v14, 3, 3
	v_lshl_add_u64 v[0:1], s[16:17], 0, v[184:185]
	v_and_b32_e32 v184, 0x70, v2
	v_lshl_add_u64 v[4:5], v[0:1], 0, v[184:185]
	v_or_b32_e32 v0, v12, v13
	v_lshlrev_b32_e32 v6, 14, v0
	v_mov_b32_e32 v7, v185
	v_lshl_add_u64 v[0:1], v[4:5], 0, v[6:7]
	global_load_dwordx4 v[132:135], v[0:1], off nt
	v_mul_u32_u24_e32 v7, 0x84, v12
	v_add3_u32 v7, s79, v184, v7
	v_or_b32_e32 v11, 8, v12
	v_add_u32_e32 v9, 0x420, v7
	v_or_b32_e32 v10, 16, v12
	v_add_u32_e32 v15, 0xc60, v7
	s_lshl_b64 s[26:27], s[60:61], 2
	s_waitcnt lgkmcnt(0)
	s_add_u32 s26, s38, s26
	v_and_b32_e32 v14, 7, v14
	s_addc_u32 s27, s39, s27
	s_cmp_lg_u64 s[38:39], 0
	s_cselect_b64 s[40:41], -1, 0
	s_cmp_eq_u64 s[38:39], 0
	v_or_b32_e32 v0, v11, v13
	v_lshlrev_b32_e32 v184, 14, v0
	v_lshl_add_u64 v[0:1], v[4:5], 0, v[184:185]
	global_load_dwordx4 v[136:139], v[0:1], off nt
	v_add_u32_e32 v0, 0x428, v7
	v_or_b32_e32 v0, v10, v13
	v_lshlrev_b32_e32 v184, 14, v0
	v_lshl_add_u64 v[0:1], v[4:5], 0, v[184:185]
	global_load_dwordx4 v[140:143], v[0:1], off nt
	v_add_u32_e32 v9, 0x840, v7
	v_add_u32_e32 v0, 0x848, v7
	v_or_b32_e32 v9, 24, v12
	v_or_b32_e32 v0, v9, v13
	v_lshlrev_b32_e32 v184, 14, v0
	v_lshl_add_u64 v[0:1], v[4:5], 0, v[184:185]
	global_load_dwordx4 v[144:147], v[0:1], off nt
	v_or_b32_e32 v184, 0x80000, v6
	v_add_u32_e32 v0, 0xc68, v7
	v_lshl_add_u64 v[0:1], v[4:5], 0, v[184:185]
	global_load_dwordx4 v[148:151], v[0:1], off nt
	v_add_u32_e32 v15, 0x1080, v7
	v_or_b32_e32 v184, 0xa0000, v6
	v_add_u32_e32 v0, 0x1088, v7
	v_lshl_add_u64 v[0:1], v[4:5], 0, v[184:185]
	global_load_dwordx4 v[152:155], v[0:1], off nt
	v_add_u32_e32 v15, 0x14a0, v7
	v_or_b32_e32 v184, 0xc0000, v6
	v_add_u32_e32 v0, 0x14a8, v7
	v_lshl_add_u64 v[0:1], v[4:5], 0, v[184:185]
	global_load_dwordx4 v[156:159], v[0:1], off nt
	v_add_u32_e32 v15, 0x18c0, v7
	v_or_b32_e32 v184, 0xe0000, v6
	v_add_u32_e32 v0, 0x18c8, v7
	v_lshl_add_u64 v[0:1], v[4:5], 0, v[184:185]
	global_load_dwordx4 v[160:163], v[0:1], off nt
	v_add_u32_e32 v4, 0x1ce0, v7
	v_lshlrev_b32_e32 v15, 3, v14
	v_add_u32_e32 v0, 0x1ce8, v7
	s_waitcnt vmcnt(0)
	v_add_u32_e32 v164, 0x0, v7
	ds_write2_b32 v164, v132, v133 offset1:1
	ds_write2_b32 v164, v134, v135 offset0:2 offset1:3
	v_add_u32_e32 v164, 0x420, v7
	ds_write2_b32 v164, v136, v137 offset1:1
	ds_write2_b32 v164, v138, v139 offset0:2 offset1:3
	v_add_u32_e32 v164, 0x840, v7
	ds_write2_b32 v164, v140, v141 offset1:1
	ds_write2_b32 v164, v142, v143 offset0:2 offset1:3
	v_add_u32_e32 v164, 0xc60, v7
	ds_write2_b32 v164, v144, v145 offset1:1
	ds_write2_b32 v164, v146, v147 offset0:2 offset1:3
	v_add_u32_e32 v164, 0x1080, v7
	ds_write2_b32 v164, v148, v149 offset1:1
	ds_write2_b32 v164, v150, v151 offset0:2 offset1:3
	v_add_u32_e32 v164, 0x14a0, v7
	ds_write2_b32 v164, v152, v153 offset1:1
	ds_write2_b32 v164, v154, v155 offset0:2 offset1:3
	v_add_u32_e32 v164, 0x18c0, v7
	ds_write2_b32 v164, v156, v157 offset1:1
	ds_write2_b32 v164, v158, v159 offset0:2 offset1:3
	v_add_u32_e32 v164, 0x1ce0, v7
	ds_write2_b32 v164, v160, v161 offset1:1
	ds_write2_b32 v164, v162, v163 offset0:2 offset1:3
	s_waitcnt lgkmcnt(0)
	v_or_b32_e32 v1, v15, v13
	v_mov_b32_e32 v0, 1.0
	v_lshlrev_b32_e32 v16, 2, v1
	v_mov_b32_e32 v2, 1.0
	s_cbranch_scc1 .LBB0_494
	global_load_dword v2, v16, s[26:27]

; #define LAS __attribute__((address_space(3)))
; __device__ __forceinline__ void atomic_addq(i64* p, float v, float scale) { (void)__hip_atomic_fetch_add((unsigned long long*)p, (unsigned long long)(i64)__builtin_rintf(v * scale), __ATOMIC_RELAXED, __HIP_MEMORY_SCOPE_AGENT); }
; #define LDS_WAIT() asm volatile("s_waitcnt lgkmcnt(0)" ::: "memory")
; __device__ __forceinline__ float bf_round(float f) { return __uint_as_float(f2bf(f) << 16); }
; #define INP(i) (kargs()->in[i])
; template <class Map>
; __device__ __forceinline__ void conv_item(const Frame& F, int it, const float* W, int K, int N, bf16_t* WT, const float* gk, int gmask, float gmul, const float* bk, i64* cs, i64* bw, Map map) {
;     ...
;         const int kb = it / nblk, nb = it % nblk, k0 = 64 * kb, n0 = 32 * nb, v0 = map(n0);
; #pragma unroll
;         for (int i = 0; i < 8; ++i) { const int kk = 8 * i + (lane >> 3), c4 = (lane & 7) * 4;
;             const f32x4 w4 = __builtin_nontemporal_load((const f32x4*)(W + (size_t)(k0 + kk) * N + n0 + c4)); LAS float* d = scr + kk * 33 + c4; d[0] = w4[0]; d[1] = w4[1]; d[2] = w4[2]; d[3] = w4[3]; }
;         LDS_WAIT(); asm volatile("" ::: "memory");
;         if (bk) {
;             const int n = lane & 31, kh = lane >> 5; float sb = 0.f, sc = 0.f;
; #pragma unroll 8
;             for (int j = 0; j < 32; ++j) { const int kk = kh * 32 + j; const float w = scr[kk * 33 + n]; sb += bk[k0 + kk] * w; sc += bf_round(gk[(k0 + kk) & gmask] * gmul * w); }
;             { auto r = __builtin_amdgcn_permlane32_swap(__float_as_uint(sb), __float_as_uint(sb), false, false); sb = __uint_as_float(r[0]) + __uint_as_float(r[1]); }
;             { auto r = __builtin_amdgcn_permlane32_swap(__float_as_uint(sc), __float_as_uint(sc), false, false); sc = __uint_as_float(r[0]) + __uint_as_float(r[1]); }
;             if (lane < 32) { atomic_addq(bw + v0 + n, sb, FX_COL); atomic_addq(cs + v0 + n, sc, FX_COL); }
;         }
;         const int c = lane & 7; float gl[8];
; #pragma unroll
;         for (int i = 0; i < 8; ++i) gl[i] = gk ? gk[(k0 + 8 * c + i) & gmask] * gmul : 1.0f;
; __device__ BG_ATTR void bg_item(const Frame& F, unsigned char* ws, const int L, int id) {
;     ...
;         if (id < NI_UQ) { conv_item(F, id, INP(5) + (size_t)j * MLA_RANK * 3072, MLA_RANK, 3072, Wuq, INP(3) + j * MLA_RANK, MLA_RANK - 1, 1.f, nullptr, nullptr, nullptr, MapMlaUq()); return; } id -= NI_UQ;
.LBB0_510:
	s_andn2_saveexec_b64 s[6:7], s[6:7]
	s_cbranch_execz .LBB0_532
	v_add_u16_e32 v2, 0xfbc0, v1
	v_mul_u32_u24_e32 v1, 0xaaab, v2
	v_lshrrev_b32_e32 v1, 22, v1
	v_mul_lo_u16_e32 v3, 0x60, v1
	v_sub_u16_e32 v3, v2, v3
	v_lshlrev_b16_e32 v2, 5, v3
	v_mul_u32_u24_e32 v4, 0x2aab, v2
	v_lshrrev_b32_e32 v4, 21, v4
	v_readlane_b32 s24, v252, 14
	v_mul_lo_u16_e32 v4, 0xc0, v4
	v_readlane_b32 s25, v252, 15
	v_readlane_b32 s12, v252, 12
	v_mul_lo_u16_e32 v3, 0xab, v3
	v_sub_u16_e32 v4, v2, v4
	s_movk_i32 s26, 0x7f
	s_mov_b64 s[16:17], s[24:25]
	v_readlane_b32 s13, v252, 13
	v_mov_b32_e32 v0, v220
	v_lshrrev_b16_e32 v3, 10, v3
	v_cmp_lt_u16_e32 vcc, s26, v4
	s_and_saveexec_b64 s[26:27], vcc
	s_xor_b64 s[26:27], exec, s[26:27]
	v_lshlrev_b32_e32 v5, 6, v3
	v_and_b32_e32 v5, 0x700, v5
	v_lshlrev_b32_e32 v3, 5, v3
	v_lshl_add_u32 v4, v4, 2, v5
	v_and_b32_e32 v3, 0x60, v3
	s_movk_i32 s38, 0x600
	v_add3_u32 v8, v4, v3, s38
	s_or_saveexec_b64 s[38:39], s[26:27]
	s_load_dwordx2 s[16:17], s[16:17], 0x28
	s_nop 0
	s_load_dwordx2 s[26:27], s[24:25], 0x18
	s_xor_b64 exec, exec, s[38:39]
	v_lshl_or_b32 v8, v3, 7, v4
	s_or_b64 exec, exec, s[38:39]
	s_waitcnt lgkmcnt(0)
	s_add_u32 s16, s16, s43
	s_addc_u32 s17, s17, s21
	v_lshlrev_b16_e32 v13, 6, v1
	v_bfe_u32 v12, v0, 3, 3
	v_lshlrev_b32_e32 v184, 2, v2
	v_lshlrev_b32_e32 v1, 4, v0
	v_lshl_add_u64 v[2:3], s[16:17], 0, v[184:185]
	v_and_b32_e32 v184, 0x70, v1
	v_or_b32_e32 v1, v12, v13
	v_lshl_add_u64 v[6:7], v[2:3], 0, v[184:185]
	v_mul_u32_u24_e32 v2, 0x3000, v1
	v_mov_b32_e32 v3, v185
	v_lshl_add_u64 v[2:3], v[6:7], 0, v[2:3]
	global_load_dwordx4 v[132:135], v[2:3], off nt
	v_mul_u32_u24_e32 v9, 0x84, v12
	v_add3_u32 v14, s79, v184, v9
	v_or_b32_e32 v11, 8, v12
	v_add_u32_e32 v9, 0x420, v14
	v_or_b32_e32 v10, 16, v12
	v_add_u32_e32 v15, 0xc60, v14
	s_lshl_b64 s[24:25], s[60:61], 2
	s_add_u32 s24, s26, s24
	s_addc_u32 s25, s27, s25
	s_movk_i32 s16, 0x1c0
	s_cmp_lg_u64 s[26:27], 0
	s_cselect_b64 s[40:41], -1, 0
	s_cmp_eq_u64 s[26:27], 0
	v_or_b32_e32 v2, v11, v13
	v_mul_u32_u24_e32 v184, 0x3000, v2
	v_lshl_add_u64 v[2:3], v[6:7], 0, v[184:185]
	global_load_dwordx4 v[136:139], v[2:3], off nt
	v_add_u32_e32 v2, 0x428, v14
	v_or_b32_e32 v2, v10, v13
	v_mul_u32_u24_e32 v184, 0x3000, v2
	v_lshl_add_u64 v[2:3], v[6:7], 0, v[184:185]
	global_load_dwordx4 v[140:143], v[2:3], off nt
	v_add_u32_e32 v9, 0x840, v14
	v_add_u32_e32 v2, 0x848, v14
	v_or_b32_e32 v9, 24, v12
	v_or_b32_e32 v2, v9, v13
	v_mul_u32_u24_e32 v184, 0x3000, v2
	v_lshl_add_u64 v[2:3], v[6:7], 0, v[184:185]
	global_load_dwordx4 v[144:147], v[2:3], off nt
	v_add_u32_e32 v2, 0xc68, v14
	v_or_b32_e32 v2, 32, v1
	v_mul_u32_u24_e32 v184, 0x3000, v2
	v_lshl_add_u64 v[2:3], v[6:7], 0, v[184:185]
	global_load_dwordx4 v[148:151], v[2:3], off nt
	v_add_u32_e32 v15, 0x1080, v14
	v_add_u32_e32 v2, 0x1088, v14
	v_or_b32_e32 v2, 40, v1
	v_mul_u32_u24_e32 v184, 0x3000, v2
	v_lshl_add_u64 v[2:3], v[6:7], 0, v[184:185]
	global_load_dwordx4 v[152:155], v[2:3], off nt
	v_add_u32_e32 v15, 0x14a0, v14
	v_add_u32_e32 v2, 0x14a8, v14
	v_or_b32_e32 v2, 48, v1
	v_mul_u32_u24_e32 v184, 0x3000, v2
	v_lshl_add_u64 v[2:3], v[6:7], 0, v[184:185]
	global_load_dwordx4 v[156:159], v[2:3], off nt
	v_add_u32_e32 v15, 0x18c0, v14
	v_or_b32_e32 v1, 56, v1
	v_mul_u32_u24_e32 v184, 0x3000, v1
	v_add_u32_e32 v1, 0x1ce0, v14
	v_add_u32_e32 v2, 0x18c8, v14
	v_lshl_add_u64 v[2:3], v[6:7], 0, v[184:185]
	global_load_dwordx4 v[160:163], v[2:3], off nt
	v_add_u32_e32 v1, 0x1ce8, v14
	s_waitcnt vmcnt(0)
	v_add_u32_e32 v164, 0x0, v14
	ds_write2_b32 v164, v132, v133 offset1:1
	ds_write2_b32 v164, v134, v135 offset0:2 offset1:3
	v_add_u32_e32 v164, 0x420, v14
	ds_write2_b32 v164, v136, v137 offset1:1
	ds_write2_b32 v164, v138, v139 offset0:2 offset1:3
	v_add_u32_e32 v164, 0x840, v14
	ds_write2_b32 v164, v140, v141 offset1:1
	ds_write2_b32 v164, v142, v143 offset0:2 offset1:3
	v_add_u32_e32 v164, 0xc60, v14
	ds_write2_b32 v164, v144, v145 offset1:1
	ds_write2_b32 v164, v146, v147 offset0:2 offset1:3
	v_add_u32_e32 v164, 0x1080, v14
	ds_write2_b32 v164, v148, v149 offset1:1
	ds_write2_b32 v164, v150, v151 offset0:2 offset1:3
	v_add_u32_e32 v164, 0x14a0, v14
	ds_write2_b32 v164, v152, v153 offset1:1
	ds_write2_b32 v164, v154, v155 offset0:2 offset1:3
	v_add_u32_e32 v164, 0x18c0, v14
	ds_write2_b32 v164, v156, v157 offset1:1
	ds_write2_b32 v164, v158, v159 offset0:2 offset1:3
	v_add_u32_e32 v164, 0x1ce0, v14
	ds_write2_b32 v164, v160, v161 offset1:1
	ds_write2_b32 v164, v162, v163 offset0:2 offset1:3
	s_waitcnt lgkmcnt(0)
	v_and_b32_e32 v14, 7, v0
	v_lshlrev_b32_e32 v15, 3, v14
	v_and_or_b32 v1, v13, s16, v15
	v_mov_b32_e32 v0, 1.0
	v_lshlrev_b32_e32 v16, 2, v1
	v_mov_b32_e32 v2, 1.0
	s_cbranch_scc1 .LBB0_517
	global_load_dword v2, v16, s[24:25]

; #define LAS __attribute__((address_space(3)))
; template <class Map>
; __device__ __forceinline__ void conv_item(const Frame& F, int it, const float* W, int K, int N, bf16_t* WT, const float* gk, int gmask, float gmul, const float* bk, i64* cs, i64* bw, Map map) {
;     ...
;         const int kb = it / nblk, nb = it % nblk, k0 = 64 * kb, n0 = 32 * nb, v0 = map(n0);
; #pragma unroll
;         for (int i = 0; i < 8; ++i) { const int kk = 8 * i + (lane >> 3), c4 = (lane & 7) * 4;
;             const f32x4 w4 = __builtin_nontemporal_load((const f32x4*)(W + (size_t)(k0 + kk) * N + n0 + c4)); LAS float* d = scr + kk * 33 + c4; d[0] = w4[0]; d[1] = w4[1]; d[2] = w4[2]; d[3] = w4[3]; }
;         LDS_WAIT(); asm volatile("" ::: "memory");
;         if (bk) {
;             const int n = lane & 31, kh = lane >> 5; float sb = 0.f, sc = 0.f;
; #pragma unroll 8
;             for (int j = 0; j < 32; ++j) { const int kk = kh * 32 + j; const float w = scr[kk * 33 + n]; sb += bk[k0 + kk] * w; sc += bf_round(gk[(k0 + kk) & gmask] * gmul * w); }
;             { auto r = __builtin_amdgcn_permlane32_swap(__float_as_uint(sb), __float_as_uint(sb), false, false); sb = __uint_as_float(r[0]) + __uint_as_float(r[1]); }
;             { auto r = __builtin_amdgcn_permlane32_swap(__float_as_uint(sc), __float_as_uint(sc), false, false); sc = __uint_as_float(r[0]) + __uint_as_float(r[1]); }
;             if (lane < 32) { atomic_addq(bw + v0 + n, sb, FX_COL); atomic_addq(cs + v0 + n, sc, FX_COL); }
;         }
;         const int c = lane & 7; float gl[8];
; #pragma unroll
;         for (int i = 0; i < 8; ++i) gl[i] = gk ? gk[(k0 + 8 * c + i) & gmask] * gmul : 1.0f;
; #pragma unroll
;         for (int j = 0; j < 4; ++j) { const int n = (lane >> 3) + 8 * j; const LAS float* s = scr + (8 * c) * 33 + n;
;             u32x4 o; o.x = pk2(s[0 * 33] * gl[0], s[1 * 33] * gl[1]); o.y = pk2(s[2 * 33] * gl[2], s[3 * 33] * gl[3]); o.z = pk2(s[4 * 33] * gl[4], s[5 * 33] * gl[5]); o.w = pk2(s[6 * 33] * gl[6], s[7 * 33] * gl[7]);
;             __builtin_nontemporal_store(o, (u32x4*)(WT + (size_t)(v0 + n) * K + k0 + 8 * c)); }
; __device__ BG_ATTR void bg_item(const Frame& F, unsigned char* ws, const int L, int id) {
;     ...
;         if (id < NI_MIX) { conv_item(F, id, INP(2) + (size_t)j * DM * MLA_IN, DM, MLA_IN, Wmix, nullptr, 0, 1.f, nullptr, nullptr, nullptr, MapMlaIn()); return; } id -= NI_MIX;
.LBB0_533:
	s_andn2_saveexec_b64 s[6:7], s[92:93]
	s_cbranch_execz .LBB0_535
	v_readlane_b32 s12, v252, 14
	v_readlane_b32 s13, v252, 15
	s_load_dwordx2 s[12:13], s[12:13], 0x10
	s_mov_b32 s24, 0xf0f1
	v_mul_u32_u24_sdwa v0, v1, s24 dst_sel:DWORD dst_unused:UNUSED_PAD src0_sel:WORD_0 src1_sel:DWORD
	v_lshrrev_b32_e32 v0, 21, v0
	v_mul_lo_u16_e32 v2, 34, v0
	s_waitcnt lgkmcnt(0)
	s_add_u32 s16, s12, s54
	s_addc_u32 s17, s13, s52
	v_readlane_b32 s12, v252, 12
	v_sub_u16_e32 v14, v1, v2
	v_readlane_b32 s13, v252, 13
	v_mov_b32_e32 v6, v220
	v_lshlrev_b16_e32 v16, 5, v14
	v_lshlrev_b16_e32 v15, 6, v0
	v_bfe_u32 v7, v6, 3, 3
	v_lshlrev_b32_e32 v184, 2, v16
	v_lshlrev_b32_e32 v2, 4, v6
	v_lshl_add_u64 v[0:1], s[16:17], 0, v[184:185]
	v_and_b32_e32 v184, 0x70, v2
	v_or_b32_e32 v24, v7, v15
	v_lshl_add_u64 v[12:13], v[0:1], 0, v[184:185]
	v_mul_u32_u24_e32 v0, 0x1100, v24
	v_mov_b32_e32 v1, v185
	v_lshl_add_u64 v[0:1], v[12:13], 0, v[0:1]
	global_load_dwordx4 v[132:135], v[0:1], off nt
	v_mul_u32_u24_e32 v4, 0x84, v7
	v_add3_u32 v25, s79, v184, v4
	v_or_b32_e32 v5, 8, v7
	v_add_u32_e32 v4, 0x420, v25
	v_add_u32_e32 v8, 0x840, v25
	v_add_u32_e32 v17, 0x60, v16
	v_cmp_gt_u16_e32 vcc, 33, v14
	v_or_b32_e32 v0, v5, v15
	v_mul_u32_u24_e32 v184, 0x1100, v0
	v_lshl_add_u64 v[0:1], v[12:13], 0, v[184:185]
	global_load_dwordx4 v[136:139], v[0:1], off nt
	v_add_u32_e32 v0, 0x428, v25
	v_or_b32_e32 v4, 16, v7
	v_or_b32_e32 v0, v4, v15
	v_mul_u32_u24_e32 v184, 0x1100, v0
	v_lshl_add_u64 v[0:1], v[12:13], 0, v[184:185]
	global_load_dwordx4 v[140:143], v[0:1], off nt
	v_add_u32_e32 v0, 0x848, v25
	v_or_b32_e32 v2, 24, v7
	v_or_b32_e32 v0, v2, v15
	v_mul_u32_u24_e32 v184, 0x1100, v0
	v_lshl_add_u64 v[0:1], v[12:13], 0, v[184:185]
	global_load_dwordx4 v[144:147], v[0:1], off nt
	v_add_u32_e32 v0, 0xc60, v25
	v_cndmask_b32_e32 v3, v17, v16, vcc
	v_or_b32_e32 v5, v5, v3
	v_or_b32_e32 v4, v4, v3
	v_or_b32_e32 v2, v2, v3
	v_add_u32_e32 v0, 0xc68, v25
	v_or_b32_e32 v0, 32, v24
	v_mul_u32_u24_e32 v184, 0x1100, v0
	v_lshl_add_u64 v[0:1], v[12:13], 0, v[184:185]
	global_load_dwordx4 v[148:151], v[0:1], off nt
	v_add_u32_e32 v0, 0x1080, v25
	v_add_u32_e32 v0, 0x1088, v25
	v_or_b32_e32 v0, 40, v24
	v_mul_u32_u24_e32 v184, 0x1100, v0
	v_lshl_add_u64 v[0:1], v[12:13], 0, v[184:185]
	global_load_dwordx4 v[152:155], v[0:1], off nt
	v_add_u32_e32 v0, 0x14a0, v25
	v_add_u32_e32 v0, 0x14a8, v25
	v_or_b32_e32 v0, 48, v24
	v_mul_u32_u24_e32 v184, 0x1100, v0
	v_lshl_add_u64 v[0:1], v[12:13], 0, v[184:185]
	global_load_dwordx4 v[156:159], v[0:1], off nt
	v_add_u32_e32 v0, 0x18c0, v25
	v_add_u32_e32 v0, 0x18c8, v25
	v_or_b32_e32 v0, 56, v24
	v_mul_u32_u24_e32 v184, 0x1100, v0
	v_lshl_add_u64 v[0:1], v[12:13], 0, v[184:185]
	global_load_dwordx4 v[160:163], v[0:1], off nt
	v_add_u32_e32 v0, 0x1ce0, v25
	v_lshlrev_b32_e32 v184, 1, v15
	v_add_u32_e32 v0, 0x1ce8, v25
	s_waitcnt vmcnt(0)
	v_add_u32_e32 v164, 0x0, v25
	ds_write2_b32 v164, v132, v133 offset1:1
	ds_write2_b32 v164, v134, v135 offset0:2 offset1:3
	v_add_u32_e32 v164, 0x420, v25
	ds_write2_b32 v164, v136, v137 offset1:1
	ds_write2_b32 v164, v138, v139 offset0:2 offset1:3
	v_add_u32_e32 v164, 0x840, v25
	ds_write2_b32 v164, v140, v141 offset1:1
	ds_write2_b32 v164, v142, v143 offset0:2 offset1:3
	v_add_u32_e32 v164, 0xc60, v25
	ds_write2_b32 v164, v144, v145 offset1:1
	ds_write2_b32 v164, v146, v147 offset0:2 offset1:3
	v_add_u32_e32 v164, 0x1080, v25
	ds_write2_b32 v164, v148, v149 offset1:1
	ds_write2_b32 v164, v150, v151 offset0:2 offset1:3
	v_add_u32_e32 v164, 0x14a0, v25
	ds_write2_b32 v164, v152, v153 offset1:1
	ds_write2_b32 v164, v154, v155 offset0:2 offset1:3
	v_add_u32_e32 v164, 0x18c0, v25
	ds_write2_b32 v164, v156, v157 offset1:1
	ds_write2_b32 v164, v158, v159 offset0:2 offset1:3
	v_add_u32_e32 v164, 0x1ce0, v25
	ds_write2_b32 v164, v160, v161 offset1:1
	ds_write2_b32 v164, v162, v163 offset0:2 offset1:3
	v_lshlrev_b32_e32 v0, 3, v6
	v_and_b32_e32 v6, 56, v0
	s_waitcnt lgkmcnt(0)
	v_mul_u32_u24_e32 v8, 0x84, v6
	v_lshl_add_u64 v[0:1], s[12:13], 0, v[184:185]
	v_lshlrev_b32_e32 v184, 1, v6
	v_lshlrev_b32_e32 v6, 2, v7
	v_add3_u32 v6, s79, v8, v6
	ds_read_b32 v8, v6
	ds_read_b32 v9, v6 offset:132
	v_lshl_add_u64 v[0:1], v[0:1], 0, v[184:185]
	s_mov_b64 s[12:13], 0x800000
	v_or_b32_e32 v7, v7, v3
	s_waitcnt lgkmcnt(1)
	v_bfe_u32 v10, v8, 16, 1
	v_add3_u32 v8, v8, v10, s73
	s_waitcnt lgkmcnt(0)
; #define LAS __attribute__((address_space(3)))
; #define LDS_WAIT() asm volatile("s_waitcnt lgkmcnt(0)" ::: "memory")
; __device__ __forceinline__ unsigned pk2(float lo, float hi) { return f2bf(lo) | (f2bf(hi) << 16); }
; template <class Map>
; __device__ __forceinline__ void conv_item(const Frame& F, int it, const float* W, int K, int N, bf16_t* WT, const float* gk, int gmask, float gmul, const float* bk, i64* cs, i64* bw, Map map) {
;     ...
;         const int c = lane & 7; float gl[8];
; #pragma unroll
;         for (int i = 0; i < 8; ++i) gl[i] = gk ? gk[(k0 + 8 * c + i) & gmask] * gmul : 1.0f;
; #pragma unroll
;         for (int j = 0; j < 4; ++j) { const int n = (lane >> 3) + 8 * j; const LAS float* s = scr + (8 * c) * 33 + n;
;             u32x4 o; o.x = pk2(s[0 * 33] * gl[0], s[1 * 33] * gl[1]); o.y = pk2(s[2 * 33] * gl[2], s[3 * 33] * gl[3]); o.z = pk2(s[4 * 33] * gl[4], s[5 * 33] * gl[5]); o.w = pk2(s[6 * 33] * gl[6], s[7 * 33] * gl[7]);
;             __builtin_nontemporal_store(o, (u32x4*)(WT + (size_t)(v0 + n) * K + k0 + 8 * c)); }
;         LDS_WAIT(); asm volatile("" ::: "memory");
	v_bfe_u32 v10, v9, 16, 1
	v_lshrrev_b32_e32 v8, 16, v8
	v_add3_u32 v9, v9, v10, s73
	v_and_or_b32 v8, v9, s72, v8
	ds_read_b32 v9, v6 offset:264
	ds_read_b32 v10, v6 offset:396
	v_lshl_add_u64 v[0:1], v[0:1], 0, s[12:13]
	v_lshlrev_b32_e32 v184, 12, v7
	s_waitcnt lgkmcnt(1)
	v_bfe_u32 v11, v9, 16, 1
	v_add3_u32 v9, v9, v11, s73
	s_waitcnt lgkmcnt(0)
	v_bfe_u32 v11, v10, 16, 1
	v_lshrrev_b32_e32 v9, 16, v9
	v_add3_u32 v10, v10, v11, s73
	v_and_or_b32 v9, v10, s72, v9
	ds_read_b32 v10, v6 offset:528
	ds_read_b32 v11, v6 offset:660
	s_waitcnt lgkmcnt(1)
	v_bfe_u32 v12, v10, 16, 1
	v_add3_u32 v10, v10, v12, s73
	s_waitcnt lgkmcnt(0)
	v_bfe_u32 v12, v11, 16, 1
	v_lshrrev_b32_e32 v10, 16, v10
	v_add3_u32 v11, v11, v12, s73
	v_and_or_b32 v10, v11, s72, v10
	ds_read_b32 v11, v6 offset:792
	ds_read_b32 v12, v6 offset:924
	s_waitcnt lgkmcnt(1)
	v_bfe_u32 v13, v11, 16, 1
	v_add3_u32 v11, v11, v13, s73
	s_waitcnt lgkmcnt(0)
	v_bfe_u32 v13, v12, 16, 1
	v_lshrrev_b32_e32 v11, 16, v11
	v_add3_u32 v12, v12, v13, s73
	v_and_or_b32 v11, v12, s72, v11
	v_lshl_add_u64 v[12:13], v[0:1], 0, v[184:185]
	flat_store_dwordx4 v[12:13], v[8:11] nt
	ds_read_b32 v7, v6 offset:32
	ds_read_b32 v8, v6 offset:164
	v_lshlrev_b32_e32 v184, 12, v5
	s_waitcnt lgkmcnt(0)
	v_bfe_u32 v9, v7, 16, 1
	v_add3_u32 v7, v7, v9, s73
	v_bfe_u32 v9, v8, 16, 1
	v_lshrrev_b32_e32 v7, 16, v7
	v_add3_u32 v8, v8, v9, s73
	v_and_or_b32 v8, v8, s72, v7
	ds_read_b32 v7, v6 offset:296
	ds_read_b32 v9, v6 offset:428
	s_waitcnt lgkmcnt(0)
	v_bfe_u32 v10, v7, 16, 1
	v_add3_u32 v7, v7, v10, s73
	v_bfe_u32 v10, v9, 16, 1
	v_lshrrev_b32_e32 v7, 16, v7
	v_add3_u32 v9, v9, v10, s73
	v_and_or_b32 v9, v9, s72, v7
	ds_read_b32 v7, v6 offset:560
	ds_read_b32 v10, v6 offset:692
	s_waitcnt lgkmcnt(0)
	v_bfe_u32 v11, v7, 16, 1
	v_add3_u32 v7, v7, v11, s73
	v_bfe_u32 v11, v10, 16, 1
	v_lshrrev_b32_e32 v7, 16, v7
	v_add3_u32 v10, v10, v11, s73
	v_and_or_b32 v10, v10, s72, v7
	ds_read_b32 v7, v6 offset:824
	ds_read_b32 v11, v6 offset:956
	s_waitcnt lgkmcnt(0)
	v_bfe_u32 v12, v7, 16, 1
	v_add3_u32 v7, v7, v12, s73
	v_bfe_u32 v12, v11, 16, 1
	v_lshrrev_b32_e32 v7, 16, v7
	v_add3_u32 v11, v11, v12, s73
	v_and_or_b32 v11, v11, s72, v7
	v_lshl_add_u64 v[12:13], v[0:1], 0, v[184:185]
	flat_store_dwordx4 v[12:13], v[8:11] nt
	ds_read_b32 v5, v6 offset:64
	ds_read_b32 v7, v6 offset:196
	v_lshlrev_b32_e32 v184, 12, v4
	s_waitcnt lgkmcnt(0)
	v_bfe_u32 v8, v5, 16, 1
	v_add3_u32 v5, v5, v8, s73
	v_bfe_u32 v8, v7, 16, 1
	v_lshrrev_b32_e32 v5, 16, v5
	v_add3_u32 v7, v7, v8, s73
	v_and_or_b32 v8, v7, s72, v5
	ds_read_b32 v5, v6 offset:328
	ds_read_b32 v7, v6 offset:460
	s_waitcnt lgkmcnt(0)
	v_bfe_u32 v9, v5, 16, 1
	v_add3_u32 v5, v5, v9, s73
	v_bfe_u32 v9, v7, 16, 1
	v_lshrrev_b32_e32 v5, 16, v5
	v_add3_u32 v7, v7, v9, s73
	v_and_or_b32 v9, v7, s72, v5
	ds_read_b32 v5, v6 offset:592
	ds_read_b32 v7, v6 offset:724
	s_waitcnt lgkmcnt(0)
	v_bfe_u32 v10, v5, 16, 1
	v_add3_u32 v5, v5, v10, s73
	v_bfe_u32 v10, v7, 16, 1
	v_lshrrev_b32_e32 v5, 16, v5
	v_add3_u32 v7, v7, v10, s73
	v_and_or_b32 v10, v7, s72, v5
	ds_read_b32 v5, v6 offset:856
	ds_read_b32 v7, v6 offset:988
	s_waitcnt lgkmcnt(0)
	v_bfe_u32 v11, v5, 16, 1
	v_add3_u32 v5, v5, v11, s73
	v_bfe_u32 v11, v7, 16, 1
	v_lshrrev_b32_e32 v5, 16, v5
	v_add3_u32 v7, v7, v11, s73
	v_and_or_b32 v11, v7, s72, v5
	v_lshl_add_u64 v[4:5], v[0:1], 0, v[184:185]
	flat_store_dwordx4 v[4:5], v[8:11] nt
	ds_read_b32 v4, v6 offset:96
	ds_read_b32 v5, v6 offset:228
	v_lshlrev_b32_e32 v184, 12, v2
	v_lshl_add_u64 v[0:1], v[0:1], 0, v[184:185]
	s_waitcnt lgkmcnt(0)
	v_bfe_u32 v7, v4, 16, 1
	v_add3_u32 v4, v4, v7, s73
	v_bfe_u32 v7, v5, 16, 1
	v_lshrrev_b32_e32 v4, 16, v4
	v_add3_u32 v5, v5, v7, s73
	v_and_or_b32 v8, v5, s72, v4
	ds_read_b32 v4, v6 offset:360
	ds_read_b32 v5, v6 offset:492
	s_waitcnt lgkmcnt(0)
	v_bfe_u32 v7, v4, 16, 1
	v_add3_u32 v4, v4, v7, s73
	v_bfe_u32 v7, v5, 16, 1
	v_lshrrev_b32_e32 v4, 16, v4
	v_add3_u32 v5, v5, v7, s73
	v_and_or_b32 v9, v5, s72, v4
	ds_read_b32 v4, v6 offset:624
	ds_read_b32 v5, v6 offset:756
	s_waitcnt lgkmcnt(0)
	v_bfe_u32 v7, v4, 16, 1
	v_add3_u32 v4, v4, v7, s73
	v_bfe_u32 v7, v5, 16, 1
	v_lshrrev_b32_e32 v4, 16, v4
	v_add3_u32 v5, v5, v7, s73
	v_and_or_b32 v10, v5, s72, v4
	ds_read_b32 v4, v6 offset:888
	ds_read_b32 v5, v6 offset:1020
	s_waitcnt lgkmcnt(0)
	v_bfe_u32 v6, v4, 16, 1
	v_add3_u32 v4, v4, v6, s73
	v_bfe_u32 v6, v5, 16, 1
	v_lshrrev_b32_e32 v4, 16, v4
	v_add3_u32 v5, v5, v6, s73
	v_and_or_b32 v11, v5, s72, v4
	flat_store_dwordx4 v[0:1], v[8:11] nt
	s_waitcnt lgkmcnt(0)

; #define LAS __attribute__((address_space(3)))
; template <class Map>
; __device__ __forceinline__ void conv_item(const Frame& F, int it, const float* W, int K, int N, bf16_t* WT, const float* gk, int gmask, float gmul, const float* bk, i64* cs, i64* bw, Map map) {
;     ...
;         const int kb = it / nblk, nb = it % nblk, k0 = 64 * kb, n0 = 32 * nb, v0 = map(n0);
; #pragma unroll
;         for (int i = 0; i < 8; ++i) { const int kk = 8 * i + (lane >> 3), c4 = (lane & 7) * 4;
;             const f32x4 w4 = __builtin_nontemporal_load((const f32x4*)(W + (size_t)(k0 + kk) * N + n0 + c4)); LAS float* d = scr + kk * 33 + c4; d[0] = w4[0]; d[1] = w4[1]; d[2] = w4[2]; d[3] = w4[3]; }
;         LDS_WAIT(); asm volatile("" ::: "memory");
;         if (bk) {
;             const int n = lane & 31, kh = lane >> 5; float sb = 0.f, sc = 0.f;
; #pragma unroll 8
;             for (int j = 0; j < 32; ++j) { const int kk = kh * 32 + j; const float w = scr[kk * 33 + n]; sb += bk[k0 + kk] * w; sc += bf_round(gk[(k0 + kk) & gmask] * gmul * w); }
;             { auto r = __builtin_amdgcn_permlane32_swap(__float_as_uint(sb), __float_as_uint(sb), false, false); sb = __uint_as_float(r[0]) + __uint_as_float(r[1]); }
;             { auto r = __builtin_amdgcn_permlane32_swap(__float_as_uint(sc), __float_as_uint(sc), false, false); sc = __uint_as_float(r[0]) + __uint_as_float(r[1]); }
;             if (lane < 32) { atomic_addq(bw + v0 + n, sb, FX_COL); atomic_addq(cs + v0 + n, sc, FX_COL); }
;         }
;         const int c = lane & 7; float gl[8];
; #pragma unroll
;         for (int i = 0; i < 8; ++i) gl[i] = gk ? gk[(k0 + 8 * c + i) & gmask] * gmul : 1.0f;
; #pragma unroll
;         for (int j = 0; j < 4; ++j) { const int n = (lane >> 3) + 8 * j; const LAS float* s = scr + (8 * c) * 33 + n;
;             u32x4 o; o.x = pk2(s[0 * 33] * gl[0], s[1 * 33] * gl[1]); o.y = pk2(s[2 * 33] * gl[2], s[3 * 33] * gl[3]); o.z = pk2(s[4 * 33] * gl[4], s[5 * 33] * gl[5]); o.w = pk2(s[6 * 33] * gl[6], s[7 * 33] * gl[7]);
;             __builtin_nontemporal_store(o, (u32x4*)(WT + (size_t)(v0 + n) * K + k0 + 8 * c)); }
; __device__ BG_ATTR void bg_item(const Frame& F, unsigned char* ws, const int L, int id) {
;     ...
;         if (id < NI_DMIX) { conv_item(F, id, INP(8) + (size_t)j * DM * 6144, DM, 6144, Wmix, nullptr, 0, 1.f, nullptr, nullptr, nullptr, MapIdent()); return; } id -= NI_DMIX;
.LBB0_642:
	v_readlane_b32 s12, v252, 14
	v_readlane_b32 s13, v252, 15
	s_load_dwordx2 s[12:13], s[12:13], 0x40
	v_mov_b32_e32 v5, v220
	v_mov_b32_e32 v1, v185
	s_waitcnt lgkmcnt(0)
	s_add_u32 s24, s12, s79
	s_addc_u32 s25, s13, s78
	s_and_b32 s16, s86, 0xffff
	s_mul_i32 s16, s16, 0xaaab
	s_lshr_b32 s17, s16, 23
	s_mul_i32 s16, s17, 0xc0
	s_sub_i32 s16, s86, s16
	v_readlane_b32 s12, v252, 12
	s_lshl_b32 s16, s16, 5
	v_readlane_b32 s13, v252, 13
	s_and_b32 s16, s16, 0xffe0
	s_lshl_b32 s26, s17, 6
	v_bfe_u32 v6, v5, 3, 3
	s_lshl_b32 s27, s16, 2
	s_add_u32 s24, s24, s27
	v_lshlrev_b32_e32 v0, 4, v5
	v_or_b32_e32 v7, s26, v6
	s_addc_u32 s25, s25, 0
	v_and_b32_e32 v184, 0x70, v0
	v_mul_u32_u24_e32 v0, 0x1800, v7
	v_lshl_add_u64 v[14:15], s[24:25], 0, v[184:185]
	v_lshlrev_b32_e32 v0, 2, v0
	v_lshl_add_u64 v[0:1], v[14:15], 0, v[0:1]
	global_load_dwordx4 v[132:135], v[0:1], off nt
	v_mul_u32_u24_e32 v4, 0x84, v6
	v_readlane_b32 s24, v255, 17
	s_lshl_b32 s17, s17, 7
	s_add_u32 s12, s12, s17
	v_add3_u32 v16, s24, v184, v4
	v_or_b32_e32 v4, 8, v6
	v_add_u32_e32 v8, 0x420, v16
	s_addc_u32 s13, s13, 0
	v_or_b32_e32 v0, s26, v4
	v_mul_u32_u24_e32 v0, 0x1800, v0
	v_lshlrev_b32_e32 v184, 2, v0
	v_lshl_add_u64 v[0:1], v[14:15], 0, v[184:185]
	global_load_dwordx4 v[136:139], v[0:1], off nt
	v_or_b32_e32 v4, s16, v4
	v_add_u32_e32 v0, 0x428, v16
	v_or_b32_e32 v3, 16, v6
	v_or_b32_e32 v0, s26, v3
	v_mul_u32_u24_e32 v0, 0x1800, v0
	v_lshlrev_b32_e32 v184, 2, v0
	v_lshl_add_u64 v[0:1], v[14:15], 0, v[184:185]
	global_load_dwordx4 v[140:143], v[0:1], off nt
	v_add_u32_e32 v0, 0x840, v16
	v_or_b32_e32 v2, 24, v6
	v_or_b32_e32 v3, s16, v3
	v_add_u32_e32 v0, 0x848, v16
	v_or_b32_e32 v0, s26, v2
	v_mul_u32_u24_e32 v0, 0x1800, v0
	v_lshlrev_b32_e32 v184, 2, v0
	v_lshl_add_u64 v[0:1], v[14:15], 0, v[184:185]
	global_load_dwordx4 v[144:147], v[0:1], off nt
	v_add_u32_e32 v0, 0xc60, v16
	v_or_b32_e32 v2, s16, v2
	v_add_u32_e32 v0, 0xc68, v16
	v_or_b32_e32 v0, 32, v7
	v_mul_u32_u24_e32 v0, 0x1800, v0
	v_lshlrev_b32_e32 v184, 2, v0
	v_lshl_add_u64 v[0:1], v[14:15], 0, v[184:185]
	global_load_dwordx4 v[148:151], v[0:1], off nt
	v_add_u32_e32 v0, 0x1080, v16
	v_add_u32_e32 v0, 0x1088, v16
	v_or_b32_e32 v0, 40, v7
	v_mul_u32_u24_e32 v0, 0x1800, v0
	v_lshlrev_b32_e32 v184, 2, v0
	v_lshl_add_u64 v[0:1], v[14:15], 0, v[184:185]
	global_load_dwordx4 v[152:155], v[0:1], off nt
	v_add_u32_e32 v0, 0x14a0, v16
	v_add_u32_e32 v0, 0x14a8, v16
	v_or_b32_e32 v0, 48, v7
	v_mul_u32_u24_e32 v0, 0x1800, v0
	v_lshlrev_b32_e32 v184, 2, v0
	v_lshl_add_u64 v[0:1], v[14:15], 0, v[184:185]
	global_load_dwordx4 v[156:159], v[0:1], off nt
	v_add_u32_e32 v0, 0x18c0, v16
	v_add_u32_e32 v0, 0x18c8, v16
	v_or_b32_e32 v0, 56, v7
	v_mul_u32_u24_e32 v0, 0x1800, v0
	v_lshlrev_b32_e32 v184, 2, v0
	v_lshl_add_u64 v[0:1], v[14:15], 0, v[184:185]
	global_load_dwordx4 v[160:163], v[0:1], off nt
	v_add_u32_e32 v0, 0x1ce0, v16
	v_lshlrev_b32_e32 v7, 2, v6
	v_or_b32_e32 v6, s16, v6
	v_add_u32_e32 v0, 0x1ce8, v16
	s_waitcnt vmcnt(0)
	v_add_u32_e32 v164, 0x0, v16
	ds_write2_b32 v164, v132, v133 offset1:1
	ds_write2_b32 v164, v134, v135 offset0:2 offset1:3
	v_add_u32_e32 v164, 0x420, v16
	ds_write2_b32 v164, v136, v137 offset1:1
	ds_write2_b32 v164, v138, v139 offset0:2 offset1:3
	v_add_u32_e32 v164, 0x840, v16
	ds_write2_b32 v164, v140, v141 offset1:1
	ds_write2_b32 v164, v142, v143 offset0:2 offset1:3
	v_add_u32_e32 v164, 0xc60, v16
	ds_write2_b32 v164, v144, v145 offset1:1
	ds_write2_b32 v164, v146, v147 offset0:2 offset1:3
	v_add_u32_e32 v164, 0x1080, v16
	ds_write2_b32 v164, v148, v149 offset1:1
	ds_write2_b32 v164, v150, v151 offset0:2 offset1:3
	v_add_u32_e32 v164, 0x14a0, v16
	ds_write2_b32 v164, v152, v153 offset1:1
	ds_write2_b32 v164, v154, v155 offset0:2 offset1:3
	v_add_u32_e32 v164, 0x18c0, v16
	ds_write2_b32 v164, v156, v157 offset1:1
	ds_write2_b32 v164, v158, v159 offset0:2 offset1:3
	v_add_u32_e32 v164, 0x1ce0, v16
	ds_write2_b32 v164, v160, v161 offset1:1
	ds_write2_b32 v164, v162, v163 offset0:2 offset1:3
	v_and_b32_e32 v0, 7, v5
	s_waitcnt lgkmcnt(0)
	v_mul_u32_u24_e32 v5, 0x420, v0
	v_add3_u32 v5, s24, v5, v7
	ds_read_b32 v7, v5
	ds_read_b32 v8, v5 offset:132
	v_lshlrev_b32_e32 v184, 4, v0
	v_lshl_add_u64 v[0:1], s[12:13], 0, v[184:185]
	s_mov_b64 s[12:13], 0x39500000
	s_waitcnt lgkmcnt(1)
	v_bfe_u32 v9, v7, 16, 1
	v_add3_u32 v7, v7, v9, s73
	s_waitcnt lgkmcnt(0)
; #define LAS __attribute__((address_space(3)))
; #define LDS_WAIT() asm volatile("s_waitcnt lgkmcnt(0)" ::: "memory")
; __device__ __forceinline__ unsigned pk2(float lo, float hi) { return f2bf(lo) | (f2bf(hi) << 16); }
; template <class Map>
; __device__ __forceinline__ void conv_item(const Frame& F, int it, const float* W, int K, int N, bf16_t* WT, const float* gk, int gmask, float gmul, const float* bk, i64* cs, i64* bw, Map map) {
;     ...
;         const int c = lane & 7; float gl[8];
; #pragma unroll
;         for (int i = 0; i < 8; ++i) gl[i] = gk ? gk[(k0 + 8 * c + i) & gmask] * gmul : 1.0f;
; #pragma unroll
;         for (int j = 0; j < 4; ++j) { const int n = (lane >> 3) + 8 * j; const LAS float* s = scr + (8 * c) * 33 + n;
;             u32x4 o; o.x = pk2(s[0 * 33] * gl[0], s[1 * 33] * gl[1]); o.y = pk2(s[2 * 33] * gl[2], s[3 * 33] * gl[3]); o.z = pk2(s[4 * 33] * gl[4], s[5 * 33] * gl[5]); o.w = pk2(s[6 * 33] * gl[6], s[7 * 33] * gl[7]);
;             __builtin_nontemporal_store(o, (u32x4*)(WT + (size_t)(v0 + n) * K + k0 + 8 * c)); }
;         LDS_WAIT(); asm volatile("" ::: "memory");
	v_bfe_u32 v9, v8, 16, 1
	v_lshrrev_b32_e32 v7, 16, v7
	v_add3_u32 v8, v8, v9, s73
	v_and_or_b32 v8, v8, s72, v7
	ds_read_b32 v7, v5 offset:264
	ds_read_b32 v9, v5 offset:396
	v_lshl_add_u64 v[0:1], v[0:1], 0, s[12:13]
	v_lshlrev_b32_e32 v184, 12, v6
	s_waitcnt lgkmcnt(1)
	v_bfe_u32 v10, v7, 16, 1
	v_add3_u32 v7, v7, v10, s73
	s_waitcnt lgkmcnt(0)
	v_bfe_u32 v10, v9, 16, 1
	v_lshrrev_b32_e32 v7, 16, v7
	v_add3_u32 v9, v9, v10, s73
	v_and_or_b32 v9, v9, s72, v7
	ds_read_b32 v7, v5 offset:528
	ds_read_b32 v10, v5 offset:660
	s_waitcnt lgkmcnt(1)
	v_bfe_u32 v11, v7, 16, 1
	v_add3_u32 v7, v7, v11, s73
	s_waitcnt lgkmcnt(0)
	v_bfe_u32 v11, v10, 16, 1
	v_lshrrev_b32_e32 v7, 16, v7
	v_add3_u32 v10, v10, v11, s73
	v_and_or_b32 v10, v10, s72, v7
	ds_read_b32 v7, v5 offset:792
	ds_read_b32 v11, v5 offset:924
	s_waitcnt lgkmcnt(1)
	v_bfe_u32 v14, v7, 16, 1
	v_add3_u32 v7, v7, v14, s73
	s_waitcnt lgkmcnt(0)
	v_bfe_u32 v14, v11, 16, 1
	v_lshrrev_b32_e32 v7, 16, v7
	v_add3_u32 v11, v11, v14, s73
	v_and_or_b32 v11, v11, s72, v7
	v_lshl_add_u64 v[6:7], v[0:1], 0, v[184:185]
	flat_store_dwordx4 v[6:7], v[8:11] nt
	ds_read_b32 v6, v5 offset:32
	ds_read_b32 v7, v5 offset:164
	v_lshlrev_b32_e32 v184, 12, v4
	s_waitcnt lgkmcnt(0)
	v_bfe_u32 v8, v6, 16, 1
	v_add3_u32 v6, v6, v8, s73
	v_bfe_u32 v8, v7, 16, 1
	v_lshrrev_b32_e32 v6, 16, v6
	v_add3_u32 v7, v7, v8, s73
	v_and_or_b32 v6, v7, s72, v6
	ds_read_b32 v7, v5 offset:296
	ds_read_b32 v8, v5 offset:428
	s_waitcnt lgkmcnt(0)
	v_bfe_u32 v9, v7, 16, 1
	v_add3_u32 v7, v7, v9, s73
	v_bfe_u32 v9, v8, 16, 1
	v_lshrrev_b32_e32 v7, 16, v7
	v_add3_u32 v8, v8, v9, s73
	v_and_or_b32 v7, v8, s72, v7
	ds_read_b32 v8, v5 offset:560
	ds_read_b32 v9, v5 offset:692
	s_waitcnt lgkmcnt(0)
	v_bfe_u32 v10, v8, 16, 1
	v_add3_u32 v8, v8, v10, s73
	v_bfe_u32 v10, v9, 16, 1
	v_lshrrev_b32_e32 v8, 16, v8
	v_add3_u32 v9, v9, v10, s73
	v_and_or_b32 v8, v9, s72, v8
	ds_read_b32 v9, v5 offset:824
	ds_read_b32 v10, v5 offset:956
	s_waitcnt lgkmcnt(0)
	v_bfe_u32 v11, v9, 16, 1
	v_add3_u32 v9, v9, v11, s73
	v_bfe_u32 v11, v10, 16, 1
	v_lshrrev_b32_e32 v9, 16, v9
	v_add3_u32 v10, v10, v11, s73
	v_and_or_b32 v9, v10, s72, v9
	v_lshl_add_u64 v[10:11], v[0:1], 0, v[184:185]
	flat_store_dwordx4 v[10:11], v[6:9] nt
	ds_read_b32 v4, v5 offset:64
	ds_read_b32 v6, v5 offset:196
	v_lshlrev_b32_e32 v184, 12, v3
	s_waitcnt lgkmcnt(0)
	v_bfe_u32 v7, v4, 16, 1
	v_add3_u32 v4, v4, v7, s73
	v_bfe_u32 v7, v6, 16, 1
	v_lshrrev_b32_e32 v4, 16, v4
	v_add3_u32 v6, v6, v7, s73
	v_and_or_b32 v6, v6, s72, v4
	ds_read_b32 v4, v5 offset:328
	ds_read_b32 v7, v5 offset:460
	s_waitcnt lgkmcnt(0)
	v_bfe_u32 v8, v4, 16, 1
	v_add3_u32 v4, v4, v8, s73
	v_bfe_u32 v8, v7, 16, 1
	v_lshrrev_b32_e32 v4, 16, v4
	v_add3_u32 v7, v7, v8, s73
	v_and_or_b32 v7, v7, s72, v4
	ds_read_b32 v4, v5 offset:592
	ds_read_b32 v8, v5 offset:724
	s_waitcnt lgkmcnt(0)
	v_bfe_u32 v9, v4, 16, 1
	v_add3_u32 v4, v4, v9, s73
	v_bfe_u32 v9, v8, 16, 1
	v_lshrrev_b32_e32 v4, 16, v4
	v_add3_u32 v8, v8, v9, s73
	v_and_or_b32 v8, v8, s72, v4
	ds_read_b32 v4, v5 offset:856
	ds_read_b32 v9, v5 offset:988
	s_waitcnt lgkmcnt(0)
	v_bfe_u32 v10, v4, 16, 1
	v_add3_u32 v4, v4, v10, s73
	v_bfe_u32 v10, v9, 16, 1
	v_lshrrev_b32_e32 v4, 16, v4
	v_add3_u32 v9, v9, v10, s73
	v_and_or_b32 v9, v9, s72, v4
	v_lshl_add_u64 v[10:11], v[0:1], 0, v[184:185]
	flat_store_dwordx4 v[10:11], v[6:9] nt
	ds_read_b32 v3, v5 offset:96
	ds_read_b32 v4, v5 offset:228
	v_lshlrev_b32_e32 v184, 12, v2
	v_lshl_add_u64 v[0:1], v[0:1], 0, v[184:185]
	s_waitcnt lgkmcnt(0)
	v_bfe_u32 v6, v3, 16, 1
	v_add3_u32 v3, v3, v6, s73
	v_bfe_u32 v6, v4, 16, 1
	v_lshrrev_b32_e32 v3, 16, v3
	v_add3_u32 v4, v4, v6, s73
	v_and_or_b32 v6, v4, s72, v3
	ds_read_b32 v3, v5 offset:360
	ds_read_b32 v4, v5 offset:492
	s_waitcnt lgkmcnt(0)
	v_bfe_u32 v7, v3, 16, 1
	v_add3_u32 v3, v3, v7, s73
	v_bfe_u32 v7, v4, 16, 1
	v_lshrrev_b32_e32 v3, 16, v3
	v_add3_u32 v4, v4, v7, s73
	v_and_or_b32 v7, v4, s72, v3
	ds_read_b32 v3, v5 offset:624
	ds_read_b32 v4, v5 offset:756
	s_waitcnt lgkmcnt(0)
	v_bfe_u32 v8, v3, 16, 1
	v_add3_u32 v3, v3, v8, s73
	v_bfe_u32 v8, v4, 16, 1
	v_lshrrev_b32_e32 v3, 16, v3
	v_add3_u32 v4, v4, v8, s73
	v_and_or_b32 v8, v4, s72, v3
	ds_read_b32 v3, v5 offset:888
	ds_read_b32 v4, v5 offset:1020
	s_waitcnt lgkmcnt(0)
	v_bfe_u32 v5, v3, 16, 1
	v_add3_u32 v3, v3, v5, s73
	v_bfe_u32 v5, v4, 16, 1
	v_lshrrev_b32_e32 v3, 16, v3
	v_add3_u32 v4, v4, v5, s73
	v_and_or_b32 v9, v4, s72, v3
	flat_store_dwordx4 v[0:1], v[6:9] nt
	s_waitcnt lgkmcnt(0)

; #define LAS __attribute__((address_space(3)))
; #define INP(i) (kargs()->in[i])
; template <class Map>
; __device__ __forceinline__ void conv_item(const Frame& F, int it, const float* W, int K, int N, bf16_t* WT, const float* gk, int gmask, float gmul, const float* bk, i64* cs, i64* bw, Map map) {
;     ...
;         const int kb = it / nblk, nb = it % nblk, k0 = 64 * kb, n0 = 32 * nb, v0 = map(n0);
; #pragma unroll
;         for (int i = 0; i < 8; ++i) { const int kk = 8 * i + (lane >> 3), c4 = (lane & 7) * 4;
;             const f32x4 w4 = __builtin_nontemporal_load((const f32x4*)(W + (size_t)(k0 + kk) * N + n0 + c4)); LAS float* d = scr + kk * 33 + c4; d[0] = w4[0]; d[1] = w4[1]; d[2] = w4[2]; d[3] = w4[3]; }
;         LDS_WAIT(); asm volatile("" ::: "memory");
;         if (bk) {
;             const int n = lane & 31, kh = lane >> 5; float sb = 0.f, sc = 0.f;
; #pragma unroll 8
;             for (int j = 0; j < 32; ++j) { const int kk = kh * 32 + j; const float w = scr[kk * 33 + n]; sb += bk[k0 + kk] * w; sc += bf_round(gk[(k0 + kk) & gmask] * gmul * w); }
;             { auto r = __builtin_amdgcn_permlane32_swap(__float_as_uint(sb), __float_as_uint(sb), false, false); sb = __uint_as_float(r[0]) + __uint_as_float(r[1]); }
;             { auto r = __builtin_amdgcn_permlane32_swap(__float_as_uint(sc), __float_as_uint(sc), false, false); sc = __uint_as_float(r[0]) + __uint_as_float(r[1]); }
;             if (lane < 32) { atomic_addq(bw + v0 + n, sb, FX_COL); atomic_addq(cs + v0 + n, sc, FX_COL); }
;         }
;         const int c = lane & 7; float gl[8];
; #pragma unroll
;         for (int i = 0; i < 8; ++i) gl[i] = gk ? gk[(k0 + 8 * c + i) & gmask] * gmul : 1.0f;
; #pragma unroll
;         for (int j = 0; j < 4; ++j) { const int n = (lane >> 3) + 8 * j; const LAS float* s = scr + (8 * c) * 33 + n;
;             u32x4 o; o.x = pk2(s[0 * 33] * gl[0], s[1 * 33] * gl[1]); o.y = pk2(s[2 * 33] * gl[2], s[3 * 33] * gl[3]); o.z = pk2(s[4 * 33] * gl[4], s[5 * 33] * gl[5]); o.w = pk2(s[6 * 33] * gl[6], s[7 * 33] * gl[7]);
;             __builtin_nontemporal_store(o, (u32x4*)(WT + (size_t)(v0 + n) * K + k0 + 8 * c)); }
; __device__ BG_ATTR void bg_item(const Frame& F, unsigned char* ws, const int L, int id) {
;     ...
;     if (id < NI_P) { conv_item(F, id, INP(18) + (size_t)L * PLE * DM, PLE, DM, Wp, nullptr, 0, 1.f, nullptr, nullptr, nullptr, MapIdent()); return; } id -= NI_P;
.LBB0_654:
	s_andn2_b64 vcc, exec, s[12:13]
	s_cbranch_vccnz .LBB0_656
	v_readlane_b32 s12, v252, 14
	v_readlane_b32 s13, v252, 15
	s_load_dwordx2 s[12:13], s[12:13], 0x90
	v_mov_b32_e32 v7, v220
	v_mov_b32_e32 v5, v185
	s_waitcnt lgkmcnt(0)
	s_add_u32 s25, s12, s42
	s_addc_u32 s27, s13, s43
	s_lshl_b32 s17, s16, 5
	v_readlane_b32 s12, v252, 12
	s_and_b32 s17, s17, 0x7e0
	v_readlane_b32 s13, v252, 13
	s_and_b32 s24, s86, 0xc0
	s_lshl_b32 s26, s17, 2
	s_add_u32 s26, s25, s26
	v_bfe_u32 v6, v7, 3, 3
	v_lshlrev_b32_e32 v0, 4, v7
	s_addc_u32 s27, s27, 0
	v_and_b32_e32 v184, 0x70, v0
	v_or_b32_e32 v0, s24, v6
	v_lshl_add_u64 v[14:15], s[26:27], 0, v[184:185]
	v_lshlrev_b32_e32 v4, 13, v0
	v_lshl_add_u64 v[0:1], v[14:15], 0, v[4:5]
	global_load_dwordx4 v[132:135], v[0:1], off nt
	v_mul_u32_u24_e32 v5, 0x84, v6
	v_readlane_b32 s25, v255, 17
	s_nop 1
	v_add3_u32 v16, s25, v184, v5
	v_or_b32_e32 v5, 8, v6
	v_add_u32_e32 v8, 0x420, v16
	v_or_b32_e32 v0, s24, v5
	v_lshlrev_b32_e32 v184, 13, v0
	v_lshl_add_u64 v[0:1], v[14:15], 0, v[184:185]
	global_load_dwordx4 v[136:139], v[0:1], off nt
	v_or_b32_e32 v5, s17, v5
	v_add_u32_e32 v0, 0x428, v16
	v_or_b32_e32 v3, 16, v6
	v_or_b32_e32 v0, s24, v3
	v_lshlrev_b32_e32 v184, 13, v0
	v_lshl_add_u64 v[0:1], v[14:15], 0, v[184:185]
	global_load_dwordx4 v[140:143], v[0:1], off nt
	v_add_u32_e32 v0, 0x840, v16
	v_or_b32_e32 v2, 24, v6
	v_or_b32_e32 v3, s17, v3
	v_add_u32_e32 v0, 0x848, v16
	v_or_b32_e32 v0, s24, v2
	v_lshlrev_b32_e32 v184, 13, v0
	v_lshl_add_u64 v[0:1], v[14:15], 0, v[184:185]
	global_load_dwordx4 v[144:147], v[0:1], off nt
	v_add_u32_e32 v0, 0xc60, v16
	v_or_b32_e32 v184, 0x40000, v4
	s_lshl_b32 s24, s24, 1
	s_add_u32 s12, s12, s24
	s_addc_u32 s13, s13, 0
	v_or_b32_e32 v2, s17, v2
	v_add_u32_e32 v0, 0xc68, v16
	v_lshl_add_u64 v[0:1], v[14:15], 0, v[184:185]
	global_load_dwordx4 v[148:151], v[0:1], off nt
	v_add_u32_e32 v0, 0x1080, v16
	v_or_b32_e32 v184, 0x50000, v4
	v_add_u32_e32 v0, 0x1088, v16
	v_lshl_add_u64 v[0:1], v[14:15], 0, v[184:185]
	global_load_dwordx4 v[152:155], v[0:1], off nt
	v_add_u32_e32 v0, 0x14a0, v16
	v_or_b32_e32 v184, 0x60000, v4
	v_add_u32_e32 v0, 0x14a8, v16
	v_lshl_add_u64 v[0:1], v[14:15], 0, v[184:185]
	global_load_dwordx4 v[156:159], v[0:1], off nt
	v_add_u32_e32 v0, 0x18c0, v16
	v_or_b32_e32 v184, 0x70000, v4
	v_add_u32_e32 v0, 0x18c8, v16
	v_lshl_add_u64 v[0:1], v[14:15], 0, v[184:185]
	global_load_dwordx4 v[160:163], v[0:1], off nt
	v_add_u32_e32 v0, 0x1ce0, v16
	v_add_u32_e32 v0, 0x1ce8, v16
	s_waitcnt vmcnt(0)
	v_add_u32_e32 v164, 0x0, v16
	ds_write2_b32 v164, v132, v133 offset1:1
	ds_write2_b32 v164, v134, v135 offset0:2 offset1:3
	v_add_u32_e32 v164, 0x420, v16
	ds_write2_b32 v164, v136, v137 offset1:1
	ds_write2_b32 v164, v138, v139 offset0:2 offset1:3
	v_add_u32_e32 v164, 0x840, v16
	ds_write2_b32 v164, v140, v141 offset1:1
	ds_write2_b32 v164, v142, v143 offset0:2 offset1:3
	v_add_u32_e32 v164, 0xc60, v16
	ds_write2_b32 v164, v144, v145 offset1:1
	ds_write2_b32 v164, v146, v147 offset0:2 offset1:3
	v_add_u32_e32 v164, 0x1080, v16
	ds_write2_b32 v164, v148, v149 offset1:1
	ds_write2_b32 v164, v150, v151 offset0:2 offset1:3
	v_add_u32_e32 v164, 0x14a0, v16
	ds_write2_b32 v164, v152, v153 offset1:1
	ds_write2_b32 v164, v154, v155 offset0:2 offset1:3
	v_add_u32_e32 v164, 0x18c0, v16
	ds_write2_b32 v164, v156, v157 offset1:1
	ds_write2_b32 v164, v158, v159 offset0:2 offset1:3
	v_add_u32_e32 v164, 0x1ce0, v16
	ds_write2_b32 v164, v160, v161 offset1:1
	ds_write2_b32 v164, v162, v163 offset0:2 offset1:3
	v_and_b32_e32 v0, 7, v7
	s_waitcnt lgkmcnt(0)
	v_mul_u32_u24_e32 v4, 0x420, v0
	v_lshlrev_b32_e32 v7, 2, v6
	v_add3_u32 v4, s25, v4, v7
	ds_read_b32 v7, v4
	ds_read_b32 v8, v4 offset:132
	v_lshlrev_b32_e32 v184, 4, v0
	v_lshl_add_u64 v[0:1], s[12:13], 0, v[184:185]
	s_mov_b64 s[12:13], 0x40700000
	s_waitcnt lgkmcnt(1)
	v_bfe_u32 v9, v7, 16, 1
	v_add3_u32 v7, v7, v9, s73
	s_waitcnt lgkmcnt(0)
	v_bfe_u32 v9, v8, 16, 1
	v_lshrrev_b32_e32 v7, 16, v7
	v_add3_u32 v8, v8, v9, s73
	v_and_or_b32 v8, v8, s72, v7
	ds_read_b32 v7, v4 offset:264
	ds_read_b32 v9, v4 offset:396
	v_or_b32_e32 v6, s17, v6
	v_lshl_add_u64 v[0:1], v[0:1], 0, s[12:13]
	v_lshlrev_b32_e32 v184, 9, v6
	s_waitcnt lgkmcnt(1)
; #define LAS __attribute__((address_space(3)))
; #define LDS_WAIT() asm volatile("s_waitcnt lgkmcnt(0)" ::: "memory")
; __device__ __forceinline__ unsigned pk2(float lo, float hi) { return f2bf(lo) | (f2bf(hi) << 16); }
; template <class Map>
; __device__ __forceinline__ void conv_item(const Frame& F, int it, const float* W, int K, int N, bf16_t* WT, const float* gk, int gmask, float gmul, const float* bk, i64* cs, i64* bw, Map map) {
;     ...
;         const int c = lane & 7; float gl[8];
; #pragma unroll
;         for (int i = 0; i < 8; ++i) gl[i] = gk ? gk[(k0 + 8 * c + i) & gmask] * gmul : 1.0f;
; #pragma unroll
;         for (int j = 0; j < 4; ++j) { const int n = (lane >> 3) + 8 * j; const LAS float* s = scr + (8 * c) * 33 + n;
;             u32x4 o; o.x = pk2(s[0 * 33] * gl[0], s[1 * 33] * gl[1]); o.y = pk2(s[2 * 33] * gl[2], s[3 * 33] * gl[3]); o.z = pk2(s[4 * 33] * gl[4], s[5 * 33] * gl[5]); o.w = pk2(s[6 * 33] * gl[6], s[7 * 33] * gl[7]);
;             __builtin_nontemporal_store(o, (u32x4*)(WT + (size_t)(v0 + n) * K + k0 + 8 * c)); }
;         LDS_WAIT(); asm volatile("" ::: "memory");
	v_bfe_u32 v10, v7, 16, 1
	v_add3_u32 v7, v7, v10, s73
	s_waitcnt lgkmcnt(0)
	v_bfe_u32 v10, v9, 16, 1
	v_lshrrev_b32_e32 v7, 16, v7
	v_add3_u32 v9, v9, v10, s73
	v_and_or_b32 v9, v9, s72, v7
	ds_read_b32 v7, v4 offset:528
	ds_read_b32 v10, v4 offset:660
	s_waitcnt lgkmcnt(1)
	v_bfe_u32 v11, v7, 16, 1
	v_add3_u32 v7, v7, v11, s73
	s_waitcnt lgkmcnt(0)
	v_bfe_u32 v11, v10, 16, 1
	v_lshrrev_b32_e32 v7, 16, v7
	v_add3_u32 v10, v10, v11, s73
	v_and_or_b32 v10, v10, s72, v7
	ds_read_b32 v7, v4 offset:792
	ds_read_b32 v11, v4 offset:924
	s_waitcnt lgkmcnt(1)
	v_bfe_u32 v14, v7, 16, 1
	v_add3_u32 v7, v7, v14, s73
	s_waitcnt lgkmcnt(0)
	v_bfe_u32 v14, v11, 16, 1
	v_lshrrev_b32_e32 v7, 16, v7
	v_add3_u32 v11, v11, v14, s73
	v_and_or_b32 v11, v11, s72, v7
	v_lshl_add_u64 v[6:7], v[0:1], 0, v[184:185]
	flat_store_dwordx4 v[6:7], v[8:11] nt
	ds_read_b32 v6, v4 offset:32
	ds_read_b32 v7, v4 offset:164
	v_lshlrev_b32_e32 v184, 9, v5
	s_waitcnt lgkmcnt(0)
	v_bfe_u32 v8, v6, 16, 1
	v_add3_u32 v6, v6, v8, s73
	v_bfe_u32 v8, v7, 16, 1
	v_lshrrev_b32_e32 v6, 16, v6
	v_add3_u32 v7, v7, v8, s73
	v_and_or_b32 v6, v7, s72, v6
	ds_read_b32 v7, v4 offset:296
	ds_read_b32 v8, v4 offset:428
	s_waitcnt lgkmcnt(0)
	v_bfe_u32 v9, v7, 16, 1
	v_add3_u32 v7, v7, v9, s73
	v_bfe_u32 v9, v8, 16, 1
	v_lshrrev_b32_e32 v7, 16, v7
	v_add3_u32 v8, v8, v9, s73
	v_and_or_b32 v7, v8, s72, v7
	ds_read_b32 v8, v4 offset:560
	ds_read_b32 v9, v4 offset:692
	s_waitcnt lgkmcnt(0)
	v_bfe_u32 v10, v8, 16, 1
	v_add3_u32 v8, v8, v10, s73
	v_bfe_u32 v10, v9, 16, 1
	v_lshrrev_b32_e32 v8, 16, v8
	v_add3_u32 v9, v9, v10, s73
	v_and_or_b32 v8, v9, s72, v8
	ds_read_b32 v9, v4 offset:824
	ds_read_b32 v10, v4 offset:956
	s_waitcnt lgkmcnt(0)
	v_bfe_u32 v11, v9, 16, 1
	v_add3_u32 v9, v9, v11, s73
	v_bfe_u32 v11, v10, 16, 1
	v_lshrrev_b32_e32 v9, 16, v9
	v_add3_u32 v10, v10, v11, s73
	v_and_or_b32 v9, v10, s72, v9
	v_lshl_add_u64 v[10:11], v[0:1], 0, v[184:185]
	flat_store_dwordx4 v[10:11], v[6:9] nt
	ds_read_b32 v5, v4 offset:64
	ds_read_b32 v6, v4 offset:196
	v_lshlrev_b32_e32 v184, 9, v3
	s_waitcnt lgkmcnt(0)
	v_bfe_u32 v7, v5, 16, 1
	v_add3_u32 v5, v5, v7, s73
	v_bfe_u32 v7, v6, 16, 1
	v_lshrrev_b32_e32 v5, 16, v5
	v_add3_u32 v6, v6, v7, s73
	v_and_or_b32 v6, v6, s72, v5
	ds_read_b32 v5, v4 offset:328
	ds_read_b32 v7, v4 offset:460
	s_waitcnt lgkmcnt(0)
	v_bfe_u32 v8, v5, 16, 1
	v_add3_u32 v5, v5, v8, s73
	v_bfe_u32 v8, v7, 16, 1
	v_lshrrev_b32_e32 v5, 16, v5
	v_add3_u32 v7, v7, v8, s73
	v_and_or_b32 v7, v7, s72, v5
	ds_read_b32 v5, v4 offset:592
	ds_read_b32 v8, v4 offset:724
	s_waitcnt lgkmcnt(0)
	v_bfe_u32 v9, v5, 16, 1
	v_add3_u32 v5, v5, v9, s73
	v_bfe_u32 v9, v8, 16, 1
	v_lshrrev_b32_e32 v5, 16, v5
	v_add3_u32 v8, v8, v9, s73
	v_and_or_b32 v8, v8, s72, v5
	ds_read_b32 v5, v4 offset:856
	ds_read_b32 v9, v4 offset:988
	s_waitcnt lgkmcnt(0)
	v_bfe_u32 v10, v5, 16, 1
	v_add3_u32 v5, v5, v10, s73
	v_bfe_u32 v10, v9, 16, 1
	v_lshrrev_b32_e32 v5, 16, v5
	v_add3_u32 v9, v9, v10, s73
	v_and_or_b32 v9, v9, s72, v5
	v_lshl_add_u64 v[10:11], v[0:1], 0, v[184:185]
	flat_store_dwordx4 v[10:11], v[6:9] nt
	ds_read_b32 v3, v4 offset:96
	ds_read_b32 v5, v4 offset:228
	v_lshlrev_b32_e32 v184, 9, v2
	v_lshl_add_u64 v[0:1], v[0:1], 0, v[184:185]
	s_waitcnt lgkmcnt(0)
	v_bfe_u32 v6, v3, 16, 1
	v_add3_u32 v3, v3, v6, s73
	v_bfe_u32 v6, v5, 16, 1
	v_lshrrev_b32_e32 v3, 16, v3
	v_add3_u32 v5, v5, v6, s73
	v_and_or_b32 v6, v5, s72, v3
	ds_read_b32 v3, v4 offset:360
	ds_read_b32 v5, v4 offset:492
	s_waitcnt lgkmcnt(0)
	v_bfe_u32 v7, v3, 16, 1
	v_add3_u32 v3, v3, v7, s73
	v_bfe_u32 v7, v5, 16, 1
	v_lshrrev_b32_e32 v3, 16, v3
	v_add3_u32 v5, v5, v7, s73
	v_and_or_b32 v7, v5, s72, v3
	ds_read_b32 v3, v4 offset:624
	ds_read_b32 v5, v4 offset:756
	s_waitcnt lgkmcnt(0)
	v_bfe_u32 v8, v3, 16, 1
	v_add3_u32 v3, v3, v8, s73
	v_bfe_u32 v8, v5, 16, 1
	v_lshrrev_b32_e32 v3, 16, v3
	v_add3_u32 v5, v5, v8, s73
	v_and_or_b32 v8, v5, s72, v3
	ds_read_b32 v3, v4 offset:888
	ds_read_b32 v4, v4 offset:1020
	s_waitcnt lgkmcnt(0)
	v_bfe_u32 v5, v3, 16, 1
	v_add3_u32 v3, v3, v5, s73
	v_bfe_u32 v5, v4, 16, 1
	v_lshrrev_b32_e32 v3, 16, v3
	v_add3_u32 v4, v4, v5, s73
	v_and_or_b32 v9, v4, s72, v3
	flat_store_dwordx4 v[0:1], v[6:9] nt
	s_waitcnt lgkmcnt(0)

; #define LAS __attribute__((address_space(3)))
; __device__ __forceinline__ void atomic_addq(i64* p, float v, float scale) { (void)__hip_atomic_fetch_add((unsigned long long*)p, (unsigned long long)(i64)__builtin_rintf(v * scale), __ATOMIC_RELAXED, __HIP_MEMORY_SCOPE_AGENT); }
; #define LDS_WAIT() asm volatile("s_waitcnt lgkmcnt(0)" ::: "memory")
; __device__ __forceinline__ float bf_round(float f) { return __uint_as_float(f2bf(f) << 16); }
; #define INP(i) (kargs()->in[i])
; template <class Map>
; __device__ __forceinline__ void conv_item(const Frame& F, int it, const float* W, int K, int N, bf16_t* WT, const float* gk, int gmask, float gmul, const float* bk, i64* cs, i64* bw, Map map) {
;     ...
;         const int kb = it / nblk, nb = it % nblk, k0 = 64 * kb, n0 = 32 * nb, v0 = map(n0);
; #pragma unroll
;         for (int i = 0; i < 8; ++i) { const int kk = 8 * i + (lane >> 3), c4 = (lane & 7) * 4;
;             const f32x4 w4 = __builtin_nontemporal_load((const f32x4*)(W + (size_t)(k0 + kk) * N + n0 + c4)); LAS float* d = scr + kk * 33 + c4; d[0] = w4[0]; d[1] = w4[1]; d[2] = w4[2]; d[3] = w4[3]; }
;         LDS_WAIT(); asm volatile("" ::: "memory");
;         if (bk) {
;             const int n = lane & 31, kh = lane >> 5; float sb = 0.f, sc = 0.f;
; #pragma unroll 8
;             for (int j = 0; j < 32; ++j) { const int kk = kh * 32 + j; const float w = scr[kk * 33 + n]; sb += bk[k0 + kk] * w; sc += bf_round(gk[(k0 + kk) & gmask] * gmul * w); }
;             { auto r = __builtin_amdgcn_permlane32_swap(__float_as_uint(sb), __float_as_uint(sb), false, false); sb = __uint_as_float(r[0]) + __uint_as_float(r[1]); }
;             { auto r = __builtin_amdgcn_permlane32_swap(__float_as_uint(sc), __float_as_uint(sc), false, false); sc = __uint_as_float(r[0]) + __uint_as_float(r[1]); }
;             if (lane < 32) { atomic_addq(bw + v0 + n, sb, FX_COL); atomic_addq(cs + v0 + n, sc, FX_COL); }
;         }
;         const int c = lane & 7; float gl[8];
; #pragma unroll
;         for (int i = 0; i < 8; ++i) gl[i] = gk ? gk[(k0 + 8 * c + i) & gmask] * gmul : 1.0f;
; __device__ BG_ATTR void bg_item(const Frame& F, unsigned char* ws, const int L, int id) {
;     ...
;     if (id < NI_G) { conv_item(F, id, INP(17) + (size_t)L * DM * DM, DM, DM, Wg, g2, DM - 1, 1.f, b2, csFq + 22528, csFq + 24576, MapIdent()); return; } id -= NI_G;
.LBB0_657:
	s_andn2_b64 vcc, exec, s[12:13]
	s_cbranch_vccnz .LBB0_663
	v_readlane_b32 s40, v252, 14
	v_readlane_b32 s41, v252, 15
	s_mov_b64 s[12:13], s[40:41]
	s_load_dwordx2 s[12:13], s[12:13], 0x88
	s_add_i32 s74, s86, 0x9e00
	v_readlane_b32 s70, v252, 12
	v_readlane_b32 s71, v252, 13
	s_mov_b64 s[24:25], s[70:71]
	s_waitcnt lgkmcnt(0)
	s_add_u32 s75, s12, s44
	s_addc_u32 s87, s13, s45
	s_mov_b64 s[12:13], s[40:41]
	s_load_dwordx2 s[48:49], s[12:13], 0x68
	s_lshl_b64 s[12:13], s[46:47], 2
	v_mov_b32_e32 v16, v220
	v_mov_b32_e32 v7, v185
	s_waitcnt lgkmcnt(0)
	s_add_u32 s12, s48, s12
	s_addc_u32 s13, s49, s13
	s_add_u32 s26, s12, 0x2000
	s_addc_u32 s27, s13, 0
	s_lshl_b32 s17, s16, 5
	s_mov_b64 s[12:13], s[40:41]
	s_and_b32 s17, s17, 0x7e0
	s_mov_b64 s[40:41], s[70:71]
	s_and_b32 s52, s74, 0xffc0
	s_lshl_b32 s90, s17, 2
	s_load_dwordx2 s[12:13], s[12:13], 0x70
	s_add_u32 s90, s75, s90
	v_bfe_u32 v11, v16, 3, 3
	v_lshlrev_b32_e32 v0, 4, v16
	s_addc_u32 s91, s87, 0
	v_and_b32_e32 v184, 0x70, v0
	v_or_b32_e32 v0, s52, v11
	v_lshl_add_u64 v[4:5], s[90:91], 0, v[184:185]
	v_lshlrev_b32_e32 v6, 13, v0
	v_lshl_add_u64 v[0:1], v[4:5], 0, v[6:7]
	global_load_dwordx4 v[132:135], v[0:1], off nt
	v_mul_u32_u24_e32 v7, 0x84, v11
	v_readlane_b32 s75, v255, 17
	v_or_b32_e32 v10, 8, v11
	v_or_b32_e32 v15, 16, v11
	v_add3_u32 v7, s75, v184, v7
	v_add_u32_e32 v8, 0x420, v7
	v_or_b32_e32 v14, 24, v11
	v_readlane_b32 s90, v255, 25
	v_readlane_b32 s91, v255, 26
	s_add_u32 s48, s48, s90
	s_addc_u32 s49, s49, s91
	s_and_b32 s74, s74, 0x7c0
	v_and_b32_e32 v18, 31, v16
	s_waitcnt lgkmcnt(0)
	s_add_u32 s12, s12, s90
	v_and_or_b32 v19, v16, 32, s52
	s_addc_u32 s13, s13, s91
	v_and_b32_e32 v17, 63, v16
	v_or_b32_e32 v0, s52, v10
	v_lshlrev_b32_e32 v184, 13, v0
	v_lshl_add_u64 v[0:1], v[4:5], 0, v[184:185]
	global_load_dwordx4 v[136:139], v[0:1], off nt
	v_add_u32_e32 v0, 0x428, v7
	v_or_b32_e32 v0, s52, v15
	v_lshlrev_b32_e32 v184, 13, v0
	v_lshl_add_u64 v[0:1], v[4:5], 0, v[184:185]
	global_load_dwordx4 v[140:143], v[0:1], off nt
	v_add_u32_e32 v8, 0x840, v7
	v_add_u32_e32 v0, 0x848, v7
	v_or_b32_e32 v0, s52, v14
	v_lshlrev_b32_e32 v184, 13, v0
	v_lshl_add_u64 v[0:1], v[4:5], 0, v[184:185]
	global_load_dwordx4 v[144:147], v[0:1], off nt
	v_add_u32_e32 v8, 0xc60, v7
	v_or_b32_e32 v184, 0x40000, v6
	v_add_u32_e32 v0, 0xc68, v7
	v_lshl_add_u64 v[0:1], v[4:5], 0, v[184:185]
	global_load_dwordx4 v[148:151], v[0:1], off nt
	v_add_u32_e32 v8, 0x1080, v7
	v_or_b32_e32 v184, 0x50000, v6
	v_add_u32_e32 v0, 0x1088, v7
	v_lshl_add_u64 v[0:1], v[4:5], 0, v[184:185]
	global_load_dwordx4 v[152:155], v[0:1], off nt
	v_add_u32_e32 v8, 0x14a0, v7
	v_or_b32_e32 v184, 0x60000, v6
	v_add_u32_e32 v0, 0x14a8, v7
	v_lshl_add_u64 v[0:1], v[4:5], 0, v[184:185]
	global_load_dwordx4 v[156:159], v[0:1], off nt
	v_add_u32_e32 v8, 0x18c0, v7
	v_or_b32_e32 v184, 0x70000, v6
	v_add_u32_e32 v0, 0x18c8, v7
	v_lshl_add_u64 v[0:1], v[4:5], 0, v[184:185]
	global_load_dwordx4 v[160:163], v[0:1], off nt
	v_add_u32_e32 v4, 0x1ce0, v7
	v_mov_b32_e32 v8, 0
	v_mov_b32_e32 v9, v8
	v_add_u32_e32 v0, 0x1ce8, v7
	s_waitcnt vmcnt(0)
	v_add_u32_e32 v164, 0x0, v7
	ds_write2_b32 v164, v132, v133 offset1:1
	ds_write2_b32 v164, v134, v135 offset0:2 offset1:3
	v_add_u32_e32 v164, 0x420, v7
	ds_write2_b32 v164, v136, v137 offset1:1
	ds_write2_b32 v164, v138, v139 offset0:2 offset1:3
	v_add_u32_e32 v164, 0x840, v7
	ds_write2_b32 v164, v140, v141 offset1:1
	ds_write2_b32 v164, v142, v143 offset0:2 offset1:3
	v_add_u32_e32 v164, 0xc60, v7
	ds_write2_b32 v164, v144, v145 offset1:1
	ds_write2_b32 v164, v146, v147 offset0:2 offset1:3
	v_add_u32_e32 v164, 0x1080, v7
	ds_write2_b32 v164, v148, v149 offset1:1
	ds_write2_b32 v164, v150, v151 offset0:2 offset1:3
	v_add_u32_e32 v164, 0x14a0, v7
	ds_write2_b32 v164, v152, v153 offset1:1
	ds_write2_b32 v164, v154, v155 offset0:2 offset1:3
	v_add_u32_e32 v164, 0x18c0, v7
	ds_write2_b32 v164, v156, v157 offset1:1
	ds_write2_b32 v164, v158, v159 offset0:2 offset1:3
	v_add_u32_e32 v164, 0x1ce0, v7
	ds_write2_b32 v164, v160, v161 offset1:1
	ds_write2_b32 v164, v162, v163 offset0:2 offset1:3
	v_lshrrev_b32_e32 v0, 5, v16
	v_and_b32_e32 v0, 1, v0
	v_lshlrev_b16_e32 v0, 5, v0
	v_or_b32_e32 v0, s74, v0
	s_waitcnt lgkmcnt(0)
	v_lshlrev_b32_sdwa v184, v227, v0 dst_sel:DWORD dst_unused:UNUSED_PAD src0_sel:DWORD src1_sel:WORD_0
	v_bfe_u32 v0, v16, 5, 1
	v_mul_u32_u24_e32 v0, 0x1080, v0
	v_lshl_add_u64 v[4:5], s[48:49], 0, v[184:185]
	v_lshlrev_b32_e32 v184, 2, v19
	v_lshl_or_b32 v0, v18, 2, v0
	v_lshl_add_u64 v[6:7], s[12:13], 0, v[184:185]
	v_add_u32_e32 v20, s75, v0
	s_mov_b64 s[12:13], 0
	s_movk_i32 s48, 0x2000
	s_mov_b64 s[74:75], 0x2000

; #define LAS __attribute__((address_space(3)))
; #define INP(i) (kargs()->in[i])
; template <class Map>
; __device__ __forceinline__ void conv_item(const Frame& F, int it, const float* W, int K, int N, bf16_t* WT, const float* gk, int gmask, float gmul, const float* bk, i64* cs, i64* bw, Map map) {
;     ...
;         const int kb = it / nblk, nb = it % nblk, k0 = 64 * kb, n0 = 32 * nb, v0 = map(n0);
; #pragma unroll
;         for (int i = 0; i < 8; ++i) { const int kk = 8 * i + (lane >> 3), c4 = (lane & 7) * 4;
;             const f32x4 w4 = __builtin_nontemporal_load((const f32x4*)(W + (size_t)(k0 + kk) * N + n0 + c4)); LAS float* d = scr + kk * 33 + c4; d[0] = w4[0]; d[1] = w4[1]; d[2] = w4[2]; d[3] = w4[3]; }
;         LDS_WAIT(); asm volatile("" ::: "memory");
;         if (bk) {
;             const int n = lane & 31, kh = lane >> 5; float sb = 0.f, sc = 0.f;
; #pragma unroll 8
;             for (int j = 0; j < 32; ++j) { const int kk = kh * 32 + j; const float w = scr[kk * 33 + n]; sb += bk[k0 + kk] * w; sc += bf_round(gk[(k0 + kk) & gmask] * gmul * w); }
;             { auto r = __builtin_amdgcn_permlane32_swap(__float_as_uint(sb), __float_as_uint(sb), false, false); sb = __uint_as_float(r[0]) + __uint_as_float(r[1]); }
;             { auto r = __builtin_amdgcn_permlane32_swap(__float_as_uint(sc), __float_as_uint(sc), false, false); sc = __uint_as_float(r[0]) + __uint_as_float(r[1]); }
;             if (lane < 32) { atomic_addq(bw + v0 + n, sb, FX_COL); atomic_addq(cs + v0 + n, sc, FX_COL); }
;         }
;         const int c = lane & 7; float gl[8];
; #pragma unroll
;         for (int i = 0; i < 8; ++i) gl[i] = gk ? gk[(k0 + 8 * c + i) & gmask] * gmul : 1.0f;
; #pragma unroll
;         for (int j = 0; j < 4; ++j) { const int n = (lane >> 3) + 8 * j; const LAS float* s = scr + (8 * c) * 33 + n;
;             u32x4 o; o.x = pk2(s[0 * 33] * gl[0], s[1 * 33] * gl[1]); o.y = pk2(s[2 * 33] * gl[2], s[3 * 33] * gl[3]); o.z = pk2(s[4 * 33] * gl[4], s[5 * 33] * gl[5]); o.w = pk2(s[6 * 33] * gl[6], s[7 * 33] * gl[7]);
;             __builtin_nontemporal_store(o, (u32x4*)(WT + (size_t)(v0 + n) * K + k0 + 8 * c)); }
; __device__ BG_ATTR void bg_item(const Frame& F, unsigned char* ws, const int L, int id) {
;     ...
;     if (id < NI_F2) { conv_item(F, id, INP(16) + (size_t)L * DFF * DM, DFF, DM, Wf2, nullptr, 0, 1.f, nullptr, nullptr, nullptr, MapIdent()); return; } id -= NI_F2;
.LBB0_664:
	s_andn2_b64 vcc, exec, s[12:13]
	s_cbranch_vccnz .LBB0_666
	v_readlane_b32 s12, v252, 14
	v_readlane_b32 s13, v252, 15
	s_load_dwordx2 s[12:13], s[12:13], 0x80
	s_add_i32 s17, s86, 0xb400
	s_mul_i32 s24, s20, 0x2c00000
	v_mov_b32_e32 v7, v220
	v_mov_b32_e32 v5, v185
	s_waitcnt lgkmcnt(0)
	s_add_u32 s25, s12, s24
	s_mul_hi_i32 s12, s20, 0x2c00000
	s_addc_u32 s27, s13, s12
	s_and_b32 s24, s17, 0xffc0
	s_lshl_b32 s17, s16, 5
	v_readlane_b32 s12, v252, 12
	s_and_b32 s17, s17, 0x7e0
	v_readlane_b32 s13, v252, 13
	s_lshl_b32 s26, s17, 2
	s_add_u32 s26, s25, s26
	v_bfe_u32 v6, v7, 3, 3
	v_lshlrev_b32_e32 v0, 4, v7
	s_addc_u32 s27, s27, 0
	v_and_b32_e32 v184, 0x70, v0
	v_or_b32_e32 v0, s24, v6
	v_lshl_add_u64 v[14:15], s[26:27], 0, v[184:185]
	v_lshlrev_b32_e32 v4, 13, v0
	v_lshl_add_u64 v[0:1], v[14:15], 0, v[4:5]
	global_load_dwordx4 v[132:135], v[0:1], off nt
	v_mul_u32_u24_e32 v5, 0x84, v6
	v_readlane_b32 s25, v255, 17
	s_nop 1
	v_add3_u32 v16, s25, v184, v5
	v_or_b32_e32 v5, 8, v6
	v_add_u32_e32 v8, 0x420, v16
	v_or_b32_e32 v0, s24, v5
	v_lshlrev_b32_e32 v184, 13, v0
	v_lshl_add_u64 v[0:1], v[14:15], 0, v[184:185]
	global_load_dwordx4 v[136:139], v[0:1], off nt
	v_or_b32_e32 v5, s17, v5
	v_mul_u32_u24_e32 v5, 0x1600, v5
	v_add_u32_e32 v0, 0x428, v16
	v_or_b32_e32 v3, 16, v6
	v_or_b32_e32 v0, s24, v3
	v_lshlrev_b32_e32 v184, 13, v0
	v_lshl_add_u64 v[0:1], v[14:15], 0, v[184:185]
	global_load_dwordx4 v[140:143], v[0:1], off nt
	v_add_u32_e32 v0, 0x840, v16
	v_or_b32_e32 v2, 24, v6
	v_or_b32_e32 v3, s17, v3
	v_mul_u32_u24_e32 v3, 0x1600, v3
	v_add_u32_e32 v0, 0x848, v16
	v_or_b32_e32 v0, s24, v2
	v_lshlrev_b32_e32 v184, 13, v0
	v_lshl_add_u64 v[0:1], v[14:15], 0, v[184:185]
	global_load_dwordx4 v[144:147], v[0:1], off nt
	v_add_u32_e32 v0, 0xc60, v16
	v_or_b32_e32 v184, 0x40000, v4
	s_lshl_b32 s24, s24, 1
	s_add_u32 s12, s12, s24
	s_addc_u32 s13, s13, 0
	v_or_b32_e32 v2, s17, v2
	v_mul_u32_u24_e32 v2, 0x1600, v2
	v_add_u32_e32 v0, 0xc68, v16
	v_lshl_add_u64 v[0:1], v[14:15], 0, v[184:185]
	global_load_dwordx4 v[148:151], v[0:1], off nt
	v_add_u32_e32 v0, 0x1080, v16
	v_or_b32_e32 v184, 0x50000, v4
	v_add_u32_e32 v0, 0x1088, v16
	v_lshl_add_u64 v[0:1], v[14:15], 0, v[184:185]
	global_load_dwordx4 v[152:155], v[0:1], off nt
	v_add_u32_e32 v0, 0x14a0, v16
	v_or_b32_e32 v184, 0x60000, v4
	v_add_u32_e32 v0, 0x14a8, v16
	v_lshl_add_u64 v[0:1], v[14:15], 0, v[184:185]
	global_load_dwordx4 v[156:159], v[0:1], off nt
	v_add_u32_e32 v0, 0x18c0, v16
	v_or_b32_e32 v184, 0x70000, v4
	v_add_u32_e32 v0, 0x18c8, v16
	v_lshl_add_u64 v[0:1], v[14:15], 0, v[184:185]
	global_load_dwordx4 v[160:163], v[0:1], off nt
	v_add_u32_e32 v0, 0x1ce0, v16
	v_add_u32_e32 v0, 0x1ce8, v16
	s_waitcnt vmcnt(0)
	v_add_u32_e32 v164, 0x0, v16
	ds_write2_b32 v164, v132, v133 offset1:1
	ds_write2_b32 v164, v134, v135 offset0:2 offset1:3
	v_add_u32_e32 v164, 0x420, v16
	ds_write2_b32 v164, v136, v137 offset1:1
	ds_write2_b32 v164, v138, v139 offset0:2 offset1:3
	v_add_u32_e32 v164, 0x840, v16
	ds_write2_b32 v164, v140, v141 offset1:1
	ds_write2_b32 v164, v142, v143 offset0:2 offset1:3
	v_add_u32_e32 v164, 0xc60, v16
	ds_write2_b32 v164, v144, v145 offset1:1
	ds_write2_b32 v164, v146, v147 offset0:2 offset1:3
	v_add_u32_e32 v164, 0x1080, v16
	ds_write2_b32 v164, v148, v149 offset1:1
	ds_write2_b32 v164, v150, v151 offset0:2 offset1:3
	v_add_u32_e32 v164, 0x14a0, v16
	ds_write2_b32 v164, v152, v153 offset1:1
	ds_write2_b32 v164, v154, v155 offset0:2 offset1:3
	v_add_u32_e32 v164, 0x18c0, v16
	ds_write2_b32 v164, v156, v157 offset1:1
	ds_write2_b32 v164, v158, v159 offset0:2 offset1:3
	v_add_u32_e32 v164, 0x1ce0, v16
	ds_write2_b32 v164, v160, v161 offset1:1
	ds_write2_b32 v164, v162, v163 offset0:2 offset1:3
	v_and_b32_e32 v0, 7, v7
	s_waitcnt lgkmcnt(0)
	v_mul_u32_u24_e32 v4, 0x420, v0
	v_lshlrev_b32_e32 v7, 2, v6
	v_add3_u32 v4, s25, v4, v7
	ds_read_b32 v7, v4
	ds_read_b32 v8, v4 offset:132
	v_lshlrev_b32_e32 v184, 4, v0
	v_or_b32_e32 v6, s17, v6
	v_lshl_add_u64 v[0:1], s[12:13], 0, v[184:185]
	s_waitcnt lgkmcnt(1)
	v_bfe_u32 v9, v7, 16, 1
	v_add3_u32 v7, v7, v9, s73
	s_waitcnt lgkmcnt(0)
	v_bfe_u32 v9, v8, 16, 1
	v_lshrrev_b32_e32 v7, 16, v7
	v_add3_u32 v8, v8, v9, s73
	v_and_or_b32 v8, v8, s72, v7
	ds_read_b32 v7, v4 offset:264
	ds_read_b32 v9, v4 offset:396
	s_mov_b64 s[12:13], 0x3e900000
	v_mul_u32_u24_e32 v6, 0x1600, v6
	v_lshl_add_u64 v[0:1], v[0:1], 0, s[12:13]
	s_waitcnt lgkmcnt(1)
; #define LAS __attribute__((address_space(3)))
; #define LDS_WAIT() asm volatile("s_waitcnt lgkmcnt(0)" ::: "memory")
; __device__ __forceinline__ unsigned pk2(float lo, float hi) { return f2bf(lo) | (f2bf(hi) << 16); }
; template <class Map>
; __device__ __forceinline__ void conv_item(const Frame& F, int it, const float* W, int K, int N, bf16_t* WT, const float* gk, int gmask, float gmul, const float* bk, i64* cs, i64* bw, Map map) {
;     ...
;         const int c = lane & 7; float gl[8];
; #pragma unroll
;         for (int i = 0; i < 8; ++i) gl[i] = gk ? gk[(k0 + 8 * c + i) & gmask] * gmul : 1.0f;
; #pragma unroll
;         for (int j = 0; j < 4; ++j) { const int n = (lane >> 3) + 8 * j; const LAS float* s = scr + (8 * c) * 33 + n;
;             u32x4 o; o.x = pk2(s[0 * 33] * gl[0], s[1 * 33] * gl[1]); o.y = pk2(s[2 * 33] * gl[2], s[3 * 33] * gl[3]); o.z = pk2(s[4 * 33] * gl[4], s[5 * 33] * gl[5]); o.w = pk2(s[6 * 33] * gl[6], s[7 * 33] * gl[7]);
;             __builtin_nontemporal_store(o, (u32x4*)(WT + (size_t)(v0 + n) * K + k0 + 8 * c)); }
;         LDS_WAIT(); asm volatile("" ::: "memory");
	v_bfe_u32 v10, v7, 16, 1
	v_add3_u32 v7, v7, v10, s73
	s_waitcnt lgkmcnt(0)
	v_bfe_u32 v10, v9, 16, 1
	v_lshrrev_b32_e32 v7, 16, v7
	v_add3_u32 v9, v9, v10, s73
	v_and_or_b32 v9, v9, s72, v7
	ds_read_b32 v7, v4 offset:528
	ds_read_b32 v10, v4 offset:660
	v_lshlrev_b32_e32 v184, 1, v6
	s_waitcnt lgkmcnt(1)
	v_bfe_u32 v11, v7, 16, 1
	v_add3_u32 v7, v7, v11, s73
	s_waitcnt lgkmcnt(0)
	v_bfe_u32 v11, v10, 16, 1
	v_lshrrev_b32_e32 v7, 16, v7
	v_add3_u32 v10, v10, v11, s73
	v_and_or_b32 v10, v10, s72, v7
	ds_read_b32 v7, v4 offset:792
	ds_read_b32 v11, v4 offset:924
	s_waitcnt lgkmcnt(1)
	v_bfe_u32 v14, v7, 16, 1
	v_add3_u32 v7, v7, v14, s73
	s_waitcnt lgkmcnt(0)
	v_bfe_u32 v14, v11, 16, 1
	v_lshrrev_b32_e32 v7, 16, v7
	v_add3_u32 v11, v11, v14, s73
	v_and_or_b32 v11, v11, s72, v7
	v_lshl_add_u64 v[6:7], v[0:1], 0, v[184:185]
	flat_store_dwordx4 v[6:7], v[8:11] nt
	ds_read_b32 v6, v4 offset:32
	ds_read_b32 v7, v4 offset:164
	v_lshlrev_b32_e32 v184, 1, v5
	s_waitcnt lgkmcnt(0)
	v_bfe_u32 v8, v6, 16, 1
	v_add3_u32 v6, v6, v8, s73
	v_bfe_u32 v8, v7, 16, 1
	v_lshrrev_b32_e32 v6, 16, v6
	v_add3_u32 v7, v7, v8, s73
	v_and_or_b32 v6, v7, s72, v6
	ds_read_b32 v7, v4 offset:296
	ds_read_b32 v8, v4 offset:428
	s_waitcnt lgkmcnt(0)
	v_bfe_u32 v9, v7, 16, 1
	v_add3_u32 v7, v7, v9, s73
	v_bfe_u32 v9, v8, 16, 1
	v_lshrrev_b32_e32 v7, 16, v7
	v_add3_u32 v8, v8, v9, s73
	v_and_or_b32 v7, v8, s72, v7
	ds_read_b32 v8, v4 offset:560
	ds_read_b32 v9, v4 offset:692
	s_waitcnt lgkmcnt(0)
	v_bfe_u32 v10, v8, 16, 1
	v_add3_u32 v8, v8, v10, s73
	v_bfe_u32 v10, v9, 16, 1
	v_lshrrev_b32_e32 v8, 16, v8
	v_add3_u32 v9, v9, v10, s73
	v_and_or_b32 v8, v9, s72, v8
	ds_read_b32 v9, v4 offset:824
	ds_read_b32 v10, v4 offset:956
	s_waitcnt lgkmcnt(0)
	v_bfe_u32 v11, v9, 16, 1
	v_add3_u32 v9, v9, v11, s73
	v_bfe_u32 v11, v10, 16, 1
	v_lshrrev_b32_e32 v9, 16, v9
	v_add3_u32 v10, v10, v11, s73
	v_and_or_b32 v9, v10, s72, v9
	v_lshl_add_u64 v[10:11], v[0:1], 0, v[184:185]
	flat_store_dwordx4 v[10:11], v[6:9] nt
	ds_read_b32 v5, v4 offset:64
	ds_read_b32 v6, v4 offset:196
	v_lshlrev_b32_e32 v184, 1, v3
	s_waitcnt lgkmcnt(0)
	v_bfe_u32 v7, v5, 16, 1
	v_add3_u32 v5, v5, v7, s73
	v_bfe_u32 v7, v6, 16, 1
	v_lshrrev_b32_e32 v5, 16, v5
	v_add3_u32 v6, v6, v7, s73
	v_and_or_b32 v6, v6, s72, v5
	ds_read_b32 v5, v4 offset:328
	ds_read_b32 v7, v4 offset:460
	s_waitcnt lgkmcnt(0)
	v_bfe_u32 v8, v5, 16, 1
	v_add3_u32 v5, v5, v8, s73
	v_bfe_u32 v8, v7, 16, 1
	v_lshrrev_b32_e32 v5, 16, v5
	v_add3_u32 v7, v7, v8, s73
	v_and_or_b32 v7, v7, s72, v5
	ds_read_b32 v5, v4 offset:592
	ds_read_b32 v8, v4 offset:724
	s_waitcnt lgkmcnt(0)
	v_bfe_u32 v9, v5, 16, 1
	v_add3_u32 v5, v5, v9, s73
	v_bfe_u32 v9, v8, 16, 1
	v_lshrrev_b32_e32 v5, 16, v5
	v_add3_u32 v8, v8, v9, s73
	v_and_or_b32 v8, v8, s72, v5
	ds_read_b32 v5, v4 offset:856
	ds_read_b32 v9, v4 offset:988
	s_waitcnt lgkmcnt(0)
	v_bfe_u32 v10, v5, 16, 1
	v_add3_u32 v5, v5, v10, s73
	v_bfe_u32 v10, v9, 16, 1
	v_lshrrev_b32_e32 v5, 16, v5
	v_add3_u32 v9, v9, v10, s73
	v_and_or_b32 v9, v9, s72, v5
	v_lshl_add_u64 v[10:11], v[0:1], 0, v[184:185]
	flat_store_dwordx4 v[10:11], v[6:9] nt
	ds_read_b32 v3, v4 offset:96
	ds_read_b32 v5, v4 offset:228
	v_lshlrev_b32_e32 v184, 1, v2
	v_lshl_add_u64 v[0:1], v[0:1], 0, v[184:185]
	s_waitcnt lgkmcnt(0)
	v_bfe_u32 v6, v3, 16, 1
	v_add3_u32 v3, v3, v6, s73
	v_bfe_u32 v6, v5, 16, 1
	v_lshrrev_b32_e32 v3, 16, v3
	v_add3_u32 v5, v5, v6, s73
	v_and_or_b32 v6, v5, s72, v3
	ds_read_b32 v3, v4 offset:360
	ds_read_b32 v5, v4 offset:492
	s_waitcnt lgkmcnt(0)
	v_bfe_u32 v7, v3, 16, 1
	v_add3_u32 v3, v3, v7, s73
	v_bfe_u32 v7, v5, 16, 1
	v_lshrrev_b32_e32 v3, 16, v3
	v_add3_u32 v5, v5, v7, s73
	v_and_or_b32 v7, v5, s72, v3
	ds_read_b32 v3, v4 offset:624
	ds_read_b32 v5, v4 offset:756
	s_waitcnt lgkmcnt(0)
	v_bfe_u32 v8, v3, 16, 1
	v_add3_u32 v3, v3, v8, s73
	v_bfe_u32 v8, v5, 16, 1
	v_lshrrev_b32_e32 v3, 16, v3
	v_add3_u32 v5, v5, v8, s73
	v_and_or_b32 v8, v5, s72, v3
	ds_read_b32 v3, v4 offset:888
	ds_read_b32 v4, v4 offset:1020
	s_waitcnt lgkmcnt(0)
	v_bfe_u32 v5, v3, 16, 1
	v_add3_u32 v3, v3, v5, s73
	v_bfe_u32 v5, v4, 16, 1
	v_lshrrev_b32_e32 v3, 16, v3
	v_add3_u32 v4, v4, v5, s73
	v_and_or_b32 v9, v4, s72, v3
	flat_store_dwordx4 v[0:1], v[6:9] nt
	s_waitcnt lgkmcnt(0)

; #define LAS __attribute__((address_space(3)))
; #define LDS_WAIT() asm volatile("s_waitcnt lgkmcnt(0)" ::: "memory")
; __device__ __forceinline__ float bf_round(float f) { return __uint_as_float(f2bf(f) << 16); }
; template <class Map>
; __device__ __forceinline__ void conv_item(const Frame& F, int it, const float* W, int K, int N, bf16_t* WT, const float* gk, int gmask, float gmul, const float* bk, i64* cs, i64* bw, Map map) {
;     ...
;         const int kb = it / nblk, nb = it % nblk, k0 = 64 * kb, n0 = 32 * nb, v0 = map(n0);
; #pragma unroll
;         for (int i = 0; i < 8; ++i) { const int kk = 8 * i + (lane >> 3), c4 = (lane & 7) * 4;
;             const f32x4 w4 = __builtin_nontemporal_load((const f32x4*)(W + (size_t)(k0 + kk) * N + n0 + c4)); LAS float* d = scr + kk * 33 + c4; d[0] = w4[0]; d[1] = w4[1]; d[2] = w4[2]; d[3] = w4[3]; }
;         LDS_WAIT(); asm volatile("" ::: "memory");
;         if (bk) {
;             const int n = lane & 31, kh = lane >> 5; float sb = 0.f, sc = 0.f;
; #pragma unroll 8
;             for (int j = 0; j < 32; ++j) { const int kk = kh * 32 + j; const float w = scr[kk * 33 + n]; sb += bk[k0 + kk] * w; sc += bf_round(gk[(k0 + kk) & gmask] * gmul * w); }
.LBB0_667:
	s_andn2_b64 vcc, exec, s[12:13]
	s_cbranch_vccnz .LBB0_691
	v_readlane_b32 s48, v252, 14
	v_readlane_b32 s49, v252, 15
	s_mov_b64 s[12:13], s[48:49]
	s_load_dwordx2 s[12:13], s[12:13], 0x78
	s_mul_i32 s17, s20, 0x5800000
	v_readlane_b32 s70, v252, 12
	v_readlane_b32 s71, v252, 13
	s_mov_b64 s[24:25], s[70:71]
	s_waitcnt lgkmcnt(0)
	s_add_u32 s87, s12, s17
	s_mul_hi_i32 s12, s20, 0x5800000
	s_addc_u32 s91, s13, s12
	s_mov_b64 s[12:13], s[48:49]
	s_load_dwordx2 s[40:41], s[12:13], 0x68
	s_lshl_b64 s[12:13], s[46:47], 2
	v_mov_b32_e32 v3, v220
	v_mov_b32_e32 v5, v185
	s_waitcnt lgkmcnt(0)
	s_add_u32 s26, s40, s12
	s_addc_u32 s27, s41, s13
	s_and_b32 s17, s16, 0xffff
	s_mov_b64 s[12:13], s[48:49]
	s_mul_i32 s52, s17, 0xba2f
	s_lshr_b32 s52, s52, 24
	s_load_dwordx2 s[74:75], s[12:13], 0x70
	s_mov_b64 s[12:13], s[70:71]
	s_mov_b64 s[48:49], s[70:71]
	s_mul_i32 s70, s52, 0x160
	s_sub_i32 s90, s16, s70
	s_lshl_b32 s16, s90, 5
	s_lshl_b32 s52, s52, 6
	s_and_b32 s70, s90, 0xffff
	s_add_i32 s71, s16, 0xea00
	s_cmpk_lt_u32 s70, 0xb0
	s_cselect_b32 s16, s16, s71
	s_sext_i32_i16 s92, s16
	s_lshl_b32 s71, s92, 1
	s_cmpk_gt_u32 s70, 0xaf
	s_cselect_b32 s16, 0x80, 0
	s_lshl_b32 s90, s90, 7
	s_and_b32 s70, s92, 0x60
	s_and_b32 s90, s90, 0x3ff80
	s_add_u32 s90, s87, s90
	v_bfe_u32 v17, v3, 3, 3
	v_lshlrev_b32_e32 v0, 4, v3
	s_addc_u32 s91, s91, 0
	v_and_b32_e32 v184, 0x70, v0
	v_or_b32_e32 v2, s52, v17
	v_lshl_add_u64 v[0:1], s[90:91], 0, v[184:185]
	v_mul_u32_u24_e32 v4, 0xb000, v2
	v_lshl_add_u64 v[4:5], v[0:1], 0, v[4:5]
	global_load_dwordx4 v[132:135], v[4:5], off nt
	v_mul_u32_u24_e32 v8, 0x84, v17
	v_readlane_b32 s87, v255, 17
	v_or_b32_e32 v16, 8, v17
	v_or_b32_e32 v15, 16, v17
	v_add3_u32 v8, s87, v184, v8
	v_add_u32_e32 v9, 0x420, v8
	v_or_b32_e32 v14, 24, v17
	s_and_b32 s71, s71, 0xffffff00
	s_or_b32 s16, s70, s16
	s_or_b32 s70, s16, s71
	s_waitcnt lgkmcnt(0)
	s_cmp_eq_u64 s[74:75], 0
	v_or_b32_e32 v4, s52, v16
	v_mul_u32_u24_e32 v184, 0xb000, v4
	v_lshl_add_u64 v[4:5], v[0:1], 0, v[184:185]
	global_load_dwordx4 v[136:139], v[4:5], off nt
	v_add_u32_e32 v4, 0x428, v8
	v_or_b32_e32 v4, s52, v15
	v_mul_u32_u24_e32 v184, 0xb000, v4
	v_lshl_add_u64 v[4:5], v[0:1], 0, v[184:185]
	global_load_dwordx4 v[140:143], v[4:5], off nt
	v_add_u32_e32 v9, 0x840, v8
	v_add_u32_e32 v4, 0x848, v8
	v_or_b32_e32 v4, s52, v14
	v_mul_u32_u24_e32 v184, 0xb000, v4
	v_lshl_add_u64 v[4:5], v[0:1], 0, v[184:185]
	global_load_dwordx4 v[144:147], v[4:5], off nt
	v_add_u32_e32 v9, 0xc60, v8
	v_add_u32_e32 v4, 0xc68, v8
	v_or_b32_e32 v4, 32, v2
	v_mul_u32_u24_e32 v184, 0xb000, v4
	v_lshl_add_u64 v[4:5], v[0:1], 0, v[184:185]
	global_load_dwordx4 v[148:151], v[4:5], off nt
	v_add_u32_e32 v9, 0x1080, v8
	v_add_u32_e32 v4, 0x1088, v8
	v_or_b32_e32 v4, 40, v2
	v_mul_u32_u24_e32 v184, 0xb000, v4
	v_lshl_add_u64 v[4:5], v[0:1], 0, v[184:185]
	global_load_dwordx4 v[152:155], v[4:5], off nt
	v_add_u32_e32 v9, 0x14a0, v8
	v_add_u32_e32 v4, 0x14a8, v8
	v_or_b32_e32 v4, 48, v2
	v_mul_u32_u24_e32 v184, 0xb000, v4
	v_lshl_add_u64 v[4:5], v[0:1], 0, v[184:185]
	global_load_dwordx4 v[156:159], v[4:5], off nt
	v_or_b32_e32 v2, 56, v2
	v_add_u32_e32 v9, 0x18c0, v8
	v_mul_u32_u24_e32 v184, 0xb000, v2
	v_lshl_add_u64 v[0:1], v[0:1], 0, v[184:185]
	v_add_u32_e32 v4, 0x18c8, v8
	global_load_dwordx4 v[160:163], v[0:1], off nt
	v_add_u32_e32 v0, 0x1ce0, v8
	v_add_u32_e32 v0, 0x1ce8, v8
	s_waitcnt vmcnt(0)
	v_add_u32_e32 v164, 0x0, v8
	ds_write2_b32 v164, v132, v133 offset1:1
	ds_write2_b32 v164, v134, v135 offset0:2 offset1:3
	v_add_u32_e32 v164, 0x420, v8
	ds_write2_b32 v164, v136, v137 offset1:1
	ds_write2_b32 v164, v138, v139 offset0:2 offset1:3
	v_add_u32_e32 v164, 0x840, v8
	ds_write2_b32 v164, v140, v141 offset1:1
	ds_write2_b32 v164, v142, v143 offset0:2 offset1:3
	v_add_u32_e32 v164, 0xc60, v8
	ds_write2_b32 v164, v144, v145 offset1:1
	ds_write2_b32 v164, v146, v147 offset0:2 offset1:3
	v_add_u32_e32 v164, 0x1080, v8
	ds_write2_b32 v164, v148, v149 offset1:1
	ds_write2_b32 v164, v150, v151 offset0:2 offset1:3
	v_add_u32_e32 v164, 0x14a0, v8
	ds_write2_b32 v164, v152, v153 offset1:1
	ds_write2_b32 v164, v154, v155 offset0:2 offset1:3
	v_add_u32_e32 v164, 0x18c0, v8
	ds_write2_b32 v164, v156, v157 offset1:1
	ds_write2_b32 v164, v158, v159 offset0:2 offset1:3
	v_add_u32_e32 v164, 0x1ce0, v8
	ds_write2_b32 v164, v160, v161 offset1:1
	ds_write2_b32 v164, v162, v163 offset0:2 offset1:3
	s_waitcnt lgkmcnt(0)
	s_cbranch_scc1 .LBB0_674
	v_readlane_b32 s90, v255, 25
	v_and_b32_e32 v0, 32, v3
	v_readlane_b32 s91, v255, 26
	s_add_u32 s74, s74, s90
	s_mul_hi_u32 s71, s17, 0xba2e8c
	s_addc_u32 s75, s75, s91
	v_add_u32_e32 v20, s52, v0
	s_lshl_b32 s16, s71, 8
	v_lshlrev_b32_e32 v184, 2, v20
	v_bfe_u32 v1, v3, 5, 1
	s_add_u32 s16, s74, s16
	v_lshl_add_u64 v[4:5], s[74:75], 0, v[184:185]
	v_lshrrev_b32_e32 v0, 5, v3
	v_lshlrev_b32_e32 v184, 7, v1
	s_addc_u32 s17, s75, 0
	v_lshl_add_u64 v[6:7], s[16:17], 0, v[184:185]
	s_add_u32 s16, s40, s90
	v_and_b32_e32 v0, 1, v0
	s_addc_u32 s17, s41, s91
	s_lshl_b32 s71, s71, 6
	v_lshlrev_b16_e32 v0, 5, v0
	v_or_b32_e32 v0, s71, v0
	v_and_b32_e32 v0, 0x7e0, v0
	v_and_b32_e32 v18, 31, v3
	v_lshlrev_b32_e32 v184, 2, v0
	v_mul_u32_u24_e32 v0, 0x1080, v1
	v_lshl_add_u64 v[8:9], s[16:17], 0, v[184:185]
	v_lshl_or_b32 v0, v18, 2, v0
	v_readlane_b32 s16, v255, 17
	v_and_b32_e32 v19, 63, v3
	s_mov_b64 s[74:75], 0
	v_add_u32_e32 v21, s16, v0
	v_mov_b32_e32 v0, 0
	v_mov_b32_e32 v1, v0

; #define LAS __attribute__((address_space(3)))
; #define LDS_WAIT() asm volatile("s_waitcnt lgkmcnt(0)" ::: "memory")
; template <class Map>
; __device__ __forceinline__ void conv_item(const Frame& F, int it, const float* W, int K, int N, bf16_t* WT, const float* gk, int gmask, float gmul, const float* bk, i64* cs, i64* bw, Map map) {
;     ...
;         const int kb = it / nblk, nb = it % nblk, k0 = 64 * kb, n0 = 32 * nb, v0 = map(n0);
; #pragma unroll
;         for (int i = 0; i < 8; ++i) { const int kk = 8 * i + (lane >> 3), c4 = (lane & 7) * 4;
;             const f32x4 w4 = __builtin_nontemporal_load((const f32x4*)(W + (size_t)(k0 + kk) * N + n0 + c4)); LAS float* d = scr + kk * 33 + c4; d[0] = w4[0]; d[1] = w4[1]; d[2] = w4[2]; d[3] = w4[3]; }
;         LDS_WAIT(); asm volatile("" ::: "memory");
;     ...
;         const int c = lane & 7; float gl[8];
; #pragma unroll
;         for (int i = 0; i < 8; ++i) gl[i] = gk ? gk[(k0 + 8 * c + i) & gmask] * gmul : 1.0f;
.LBB0_692:
	s_andn2_b64 vcc, exec, s[12:13]
	s_cbranch_vccnz .LBB0_710
	v_readlane_b32 s16, v252, 14
	v_readlane_b32 s17, v252, 15
	s_mov_b64 s[12:13], s[16:17]
	s_load_dwordx2 s[12:13], s[12:13], 0x58
	s_add_i32 s40, s86, 0xe800
	v_mov_b32_e32 v14, v220
	v_mov_b32_e32 v7, v185
	s_waitcnt lgkmcnt(0)
	s_add_u32 s41, s12, s30
	s_addc_u32 s48, s13, s31
	v_readlane_b32 s12, v252, 12
	v_readlane_b32 s13, v252, 13
	s_load_dwordx2 s[26:27], s[16:17], 0x50
	s_waitcnt lgkmcnt(0)
	s_add_u32 s24, s26, s62
	s_addc_u32 s25, s27, s63
	s_lshl_b32 s16, s86, 5
	s_and_b32 s16, s16, 0x7e0
	s_and_b32 s17, s40, 0xffc0
	s_lshl_b32 s40, s16, 2
	v_bfe_u32 v11, v14, 3, 3
	s_add_u32 s40, s41, s40
	v_lshlrev_b32_e32 v0, 4, v14
	s_addc_u32 s41, s48, 0
	v_and_b32_e32 v184, 0x70, v0
	v_or_b32_e32 v0, s17, v11
	v_lshl_add_u64 v[4:5], s[40:41], 0, v[184:185]
	v_lshlrev_b32_e32 v6, 13, v0
	v_lshl_add_u64 v[0:1], v[4:5], 0, v[6:7]
	global_load_dwordx4 v[132:135], v[0:1], off nt
	v_mul_u32_u24_e32 v7, 0x84, v11
	v_readlane_b32 s40, v255, 17
	v_or_b32_e32 v10, 8, v11
	v_or_b32_e32 v9, 16, v11
	v_add3_u32 v7, s40, v184, v7
	v_add_u32_e32 v8, 0x420, v7
	v_add_u32_e32 v15, 0xc60, v7
	v_and_b32_e32 v14, 7, v14
	s_cmp_lg_u64 s[26:27], 0
	s_cselect_b64 s[48:49], -1, 0
	s_cmp_eq_u64 s[26:27], 0
	v_or_b32_e32 v0, s17, v10
	v_lshlrev_b32_e32 v184, 13, v0
	v_lshl_add_u64 v[0:1], v[4:5], 0, v[184:185]
	global_load_dwordx4 v[136:139], v[0:1], off nt
	v_add_u32_e32 v0, 0x428, v7
	v_or_b32_e32 v0, s17, v9
	v_lshlrev_b32_e32 v184, 13, v0
	v_lshl_add_u64 v[0:1], v[4:5], 0, v[184:185]
	global_load_dwordx4 v[140:143], v[0:1], off nt
	v_add_u32_e32 v8, 0x840, v7
	v_add_u32_e32 v0, 0x848, v7
	v_or_b32_e32 v8, 24, v11
	v_or_b32_e32 v0, s17, v8
	v_lshlrev_b32_e32 v184, 13, v0
	v_lshl_add_u64 v[0:1], v[4:5], 0, v[184:185]
	global_load_dwordx4 v[144:147], v[0:1], off nt
	v_or_b32_e32 v184, 0x40000, v6
	v_add_u32_e32 v0, 0xc68, v7
	v_lshl_add_u64 v[0:1], v[4:5], 0, v[184:185]
	global_load_dwordx4 v[148:151], v[0:1], off nt
	v_add_u32_e32 v15, 0x1080, v7
	v_or_b32_e32 v184, 0x50000, v6
	v_add_u32_e32 v0, 0x1088, v7
	v_lshl_add_u64 v[0:1], v[4:5], 0, v[184:185]
	global_load_dwordx4 v[152:155], v[0:1], off nt
	v_add_u32_e32 v15, 0x14a0, v7
	v_or_b32_e32 v184, 0x60000, v6
	v_add_u32_e32 v0, 0x14a8, v7
	v_lshl_add_u64 v[0:1], v[4:5], 0, v[184:185]
	global_load_dwordx4 v[156:159], v[0:1], off nt
	v_add_u32_e32 v15, 0x18c0, v7
	v_or_b32_e32 v184, 0x70000, v6
	v_add_u32_e32 v0, 0x18c8, v7
	v_lshl_add_u64 v[0:1], v[4:5], 0, v[184:185]
	global_load_dwordx4 v[160:163], v[0:1], off nt
	v_add_u32_e32 v4, 0x1ce0, v7
	v_lshlrev_b32_e32 v15, 3, v14
	v_add_u32_e32 v0, 0x1ce8, v7
	s_waitcnt vmcnt(0)
	v_add_u32_e32 v164, 0x0, v7
	ds_write2_b32 v164, v132, v133 offset1:1
	ds_write2_b32 v164, v134, v135 offset0:2 offset1:3
	v_add_u32_e32 v164, 0x420, v7
	ds_write2_b32 v164, v136, v137 offset1:1
	ds_write2_b32 v164, v138, v139 offset0:2 offset1:3
	v_add_u32_e32 v164, 0x840, v7
	ds_write2_b32 v164, v140, v141 offset1:1
	ds_write2_b32 v164, v142, v143 offset0:2 offset1:3
	v_add_u32_e32 v164, 0xc60, v7
	ds_write2_b32 v164, v144, v145 offset1:1
	ds_write2_b32 v164, v146, v147 offset0:2 offset1:3
	v_add_u32_e32 v164, 0x1080, v7
	ds_write2_b32 v164, v148, v149 offset1:1
	ds_write2_b32 v164, v150, v151 offset0:2 offset1:3
	v_add_u32_e32 v164, 0x14a0, v7
	ds_write2_b32 v164, v152, v153 offset1:1
	ds_write2_b32 v164, v154, v155 offset0:2 offset1:3
	v_add_u32_e32 v164, 0x18c0, v7
	ds_write2_b32 v164, v156, v157 offset1:1
	ds_write2_b32 v164, v158, v159 offset0:2 offset1:3
	v_add_u32_e32 v164, 0x1ce0, v7
	ds_write2_b32 v164, v160, v161 offset1:1
	ds_write2_b32 v164, v162, v163 offset0:2 offset1:3
	s_waitcnt lgkmcnt(0)
	v_or_b32_e32 v1, s17, v15
	v_and_b32_e32 v1, 0xf8, v1
	v_mov_b32_e32 v0, 1.0
	v_lshlrev_b32_e32 v16, 2, v1
	v_mov_b32_e32 v2, 1.0
	s_cbranch_scc1 .LBB0_695
	global_load_dword v1, v16, s[24:25]
	s_waitcnt vmcnt(0)
	v_mul_f32_e32 v2, v13, v1

; #define LAS __attribute__((address_space(3)))
; #define LDS_WAIT() asm volatile("s_waitcnt lgkmcnt(0)" ::: "memory")
; __device__ __forceinline__ unsigned pk2(float lo, float hi) { return f2bf(lo) | (f2bf(hi) << 16); }
; template <class Map>
; __device__ __forceinline__ void conv_item(const Frame& F, int it, const float* W, int K, int N, bf16_t* WT, const float* gk, int gmask, float gmul, const float* bk, i64* cs, i64* bw, Map map) {
;     ...
;         const int kb = it / nblk, nb = it % nblk, k0 = 64 * kb, n0 = 32 * nb, v0 = map(n0);
; #pragma unroll
;         for (int i = 0; i < 8; ++i) { const int kk = 8 * i + (lane >> 3), c4 = (lane & 7) * 4;
;             const f32x4 w4 = __builtin_nontemporal_load((const f32x4*)(W + (size_t)(k0 + kk) * N + n0 + c4)); LAS float* d = scr + kk * 33 + c4; d[0] = w4[0]; d[1] = w4[1]; d[2] = w4[2]; d[3] = w4[3]; }
;         LDS_WAIT(); asm volatile("" ::: "memory");
;     ...
;         const int c = lane & 7; float gl[8];
; #pragma unroll
;         for (int i = 0; i < 8; ++i) gl[i] = gk ? gk[(k0 + 8 * c + i) & gmask] * gmul : 1.0f;
; #pragma unroll
;         for (int j = 0; j < 4; ++j) { const int n = (lane >> 3) + 8 * j; const LAS float* s = scr + (8 * c) * 33 + n;
;             u32x4 o; o.x = pk2(s[0 * 33] * gl[0], s[1 * 33] * gl[1]); o.y = pk2(s[2 * 33] * gl[2], s[3 * 33] * gl[3]); o.z = pk2(s[4 * 33] * gl[4], s[5 * 33] * gl[5]); o.w = pk2(s[6 * 33] * gl[6], s[7 * 33] * gl[7]);
.LBB0_848:
	s_andn2_saveexec_b64 s[84:85], s[12:13]
	s_cbranch_execz .LBB0_850
	v_readlane_b32 s12, v252, 14
	v_readlane_b32 s13, v252, 15
	s_load_dwordx2 s[12:13], s[12:13], 0x90
	v_lshlrev_b32_e32 v0, 5, v0
	v_mov_b32_e32 v14, v220
	v_and_b32_e32 v2, 0x7e0, v0
	v_and_b32_e32 v15, 0xc0, v1
	s_waitcnt lgkmcnt(0)
	s_add_u32 s16, s12, s42
	s_addc_u32 s17, s13, s43
	v_readlane_b32 s12, v252, 12
	v_readlane_b32 s13, v252, 13
	v_lshlrev_b32_e32 v184, 2, v2
	v_bfe_u32 v7, v14, 3, 3
	v_lshlrev_b32_e32 v3, 4, v14
	v_lshl_add_u64 v[0:1], s[16:17], 0, v[184:185]
	v_and_b32_e32 v184, 0x70, v3
	v_or_b32_e32 v3, v7, v15
	v_lshl_add_u64 v[0:1], v[0:1], 0, v[184:185]
	v_lshlrev_b32_e32 v12, 13, v3
	v_mov_b32_e32 v13, v185
	v_lshl_add_u64 v[4:5], v[0:1], 0, v[12:13]
	global_load_dwordx4 v[132:135], v[4:5], off nt
	v_mul_u32_u24_e32 v3, 0x84, v7
	v_or_b32_e32 v6, 8, v7
	v_add3_u32 v13, s79, v184, v3
	v_or_b32_e32 v3, v6, v15
	v_lshlrev_b32_e32 v184, 13, v3
	v_lshl_add_u64 v[4:5], v[0:1], 0, v[184:185]
	v_add_u32_e32 v3, 0x420, v13
	v_or_b32_e32 v6, v6, v2
	global_load_dwordx4 v[136:139], v[4:5], off nt
	v_or_b32_e32 v4, 16, v7
	v_add_u32_e32 v3, 0x428, v13
	v_or_b32_e32 v3, v4, v15
	v_lshlrev_b32_e32 v184, 13, v3
	v_lshl_add_u64 v[8:9], v[0:1], 0, v[184:185]
	global_load_dwordx4 v[140:143], v[8:9], off nt
	v_add_u32_e32 v3, 0x840, v13
	v_or_b32_e32 v4, v4, v2
	v_add_u32_e32 v3, 0x848, v13
	v_or_b32_e32 v3, 24, v7
	v_or_b32_e32 v5, v3, v15
	v_lshlrev_b32_e32 v184, 13, v5
	v_lshl_add_u64 v[8:9], v[0:1], 0, v[184:185]
	global_load_dwordx4 v[144:147], v[8:9], off nt
	v_add_u32_e32 v5, 0xc60, v13
	v_or_b32_e32 v184, 0x40000, v12
	v_add_u32_e32 v5, 0xc68, v13
	v_lshl_add_u64 v[8:9], v[0:1], 0, v[184:185]
	global_load_dwordx4 v[148:151], v[8:9], off nt
	v_add_u32_e32 v5, 0x1080, v13
	v_or_b32_e32 v184, 0x50000, v12
	v_add_u32_e32 v5, 0x1088, v13
	v_lshl_add_u64 v[8:9], v[0:1], 0, v[184:185]
	global_load_dwordx4 v[152:155], v[8:9], off nt
	v_add_u32_e32 v5, 0x14a0, v13
	v_or_b32_e32 v184, 0x60000, v12
	v_add_u32_e32 v5, 0x14a8, v13
	v_lshl_add_u64 v[8:9], v[0:1], 0, v[184:185]
	global_load_dwordx4 v[156:159], v[8:9], off nt
	v_add_u32_e32 v5, 0x18c0, v13
	v_or_b32_e32 v184, 0x70000, v12
	v_lshl_add_u64 v[0:1], v[0:1], 0, v[184:185]
	v_lshlrev_b32_e32 v184, 1, v15
	v_add_u32_e32 v5, 0x18c8, v13
	global_load_dwordx4 v[160:163], v[0:1], off nt
	v_add_u32_e32 v0, 0x1ce0, v13
	v_and_b32_e32 v5, 7, v14
	v_add_u32_e32 v0, 0x1ce8, v13
	s_waitcnt vmcnt(0)
	v_add_u32_e32 v164, 0x0, v13
	ds_write2_b32 v164, v132, v133 offset1:1
	ds_write2_b32 v164, v134, v135 offset0:2 offset1:3
	v_add_u32_e32 v164, 0x420, v13
	ds_write2_b32 v164, v136, v137 offset1:1
	ds_write2_b32 v164, v138, v139 offset0:2 offset1:3
	v_add_u32_e32 v164, 0x840, v13
	ds_write2_b32 v164, v140, v141 offset1:1
	ds_write2_b32 v164, v142, v143 offset0:2 offset1:3
	v_add_u32_e32 v164, 0xc60, v13
	ds_write2_b32 v164, v144, v145 offset1:1
	ds_write2_b32 v164, v146, v147 offset0:2 offset1:3
	v_add_u32_e32 v164, 0x1080, v13
	ds_write2_b32 v164, v148, v149 offset1:1
	ds_write2_b32 v164, v150, v151 offset0:2 offset1:3
	v_add_u32_e32 v164, 0x14a0, v13
	ds_write2_b32 v164, v152, v153 offset1:1
	ds_write2_b32 v164, v154, v155 offset0:2 offset1:3
	v_add_u32_e32 v164, 0x18c0, v13
	ds_write2_b32 v164, v156, v157 offset1:1
	ds_write2_b32 v164, v158, v159 offset0:2 offset1:3
	v_add_u32_e32 v164, 0x1ce0, v13
	ds_write2_b32 v164, v160, v161 offset1:1
	ds_write2_b32 v164, v162, v163 offset0:2 offset1:3
	s_waitcnt lgkmcnt(0)
	v_mul_u32_u24_e32 v8, 0x420, v5
	v_lshl_add_u64 v[0:1], s[12:13], 0, v[184:185]
	v_lshlrev_b32_e32 v184, 4, v5
	v_lshlrev_b32_e32 v5, 2, v7
	v_add3_u32 v5, s79, v8, v5
	ds_read_b32 v8, v5
	ds_read_b32 v9, v5 offset:132
	v_lshl_add_u64 v[0:1], v[0:1], 0, v[184:185]
	s_mov_b64 s[12:13], 0x40700000
	v_or_b32_e32 v7, v7, v2
	s_waitcnt lgkmcnt(1)
	v_bfe_u32 v10, v8, 16, 1
	v_add3_u32 v8, v8, v10, s73
	s_waitcnt lgkmcnt(0)
	v_bfe_u32 v10, v9, 16, 1
	v_lshrrev_b32_e32 v8, 16, v8
	v_add3_u32 v9, v9, v10, s73
	v_and_or_b32 v8, v9, s72, v8
	ds_read_b32 v9, v5 offset:264
	ds_read_b32 v10, v5 offset:396
	v_lshl_add_u64 v[0:1], v[0:1], 0, s[12:13]
	v_lshlrev_b32_e32 v184, 9, v7
	v_or_b32_e32 v2, v3, v2
	s_waitcnt lgkmcnt(1)
; #define LAS __attribute__((address_space(3)))
; #define LDS_WAIT() asm volatile("s_waitcnt lgkmcnt(0)" ::: "memory")
; __device__ __forceinline__ unsigned pk2(float lo, float hi) { return f2bf(lo) | (f2bf(hi) << 16); }
; template <class Map>
; __device__ __forceinline__ void conv_item(const Frame& F, int it, const float* W, int K, int N, bf16_t* WT, const float* gk, int gmask, float gmul, const float* bk, i64* cs, i64* bw, Map map) {
;     ...
;         for (int j = 0; j < 4; ++j) { const int n = (lane >> 3) + 8 * j; const LAS float* s = scr + (8 * c) * 33 + n;
;             u32x4 o; o.x = pk2(s[0 * 33] * gl[0], s[1 * 33] * gl[1]); o.y = pk2(s[2 * 33] * gl[2], s[3 * 33] * gl[3]); o.z = pk2(s[4 * 33] * gl[4], s[5 * 33] * gl[5]); o.w = pk2(s[6 * 33] * gl[6], s[7 * 33] * gl[7]);
;             __builtin_nontemporal_store(o, (u32x4*)(WT + (size_t)(v0 + n) * K + k0 + 8 * c)); }
;         LDS_WAIT(); asm volatile("" ::: "memory");
	v_bfe_u32 v11, v9, 16, 1
	v_add3_u32 v9, v9, v11, s73
	s_waitcnt lgkmcnt(0)
	v_bfe_u32 v11, v10, 16, 1
	v_lshrrev_b32_e32 v9, 16, v9
	v_add3_u32 v10, v10, v11, s73
	v_and_or_b32 v9, v10, s72, v9
	ds_read_b32 v10, v5 offset:528
	ds_read_b32 v11, v5 offset:660
	s_waitcnt lgkmcnt(1)
	v_bfe_u32 v12, v10, 16, 1
	v_add3_u32 v10, v10, v12, s73
	s_waitcnt lgkmcnt(0)
	v_bfe_u32 v12, v11, 16, 1
	v_lshrrev_b32_e32 v10, 16, v10
	v_add3_u32 v11, v11, v12, s73
	v_and_or_b32 v10, v11, s72, v10
	ds_read_b32 v11, v5 offset:792
	ds_read_b32 v12, v5 offset:924
	s_waitcnt lgkmcnt(1)
	v_bfe_u32 v13, v11, 16, 1
	v_add3_u32 v11, v11, v13, s73
	s_waitcnt lgkmcnt(0)
	v_bfe_u32 v13, v12, 16, 1
	v_lshrrev_b32_e32 v11, 16, v11
	v_add3_u32 v12, v12, v13, s73
	v_and_or_b32 v11, v12, s72, v11
	v_lshl_add_u64 v[12:13], v[0:1], 0, v[184:185]
	flat_store_dwordx4 v[12:13], v[8:11] nt
	ds_read_b32 v7, v5 offset:32
	ds_read_b32 v8, v5 offset:164
	v_lshlrev_b32_e32 v184, 9, v6
	s_waitcnt lgkmcnt(0)
	v_bfe_u32 v9, v7, 16, 1
	v_add3_u32 v7, v7, v9, s73
	v_bfe_u32 v9, v8, 16, 1
	v_lshrrev_b32_e32 v7, 16, v7
	v_add3_u32 v8, v8, v9, s73
	v_and_or_b32 v8, v8, s72, v7
	ds_read_b32 v7, v5 offset:296
	ds_read_b32 v9, v5 offset:428
	s_waitcnt lgkmcnt(0)
	v_bfe_u32 v10, v7, 16, 1
	v_add3_u32 v7, v7, v10, s73
	v_bfe_u32 v10, v9, 16, 1
	v_lshrrev_b32_e32 v7, 16, v7
	v_add3_u32 v9, v9, v10, s73
	v_and_or_b32 v9, v9, s72, v7
	ds_read_b32 v7, v5 offset:560
	ds_read_b32 v10, v5 offset:692
	s_waitcnt lgkmcnt(0)
	v_bfe_u32 v11, v7, 16, 1
	v_add3_u32 v7, v7, v11, s73
	v_bfe_u32 v11, v10, 16, 1
	v_lshrrev_b32_e32 v7, 16, v7
	v_add3_u32 v10, v10, v11, s73
	v_and_or_b32 v10, v10, s72, v7
	ds_read_b32 v7, v5 offset:824
	ds_read_b32 v11, v5 offset:956
	s_waitcnt lgkmcnt(0)
	v_bfe_u32 v12, v7, 16, 1
	v_add3_u32 v7, v7, v12, s73
	v_bfe_u32 v12, v11, 16, 1
	v_lshrrev_b32_e32 v7, 16, v7
	v_add3_u32 v11, v11, v12, s73
	v_and_or_b32 v11, v11, s72, v7
	v_lshl_add_u64 v[6:7], v[0:1], 0, v[184:185]
	flat_store_dwordx4 v[6:7], v[8:11] nt
	ds_read_b32 v6, v5 offset:64
	ds_read_b32 v7, v5 offset:196
	v_lshlrev_b32_e32 v184, 9, v4
	s_waitcnt lgkmcnt(0)
	v_bfe_u32 v8, v6, 16, 1
	v_add3_u32 v6, v6, v8, s73
	v_bfe_u32 v8, v7, 16, 1
	v_lshrrev_b32_e32 v6, 16, v6
	v_add3_u32 v7, v7, v8, s73
	v_and_or_b32 v6, v7, s72, v6
	ds_read_b32 v7, v5 offset:328
	ds_read_b32 v8, v5 offset:460
	s_waitcnt lgkmcnt(0)
	v_bfe_u32 v9, v7, 16, 1
	v_add3_u32 v7, v7, v9, s73
	v_bfe_u32 v9, v8, 16, 1
	v_lshrrev_b32_e32 v7, 16, v7
	v_add3_u32 v8, v8, v9, s73
	v_and_or_b32 v7, v8, s72, v7
	ds_read_b32 v8, v5 offset:592
	ds_read_b32 v9, v5 offset:724
	s_waitcnt lgkmcnt(0)
	v_bfe_u32 v10, v8, 16, 1
	v_add3_u32 v8, v8, v10, s73
	v_bfe_u32 v10, v9, 16, 1
	v_lshrrev_b32_e32 v8, 16, v8
	v_add3_u32 v9, v9, v10, s73
	v_and_or_b32 v8, v9, s72, v8
	ds_read_b32 v9, v5 offset:856
	ds_read_b32 v10, v5 offset:988
	s_waitcnt lgkmcnt(0)
	v_bfe_u32 v11, v9, 16, 1
	v_add3_u32 v9, v9, v11, s73
	v_bfe_u32 v11, v10, 16, 1
	v_lshrrev_b32_e32 v9, 16, v9
	v_add3_u32 v10, v10, v11, s73
	v_and_or_b32 v9, v10, s72, v9
	v_lshl_add_u64 v[10:11], v[0:1], 0, v[184:185]
	flat_store_dwordx4 v[10:11], v[6:9] nt
	ds_read_b32 v4, v5 offset:96
	ds_read_b32 v6, v5 offset:228
	v_lshlrev_b32_e32 v184, 9, v2
	v_lshl_add_u64 v[0:1], v[0:1], 0, v[184:185]
	s_waitcnt lgkmcnt(0)
	v_bfe_u32 v7, v4, 16, 1
	v_add3_u32 v4, v4, v7, s73
	v_bfe_u32 v7, v6, 16, 1
	v_lshrrev_b32_e32 v4, 16, v4
	v_add3_u32 v6, v6, v7, s73
	v_and_or_b32 v6, v6, s72, v4
	ds_read_b32 v4, v5 offset:360
	ds_read_b32 v7, v5 offset:492
	s_waitcnt lgkmcnt(0)
	v_bfe_u32 v8, v4, 16, 1
	v_add3_u32 v4, v4, v8, s73
	v_bfe_u32 v8, v7, 16, 1
	v_lshrrev_b32_e32 v4, 16, v4
	v_add3_u32 v7, v7, v8, s73
	v_and_or_b32 v7, v7, s72, v4
	ds_read_b32 v4, v5 offset:624
	ds_read_b32 v8, v5 offset:756
	s_waitcnt lgkmcnt(0)
	v_bfe_u32 v9, v4, 16, 1
	v_add3_u32 v4, v4, v9, s73
	v_bfe_u32 v9, v8, 16, 1
	v_lshrrev_b32_e32 v4, 16, v4
	v_add3_u32 v8, v8, v9, s73
	v_and_or_b32 v8, v8, s72, v4
	ds_read_b32 v4, v5 offset:888
	ds_read_b32 v5, v5 offset:1020
	s_waitcnt lgkmcnt(0)
	v_bfe_u32 v9, v4, 16, 1
	v_add3_u32 v4, v4, v9, s73
	v_bfe_u32 v9, v5, 16, 1
	v_lshrrev_b32_e32 v4, 16, v4
	v_add3_u32 v5, v5, v9, s73
	v_and_or_b32 v9, v5, s72, v4
	flat_store_dwordx4 v[0:1], v[6:9] nt
	s_waitcnt lgkmcnt(0)

; #define LAS __attribute__((address_space(3)))
; #define LDS_WAIT() asm volatile("s_waitcnt lgkmcnt(0)" ::: "memory")
; template <class Map>
; __device__ __forceinline__ void conv_item(const Frame& F, int it, const float* W, int K, int N, bf16_t* WT, const float* gk, int gmask, float gmul, const float* bk, i64* cs, i64* bw, Map map) {
;     ...
;         const int kb = it / nblk, nb = it % nblk, k0 = 64 * kb, n0 = 32 * nb, v0 = map(n0);
; #pragma unroll
;         for (int i = 0; i < 8; ++i) { const int kk = 8 * i + (lane >> 3), c4 = (lane & 7) * 4;
;             const f32x4 w4 = __builtin_nontemporal_load((const f32x4*)(W + (size_t)(k0 + kk) * N + n0 + c4)); LAS float* d = scr + kk * 33 + c4; d[0] = w4[0]; d[1] = w4[1]; d[2] = w4[2]; d[3] = w4[3]; }
;         LDS_WAIT(); asm volatile("" ::: "memory");
;         if (bk) {
;             const int n = lane & 31, kh = lane >> 5; float sb = 0.f, sc = 0.f;
; #pragma unroll 8
.LBB0_851:
	s_andn2_saveexec_b64 s[82:83], s[82:83]
	s_cbranch_execz .LBB0_857
	v_readlane_b32 s48, v252, 14
	v_readlane_b32 s49, v252, 15
	s_mov_b64 s[12:13], s[48:49]
	s_load_dwordx2 s[12:13], s[12:13], 0x88
	v_readlane_b32 s86, v252, 12
	v_readlane_b32 s87, v252, 13
	s_mov_b64 s[40:41], s[86:87]
	s_waitcnt lgkmcnt(0)
	s_add_u32 s16, s12, s44
	s_addc_u32 s17, s13, s45
	s_mov_b64 s[12:13], s[48:49]
	s_mov_b32 s21, s79
	s_load_dwordx2 s[78:79], s[12:13], 0x68
	s_lshl_b64 s[12:13], s[46:47], 2
	v_lshlrev_b32_e32 v0, 5, v0
	v_mov_b32_e32 v11, v220
	v_and_b32_e32 v12, 0x7e0, v0
	s_waitcnt lgkmcnt(0)
	s_add_u32 s12, s78, s12
	s_addc_u32 s13, s79, s13
	s_add_u32 s84, s12, 0x2000
	s_addc_u32 s85, s13, 0
	s_mov_b64 s[12:13], s[48:49]
	s_load_dwordx2 s[90:91], s[12:13], 0x70
	s_mov_b64 s[12:13], s[86:87]
	s_mov_b64 s[48:49], s[86:87]
	v_add_u32_e32 v8, 0x9e00, v1
	v_lshlrev_b32_e32 v184, 2, v12
	v_lshlrev_b32_e32 v2, 4, v11
	v_and_b32_e32 v14, 0xffc0, v8
	v_bfe_u32 v10, v11, 3, 3
	v_lshl_add_u64 v[0:1], s[16:17], 0, v[184:185]
	v_and_b32_e32 v184, 0x70, v2
	v_lshl_add_u64 v[4:5], v[0:1], 0, v[184:185]
	v_or_b32_e32 v0, v10, v14
	v_lshlrev_b32_e32 v6, 13, v0
	v_mov_b32_e32 v7, v185
	v_lshl_add_u64 v[0:1], v[4:5], 0, v[6:7]
	global_load_dwordx4 v[132:135], v[0:1], off nt
	v_mul_u32_u24_e32 v7, 0x84, v10
	v_add3_u32 v7, s21, v184, v7
	v_or_b32_e32 v26, 8, v10
	v_add_u32_e32 v9, 0x420, v7
	v_or_b32_e32 v25, 16, v10
	v_or_b32_e32 v13, 24, v10
	v_readlane_b32 s86, v255, 25
	s_add_u32 s16, s78, s86
	s_movk_i32 s78, 0x7c0
	v_readlane_b32 s87, v255, 26
	s_addc_u32 s17, s79, s87
	v_and_b32_e32 v16, 31, v11
	v_and_or_b32 v17, v11, 32, v14
	v_and_b32_e32 v15, 63, v11
	v_or_b32_e32 v0, v26, v14
	v_lshlrev_b32_e32 v184, 13, v0
	v_lshl_add_u64 v[0:1], v[4:5], 0, v[184:185]
	global_load_dwordx4 v[136:139], v[0:1], off nt
	v_add_u32_e32 v0, 0x428, v7
	v_or_b32_e32 v0, v25, v14
	v_lshlrev_b32_e32 v184, 13, v0
	v_lshl_add_u64 v[0:1], v[4:5], 0, v[184:185]
	global_load_dwordx4 v[140:143], v[0:1], off nt
	v_add_u32_e32 v9, 0x840, v7
	v_add_u32_e32 v0, 0x848, v7
	v_or_b32_e32 v0, v13, v14
	v_lshlrev_b32_e32 v184, 13, v0
	v_lshl_add_u64 v[0:1], v[4:5], 0, v[184:185]
	global_load_dwordx4 v[144:147], v[0:1], off nt
	v_add_u32_e32 v9, 0xc60, v7
	v_or_b32_e32 v184, 0x40000, v6
	v_add_u32_e32 v0, 0xc68, v7
	v_lshl_add_u64 v[0:1], v[4:5], 0, v[184:185]
	global_load_dwordx4 v[148:151], v[0:1], off nt
	v_add_u32_e32 v9, 0x1080, v7
	v_or_b32_e32 v184, 0x50000, v6
	v_add_u32_e32 v0, 0x1088, v7
	v_lshl_add_u64 v[0:1], v[4:5], 0, v[184:185]
	global_load_dwordx4 v[152:155], v[0:1], off nt
	v_add_u32_e32 v9, 0x14a0, v7
	v_or_b32_e32 v184, 0x60000, v6
	v_add_u32_e32 v0, 0x14a8, v7
	v_lshl_add_u64 v[0:1], v[4:5], 0, v[184:185]
	global_load_dwordx4 v[156:159], v[0:1], off nt
	v_add_u32_e32 v9, 0x18c0, v7
	v_or_b32_e32 v184, 0x70000, v6
	v_add_u32_e32 v0, 0x18c8, v7
	v_lshl_add_u64 v[0:1], v[4:5], 0, v[184:185]
	global_load_dwordx4 v[160:163], v[0:1], off nt
	v_add_u32_e32 v4, 0x1ce0, v7
	v_add_u32_e32 v0, 0x1ce8, v7
	s_waitcnt vmcnt(0)
	v_add_u32_e32 v164, 0x0, v7
	ds_write2_b32 v164, v132, v133 offset1:1
	ds_write2_b32 v164, v134, v135 offset0:2 offset1:3
	v_add_u32_e32 v164, 0x420, v7
	ds_write2_b32 v164, v136, v137 offset1:1
	ds_write2_b32 v164, v138, v139 offset0:2 offset1:3
	v_add_u32_e32 v164, 0x840, v7
	ds_write2_b32 v164, v140, v141 offset1:1
	ds_write2_b32 v164, v142, v143 offset0:2 offset1:3
	v_add_u32_e32 v164, 0xc60, v7
	ds_write2_b32 v164, v144, v145 offset1:1
	ds_write2_b32 v164, v146, v147 offset0:2 offset1:3
	v_add_u32_e32 v164, 0x1080, v7
	ds_write2_b32 v164, v148, v149 offset1:1
	ds_write2_b32 v164, v150, v151 offset0:2 offset1:3
	v_add_u32_e32 v164, 0x14a0, v7
	ds_write2_b32 v164, v152, v153 offset1:1
	ds_write2_b32 v164, v154, v155 offset0:2 offset1:3
	v_add_u32_e32 v164, 0x18c0, v7
	ds_write2_b32 v164, v156, v157 offset1:1
	ds_write2_b32 v164, v158, v159 offset0:2 offset1:3
	v_add_u32_e32 v164, 0x1ce0, v7
	ds_write2_b32 v164, v160, v161 offset1:1
	ds_write2_b32 v164, v162, v163 offset0:2 offset1:3
	v_lshrrev_b32_e32 v0, 5, v11
	v_and_b32_e32 v0, 1, v0
	v_lshlrev_b16_e32 v0, 5, v0
	v_bitop3_b16 v0, v8, v0, s78 bitop3:0xec
	s_waitcnt lgkmcnt(0)
	v_lshlrev_b32_sdwa v184, v227, v0 dst_sel:DWORD dst_unused:UNUSED_PAD src0_sel:DWORD src1_sel:WORD_0
	v_bfe_u32 v0, v11, 5, 1
	v_lshl_add_u64 v[4:5], s[16:17], 0, v[184:185]
	s_waitcnt lgkmcnt(0)
	s_add_u32 s16, s90, s86
	v_mul_u32_u24_e32 v0, 0x1080, v0
	s_addc_u32 s17, s91, s87
	v_lshlrev_b32_e32 v184, 2, v17
	v_lshl_or_b32 v0, v16, 2, v0
	v_mov_b32_e32 v8, 0
	v_lshl_add_u64 v[6:7], s[16:17], 0, v[184:185]
	v_add_u32_e32 v27, s21, v0
	s_mov_b64 s[90:91], 0
	v_mov_b32_e32 v9, v8
	s_movk_i32 s16, 0x2000
	s_mov_b64 s[78:79], 0x2000

; #define LAS __attribute__((address_space(3)))
; #define LDS_WAIT() asm volatile("s_waitcnt lgkmcnt(0)" ::: "memory")
; __device__ __forceinline__ unsigned pk2(float lo, float hi) { return f2bf(lo) | (f2bf(hi) << 16); }
; template <class Map>
; __device__ __forceinline__ void conv_item(const Frame& F, int it, const float* W, int K, int N, bf16_t* WT, const float* gk, int gmask, float gmul, const float* bk, i64* cs, i64* bw, Map map) {
;     ...
;         const int kb = it / nblk, nb = it % nblk, k0 = 64 * kb, n0 = 32 * nb, v0 = map(n0);
; #pragma unroll
;         for (int i = 0; i < 8; ++i) { const int kk = 8 * i + (lane >> 3), c4 = (lane & 7) * 4;
;             const f32x4 w4 = __builtin_nontemporal_load((const f32x4*)(W + (size_t)(k0 + kk) * N + n0 + c4)); LAS float* d = scr + kk * 33 + c4; d[0] = w4[0]; d[1] = w4[1]; d[2] = w4[2]; d[3] = w4[3]; }
;         LDS_WAIT(); asm volatile("" ::: "memory");
;     ...
;         const int c = lane & 7; float gl[8];
; #pragma unroll
;         for (int i = 0; i < 8; ++i) gl[i] = gk ? gk[(k0 + 8 * c + i) & gmask] * gmul : 1.0f;
; #pragma unroll
;         for (int j = 0; j < 4; ++j) { const int n = (lane >> 3) + 8 * j; const LAS float* s = scr + (8 * c) * 33 + n;
;             u32x4 o; o.x = pk2(s[0 * 33] * gl[0], s[1 * 33] * gl[1]); o.y = pk2(s[2 * 33] * gl[2], s[3 * 33] * gl[3]); o.z = pk2(s[4 * 33] * gl[4], s[5 * 33] * gl[5]); o.w = pk2(s[6 * 33] * gl[6], s[7 * 33] * gl[7]);
.LBB0_858:
	s_andn2_saveexec_b64 s[38:39], s[38:39]
	s_cbranch_execz .LBB0_860
	v_readlane_b32 s12, v252, 14
	v_readlane_b32 s13, v252, 15
	s_load_dwordx2 s[12:13], s[12:13], 0x80
	s_mul_i32 s16, s20, 0x2c00000
	v_lshlrev_b32_e32 v0, 5, v0
	v_add_u32_e32 v1, 0xb400, v1
	v_mov_b32_e32 v14, v220
	s_waitcnt lgkmcnt(0)
	s_add_u32 s16, s12, s16
	s_mul_hi_i32 s12, s20, 0x2c00000
	s_addc_u32 s17, s13, s12
	v_readlane_b32 s12, v252, 12
	v_readlane_b32 s13, v252, 13
	v_and_b32_e32 v2, 0x7e0, v0
	v_and_b32_e32 v15, 0xffc0, v1
	v_bfe_u32 v7, v14, 3, 3
	v_lshlrev_b32_e32 v184, 2, v2
	v_lshlrev_b32_e32 v3, 4, v14
	v_lshl_add_u64 v[0:1], s[16:17], 0, v[184:185]
	v_and_b32_e32 v184, 0x70, v3
	v_or_b32_e32 v3, v7, v15
	v_lshl_add_u64 v[0:1], v[0:1], 0, v[184:185]
	v_lshlrev_b32_e32 v12, 13, v3
	v_mov_b32_e32 v13, v185
	v_lshl_add_u64 v[4:5], v[0:1], 0, v[12:13]
	global_load_dwordx4 v[132:135], v[4:5], off nt
	v_mul_u32_u24_e32 v3, 0x84, v7
	v_or_b32_e32 v6, 8, v7
	v_add3_u32 v13, s79, v184, v3
	v_or_b32_e32 v3, v6, v15
	v_lshlrev_b32_e32 v184, 13, v3
	v_lshl_add_u64 v[4:5], v[0:1], 0, v[184:185]
	v_add_u32_e32 v3, 0x420, v13
	v_or_b32_e32 v6, v6, v2
	v_mul_u32_u24_e32 v6, 0x1600, v6
	global_load_dwordx4 v[136:139], v[4:5], off nt
	v_or_b32_e32 v4, 16, v7
	v_add_u32_e32 v3, 0x428, v13
	v_or_b32_e32 v3, v4, v15
	v_lshlrev_b32_e32 v184, 13, v3
	v_lshl_add_u64 v[8:9], v[0:1], 0, v[184:185]
	global_load_dwordx4 v[140:143], v[8:9], off nt
	v_add_u32_e32 v3, 0x840, v13
	v_or_b32_e32 v4, v4, v2
	v_mul_u32_u24_e32 v4, 0x1600, v4
	v_add_u32_e32 v3, 0x848, v13
	v_or_b32_e32 v3, 24, v7
	v_or_b32_e32 v5, v3, v15
	v_lshlrev_b32_e32 v184, 13, v5
	v_lshl_add_u64 v[8:9], v[0:1], 0, v[184:185]
	global_load_dwordx4 v[144:147], v[8:9], off nt
	v_add_u32_e32 v5, 0xc60, v13
	v_or_b32_e32 v184, 0x40000, v12
	v_add_u32_e32 v5, 0xc68, v13
	v_lshl_add_u64 v[8:9], v[0:1], 0, v[184:185]
	global_load_dwordx4 v[148:151], v[8:9], off nt
	v_add_u32_e32 v5, 0x1080, v13
	v_or_b32_e32 v184, 0x50000, v12
	v_add_u32_e32 v5, 0x1088, v13
	v_lshl_add_u64 v[8:9], v[0:1], 0, v[184:185]
	global_load_dwordx4 v[152:155], v[8:9], off nt
	v_add_u32_e32 v5, 0x14a0, v13
	v_or_b32_e32 v184, 0x60000, v12
	v_add_u32_e32 v5, 0x14a8, v13
	v_lshl_add_u64 v[8:9], v[0:1], 0, v[184:185]
	global_load_dwordx4 v[156:159], v[8:9], off nt
	v_add_u32_e32 v5, 0x18c0, v13
	v_or_b32_e32 v184, 0x70000, v12
	v_lshl_add_u64 v[0:1], v[0:1], 0, v[184:185]
	v_lshlrev_b32_e32 v184, 1, v15
	v_add_u32_e32 v5, 0x18c8, v13
	global_load_dwordx4 v[160:163], v[0:1], off nt
	v_add_u32_e32 v0, 0x1ce0, v13
	v_and_b32_e32 v5, 7, v14
	v_add_u32_e32 v0, 0x1ce8, v13
	s_waitcnt vmcnt(0)
	v_add_u32_e32 v164, 0x0, v13
	ds_write2_b32 v164, v132, v133 offset1:1
	ds_write2_b32 v164, v134, v135 offset0:2 offset1:3
	v_add_u32_e32 v164, 0x420, v13
	ds_write2_b32 v164, v136, v137 offset1:1
	ds_write2_b32 v164, v138, v139 offset0:2 offset1:3
	v_add_u32_e32 v164, 0x840, v13
	ds_write2_b32 v164, v140, v141 offset1:1
	ds_write2_b32 v164, v142, v143 offset0:2 offset1:3
	v_add_u32_e32 v164, 0xc60, v13
	ds_write2_b32 v164, v144, v145 offset1:1
	ds_write2_b32 v164, v146, v147 offset0:2 offset1:3
	v_add_u32_e32 v164, 0x1080, v13
	ds_write2_b32 v164, v148, v149 offset1:1
	ds_write2_b32 v164, v150, v151 offset0:2 offset1:3
	v_add_u32_e32 v164, 0x14a0, v13
	ds_write2_b32 v164, v152, v153 offset1:1
	ds_write2_b32 v164, v154, v155 offset0:2 offset1:3
	v_add_u32_e32 v164, 0x18c0, v13
	ds_write2_b32 v164, v156, v157 offset1:1
	ds_write2_b32 v164, v158, v159 offset0:2 offset1:3
	v_add_u32_e32 v164, 0x1ce0, v13
	ds_write2_b32 v164, v160, v161 offset1:1
	ds_write2_b32 v164, v162, v163 offset0:2 offset1:3
	s_waitcnt lgkmcnt(0)
	v_mul_u32_u24_e32 v8, 0x420, v5
	v_lshl_add_u64 v[0:1], s[12:13], 0, v[184:185]
	v_lshlrev_b32_e32 v184, 4, v5
	v_lshlrev_b32_e32 v5, 2, v7
	v_add3_u32 v5, s79, v8, v5
	ds_read_b32 v8, v5
	ds_read_b32 v9, v5 offset:132
	v_or_b32_e32 v7, v7, v2
	v_lshl_add_u64 v[0:1], v[0:1], 0, v[184:185]
	s_mov_b64 s[12:13], 0x3e900000
	s_waitcnt lgkmcnt(1)
	v_bfe_u32 v10, v8, 16, 1
	v_add3_u32 v8, v8, v10, s73
	s_waitcnt lgkmcnt(0)
	v_bfe_u32 v10, v9, 16, 1
	v_lshrrev_b32_e32 v8, 16, v8
	v_add3_u32 v9, v9, v10, s73
	v_and_or_b32 v8, v9, s72, v8
	ds_read_b32 v9, v5 offset:264
	ds_read_b32 v10, v5 offset:396
	v_mul_u32_u24_e32 v7, 0x1600, v7
	v_lshl_add_u64 v[0:1], v[0:1], 0, s[12:13]
	v_lshlrev_b32_e32 v184, 1, v7
	s_waitcnt lgkmcnt(1)
; #define LAS __attribute__((address_space(3)))
; #define LDS_WAIT() asm volatile("s_waitcnt lgkmcnt(0)" ::: "memory")
; __device__ __forceinline__ unsigned pk2(float lo, float hi) { return f2bf(lo) | (f2bf(hi) << 16); }
; template <class Map>
; __device__ __forceinline__ void conv_item(const Frame& F, int it, const float* W, int K, int N, bf16_t* WT, const float* gk, int gmask, float gmul, const float* bk, i64* cs, i64* bw, Map map) {
;     ...
;         for (int j = 0; j < 4; ++j) { const int n = (lane >> 3) + 8 * j; const LAS float* s = scr + (8 * c) * 33 + n;
;             u32x4 o; o.x = pk2(s[0 * 33] * gl[0], s[1 * 33] * gl[1]); o.y = pk2(s[2 * 33] * gl[2], s[3 * 33] * gl[3]); o.z = pk2(s[4 * 33] * gl[4], s[5 * 33] * gl[5]); o.w = pk2(s[6 * 33] * gl[6], s[7 * 33] * gl[7]);
;             __builtin_nontemporal_store(o, (u32x4*)(WT + (size_t)(v0 + n) * K + k0 + 8 * c)); }
;         LDS_WAIT(); asm volatile("" ::: "memory");
	v_bfe_u32 v11, v9, 16, 1
	v_add3_u32 v9, v9, v11, s73
	s_waitcnt lgkmcnt(0)
	v_bfe_u32 v11, v10, 16, 1
	v_lshrrev_b32_e32 v9, 16, v9
	v_add3_u32 v10, v10, v11, s73
	v_and_or_b32 v9, v10, s72, v9
	ds_read_b32 v10, v5 offset:528
	ds_read_b32 v11, v5 offset:660
	v_or_b32_e32 v2, v3, v2
	v_mul_u32_u24_e32 v2, 0x1600, v2
	s_waitcnt lgkmcnt(1)
	v_bfe_u32 v12, v10, 16, 1
	v_add3_u32 v10, v10, v12, s73
	s_waitcnt lgkmcnt(0)
	v_bfe_u32 v12, v11, 16, 1
	v_lshrrev_b32_e32 v10, 16, v10
	v_add3_u32 v11, v11, v12, s73
	v_and_or_b32 v10, v11, s72, v10
	ds_read_b32 v11, v5 offset:792
	ds_read_b32 v12, v5 offset:924
	s_waitcnt lgkmcnt(1)
	v_bfe_u32 v13, v11, 16, 1
	v_add3_u32 v11, v11, v13, s73
	s_waitcnt lgkmcnt(0)
	v_bfe_u32 v13, v12, 16, 1
	v_lshrrev_b32_e32 v11, 16, v11
	v_add3_u32 v12, v12, v13, s73
	v_and_or_b32 v11, v12, s72, v11
	v_lshl_add_u64 v[12:13], v[0:1], 0, v[184:185]
	flat_store_dwordx4 v[12:13], v[8:11] nt
	ds_read_b32 v7, v5 offset:32
	ds_read_b32 v8, v5 offset:164
	v_lshlrev_b32_e32 v184, 1, v6
	s_waitcnt lgkmcnt(0)
	v_bfe_u32 v9, v7, 16, 1
	v_add3_u32 v7, v7, v9, s73
	v_bfe_u32 v9, v8, 16, 1
	v_lshrrev_b32_e32 v7, 16, v7
	v_add3_u32 v8, v8, v9, s73
	v_and_or_b32 v8, v8, s72, v7
	ds_read_b32 v7, v5 offset:296
	ds_read_b32 v9, v5 offset:428
	s_waitcnt lgkmcnt(0)
	v_bfe_u32 v10, v7, 16, 1
	v_add3_u32 v7, v7, v10, s73
	v_bfe_u32 v10, v9, 16, 1
	v_lshrrev_b32_e32 v7, 16, v7
	v_add3_u32 v9, v9, v10, s73
	v_and_or_b32 v9, v9, s72, v7
	ds_read_b32 v7, v5 offset:560
	ds_read_b32 v10, v5 offset:692
	s_waitcnt lgkmcnt(0)
	v_bfe_u32 v11, v7, 16, 1
	v_add3_u32 v7, v7, v11, s73
	v_bfe_u32 v11, v10, 16, 1
	v_lshrrev_b32_e32 v7, 16, v7
	v_add3_u32 v10, v10, v11, s73
	v_and_or_b32 v10, v10, s72, v7
	ds_read_b32 v7, v5 offset:824
	ds_read_b32 v11, v5 offset:956
	s_waitcnt lgkmcnt(0)
	v_bfe_u32 v12, v7, 16, 1
	v_add3_u32 v7, v7, v12, s73
	v_bfe_u32 v12, v11, 16, 1
	v_lshrrev_b32_e32 v7, 16, v7
	v_add3_u32 v11, v11, v12, s73
	v_and_or_b32 v11, v11, s72, v7
	v_lshl_add_u64 v[6:7], v[0:1], 0, v[184:185]
	flat_store_dwordx4 v[6:7], v[8:11] nt
	ds_read_b32 v6, v5 offset:64
	ds_read_b32 v7, v5 offset:196
	v_lshlrev_b32_e32 v184, 1, v4
	s_waitcnt lgkmcnt(0)
	v_bfe_u32 v8, v6, 16, 1
	v_add3_u32 v6, v6, v8, s73
	v_bfe_u32 v8, v7, 16, 1
	v_lshrrev_b32_e32 v6, 16, v6
	v_add3_u32 v7, v7, v8, s73
	v_and_or_b32 v6, v7, s72, v6
	ds_read_b32 v7, v5 offset:328
	ds_read_b32 v8, v5 offset:460
	s_waitcnt lgkmcnt(0)
	v_bfe_u32 v9, v7, 16, 1
	v_add3_u32 v7, v7, v9, s73
	v_bfe_u32 v9, v8, 16, 1
	v_lshrrev_b32_e32 v7, 16, v7
	v_add3_u32 v8, v8, v9, s73
	v_and_or_b32 v7, v8, s72, v7
	ds_read_b32 v8, v5 offset:592
	ds_read_b32 v9, v5 offset:724
	s_waitcnt lgkmcnt(0)
	v_bfe_u32 v10, v8, 16, 1
	v_add3_u32 v8, v8, v10, s73
	v_bfe_u32 v10, v9, 16, 1
	v_lshrrev_b32_e32 v8, 16, v8
	v_add3_u32 v9, v9, v10, s73
	v_and_or_b32 v8, v9, s72, v8
	ds_read_b32 v9, v5 offset:856
	ds_read_b32 v10, v5 offset:988
	s_waitcnt lgkmcnt(0)
	v_bfe_u32 v11, v9, 16, 1
	v_add3_u32 v9, v9, v11, s73
	v_bfe_u32 v11, v10, 16, 1
	v_lshrrev_b32_e32 v9, 16, v9
	v_add3_u32 v10, v10, v11, s73
	v_and_or_b32 v9, v10, s72, v9
	v_lshl_add_u64 v[10:11], v[0:1], 0, v[184:185]
	flat_store_dwordx4 v[10:11], v[6:9] nt
	ds_read_b32 v4, v5 offset:96
	ds_read_b32 v6, v5 offset:228
	v_lshlrev_b32_e32 v184, 1, v2
	v_lshl_add_u64 v[0:1], v[0:1], 0, v[184:185]
	s_waitcnt lgkmcnt(0)
	v_bfe_u32 v7, v4, 16, 1
	v_add3_u32 v4, v4, v7, s73
	v_bfe_u32 v7, v6, 16, 1
	v_lshrrev_b32_e32 v4, 16, v4
	v_add3_u32 v6, v6, v7, s73
	v_and_or_b32 v6, v6, s72, v4
	ds_read_b32 v4, v5 offset:360
	ds_read_b32 v7, v5 offset:492
	s_waitcnt lgkmcnt(0)
	v_bfe_u32 v8, v4, 16, 1
	v_add3_u32 v4, v4, v8, s73
	v_bfe_u32 v8, v7, 16, 1
	v_lshrrev_b32_e32 v4, 16, v4
	v_add3_u32 v7, v7, v8, s73
	v_and_or_b32 v7, v7, s72, v4
	ds_read_b32 v4, v5 offset:624
	ds_read_b32 v8, v5 offset:756
	s_waitcnt lgkmcnt(0)
	v_bfe_u32 v9, v4, 16, 1
	v_add3_u32 v4, v4, v9, s73
	v_bfe_u32 v9, v8, 16, 1
	v_lshrrev_b32_e32 v4, 16, v4
	v_add3_u32 v8, v8, v9, s73
	v_and_or_b32 v8, v8, s72, v4
	ds_read_b32 v4, v5 offset:888
	ds_read_b32 v5, v5 offset:1020
	s_waitcnt lgkmcnt(0)
	v_bfe_u32 v9, v4, 16, 1
	v_add3_u32 v4, v4, v9, s73
	v_bfe_u32 v9, v5, 16, 1
	v_lshrrev_b32_e32 v4, 16, v4
	v_add3_u32 v5, v5, v9, s73
	v_and_or_b32 v9, v5, s72, v4
	flat_store_dwordx4 v[0:1], v[6:9] nt
	s_waitcnt lgkmcnt(0)

; #define LAS __attribute__((address_space(3)))
; #define LDS_WAIT() asm volatile("s_waitcnt lgkmcnt(0)" ::: "memory")
; __device__ __forceinline__ float bf_round(float f) { return __uint_as_float(f2bf(f) << 16); }
; template <class Map>
; __device__ __forceinline__ void conv_item(const Frame& F, int it, const float* W, int K, int N, bf16_t* WT, const float* gk, int gmask, float gmul, const float* bk, i64* cs, i64* bw, Map map) {
;     ...
;         const int kb = it / nblk, nb = it % nblk, k0 = 64 * kb, n0 = 32 * nb, v0 = map(n0);
; #pragma unroll
;         for (int i = 0; i < 8; ++i) { const int kk = 8 * i + (lane >> 3), c4 = (lane & 7) * 4;
;             const f32x4 w4 = __builtin_nontemporal_load((const f32x4*)(W + (size_t)(k0 + kk) * N + n0 + c4)); LAS float* d = scr + kk * 33 + c4; d[0] = w4[0]; d[1] = w4[1]; d[2] = w4[2]; d[3] = w4[3]; }
;         LDS_WAIT(); asm volatile("" ::: "memory");
;         if (bk) {
;             const int n = lane & 31, kh = lane >> 5; float sb = 0.f, sc = 0.f;
; #pragma unroll 8
;             for (int j = 0; j < 32; ++j) { const int kk = kh * 32 + j; const float w = scr[kk * 33 + n]; sb += bk[k0 + kk] * w; sc += bf_round(gk[(k0 + kk) & gmask] * gmul * w); }
.LBB0_861:
	s_andn2_saveexec_b64 s[24:25], s[24:25]
	s_cbranch_execz .LBB0_885
	v_readlane_b32 s38, v252, 14
	v_readlane_b32 s39, v252, 15
	s_mov_b64 s[12:13], s[38:39]
	s_load_dwordx2 s[12:13], s[12:13], 0x78
	s_mul_i32 s16, s20, 0x5800000
	v_readlane_b32 s90, v252, 12
	v_readlane_b32 s91, v252, 13
	s_mov_b64 s[82:83], s[90:91]
	s_waitcnt lgkmcnt(0)
	s_add_u32 s78, s12, s16
	s_mul_hi_i32 s12, s20, 0x5800000
	s_addc_u32 s79, s13, s12
	s_mov_b64 s[12:13], s[38:39]
	s_load_dwordx2 s[86:87], s[12:13], 0x68
	s_mov_b32 s16, 0xba2f
	v_mul_u32_u24_sdwa v1, v0, s16 dst_sel:DWORD dst_unused:UNUSED_PAD src0_sel:WORD_0 src1_sel:DWORD
	s_movk_i32 s16, 0x160
	s_lshl_b64 s[12:13], s[46:47], 2
	v_mul_lo_u16_sdwa v2, v1, s16 dst_sel:DWORD dst_unused:UNUSED_PAD src0_sel:BYTE_3 src1_sel:DWORD
	s_waitcnt lgkmcnt(0)
	s_add_u32 s84, s86, s12
	v_sub_u16_e32 v2, v0, v2
	v_mov_b32_e32 v4, 6
	s_movk_i32 s16, 0xaf
	s_addc_u32 s85, s87, s13
	s_mov_b64 s[12:13], s[38:39]
	v_lshlrev_b16_sdwa v25, v4, v1 dst_sel:DWORD dst_unused:UNUSED_PAD src0_sel:DWORD src1_sel:BYTE_3
	v_lshlrev_b16_e32 v1, 5, v2
	v_cmp_lt_u16_e32 vcc, s16, v2
	s_movk_i32 s16, 0xb0
	s_mov_b64 s[48:49], s[90:91]
	v_mov_b32_e32 v3, v220
	v_add_u16_e32 v4, 0xea00, v1
	v_cmp_gt_u16_e64 s[38:39], s16, v2
	s_load_dwordx2 s[12:13], s[12:13], 0x70
	v_lshlrev_b32_e32 v184, 2, v1
	v_cndmask_b32_e64 v2, v4, v1, s[38:39]
	v_mov_b32_e32 v4, 1
	v_bfe_u32 v17, v3, 3, 3
	v_lshlrev_b32_e32 v1, 4, v3
	v_lshlrev_b32_sdwa v10, v4, sext(v2) dst_sel:DWORD dst_unused:UNUSED_PAD src0_sel:DWORD src1_sel:WORD_0
	v_lshl_add_u64 v[4:5], s[78:79], 0, v[184:185]
	v_and_b32_e32 v184, 0x70, v1
	v_or_b32_e32 v1, v17, v25
	v_lshl_add_u64 v[8:9], v[4:5], 0, v[184:185]
	v_mul_u32_u24_e32 v4, 0xb000, v1
	v_mov_b32_e32 v5, v185
	v_lshl_add_u64 v[4:5], v[8:9], 0, v[4:5]
	global_load_dwordx4 v[132:135], v[4:5], off nt
	v_readlane_b32 s79, v255, 17
	v_mul_u32_u24_e32 v12, 0x84, v17
	v_or_b32_e32 v16, 8, v17
	v_add3_u32 v12, s79, v184, v12
	v_add_u32_e32 v13, 0x420, v12
	v_or_b32_e32 v15, 16, v17
	v_or_b32_e32 v14, 24, v17
	s_movk_i32 s16, 0x60
	v_cndmask_b32_e32 v11, 0, v228, vcc
	v_and_b32_sdwa v2, sext(v2), s16 dst_sel:DWORD dst_unused:UNUSED_PAD src0_sel:WORD_0 src1_sel:DWORD
	s_waitcnt lgkmcnt(0)
	s_cmp_eq_u64 s[12:13], 0
	v_or_b32_e32 v4, v16, v25
	v_mul_u32_u24_e32 v184, 0xb000, v4
	v_lshl_add_u64 v[4:5], v[8:9], 0, v[184:185]
	global_load_dwordx4 v[136:139], v[4:5], off nt
	v_add_u32_e32 v4, 0x428, v12
	v_or_b32_e32 v4, v15, v25
	v_mul_u32_u24_e32 v184, 0xb000, v4
	v_lshl_add_u64 v[4:5], v[8:9], 0, v[184:185]
	global_load_dwordx4 v[140:143], v[4:5], off nt
	v_add_u32_e32 v13, 0x840, v12
	v_add_u32_e32 v4, 0x848, v12
	v_or_b32_e32 v4, v14, v25
	v_mul_u32_u24_e32 v184, 0xb000, v4
	v_lshl_add_u64 v[4:5], v[8:9], 0, v[184:185]
	global_load_dwordx4 v[144:147], v[4:5], off nt
	v_add_u32_e32 v13, 0xc60, v12
	v_add_u32_e32 v4, 0xc68, v12
	v_or_b32_e32 v4, 32, v1
	v_mul_u32_u24_e32 v184, 0xb000, v4
	v_lshl_add_u64 v[4:5], v[8:9], 0, v[184:185]
	global_load_dwordx4 v[148:151], v[4:5], off nt
	v_add_u32_e32 v13, 0x1080, v12
	v_add_u32_e32 v4, 0x1088, v12
	v_or_b32_e32 v4, 40, v1
	v_mul_u32_u24_e32 v184, 0xb000, v4
	v_lshl_add_u64 v[4:5], v[8:9], 0, v[184:185]
	global_load_dwordx4 v[152:155], v[4:5], off nt
	v_add_u32_e32 v13, 0x14a0, v12
	v_add_u32_e32 v4, 0x14a8, v12
	v_or_b32_e32 v4, 48, v1
	v_mul_u32_u24_e32 v184, 0xb000, v4
	v_lshl_add_u64 v[4:5], v[8:9], 0, v[184:185]
	global_load_dwordx4 v[156:159], v[4:5], off nt
	v_add_u32_e32 v13, 0x18c0, v12
	v_or_b32_e32 v1, 56, v1
	v_mul_u32_u24_e32 v184, 0xb000, v1
	v_add_u32_e32 v1, 0x1ce0, v12
	v_add_u32_e32 v4, 0x18c8, v12
	v_lshl_add_u64 v[4:5], v[8:9], 0, v[184:185]
	global_load_dwordx4 v[160:163], v[4:5], off nt
	v_add_u32_e32 v1, 0x1ce8, v12
	s_waitcnt vmcnt(0)
	v_add_u32_e32 v164, 0x0, v12
	ds_write2_b32 v164, v132, v133 offset1:1
	ds_write2_b32 v164, v134, v135 offset0:2 offset1:3
	v_add_u32_e32 v164, 0x420, v12
	ds_write2_b32 v164, v136, v137 offset1:1
	ds_write2_b32 v164, v138, v139 offset0:2 offset1:3
	v_add_u32_e32 v164, 0x840, v12
	ds_write2_b32 v164, v140, v141 offset1:1
	ds_write2_b32 v164, v142, v143 offset0:2 offset1:3
	v_add_u32_e32 v164, 0xc60, v12
	ds_write2_b32 v164, v144, v145 offset1:1
	ds_write2_b32 v164, v146, v147 offset0:2 offset1:3
	v_add_u32_e32 v164, 0x1080, v12
	ds_write2_b32 v164, v148, v149 offset1:1
	ds_write2_b32 v164, v150, v151 offset0:2 offset1:3
	v_add_u32_e32 v164, 0x14a0, v12
	ds_write2_b32 v164, v152, v153 offset1:1
	ds_write2_b32 v164, v154, v155 offset0:2 offset1:3
	v_add_u32_e32 v164, 0x18c0, v12
	ds_write2_b32 v164, v156, v157 offset1:1
	ds_write2_b32 v164, v158, v159 offset0:2 offset1:3
	v_add_u32_e32 v164, 0x1ce0, v12
	ds_write2_b32 v164, v160, v161 offset1:1
	ds_write2_b32 v164, v162, v163 offset0:2 offset1:3
	s_waitcnt lgkmcnt(0)
	v_and_b32_e32 v1, 0xffffff00, v10
	v_or3_b32 v4, v2, v11, v1
	s_cbranch_scc1 .LBB0_868
	v_and_b32_e32 v1, 32, v3
	v_readlane_b32 s38, v255, 25
	v_readlane_b32 s39, v255, 26
	s_add_u32 s12, s12, s38
	v_add_u32_e32 v27, v25, v1
	s_mov_b32 s16, 0xba2e8c
	v_lshrrev_b32_e32 v1, 5, v3
	v_bfe_u32 v2, v3, 5, 1
	s_addc_u32 s13, s13, s39
	v_lshlrev_b32_e32 v184, 2, v27
	v_mul_hi_u32_u24_sdwa v0, v0, s16 dst_sel:DWORD dst_unused:UNUSED_PAD src0_sel:WORD_0 src1_sel:DWORD
	v_lshlrev_b32_e32 v8, 7, v2
	v_and_b32_e32 v1, 1, v1
	v_lshl_add_u64 v[6:7], s[12:13], 0, v[184:185]
	v_lshl_or_b32 v184, v0, 8, v8
	v_lshlrev_b16_e32 v0, 6, v0
	v_lshlrev_b16_e32 v1, 5, v1
	v_or_b32_e32 v0, v0, v1
	v_and_b32_e32 v0, 0x7e0, v0
	v_and_b32_e32 v26, 31, v3
	v_lshl_add_u64 v[8:9], s[12:13], 0, v[184:185]
	v_lshlrev_b32_e32 v184, 2, v0
	v_mul_u32_u24_e32 v0, 0x1080, v2
	s_add_u32 s12, s86, s38
	v_lshl_or_b32 v0, v26, 2, v0
	s_addc_u32 s13, s87, s39
	v_add_u32_e32 v28, s79, v0
	v_mov_b32_e32 v0, 0
	v_and_b32_e32 v5, 63, v3
	v_lshl_add_u64 v[10:11], s[12:13], 0, v[184:185]
	s_mov_b64 s[12:13], 0
	v_mov_b32_e32 v1, v0

; #define LAS __attribute__((address_space(3)))
; #define LDS_WAIT() asm volatile("s_waitcnt lgkmcnt(0)" ::: "memory")
; template <class Map>
; __device__ __forceinline__ void conv_item(const Frame& F, int it, const float* W, int K, int N, bf16_t* WT, const float* gk, int gmask, float gmul, const float* bk, i64* cs, i64* bw, Map map) {
;     ...
;         const int kb = it / nblk, nb = it % nblk, k0 = 64 * kb, n0 = 32 * nb, v0 = map(n0);
; #pragma unroll
;         for (int i = 0; i < 8; ++i) { const int kk = 8 * i + (lane >> 3), c4 = (lane & 7) * 4;
;             const f32x4 w4 = __builtin_nontemporal_load((const f32x4*)(W + (size_t)(k0 + kk) * N + n0 + c4)); LAS float* d = scr + kk * 33 + c4; d[0] = w4[0]; d[1] = w4[1]; d[2] = w4[2]; d[3] = w4[3]; }
;         LDS_WAIT(); asm volatile("" ::: "memory");
;     ...
;         const int c = lane & 7; float gl[8];
; #pragma unroll
;         for (int i = 0; i < 8; ++i) gl[i] = gk ? gk[(k0 + 8 * c + i) & gmask] * gmul : 1.0f;
.LBB0_886:
	s_andn2_saveexec_b64 s[12:13], s[26:27]
	s_cbranch_execz .LBB0_904
	v_readlane_b32 s26, v252, 14
	v_readlane_b32 s27, v252, 15
	s_mov_b64 s[16:17], s[26:27]
	s_load_dwordx2 s[16:17], s[16:17], 0x58
	v_add_u32_e32 v0, 0xe800, v1
	v_readlane_b32 s24, v252, 12
	v_and_b32_e32 v13, 0xffc0, v0
	v_lshlrev_b32_e32 v0, 5, v1
	s_waitcnt lgkmcnt(0)
	s_add_u32 s16, s16, s36
	v_readlane_b32 s25, v252, 13
	v_mov_b32_e32 v14, v220
	v_and_b32_e32 v8, 0x7e0, v0
	s_addc_u32 s17, s17, s37
	s_load_dwordx2 s[38:39], s[26:27], 0x50
	v_lshlrev_b32_e32 v184, 2, v8
	v_lshlrev_b32_e32 v2, 4, v14
	v_bfe_u32 v12, v14, 3, 3
	v_lshl_add_u64 v[0:1], s[16:17], 0, v[184:185]
	v_and_b32_e32 v184, 0x70, v2
	v_lshl_add_u64 v[4:5], v[0:1], 0, v[184:185]
	v_or_b32_e32 v0, v12, v13
	v_lshlrev_b32_e32 v6, 13, v0
	v_mov_b32_e32 v7, v185
	v_lshl_add_u64 v[0:1], v[4:5], 0, v[6:7]
	global_load_dwordx4 v[132:135], v[0:1], off nt
	v_mul_u32_u24_e32 v7, 0x84, v12
	v_add3_u32 v7, s79, v184, v7
	v_or_b32_e32 v11, 8, v12
	v_add_u32_e32 v9, 0x420, v7
	v_or_b32_e32 v10, 16, v12
	v_add_u32_e32 v15, 0xc60, v7
	v_and_b32_e32 v14, 7, v14
	s_waitcnt lgkmcnt(0)
	s_add_u32 s26, s38, s62
	s_addc_u32 s27, s39, s63
	s_cmp_lg_u64 s[38:39], 0
	s_cselect_b64 s[48:49], -1, 0
	s_cmp_eq_u64 s[38:39], 0
	v_or_b32_e32 v0, v11, v13
	v_lshlrev_b32_e32 v184, 13, v0
	v_lshl_add_u64 v[0:1], v[4:5], 0, v[184:185]
	global_load_dwordx4 v[136:139], v[0:1], off nt
	v_add_u32_e32 v0, 0x428, v7
	v_or_b32_e32 v0, v10, v13
	v_lshlrev_b32_e32 v184, 13, v0
	v_lshl_add_u64 v[0:1], v[4:5], 0, v[184:185]
	global_load_dwordx4 v[140:143], v[0:1], off nt
	v_add_u32_e32 v9, 0x840, v7
	v_add_u32_e32 v0, 0x848, v7
	v_or_b32_e32 v9, 24, v12
	v_or_b32_e32 v0, v9, v13
	v_lshlrev_b32_e32 v184, 13, v0
	v_lshl_add_u64 v[0:1], v[4:5], 0, v[184:185]
	global_load_dwordx4 v[144:147], v[0:1], off nt
	v_or_b32_e32 v184, 0x40000, v6
	v_add_u32_e32 v0, 0xc68, v7
	v_lshl_add_u64 v[0:1], v[4:5], 0, v[184:185]
	global_load_dwordx4 v[148:151], v[0:1], off nt
	v_add_u32_e32 v15, 0x1080, v7
	v_or_b32_e32 v184, 0x50000, v6
	v_add_u32_e32 v0, 0x1088, v7
	v_lshl_add_u64 v[0:1], v[4:5], 0, v[184:185]
	global_load_dwordx4 v[152:155], v[0:1], off nt
	v_add_u32_e32 v15, 0x14a0, v7
	v_or_b32_e32 v184, 0x60000, v6
	v_add_u32_e32 v0, 0x14a8, v7
	v_lshl_add_u64 v[0:1], v[4:5], 0, v[184:185]
	global_load_dwordx4 v[156:159], v[0:1], off nt
	v_add_u32_e32 v15, 0x18c0, v7
	v_or_b32_e32 v184, 0x70000, v6
	v_add_u32_e32 v0, 0x18c8, v7
	v_lshl_add_u64 v[0:1], v[4:5], 0, v[184:185]
	global_load_dwordx4 v[160:163], v[0:1], off nt
	v_add_u32_e32 v4, 0x1ce0, v7
	v_lshlrev_b32_e32 v15, 3, v14
	v_add_u32_e32 v0, 0x1ce8, v7
	s_waitcnt vmcnt(0)
	v_add_u32_e32 v164, 0x0, v7
	ds_write2_b32 v164, v132, v133 offset1:1
	ds_write2_b32 v164, v134, v135 offset0:2 offset1:3
	v_add_u32_e32 v164, 0x420, v7
	ds_write2_b32 v164, v136, v137 offset1:1
	ds_write2_b32 v164, v138, v139 offset0:2 offset1:3
	v_add_u32_e32 v164, 0x840, v7
	ds_write2_b32 v164, v140, v141 offset1:1
	ds_write2_b32 v164, v142, v143 offset0:2 offset1:3
	v_add_u32_e32 v164, 0xc60, v7
	ds_write2_b32 v164, v144, v145 offset1:1
	ds_write2_b32 v164, v146, v147 offset0:2 offset1:3
	v_add_u32_e32 v164, 0x1080, v7
	ds_write2_b32 v164, v148, v149 offset1:1
	ds_write2_b32 v164, v150, v151 offset0:2 offset1:3
	v_add_u32_e32 v164, 0x14a0, v7
	ds_write2_b32 v164, v152, v153 offset1:1
	ds_write2_b32 v164, v154, v155 offset0:2 offset1:3
	v_add_u32_e32 v164, 0x18c0, v7
	ds_write2_b32 v164, v156, v157 offset1:1
	ds_write2_b32 v164, v158, v159 offset0:2 offset1:3
	v_add_u32_e32 v164, 0x1ce0, v7
	ds_write2_b32 v164, v160, v161 offset1:1
	ds_write2_b32 v164, v162, v163 offset0:2 offset1:3
	s_waitcnt lgkmcnt(0)
	v_or_b32_e32 v1, v15, v13
	v_and_b32_e32 v1, 0xf8, v1
	v_mov_b32_e32 v0, 1.0
	v_lshlrev_b32_e32 v16, 2, v1
	v_mov_b32_e32 v2, 1.0
	s_cbranch_scc1 .LBB0_889
	global_load_dword v1, v16, s[26:27]
	s_waitcnt vmcnt(0)
	v_mul_f32_e32 v2, v21, v1

; #define LAS __attribute__((address_space(3)))
; #define LDS_WAIT() asm volatile("s_waitcnt lgkmcnt(0)" ::: "memory")
; __device__ __forceinline__ unsigned pk2(float lo, float hi) { return f2bf(lo) | (f2bf(hi) << 16); }
; template <class Map>
; __device__ __forceinline__ void conv_item(const Frame& F, int it, const float* W, int K, int N, bf16_t* WT, const float* gk, int gmask, float gmul, const float* bk, i64* cs, i64* bw, Map map) {
;     ...
;         const int kb = it / nblk, nb = it % nblk, k0 = 64 * kb, n0 = 32 * nb, v0 = map(n0);
; #pragma unroll
;         for (int i = 0; i < 8; ++i) { const int kk = 8 * i + (lane >> 3), c4 = (lane & 7) * 4;
;             const f32x4 w4 = __builtin_nontemporal_load((const f32x4*)(W + (size_t)(k0 + kk) * N + n0 + c4)); LAS float* d = scr + kk * 33 + c4; d[0] = w4[0]; d[1] = w4[1]; d[2] = w4[2]; d[3] = w4[3]; }
;         LDS_WAIT(); asm volatile("" ::: "memory");
;     ...
;         const int c = lane & 7; float gl[8];
; #pragma unroll
;         for (int i = 0; i < 8; ++i) gl[i] = gk ? gk[(k0 + 8 * c + i) & gmask] * gmul : 1.0f;
; #pragma unroll
;         for (int j = 0; j < 4; ++j) { const int n = (lane >> 3) + 8 * j; const LAS float* s = scr + (8 * c) * 33 + n;
;             u32x4 o; o.x = pk2(s[0 * 33] * gl[0], s[1 * 33] * gl[1]); o.y = pk2(s[2 * 33] * gl[2], s[3 * 33] * gl[3]); o.z = pk2(s[4 * 33] * gl[4], s[5 * 33] * gl[5]); o.w = pk2(s[6 * 33] * gl[6], s[7 * 33] * gl[7]);
.LBB0_905:
	s_andn2_saveexec_b64 s[12:13], s[92:93]
	s_cbranch_execz .LBB0_907
	v_readlane_b32 s16, v252, 14
	v_readlane_b32 s17, v252, 15
	s_load_dwordx2 s[16:17], s[16:17], 0x40
	s_mov_b32 s21, 0xaaab
	v_mul_u32_u24_sdwa v0, v1, s21 dst_sel:DWORD dst_unused:UNUSED_PAD src0_sel:WORD_0 src1_sel:DWORD
	v_lshrrev_b32_e32 v0, 23, v0
	v_readlane_b32 s24, v252, 12
	v_mul_lo_u16_e32 v2, 0xc0, v0
	v_readlane_b32 s25, v252, 13
	v_mov_b32_e32 v6, v220
	v_sub_u16_e32 v1, v1, v2
	s_waitcnt lgkmcnt(0)
	s_add_u32 s16, s16, s96
	v_lshlrev_b16_e32 v12, 6, v0
	v_lshlrev_b16_e32 v2, 5, v1
	v_bfe_u32 v7, v6, 3, 3
	s_addc_u32 s17, s17, s52
	v_lshlrev_b32_e32 v184, 2, v2
	v_lshlrev_b32_e32 v3, 4, v6
	v_or_b32_e32 v13, v7, v12
	v_lshl_add_u64 v[0:1], s[16:17], 0, v[184:185]
	v_and_b32_e32 v184, 0x70, v3
	v_mul_u32_u24_e32 v3, 0x1800, v13
	v_lshl_add_u64 v[0:1], v[0:1], 0, v[184:185]
	v_lshlrev_b32_e32 v4, 2, v3
	v_mov_b32_e32 v5, v185
	v_lshl_add_u64 v[4:5], v[0:1], 0, v[4:5]
	global_load_dwordx4 v[132:135], v[4:5], off nt
	v_mul_u32_u24_e32 v3, 0x84, v7
	v_or_b32_e32 v5, 8, v7
	v_add3_u32 v14, s79, v184, v3
	v_or_b32_e32 v3, v5, v12
	v_mul_u32_u24_e32 v3, 0x1800, v3
	v_lshlrev_b32_e32 v184, 2, v3
	v_add_u32_e32 v3, 0x420, v14
	v_or_b32_e32 v4, 16, v7
	v_add_u32_e32 v15, 0xc60, v14
	v_and_b32_e32 v6, 7, v6
	s_mov_b64 s[16:17], 0x39500000
	v_or_b32_e32 v5, v5, v2
	v_lshl_add_u64 v[8:9], v[0:1], 0, v[184:185]
	global_load_dwordx4 v[136:139], v[8:9], off nt
	v_add_u32_e32 v3, 0x428, v14
	v_or_b32_e32 v3, v4, v12
	v_mul_u32_u24_e32 v3, 0x1800, v3
	v_lshlrev_b32_e32 v184, 2, v3
	v_lshl_add_u64 v[8:9], v[0:1], 0, v[184:185]
	global_load_dwordx4 v[140:143], v[8:9], off nt
	v_add_u32_e32 v3, 0x840, v14
	v_or_b32_e32 v4, v4, v2
	v_add_u32_e32 v3, 0x848, v14
	v_or_b32_e32 v3, 24, v7
	v_or_b32_e32 v8, v3, v12
	v_mul_u32_u24_e32 v8, 0x1800, v8
	v_lshlrev_b32_e32 v184, 2, v8
	v_lshl_add_u64 v[8:9], v[0:1], 0, v[184:185]
	global_load_dwordx4 v[144:147], v[8:9], off nt
	v_add_u32_e32 v8, 0xc68, v14
	v_or_b32_e32 v8, 32, v13
	v_mul_u32_u24_e32 v8, 0x1800, v8
	v_lshlrev_b32_e32 v184, 2, v8
	v_lshl_add_u64 v[8:9], v[0:1], 0, v[184:185]
	global_load_dwordx4 v[148:151], v[8:9], off nt
	v_add_u32_e32 v15, 0x1080, v14
	v_add_u32_e32 v8, 0x1088, v14
	v_or_b32_e32 v8, 40, v13
	v_mul_u32_u24_e32 v8, 0x1800, v8
	v_lshlrev_b32_e32 v184, 2, v8
	v_lshl_add_u64 v[8:9], v[0:1], 0, v[184:185]
	global_load_dwordx4 v[152:155], v[8:9], off nt
	v_add_u32_e32 v15, 0x14a0, v14
	v_add_u32_e32 v8, 0x14a8, v14
	v_or_b32_e32 v8, 48, v13
	v_mul_u32_u24_e32 v8, 0x1800, v8
	v_lshlrev_b32_e32 v184, 2, v8
	v_lshl_add_u64 v[8:9], v[0:1], 0, v[184:185]
	global_load_dwordx4 v[156:159], v[8:9], off nt
	v_add_u32_e32 v15, 0x18c0, v14
	v_add_u32_e32 v8, 0x18c8, v14
	v_or_b32_e32 v8, 56, v13
	v_mul_u32_u24_e32 v8, 0x1800, v8
	v_lshlrev_b32_e32 v184, 2, v8
	v_lshl_add_u64 v[0:1], v[0:1], 0, v[184:185]
	global_load_dwordx4 v[160:163], v[0:1], off nt
	v_add_u32_e32 v0, 0x1ce0, v14
	v_lshlrev_b32_e32 v184, 1, v12
	v_add_u32_e32 v0, 0x1ce8, v14
	s_waitcnt vmcnt(0)
	v_add_u32_e32 v164, 0x0, v14
	ds_write2_b32 v164, v132, v133 offset1:1
	ds_write2_b32 v164, v134, v135 offset0:2 offset1:3
	v_add_u32_e32 v164, 0x420, v14
	ds_write2_b32 v164, v136, v137 offset1:1
	ds_write2_b32 v164, v138, v139 offset0:2 offset1:3
	v_add_u32_e32 v164, 0x840, v14
	ds_write2_b32 v164, v140, v141 offset1:1
	ds_write2_b32 v164, v142, v143 offset0:2 offset1:3
	v_add_u32_e32 v164, 0xc60, v14
	ds_write2_b32 v164, v144, v145 offset1:1
	ds_write2_b32 v164, v146, v147 offset0:2 offset1:3
	v_add_u32_e32 v164, 0x1080, v14
	ds_write2_b32 v164, v148, v149 offset1:1
	ds_write2_b32 v164, v150, v151 offset0:2 offset1:3
	v_add_u32_e32 v164, 0x14a0, v14
	ds_write2_b32 v164, v152, v153 offset1:1
	ds_write2_b32 v164, v154, v155 offset0:2 offset1:3
	v_add_u32_e32 v164, 0x18c0, v14
	ds_write2_b32 v164, v156, v157 offset1:1
	ds_write2_b32 v164, v158, v159 offset0:2 offset1:3
	v_add_u32_e32 v164, 0x1ce0, v14
	ds_write2_b32 v164, v160, v161 offset1:1
	ds_write2_b32 v164, v162, v163 offset0:2 offset1:3
	s_waitcnt lgkmcnt(0)
	v_mul_u32_u24_e32 v8, 0x420, v6
	v_lshl_add_u64 v[0:1], s[24:25], 0, v[184:185]
	v_lshlrev_b32_e32 v184, 4, v6
	v_lshlrev_b32_e32 v6, 2, v7
	v_add3_u32 v6, s79, v8, v6
	ds_read_b32 v8, v6
	ds_read_b32 v9, v6 offset:132
	v_lshl_add_u64 v[0:1], v[0:1], 0, v[184:185]
	v_or_b32_e32 v7, v7, v2
	v_lshl_add_u64 v[0:1], v[0:1], 0, s[16:17]
	s_waitcnt lgkmcnt(1)
	v_bfe_u32 v10, v8, 16, 1
	v_add3_u32 v8, v8, v10, s73
	s_waitcnt lgkmcnt(0)
; #define LAS __attribute__((address_space(3)))
; #define LDS_WAIT() asm volatile("s_waitcnt lgkmcnt(0)" ::: "memory")
; __device__ __forceinline__ unsigned pk2(float lo, float hi) { return f2bf(lo) | (f2bf(hi) << 16); }
; template <class Map>
; __device__ __forceinline__ void conv_item(const Frame& F, int it, const float* W, int K, int N, bf16_t* WT, const float* gk, int gmask, float gmul, const float* bk, i64* cs, i64* bw, Map map) {
;     ...
;         for (int j = 0; j < 4; ++j) { const int n = (lane >> 3) + 8 * j; const LAS float* s = scr + (8 * c) * 33 + n;
;             u32x4 o; o.x = pk2(s[0 * 33] * gl[0], s[1 * 33] * gl[1]); o.y = pk2(s[2 * 33] * gl[2], s[3 * 33] * gl[3]); o.z = pk2(s[4 * 33] * gl[4], s[5 * 33] * gl[5]); o.w = pk2(s[6 * 33] * gl[6], s[7 * 33] * gl[7]);
;             __builtin_nontemporal_store(o, (u32x4*)(WT + (size_t)(v0 + n) * K + k0 + 8 * c)); }
;         LDS_WAIT(); asm volatile("" ::: "memory");
	v_bfe_u32 v10, v9, 16, 1
	v_lshrrev_b32_e32 v8, 16, v8
	v_add3_u32 v9, v9, v10, s73
	v_and_or_b32 v8, v9, s72, v8
	ds_read_b32 v9, v6 offset:264
	ds_read_b32 v10, v6 offset:396
	v_lshlrev_b32_e32 v184, 12, v7
	v_or_b32_e32 v2, v3, v2
	s_waitcnt lgkmcnt(1)
	v_bfe_u32 v11, v9, 16, 1
	v_add3_u32 v9, v9, v11, s73
	s_waitcnt lgkmcnt(0)
	v_bfe_u32 v11, v10, 16, 1
	v_lshrrev_b32_e32 v9, 16, v9
	v_add3_u32 v10, v10, v11, s73
	v_and_or_b32 v9, v10, s72, v9
	ds_read_b32 v10, v6 offset:528
	ds_read_b32 v11, v6 offset:660
	s_waitcnt lgkmcnt(1)
	v_bfe_u32 v12, v10, 16, 1
	v_add3_u32 v10, v10, v12, s73
	s_waitcnt lgkmcnt(0)
	v_bfe_u32 v12, v11, 16, 1
	v_lshrrev_b32_e32 v10, 16, v10
	v_add3_u32 v11, v11, v12, s73
	v_and_or_b32 v10, v11, s72, v10
	ds_read_b32 v11, v6 offset:792
	ds_read_b32 v12, v6 offset:924
	s_waitcnt lgkmcnt(1)
	v_bfe_u32 v13, v11, 16, 1
	v_add3_u32 v11, v11, v13, s73
	s_waitcnt lgkmcnt(0)
	v_bfe_u32 v13, v12, 16, 1
	v_lshrrev_b32_e32 v11, 16, v11
	v_add3_u32 v12, v12, v13, s73
	v_and_or_b32 v11, v12, s72, v11
	v_lshl_add_u64 v[12:13], v[0:1], 0, v[184:185]
	flat_store_dwordx4 v[12:13], v[8:11] nt
	ds_read_b32 v7, v6 offset:32
	ds_read_b32 v8, v6 offset:164
	v_lshlrev_b32_e32 v184, 12, v5
	s_waitcnt lgkmcnt(0)
	v_bfe_u32 v9, v7, 16, 1
	v_add3_u32 v7, v7, v9, s73
	v_bfe_u32 v9, v8, 16, 1
	v_lshrrev_b32_e32 v7, 16, v7
	v_add3_u32 v8, v8, v9, s73
	v_and_or_b32 v8, v8, s72, v7
	ds_read_b32 v7, v6 offset:296
	ds_read_b32 v9, v6 offset:428
	s_waitcnt lgkmcnt(0)
	v_bfe_u32 v10, v7, 16, 1
	v_add3_u32 v7, v7, v10, s73
	v_bfe_u32 v10, v9, 16, 1
	v_lshrrev_b32_e32 v7, 16, v7
	v_add3_u32 v9, v9, v10, s73
	v_and_or_b32 v9, v9, s72, v7
	ds_read_b32 v7, v6 offset:560
	ds_read_b32 v10, v6 offset:692
	s_waitcnt lgkmcnt(0)
	v_bfe_u32 v11, v7, 16, 1
	v_add3_u32 v7, v7, v11, s73
	v_bfe_u32 v11, v10, 16, 1
	v_lshrrev_b32_e32 v7, 16, v7
	v_add3_u32 v10, v10, v11, s73
	v_and_or_b32 v10, v10, s72, v7
	ds_read_b32 v7, v6 offset:824
	ds_read_b32 v11, v6 offset:956
	s_waitcnt lgkmcnt(0)
	v_bfe_u32 v12, v7, 16, 1
	v_add3_u32 v7, v7, v12, s73
	v_bfe_u32 v12, v11, 16, 1
	v_lshrrev_b32_e32 v7, 16, v7
	v_add3_u32 v11, v11, v12, s73
	v_and_or_b32 v11, v11, s72, v7
	v_lshl_add_u64 v[12:13], v[0:1], 0, v[184:185]
	flat_store_dwordx4 v[12:13], v[8:11] nt
	ds_read_b32 v5, v6 offset:64
	ds_read_b32 v7, v6 offset:196
	v_lshlrev_b32_e32 v184, 12, v4
	s_waitcnt lgkmcnt(0)
	v_bfe_u32 v8, v5, 16, 1
	v_add3_u32 v5, v5, v8, s73
	v_bfe_u32 v8, v7, 16, 1
	v_lshrrev_b32_e32 v5, 16, v5
	v_add3_u32 v7, v7, v8, s73
	v_and_or_b32 v8, v7, s72, v5
	ds_read_b32 v5, v6 offset:328
	ds_read_b32 v7, v6 offset:460
	s_waitcnt lgkmcnt(0)
	v_bfe_u32 v9, v5, 16, 1
	v_add3_u32 v5, v5, v9, s73
	v_bfe_u32 v9, v7, 16, 1
	v_lshrrev_b32_e32 v5, 16, v5
	v_add3_u32 v7, v7, v9, s73
	v_and_or_b32 v9, v7, s72, v5
	ds_read_b32 v5, v6 offset:592
	ds_read_b32 v7, v6 offset:724
	s_waitcnt lgkmcnt(0)
	v_bfe_u32 v10, v5, 16, 1
	v_add3_u32 v5, v5, v10, s73
	v_bfe_u32 v10, v7, 16, 1
	v_lshrrev_b32_e32 v5, 16, v5
	v_add3_u32 v7, v7, v10, s73
	v_and_or_b32 v10, v7, s72, v5
	ds_read_b32 v5, v6 offset:856
	ds_read_b32 v7, v6 offset:988
	s_waitcnt lgkmcnt(0)
	v_bfe_u32 v11, v5, 16, 1
	v_add3_u32 v5, v5, v11, s73
	v_bfe_u32 v11, v7, 16, 1
	v_lshrrev_b32_e32 v5, 16, v5
	v_add3_u32 v7, v7, v11, s73
	v_and_or_b32 v11, v7, s72, v5
	v_lshl_add_u64 v[4:5], v[0:1], 0, v[184:185]
	flat_store_dwordx4 v[4:5], v[8:11] nt
	ds_read_b32 v4, v6 offset:96
	ds_read_b32 v5, v6 offset:228
	v_lshlrev_b32_e32 v184, 12, v2
	v_lshl_add_u64 v[0:1], v[0:1], 0, v[184:185]
	s_waitcnt lgkmcnt(0)
	v_bfe_u32 v7, v4, 16, 1
	v_add3_u32 v4, v4, v7, s73
	v_bfe_u32 v7, v5, 16, 1
	v_lshrrev_b32_e32 v4, 16, v4
	v_add3_u32 v5, v5, v7, s73
	v_and_or_b32 v8, v5, s72, v4
	ds_read_b32 v4, v6 offset:360
	ds_read_b32 v5, v6 offset:492
	s_waitcnt lgkmcnt(0)
	v_bfe_u32 v7, v4, 16, 1
	v_add3_u32 v4, v4, v7, s73
	v_bfe_u32 v7, v5, 16, 1
	v_lshrrev_b32_e32 v4, 16, v4
	v_add3_u32 v5, v5, v7, s73
	v_and_or_b32 v9, v5, s72, v4
	ds_read_b32 v4, v6 offset:624
	ds_read_b32 v5, v6 offset:756
	s_waitcnt lgkmcnt(0)
	v_bfe_u32 v7, v4, 16, 1
	v_add3_u32 v4, v4, v7, s73
	v_bfe_u32 v7, v5, 16, 1
	v_lshrrev_b32_e32 v4, 16, v4
	v_add3_u32 v5, v5, v7, s73
	v_and_or_b32 v10, v5, s72, v4
	ds_read_b32 v4, v6 offset:888
	ds_read_b32 v5, v6 offset:1020
	s_waitcnt lgkmcnt(0)
	v_bfe_u32 v6, v4, 16, 1
	v_add3_u32 v4, v4, v6, s73
	v_bfe_u32 v6, v5, 16, 1
	v_lshrrev_b32_e32 v4, 16, v4
	v_add3_u32 v5, v5, v6, s73
	v_and_or_b32 v11, v5, s72, v4
	flat_store_dwordx4 v[0:1], v[8:11] nt
	s_waitcnt lgkmcnt(0)

; #define LAS __attribute__((address_space(3)))
; #define LDS_WAIT() asm volatile("s_waitcnt lgkmcnt(0)" ::: "memory")
; template <class Map>
; __device__ __forceinline__ void conv_item(const Frame& F, int it, const float* W, int K, int N, bf16_t* WT, const float* gk, int gmask, float gmul, const float* bk, i64* cs, i64* bw, Map map) {
;     ...
;         const int kb = it / nblk, nb = it % nblk, k0 = 64 * kb, n0 = 32 * nb, v0 = map(n0);
; #pragma unroll
;         for (int i = 0; i < 8; ++i) { const int kk = 8 * i + (lane >> 3), c4 = (lane & 7) * 4;
;             const f32x4 w4 = __builtin_nontemporal_load((const f32x4*)(W + (size_t)(k0 + kk) * N + n0 + c4)); LAS float* d = scr + kk * 33 + c4; d[0] = w4[0]; d[1] = w4[1]; d[2] = w4[2]; d[3] = w4[3]; }
;         LDS_WAIT(); asm volatile("" ::: "memory");
;     ...
;         const int c = lane & 7; float gl[8];
; #pragma unroll
;         for (int i = 0; i < 8; ++i) gl[i] = gk ? gk[(k0 + 8 * c + i) & gmask] * gmul : 1.0f;
.LBB0_1165:
	s_or_b64 exec, exec, s[6:7]
	v_readlane_b32 s12, v255, 31
	v_readlane_b32 s13, v255, 32
	s_mov_b64 s[10:11], -1
	s_mov_b64 s[6:7], 0
	s_and_b64 vcc, exec, s[12:13]
	s_mov_b64 s[24:25], 0
	s_cbranch_vccz .LBB0_1189
	s_movk_i32 s10, 0x17ff
	v_cmp_lt_u32_e32 vcc, s10, v21
	s_and_saveexec_b64 s[10:11], vcc
	s_xor_b64 s[10:11], exec, s[10:11]
	s_cbranch_execz .LBB0_1186
	s_movk_i32 s12, 0x2000
	v_cmp_gt_u32_e32 vcc, s12, v21
	s_mov_b64 s[16:17], -1
	s_and_saveexec_b64 s[12:13], vcc
	s_cbranch_execz .LBB0_1185
	v_readlane_b32 s26, v252, 14
	v_readlane_b32 s27, v252, 15
	s_mov_b64 s[16:17], s[26:27]
	s_load_dwordx2 s[16:17], s[16:17], 0x58
	v_add_u32_e32 v0, 0xe800, v21
	v_readlane_b32 s24, v252, 12
	v_and_b32_e32 v13, 0xffc0, v0
	v_lshlrev_b32_e32 v0, 5, v21
	s_waitcnt lgkmcnt(0)
	s_add_u32 s16, s16, s92
	v_readlane_b32 s25, v252, 13
	v_mov_b32_e32 v22, v220
	v_and_b32_e32 v8, 0x7e0, v0
	s_addc_u32 s17, s17, s93
	s_load_dwordx2 s[30:31], s[26:27], 0x50
	v_lshlrev_b32_e32 v184, 2, v8
	v_lshlrev_b32_e32 v2, 4, v22
	v_bfe_u32 v12, v22, 3, 3
	v_lshl_add_u64 v[0:1], s[16:17], 0, v[184:185]
	v_and_b32_e32 v184, 0x70, v2
	v_lshl_add_u64 v[4:5], v[0:1], 0, v[184:185]
	v_or_b32_e32 v0, v12, v13
	v_lshlrev_b32_e32 v6, 13, v0
	v_mov_b32_e32 v7, v185
	v_lshl_add_u64 v[0:1], v[4:5], 0, v[6:7]
	global_load_dwordx4 v[132:135], v[0:1], off nt
	v_mul_u32_u24_e32 v7, 0x84, v12
	v_add3_u32 v7, s79, v184, v7
	v_or_b32_e32 v11, 8, v12
	v_add_u32_e32 v9, 0x420, v7
	v_or_b32_e32 v10, 16, v12
	v_add_u32_e32 v23, 0xc60, v7
	v_readlane_b32 s26, v255, 60
	v_and_b32_e32 v22, 7, v22
	v_readlane_b32 s27, v255, 61
	s_waitcnt lgkmcnt(0)
	s_add_u32 s26, s30, s26
	s_addc_u32 s27, s31, s27
	s_cmp_lg_u64 s[30:31], 0
	s_cselect_b64 s[40:41], -1, 0
	s_cmp_eq_u64 s[30:31], 0
	v_or_b32_e32 v0, v11, v13
	v_lshlrev_b32_e32 v184, 13, v0
	v_lshl_add_u64 v[0:1], v[4:5], 0, v[184:185]
	global_load_dwordx4 v[136:139], v[0:1], off nt
	v_add_u32_e32 v0, 0x428, v7
	v_or_b32_e32 v0, v10, v13
	v_lshlrev_b32_e32 v184, 13, v0
	v_lshl_add_u64 v[0:1], v[4:5], 0, v[184:185]
	global_load_dwordx4 v[140:143], v[0:1], off nt
	v_add_u32_e32 v9, 0x840, v7
	v_add_u32_e32 v0, 0x848, v7
	v_or_b32_e32 v9, 24, v12
	v_or_b32_e32 v0, v9, v13
	v_lshlrev_b32_e32 v184, 13, v0
	v_lshl_add_u64 v[0:1], v[4:5], 0, v[184:185]
	global_load_dwordx4 v[144:147], v[0:1], off nt
	v_or_b32_e32 v184, 0x40000, v6
	v_add_u32_e32 v0, 0xc68, v7
	v_lshl_add_u64 v[0:1], v[4:5], 0, v[184:185]
	global_load_dwordx4 v[148:151], v[0:1], off nt
	v_add_u32_e32 v23, 0x1080, v7
	v_or_b32_e32 v184, 0x50000, v6
	v_add_u32_e32 v0, 0x1088, v7
	v_lshl_add_u64 v[0:1], v[4:5], 0, v[184:185]
	global_load_dwordx4 v[152:155], v[0:1], off nt
	v_add_u32_e32 v23, 0x14a0, v7
	v_or_b32_e32 v184, 0x60000, v6
	v_add_u32_e32 v0, 0x14a8, v7
	v_lshl_add_u64 v[0:1], v[4:5], 0, v[184:185]
	global_load_dwordx4 v[156:159], v[0:1], off nt
	v_add_u32_e32 v23, 0x18c0, v7
	v_or_b32_e32 v184, 0x70000, v6
	v_add_u32_e32 v0, 0x18c8, v7
	v_lshl_add_u64 v[0:1], v[4:5], 0, v[184:185]
	global_load_dwordx4 v[160:163], v[0:1], off nt
	v_add_u32_e32 v4, 0x1ce0, v7
	v_lshlrev_b32_e32 v23, 3, v22
	v_add_u32_e32 v0, 0x1ce8, v7
	s_waitcnt vmcnt(0)
	v_add_u32_e32 v164, 0x0, v7
	ds_write2_b32 v164, v132, v133 offset1:1
	ds_write2_b32 v164, v134, v135 offset0:2 offset1:3
	v_add_u32_e32 v164, 0x420, v7
	ds_write2_b32 v164, v136, v137 offset1:1
	ds_write2_b32 v164, v138, v139 offset0:2 offset1:3
	v_add_u32_e32 v164, 0x840, v7
	ds_write2_b32 v164, v140, v141 offset1:1
	ds_write2_b32 v164, v142, v143 offset0:2 offset1:3
	v_add_u32_e32 v164, 0xc60, v7
	ds_write2_b32 v164, v144, v145 offset1:1
	ds_write2_b32 v164, v146, v147 offset0:2 offset1:3
	v_add_u32_e32 v164, 0x1080, v7
	ds_write2_b32 v164, v148, v149 offset1:1
	ds_write2_b32 v164, v150, v151 offset0:2 offset1:3
	v_add_u32_e32 v164, 0x14a0, v7
	ds_write2_b32 v164, v152, v153 offset1:1
	ds_write2_b32 v164, v154, v155 offset0:2 offset1:3
	v_add_u32_e32 v164, 0x18c0, v7
	ds_write2_b32 v164, v156, v157 offset1:1
	ds_write2_b32 v164, v158, v159 offset0:2 offset1:3
	v_add_u32_e32 v164, 0x1ce0, v7
	ds_write2_b32 v164, v160, v161 offset1:1
	ds_write2_b32 v164, v162, v163 offset0:2 offset1:3
	s_waitcnt lgkmcnt(0)
	v_or_b32_e32 v1, v23, v13
	v_and_b32_e32 v1, 0xf8, v1
	v_mov_b32_e32 v0, 1.0
	v_lshlrev_b32_e32 v24, 2, v1
	v_mov_b32_e32 v2, 1.0
	s_cbranch_scc1 .LBB0_1170
	global_load_dword v1, v24, s[26:27]
	s_waitcnt vmcnt(0)
	v_mul_f32_e32 v2, v15, v1

; #define LAS __attribute__((address_space(3)))
; #define LDS_WAIT() asm volatile("s_waitcnt lgkmcnt(0)" ::: "memory")
; __device__ __forceinline__ unsigned pk2(float lo, float hi) { return f2bf(lo) | (f2bf(hi) << 16); }
; template <class Map>
; __device__ __forceinline__ void conv_item(const Frame& F, int it, const float* W, int K, int N, bf16_t* WT, const float* gk, int gmask, float gmul, const float* bk, i64* cs, i64* bw, Map map) {
;     ...
;         const int kb = it / nblk, nb = it % nblk, k0 = 64 * kb, n0 = 32 * nb, v0 = map(n0);
; #pragma unroll
;         for (int i = 0; i < 8; ++i) { const int kk = 8 * i + (lane >> 3), c4 = (lane & 7) * 4;
;             const f32x4 w4 = __builtin_nontemporal_load((const f32x4*)(W + (size_t)(k0 + kk) * N + n0 + c4)); LAS float* d = scr + kk * 33 + c4; d[0] = w4[0]; d[1] = w4[1]; d[2] = w4[2]; d[3] = w4[3]; }
;         LDS_WAIT(); asm volatile("" ::: "memory");
;     ...
;         const int c = lane & 7; float gl[8];
; #pragma unroll
;         for (int i = 0; i < 8; ++i) gl[i] = gk ? gk[(k0 + 8 * c + i) & gmask] * gmul : 1.0f;
; #pragma unroll
;         for (int j = 0; j < 4; ++j) { const int n = (lane >> 3) + 8 * j; const LAS float* s = scr + (8 * c) * 33 + n;
;             u32x4 o; o.x = pk2(s[0 * 33] * gl[0], s[1 * 33] * gl[1]); o.y = pk2(s[2 * 33] * gl[2], s[3 * 33] * gl[3]); o.z = pk2(s[4 * 33] * gl[4], s[5 * 33] * gl[5]); o.w = pk2(s[6 * 33] * gl[6], s[7 * 33] * gl[7]);
.LBB0_1186:
	s_andn2_saveexec_b64 s[10:11], s[10:11]
	s_cbranch_execz .LBB0_1188
	v_readlane_b32 s12, v252, 14
	v_readlane_b32 s13, v252, 15
	s_load_dwordx2 s[12:13], s[12:13], 0x40
	s_mov_b32 s26, 0xaaab
	v_readlane_b32 s16, v255, 49
	v_mul_u32_u24_sdwa v0, v21, s26 dst_sel:DWORD dst_unused:UNUSED_PAD src0_sel:WORD_0 src1_sel:DWORD
	v_lshrrev_b32_e32 v0, 23, v0
	s_waitcnt lgkmcnt(0)
	s_add_u32 s16, s12, s16
	v_readlane_b32 s12, v255, 47
	s_addc_u32 s17, s13, s12
	v_readlane_b32 s12, v252, 12
	v_mul_lo_u16_e32 v1, 0xc0, v0
	v_readlane_b32 s13, v252, 13
	v_mov_b32_e32 v6, v220
	v_sub_u16_e32 v1, v21, v1
	v_lshlrev_b16_e32 v12, 6, v0
	v_lshlrev_b16_e32 v2, 5, v1
	v_bfe_u32 v7, v6, 3, 3
	v_lshlrev_b32_e32 v184, 2, v2
	v_lshlrev_b32_e32 v3, 4, v6
	v_or_b32_e32 v13, v7, v12
	v_lshl_add_u64 v[0:1], s[16:17], 0, v[184:185]
	v_and_b32_e32 v184, 0x70, v3
	v_mul_u32_u24_e32 v3, 0x1800, v13
	v_lshl_add_u64 v[0:1], v[0:1], 0, v[184:185]
	v_lshlrev_b32_e32 v4, 2, v3
	v_mov_b32_e32 v5, v185
	v_lshl_add_u64 v[4:5], v[0:1], 0, v[4:5]
	global_load_dwordx4 v[132:135], v[4:5], off nt
	v_mul_u32_u24_e32 v3, 0x84, v7
	v_or_b32_e32 v5, 8, v7
	v_add3_u32 v22, s79, v184, v3
	v_or_b32_e32 v3, v5, v12
	v_mul_u32_u24_e32 v3, 0x1800, v3
	v_lshlrev_b32_e32 v184, 2, v3
	v_add_u32_e32 v3, 0x420, v22
	v_or_b32_e32 v4, 16, v7
	v_add_u32_e32 v23, 0xc60, v22
	v_and_b32_e32 v6, 7, v6
	v_or_b32_e32 v5, v5, v2
	v_lshl_add_u64 v[8:9], v[0:1], 0, v[184:185]
	global_load_dwordx4 v[136:139], v[8:9], off nt
	v_add_u32_e32 v3, 0x428, v22
	v_or_b32_e32 v3, v4, v12
	v_mul_u32_u24_e32 v3, 0x1800, v3
	v_lshlrev_b32_e32 v184, 2, v3
	v_lshl_add_u64 v[8:9], v[0:1], 0, v[184:185]
	global_load_dwordx4 v[140:143], v[8:9], off nt
	v_add_u32_e32 v3, 0x840, v22
	v_or_b32_e32 v4, v4, v2
	v_add_u32_e32 v3, 0x848, v22
	v_or_b32_e32 v3, 24, v7
	v_or_b32_e32 v8, v3, v12
	v_mul_u32_u24_e32 v8, 0x1800, v8
	v_lshlrev_b32_e32 v184, 2, v8
	v_lshl_add_u64 v[8:9], v[0:1], 0, v[184:185]
	global_load_dwordx4 v[144:147], v[8:9], off nt
	v_add_u32_e32 v8, 0xc68, v22
	v_or_b32_e32 v8, 32, v13
	v_mul_u32_u24_e32 v8, 0x1800, v8
	v_lshlrev_b32_e32 v184, 2, v8
	v_lshl_add_u64 v[8:9], v[0:1], 0, v[184:185]
	global_load_dwordx4 v[148:151], v[8:9], off nt
	v_add_u32_e32 v23, 0x1080, v22
	v_add_u32_e32 v8, 0x1088, v22
	v_or_b32_e32 v8, 40, v13
	v_mul_u32_u24_e32 v8, 0x1800, v8
	v_lshlrev_b32_e32 v184, 2, v8
	v_lshl_add_u64 v[8:9], v[0:1], 0, v[184:185]
	global_load_dwordx4 v[152:155], v[8:9], off nt
	v_add_u32_e32 v23, 0x14a0, v22
	v_add_u32_e32 v8, 0x14a8, v22
	v_or_b32_e32 v8, 48, v13
	v_mul_u32_u24_e32 v8, 0x1800, v8
	v_lshlrev_b32_e32 v184, 2, v8
	v_lshl_add_u64 v[8:9], v[0:1], 0, v[184:185]
	global_load_dwordx4 v[156:159], v[8:9], off nt
	v_add_u32_e32 v23, 0x18c0, v22
	v_add_u32_e32 v8, 0x18c8, v22
	v_or_b32_e32 v8, 56, v13
	v_mul_u32_u24_e32 v8, 0x1800, v8
	v_lshlrev_b32_e32 v184, 2, v8
	v_lshl_add_u64 v[0:1], v[0:1], 0, v[184:185]
	global_load_dwordx4 v[160:163], v[0:1], off nt
	v_add_u32_e32 v0, 0x1ce0, v22
	v_lshlrev_b32_e32 v184, 1, v12
	v_add_u32_e32 v0, 0x1ce8, v22
	s_waitcnt vmcnt(0)
	v_add_u32_e32 v164, 0x0, v22
	ds_write2_b32 v164, v132, v133 offset1:1
	ds_write2_b32 v164, v134, v135 offset0:2 offset1:3
	v_add_u32_e32 v164, 0x420, v22
	ds_write2_b32 v164, v136, v137 offset1:1
	ds_write2_b32 v164, v138, v139 offset0:2 offset1:3
	v_add_u32_e32 v164, 0x840, v22
	ds_write2_b32 v164, v140, v141 offset1:1
	ds_write2_b32 v164, v142, v143 offset0:2 offset1:3
	v_add_u32_e32 v164, 0xc60, v22
	ds_write2_b32 v164, v144, v145 offset1:1
	ds_write2_b32 v164, v146, v147 offset0:2 offset1:3
	v_add_u32_e32 v164, 0x1080, v22
	ds_write2_b32 v164, v148, v149 offset1:1
	ds_write2_b32 v164, v150, v151 offset0:2 offset1:3
	v_add_u32_e32 v164, 0x14a0, v22
	ds_write2_b32 v164, v152, v153 offset1:1
	ds_write2_b32 v164, v154, v155 offset0:2 offset1:3
	v_add_u32_e32 v164, 0x18c0, v22
	ds_write2_b32 v164, v156, v157 offset1:1
	ds_write2_b32 v164, v158, v159 offset0:2 offset1:3
	v_add_u32_e32 v164, 0x1ce0, v22
	ds_write2_b32 v164, v160, v161 offset1:1
	ds_write2_b32 v164, v162, v163 offset0:2 offset1:3
	s_waitcnt lgkmcnt(0)
	v_mul_u32_u24_e32 v8, 0x420, v6
	v_lshl_add_u64 v[0:1], s[12:13], 0, v[184:185]
	v_lshlrev_b32_e32 v184, 4, v6
	v_lshlrev_b32_e32 v6, 2, v7
	v_add3_u32 v6, s79, v8, v6
	ds_read_b32 v8, v6
	ds_read_b32 v9, v6 offset:132
	v_lshl_add_u64 v[0:1], v[0:1], 0, v[184:185]
	s_mov_b64 s[12:13], 0x39500000
	v_or_b32_e32 v7, v7, v2
	s_waitcnt lgkmcnt(1)
	v_bfe_u32 v10, v8, 16, 1
	v_add3_u32 v8, v8, v10, s73
	s_waitcnt lgkmcnt(0)
; #define LAS __attribute__((address_space(3)))
; #define LDS_WAIT() asm volatile("s_waitcnt lgkmcnt(0)" ::: "memory")
; __device__ __forceinline__ unsigned pk2(float lo, float hi) { return f2bf(lo) | (f2bf(hi) << 16); }
; template <class Map>
; __device__ __forceinline__ void conv_item(const Frame& F, int it, const float* W, int K, int N, bf16_t* WT, const float* gk, int gmask, float gmul, const float* bk, i64* cs, i64* bw, Map map) {
;     ...
;         for (int j = 0; j < 4; ++j) { const int n = (lane >> 3) + 8 * j; const LAS float* s = scr + (8 * c) * 33 + n;
;             u32x4 o; o.x = pk2(s[0 * 33] * gl[0], s[1 * 33] * gl[1]); o.y = pk2(s[2 * 33] * gl[2], s[3 * 33] * gl[3]); o.z = pk2(s[4 * 33] * gl[4], s[5 * 33] * gl[5]); o.w = pk2(s[6 * 33] * gl[6], s[7 * 33] * gl[7]);
;             __builtin_nontemporal_store(o, (u32x4*)(WT + (size_t)(v0 + n) * K + k0 + 8 * c)); }
;         LDS_WAIT(); asm volatile("" ::: "memory");
	v_bfe_u32 v10, v9, 16, 1
	v_lshrrev_b32_e32 v8, 16, v8
	v_add3_u32 v9, v9, v10, s73
	v_and_or_b32 v8, v9, s72, v8
	ds_read_b32 v9, v6 offset:264
	ds_read_b32 v10, v6 offset:396
	v_lshl_add_u64 v[0:1], v[0:1], 0, s[12:13]
	v_lshlrev_b32_e32 v184, 12, v7
	v_or_b32_e32 v2, v3, v2
	s_waitcnt lgkmcnt(1)
	v_bfe_u32 v11, v9, 16, 1
	v_add3_u32 v9, v9, v11, s73
	s_waitcnt lgkmcnt(0)
	v_bfe_u32 v11, v10, 16, 1
	v_lshrrev_b32_e32 v9, 16, v9
	v_add3_u32 v10, v10, v11, s73
	v_and_or_b32 v9, v10, s72, v9
	ds_read_b32 v10, v6 offset:528
	ds_read_b32 v11, v6 offset:660
	s_waitcnt lgkmcnt(1)
	v_bfe_u32 v12, v10, 16, 1
	v_add3_u32 v10, v10, v12, s73
	s_waitcnt lgkmcnt(0)
	v_bfe_u32 v12, v11, 16, 1
	v_lshrrev_b32_e32 v10, 16, v10
	v_add3_u32 v11, v11, v12, s73
	v_and_or_b32 v10, v11, s72, v10
	ds_read_b32 v11, v6 offset:792
	ds_read_b32 v12, v6 offset:924
	s_waitcnt lgkmcnt(1)
	v_bfe_u32 v13, v11, 16, 1
	v_add3_u32 v11, v11, v13, s73
	s_waitcnt lgkmcnt(0)
	v_bfe_u32 v13, v12, 16, 1
	v_lshrrev_b32_e32 v11, 16, v11
	v_add3_u32 v12, v12, v13, s73
	v_and_or_b32 v11, v12, s72, v11
	v_lshl_add_u64 v[12:13], v[0:1], 0, v[184:185]
	flat_store_dwordx4 v[12:13], v[8:11] nt
	ds_read_b32 v7, v6 offset:32
	ds_read_b32 v8, v6 offset:164
	v_lshlrev_b32_e32 v184, 12, v5
	s_waitcnt lgkmcnt(0)
	v_bfe_u32 v9, v7, 16, 1
	v_add3_u32 v7, v7, v9, s73
	v_bfe_u32 v9, v8, 16, 1
	v_lshrrev_b32_e32 v7, 16, v7
	v_add3_u32 v8, v8, v9, s73
	v_and_or_b32 v8, v8, s72, v7
	ds_read_b32 v7, v6 offset:296
	ds_read_b32 v9, v6 offset:428
	s_waitcnt lgkmcnt(0)
	v_bfe_u32 v10, v7, 16, 1
	v_add3_u32 v7, v7, v10, s73
	v_bfe_u32 v10, v9, 16, 1
	v_lshrrev_b32_e32 v7, 16, v7
	v_add3_u32 v9, v9, v10, s73
	v_and_or_b32 v9, v9, s72, v7
	ds_read_b32 v7, v6 offset:560
	ds_read_b32 v10, v6 offset:692
	s_waitcnt lgkmcnt(0)
	v_bfe_u32 v11, v7, 16, 1
	v_add3_u32 v7, v7, v11, s73
	v_bfe_u32 v11, v10, 16, 1
	v_lshrrev_b32_e32 v7, 16, v7
	v_add3_u32 v10, v10, v11, s73
	v_and_or_b32 v10, v10, s72, v7
	ds_read_b32 v7, v6 offset:824
	ds_read_b32 v11, v6 offset:956
	s_waitcnt lgkmcnt(0)
	v_bfe_u32 v12, v7, 16, 1
	v_add3_u32 v7, v7, v12, s73
	v_bfe_u32 v12, v11, 16, 1
	v_lshrrev_b32_e32 v7, 16, v7
	v_add3_u32 v11, v11, v12, s73
	v_and_or_b32 v11, v11, s72, v7
	v_lshl_add_u64 v[12:13], v[0:1], 0, v[184:185]
	flat_store_dwordx4 v[12:13], v[8:11] nt
	ds_read_b32 v5, v6 offset:64
	ds_read_b32 v7, v6 offset:196
	v_lshlrev_b32_e32 v184, 12, v4
	s_waitcnt lgkmcnt(0)
	v_bfe_u32 v8, v5, 16, 1
	v_add3_u32 v5, v5, v8, s73
	v_bfe_u32 v8, v7, 16, 1
	v_lshrrev_b32_e32 v5, 16, v5
	v_add3_u32 v7, v7, v8, s73
	v_and_or_b32 v8, v7, s72, v5
	ds_read_b32 v5, v6 offset:328
	ds_read_b32 v7, v6 offset:460
	s_waitcnt lgkmcnt(0)
	v_bfe_u32 v9, v5, 16, 1
	v_add3_u32 v5, v5, v9, s73
	v_bfe_u32 v9, v7, 16, 1
	v_lshrrev_b32_e32 v5, 16, v5
	v_add3_u32 v7, v7, v9, s73
	v_and_or_b32 v9, v7, s72, v5
	ds_read_b32 v5, v6 offset:592
	ds_read_b32 v7, v6 offset:724
	s_waitcnt lgkmcnt(0)
	v_bfe_u32 v10, v5, 16, 1
	v_add3_u32 v5, v5, v10, s73
	v_bfe_u32 v10, v7, 16, 1
	v_lshrrev_b32_e32 v5, 16, v5
	v_add3_u32 v7, v7, v10, s73
	v_and_or_b32 v10, v7, s72, v5
	ds_read_b32 v5, v6 offset:856
	ds_read_b32 v7, v6 offset:988
	s_waitcnt lgkmcnt(0)
	v_bfe_u32 v11, v5, 16, 1
	v_add3_u32 v5, v5, v11, s73
	v_bfe_u32 v11, v7, 16, 1
	v_lshrrev_b32_e32 v5, 16, v5
	v_add3_u32 v7, v7, v11, s73
	v_and_or_b32 v11, v7, s72, v5
	v_lshl_add_u64 v[4:5], v[0:1], 0, v[184:185]
	flat_store_dwordx4 v[4:5], v[8:11] nt
	ds_read_b32 v4, v6 offset:96
	ds_read_b32 v5, v6 offset:228
	v_lshlrev_b32_e32 v184, 12, v2
	v_lshl_add_u64 v[0:1], v[0:1], 0, v[184:185]
	s_waitcnt lgkmcnt(0)
	v_bfe_u32 v7, v4, 16, 1
	v_add3_u32 v4, v4, v7, s73
	v_bfe_u32 v7, v5, 16, 1
	v_lshrrev_b32_e32 v4, 16, v4
	v_add3_u32 v5, v5, v7, s73
	v_and_or_b32 v8, v5, s72, v4
	ds_read_b32 v4, v6 offset:360
	ds_read_b32 v5, v6 offset:492
	s_waitcnt lgkmcnt(0)
	v_bfe_u32 v7, v4, 16, 1
	v_add3_u32 v4, v4, v7, s73
	v_bfe_u32 v7, v5, 16, 1
	v_lshrrev_b32_e32 v4, 16, v4
	v_add3_u32 v5, v5, v7, s73
	v_and_or_b32 v9, v5, s72, v4
	ds_read_b32 v4, v6 offset:624
	ds_read_b32 v5, v6 offset:756
	s_waitcnt lgkmcnt(0)
	v_bfe_u32 v7, v4, 16, 1
	v_add3_u32 v4, v4, v7, s73
	v_bfe_u32 v7, v5, 16, 1
	v_lshrrev_b32_e32 v4, 16, v4
	v_add3_u32 v5, v5, v7, s73
	v_and_or_b32 v10, v5, s72, v4
	ds_read_b32 v4, v6 offset:888
	ds_read_b32 v5, v6 offset:1020
	s_waitcnt lgkmcnt(0)
	v_bfe_u32 v6, v4, 16, 1
	v_add3_u32 v4, v4, v6, s73
	v_bfe_u32 v6, v5, 16, 1
	v_lshrrev_b32_e32 v4, 16, v4
	v_add3_u32 v5, v5, v6, s73
	v_and_or_b32 v11, v5, s72, v4
	flat_store_dwordx4 v[0:1], v[8:11] nt
	s_waitcnt lgkmcnt(0)

; #define LAS __attribute__((address_space(3)))
; #define LDS_WAIT() asm volatile("s_waitcnt lgkmcnt(0)" ::: "memory")
; __device__ __forceinline__ unsigned pk2(float lo, float hi) { return f2bf(lo) | (f2bf(hi) << 16); }
; template <class Map>
; __device__ __forceinline__ void conv_item(const Frame& F, int it, const float* W, int K, int N, bf16_t* WT, const float* gk, int gmask, float gmul, const float* bk, i64* cs, i64* bw, Map map) {
;     ...
;         const int kb = it / nblk, nb = it % nblk, k0 = 64 * kb, n0 = 32 * nb, v0 = map(n0);
; #pragma unroll
;         for (int i = 0; i < 8; ++i) { const int kk = 8 * i + (lane >> 3), c4 = (lane & 7) * 4;
;             const f32x4 w4 = __builtin_nontemporal_load((const f32x4*)(W + (size_t)(k0 + kk) * N + n0 + c4)); LAS float* d = scr + kk * 33 + c4; d[0] = w4[0]; d[1] = w4[1]; d[2] = w4[2]; d[3] = w4[3]; }
;         LDS_WAIT(); asm volatile("" ::: "memory");
;     ...
;         const int c = lane & 7; float gl[8];
; #pragma unroll
;         for (int i = 0; i < 8; ++i) gl[i] = gk ? gk[(k0 + 8 * c + i) & gmask] * gmul : 1.0f;
; #pragma unroll
;         for (int j = 0; j < 4; ++j) { const int n = (lane >> 3) + 8 * j; const LAS float* s = scr + (8 * c) * 33 + n;
;             u32x4 o; o.x = pk2(s[0 * 33] * gl[0], s[1 * 33] * gl[1]); o.y = pk2(s[2 * 33] * gl[2], s[3 * 33] * gl[3]); o.z = pk2(s[4 * 33] * gl[4], s[5 * 33] * gl[5]); o.w = pk2(s[6 * 33] * gl[6], s[7 * 33] * gl[7]);
.LBB0_1198:
	v_readlane_b32 s12, v252, 14
	v_readlane_b32 s13, v252, 15
	s_load_dwordx2 s[12:13], s[12:13], 0x38
	v_add_u32_e32 v0, 0xf4c0, v21
	v_and_b32_e32 v23, 0xffc0, v0
	v_lshlrev_b32_e32 v0, 5, v21
	v_mov_b32_e32 v22, v220
	s_waitcnt lgkmcnt(0)
	s_add_u32 s16, s12, s92
	s_addc_u32 s17, s13, s93
	v_readlane_b32 s12, v252, 12
	v_readlane_b32 s13, v252, 13
	v_and_b32_e32 v2, 0x7e0, v0
	v_lshlrev_b32_e32 v184, 2, v2
	v_bfe_u32 v7, v22, 3, 3
	v_lshlrev_b32_e32 v3, 4, v22
	v_lshl_add_u64 v[0:1], s[16:17], 0, v[184:185]
	v_and_b32_e32 v184, 0x70, v3
	v_or_b32_e32 v3, v7, v23
	v_lshl_add_u64 v[0:1], v[0:1], 0, v[184:185]
	v_lshlrev_b32_e32 v12, 13, v3
	v_mov_b32_e32 v13, v185
	v_lshl_add_u64 v[4:5], v[0:1], 0, v[12:13]
	global_load_dwordx4 v[132:135], v[4:5], off nt
	v_mul_u32_u24_e32 v3, 0x84, v7
	v_or_b32_e32 v6, 8, v7
	v_add3_u32 v13, s79, v184, v3
	v_or_b32_e32 v3, v6, v23
	v_lshlrev_b32_e32 v184, 13, v3
	v_lshl_add_u64 v[4:5], v[0:1], 0, v[184:185]
	v_add_u32_e32 v3, 0x420, v13
	v_or_b32_e32 v6, v6, v2
	global_load_dwordx4 v[136:139], v[4:5], off nt
	v_or_b32_e32 v4, 16, v7
	v_add_u32_e32 v3, 0x428, v13
	v_or_b32_e32 v3, v4, v23
	v_lshlrev_b32_e32 v184, 13, v3
	v_lshl_add_u64 v[8:9], v[0:1], 0, v[184:185]
	global_load_dwordx4 v[140:143], v[8:9], off nt
	v_add_u32_e32 v3, 0x840, v13
	v_or_b32_e32 v4, v4, v2
	v_add_u32_e32 v3, 0x848, v13
	v_or_b32_e32 v3, 24, v7
	v_or_b32_e32 v5, v3, v23
	v_lshlrev_b32_e32 v184, 13, v5
	v_lshl_add_u64 v[8:9], v[0:1], 0, v[184:185]
	global_load_dwordx4 v[144:147], v[8:9], off nt
	v_add_u32_e32 v5, 0xc60, v13
	v_or_b32_e32 v184, 0x40000, v12
	v_add_u32_e32 v5, 0xc68, v13
	v_lshl_add_u64 v[8:9], v[0:1], 0, v[184:185]
	global_load_dwordx4 v[148:151], v[8:9], off nt
	v_add_u32_e32 v5, 0x1080, v13
	v_or_b32_e32 v184, 0x50000, v12
	v_add_u32_e32 v5, 0x1088, v13
	v_lshl_add_u64 v[8:9], v[0:1], 0, v[184:185]
	global_load_dwordx4 v[152:155], v[8:9], off nt
	v_add_u32_e32 v5, 0x14a0, v13
	v_or_b32_e32 v184, 0x60000, v12
	v_add_u32_e32 v5, 0x14a8, v13
	v_lshl_add_u64 v[8:9], v[0:1], 0, v[184:185]
	global_load_dwordx4 v[156:159], v[8:9], off nt
	v_add_u32_e32 v5, 0x18c0, v13
	v_or_b32_e32 v184, 0x70000, v12
	v_lshl_add_u64 v[0:1], v[0:1], 0, v[184:185]
	v_lshlrev_b32_e32 v184, 1, v23
	v_add_u32_e32 v5, 0x18c8, v13
	global_load_dwordx4 v[160:163], v[0:1], off nt
	v_add_u32_e32 v0, 0x1ce0, v13
	v_and_b32_e32 v5, 7, v22
	v_add_u32_e32 v0, 0x1ce8, v13
	s_waitcnt vmcnt(0)
	v_add_u32_e32 v164, 0x0, v13
	ds_write2_b32 v164, v132, v133 offset1:1
	ds_write2_b32 v164, v134, v135 offset0:2 offset1:3
	v_add_u32_e32 v164, 0x420, v13
	ds_write2_b32 v164, v136, v137 offset1:1
	ds_write2_b32 v164, v138, v139 offset0:2 offset1:3
	v_add_u32_e32 v164, 0x840, v13
	ds_write2_b32 v164, v140, v141 offset1:1
	ds_write2_b32 v164, v142, v143 offset0:2 offset1:3
	v_add_u32_e32 v164, 0xc60, v13
	ds_write2_b32 v164, v144, v145 offset1:1
	ds_write2_b32 v164, v146, v147 offset0:2 offset1:3
	v_add_u32_e32 v164, 0x1080, v13
	ds_write2_b32 v164, v148, v149 offset1:1
	ds_write2_b32 v164, v150, v151 offset0:2 offset1:3
	v_add_u32_e32 v164, 0x14a0, v13
	ds_write2_b32 v164, v152, v153 offset1:1
	ds_write2_b32 v164, v154, v155 offset0:2 offset1:3
	v_add_u32_e32 v164, 0x18c0, v13
	ds_write2_b32 v164, v156, v157 offset1:1
	ds_write2_b32 v164, v158, v159 offset0:2 offset1:3
	v_add_u32_e32 v164, 0x1ce0, v13
	ds_write2_b32 v164, v160, v161 offset1:1
	ds_write2_b32 v164, v162, v163 offset0:2 offset1:3
	s_waitcnt lgkmcnt(0)
	v_mul_u32_u24_e32 v8, 0x420, v5
	v_lshl_add_u64 v[0:1], s[12:13], 0, v[184:185]
	v_lshlrev_b32_e32 v184, 4, v5
	v_lshlrev_b32_e32 v5, 2, v7
	v_add3_u32 v5, s79, v8, v5
	ds_read_b32 v8, v5
	ds_read_b32 v9, v5 offset:132
	v_lshl_add_u64 v[0:1], v[0:1], 0, v[184:185]
	s_mov_b64 s[12:13], 0x2800000
	v_or_b32_e32 v7, v7, v2
	s_waitcnt lgkmcnt(1)
	v_bfe_u32 v10, v8, 16, 1
	v_add3_u32 v8, v8, v10, s73
	s_waitcnt lgkmcnt(0)
	v_bfe_u32 v10, v9, 16, 1
	v_lshrrev_b32_e32 v8, 16, v8
	v_add3_u32 v9, v9, v10, s73
	v_and_or_b32 v8, v9, s72, v8
	ds_read_b32 v9, v5 offset:264
	ds_read_b32 v10, v5 offset:396
	v_lshl_add_u64 v[0:1], v[0:1], 0, s[12:13]
	v_lshlrev_b32_e32 v184, 12, v7
	v_or_b32_e32 v2, v3, v2
	s_waitcnt lgkmcnt(1)
	v_bfe_u32 v11, v9, 16, 1
	v_add3_u32 v9, v9, v11, s73
	s_waitcnt lgkmcnt(0)
; #define LAS __attribute__((address_space(3)))
; #define LDS_WAIT() asm volatile("s_waitcnt lgkmcnt(0)" ::: "memory")
; __device__ __forceinline__ unsigned pk2(float lo, float hi) { return f2bf(lo) | (f2bf(hi) << 16); }
; template <class Map>
; __device__ __forceinline__ void conv_item(const Frame& F, int it, const float* W, int K, int N, bf16_t* WT, const float* gk, int gmask, float gmul, const float* bk, i64* cs, i64* bw, Map map) {
;     ...
;         for (int j = 0; j < 4; ++j) { const int n = (lane >> 3) + 8 * j; const LAS float* s = scr + (8 * c) * 33 + n;
;             u32x4 o; o.x = pk2(s[0 * 33] * gl[0], s[1 * 33] * gl[1]); o.y = pk2(s[2 * 33] * gl[2], s[3 * 33] * gl[3]); o.z = pk2(s[4 * 33] * gl[4], s[5 * 33] * gl[5]); o.w = pk2(s[6 * 33] * gl[6], s[7 * 33] * gl[7]);
;             __builtin_nontemporal_store(o, (u32x4*)(WT + (size_t)(v0 + n) * K + k0 + 8 * c)); }
;         LDS_WAIT(); asm volatile("" ::: "memory");
	v_bfe_u32 v11, v10, 16, 1
	v_lshrrev_b32_e32 v9, 16, v9
	v_add3_u32 v10, v10, v11, s73
	v_and_or_b32 v9, v10, s72, v9
	ds_read_b32 v10, v5 offset:528
	ds_read_b32 v11, v5 offset:660
	s_waitcnt lgkmcnt(1)
	v_bfe_u32 v12, v10, 16, 1
	v_add3_u32 v10, v10, v12, s73
	s_waitcnt lgkmcnt(0)
	v_bfe_u32 v12, v11, 16, 1
	v_lshrrev_b32_e32 v10, 16, v10
	v_add3_u32 v11, v11, v12, s73
	v_and_or_b32 v10, v11, s72, v10
	ds_read_b32 v11, v5 offset:792
	ds_read_b32 v12, v5 offset:924
	s_waitcnt lgkmcnt(1)
	v_bfe_u32 v13, v11, 16, 1
	v_add3_u32 v11, v11, v13, s73
	s_waitcnt lgkmcnt(0)
	v_bfe_u32 v13, v12, 16, 1
	v_lshrrev_b32_e32 v11, 16, v11
	v_add3_u32 v12, v12, v13, s73
	v_and_or_b32 v11, v12, s72, v11
	v_lshl_add_u64 v[12:13], v[0:1], 0, v[184:185]
	flat_store_dwordx4 v[12:13], v[8:11] nt
	ds_read_b32 v7, v5 offset:32
	ds_read_b32 v8, v5 offset:164
	v_lshlrev_b32_e32 v184, 12, v6
	s_waitcnt lgkmcnt(0)
	v_bfe_u32 v9, v7, 16, 1
	v_add3_u32 v7, v7, v9, s73
	v_bfe_u32 v9, v8, 16, 1
	v_lshrrev_b32_e32 v7, 16, v7
	v_add3_u32 v8, v8, v9, s73
	v_and_or_b32 v8, v8, s72, v7
	ds_read_b32 v7, v5 offset:296
	ds_read_b32 v9, v5 offset:428
	s_waitcnt lgkmcnt(0)
	v_bfe_u32 v10, v7, 16, 1
	v_add3_u32 v7, v7, v10, s73
	v_bfe_u32 v10, v9, 16, 1
	v_lshrrev_b32_e32 v7, 16, v7
	v_add3_u32 v9, v9, v10, s73
	v_and_or_b32 v9, v9, s72, v7
	ds_read_b32 v7, v5 offset:560
	ds_read_b32 v10, v5 offset:692
	s_waitcnt lgkmcnt(0)
	v_bfe_u32 v11, v7, 16, 1
	v_add3_u32 v7, v7, v11, s73
	v_bfe_u32 v11, v10, 16, 1
	v_lshrrev_b32_e32 v7, 16, v7
	v_add3_u32 v10, v10, v11, s73
	v_and_or_b32 v10, v10, s72, v7
	ds_read_b32 v7, v5 offset:824
	ds_read_b32 v11, v5 offset:956
	s_waitcnt lgkmcnt(0)
	v_bfe_u32 v12, v7, 16, 1
	v_add3_u32 v7, v7, v12, s73
	v_bfe_u32 v12, v11, 16, 1
	v_lshrrev_b32_e32 v7, 16, v7
	v_add3_u32 v11, v11, v12, s73
	v_and_or_b32 v11, v11, s72, v7
	v_lshl_add_u64 v[6:7], v[0:1], 0, v[184:185]
	flat_store_dwordx4 v[6:7], v[8:11] nt
	ds_read_b32 v6, v5 offset:64
	ds_read_b32 v7, v5 offset:196
	v_lshlrev_b32_e32 v184, 12, v4
	s_waitcnt lgkmcnt(0)
	v_bfe_u32 v8, v6, 16, 1
	v_add3_u32 v6, v6, v8, s73
	v_bfe_u32 v8, v7, 16, 1
	v_lshrrev_b32_e32 v6, 16, v6
	v_add3_u32 v7, v7, v8, s73
	v_and_or_b32 v6, v7, s72, v6
	ds_read_b32 v7, v5 offset:328
	ds_read_b32 v8, v5 offset:460
	s_waitcnt lgkmcnt(0)
	v_bfe_u32 v9, v7, 16, 1
	v_add3_u32 v7, v7, v9, s73
	v_bfe_u32 v9, v8, 16, 1
	v_lshrrev_b32_e32 v7, 16, v7
	v_add3_u32 v8, v8, v9, s73
	v_and_or_b32 v7, v8, s72, v7
	ds_read_b32 v8, v5 offset:592
	ds_read_b32 v9, v5 offset:724
	s_waitcnt lgkmcnt(0)
	v_bfe_u32 v10, v8, 16, 1
	v_add3_u32 v8, v8, v10, s73
	v_bfe_u32 v10, v9, 16, 1
	v_lshrrev_b32_e32 v8, 16, v8
	v_add3_u32 v9, v9, v10, s73
	v_and_or_b32 v8, v9, s72, v8
	ds_read_b32 v9, v5 offset:856
	ds_read_b32 v10, v5 offset:988
	s_waitcnt lgkmcnt(0)
	v_bfe_u32 v11, v9, 16, 1
	v_add3_u32 v9, v9, v11, s73
	v_bfe_u32 v11, v10, 16, 1
	v_lshrrev_b32_e32 v9, 16, v9
	v_add3_u32 v10, v10, v11, s73
	v_and_or_b32 v9, v10, s72, v9
	v_lshl_add_u64 v[10:11], v[0:1], 0, v[184:185]
	flat_store_dwordx4 v[10:11], v[6:9] nt
	ds_read_b32 v4, v5 offset:96
	ds_read_b32 v6, v5 offset:228
	v_lshlrev_b32_e32 v184, 12, v2
	v_lshl_add_u64 v[0:1], v[0:1], 0, v[184:185]
	s_waitcnt lgkmcnt(0)
	v_bfe_u32 v7, v4, 16, 1
	v_add3_u32 v4, v4, v7, s73
	v_bfe_u32 v7, v6, 16, 1
	v_lshrrev_b32_e32 v4, 16, v4
	v_add3_u32 v6, v6, v7, s73
	v_and_or_b32 v6, v6, s72, v4
	ds_read_b32 v4, v5 offset:360
	ds_read_b32 v7, v5 offset:492
	s_waitcnt lgkmcnt(0)
	v_bfe_u32 v8, v4, 16, 1
	v_add3_u32 v4, v4, v8, s73
	v_bfe_u32 v8, v7, 16, 1
	v_lshrrev_b32_e32 v4, 16, v4
	v_add3_u32 v7, v7, v8, s73
	v_and_or_b32 v7, v7, s72, v4
	ds_read_b32 v4, v5 offset:624
	ds_read_b32 v8, v5 offset:756
	s_waitcnt lgkmcnt(0)
	v_bfe_u32 v9, v4, 16, 1
	v_add3_u32 v4, v4, v9, s73
	v_bfe_u32 v9, v8, 16, 1
	v_lshrrev_b32_e32 v4, 16, v4
	v_add3_u32 v8, v8, v9, s73
	v_and_or_b32 v8, v8, s72, v4
	ds_read_b32 v4, v5 offset:888
	ds_read_b32 v5, v5 offset:1020
	s_waitcnt lgkmcnt(0)
	v_bfe_u32 v9, v4, 16, 1
	v_add3_u32 v4, v4, v9, s73
	v_bfe_u32 v9, v5, 16, 1
	v_lshrrev_b32_e32 v4, 16, v4
	v_add3_u32 v5, v5, v9, s73
	v_and_or_b32 v9, v5, s72, v4
	flat_store_dwordx4 v[0:1], v[6:9] nt
	s_waitcnt lgkmcnt(0)
	s_or_b64 exec, exec, s[6:7]
	s_and_saveexec_b64 s[6:7], s[30:31]
	s_cbranch_execz .LBB0_1261
	s_branch .LBB0_1244

; #define LAS __attribute__((address_space(3)))
; #define LDS_WAIT() asm volatile("s_waitcnt lgkmcnt(0)" ::: "memory")
; __device__ __forceinline__ unsigned pk2(float lo, float hi) { return f2bf(lo) | (f2bf(hi) << 16); }
; template <class Map>
; __device__ __forceinline__ void conv_item(const Frame& F, int it, const float* W, int K, int N, bf16_t* WT, const float* gk, int gmask, float gmul, const float* bk, i64* cs, i64* bw, Map map) {
;     ...
;         const int kb = it / nblk, nb = it % nblk, k0 = 64 * kb, n0 = 32 * nb, v0 = map(n0);
; #pragma unroll
;         for (int i = 0; i < 8; ++i) { const int kk = 8 * i + (lane >> 3), c4 = (lane & 7) * 4;
;             const f32x4 w4 = __builtin_nontemporal_load((const f32x4*)(W + (size_t)(k0 + kk) * N + n0 + c4)); LAS float* d = scr + kk * 33 + c4; d[0] = w4[0]; d[1] = w4[1]; d[2] = w4[2]; d[3] = w4[3]; }
;         LDS_WAIT(); asm volatile("" ::: "memory");
;     ...
;         const int c = lane & 7; float gl[8];
; #pragma unroll
;         for (int i = 0; i < 8; ++i) gl[i] = gk ? gk[(k0 + 8 * c + i) & gmask] * gmul : 1.0f;
; #pragma unroll
;         for (int j = 0; j < 4; ++j) { const int n = (lane >> 3) + 8 * j; const LAS float* s = scr + (8 * c) * 33 + n;
;             u32x4 o; o.x = pk2(s[0 * 33] * gl[0], s[1 * 33] * gl[1]); o.y = pk2(s[2 * 33] * gl[2], s[3 * 33] * gl[3]); o.z = pk2(s[4 * 33] * gl[4], s[5 * 33] * gl[5]); o.w = pk2(s[6 * 33] * gl[6], s[7 * 33] * gl[7]);
.LBB0_1205:
	s_andn2_saveexec_b64 s[70:71], s[12:13]
	s_cbranch_execz .LBB0_1207
	v_readlane_b32 s12, v252, 14
	v_readlane_b32 s13, v252, 15
	s_load_dwordx2 s[12:13], s[12:13], 0x90
	v_readlane_b32 s16, v255, 52
	v_readlane_b32 s17, v255, 53
	v_and_b32_e32 v23, 0xc0, v0
	v_lshlrev_b32_e32 v0, 5, v0
	s_waitcnt lgkmcnt(0)
	s_add_u32 s16, s12, s16
	s_addc_u32 s17, s13, s17
	v_readlane_b32 s12, v252, 12
	v_readlane_b32 s13, v252, 13
	v_mov_b32_e32 v22, v220
	v_and_b32_e32 v2, 0x7e0, v0
	v_lshlrev_b32_e32 v184, 2, v2
	v_bfe_u32 v7, v22, 3, 3
	v_lshlrev_b32_e32 v3, 4, v22
	v_lshl_add_u64 v[0:1], s[16:17], 0, v[184:185]
	v_and_b32_e32 v184, 0x70, v3
	v_or_b32_e32 v3, v7, v23
	v_lshl_add_u64 v[0:1], v[0:1], 0, v[184:185]
	v_lshlrev_b32_e32 v12, 13, v3
	v_mov_b32_e32 v13, v185
	v_lshl_add_u64 v[4:5], v[0:1], 0, v[12:13]
	global_load_dwordx4 v[132:135], v[4:5], off nt
	v_mul_u32_u24_e32 v3, 0x84, v7
	v_or_b32_e32 v6, 8, v7
	v_add3_u32 v13, s79, v184, v3
	v_or_b32_e32 v3, v6, v23
	v_lshlrev_b32_e32 v184, 13, v3
	v_lshl_add_u64 v[4:5], v[0:1], 0, v[184:185]
	v_add_u32_e32 v3, 0x420, v13
	v_readlane_b32 s48, v255, 39
	s_add_u32 s12, s12, s48
	s_addc_u32 s13, s13, 0
	v_or_b32_e32 v6, v6, v2
	global_load_dwordx4 v[136:139], v[4:5], off nt
	v_or_b32_e32 v4, 16, v7
	v_add_u32_e32 v3, 0x428, v13
	v_or_b32_e32 v3, v4, v23
	v_lshlrev_b32_e32 v184, 13, v3
	v_lshl_add_u64 v[8:9], v[0:1], 0, v[184:185]
	global_load_dwordx4 v[140:143], v[8:9], off nt
	v_add_u32_e32 v3, 0x840, v13
	v_or_b32_e32 v4, v4, v2
	v_add_u32_e32 v3, 0x848, v13
	v_or_b32_e32 v3, 24, v7
	v_or_b32_e32 v5, v3, v23
	v_lshlrev_b32_e32 v184, 13, v5
	v_lshl_add_u64 v[8:9], v[0:1], 0, v[184:185]
	global_load_dwordx4 v[144:147], v[8:9], off nt
	v_add_u32_e32 v5, 0xc60, v13
	v_or_b32_e32 v184, 0x40000, v12
	v_add_u32_e32 v5, 0xc68, v13
	v_lshl_add_u64 v[8:9], v[0:1], 0, v[184:185]
	global_load_dwordx4 v[148:151], v[8:9], off nt
	v_add_u32_e32 v5, 0x1080, v13
	v_or_b32_e32 v184, 0x50000, v12
	v_add_u32_e32 v5, 0x1088, v13
	v_lshl_add_u64 v[8:9], v[0:1], 0, v[184:185]
	global_load_dwordx4 v[152:155], v[8:9], off nt
	v_add_u32_e32 v5, 0x14a0, v13
	v_or_b32_e32 v184, 0x60000, v12
	v_add_u32_e32 v5, 0x14a8, v13
	v_lshl_add_u64 v[8:9], v[0:1], 0, v[184:185]
	global_load_dwordx4 v[156:159], v[8:9], off nt
	v_add_u32_e32 v5, 0x18c0, v13
	v_or_b32_e32 v184, 0x70000, v12
	v_lshl_add_u64 v[0:1], v[0:1], 0, v[184:185]
	v_lshlrev_b32_e32 v184, 1, v23
	v_add_u32_e32 v5, 0x18c8, v13
	global_load_dwordx4 v[160:163], v[0:1], off nt
	v_add_u32_e32 v0, 0x1ce0, v13
	v_and_b32_e32 v5, 7, v22
	v_add_u32_e32 v0, 0x1ce8, v13
	s_waitcnt vmcnt(0)
	v_add_u32_e32 v164, 0x0, v13
	ds_write2_b32 v164, v132, v133 offset1:1
	ds_write2_b32 v164, v134, v135 offset0:2 offset1:3
	v_add_u32_e32 v164, 0x420, v13
	ds_write2_b32 v164, v136, v137 offset1:1
	ds_write2_b32 v164, v138, v139 offset0:2 offset1:3
	v_add_u32_e32 v164, 0x840, v13
	ds_write2_b32 v164, v140, v141 offset1:1
	ds_write2_b32 v164, v142, v143 offset0:2 offset1:3
	v_add_u32_e32 v164, 0xc60, v13
	ds_write2_b32 v164, v144, v145 offset1:1
	ds_write2_b32 v164, v146, v147 offset0:2 offset1:3
	v_add_u32_e32 v164, 0x1080, v13
	ds_write2_b32 v164, v148, v149 offset1:1
	ds_write2_b32 v164, v150, v151 offset0:2 offset1:3
	v_add_u32_e32 v164, 0x14a0, v13
	ds_write2_b32 v164, v152, v153 offset1:1
	ds_write2_b32 v164, v154, v155 offset0:2 offset1:3
	v_add_u32_e32 v164, 0x18c0, v13
	ds_write2_b32 v164, v156, v157 offset1:1
	ds_write2_b32 v164, v158, v159 offset0:2 offset1:3
	v_add_u32_e32 v164, 0x1ce0, v13
	ds_write2_b32 v164, v160, v161 offset1:1
	ds_write2_b32 v164, v162, v163 offset0:2 offset1:3
	s_waitcnt lgkmcnt(0)
	v_mul_u32_u24_e32 v8, 0x420, v5
	v_lshl_add_u64 v[0:1], s[12:13], 0, v[184:185]
	v_lshlrev_b32_e32 v184, 4, v5
	v_lshlrev_b32_e32 v5, 2, v7
	v_add3_u32 v5, s79, v8, v5
	ds_read_b32 v8, v5
	ds_read_b32 v9, v5 offset:132
	v_lshl_add_u64 v[0:1], v[0:1], 0, v[184:185]
	s_mov_b64 s[12:13], 0x7a00000
	v_or_b32_e32 v7, v7, v2
	s_waitcnt lgkmcnt(1)
	v_bfe_u32 v10, v8, 16, 1
	v_add3_u32 v8, v8, v10, s73
	s_waitcnt lgkmcnt(0)
	v_bfe_u32 v10, v9, 16, 1
	v_lshrrev_b32_e32 v8, 16, v8
	v_add3_u32 v9, v9, v10, s73
	v_and_or_b32 v8, v9, s72, v8
	ds_read_b32 v9, v5 offset:264
	ds_read_b32 v10, v5 offset:396
	v_lshl_add_u64 v[0:1], v[0:1], 0, s[12:13]
	v_lshlrev_b32_e32 v184, 9, v7
	v_or_b32_e32 v2, v3, v2
	s_waitcnt lgkmcnt(1)
; #define LAS __attribute__((address_space(3)))
; #define LDS_WAIT() asm volatile("s_waitcnt lgkmcnt(0)" ::: "memory")
; __device__ __forceinline__ unsigned pk2(float lo, float hi) { return f2bf(lo) | (f2bf(hi) << 16); }
; template <class Map>
; __device__ __forceinline__ void conv_item(const Frame& F, int it, const float* W, int K, int N, bf16_t* WT, const float* gk, int gmask, float gmul, const float* bk, i64* cs, i64* bw, Map map) {
;     ...
;         for (int j = 0; j < 4; ++j) { const int n = (lane >> 3) + 8 * j; const LAS float* s = scr + (8 * c) * 33 + n;
;             u32x4 o; o.x = pk2(s[0 * 33] * gl[0], s[1 * 33] * gl[1]); o.y = pk2(s[2 * 33] * gl[2], s[3 * 33] * gl[3]); o.z = pk2(s[4 * 33] * gl[4], s[5 * 33] * gl[5]); o.w = pk2(s[6 * 33] * gl[6], s[7 * 33] * gl[7]);
;             __builtin_nontemporal_store(o, (u32x4*)(WT + (size_t)(v0 + n) * K + k0 + 8 * c)); }
;         LDS_WAIT(); asm volatile("" ::: "memory");
	v_bfe_u32 v11, v9, 16, 1
	v_add3_u32 v9, v9, v11, s73
	s_waitcnt lgkmcnt(0)
	v_bfe_u32 v11, v10, 16, 1
	v_lshrrev_b32_e32 v9, 16, v9
	v_add3_u32 v10, v10, v11, s73
	v_and_or_b32 v9, v10, s72, v9
	ds_read_b32 v10, v5 offset:528
	ds_read_b32 v11, v5 offset:660
	s_waitcnt lgkmcnt(1)
	v_bfe_u32 v12, v10, 16, 1
	v_add3_u32 v10, v10, v12, s73
	s_waitcnt lgkmcnt(0)
	v_bfe_u32 v12, v11, 16, 1
	v_lshrrev_b32_e32 v10, 16, v10
	v_add3_u32 v11, v11, v12, s73
	v_and_or_b32 v10, v11, s72, v10
	ds_read_b32 v11, v5 offset:792
	ds_read_b32 v12, v5 offset:924
	s_waitcnt lgkmcnt(1)
	v_bfe_u32 v13, v11, 16, 1
	v_add3_u32 v11, v11, v13, s73
	s_waitcnt lgkmcnt(0)
	v_bfe_u32 v13, v12, 16, 1
	v_lshrrev_b32_e32 v11, 16, v11
	v_add3_u32 v12, v12, v13, s73
	v_and_or_b32 v11, v12, s72, v11
	v_lshl_add_u64 v[12:13], v[0:1], 0, v[184:185]
	flat_store_dwordx4 v[12:13], v[8:11] nt
	ds_read_b32 v7, v5 offset:32
	ds_read_b32 v8, v5 offset:164
	v_lshlrev_b32_e32 v184, 9, v6
	s_waitcnt lgkmcnt(0)
	v_bfe_u32 v9, v7, 16, 1
	v_add3_u32 v7, v7, v9, s73
	v_bfe_u32 v9, v8, 16, 1
	v_lshrrev_b32_e32 v7, 16, v7
	v_add3_u32 v8, v8, v9, s73
	v_and_or_b32 v8, v8, s72, v7
	ds_read_b32 v7, v5 offset:296
	ds_read_b32 v9, v5 offset:428
	s_waitcnt lgkmcnt(0)
	v_bfe_u32 v10, v7, 16, 1
	v_add3_u32 v7, v7, v10, s73
	v_bfe_u32 v10, v9, 16, 1
	v_lshrrev_b32_e32 v7, 16, v7
	v_add3_u32 v9, v9, v10, s73
	v_and_or_b32 v9, v9, s72, v7
	ds_read_b32 v7, v5 offset:560
	ds_read_b32 v10, v5 offset:692
	s_waitcnt lgkmcnt(0)
	v_bfe_u32 v11, v7, 16, 1
	v_add3_u32 v7, v7, v11, s73
	v_bfe_u32 v11, v10, 16, 1
	v_lshrrev_b32_e32 v7, 16, v7
	v_add3_u32 v10, v10, v11, s73
	v_and_or_b32 v10, v10, s72, v7
	ds_read_b32 v7, v5 offset:824
	ds_read_b32 v11, v5 offset:956
	s_waitcnt lgkmcnt(0)
	v_bfe_u32 v12, v7, 16, 1
	v_add3_u32 v7, v7, v12, s73
	v_bfe_u32 v12, v11, 16, 1
	v_lshrrev_b32_e32 v7, 16, v7
	v_add3_u32 v11, v11, v12, s73
	v_and_or_b32 v11, v11, s72, v7
	v_lshl_add_u64 v[6:7], v[0:1], 0, v[184:185]
	flat_store_dwordx4 v[6:7], v[8:11] nt
	ds_read_b32 v6, v5 offset:64
	ds_read_b32 v7, v5 offset:196
	v_lshlrev_b32_e32 v184, 9, v4
	s_waitcnt lgkmcnt(0)
	v_bfe_u32 v8, v6, 16, 1
	v_add3_u32 v6, v6, v8, s73
	v_bfe_u32 v8, v7, 16, 1
	v_lshrrev_b32_e32 v6, 16, v6
	v_add3_u32 v7, v7, v8, s73
	v_and_or_b32 v6, v7, s72, v6
	ds_read_b32 v7, v5 offset:328
	ds_read_b32 v8, v5 offset:460
	s_waitcnt lgkmcnt(0)
	v_bfe_u32 v9, v7, 16, 1
	v_add3_u32 v7, v7, v9, s73
	v_bfe_u32 v9, v8, 16, 1
	v_lshrrev_b32_e32 v7, 16, v7
	v_add3_u32 v8, v8, v9, s73
	v_and_or_b32 v7, v8, s72, v7
	ds_read_b32 v8, v5 offset:592
	ds_read_b32 v9, v5 offset:724
	s_waitcnt lgkmcnt(0)
	v_bfe_u32 v10, v8, 16, 1
	v_add3_u32 v8, v8, v10, s73
	v_bfe_u32 v10, v9, 16, 1
	v_lshrrev_b32_e32 v8, 16, v8
	v_add3_u32 v9, v9, v10, s73
	v_and_or_b32 v8, v9, s72, v8
	ds_read_b32 v9, v5 offset:856
	ds_read_b32 v10, v5 offset:988
	s_waitcnt lgkmcnt(0)
	v_bfe_u32 v11, v9, 16, 1
	v_add3_u32 v9, v9, v11, s73
	v_bfe_u32 v11, v10, 16, 1
	v_lshrrev_b32_e32 v9, 16, v9
	v_add3_u32 v10, v10, v11, s73
	v_and_or_b32 v9, v10, s72, v9
	v_lshl_add_u64 v[10:11], v[0:1], 0, v[184:185]
	flat_store_dwordx4 v[10:11], v[6:9] nt
	ds_read_b32 v4, v5 offset:96
	ds_read_b32 v6, v5 offset:228
	v_lshlrev_b32_e32 v184, 9, v2
	v_lshl_add_u64 v[0:1], v[0:1], 0, v[184:185]
	s_waitcnt lgkmcnt(0)
	v_bfe_u32 v7, v4, 16, 1
	v_add3_u32 v4, v4, v7, s73
	v_bfe_u32 v7, v6, 16, 1
	v_lshrrev_b32_e32 v4, 16, v4
	v_add3_u32 v6, v6, v7, s73
	v_and_or_b32 v6, v6, s72, v4
	ds_read_b32 v4, v5 offset:360
	ds_read_b32 v7, v5 offset:492
	s_waitcnt lgkmcnt(0)
	v_bfe_u32 v8, v4, 16, 1
	v_add3_u32 v4, v4, v8, s73
	v_bfe_u32 v8, v7, 16, 1
	v_lshrrev_b32_e32 v4, 16, v4
	v_add3_u32 v7, v7, v8, s73
	v_and_or_b32 v7, v7, s72, v4
	ds_read_b32 v4, v5 offset:624
	ds_read_b32 v8, v5 offset:756
	s_waitcnt lgkmcnt(0)
	v_bfe_u32 v9, v4, 16, 1
	v_add3_u32 v4, v4, v9, s73
	v_bfe_u32 v9, v8, 16, 1
	v_lshrrev_b32_e32 v4, 16, v4
	v_add3_u32 v8, v8, v9, s73
	v_and_or_b32 v8, v8, s72, v4
	ds_read_b32 v4, v5 offset:888
	ds_read_b32 v5, v5 offset:1020
	s_waitcnt lgkmcnt(0)
	v_bfe_u32 v9, v4, 16, 1
	v_add3_u32 v4, v4, v9, s73
	v_bfe_u32 v9, v5, 16, 1
	v_lshrrev_b32_e32 v4, 16, v4
	v_add3_u32 v5, v5, v9, s73
	v_and_or_b32 v9, v5, s72, v4
	flat_store_dwordx4 v[0:1], v[6:9] nt
	s_waitcnt lgkmcnt(0)

; #define LAS __attribute__((address_space(3)))
; #define LDS_WAIT() asm volatile("s_waitcnt lgkmcnt(0)" ::: "memory")
; template <class Map>
; __device__ __forceinline__ void conv_item(const Frame& F, int it, const float* W, int K, int N, bf16_t* WT, const float* gk, int gmask, float gmul, const float* bk, i64* cs, i64* bw, Map map) {
;     ...
;         const int kb = it / nblk, nb = it % nblk, k0 = 64 * kb, n0 = 32 * nb, v0 = map(n0);
; #pragma unroll
;         for (int i = 0; i < 8; ++i) { const int kk = 8 * i + (lane >> 3), c4 = (lane & 7) * 4;
;             const f32x4 w4 = __builtin_nontemporal_load((const f32x4*)(W + (size_t)(k0 + kk) * N + n0 + c4)); LAS float* d = scr + kk * 33 + c4; d[0] = w4[0]; d[1] = w4[1]; d[2] = w4[2]; d[3] = w4[3]; }
;         LDS_WAIT(); asm volatile("" ::: "memory");
;         if (bk) {
;             const int n = lane & 31, kh = lane >> 5; float sb = 0.f, sc = 0.f;
; #pragma unroll 8
.LBB0_1208:
	s_andn2_saveexec_b64 s[70:71], s[56:57]
	s_cbranch_execz .LBB0_1214
	v_readlane_b32 s48, v252, 14
	v_readlane_b32 s49, v252, 15
	s_mov_b64 s[12:13], s[48:49]
	s_load_dwordx2 s[12:13], s[12:13], 0x88
	v_writelane_b32 v255, s66, 33
	v_readlane_b32 s56, v252, 12
	v_readlane_b32 s57, v252, 13
	v_writelane_b32 v255, s67, 34
	s_mov_b64 s[58:59], s[56:57]
	v_readlane_b32 s16, v255, 54
	v_readlane_b32 s17, v255, 55
	s_waitcnt lgkmcnt(0)
	s_add_u32 s16, s12, s16
	s_addc_u32 s17, s13, s17
	s_mov_b64 s[12:13], s[48:49]
	s_mov_b32 vcc_lo, s79
	s_load_dwordx2 s[78:79], s[12:13], 0x68
	v_readlane_b32 s12, v255, 56
	v_readlane_b32 s13, v255, 57
	s_lshl_b64 s[12:13], s[12:13], 2
	v_add_u32_e32 v10, 0xbe00, v0
	s_waitcnt lgkmcnt(0)
	s_add_u32 s12, s78, s12
	s_addc_u32 s13, s79, s13
	s_add_u32 s84, s12, 0x2000
	s_addc_u32 s85, s13, 0
	s_mov_b64 s[12:13], s[48:49]
	v_lshlrev_b32_e32 v0, 5, v0
	s_load_dwordx2 s[86:87], s[12:13], 0x70
	s_mov_b64 s[12:13], s[56:57]
	s_mov_b64 s[48:49], s[56:57]
	v_mov_b32_e32 v24, v220
	v_and_b32_e32 v8, 0x7e0, v0
	v_lshlrev_b32_e32 v184, 2, v8
	v_lshlrev_b32_e32 v2, 4, v24
	v_and_b32_e32 v23, 0xffc0, v10
	v_bfe_u32 v22, v24, 3, 3
	v_lshl_add_u64 v[0:1], s[16:17], 0, v[184:185]
	v_and_b32_e32 v184, 0x70, v2
	v_lshl_add_u64 v[4:5], v[0:1], 0, v[184:185]
	v_or_b32_e32 v0, v22, v23
	v_lshlrev_b32_e32 v6, 13, v0
	v_mov_b32_e32 v7, v185
	v_lshl_add_u64 v[0:1], v[4:5], 0, v[6:7]
	global_load_dwordx4 v[132:135], v[0:1], off nt
	v_mul_u32_u24_e32 v7, 0x84, v22
	v_add3_u32 v7, vcc_lo, v184, v7
	v_or_b32_e32 v13, 8, v22
	v_add_u32_e32 v9, 0x420, v7
	v_or_b32_e32 v12, 16, v22
	v_add_u32_e32 v11, 0xc60, v7
	v_readlane_b32 s66, v255, 25
	s_movk_i32 s56, 0x7c0
	v_readlane_b32 s67, v255, 26
	s_add_u32 s16, s78, s66
	s_addc_u32 s17, s79, s67
	v_and_b32_e32 v26, 31, v24
	v_and_or_b32 v27, v24, 32, v23
	v_and_b32_e32 v25, 63, v24
	v_or_b32_e32 v0, v13, v23
	v_lshlrev_b32_e32 v184, 13, v0
	v_lshl_add_u64 v[0:1], v[4:5], 0, v[184:185]
	global_load_dwordx4 v[136:139], v[0:1], off nt
	v_add_u32_e32 v0, 0x428, v7
	v_or_b32_e32 v0, v12, v23
	v_lshlrev_b32_e32 v184, 13, v0
	v_lshl_add_u64 v[0:1], v[4:5], 0, v[184:185]
	global_load_dwordx4 v[140:143], v[0:1], off nt
	v_add_u32_e32 v9, 0x840, v7
	v_add_u32_e32 v0, 0x848, v7
	v_or_b32_e32 v9, 24, v22
	v_or_b32_e32 v0, v9, v23
	v_lshlrev_b32_e32 v184, 13, v0
	v_lshl_add_u64 v[0:1], v[4:5], 0, v[184:185]
	global_load_dwordx4 v[144:147], v[0:1], off nt
	v_or_b32_e32 v184, 0x40000, v6
	v_add_u32_e32 v0, 0xc68, v7
	v_lshl_add_u64 v[0:1], v[4:5], 0, v[184:185]
	global_load_dwordx4 v[148:151], v[0:1], off nt
	v_add_u32_e32 v11, 0x1080, v7
	v_or_b32_e32 v184, 0x50000, v6
	v_add_u32_e32 v0, 0x1088, v7
	v_lshl_add_u64 v[0:1], v[4:5], 0, v[184:185]
	global_load_dwordx4 v[152:155], v[0:1], off nt
	v_add_u32_e32 v11, 0x14a0, v7
	v_or_b32_e32 v184, 0x60000, v6
	v_add_u32_e32 v0, 0x14a8, v7
	v_lshl_add_u64 v[0:1], v[4:5], 0, v[184:185]
	global_load_dwordx4 v[156:159], v[0:1], off nt
	v_add_u32_e32 v11, 0x18c0, v7
	v_or_b32_e32 v184, 0x70000, v6
	v_add_u32_e32 v0, 0x18c8, v7
	v_lshl_add_u64 v[0:1], v[4:5], 0, v[184:185]
	global_load_dwordx4 v[160:163], v[0:1], off nt
	v_add_u32_e32 v4, 0x1ce0, v7
	v_add_u32_e32 v0, 0x1ce8, v7
	s_waitcnt vmcnt(0)
	v_add_u32_e32 v164, 0x0, v7
	ds_write2_b32 v164, v132, v133 offset1:1
	ds_write2_b32 v164, v134, v135 offset0:2 offset1:3
	v_add_u32_e32 v164, 0x420, v7
	ds_write2_b32 v164, v136, v137 offset1:1
	ds_write2_b32 v164, v138, v139 offset0:2 offset1:3
	v_add_u32_e32 v164, 0x840, v7
	ds_write2_b32 v164, v140, v141 offset1:1
	ds_write2_b32 v164, v142, v143 offset0:2 offset1:3
	v_add_u32_e32 v164, 0xc60, v7
	ds_write2_b32 v164, v144, v145 offset1:1
	ds_write2_b32 v164, v146, v147 offset0:2 offset1:3
	v_add_u32_e32 v164, 0x1080, v7
	ds_write2_b32 v164, v148, v149 offset1:1
	ds_write2_b32 v164, v150, v151 offset0:2 offset1:3
	v_add_u32_e32 v164, 0x14a0, v7
	ds_write2_b32 v164, v152, v153 offset1:1
	ds_write2_b32 v164, v154, v155 offset0:2 offset1:3
	v_add_u32_e32 v164, 0x18c0, v7
	ds_write2_b32 v164, v156, v157 offset1:1
	ds_write2_b32 v164, v158, v159 offset0:2 offset1:3
	v_add_u32_e32 v164, 0x1ce0, v7
	ds_write2_b32 v164, v160, v161 offset1:1
	ds_write2_b32 v164, v162, v163 offset0:2 offset1:3
	v_lshrrev_b32_e32 v0, 5, v24
	v_and_b32_e32 v0, 1, v0
	v_lshlrev_b16_e32 v0, 5, v0
	v_bitop3_b16 v0, v10, v0, s56 bitop3:0xec
	s_waitcnt lgkmcnt(0)
	v_lshlrev_b32_sdwa v184, v227, v0 dst_sel:DWORD dst_unused:UNUSED_PAD src0_sel:DWORD src1_sel:WORD_0
	v_bfe_u32 v0, v24, 5, 1
	v_lshl_add_u64 v[4:5], s[16:17], 0, v[184:185]
	s_waitcnt lgkmcnt(0)
	s_add_u32 s16, s86, s66
	v_mul_u32_u24_e32 v0, 0x1080, v0
	s_addc_u32 s17, s87, s67
	v_lshlrev_b32_e32 v184, 2, v27
	v_lshl_or_b32 v0, v26, 2, v0
	v_mov_b32_e32 v10, 0
	v_lshl_add_u64 v[6:7], s[16:17], 0, v[184:185]
	v_add_u32_e32 v28, vcc_lo, v0
	s_mov_b64 s[86:87], 0
	v_mov_b32_e32 v11, v10
	s_movk_i32 s16, 0x2000
	s_mov_b64 s[56:57], 0x2000

; #define LAS __attribute__((address_space(3)))
; #define LDS_WAIT() asm volatile("s_waitcnt lgkmcnt(0)" ::: "memory")
; __device__ __forceinline__ unsigned pk2(float lo, float hi) { return f2bf(lo) | (f2bf(hi) << 16); }
; template <class Map>
; __device__ __forceinline__ void conv_item(const Frame& F, int it, const float* W, int K, int N, bf16_t* WT, const float* gk, int gmask, float gmul, const float* bk, i64* cs, i64* bw, Map map) {
;     ...
;         const int kb = it / nblk, nb = it % nblk, k0 = 64 * kb, n0 = 32 * nb, v0 = map(n0);
; #pragma unroll
;         for (int i = 0; i < 8; ++i) { const int kk = 8 * i + (lane >> 3), c4 = (lane & 7) * 4;
;             const f32x4 w4 = __builtin_nontemporal_load((const f32x4*)(W + (size_t)(k0 + kk) * N + n0 + c4)); LAS float* d = scr + kk * 33 + c4; d[0] = w4[0]; d[1] = w4[1]; d[2] = w4[2]; d[3] = w4[3]; }
;         LDS_WAIT(); asm volatile("" ::: "memory");
;     ...
;         const int c = lane & 7; float gl[8];
; #pragma unroll
;         for (int i = 0; i < 8; ++i) gl[i] = gk ? gk[(k0 + 8 * c + i) & gmask] * gmul : 1.0f;
; #pragma unroll
;         for (int j = 0; j < 4; ++j) { const int n = (lane >> 3) + 8 * j; const LAS float* s = scr + (8 * c) * 33 + n;
;             u32x4 o; o.x = pk2(s[0 * 33] * gl[0], s[1 * 33] * gl[1]); o.y = pk2(s[2 * 33] * gl[2], s[3 * 33] * gl[3]); o.z = pk2(s[4 * 33] * gl[4], s[5 * 33] * gl[5]); o.w = pk2(s[6 * 33] * gl[6], s[7 * 33] * gl[7]);
.LBB0_1215:
	s_andn2_saveexec_b64 s[42:43], s[42:43]
	s_cbranch_execz .LBB0_1217
	v_readlane_b32 s12, v252, 14
	v_readlane_b32 s13, v252, 15
	s_load_dwordx2 s[12:13], s[12:13], 0x80
	s_mul_i32 s16, s20, 0x2c00000
	v_add_u32_e32 v1, 0xd400, v0
	v_lshlrev_b32_e32 v0, 5, v0
	v_mov_b32_e32 v22, v220
	s_waitcnt lgkmcnt(0)
	s_add_u32 s16, s12, s16
	s_mul_hi_i32 s12, s20, 0x2c00000
	s_addc_u32 s17, s13, s12
	v_readlane_b32 s12, v252, 12
	v_readlane_b32 s13, v252, 13
	v_and_b32_e32 v2, 0x7e0, v0
	v_and_b32_e32 v23, 0xffc0, v1
	v_bfe_u32 v7, v22, 3, 3
	v_lshlrev_b32_e32 v184, 2, v2
	v_lshlrev_b32_e32 v3, 4, v22
	v_lshl_add_u64 v[0:1], s[16:17], 0, v[184:185]
	v_and_b32_e32 v184, 0x70, v3
	v_or_b32_e32 v3, v7, v23
	v_lshl_add_u64 v[0:1], v[0:1], 0, v[184:185]
	v_lshlrev_b32_e32 v12, 13, v3
	v_mov_b32_e32 v13, v185
	v_lshl_add_u64 v[4:5], v[0:1], 0, v[12:13]
	global_load_dwordx4 v[132:135], v[4:5], off nt
	v_mul_u32_u24_e32 v3, 0x84, v7
	v_or_b32_e32 v6, 8, v7
	v_add3_u32 v13, s79, v184, v3
	v_or_b32_e32 v3, v6, v23
	v_lshlrev_b32_e32 v184, 13, v3
	v_lshl_add_u64 v[4:5], v[0:1], 0, v[184:185]
	v_add_u32_e32 v3, 0x420, v13
	v_readlane_b32 s48, v255, 39
	s_add_u32 s12, s12, s48
	s_addc_u32 s13, s13, 0
	v_or_b32_e32 v6, v6, v2
	v_mul_u32_u24_e32 v6, 0x1600, v6
	global_load_dwordx4 v[136:139], v[4:5], off nt
	v_or_b32_e32 v4, 16, v7
	v_add_u32_e32 v3, 0x428, v13
	v_or_b32_e32 v3, v4, v23
	v_lshlrev_b32_e32 v184, 13, v3
	v_lshl_add_u64 v[8:9], v[0:1], 0, v[184:185]
	global_load_dwordx4 v[140:143], v[8:9], off nt
	v_add_u32_e32 v3, 0x840, v13
	v_or_b32_e32 v4, v4, v2
	v_mul_u32_u24_e32 v4, 0x1600, v4
	v_add_u32_e32 v3, 0x848, v13
	v_or_b32_e32 v3, 24, v7
	v_or_b32_e32 v5, v3, v23
	v_lshlrev_b32_e32 v184, 13, v5
	v_lshl_add_u64 v[8:9], v[0:1], 0, v[184:185]
	global_load_dwordx4 v[144:147], v[8:9], off nt
	v_add_u32_e32 v5, 0xc60, v13
	v_or_b32_e32 v184, 0x40000, v12
	v_add_u32_e32 v5, 0xc68, v13
	v_lshl_add_u64 v[8:9], v[0:1], 0, v[184:185]
	global_load_dwordx4 v[148:151], v[8:9], off nt
	v_add_u32_e32 v5, 0x1080, v13
	v_or_b32_e32 v184, 0x50000, v12
	v_add_u32_e32 v5, 0x1088, v13
	v_lshl_add_u64 v[8:9], v[0:1], 0, v[184:185]
	global_load_dwordx4 v[152:155], v[8:9], off nt
	v_add_u32_e32 v5, 0x14a0, v13
	v_or_b32_e32 v184, 0x60000, v12
	v_add_u32_e32 v5, 0x14a8, v13
	v_lshl_add_u64 v[8:9], v[0:1], 0, v[184:185]
	global_load_dwordx4 v[156:159], v[8:9], off nt
	v_add_u32_e32 v5, 0x18c0, v13
	v_or_b32_e32 v184, 0x70000, v12
	v_lshl_add_u64 v[0:1], v[0:1], 0, v[184:185]
	v_lshlrev_b32_e32 v184, 1, v23
	v_add_u32_e32 v5, 0x18c8, v13
	global_load_dwordx4 v[160:163], v[0:1], off nt
	v_add_u32_e32 v0, 0x1ce0, v13
	v_and_b32_e32 v5, 7, v22
	v_add_u32_e32 v0, 0x1ce8, v13
	s_waitcnt vmcnt(0)
	v_add_u32_e32 v164, 0x0, v13
	ds_write2_b32 v164, v132, v133 offset1:1
	ds_write2_b32 v164, v134, v135 offset0:2 offset1:3
	v_add_u32_e32 v164, 0x420, v13
	ds_write2_b32 v164, v136, v137 offset1:1
	ds_write2_b32 v164, v138, v139 offset0:2 offset1:3
	v_add_u32_e32 v164, 0x840, v13
	ds_write2_b32 v164, v140, v141 offset1:1
	ds_write2_b32 v164, v142, v143 offset0:2 offset1:3
	v_add_u32_e32 v164, 0xc60, v13
	ds_write2_b32 v164, v144, v145 offset1:1
	ds_write2_b32 v164, v146, v147 offset0:2 offset1:3
	v_add_u32_e32 v164, 0x1080, v13
	ds_write2_b32 v164, v148, v149 offset1:1
	ds_write2_b32 v164, v150, v151 offset0:2 offset1:3
	v_add_u32_e32 v164, 0x14a0, v13
	ds_write2_b32 v164, v152, v153 offset1:1
	ds_write2_b32 v164, v154, v155 offset0:2 offset1:3
	v_add_u32_e32 v164, 0x18c0, v13
	ds_write2_b32 v164, v156, v157 offset1:1
	ds_write2_b32 v164, v158, v159 offset0:2 offset1:3
	v_add_u32_e32 v164, 0x1ce0, v13
	ds_write2_b32 v164, v160, v161 offset1:1
	ds_write2_b32 v164, v162, v163 offset0:2 offset1:3
	s_waitcnt lgkmcnt(0)
	v_mul_u32_u24_e32 v8, 0x420, v5
	v_lshl_add_u64 v[0:1], s[12:13], 0, v[184:185]
	v_lshlrev_b32_e32 v184, 4, v5
	v_lshlrev_b32_e32 v5, 2, v7
	v_add3_u32 v5, s79, v8, v5
	ds_read_b32 v8, v5
	ds_read_b32 v9, v5 offset:132
	v_or_b32_e32 v7, v7, v2
	v_lshl_add_u64 v[0:1], v[0:1], 0, v[184:185]
	s_mov_b64 s[12:13], 0x5c00000
	s_waitcnt lgkmcnt(1)
	v_bfe_u32 v10, v8, 16, 1
	v_add3_u32 v8, v8, v10, s73
	s_waitcnt lgkmcnt(0)
	v_bfe_u32 v10, v9, 16, 1
	v_lshrrev_b32_e32 v8, 16, v8
	v_add3_u32 v9, v9, v10, s73
	v_and_or_b32 v8, v9, s72, v8
	ds_read_b32 v9, v5 offset:264
	ds_read_b32 v10, v5 offset:396
	v_mul_u32_u24_e32 v7, 0x1600, v7
	v_lshl_add_u64 v[0:1], v[0:1], 0, s[12:13]
	v_lshlrev_b32_e32 v184, 1, v7
	s_waitcnt lgkmcnt(1)
; #define LAS __attribute__((address_space(3)))
; #define LDS_WAIT() asm volatile("s_waitcnt lgkmcnt(0)" ::: "memory")
; __device__ __forceinline__ unsigned pk2(float lo, float hi) { return f2bf(lo) | (f2bf(hi) << 16); }
; template <class Map>
; __device__ __forceinline__ void conv_item(const Frame& F, int it, const float* W, int K, int N, bf16_t* WT, const float* gk, int gmask, float gmul, const float* bk, i64* cs, i64* bw, Map map) {
;     ...
;         for (int j = 0; j < 4; ++j) { const int n = (lane >> 3) + 8 * j; const LAS float* s = scr + (8 * c) * 33 + n;
;             u32x4 o; o.x = pk2(s[0 * 33] * gl[0], s[1 * 33] * gl[1]); o.y = pk2(s[2 * 33] * gl[2], s[3 * 33] * gl[3]); o.z = pk2(s[4 * 33] * gl[4], s[5 * 33] * gl[5]); o.w = pk2(s[6 * 33] * gl[6], s[7 * 33] * gl[7]);
;             __builtin_nontemporal_store(o, (u32x4*)(WT + (size_t)(v0 + n) * K + k0 + 8 * c)); }
;         LDS_WAIT(); asm volatile("" ::: "memory");
	v_bfe_u32 v11, v9, 16, 1
	v_add3_u32 v9, v9, v11, s73
	s_waitcnt lgkmcnt(0)
	v_bfe_u32 v11, v10, 16, 1
	v_lshrrev_b32_e32 v9, 16, v9
	v_add3_u32 v10, v10, v11, s73
	v_and_or_b32 v9, v10, s72, v9
	ds_read_b32 v10, v5 offset:528
	ds_read_b32 v11, v5 offset:660
	v_or_b32_e32 v2, v3, v2
	v_mul_u32_u24_e32 v2, 0x1600, v2
	s_waitcnt lgkmcnt(1)
	v_bfe_u32 v12, v10, 16, 1
	v_add3_u32 v10, v10, v12, s73
	s_waitcnt lgkmcnt(0)
	v_bfe_u32 v12, v11, 16, 1
	v_lshrrev_b32_e32 v10, 16, v10
	v_add3_u32 v11, v11, v12, s73
	v_and_or_b32 v10, v11, s72, v10
	ds_read_b32 v11, v5 offset:792
	ds_read_b32 v12, v5 offset:924
	s_waitcnt lgkmcnt(1)
	v_bfe_u32 v13, v11, 16, 1
	v_add3_u32 v11, v11, v13, s73
	s_waitcnt lgkmcnt(0)
	v_bfe_u32 v13, v12, 16, 1
	v_lshrrev_b32_e32 v11, 16, v11
	v_add3_u32 v12, v12, v13, s73
	v_and_or_b32 v11, v12, s72, v11
	v_lshl_add_u64 v[12:13], v[0:1], 0, v[184:185]
	flat_store_dwordx4 v[12:13], v[8:11] nt
	ds_read_b32 v7, v5 offset:32
	ds_read_b32 v8, v5 offset:164
	v_lshlrev_b32_e32 v184, 1, v6
	s_waitcnt lgkmcnt(0)
	v_bfe_u32 v9, v7, 16, 1
	v_add3_u32 v7, v7, v9, s73
	v_bfe_u32 v9, v8, 16, 1
	v_lshrrev_b32_e32 v7, 16, v7
	v_add3_u32 v8, v8, v9, s73
	v_and_or_b32 v8, v8, s72, v7
	ds_read_b32 v7, v5 offset:296
	ds_read_b32 v9, v5 offset:428
	s_waitcnt lgkmcnt(0)
	v_bfe_u32 v10, v7, 16, 1
	v_add3_u32 v7, v7, v10, s73
	v_bfe_u32 v10, v9, 16, 1
	v_lshrrev_b32_e32 v7, 16, v7
	v_add3_u32 v9, v9, v10, s73
	v_and_or_b32 v9, v9, s72, v7
	ds_read_b32 v7, v5 offset:560
	ds_read_b32 v10, v5 offset:692
	s_waitcnt lgkmcnt(0)
	v_bfe_u32 v11, v7, 16, 1
	v_add3_u32 v7, v7, v11, s73
	v_bfe_u32 v11, v10, 16, 1
	v_lshrrev_b32_e32 v7, 16, v7
	v_add3_u32 v10, v10, v11, s73
	v_and_or_b32 v10, v10, s72, v7
	ds_read_b32 v7, v5 offset:824
	ds_read_b32 v11, v5 offset:956
	s_waitcnt lgkmcnt(0)
	v_bfe_u32 v12, v7, 16, 1
	v_add3_u32 v7, v7, v12, s73
	v_bfe_u32 v12, v11, 16, 1
	v_lshrrev_b32_e32 v7, 16, v7
	v_add3_u32 v11, v11, v12, s73
	v_and_or_b32 v11, v11, s72, v7
	v_lshl_add_u64 v[6:7], v[0:1], 0, v[184:185]
	flat_store_dwordx4 v[6:7], v[8:11] nt
	ds_read_b32 v6, v5 offset:64
	ds_read_b32 v7, v5 offset:196
	v_lshlrev_b32_e32 v184, 1, v4
	s_waitcnt lgkmcnt(0)
	v_bfe_u32 v8, v6, 16, 1
	v_add3_u32 v6, v6, v8, s73
	v_bfe_u32 v8, v7, 16, 1
	v_lshrrev_b32_e32 v6, 16, v6
	v_add3_u32 v7, v7, v8, s73
	v_and_or_b32 v6, v7, s72, v6
	ds_read_b32 v7, v5 offset:328
	ds_read_b32 v8, v5 offset:460
	s_waitcnt lgkmcnt(0)
	v_bfe_u32 v9, v7, 16, 1
	v_add3_u32 v7, v7, v9, s73
	v_bfe_u32 v9, v8, 16, 1
	v_lshrrev_b32_e32 v7, 16, v7
	v_add3_u32 v8, v8, v9, s73
	v_and_or_b32 v7, v8, s72, v7
	ds_read_b32 v8, v5 offset:592
	ds_read_b32 v9, v5 offset:724
	s_waitcnt lgkmcnt(0)
	v_bfe_u32 v10, v8, 16, 1
	v_add3_u32 v8, v8, v10, s73
	v_bfe_u32 v10, v9, 16, 1
	v_lshrrev_b32_e32 v8, 16, v8
	v_add3_u32 v9, v9, v10, s73
	v_and_or_b32 v8, v9, s72, v8
	ds_read_b32 v9, v5 offset:856
	ds_read_b32 v10, v5 offset:988
	s_waitcnt lgkmcnt(0)
	v_bfe_u32 v11, v9, 16, 1
	v_add3_u32 v9, v9, v11, s73
	v_bfe_u32 v11, v10, 16, 1
	v_lshrrev_b32_e32 v9, 16, v9
	v_add3_u32 v10, v10, v11, s73
	v_and_or_b32 v9, v10, s72, v9
	v_lshl_add_u64 v[10:11], v[0:1], 0, v[184:185]
	flat_store_dwordx4 v[10:11], v[6:9] nt
	ds_read_b32 v4, v5 offset:96
	ds_read_b32 v6, v5 offset:228
	v_lshlrev_b32_e32 v184, 1, v2
	v_lshl_add_u64 v[0:1], v[0:1], 0, v[184:185]
	s_waitcnt lgkmcnt(0)
	v_bfe_u32 v7, v4, 16, 1
	v_add3_u32 v4, v4, v7, s73
	v_bfe_u32 v7, v6, 16, 1
	v_lshrrev_b32_e32 v4, 16, v4
	v_add3_u32 v6, v6, v7, s73
	v_and_or_b32 v6, v6, s72, v4
	ds_read_b32 v4, v5 offset:360
	ds_read_b32 v7, v5 offset:492
	s_waitcnt lgkmcnt(0)
	v_bfe_u32 v8, v4, 16, 1
	v_add3_u32 v4, v4, v8, s73
	v_bfe_u32 v8, v7, 16, 1
	v_lshrrev_b32_e32 v4, 16, v4
	v_add3_u32 v7, v7, v8, s73
	v_and_or_b32 v7, v7, s72, v4
	ds_read_b32 v4, v5 offset:624
	ds_read_b32 v8, v5 offset:756
	s_waitcnt lgkmcnt(0)
	v_bfe_u32 v9, v4, 16, 1
	v_add3_u32 v4, v4, v9, s73
	v_bfe_u32 v9, v8, 16, 1
	v_lshrrev_b32_e32 v4, 16, v4
	v_add3_u32 v8, v8, v9, s73
	v_and_or_b32 v8, v8, s72, v4
	ds_read_b32 v4, v5 offset:888
	ds_read_b32 v5, v5 offset:1020
	s_waitcnt lgkmcnt(0)
	v_bfe_u32 v9, v4, 16, 1
	v_add3_u32 v4, v4, v9, s73
	v_bfe_u32 v9, v5, 16, 1
	v_lshrrev_b32_e32 v4, 16, v4
	v_add3_u32 v5, v5, v9, s73
	v_and_or_b32 v9, v5, s72, v4
	flat_store_dwordx4 v[0:1], v[6:9] nt
	s_waitcnt lgkmcnt(0)

; #define LAS __attribute__((address_space(3)))
; #define LDS_WAIT() asm volatile("s_waitcnt lgkmcnt(0)" ::: "memory")
; __device__ __forceinline__ float bf_round(float f) { return __uint_as_float(f2bf(f) << 16); }
; template <class Map>
; __device__ __forceinline__ void conv_item(const Frame& F, int it, const float* W, int K, int N, bf16_t* WT, const float* gk, int gmask, float gmul, const float* bk, i64* cs, i64* bw, Map map) {
;     ...
;         const int kb = it / nblk, nb = it % nblk, k0 = 64 * kb, n0 = 32 * nb, v0 = map(n0);
; #pragma unroll
;         for (int i = 0; i < 8; ++i) { const int kk = 8 * i + (lane >> 3), c4 = (lane & 7) * 4;
;             const f32x4 w4 = __builtin_nontemporal_load((const f32x4*)(W + (size_t)(k0 + kk) * N + n0 + c4)); LAS float* d = scr + kk * 33 + c4; d[0] = w4[0]; d[1] = w4[1]; d[2] = w4[2]; d[3] = w4[3]; }
;         LDS_WAIT(); asm volatile("" ::: "memory");
;         if (bk) {
;             const int n = lane & 31, kh = lane >> 5; float sb = 0.f, sc = 0.f;
; #pragma unroll 8
;             for (int j = 0; j < 32; ++j) { const int kk = kh * 32 + j; const float w = scr[kk * 33 + n]; sb += bk[k0 + kk] * w; sc += bf_round(gk[(k0 + kk) & gmask] * gmul * w); }
.LBB0_1218:
	s_andn2_saveexec_b64 s[24:25], s[24:25]
	s_cbranch_execz .LBB0_1242
	v_readlane_b32 s42, v252, 14
	v_readlane_b32 s43, v252, 15
	s_mov_b64 s[12:13], s[42:43]
	s_load_dwordx2 s[12:13], s[12:13], 0x78
	s_mul_i32 s16, s20, 0x5800000
	v_readlane_b32 s86, v252, 12
	v_readlane_b32 s87, v252, 13
	s_mov_b64 s[56:57], s[86:87]
	s_waitcnt lgkmcnt(0)
	s_add_u32 s78, s12, s16
	s_mul_hi_i32 s12, s20, 0x5800000
	s_addc_u32 s79, s13, s12
	s_mov_b64 s[12:13], s[42:43]
	s_load_dwordx2 s[84:85], s[12:13], 0x68
	v_readlane_b32 s12, v255, 56
	s_mov_b32 s16, 0xba2f
	v_readlane_b32 s13, v255, 57
	v_mul_u32_u24_sdwa v1, v0, s16 dst_sel:DWORD dst_unused:UNUSED_PAD src0_sel:WORD_0 src1_sel:DWORD
	s_movk_i32 s16, 0x160
	s_lshl_b64 s[12:13], s[12:13], 2
	v_mul_lo_u16_sdwa v2, v1, s16 dst_sel:DWORD dst_unused:UNUSED_PAD src0_sel:BYTE_3 src1_sel:DWORD
	s_waitcnt lgkmcnt(0)
	s_add_u32 s70, s84, s12
	v_sub_u16_e32 v2, v0, v2
	v_mov_b32_e32 v4, 6
	s_movk_i32 s16, 0xaf
	s_addc_u32 s71, s85, s13
	s_mov_b64 s[12:13], s[42:43]
	v_lshlrev_b16_sdwa v26, v4, v1 dst_sel:DWORD dst_unused:UNUSED_PAD src0_sel:DWORD src1_sel:BYTE_3
	v_lshlrev_b16_e32 v1, 5, v2
	v_cmp_lt_u16_e32 vcc, s16, v2
	s_movk_i32 s16, 0xb0
	s_mov_b64 s[48:49], s[86:87]
	v_mov_b32_e32 v3, v220
	v_add_u16_e32 v4, 0xea00, v1
	v_cmp_gt_u16_e64 s[42:43], s16, v2
	s_load_dwordx2 s[12:13], s[12:13], 0x70
	v_lshlrev_b32_e32 v184, 2, v1
	v_cndmask_b32_e64 v2, v4, v1, s[42:43]
	v_mov_b32_e32 v4, 1
	v_bfe_u32 v25, v3, 3, 3
	v_lshlrev_b32_e32 v1, 4, v3
	v_lshlrev_b32_sdwa v10, v4, sext(v2) dst_sel:DWORD dst_unused:UNUSED_PAD src0_sel:DWORD src1_sel:WORD_0
	v_lshl_add_u64 v[4:5], s[78:79], 0, v[184:185]
	v_and_b32_e32 v184, 0x70, v1
	v_or_b32_e32 v1, v25, v26
	v_lshl_add_u64 v[8:9], v[4:5], 0, v[184:185]
	v_mul_u32_u24_e32 v4, 0xb000, v1
	v_mov_b32_e32 v5, v185
	v_lshl_add_u64 v[4:5], v[8:9], 0, v[4:5]
	global_load_dwordx4 v[132:135], v[4:5], off nt
	v_readlane_b32 s79, v255, 17
	v_mul_u32_u24_e32 v12, 0x84, v25
	v_or_b32_e32 v24, 8, v25
	v_add3_u32 v12, s79, v184, v12
	v_add_u32_e32 v13, 0x420, v12
	v_or_b32_e32 v23, 16, v25
	v_or_b32_e32 v22, 24, v25
	s_movk_i32 s16, 0x60
	v_cndmask_b32_e32 v11, 0, v228, vcc
	v_and_b32_sdwa v2, sext(v2), s16 dst_sel:DWORD dst_unused:UNUSED_PAD src0_sel:WORD_0 src1_sel:DWORD
	s_waitcnt lgkmcnt(0)
	s_cmp_eq_u64 s[12:13], 0
	v_or_b32_e32 v4, v24, v26
	v_mul_u32_u24_e32 v184, 0xb000, v4
	v_lshl_add_u64 v[4:5], v[8:9], 0, v[184:185]
	global_load_dwordx4 v[136:139], v[4:5], off nt
	v_add_u32_e32 v4, 0x428, v12
	v_or_b32_e32 v4, v23, v26
	v_mul_u32_u24_e32 v184, 0xb000, v4
	v_lshl_add_u64 v[4:5], v[8:9], 0, v[184:185]
	global_load_dwordx4 v[140:143], v[4:5], off nt
	v_add_u32_e32 v13, 0x840, v12
	v_add_u32_e32 v4, 0x848, v12
	v_or_b32_e32 v4, v22, v26
	v_mul_u32_u24_e32 v184, 0xb000, v4
	v_lshl_add_u64 v[4:5], v[8:9], 0, v[184:185]
	global_load_dwordx4 v[144:147], v[4:5], off nt
	v_add_u32_e32 v13, 0xc60, v12
	v_add_u32_e32 v4, 0xc68, v12
	v_or_b32_e32 v4, 32, v1
	v_mul_u32_u24_e32 v184, 0xb000, v4
	v_lshl_add_u64 v[4:5], v[8:9], 0, v[184:185]
	global_load_dwordx4 v[148:151], v[4:5], off nt
	v_add_u32_e32 v13, 0x1080, v12
	v_add_u32_e32 v4, 0x1088, v12
	v_or_b32_e32 v4, 40, v1
	v_mul_u32_u24_e32 v184, 0xb000, v4
	v_lshl_add_u64 v[4:5], v[8:9], 0, v[184:185]
	global_load_dwordx4 v[152:155], v[4:5], off nt
	v_add_u32_e32 v13, 0x14a0, v12
	v_add_u32_e32 v4, 0x14a8, v12
	v_or_b32_e32 v4, 48, v1
	v_mul_u32_u24_e32 v184, 0xb000, v4
	v_lshl_add_u64 v[4:5], v[8:9], 0, v[184:185]
	global_load_dwordx4 v[156:159], v[4:5], off nt
	v_add_u32_e32 v13, 0x18c0, v12
	v_or_b32_e32 v1, 56, v1
	v_mul_u32_u24_e32 v184, 0xb000, v1
	v_add_u32_e32 v1, 0x1ce0, v12
	v_add_u32_e32 v4, 0x18c8, v12
	v_lshl_add_u64 v[4:5], v[8:9], 0, v[184:185]
	global_load_dwordx4 v[160:163], v[4:5], off nt
	v_add_u32_e32 v1, 0x1ce8, v12
	s_waitcnt vmcnt(0)
	v_add_u32_e32 v164, 0x0, v12
	ds_write2_b32 v164, v132, v133 offset1:1
	ds_write2_b32 v164, v134, v135 offset0:2 offset1:3
	v_add_u32_e32 v164, 0x420, v12
	ds_write2_b32 v164, v136, v137 offset1:1
	ds_write2_b32 v164, v138, v139 offset0:2 offset1:3
	v_add_u32_e32 v164, 0x840, v12
	ds_write2_b32 v164, v140, v141 offset1:1
	ds_write2_b32 v164, v142, v143 offset0:2 offset1:3
	v_add_u32_e32 v164, 0xc60, v12
	ds_write2_b32 v164, v144, v145 offset1:1
	ds_write2_b32 v164, v146, v147 offset0:2 offset1:3
	v_add_u32_e32 v164, 0x1080, v12
	ds_write2_b32 v164, v148, v149 offset1:1
	ds_write2_b32 v164, v150, v151 offset0:2 offset1:3
	v_add_u32_e32 v164, 0x14a0, v12
	ds_write2_b32 v164, v152, v153 offset1:1
	ds_write2_b32 v164, v154, v155 offset0:2 offset1:3
	v_add_u32_e32 v164, 0x18c0, v12
	ds_write2_b32 v164, v156, v157 offset1:1
	ds_write2_b32 v164, v158, v159 offset0:2 offset1:3
	v_add_u32_e32 v164, 0x1ce0, v12
	ds_write2_b32 v164, v160, v161 offset1:1
	ds_write2_b32 v164, v162, v163 offset0:2 offset1:3
	s_waitcnt lgkmcnt(0)
	v_and_b32_e32 v1, 0xffffff00, v10
	v_or3_b32 v4, v2, v11, v1
	s_cbranch_scc1 .LBB0_1225
	v_and_b32_e32 v1, 32, v3
	v_readlane_b32 s42, v255, 25
	v_readlane_b32 s43, v255, 26
	s_add_u32 s12, s12, s42
	v_add_u32_e32 v28, v26, v1
	s_mov_b32 s16, 0xba2e8c
	v_lshrrev_b32_e32 v1, 5, v3
	v_bfe_u32 v2, v3, 5, 1
	s_addc_u32 s13, s13, s43
	v_lshlrev_b32_e32 v184, 2, v28
	v_mul_hi_u32_u24_sdwa v0, v0, s16 dst_sel:DWORD dst_unused:UNUSED_PAD src0_sel:WORD_0 src1_sel:DWORD
	v_lshlrev_b32_e32 v8, 7, v2
	v_and_b32_e32 v1, 1, v1
	v_lshl_add_u64 v[6:7], s[12:13], 0, v[184:185]
	v_lshl_or_b32 v184, v0, 8, v8
	v_lshlrev_b16_e32 v0, 6, v0
	v_lshlrev_b16_e32 v1, 5, v1
	v_or_b32_e32 v0, v0, v1
	v_and_b32_e32 v0, 0x7e0, v0
	v_and_b32_e32 v27, 31, v3
	v_lshl_add_u64 v[8:9], s[12:13], 0, v[184:185]
	v_lshlrev_b32_e32 v184, 2, v0
	v_mul_u32_u24_e32 v0, 0x1080, v2
	s_add_u32 s12, s84, s42
	v_lshl_or_b32 v0, v27, 2, v0
	s_addc_u32 s13, s85, s43
	v_add_u32_e32 v29, s79, v0
	v_mov_b32_e32 v0, 0
	v_and_b32_e32 v5, 63, v3
	v_lshl_add_u64 v[10:11], s[12:13], 0, v[184:185]
	s_mov_b64 s[12:13], 0
	v_mov_b32_e32 v1, v0

; #define LAS __attribute__((address_space(3)))
; __device__ __forceinline__ void atomic_addq(i64* p, float v, float scale) { (void)__hip_atomic_fetch_add((unsigned long long*)p, (unsigned long long)(i64)__builtin_rintf(v * scale), __ATOMIC_RELAXED, __HIP_MEMORY_SCOPE_AGENT); }
; #define F_LANE() (tid_of(F.wave) & 63)
; #define INP(i) (kargs()->in[i])
; template <class Map>
; __device__ __forceinline__ void conv_item(const Frame& F, int it, const float* W, int K, int N, bf16_t* WT, const float* gk, int gmask, float gmul, const float* bk, i64* cs, i64* bw, Map map) {
;     LAS float* scr = (LAS float*)(F.lds + F.wave * 16384);
;     const int lane = F_LANE(), nblk = N / 32;
;     {
;         const int kb = it / nblk, nb = it % nblk, k0 = 64 * kb, n0 = 32 * nb, v0 = map(n0);
; #pragma unroll
;         for (int i = 0; i < 8; ++i) { const int kk = 8 * i + (lane >> 3), c4 = (lane & 7) * 4;
;             const f32x4 w4 = __builtin_nontemporal_load((const f32x4*)(W + (size_t)(k0 + kk) * N + n0 + c4)); LAS float* d = scr + kk * 33 + c4; d[0] = w4[0]; d[1] = w4[1]; d[2] = w4[2]; d[3] = w4[3]; }
;         LDS_WAIT(); asm volatile("" ::: "memory");
;         if (bk) {
;             const int n = lane & 31, kh = lane >> 5; float sb = 0.f, sc = 0.f;
; #pragma unroll 8
;             for (int j = 0; j < 32; ++j) { const int kk = kh * 32 + j; const float w = scr[kk * 33 + n]; sb += bk[k0 + kk] * w; sc += bf_round(gk[(k0 + kk) & gmask] * gmul * w); }
;             { auto r = __builtin_amdgcn_permlane32_swap(__float_as_uint(sb), __float_as_uint(sb), false, false); sb = __uint_as_float(r[0]) + __uint_as_float(r[1]); }
;             { auto r = __builtin_amdgcn_permlane32_swap(__float_as_uint(sc), __float_as_uint(sc), false, false); sc = __uint_as_float(r[0]) + __uint_as_float(r[1]); }
;             if (lane < 32) { atomic_addq(bw + v0 + n, sb, FX_COL); atomic_addq(cs + v0 + n, sc, FX_COL); }
;         }
;         const int c = lane & 7; float gl[8];
; #pragma unroll
;         for (int i = 0; i < 8; ++i) gl[i] = gk ? gk[(k0 + 8 * c + i) & gmask] * gmul : 1.0f;
; __device__ BG_ATTR void bg_item(const Frame& F, unsigned char* ws, const int L, int id) {
;     ...
;         if (id < NI_UKV) { conv_item(F, id, INP(6) + (size_t)j * MLA_RANK * 4096, MLA_RANK, 4096, Wukv, INP(4) + j * MLA_RANK, MLA_RANK - 1, 1.f, nullptr, nullptr, nullptr, MapIdent()); return; } id -= NI_UKV;
.LBB0_1244:
	v_readlane_b32 s24, v252, 14
	v_readlane_b32 s25, v252, 15
	s_mov_b64 s[12:13], s[24:25]
	s_load_dwordx2 s[12:13], s[12:13], 0x30
	v_add_u32_e32 v0, 0xfffff8c0, v21
	v_lshrrev_b32_e32 v1, 1, v0
	v_lshlrev_b32_e32 v0, 5, v0
	v_mov_b32_e32 v22, v220
	s_waitcnt lgkmcnt(0)
	s_add_u32 s16, s12, s96
	s_addc_u32 s17, s13, s97
	v_readlane_b32 s12, v252, 12
	v_readlane_b32 s13, v252, 13
	v_and_b32_e32 v8, 0xfe0, v0
	s_load_dwordx2 s[26:27], s[24:25], 0x20
	v_lshlrev_b32_e32 v184, 2, v8
	v_lshlrev_b32_e32 v2, 4, v22
	v_and_b32_e32 v13, 0x7fc0, v1
	v_bfe_u32 v12, v22, 3, 3
	v_lshl_add_u64 v[0:1], s[16:17], 0, v[184:185]
	v_and_b32_e32 v184, 0x70, v2
	v_lshl_add_u64 v[4:5], v[0:1], 0, v[184:185]
	v_or_b32_e32 v0, v12, v13
	v_lshlrev_b32_e32 v6, 14, v0
	v_mov_b32_e32 v7, v185
	v_lshl_add_u64 v[0:1], v[4:5], 0, v[6:7]
	global_load_dwordx4 v[132:135], v[0:1], off nt
	v_mul_u32_u24_e32 v7, 0x84, v12
	v_add3_u32 v7, s79, v184, v7
	v_or_b32_e32 v11, 8, v12
	v_add_u32_e32 v9, 0x420, v7
	v_or_b32_e32 v10, 16, v12
	v_add_u32_e32 v23, 0xc60, v7
	s_lshl_b64 s[24:25], s[90:91], 2
	s_waitcnt lgkmcnt(0)
	s_add_u32 s24, s26, s24
	v_and_b32_e32 v22, 7, v22
	s_addc_u32 s25, s27, s25
	s_cmp_lg_u64 s[26:27], 0
	s_cselect_b64 s[30:31], -1, 0
	s_cmp_eq_u64 s[26:27], 0
	v_or_b32_e32 v0, v11, v13
	v_lshlrev_b32_e32 v184, 14, v0
	v_lshl_add_u64 v[0:1], v[4:5], 0, v[184:185]
	global_load_dwordx4 v[136:139], v[0:1], off nt
	v_add_u32_e32 v0, 0x428, v7
	v_or_b32_e32 v0, v10, v13
	v_lshlrev_b32_e32 v184, 14, v0
	v_lshl_add_u64 v[0:1], v[4:5], 0, v[184:185]
	global_load_dwordx4 v[140:143], v[0:1], off nt
	v_add_u32_e32 v9, 0x840, v7
	v_add_u32_e32 v0, 0x848, v7
	v_or_b32_e32 v9, 24, v12
	v_or_b32_e32 v0, v9, v13
	v_lshlrev_b32_e32 v184, 14, v0
	v_lshl_add_u64 v[0:1], v[4:5], 0, v[184:185]
	global_load_dwordx4 v[144:147], v[0:1], off nt
	v_or_b32_e32 v184, 0x80000, v6
	v_add_u32_e32 v0, 0xc68, v7
	v_lshl_add_u64 v[0:1], v[4:5], 0, v[184:185]
	global_load_dwordx4 v[148:151], v[0:1], off nt
	v_add_u32_e32 v23, 0x1080, v7
	v_or_b32_e32 v184, 0xa0000, v6
	v_add_u32_e32 v0, 0x1088, v7
	v_lshl_add_u64 v[0:1], v[4:5], 0, v[184:185]
	global_load_dwordx4 v[152:155], v[0:1], off nt
	v_add_u32_e32 v23, 0x14a0, v7
	v_or_b32_e32 v184, 0xc0000, v6
	v_add_u32_e32 v0, 0x14a8, v7
	v_lshl_add_u64 v[0:1], v[4:5], 0, v[184:185]
	global_load_dwordx4 v[156:159], v[0:1], off nt
	v_add_u32_e32 v23, 0x18c0, v7
	v_or_b32_e32 v184, 0xe0000, v6
	v_add_u32_e32 v0, 0x18c8, v7
	v_lshl_add_u64 v[0:1], v[4:5], 0, v[184:185]
	global_load_dwordx4 v[160:163], v[0:1], off nt
	v_add_u32_e32 v4, 0x1ce0, v7
	v_lshlrev_b32_e32 v23, 3, v22
	v_add_u32_e32 v0, 0x1ce8, v7
	s_waitcnt vmcnt(0)
	v_add_u32_e32 v164, 0x0, v7
	ds_write2_b32 v164, v132, v133 offset1:1
	ds_write2_b32 v164, v134, v135 offset0:2 offset1:3
	v_add_u32_e32 v164, 0x420, v7
	ds_write2_b32 v164, v136, v137 offset1:1
	ds_write2_b32 v164, v138, v139 offset0:2 offset1:3
	v_add_u32_e32 v164, 0x840, v7
	ds_write2_b32 v164, v140, v141 offset1:1
	ds_write2_b32 v164, v142, v143 offset0:2 offset1:3
	v_add_u32_e32 v164, 0xc60, v7
	ds_write2_b32 v164, v144, v145 offset1:1
	ds_write2_b32 v164, v146, v147 offset0:2 offset1:3
	v_add_u32_e32 v164, 0x1080, v7
	ds_write2_b32 v164, v148, v149 offset1:1
	ds_write2_b32 v164, v150, v151 offset0:2 offset1:3
	v_add_u32_e32 v164, 0x14a0, v7
	ds_write2_b32 v164, v152, v153 offset1:1
	ds_write2_b32 v164, v154, v155 offset0:2 offset1:3
	v_add_u32_e32 v164, 0x18c0, v7
	ds_write2_b32 v164, v156, v157 offset1:1
	ds_write2_b32 v164, v158, v159 offset0:2 offset1:3
	v_add_u32_e32 v164, 0x1ce0, v7
	ds_write2_b32 v164, v160, v161 offset1:1
	ds_write2_b32 v164, v162, v163 offset0:2 offset1:3
	s_waitcnt lgkmcnt(0)
	v_or_b32_e32 v1, v23, v13
	v_mov_b32_e32 v0, 1.0
	v_lshlrev_b32_e32 v24, 2, v1
	v_mov_b32_e32 v2, 1.0
	s_cbranch_scc1 .LBB0_1246
	global_load_dword v2, v24, s[24:25]

; #define LAS __attribute__((address_space(3)))
; __device__ __forceinline__ void atomic_addq(i64* p, float v, float scale) { (void)__hip_atomic_fetch_add((unsigned long long*)p, (unsigned long long)(i64)__builtin_rintf(v * scale), __ATOMIC_RELAXED, __HIP_MEMORY_SCOPE_AGENT); }
; #define F_LANE() (tid_of(F.wave) & 63)
; #define INP(i) (kargs()->in[i])
; template <class Map>
; __device__ __forceinline__ void conv_item(const Frame& F, int it, const float* W, int K, int N, bf16_t* WT, const float* gk, int gmask, float gmul, const float* bk, i64* cs, i64* bw, Map map) {
;     LAS float* scr = (LAS float*)(F.lds + F.wave * 16384);
;     const int lane = F_LANE(), nblk = N / 32;
;     {
;         const int kb = it / nblk, nb = it % nblk, k0 = 64 * kb, n0 = 32 * nb, v0 = map(n0);
; #pragma unroll
;         for (int i = 0; i < 8; ++i) { const int kk = 8 * i + (lane >> 3), c4 = (lane & 7) * 4;
;             const f32x4 w4 = __builtin_nontemporal_load((const f32x4*)(W + (size_t)(k0 + kk) * N + n0 + c4)); LAS float* d = scr + kk * 33 + c4; d[0] = w4[0]; d[1] = w4[1]; d[2] = w4[2]; d[3] = w4[3]; }
;         LDS_WAIT(); asm volatile("" ::: "memory");
;         if (bk) {
;             const int n = lane & 31, kh = lane >> 5; float sb = 0.f, sc = 0.f;
; #pragma unroll 8
;             for (int j = 0; j < 32; ++j) { const int kk = kh * 32 + j; const float w = scr[kk * 33 + n]; sb += bk[k0 + kk] * w; sc += bf_round(gk[(k0 + kk) & gmask] * gmul * w); }
;             { auto r = __builtin_amdgcn_permlane32_swap(__float_as_uint(sb), __float_as_uint(sb), false, false); sb = __uint_as_float(r[0]) + __uint_as_float(r[1]); }
;             { auto r = __builtin_amdgcn_permlane32_swap(__float_as_uint(sc), __float_as_uint(sc), false, false); sc = __uint_as_float(r[0]) + __uint_as_float(r[1]); }
;             if (lane < 32) { atomic_addq(bw + v0 + n, sb, FX_COL); atomic_addq(cs + v0 + n, sc, FX_COL); }
;         }
;         const int c = lane & 7; float gl[8];
; #pragma unroll
;         for (int i = 0; i < 8; ++i) gl[i] = gk ? gk[(k0 + 8 * c + i) & gmask] * gmul : 1.0f;
; __device__ BG_ATTR void bg_item(const Frame& F, unsigned char* ws, const int L, int id) {
;     ...
;         if (id < NI_UQ) { conv_item(F, id, INP(5) + (size_t)j * MLA_RANK * 3072, MLA_RANK, 3072, Wuq, INP(3) + j * MLA_RANK, MLA_RANK - 1, 1.f, nullptr, nullptr, nullptr, MapMlaUq()); return; } id -= NI_UQ;
.LBB0_1261:
	s_or_b64 exec, exec, s[6:7]
	s_and_saveexec_b64 s[6:7], s[40:41]
	s_xor_b64 s[6:7], exec, s[6:7]
	s_cbranch_execz .LBB0_1283
	v_add_u16_e32 v2, 0xfbc0, v21
	v_mul_u32_u24_e32 v1, 0xaaab, v2
	v_lshrrev_b32_e32 v1, 22, v1
	v_mul_lo_u16_e32 v3, 0x60, v1
	v_sub_u16_e32 v3, v2, v3
	v_lshlrev_b16_e32 v2, 5, v3
	v_mul_u32_u24_e32 v4, 0x2aab, v2
	v_lshrrev_b32_e32 v4, 21, v4
	v_readlane_b32 s24, v252, 14
	v_mul_lo_u16_e32 v4, 0xc0, v4
	v_readlane_b32 s25, v252, 15
	v_readlane_b32 s12, v252, 12
	v_mul_lo_u16_e32 v3, 0xab, v3
	v_sub_u16_e32 v4, v2, v4
	s_movk_i32 s26, 0x7f
	s_mov_b64 s[16:17], s[24:25]
	v_readlane_b32 s13, v252, 13
	v_mov_b32_e32 v0, v220
	v_lshrrev_b16_e32 v3, 10, v3
	v_cmp_lt_u16_e32 vcc, s26, v4
	s_and_saveexec_b64 s[26:27], vcc
	s_xor_b64 s[26:27], exec, s[26:27]
	v_lshlrev_b32_e32 v5, 6, v3
	v_and_b32_e32 v5, 0x700, v5
	v_lshlrev_b32_e32 v3, 5, v3
	v_lshl_add_u32 v4, v4, 2, v5
	v_and_b32_e32 v3, 0x60, v3
	s_movk_i32 s30, 0x600
	v_add3_u32 v8, v4, v3, s30
	s_or_saveexec_b64 s[30:31], s[26:27]
	s_load_dwordx2 s[16:17], s[16:17], 0x28
	s_nop 0
	s_load_dwordx2 s[26:27], s[24:25], 0x18
	s_xor_b64 exec, exec, s[30:31]
	v_lshl_or_b32 v8, v3, 7, v4
	s_or_b64 exec, exec, s[30:31]
	v_readlane_b32 s24, v255, 41
	s_waitcnt lgkmcnt(0)
	s_add_u32 s16, s16, s24
	v_readlane_b32 s24, v255, 35
	s_addc_u32 s17, s17, s24
	v_lshlrev_b16_e32 v13, 6, v1
	v_bfe_u32 v12, v0, 3, 3
	v_lshlrev_b32_e32 v184, 2, v2
	v_lshlrev_b32_e32 v1, 4, v0
	v_lshl_add_u64 v[2:3], s[16:17], 0, v[184:185]
	v_and_b32_e32 v184, 0x70, v1
	v_or_b32_e32 v1, v12, v13
	v_lshl_add_u64 v[6:7], v[2:3], 0, v[184:185]
	v_mul_u32_u24_e32 v2, 0x3000, v1
	v_mov_b32_e32 v3, v185
	v_lshl_add_u64 v[2:3], v[6:7], 0, v[2:3]
	global_load_dwordx4 v[132:135], v[2:3], off nt
	v_mul_u32_u24_e32 v9, 0x84, v12
	v_add3_u32 v22, s79, v184, v9
	v_or_b32_e32 v11, 8, v12
	v_add_u32_e32 v9, 0x420, v22
	v_or_b32_e32 v10, 16, v12
	v_add_u32_e32 v23, 0xc60, v22
	s_lshl_b64 s[24:25], s[90:91], 2
	s_add_u32 s24, s26, s24
	s_addc_u32 s25, s27, s25
	s_movk_i32 s16, 0x1c0
	s_cmp_lg_u64 s[26:27], 0
	s_cselect_b64 s[30:31], -1, 0
	s_cmp_eq_u64 s[26:27], 0
	v_or_b32_e32 v2, v11, v13
	v_mul_u32_u24_e32 v184, 0x3000, v2
	v_lshl_add_u64 v[2:3], v[6:7], 0, v[184:185]
	global_load_dwordx4 v[136:139], v[2:3], off nt
	v_add_u32_e32 v2, 0x428, v22
	v_or_b32_e32 v2, v10, v13
	v_mul_u32_u24_e32 v184, 0x3000, v2
	v_lshl_add_u64 v[2:3], v[6:7], 0, v[184:185]
	global_load_dwordx4 v[140:143], v[2:3], off nt
	v_add_u32_e32 v9, 0x840, v22
	v_add_u32_e32 v2, 0x848, v22
	v_or_b32_e32 v9, 24, v12
	v_or_b32_e32 v2, v9, v13
	v_mul_u32_u24_e32 v184, 0x3000, v2
	v_lshl_add_u64 v[2:3], v[6:7], 0, v[184:185]
	global_load_dwordx4 v[144:147], v[2:3], off nt
	v_add_u32_e32 v2, 0xc68, v22
	v_or_b32_e32 v2, 32, v1
	v_mul_u32_u24_e32 v184, 0x3000, v2
	v_lshl_add_u64 v[2:3], v[6:7], 0, v[184:185]
	global_load_dwordx4 v[148:151], v[2:3], off nt
	v_add_u32_e32 v23, 0x1080, v22
	v_add_u32_e32 v2, 0x1088, v22
	v_or_b32_e32 v2, 40, v1
	v_mul_u32_u24_e32 v184, 0x3000, v2
	v_lshl_add_u64 v[2:3], v[6:7], 0, v[184:185]
	global_load_dwordx4 v[152:155], v[2:3], off nt
	v_add_u32_e32 v23, 0x14a0, v22
	v_add_u32_e32 v2, 0x14a8, v22
	v_or_b32_e32 v2, 48, v1
	v_mul_u32_u24_e32 v184, 0x3000, v2
	v_lshl_add_u64 v[2:3], v[6:7], 0, v[184:185]
	global_load_dwordx4 v[156:159], v[2:3], off nt
	v_add_u32_e32 v23, 0x18c0, v22
	v_or_b32_e32 v1, 56, v1
	v_mul_u32_u24_e32 v184, 0x3000, v1
	v_add_u32_e32 v1, 0x1ce0, v22
	v_add_u32_e32 v2, 0x18c8, v22
	v_lshl_add_u64 v[2:3], v[6:7], 0, v[184:185]
	global_load_dwordx4 v[160:163], v[2:3], off nt
	v_add_u32_e32 v1, 0x1ce8, v22
	s_waitcnt vmcnt(0)
	v_add_u32_e32 v164, 0x0, v22
	ds_write2_b32 v164, v132, v133 offset1:1
	ds_write2_b32 v164, v134, v135 offset0:2 offset1:3
	v_add_u32_e32 v164, 0x420, v22
	ds_write2_b32 v164, v136, v137 offset1:1
	ds_write2_b32 v164, v138, v139 offset0:2 offset1:3
	v_add_u32_e32 v164, 0x840, v22
	ds_write2_b32 v164, v140, v141 offset1:1
	ds_write2_b32 v164, v142, v143 offset0:2 offset1:3
	v_add_u32_e32 v164, 0xc60, v22
	ds_write2_b32 v164, v144, v145 offset1:1
	ds_write2_b32 v164, v146, v147 offset0:2 offset1:3
	v_add_u32_e32 v164, 0x1080, v22
	ds_write2_b32 v164, v148, v149 offset1:1
	ds_write2_b32 v164, v150, v151 offset0:2 offset1:3
	v_add_u32_e32 v164, 0x14a0, v22
	ds_write2_b32 v164, v152, v153 offset1:1
	ds_write2_b32 v164, v154, v155 offset0:2 offset1:3
	v_add_u32_e32 v164, 0x18c0, v22
	ds_write2_b32 v164, v156, v157 offset1:1
	ds_write2_b32 v164, v158, v159 offset0:2 offset1:3
	v_add_u32_e32 v164, 0x1ce0, v22
	ds_write2_b32 v164, v160, v161 offset1:1
	ds_write2_b32 v164, v162, v163 offset0:2 offset1:3
	s_waitcnt lgkmcnt(0)
	v_and_b32_e32 v22, 7, v0
	v_lshlrev_b32_e32 v23, 3, v22
	v_and_or_b32 v1, v13, s16, v23
	v_mov_b32_e32 v0, 1.0
	v_lshlrev_b32_e32 v24, 2, v1
	v_mov_b32_e32 v2, 1.0
	s_cbranch_scc1 .LBB0_1268
	global_load_dword v2, v24, s[24:25]

; #define LAS __attribute__((address_space(3)))
; #define F_LANE() (tid_of(F.wave) & 63)
; #define LDS_WAIT() asm volatile("s_waitcnt lgkmcnt(0)" ::: "memory")
; template <class Map>
; __device__ __forceinline__ void conv_item(const Frame& F, int it, const float* W, int K, int N, bf16_t* WT, const float* gk, int gmask, float gmul, const float* bk, i64* cs, i64* bw, Map map) {
;     LAS float* scr = (LAS float*)(F.lds + F.wave * 16384);
;     const int lane = F_LANE(), nblk = N / 32;
;     {
;         const int kb = it / nblk, nb = it % nblk, k0 = 64 * kb, n0 = 32 * nb, v0 = map(n0);
; #pragma unroll
;         for (int i = 0; i < 8; ++i) { const int kk = 8 * i + (lane >> 3), c4 = (lane & 7) * 4;
;             const f32x4 w4 = __builtin_nontemporal_load((const f32x4*)(W + (size_t)(k0 + kk) * N + n0 + c4)); LAS float* d = scr + kk * 33 + c4; d[0] = w4[0]; d[1] = w4[1]; d[2] = w4[2]; d[3] = w4[3]; }
;         LDS_WAIT(); asm volatile("" ::: "memory");
;         if (bk) {
;             const int n = lane & 31, kh = lane >> 5; float sb = 0.f, sc = 0.f;
; #pragma unroll 8
;             for (int j = 0; j < 32; ++j) { const int kk = kh * 32 + j; const float w = scr[kk * 33 + n]; sb += bk[k0 + kk] * w; sc += bf_round(gk[(k0 + kk) & gmask] * gmul * w); }
;             { auto r = __builtin_amdgcn_permlane32_swap(__float_as_uint(sb), __float_as_uint(sb), false, false); sb = __uint_as_float(r[0]) + __uint_as_float(r[1]); }
;             { auto r = __builtin_amdgcn_permlane32_swap(__float_as_uint(sc), __float_as_uint(sc), false, false); sc = __uint_as_float(r[0]) + __uint_as_float(r[1]); }
;             if (lane < 32) { atomic_addq(bw + v0 + n, sb, FX_COL); atomic_addq(cs + v0 + n, sc, FX_COL); }
;         }
;         const int c = lane & 7; float gl[8];
; #pragma unroll
;         for (int i = 0; i < 8; ++i) gl[i] = gk ? gk[(k0 + 8 * c + i) & gmask] * gmul : 1.0f;
; #pragma unroll
;         for (int j = 0; j < 4; ++j) { const int n = (lane >> 3) + 8 * j; const LAS float* s = scr + (8 * c) * 33 + n;
;             u32x4 o; o.x = pk2(s[0 * 33] * gl[0], s[1 * 33] * gl[1]); o.y = pk2(s[2 * 33] * gl[2], s[3 * 33] * gl[3]); o.z = pk2(s[4 * 33] * gl[4], s[5 * 33] * gl[5]); o.w = pk2(s[6 * 33] * gl[6], s[7 * 33] * gl[7]);
;             __builtin_nontemporal_store(o, (u32x4*)(WT + (size_t)(v0 + n) * K + k0 + 8 * c)); }
.LBB0_1283:
	s_or_b64 exec, exec, s[6:7]
	s_and_saveexec_b64 s[6:7], s[10:11]
	s_cbranch_execz .LBB0_1285
	v_readlane_b32 s10, v252, 14
	v_readlane_b32 s11, v252, 15
	s_load_dwordx2 s[10:11], s[10:11], 0x10
	s_mov_b32 s16, 0xf0f1
	v_mul_u32_u24_sdwa v0, v21, s16 dst_sel:DWORD dst_unused:UNUSED_PAD src0_sel:WORD_0 src1_sel:DWORD
	v_lshrrev_b32_e32 v0, 21, v0
	v_mul_lo_u16_e32 v1, 34, v0
	s_waitcnt lgkmcnt(0)
	s_add_u32 s12, s10, s61
	s_addc_u32 s13, s11, s21
	v_readlane_b32 s10, v252, 12
	v_sub_u16_e32 v21, v21, v1
	v_readlane_b32 s11, v252, 13
	v_mov_b32_e32 v6, v220
	v_lshlrev_b16_e32 v23, 5, v21
	v_lshlrev_b16_e32 v22, 6, v0
	v_bfe_u32 v7, v6, 3, 3
	v_lshlrev_b32_e32 v184, 2, v23
	v_lshlrev_b32_e32 v2, 4, v6
	v_lshl_add_u64 v[0:1], s[12:13], 0, v[184:185]
	v_and_b32_e32 v184, 0x70, v2
	v_or_b32_e32 v25, v7, v22
	v_lshl_add_u64 v[12:13], v[0:1], 0, v[184:185]
	v_mul_u32_u24_e32 v0, 0x1100, v25
	v_mov_b32_e32 v1, v185
	v_lshl_add_u64 v[0:1], v[12:13], 0, v[0:1]
	global_load_dwordx4 v[132:135], v[0:1], off nt
	v_mul_u32_u24_e32 v4, 0x84, v7
	v_add3_u32 v26, s79, v184, v4
	v_or_b32_e32 v5, 8, v7
	v_add_u32_e32 v4, 0x420, v26
	v_add_u32_e32 v8, 0x840, v26
	v_add_u32_e32 v24, 0x60, v23
	v_cmp_gt_u16_e32 vcc, 33, v21
	v_or_b32_e32 v0, v5, v22
	v_mul_u32_u24_e32 v184, 0x1100, v0
	v_lshl_add_u64 v[0:1], v[12:13], 0, v[184:185]
	global_load_dwordx4 v[136:139], v[0:1], off nt
	v_add_u32_e32 v0, 0x428, v26
	v_or_b32_e32 v4, 16, v7
	v_or_b32_e32 v0, v4, v22
	v_mul_u32_u24_e32 v184, 0x1100, v0
	v_lshl_add_u64 v[0:1], v[12:13], 0, v[184:185]
	global_load_dwordx4 v[140:143], v[0:1], off nt
	v_add_u32_e32 v0, 0x848, v26
	v_or_b32_e32 v2, 24, v7
	v_or_b32_e32 v0, v2, v22
	v_mul_u32_u24_e32 v184, 0x1100, v0
	v_lshl_add_u64 v[0:1], v[12:13], 0, v[184:185]
	global_load_dwordx4 v[144:147], v[0:1], off nt
	v_add_u32_e32 v0, 0xc60, v26
	v_cndmask_b32_e32 v3, v24, v23, vcc
	v_or_b32_e32 v5, v5, v3
	v_or_b32_e32 v4, v4, v3
	v_or_b32_e32 v2, v2, v3
	v_add_u32_e32 v0, 0xc68, v26
	v_or_b32_e32 v0, 32, v25
	v_mul_u32_u24_e32 v184, 0x1100, v0
	v_lshl_add_u64 v[0:1], v[12:13], 0, v[184:185]
	global_load_dwordx4 v[148:151], v[0:1], off nt
	v_add_u32_e32 v0, 0x1080, v26
	v_add_u32_e32 v0, 0x1088, v26
	v_or_b32_e32 v0, 40, v25
	v_mul_u32_u24_e32 v184, 0x1100, v0
	v_lshl_add_u64 v[0:1], v[12:13], 0, v[184:185]
	global_load_dwordx4 v[152:155], v[0:1], off nt
	v_add_u32_e32 v0, 0x14a0, v26
	v_add_u32_e32 v0, 0x14a8, v26
	v_or_b32_e32 v0, 48, v25
	v_mul_u32_u24_e32 v184, 0x1100, v0
	v_lshl_add_u64 v[0:1], v[12:13], 0, v[184:185]
	global_load_dwordx4 v[156:159], v[0:1], off nt
	v_add_u32_e32 v0, 0x18c0, v26
	v_add_u32_e32 v0, 0x18c8, v26
	v_or_b32_e32 v0, 56, v25
	v_mul_u32_u24_e32 v184, 0x1100, v0
	v_lshl_add_u64 v[0:1], v[12:13], 0, v[184:185]
	global_load_dwordx4 v[160:163], v[0:1], off nt
	v_add_u32_e32 v0, 0x1ce0, v26
	v_lshlrev_b32_e32 v184, 1, v22
	v_add_u32_e32 v0, 0x1ce8, v26
	s_waitcnt vmcnt(0)
	v_add_u32_e32 v164, 0x0, v26
	ds_write2_b32 v164, v132, v133 offset1:1
	ds_write2_b32 v164, v134, v135 offset0:2 offset1:3
	v_add_u32_e32 v164, 0x420, v26
	ds_write2_b32 v164, v136, v137 offset1:1
	ds_write2_b32 v164, v138, v139 offset0:2 offset1:3
	v_add_u32_e32 v164, 0x840, v26
	ds_write2_b32 v164, v140, v141 offset1:1
	ds_write2_b32 v164, v142, v143 offset0:2 offset1:3
	v_add_u32_e32 v164, 0xc60, v26
	ds_write2_b32 v164, v144, v145 offset1:1
	ds_write2_b32 v164, v146, v147 offset0:2 offset1:3
	v_add_u32_e32 v164, 0x1080, v26
	ds_write2_b32 v164, v148, v149 offset1:1
	ds_write2_b32 v164, v150, v151 offset0:2 offset1:3
	v_add_u32_e32 v164, 0x14a0, v26
	ds_write2_b32 v164, v152, v153 offset1:1
	ds_write2_b32 v164, v154, v155 offset0:2 offset1:3
	v_add_u32_e32 v164, 0x18c0, v26
	ds_write2_b32 v164, v156, v157 offset1:1
	ds_write2_b32 v164, v158, v159 offset0:2 offset1:3
	v_add_u32_e32 v164, 0x1ce0, v26
	ds_write2_b32 v164, v160, v161 offset1:1
	ds_write2_b32 v164, v162, v163 offset0:2 offset1:3
	v_lshlrev_b32_e32 v0, 3, v6
	v_and_b32_e32 v6, 56, v0
	s_waitcnt lgkmcnt(0)
	v_mul_u32_u24_e32 v8, 0x84, v6
	v_lshl_add_u64 v[0:1], s[10:11], 0, v[184:185]
	v_lshlrev_b32_e32 v184, 1, v6
	v_lshlrev_b32_e32 v6, 2, v7
	v_add3_u32 v6, s79, v8, v6
	ds_read_b32 v8, v6
	ds_read_b32 v9, v6 offset:132
	v_lshl_add_u64 v[0:1], v[0:1], 0, v[184:185]
	s_mov_b64 s[10:11], 0x800000
	v_or_b32_e32 v7, v7, v3
	s_waitcnt lgkmcnt(1)
	v_bfe_u32 v10, v8, 16, 1
	v_add3_u32 v8, v8, v10, s73
	s_waitcnt lgkmcnt(0)
; #define LAS __attribute__((address_space(3)))
; #define LDS_WAIT() asm volatile("s_waitcnt lgkmcnt(0)" ::: "memory")
; __device__ __forceinline__ unsigned pk2(float lo, float hi) { return f2bf(lo) | (f2bf(hi) << 16); }
; template <class Map>
; __device__ __forceinline__ void conv_item(const Frame& F, int it, const float* W, int K, int N, bf16_t* WT, const float* gk, int gmask, float gmul, const float* bk, i64* cs, i64* bw, Map map) {
;     ...
;         const int c = lane & 7; float gl[8];
; #pragma unroll
;         for (int i = 0; i < 8; ++i) gl[i] = gk ? gk[(k0 + 8 * c + i) & gmask] * gmul : 1.0f;
; #pragma unroll
;         for (int j = 0; j < 4; ++j) { const int n = (lane >> 3) + 8 * j; const LAS float* s = scr + (8 * c) * 33 + n;
;             u32x4 o; o.x = pk2(s[0 * 33] * gl[0], s[1 * 33] * gl[1]); o.y = pk2(s[2 * 33] * gl[2], s[3 * 33] * gl[3]); o.z = pk2(s[4 * 33] * gl[4], s[5 * 33] * gl[5]); o.w = pk2(s[6 * 33] * gl[6], s[7 * 33] * gl[7]);
;             __builtin_nontemporal_store(o, (u32x4*)(WT + (size_t)(v0 + n) * K + k0 + 8 * c)); }
;         LDS_WAIT(); asm volatile("" ::: "memory");
	v_bfe_u32 v10, v9, 16, 1
	v_lshrrev_b32_e32 v8, 16, v8
	v_add3_u32 v9, v9, v10, s73
	v_and_or_b32 v8, v9, s72, v8
	ds_read_b32 v9, v6 offset:264
	ds_read_b32 v10, v6 offset:396
	v_lshl_add_u64 v[0:1], v[0:1], 0, s[10:11]
	v_lshlrev_b32_e32 v184, 12, v7
	s_waitcnt lgkmcnt(1)
	v_bfe_u32 v11, v9, 16, 1
	v_add3_u32 v9, v9, v11, s73
	s_waitcnt lgkmcnt(0)
	v_bfe_u32 v11, v10, 16, 1
	v_lshrrev_b32_e32 v9, 16, v9
	v_add3_u32 v10, v10, v11, s73
	v_and_or_b32 v9, v10, s72, v9
	ds_read_b32 v10, v6 offset:528
	ds_read_b32 v11, v6 offset:660
	s_waitcnt lgkmcnt(1)
	v_bfe_u32 v12, v10, 16, 1
	v_add3_u32 v10, v10, v12, s73
	s_waitcnt lgkmcnt(0)
	v_bfe_u32 v12, v11, 16, 1
	v_lshrrev_b32_e32 v10, 16, v10
	v_add3_u32 v11, v11, v12, s73
	v_and_or_b32 v10, v11, s72, v10
	ds_read_b32 v11, v6 offset:792
	ds_read_b32 v12, v6 offset:924
	s_waitcnt lgkmcnt(1)
	v_bfe_u32 v13, v11, 16, 1
	v_add3_u32 v11, v11, v13, s73
	s_waitcnt lgkmcnt(0)
	v_bfe_u32 v13, v12, 16, 1
	v_lshrrev_b32_e32 v11, 16, v11
	v_add3_u32 v12, v12, v13, s73
	v_and_or_b32 v11, v12, s72, v11
	v_lshl_add_u64 v[12:13], v[0:1], 0, v[184:185]
	flat_store_dwordx4 v[12:13], v[8:11] nt
	ds_read_b32 v7, v6 offset:32
	ds_read_b32 v8, v6 offset:164
	v_lshlrev_b32_e32 v184, 12, v5
	s_waitcnt lgkmcnt(0)
	v_bfe_u32 v9, v7, 16, 1
	v_add3_u32 v7, v7, v9, s73
	v_bfe_u32 v9, v8, 16, 1
	v_lshrrev_b32_e32 v7, 16, v7
	v_add3_u32 v8, v8, v9, s73
	v_and_or_b32 v8, v8, s72, v7
	ds_read_b32 v7, v6 offset:296
	ds_read_b32 v9, v6 offset:428
	s_waitcnt lgkmcnt(0)
	v_bfe_u32 v10, v7, 16, 1
	v_add3_u32 v7, v7, v10, s73
	v_bfe_u32 v10, v9, 16, 1
	v_lshrrev_b32_e32 v7, 16, v7
	v_add3_u32 v9, v9, v10, s73
	v_and_or_b32 v9, v9, s72, v7
	ds_read_b32 v7, v6 offset:560
	ds_read_b32 v10, v6 offset:692
	s_waitcnt lgkmcnt(0)
	v_bfe_u32 v11, v7, 16, 1
	v_add3_u32 v7, v7, v11, s73
	v_bfe_u32 v11, v10, 16, 1
	v_lshrrev_b32_e32 v7, 16, v7
	v_add3_u32 v10, v10, v11, s73
	v_and_or_b32 v10, v10, s72, v7
	ds_read_b32 v7, v6 offset:824
	ds_read_b32 v11, v6 offset:956
	s_waitcnt lgkmcnt(0)
	v_bfe_u32 v12, v7, 16, 1
	v_add3_u32 v7, v7, v12, s73
	v_bfe_u32 v12, v11, 16, 1
	v_lshrrev_b32_e32 v7, 16, v7
	v_add3_u32 v11, v11, v12, s73
	v_and_or_b32 v11, v11, s72, v7
	v_lshl_add_u64 v[12:13], v[0:1], 0, v[184:185]
	flat_store_dwordx4 v[12:13], v[8:11] nt
	ds_read_b32 v5, v6 offset:64
	ds_read_b32 v7, v6 offset:196
	v_lshlrev_b32_e32 v184, 12, v4
	s_waitcnt lgkmcnt(0)
	v_bfe_u32 v8, v5, 16, 1
	v_add3_u32 v5, v5, v8, s73
	v_bfe_u32 v8, v7, 16, 1
	v_lshrrev_b32_e32 v5, 16, v5
	v_add3_u32 v7, v7, v8, s73
	v_and_or_b32 v8, v7, s72, v5
	ds_read_b32 v5, v6 offset:328
	ds_read_b32 v7, v6 offset:460
	s_waitcnt lgkmcnt(0)
	v_bfe_u32 v9, v5, 16, 1
	v_add3_u32 v5, v5, v9, s73
	v_bfe_u32 v9, v7, 16, 1
	v_lshrrev_b32_e32 v5, 16, v5
	v_add3_u32 v7, v7, v9, s73
	v_and_or_b32 v9, v7, s72, v5
	ds_read_b32 v5, v6 offset:592
	ds_read_b32 v7, v6 offset:724
	s_waitcnt lgkmcnt(0)
	v_bfe_u32 v10, v5, 16, 1
	v_add3_u32 v5, v5, v10, s73
	v_bfe_u32 v10, v7, 16, 1
	v_lshrrev_b32_e32 v5, 16, v5
	v_add3_u32 v7, v7, v10, s73
	v_and_or_b32 v10, v7, s72, v5
	ds_read_b32 v5, v6 offset:856
	ds_read_b32 v7, v6 offset:988
	s_waitcnt lgkmcnt(0)
	v_bfe_u32 v11, v5, 16, 1
	v_add3_u32 v5, v5, v11, s73
	v_bfe_u32 v11, v7, 16, 1
	v_lshrrev_b32_e32 v5, 16, v5
	v_add3_u32 v7, v7, v11, s73
	v_and_or_b32 v11, v7, s72, v5
	v_lshl_add_u64 v[4:5], v[0:1], 0, v[184:185]
	flat_store_dwordx4 v[4:5], v[8:11] nt
	ds_read_b32 v4, v6 offset:96
	ds_read_b32 v5, v6 offset:228
	v_lshlrev_b32_e32 v184, 12, v2
	v_lshl_add_u64 v[0:1], v[0:1], 0, v[184:185]
	s_waitcnt lgkmcnt(0)
	v_bfe_u32 v7, v4, 16, 1
	v_add3_u32 v4, v4, v7, s73
	v_bfe_u32 v7, v5, 16, 1
	v_lshrrev_b32_e32 v4, 16, v4
	v_add3_u32 v5, v5, v7, s73
	v_and_or_b32 v8, v5, s72, v4
	ds_read_b32 v4, v6 offset:360
	ds_read_b32 v5, v6 offset:492
	s_waitcnt lgkmcnt(0)
	v_bfe_u32 v7, v4, 16, 1
	v_add3_u32 v4, v4, v7, s73
	v_bfe_u32 v7, v5, 16, 1
	v_lshrrev_b32_e32 v4, 16, v4
	v_add3_u32 v5, v5, v7, s73
	v_and_or_b32 v9, v5, s72, v4
	ds_read_b32 v4, v6 offset:624
	ds_read_b32 v5, v6 offset:756
	s_waitcnt lgkmcnt(0)
	v_bfe_u32 v7, v4, 16, 1
	v_add3_u32 v4, v4, v7, s73
	v_bfe_u32 v7, v5, 16, 1
	v_lshrrev_b32_e32 v4, 16, v4
	v_add3_u32 v5, v5, v7, s73
	v_and_or_b32 v10, v5, s72, v4
	ds_read_b32 v4, v6 offset:888
	ds_read_b32 v5, v6 offset:1020
	s_waitcnt lgkmcnt(0)
	v_bfe_u32 v6, v4, 16, 1
	v_add3_u32 v4, v4, v6, s73
	v_bfe_u32 v6, v5, 16, 1
	v_lshrrev_b32_e32 v4, 16, v4
	v_add3_u32 v5, v5, v6, s73
	v_and_or_b32 v11, v5, s72, v4
	flat_store_dwordx4 v[0:1], v[8:11] nt
	s_waitcnt lgkmcnt(0)

; #define LAS __attribute__((address_space(3)))
; __device__ __forceinline__ void atomic_addq(i64* p, float v, float scale) { (void)__hip_atomic_fetch_add((unsigned long long*)p, (unsigned long long)(i64)__builtin_rintf(v * scale), __ATOMIC_RELAXED, __HIP_MEMORY_SCOPE_AGENT); }
; #define F_LANE() (tid_of(F.wave) & 63)
; #define INP(i) (kargs()->in[i])
; template <class Map>
; __device__ __forceinline__ void conv_item(const Frame& F, int it, const float* W, int K, int N, bf16_t* WT, const float* gk, int gmask, float gmul, const float* bk, i64* cs, i64* bw, Map map) {
;     LAS float* scr = (LAS float*)(F.lds + F.wave * 16384);
;     const int lane = F_LANE(), nblk = N / 32;
;     {
;         const int kb = it / nblk, nb = it % nblk, k0 = 64 * kb, n0 = 32 * nb, v0 = map(n0);
; #pragma unroll
;         for (int i = 0; i < 8; ++i) { const int kk = 8 * i + (lane >> 3), c4 = (lane & 7) * 4;
;             const f32x4 w4 = __builtin_nontemporal_load((const f32x4*)(W + (size_t)(k0 + kk) * N + n0 + c4)); LAS float* d = scr + kk * 33 + c4; d[0] = w4[0]; d[1] = w4[1]; d[2] = w4[2]; d[3] = w4[3]; }
;         LDS_WAIT(); asm volatile("" ::: "memory");
;         if (bk) {
;             const int n = lane & 31, kh = lane >> 5; float sb = 0.f, sc = 0.f;
; #pragma unroll 8
;             for (int j = 0; j < 32; ++j) { const int kk = kh * 32 + j; const float w = scr[kk * 33 + n]; sb += bk[k0 + kk] * w; sc += bf_round(gk[(k0 + kk) & gmask] * gmul * w); }
;             { auto r = __builtin_amdgcn_permlane32_swap(__float_as_uint(sb), __float_as_uint(sb), false, false); sb = __uint_as_float(r[0]) + __uint_as_float(r[1]); }
;             { auto r = __builtin_amdgcn_permlane32_swap(__float_as_uint(sc), __float_as_uint(sc), false, false); sc = __uint_as_float(r[0]) + __uint_as_float(r[1]); }
;             if (lane < 32) { atomic_addq(bw + v0 + n, sb, FX_COL); atomic_addq(cs + v0 + n, sc, FX_COL); }
;         }
;         const int c = lane & 7; float gl[8];
; #pragma unroll
;         for (int i = 0; i < 8; ++i) gl[i] = gk ? gk[(k0 + 8 * c + i) & gmask] * gmul : 1.0f;
; __device__ BG_ATTR void bg_item(const Frame& F, unsigned char* ws, const int L, int id) {
;     ...
;         if (id < NI_O) { conv_item(F, id, INP(11) + (size_t)j * DM * DM, DM, DM, Wo, INP(10) + j * 256, 255, (j ? 1.0f - LAM_INIT_1 : 1.0f - LAM_INIT_0), nullptr, nullptr, nullptr, MapIdent()); return; } id -= NI_O;
.LBB0_1387:
	s_or_b64 exec, exec, s[6:7]
	s_mov_b64 s[6:7], -1
	s_mov_b64 s[40:41], 0
	s_and_b64 vcc, exec, s[66:67]
	s_mov_b64 s[42:43], 0
	s_cbranch_vccz .LBB0_1411
	s_movk_i32 s6, 0x17ff
	v_cmp_lt_u32_e32 vcc, s6, v21
	s_and_saveexec_b64 s[6:7], vcc
	s_xor_b64 s[6:7], exec, s[6:7]
	s_cbranch_execz .LBB0_1408
	s_movk_i32 s12, 0x2000
	v_cmp_gt_u32_e32 vcc, s12, v21
	s_mov_b64 s[16:17], -1
	s_and_saveexec_b64 s[12:13], vcc
	s_cbranch_execz .LBB0_1407
	v_readlane_b32 s24, v252, 14
	v_readlane_b32 s25, v252, 15
	s_mov_b64 s[16:17], s[24:25]
	s_load_dwordx2 s[16:17], s[16:17], 0x58
	v_add_u32_e32 v0, 0xe800, v21
	v_readlane_b32 s18, v252, 12
	v_and_b32_e32 v13, 0xffc0, v0
	v_lshlrev_b32_e32 v0, 5, v21
	s_waitcnt lgkmcnt(0)
	s_add_u32 s16, s16, s54
	v_readlane_b32 s19, v252, 13
	v_mov_b32_e32 v22, v220
	v_and_b32_e32 v8, 0x7e0, v0
	s_addc_u32 s17, s17, s55
	s_load_dwordx2 s[26:27], s[24:25], 0x50
	v_lshlrev_b32_e32 v184, 2, v8
	v_lshlrev_b32_e32 v2, 4, v22
	v_bfe_u32 v12, v22, 3, 3
	v_lshl_add_u64 v[0:1], s[16:17], 0, v[184:185]
	v_and_b32_e32 v184, 0x70, v2
	v_lshl_add_u64 v[4:5], v[0:1], 0, v[184:185]
	v_or_b32_e32 v0, v12, v13
	v_lshlrev_b32_e32 v6, 13, v0
	v_mov_b32_e32 v7, v185
	v_lshl_add_u64 v[0:1], v[4:5], 0, v[6:7]
	global_load_dwordx4 v[132:135], v[0:1], off nt
	v_mul_u32_u24_e32 v7, 0x84, v12
	v_add3_u32 v7, s79, v184, v7
	v_or_b32_e32 v11, 8, v12
	v_add_u32_e32 v9, 0x420, v7
	v_or_b32_e32 v10, 16, v12
	v_add_u32_e32 v23, 0xc60, v7
	v_readlane_b32 s24, v255, 43
	v_and_b32_e32 v22, 7, v22
	v_readlane_b32 s25, v255, 44
	s_waitcnt lgkmcnt(0)
	s_add_u32 s24, s26, s24
	s_addc_u32 s25, s27, s25
	s_cmp_lg_u64 s[26:27], 0
	s_cselect_b64 s[48:49], -1, 0
	s_cmp_eq_u64 s[26:27], 0
	v_or_b32_e32 v0, v11, v13
	v_lshlrev_b32_e32 v184, 13, v0
	v_lshl_add_u64 v[0:1], v[4:5], 0, v[184:185]
	global_load_dwordx4 v[136:139], v[0:1], off nt
	v_add_u32_e32 v0, 0x428, v7
	v_or_b32_e32 v0, v10, v13
	v_lshlrev_b32_e32 v184, 13, v0
	v_lshl_add_u64 v[0:1], v[4:5], 0, v[184:185]
	global_load_dwordx4 v[140:143], v[0:1], off nt
	v_add_u32_e32 v9, 0x840, v7
	v_add_u32_e32 v0, 0x848, v7
	v_or_b32_e32 v9, 24, v12
	v_or_b32_e32 v0, v9, v13
	v_lshlrev_b32_e32 v184, 13, v0
	v_lshl_add_u64 v[0:1], v[4:5], 0, v[184:185]
	global_load_dwordx4 v[144:147], v[0:1], off nt
	v_or_b32_e32 v184, 0x40000, v6
	v_add_u32_e32 v0, 0xc68, v7
	v_lshl_add_u64 v[0:1], v[4:5], 0, v[184:185]
	global_load_dwordx4 v[148:151], v[0:1], off nt
	v_add_u32_e32 v23, 0x1080, v7
	v_or_b32_e32 v184, 0x50000, v6
	v_add_u32_e32 v0, 0x1088, v7
	v_lshl_add_u64 v[0:1], v[4:5], 0, v[184:185]
	global_load_dwordx4 v[152:155], v[0:1], off nt
	v_add_u32_e32 v23, 0x14a0, v7
	v_or_b32_e32 v184, 0x60000, v6
	v_add_u32_e32 v0, 0x14a8, v7
	v_lshl_add_u64 v[0:1], v[4:5], 0, v[184:185]
	global_load_dwordx4 v[156:159], v[0:1], off nt
	v_add_u32_e32 v23, 0x18c0, v7
	v_or_b32_e32 v184, 0x70000, v6
	v_add_u32_e32 v0, 0x18c8, v7
	v_lshl_add_u64 v[0:1], v[4:5], 0, v[184:185]
	global_load_dwordx4 v[160:163], v[0:1], off nt
	v_add_u32_e32 v4, 0x1ce0, v7
	v_lshlrev_b32_e32 v23, 3, v22
	v_add_u32_e32 v0, 0x1ce8, v7
	s_waitcnt vmcnt(0)
	v_add_u32_e32 v164, 0x0, v7
	ds_write2_b32 v164, v132, v133 offset1:1
	ds_write2_b32 v164, v134, v135 offset0:2 offset1:3
	v_add_u32_e32 v164, 0x420, v7
	ds_write2_b32 v164, v136, v137 offset1:1
	ds_write2_b32 v164, v138, v139 offset0:2 offset1:3
	v_add_u32_e32 v164, 0x840, v7
	ds_write2_b32 v164, v140, v141 offset1:1
	ds_write2_b32 v164, v142, v143 offset0:2 offset1:3
	v_add_u32_e32 v164, 0xc60, v7
	ds_write2_b32 v164, v144, v145 offset1:1
	ds_write2_b32 v164, v146, v147 offset0:2 offset1:3
	v_add_u32_e32 v164, 0x1080, v7
	ds_write2_b32 v164, v148, v149 offset1:1
	ds_write2_b32 v164, v150, v151 offset0:2 offset1:3
	v_add_u32_e32 v164, 0x14a0, v7
	ds_write2_b32 v164, v152, v153 offset1:1
	ds_write2_b32 v164, v154, v155 offset0:2 offset1:3
	v_add_u32_e32 v164, 0x18c0, v7
	ds_write2_b32 v164, v156, v157 offset1:1
	ds_write2_b32 v164, v158, v159 offset0:2 offset1:3
	v_add_u32_e32 v164, 0x1ce0, v7
	ds_write2_b32 v164, v160, v161 offset1:1
	ds_write2_b32 v164, v162, v163 offset0:2 offset1:3
	s_waitcnt lgkmcnt(0)
	v_or_b32_e32 v1, v23, v13
	v_and_b32_e32 v1, 0xf8, v1
	v_mov_b32_e32 v0, 1.0
	v_lshlrev_b32_e32 v24, 2, v1
	v_mov_b32_e32 v2, 1.0
	s_cbranch_scc1 .LBB0_1392
	global_load_dword v1, v24, s[24:25]
	s_waitcnt vmcnt(0)
	v_mul_f32_e32 v2, v15, v1

; #define LAS __attribute__((address_space(3)))
; #define F_LANE() (tid_of(F.wave) & 63)
; #define LDS_WAIT() asm volatile("s_waitcnt lgkmcnt(0)" ::: "memory")
; template <class Map>
; __device__ __forceinline__ void conv_item(const Frame& F, int it, const float* W, int K, int N, bf16_t* WT, const float* gk, int gmask, float gmul, const float* bk, i64* cs, i64* bw, Map map) {
;     LAS float* scr = (LAS float*)(F.lds + F.wave * 16384);
;     const int lane = F_LANE(), nblk = N / 32;
;     {
;         const int kb = it / nblk, nb = it % nblk, k0 = 64 * kb, n0 = 32 * nb, v0 = map(n0);
; #pragma unroll
;         for (int i = 0; i < 8; ++i) { const int kk = 8 * i + (lane >> 3), c4 = (lane & 7) * 4;
;             const f32x4 w4 = __builtin_nontemporal_load((const f32x4*)(W + (size_t)(k0 + kk) * N + n0 + c4)); LAS float* d = scr + kk * 33 + c4; d[0] = w4[0]; d[1] = w4[1]; d[2] = w4[2]; d[3] = w4[3]; }
;         LDS_WAIT(); asm volatile("" ::: "memory");
;         if (bk) {
;             const int n = lane & 31, kh = lane >> 5; float sb = 0.f, sc = 0.f;
; #pragma unroll 8
;             for (int j = 0; j < 32; ++j) { const int kk = kh * 32 + j; const float w = scr[kk * 33 + n]; sb += bk[k0 + kk] * w; sc += bf_round(gk[(k0 + kk) & gmask] * gmul * w); }
;             { auto r = __builtin_amdgcn_permlane32_swap(__float_as_uint(sb), __float_as_uint(sb), false, false); sb = __uint_as_float(r[0]) + __uint_as_float(r[1]); }
;             { auto r = __builtin_amdgcn_permlane32_swap(__float_as_uint(sc), __float_as_uint(sc), false, false); sc = __uint_as_float(r[0]) + __uint_as_float(r[1]); }
;             if (lane < 32) { atomic_addq(bw + v0 + n, sb, FX_COL); atomic_addq(cs + v0 + n, sc, FX_COL); }
;         }
;         const int c = lane & 7; float gl[8];
; #pragma unroll
;         for (int i = 0; i < 8; ++i) gl[i] = gk ? gk[(k0 + 8 * c + i) & gmask] * gmul : 1.0f;
; #pragma unroll
;         for (int j = 0; j < 4; ++j) { const int n = (lane >> 3) + 8 * j; const LAS float* s = scr + (8 * c) * 33 + n;
;             u32x4 o; o.x = pk2(s[0 * 33] * gl[0], s[1 * 33] * gl[1]); o.y = pk2(s[2 * 33] * gl[2], s[3 * 33] * gl[3]); o.z = pk2(s[4 * 33] * gl[4], s[5 * 33] * gl[5]); o.w = pk2(s[6 * 33] * gl[6], s[7 * 33] * gl[7]);
;             __builtin_nontemporal_store(o, (u32x4*)(WT + (size_t)(v0 + n) * K + k0 + 8 * c)); }
.LBB0_1408:
	s_andn2_saveexec_b64 s[6:7], s[6:7]
	s_cbranch_execz .LBB0_1410
	v_readlane_b32 s12, v252, 14
	v_readlane_b32 s13, v252, 15
	s_load_dwordx2 s[12:13], s[12:13], 0x40
	s_mov_b32 s18, 0xaaab
	v_readlane_b32 s16, v255, 49
	v_mul_u32_u24_sdwa v0, v21, s18 dst_sel:DWORD dst_unused:UNUSED_PAD src0_sel:WORD_0 src1_sel:DWORD
	v_lshrrev_b32_e32 v0, 23, v0
	s_waitcnt lgkmcnt(0)
	s_add_u32 s16, s12, s16
	v_readlane_b32 s12, v255, 47
	s_addc_u32 s17, s13, s12
	v_readlane_b32 s12, v252, 12
	v_mul_lo_u16_e32 v1, 0xc0, v0
	v_readlane_b32 s13, v252, 13
	v_mov_b32_e32 v6, v220
	v_sub_u16_e32 v1, v21, v1
	v_lshlrev_b16_e32 v12, 6, v0
	v_lshlrev_b16_e32 v2, 5, v1
	v_bfe_u32 v7, v6, 3, 3
	v_lshlrev_b32_e32 v184, 2, v2
	v_lshlrev_b32_e32 v3, 4, v6
	v_or_b32_e32 v13, v7, v12
	v_lshl_add_u64 v[0:1], s[16:17], 0, v[184:185]
	v_and_b32_e32 v184, 0x70, v3
	v_mul_u32_u24_e32 v3, 0x1800, v13
	v_lshl_add_u64 v[0:1], v[0:1], 0, v[184:185]
	v_lshlrev_b32_e32 v4, 2, v3
	v_mov_b32_e32 v5, v185
	v_lshl_add_u64 v[4:5], v[0:1], 0, v[4:5]
	global_load_dwordx4 v[132:135], v[4:5], off nt
	v_mul_u32_u24_e32 v3, 0x84, v7
	v_or_b32_e32 v5, 8, v7
	v_add3_u32 v22, s79, v184, v3
	v_or_b32_e32 v3, v5, v12
	v_mul_u32_u24_e32 v3, 0x1800, v3
	v_lshlrev_b32_e32 v184, 2, v3
	v_add_u32_e32 v3, 0x420, v22
	v_or_b32_e32 v4, 16, v7
	v_add_u32_e32 v23, 0xc60, v22
	v_and_b32_e32 v6, 7, v6
	v_or_b32_e32 v5, v5, v2
	v_lshl_add_u64 v[8:9], v[0:1], 0, v[184:185]
	global_load_dwordx4 v[136:139], v[8:9], off nt
	v_add_u32_e32 v3, 0x428, v22
	v_or_b32_e32 v3, v4, v12
	v_mul_u32_u24_e32 v3, 0x1800, v3
	v_lshlrev_b32_e32 v184, 2, v3
	v_lshl_add_u64 v[8:9], v[0:1], 0, v[184:185]
	global_load_dwordx4 v[140:143], v[8:9], off nt
	v_add_u32_e32 v3, 0x840, v22
	v_or_b32_e32 v4, v4, v2
	v_add_u32_e32 v3, 0x848, v22
	v_or_b32_e32 v3, 24, v7
	v_or_b32_e32 v8, v3, v12
	v_mul_u32_u24_e32 v8, 0x1800, v8
	v_lshlrev_b32_e32 v184, 2, v8
	v_lshl_add_u64 v[8:9], v[0:1], 0, v[184:185]
	global_load_dwordx4 v[144:147], v[8:9], off nt
	v_add_u32_e32 v8, 0xc68, v22
	v_or_b32_e32 v8, 32, v13
	v_mul_u32_u24_e32 v8, 0x1800, v8
	v_lshlrev_b32_e32 v184, 2, v8
	v_lshl_add_u64 v[8:9], v[0:1], 0, v[184:185]
	global_load_dwordx4 v[148:151], v[8:9], off nt
	v_add_u32_e32 v23, 0x1080, v22
	v_add_u32_e32 v8, 0x1088, v22
	v_or_b32_e32 v8, 40, v13
	v_mul_u32_u24_e32 v8, 0x1800, v8
	v_lshlrev_b32_e32 v184, 2, v8
	v_lshl_add_u64 v[8:9], v[0:1], 0, v[184:185]
	global_load_dwordx4 v[152:155], v[8:9], off nt
	v_add_u32_e32 v23, 0x14a0, v22
	v_add_u32_e32 v8, 0x14a8, v22
	v_or_b32_e32 v8, 48, v13
	v_mul_u32_u24_e32 v8, 0x1800, v8
	v_lshlrev_b32_e32 v184, 2, v8
	v_lshl_add_u64 v[8:9], v[0:1], 0, v[184:185]
	global_load_dwordx4 v[156:159], v[8:9], off nt
	v_add_u32_e32 v23, 0x18c0, v22
	v_add_u32_e32 v8, 0x18c8, v22
	v_or_b32_e32 v8, 56, v13
	v_mul_u32_u24_e32 v8, 0x1800, v8
	v_lshlrev_b32_e32 v184, 2, v8
	v_lshl_add_u64 v[0:1], v[0:1], 0, v[184:185]
	global_load_dwordx4 v[160:163], v[0:1], off nt
	v_add_u32_e32 v0, 0x1ce0, v22
	v_lshlrev_b32_e32 v184, 1, v12
	v_add_u32_e32 v0, 0x1ce8, v22
	s_waitcnt vmcnt(0)
	v_add_u32_e32 v164, 0x0, v22
	ds_write2_b32 v164, v132, v133 offset1:1
	ds_write2_b32 v164, v134, v135 offset0:2 offset1:3
	v_add_u32_e32 v164, 0x420, v22
	ds_write2_b32 v164, v136, v137 offset1:1
	ds_write2_b32 v164, v138, v139 offset0:2 offset1:3
	v_add_u32_e32 v164, 0x840, v22
	ds_write2_b32 v164, v140, v141 offset1:1
	ds_write2_b32 v164, v142, v143 offset0:2 offset1:3
	v_add_u32_e32 v164, 0xc60, v22
	ds_write2_b32 v164, v144, v145 offset1:1
	ds_write2_b32 v164, v146, v147 offset0:2 offset1:3
	v_add_u32_e32 v164, 0x1080, v22
	ds_write2_b32 v164, v148, v149 offset1:1
	ds_write2_b32 v164, v150, v151 offset0:2 offset1:3
	v_add_u32_e32 v164, 0x14a0, v22
	ds_write2_b32 v164, v152, v153 offset1:1
	ds_write2_b32 v164, v154, v155 offset0:2 offset1:3
	v_add_u32_e32 v164, 0x18c0, v22
	ds_write2_b32 v164, v156, v157 offset1:1
	ds_write2_b32 v164, v158, v159 offset0:2 offset1:3
	v_add_u32_e32 v164, 0x1ce0, v22
	ds_write2_b32 v164, v160, v161 offset1:1
	ds_write2_b32 v164, v162, v163 offset0:2 offset1:3
	s_waitcnt lgkmcnt(0)
	v_mul_u32_u24_e32 v8, 0x420, v6
	v_lshl_add_u64 v[0:1], s[12:13], 0, v[184:185]
	v_lshlrev_b32_e32 v184, 4, v6
	v_lshlrev_b32_e32 v6, 2, v7
	v_add3_u32 v6, s79, v8, v6
	ds_read_b32 v8, v6
	ds_read_b32 v9, v6 offset:132
	v_lshl_add_u64 v[0:1], v[0:1], 0, v[184:185]
	s_mov_b64 s[12:13], 0x39500000
	v_or_b32_e32 v7, v7, v2
	s_waitcnt lgkmcnt(1)
	v_bfe_u32 v10, v8, 16, 1
	v_add3_u32 v8, v8, v10, s73
	s_waitcnt lgkmcnt(0)
; #define LAS __attribute__((address_space(3)))
; #define LDS_WAIT() asm volatile("s_waitcnt lgkmcnt(0)" ::: "memory")
; __device__ __forceinline__ unsigned pk2(float lo, float hi) { return f2bf(lo) | (f2bf(hi) << 16); }
; template <class Map>
; __device__ __forceinline__ void conv_item(const Frame& F, int it, const float* W, int K, int N, bf16_t* WT, const float* gk, int gmask, float gmul, const float* bk, i64* cs, i64* bw, Map map) {
;     ...
;         const int c = lane & 7; float gl[8];
; #pragma unroll
;         for (int i = 0; i < 8; ++i) gl[i] = gk ? gk[(k0 + 8 * c + i) & gmask] * gmul : 1.0f;
; #pragma unroll
;         for (int j = 0; j < 4; ++j) { const int n = (lane >> 3) + 8 * j; const LAS float* s = scr + (8 * c) * 33 + n;
;             u32x4 o; o.x = pk2(s[0 * 33] * gl[0], s[1 * 33] * gl[1]); o.y = pk2(s[2 * 33] * gl[2], s[3 * 33] * gl[3]); o.z = pk2(s[4 * 33] * gl[4], s[5 * 33] * gl[5]); o.w = pk2(s[6 * 33] * gl[6], s[7 * 33] * gl[7]);
;             __builtin_nontemporal_store(o, (u32x4*)(WT + (size_t)(v0 + n) * K + k0 + 8 * c)); }
;         LDS_WAIT(); asm volatile("" ::: "memory");
	v_bfe_u32 v10, v9, 16, 1
	v_lshrrev_b32_e32 v8, 16, v8
	v_add3_u32 v9, v9, v10, s73
	v_and_or_b32 v8, v9, s72, v8
	ds_read_b32 v9, v6 offset:264
	ds_read_b32 v10, v6 offset:396
	v_lshl_add_u64 v[0:1], v[0:1], 0, s[12:13]
	v_lshlrev_b32_e32 v184, 12, v7
	v_or_b32_e32 v2, v3, v2
	s_waitcnt lgkmcnt(1)
	v_bfe_u32 v11, v9, 16, 1
	v_add3_u32 v9, v9, v11, s73
	s_waitcnt lgkmcnt(0)
	v_bfe_u32 v11, v10, 16, 1
	v_lshrrev_b32_e32 v9, 16, v9
	v_add3_u32 v10, v10, v11, s73
	v_and_or_b32 v9, v10, s72, v9
	ds_read_b32 v10, v6 offset:528
	ds_read_b32 v11, v6 offset:660
	s_waitcnt lgkmcnt(1)
	v_bfe_u32 v12, v10, 16, 1
	v_add3_u32 v10, v10, v12, s73
	s_waitcnt lgkmcnt(0)
	v_bfe_u32 v12, v11, 16, 1
	v_lshrrev_b32_e32 v10, 16, v10
	v_add3_u32 v11, v11, v12, s73
	v_and_or_b32 v10, v11, s72, v10
	ds_read_b32 v11, v6 offset:792
	ds_read_b32 v12, v6 offset:924
	s_waitcnt lgkmcnt(1)
	v_bfe_u32 v13, v11, 16, 1
	v_add3_u32 v11, v11, v13, s73
	s_waitcnt lgkmcnt(0)
	v_bfe_u32 v13, v12, 16, 1
	v_lshrrev_b32_e32 v11, 16, v11
	v_add3_u32 v12, v12, v13, s73
	v_and_or_b32 v11, v12, s72, v11
	v_lshl_add_u64 v[12:13], v[0:1], 0, v[184:185]
	flat_store_dwordx4 v[12:13], v[8:11] nt
	ds_read_b32 v7, v6 offset:32
	ds_read_b32 v8, v6 offset:164
	v_lshlrev_b32_e32 v184, 12, v5
	s_waitcnt lgkmcnt(0)
	v_bfe_u32 v9, v7, 16, 1
	v_add3_u32 v7, v7, v9, s73
	v_bfe_u32 v9, v8, 16, 1
	v_lshrrev_b32_e32 v7, 16, v7
	v_add3_u32 v8, v8, v9, s73
	v_and_or_b32 v8, v8, s72, v7
	ds_read_b32 v7, v6 offset:296
	ds_read_b32 v9, v6 offset:428
	s_waitcnt lgkmcnt(0)
	v_bfe_u32 v10, v7, 16, 1
	v_add3_u32 v7, v7, v10, s73
	v_bfe_u32 v10, v9, 16, 1
	v_lshrrev_b32_e32 v7, 16, v7
	v_add3_u32 v9, v9, v10, s73
	v_and_or_b32 v9, v9, s72, v7
	ds_read_b32 v7, v6 offset:560
	ds_read_b32 v10, v6 offset:692
	s_waitcnt lgkmcnt(0)
	v_bfe_u32 v11, v7, 16, 1
	v_add3_u32 v7, v7, v11, s73
	v_bfe_u32 v11, v10, 16, 1
	v_lshrrev_b32_e32 v7, 16, v7
	v_add3_u32 v10, v10, v11, s73
	v_and_or_b32 v10, v10, s72, v7
	ds_read_b32 v7, v6 offset:824
	ds_read_b32 v11, v6 offset:956
	s_waitcnt lgkmcnt(0)
	v_bfe_u32 v12, v7, 16, 1
	v_add3_u32 v7, v7, v12, s73
	v_bfe_u32 v12, v11, 16, 1
	v_lshrrev_b32_e32 v7, 16, v7
	v_add3_u32 v11, v11, v12, s73
	v_and_or_b32 v11, v11, s72, v7
	v_lshl_add_u64 v[12:13], v[0:1], 0, v[184:185]
	flat_store_dwordx4 v[12:13], v[8:11] nt
	ds_read_b32 v5, v6 offset:64
	ds_read_b32 v7, v6 offset:196
	v_lshlrev_b32_e32 v184, 12, v4
	s_waitcnt lgkmcnt(0)
	v_bfe_u32 v8, v5, 16, 1
	v_add3_u32 v5, v5, v8, s73
	v_bfe_u32 v8, v7, 16, 1
	v_lshrrev_b32_e32 v5, 16, v5
	v_add3_u32 v7, v7, v8, s73
	v_and_or_b32 v8, v7, s72, v5
	ds_read_b32 v5, v6 offset:328
	ds_read_b32 v7, v6 offset:460
	s_waitcnt lgkmcnt(0)
	v_bfe_u32 v9, v5, 16, 1
	v_add3_u32 v5, v5, v9, s73
	v_bfe_u32 v9, v7, 16, 1
	v_lshrrev_b32_e32 v5, 16, v5
	v_add3_u32 v7, v7, v9, s73
	v_and_or_b32 v9, v7, s72, v5
	ds_read_b32 v5, v6 offset:592
	ds_read_b32 v7, v6 offset:724
	s_waitcnt lgkmcnt(0)
	v_bfe_u32 v10, v5, 16, 1
	v_add3_u32 v5, v5, v10, s73
	v_bfe_u32 v10, v7, 16, 1
	v_lshrrev_b32_e32 v5, 16, v5
	v_add3_u32 v7, v7, v10, s73
	v_and_or_b32 v10, v7, s72, v5
	ds_read_b32 v5, v6 offset:856
	ds_read_b32 v7, v6 offset:988
	s_waitcnt lgkmcnt(0)
	v_bfe_u32 v11, v5, 16, 1
	v_add3_u32 v5, v5, v11, s73
	v_bfe_u32 v11, v7, 16, 1
	v_lshrrev_b32_e32 v5, 16, v5
	v_add3_u32 v7, v7, v11, s73
	v_and_or_b32 v11, v7, s72, v5
	v_lshl_add_u64 v[4:5], v[0:1], 0, v[184:185]
	flat_store_dwordx4 v[4:5], v[8:11] nt
	ds_read_b32 v4, v6 offset:96
	ds_read_b32 v5, v6 offset:228
	v_lshlrev_b32_e32 v184, 12, v2
	v_lshl_add_u64 v[0:1], v[0:1], 0, v[184:185]
	s_waitcnt lgkmcnt(0)
	v_bfe_u32 v7, v4, 16, 1
	v_add3_u32 v4, v4, v7, s73
	v_bfe_u32 v7, v5, 16, 1
	v_lshrrev_b32_e32 v4, 16, v4
	v_add3_u32 v5, v5, v7, s73
	v_and_or_b32 v8, v5, s72, v4
	ds_read_b32 v4, v6 offset:360
	ds_read_b32 v5, v6 offset:492
	s_waitcnt lgkmcnt(0)
	v_bfe_u32 v7, v4, 16, 1
	v_add3_u32 v4, v4, v7, s73
	v_bfe_u32 v7, v5, 16, 1
	v_lshrrev_b32_e32 v4, 16, v4
	v_add3_u32 v5, v5, v7, s73
	v_and_or_b32 v9, v5, s72, v4
	ds_read_b32 v4, v6 offset:624
	ds_read_b32 v5, v6 offset:756
	s_waitcnt lgkmcnt(0)
	v_bfe_u32 v7, v4, 16, 1
	v_add3_u32 v4, v4, v7, s73
	v_bfe_u32 v7, v5, 16, 1
	v_lshrrev_b32_e32 v4, 16, v4
	v_add3_u32 v5, v5, v7, s73
	v_and_or_b32 v10, v5, s72, v4
	ds_read_b32 v4, v6 offset:888
	ds_read_b32 v5, v6 offset:1020
	s_waitcnt lgkmcnt(0)
	v_bfe_u32 v6, v4, 16, 1
	v_add3_u32 v4, v4, v6, s73
	v_bfe_u32 v6, v5, 16, 1
	v_lshrrev_b32_e32 v4, 16, v4
	v_add3_u32 v5, v5, v6, s73
	v_and_or_b32 v11, v5, s72, v4
	flat_store_dwordx4 v[0:1], v[8:11] nt
	s_waitcnt lgkmcnt(0)

; #define LAS __attribute__((address_space(3)))
; #define F_LANE() (tid_of(F.wave) & 63)
; #define LDS_WAIT() asm volatile("s_waitcnt lgkmcnt(0)" ::: "memory")
; template <class Map>
; __device__ __forceinline__ void conv_item(const Frame& F, int it, const float* W, int K, int N, bf16_t* WT, const float* gk, int gmask, float gmul, const float* bk, i64* cs, i64* bw, Map map) {
;     LAS float* scr = (LAS float*)(F.lds + F.wave * 16384);
;     const int lane = F_LANE(), nblk = N / 32;
;     {
;         const int kb = it / nblk, nb = it % nblk, k0 = 64 * kb, n0 = 32 * nb, v0 = map(n0);
; #pragma unroll
;         for (int i = 0; i < 8; ++i) { const int kk = 8 * i + (lane >> 3), c4 = (lane & 7) * 4;
;             const f32x4 w4 = __builtin_nontemporal_load((const f32x4*)(W + (size_t)(k0 + kk) * N + n0 + c4)); LAS float* d = scr + kk * 33 + c4; d[0] = w4[0]; d[1] = w4[1]; d[2] = w4[2]; d[3] = w4[3]; }
;         LDS_WAIT(); asm volatile("" ::: "memory");
;         if (bk) {
;             const int n = lane & 31, kh = lane >> 5; float sb = 0.f, sc = 0.f;
; #pragma unroll 8
;             for (int j = 0; j < 32; ++j) { const int kk = kh * 32 + j; const float w = scr[kk * 33 + n]; sb += bk[k0 + kk] * w; sc += bf_round(gk[(k0 + kk) & gmask] * gmul * w); }
;             { auto r = __builtin_amdgcn_permlane32_swap(__float_as_uint(sb), __float_as_uint(sb), false, false); sb = __uint_as_float(r[0]) + __uint_as_float(r[1]); }
;             { auto r = __builtin_amdgcn_permlane32_swap(__float_as_uint(sc), __float_as_uint(sc), false, false); sc = __uint_as_float(r[0]) + __uint_as_float(r[1]); }
;             if (lane < 32) { atomic_addq(bw + v0 + n, sb, FX_COL); atomic_addq(cs + v0 + n, sc, FX_COL); }
;         }
;         const int c = lane & 7; float gl[8];
; #pragma unroll
;         for (int i = 0; i < 8; ++i) gl[i] = gk ? gk[(k0 + 8 * c + i) & gmask] * gmul : 1.0f;
; #pragma unroll
;         for (int j = 0; j < 4; ++j) { const int n = (lane >> 3) + 8 * j; const LAS float* s = scr + (8 * c) * 33 + n;
;             u32x4 o; o.x = pk2(s[0 * 33] * gl[0], s[1 * 33] * gl[1]); o.y = pk2(s[2 * 33] * gl[2], s[3 * 33] * gl[3]); o.z = pk2(s[4 * 33] * gl[4], s[5 * 33] * gl[5]); o.w = pk2(s[6 * 33] * gl[6], s[7 * 33] * gl[7]);
;             __builtin_nontemporal_store(o, (u32x4*)(WT + (size_t)(v0 + n) * K + k0 + 8 * c)); }
.LBB0_1420:
	v_readlane_b32 s12, v252, 14
	v_readlane_b32 s13, v252, 15
	s_load_dwordx2 s[12:13], s[12:13], 0x38
	v_add_u32_e32 v0, 0xf4c0, v21
	v_and_b32_e32 v23, 0xffc0, v0
	v_lshlrev_b32_e32 v0, 5, v21
	v_mov_b32_e32 v22, v220
	s_waitcnt lgkmcnt(0)
	s_add_u32 s16, s12, s54
	s_addc_u32 s17, s13, s55
	v_readlane_b32 s12, v252, 12
	v_readlane_b32 s13, v252, 13
	v_and_b32_e32 v2, 0x7e0, v0
	v_lshlrev_b32_e32 v184, 2, v2
	v_bfe_u32 v7, v22, 3, 3
	v_lshlrev_b32_e32 v3, 4, v22
	v_lshl_add_u64 v[0:1], s[16:17], 0, v[184:185]
	v_and_b32_e32 v184, 0x70, v3
	v_or_b32_e32 v3, v7, v23
	v_lshl_add_u64 v[0:1], v[0:1], 0, v[184:185]
	v_lshlrev_b32_e32 v12, 13, v3
	v_mov_b32_e32 v13, v185
	v_lshl_add_u64 v[4:5], v[0:1], 0, v[12:13]
	global_load_dwordx4 v[132:135], v[4:5], off nt
	v_mul_u32_u24_e32 v3, 0x84, v7
	v_or_b32_e32 v6, 8, v7
	v_add3_u32 v13, s79, v184, v3
	v_or_b32_e32 v3, v6, v23
	v_lshlrev_b32_e32 v184, 13, v3
	v_lshl_add_u64 v[4:5], v[0:1], 0, v[184:185]
	v_add_u32_e32 v3, 0x420, v13
	v_or_b32_e32 v6, v6, v2
	global_load_dwordx4 v[136:139], v[4:5], off nt
	v_or_b32_e32 v4, 16, v7
	v_add_u32_e32 v3, 0x428, v13
	v_or_b32_e32 v3, v4, v23
	v_lshlrev_b32_e32 v184, 13, v3
	v_lshl_add_u64 v[8:9], v[0:1], 0, v[184:185]
	global_load_dwordx4 v[140:143], v[8:9], off nt
	v_add_u32_e32 v3, 0x840, v13
	v_or_b32_e32 v4, v4, v2
	v_add_u32_e32 v3, 0x848, v13
	v_or_b32_e32 v3, 24, v7
	v_or_b32_e32 v5, v3, v23
	v_lshlrev_b32_e32 v184, 13, v5
	v_lshl_add_u64 v[8:9], v[0:1], 0, v[184:185]
	global_load_dwordx4 v[144:147], v[8:9], off nt
	v_add_u32_e32 v5, 0xc60, v13
	v_or_b32_e32 v184, 0x40000, v12
	v_add_u32_e32 v5, 0xc68, v13
	v_lshl_add_u64 v[8:9], v[0:1], 0, v[184:185]
	global_load_dwordx4 v[148:151], v[8:9], off nt
	v_add_u32_e32 v5, 0x1080, v13
	v_or_b32_e32 v184, 0x50000, v12
	v_add_u32_e32 v5, 0x1088, v13
	v_lshl_add_u64 v[8:9], v[0:1], 0, v[184:185]
	global_load_dwordx4 v[152:155], v[8:9], off nt
	v_add_u32_e32 v5, 0x14a0, v13
	v_or_b32_e32 v184, 0x60000, v12
	v_add_u32_e32 v5, 0x14a8, v13
	v_lshl_add_u64 v[8:9], v[0:1], 0, v[184:185]
	global_load_dwordx4 v[156:159], v[8:9], off nt
	v_add_u32_e32 v5, 0x18c0, v13
	v_or_b32_e32 v184, 0x70000, v12
	v_lshl_add_u64 v[0:1], v[0:1], 0, v[184:185]
	v_lshlrev_b32_e32 v184, 1, v23
	v_add_u32_e32 v5, 0x18c8, v13
	global_load_dwordx4 v[160:163], v[0:1], off nt
	v_add_u32_e32 v0, 0x1ce0, v13
	v_and_b32_e32 v5, 7, v22
	v_add_u32_e32 v0, 0x1ce8, v13
	s_waitcnt vmcnt(0)
	v_add_u32_e32 v164, 0x0, v13
	ds_write2_b32 v164, v132, v133 offset1:1
	ds_write2_b32 v164, v134, v135 offset0:2 offset1:3
	v_add_u32_e32 v164, 0x420, v13
	ds_write2_b32 v164, v136, v137 offset1:1
	ds_write2_b32 v164, v138, v139 offset0:2 offset1:3
	v_add_u32_e32 v164, 0x840, v13
	ds_write2_b32 v164, v140, v141 offset1:1
	ds_write2_b32 v164, v142, v143 offset0:2 offset1:3
	v_add_u32_e32 v164, 0xc60, v13
	ds_write2_b32 v164, v144, v145 offset1:1
	ds_write2_b32 v164, v146, v147 offset0:2 offset1:3
	v_add_u32_e32 v164, 0x1080, v13
	ds_write2_b32 v164, v148, v149 offset1:1
	ds_write2_b32 v164, v150, v151 offset0:2 offset1:3
	v_add_u32_e32 v164, 0x14a0, v13
	ds_write2_b32 v164, v152, v153 offset1:1
	ds_write2_b32 v164, v154, v155 offset0:2 offset1:3
	v_add_u32_e32 v164, 0x18c0, v13
	ds_write2_b32 v164, v156, v157 offset1:1
	ds_write2_b32 v164, v158, v159 offset0:2 offset1:3
	v_add_u32_e32 v164, 0x1ce0, v13
	ds_write2_b32 v164, v160, v161 offset1:1
	ds_write2_b32 v164, v162, v163 offset0:2 offset1:3
	s_waitcnt lgkmcnt(0)
	v_mul_u32_u24_e32 v8, 0x420, v5
	v_lshl_add_u64 v[0:1], s[12:13], 0, v[184:185]
	v_lshlrev_b32_e32 v184, 4, v5
	v_lshlrev_b32_e32 v5, 2, v7
	v_add3_u32 v5, s79, v8, v5
	ds_read_b32 v8, v5
	ds_read_b32 v9, v5 offset:132
	v_lshl_add_u64 v[0:1], v[0:1], 0, v[184:185]
	s_mov_b64 s[12:13], 0x2800000
	v_or_b32_e32 v7, v7, v2
	s_waitcnt lgkmcnt(1)
	v_bfe_u32 v10, v8, 16, 1
	v_add3_u32 v8, v8, v10, s73
	s_waitcnt lgkmcnt(0)
	v_bfe_u32 v10, v9, 16, 1
	v_lshrrev_b32_e32 v8, 16, v8
	v_add3_u32 v9, v9, v10, s73
	v_and_or_b32 v8, v9, s72, v8
	ds_read_b32 v9, v5 offset:264
	ds_read_b32 v10, v5 offset:396
	v_lshl_add_u64 v[0:1], v[0:1], 0, s[12:13]
	v_lshlrev_b32_e32 v184, 12, v7
	v_or_b32_e32 v2, v3, v2
	s_waitcnt lgkmcnt(1)
	v_bfe_u32 v11, v9, 16, 1
	v_add3_u32 v9, v9, v11, s73
	s_waitcnt lgkmcnt(0)
; #define LAS __attribute__((address_space(3)))
; #define LDS_WAIT() asm volatile("s_waitcnt lgkmcnt(0)" ::: "memory")
; __device__ __forceinline__ unsigned pk2(float lo, float hi) { return f2bf(lo) | (f2bf(hi) << 16); }
; template <class Map>
; __device__ __forceinline__ void conv_item(const Frame& F, int it, const float* W, int K, int N, bf16_t* WT, const float* gk, int gmask, float gmul, const float* bk, i64* cs, i64* bw, Map map) {
;     ...
;         const int c = lane & 7; float gl[8];
; #pragma unroll
;         for (int i = 0; i < 8; ++i) gl[i] = gk ? gk[(k0 + 8 * c + i) & gmask] * gmul : 1.0f;
; #pragma unroll
;         for (int j = 0; j < 4; ++j) { const int n = (lane >> 3) + 8 * j; const LAS float* s = scr + (8 * c) * 33 + n;
;             u32x4 o; o.x = pk2(s[0 * 33] * gl[0], s[1 * 33] * gl[1]); o.y = pk2(s[2 * 33] * gl[2], s[3 * 33] * gl[3]); o.z = pk2(s[4 * 33] * gl[4], s[5 * 33] * gl[5]); o.w = pk2(s[6 * 33] * gl[6], s[7 * 33] * gl[7]);
;             __builtin_nontemporal_store(o, (u32x4*)(WT + (size_t)(v0 + n) * K + k0 + 8 * c)); }
;         LDS_WAIT(); asm volatile("" ::: "memory");
	v_bfe_u32 v11, v10, 16, 1
	v_lshrrev_b32_e32 v9, 16, v9
	v_add3_u32 v10, v10, v11, s73
	v_and_or_b32 v9, v10, s72, v9
	ds_read_b32 v10, v5 offset:528
	ds_read_b32 v11, v5 offset:660
	s_waitcnt lgkmcnt(1)
	v_bfe_u32 v12, v10, 16, 1
	v_add3_u32 v10, v10, v12, s73
	s_waitcnt lgkmcnt(0)
	v_bfe_u32 v12, v11, 16, 1
	v_lshrrev_b32_e32 v10, 16, v10
	v_add3_u32 v11, v11, v12, s73
	v_and_or_b32 v10, v11, s72, v10
	ds_read_b32 v11, v5 offset:792
	ds_read_b32 v12, v5 offset:924
	s_waitcnt lgkmcnt(1)
	v_bfe_u32 v13, v11, 16, 1
	v_add3_u32 v11, v11, v13, s73
	s_waitcnt lgkmcnt(0)
	v_bfe_u32 v13, v12, 16, 1
	v_lshrrev_b32_e32 v11, 16, v11
	v_add3_u32 v12, v12, v13, s73
	v_and_or_b32 v11, v12, s72, v11
	v_lshl_add_u64 v[12:13], v[0:1], 0, v[184:185]
	flat_store_dwordx4 v[12:13], v[8:11] nt
	ds_read_b32 v7, v5 offset:32
	ds_read_b32 v8, v5 offset:164
	v_lshlrev_b32_e32 v184, 12, v6
	s_waitcnt lgkmcnt(0)
	v_bfe_u32 v9, v7, 16, 1
	v_add3_u32 v7, v7, v9, s73
	v_bfe_u32 v9, v8, 16, 1
	v_lshrrev_b32_e32 v7, 16, v7
	v_add3_u32 v8, v8, v9, s73
	v_and_or_b32 v8, v8, s72, v7
	ds_read_b32 v7, v5 offset:296
	ds_read_b32 v9, v5 offset:428
	s_waitcnt lgkmcnt(0)
	v_bfe_u32 v10, v7, 16, 1
	v_add3_u32 v7, v7, v10, s73
	v_bfe_u32 v10, v9, 16, 1
	v_lshrrev_b32_e32 v7, 16, v7
	v_add3_u32 v9, v9, v10, s73
	v_and_or_b32 v9, v9, s72, v7
	ds_read_b32 v7, v5 offset:560
	ds_read_b32 v10, v5 offset:692
	s_waitcnt lgkmcnt(0)
	v_bfe_u32 v11, v7, 16, 1
	v_add3_u32 v7, v7, v11, s73
	v_bfe_u32 v11, v10, 16, 1
	v_lshrrev_b32_e32 v7, 16, v7
	v_add3_u32 v10, v10, v11, s73
	v_and_or_b32 v10, v10, s72, v7
	ds_read_b32 v7, v5 offset:824
	ds_read_b32 v11, v5 offset:956
	s_waitcnt lgkmcnt(0)
	v_bfe_u32 v12, v7, 16, 1
	v_add3_u32 v7, v7, v12, s73
	v_bfe_u32 v12, v11, 16, 1
	v_lshrrev_b32_e32 v7, 16, v7
	v_add3_u32 v11, v11, v12, s73
	v_and_or_b32 v11, v11, s72, v7
	v_lshl_add_u64 v[6:7], v[0:1], 0, v[184:185]
	flat_store_dwordx4 v[6:7], v[8:11] nt
	ds_read_b32 v6, v5 offset:64
	ds_read_b32 v7, v5 offset:196
	v_lshlrev_b32_e32 v184, 12, v4
	s_waitcnt lgkmcnt(0)
	v_bfe_u32 v8, v6, 16, 1
	v_add3_u32 v6, v6, v8, s73
	v_bfe_u32 v8, v7, 16, 1
	v_lshrrev_b32_e32 v6, 16, v6
	v_add3_u32 v7, v7, v8, s73
	v_and_or_b32 v6, v7, s72, v6
	ds_read_b32 v7, v5 offset:328
	ds_read_b32 v8, v5 offset:460
	s_waitcnt lgkmcnt(0)
	v_bfe_u32 v9, v7, 16, 1
	v_add3_u32 v7, v7, v9, s73
	v_bfe_u32 v9, v8, 16, 1
	v_lshrrev_b32_e32 v7, 16, v7
	v_add3_u32 v8, v8, v9, s73
	v_and_or_b32 v7, v8, s72, v7
	ds_read_b32 v8, v5 offset:592
	ds_read_b32 v9, v5 offset:724
	s_waitcnt lgkmcnt(0)
	v_bfe_u32 v10, v8, 16, 1
	v_add3_u32 v8, v8, v10, s73
	v_bfe_u32 v10, v9, 16, 1
	v_lshrrev_b32_e32 v8, 16, v8
	v_add3_u32 v9, v9, v10, s73
	v_and_or_b32 v8, v9, s72, v8
	ds_read_b32 v9, v5 offset:856
	ds_read_b32 v10, v5 offset:988
	s_waitcnt lgkmcnt(0)
	v_bfe_u32 v11, v9, 16, 1
	v_add3_u32 v9, v9, v11, s73
	v_bfe_u32 v11, v10, 16, 1
	v_lshrrev_b32_e32 v9, 16, v9
	v_add3_u32 v10, v10, v11, s73
	v_and_or_b32 v9, v10, s72, v9
	v_lshl_add_u64 v[10:11], v[0:1], 0, v[184:185]
	flat_store_dwordx4 v[10:11], v[6:9] nt
	ds_read_b32 v4, v5 offset:96
	ds_read_b32 v6, v5 offset:228
	v_lshlrev_b32_e32 v184, 12, v2
	v_lshl_add_u64 v[0:1], v[0:1], 0, v[184:185]
	s_waitcnt lgkmcnt(0)
	v_bfe_u32 v7, v4, 16, 1
	v_add3_u32 v4, v4, v7, s73
	v_bfe_u32 v7, v6, 16, 1
	v_lshrrev_b32_e32 v4, 16, v4
	v_add3_u32 v6, v6, v7, s73
	v_and_or_b32 v6, v6, s72, v4
	ds_read_b32 v4, v5 offset:360
	ds_read_b32 v7, v5 offset:492
	s_waitcnt lgkmcnt(0)
	v_bfe_u32 v8, v4, 16, 1
	v_add3_u32 v4, v4, v8, s73
	v_bfe_u32 v8, v7, 16, 1
	v_lshrrev_b32_e32 v4, 16, v4
	v_add3_u32 v7, v7, v8, s73
	v_and_or_b32 v7, v7, s72, v4
	ds_read_b32 v4, v5 offset:624
	ds_read_b32 v8, v5 offset:756
	s_waitcnt lgkmcnt(0)
	v_bfe_u32 v9, v4, 16, 1
	v_add3_u32 v4, v4, v9, s73
	v_bfe_u32 v9, v8, 16, 1
	v_lshrrev_b32_e32 v4, 16, v4
	v_add3_u32 v8, v8, v9, s73
	v_and_or_b32 v8, v8, s72, v4
	ds_read_b32 v4, v5 offset:888
	ds_read_b32 v5, v5 offset:1020
	s_waitcnt lgkmcnt(0)
	v_bfe_u32 v9, v4, 16, 1
	v_add3_u32 v4, v4, v9, s73
	v_bfe_u32 v9, v5, 16, 1
	v_lshrrev_b32_e32 v4, 16, v4
	v_add3_u32 v5, v5, v9, s73
	v_and_or_b32 v9, v5, s72, v4
	flat_store_dwordx4 v[0:1], v[6:9] nt
	s_waitcnt lgkmcnt(0)
	s_or_b64 exec, exec, s[24:25]
	s_and_saveexec_b64 s[12:13], s[26:27]
	s_cbranch_execz .LBB0_1483
	s_branch .LBB0_1466

; #define LAS __attribute__((address_space(3)))
; #define F_LANE() (tid_of(F.wave) & 63)
; #define LDS_WAIT() asm volatile("s_waitcnt lgkmcnt(0)" ::: "memory")
; template <class Map>
; __device__ __forceinline__ void conv_item(const Frame& F, int it, const float* W, int K, int N, bf16_t* WT, const float* gk, int gmask, float gmul, const float* bk, i64* cs, i64* bw, Map map) {
;     LAS float* scr = (LAS float*)(F.lds + F.wave * 16384);
;     const int lane = F_LANE(), nblk = N / 32;
;     {
;         const int kb = it / nblk, nb = it % nblk, k0 = 64 * kb, n0 = 32 * nb, v0 = map(n0);
; #pragma unroll
;         for (int i = 0; i < 8; ++i) { const int kk = 8 * i + (lane >> 3), c4 = (lane & 7) * 4;
;             const f32x4 w4 = __builtin_nontemporal_load((const f32x4*)(W + (size_t)(k0 + kk) * N + n0 + c4)); LAS float* d = scr + kk * 33 + c4; d[0] = w4[0]; d[1] = w4[1]; d[2] = w4[2]; d[3] = w4[3]; }
;         LDS_WAIT(); asm volatile("" ::: "memory");
;         if (bk) {
;             const int n = lane & 31, kh = lane >> 5; float sb = 0.f, sc = 0.f;
; #pragma unroll 8
;             for (int j = 0; j < 32; ++j) { const int kk = kh * 32 + j; const float w = scr[kk * 33 + n]; sb += bk[k0 + kk] * w; sc += bf_round(gk[(k0 + kk) & gmask] * gmul * w); }
;             { auto r = __builtin_amdgcn_permlane32_swap(__float_as_uint(sb), __float_as_uint(sb), false, false); sb = __uint_as_float(r[0]) + __uint_as_float(r[1]); }
;             { auto r = __builtin_amdgcn_permlane32_swap(__float_as_uint(sc), __float_as_uint(sc), false, false); sc = __uint_as_float(r[0]) + __uint_as_float(r[1]); }
;             if (lane < 32) { atomic_addq(bw + v0 + n, sb, FX_COL); atomic_addq(cs + v0 + n, sc, FX_COL); }
;         }
;         const int c = lane & 7; float gl[8];
; #pragma unroll
;         for (int i = 0; i < 8; ++i) gl[i] = gk ? gk[(k0 + 8 * c + i) & gmask] * gmul : 1.0f;
; #pragma unroll
;         for (int j = 0; j < 4; ++j) { const int n = (lane >> 3) + 8 * j; const LAS float* s = scr + (8 * c) * 33 + n;
;             u32x4 o; o.x = pk2(s[0 * 33] * gl[0], s[1 * 33] * gl[1]); o.y = pk2(s[2 * 33] * gl[2], s[3 * 33] * gl[3]); o.z = pk2(s[4 * 33] * gl[4], s[5 * 33] * gl[5]); o.w = pk2(s[6 * 33] * gl[6], s[7 * 33] * gl[7]);
;             __builtin_nontemporal_store(o, (u32x4*)(WT + (size_t)(v0 + n) * K + k0 + 8 * c)); }
.LBB0_1427:
	s_andn2_saveexec_b64 s[84:85], s[12:13]
	s_cbranch_execz .LBB0_1429
	v_readlane_b32 s12, v252, 14
	v_readlane_b32 s13, v252, 15
	s_load_dwordx2 s[12:13], s[12:13], 0x90
	v_readlane_b32 s16, v255, 50
	v_readlane_b32 s17, v255, 51
	v_and_b32_e32 v23, 0xc0, v0
	v_lshlrev_b32_e32 v0, 5, v0
	s_waitcnt lgkmcnt(0)
	s_add_u32 s16, s12, s16
	s_addc_u32 s17, s13, s17
	v_readlane_b32 s12, v252, 12
	v_readlane_b32 s13, v252, 13
	v_mov_b32_e32 v22, v220
	v_and_b32_e32 v2, 0x7e0, v0
	v_lshlrev_b32_e32 v184, 2, v2
	v_bfe_u32 v7, v22, 3, 3
	v_lshlrev_b32_e32 v3, 4, v22
	v_lshl_add_u64 v[0:1], s[16:17], 0, v[184:185]
	v_and_b32_e32 v184, 0x70, v3
	v_or_b32_e32 v3, v7, v23
	v_lshl_add_u64 v[0:1], v[0:1], 0, v[184:185]
	v_lshlrev_b32_e32 v12, 13, v3
	v_mov_b32_e32 v13, v185
	v_lshl_add_u64 v[4:5], v[0:1], 0, v[12:13]
	global_load_dwordx4 v[132:135], v[4:5], off nt
	v_mul_u32_u24_e32 v3, 0x84, v7
	v_or_b32_e32 v6, 8, v7
	v_add3_u32 v13, s79, v184, v3
	v_or_b32_e32 v3, v6, v23
	v_lshlrev_b32_e32 v184, 13, v3
	v_lshl_add_u64 v[4:5], v[0:1], 0, v[184:185]
	v_add_u32_e32 v3, 0x420, v13
	s_add_u32 s12, s12, s58
	s_addc_u32 s13, s13, 0
	v_or_b32_e32 v6, v6, v2
	global_load_dwordx4 v[136:139], v[4:5], off nt
	v_or_b32_e32 v4, 16, v7
	v_add_u32_e32 v3, 0x428, v13
	v_or_b32_e32 v3, v4, v23
	v_lshlrev_b32_e32 v184, 13, v3
	v_lshl_add_u64 v[8:9], v[0:1], 0, v[184:185]
	global_load_dwordx4 v[140:143], v[8:9], off nt
	v_add_u32_e32 v3, 0x840, v13
	v_or_b32_e32 v4, v4, v2
	v_add_u32_e32 v3, 0x848, v13
	v_or_b32_e32 v3, 24, v7
	v_or_b32_e32 v5, v3, v23
	v_lshlrev_b32_e32 v184, 13, v5
	v_lshl_add_u64 v[8:9], v[0:1], 0, v[184:185]
	global_load_dwordx4 v[144:147], v[8:9], off nt
	v_add_u32_e32 v5, 0xc60, v13
	v_or_b32_e32 v184, 0x40000, v12
	v_add_u32_e32 v5, 0xc68, v13
	v_lshl_add_u64 v[8:9], v[0:1], 0, v[184:185]
	global_load_dwordx4 v[148:151], v[8:9], off nt
	v_add_u32_e32 v5, 0x1080, v13
	v_or_b32_e32 v184, 0x50000, v12
	v_add_u32_e32 v5, 0x1088, v13
	v_lshl_add_u64 v[8:9], v[0:1], 0, v[184:185]
	global_load_dwordx4 v[152:155], v[8:9], off nt
	v_add_u32_e32 v5, 0x14a0, v13
	v_or_b32_e32 v184, 0x60000, v12
	v_add_u32_e32 v5, 0x14a8, v13
	v_lshl_add_u64 v[8:9], v[0:1], 0, v[184:185]
	global_load_dwordx4 v[156:159], v[8:9], off nt
	v_add_u32_e32 v5, 0x18c0, v13
	v_or_b32_e32 v184, 0x70000, v12
	v_lshl_add_u64 v[0:1], v[0:1], 0, v[184:185]
	v_lshlrev_b32_e32 v184, 1, v23
	v_add_u32_e32 v5, 0x18c8, v13
	global_load_dwordx4 v[160:163], v[0:1], off nt
	v_add_u32_e32 v0, 0x1ce0, v13
	v_and_b32_e32 v5, 7, v22
	v_add_u32_e32 v0, 0x1ce8, v13
	s_waitcnt vmcnt(0)
	v_add_u32_e32 v164, 0x0, v13
	ds_write2_b32 v164, v132, v133 offset1:1
	ds_write2_b32 v164, v134, v135 offset0:2 offset1:3
	v_add_u32_e32 v164, 0x420, v13
	ds_write2_b32 v164, v136, v137 offset1:1
	ds_write2_b32 v164, v138, v139 offset0:2 offset1:3
	v_add_u32_e32 v164, 0x840, v13
	ds_write2_b32 v164, v140, v141 offset1:1
	ds_write2_b32 v164, v142, v143 offset0:2 offset1:3
	v_add_u32_e32 v164, 0xc60, v13
	ds_write2_b32 v164, v144, v145 offset1:1
	ds_write2_b32 v164, v146, v147 offset0:2 offset1:3
	v_add_u32_e32 v164, 0x1080, v13
	ds_write2_b32 v164, v148, v149 offset1:1
	ds_write2_b32 v164, v150, v151 offset0:2 offset1:3
	v_add_u32_e32 v164, 0x14a0, v13
	ds_write2_b32 v164, v152, v153 offset1:1
	ds_write2_b32 v164, v154, v155 offset0:2 offset1:3
	v_add_u32_e32 v164, 0x18c0, v13
	ds_write2_b32 v164, v156, v157 offset1:1
	ds_write2_b32 v164, v158, v159 offset0:2 offset1:3
	v_add_u32_e32 v164, 0x1ce0, v13
	ds_write2_b32 v164, v160, v161 offset1:1
	ds_write2_b32 v164, v162, v163 offset0:2 offset1:3
	s_waitcnt lgkmcnt(0)
	v_mul_u32_u24_e32 v8, 0x420, v5
	v_lshl_add_u64 v[0:1], s[12:13], 0, v[184:185]
	v_lshlrev_b32_e32 v184, 4, v5
	v_lshlrev_b32_e32 v5, 2, v7
	v_add3_u32 v5, s79, v8, v5
	ds_read_b32 v8, v5
	ds_read_b32 v9, v5 offset:132
	v_lshl_add_u64 v[0:1], v[0:1], 0, v[184:185]
	s_mov_b64 s[12:13], 0x7a00000
	v_or_b32_e32 v7, v7, v2
	s_waitcnt lgkmcnt(1)
	v_bfe_u32 v10, v8, 16, 1
	v_add3_u32 v8, v8, v10, s73
	s_waitcnt lgkmcnt(0)
	v_bfe_u32 v10, v9, 16, 1
	v_lshrrev_b32_e32 v8, 16, v8
	v_add3_u32 v9, v9, v10, s73
	v_and_or_b32 v8, v9, s72, v8
	ds_read_b32 v9, v5 offset:264
	ds_read_b32 v10, v5 offset:396
	v_lshl_add_u64 v[0:1], v[0:1], 0, s[12:13]
	v_lshlrev_b32_e32 v184, 9, v7
	v_or_b32_e32 v2, v3, v2
	s_waitcnt lgkmcnt(1)
; #define LAS __attribute__((address_space(3)))
; #define LDS_WAIT() asm volatile("s_waitcnt lgkmcnt(0)" ::: "memory")
; __device__ __forceinline__ unsigned pk2(float lo, float hi) { return f2bf(lo) | (f2bf(hi) << 16); }
; template <class Map>
; __device__ __forceinline__ void conv_item(const Frame& F, int it, const float* W, int K, int N, bf16_t* WT, const float* gk, int gmask, float gmul, const float* bk, i64* cs, i64* bw, Map map) {
;     ...
;         const int c = lane & 7; float gl[8];
; #pragma unroll
;         for (int i = 0; i < 8; ++i) gl[i] = gk ? gk[(k0 + 8 * c + i) & gmask] * gmul : 1.0f;
; #pragma unroll
;         for (int j = 0; j < 4; ++j) { const int n = (lane >> 3) + 8 * j; const LAS float* s = scr + (8 * c) * 33 + n;
;             u32x4 o; o.x = pk2(s[0 * 33] * gl[0], s[1 * 33] * gl[1]); o.y = pk2(s[2 * 33] * gl[2], s[3 * 33] * gl[3]); o.z = pk2(s[4 * 33] * gl[4], s[5 * 33] * gl[5]); o.w = pk2(s[6 * 33] * gl[6], s[7 * 33] * gl[7]);
;             __builtin_nontemporal_store(o, (u32x4*)(WT + (size_t)(v0 + n) * K + k0 + 8 * c)); }
;         LDS_WAIT(); asm volatile("" ::: "memory");
	v_bfe_u32 v11, v9, 16, 1
	v_add3_u32 v9, v9, v11, s73
	s_waitcnt lgkmcnt(0)
	v_bfe_u32 v11, v10, 16, 1
	v_lshrrev_b32_e32 v9, 16, v9
	v_add3_u32 v10, v10, v11, s73
	v_and_or_b32 v9, v10, s72, v9
	ds_read_b32 v10, v5 offset:528
	ds_read_b32 v11, v5 offset:660
	s_waitcnt lgkmcnt(1)
	v_bfe_u32 v12, v10, 16, 1
	v_add3_u32 v10, v10, v12, s73
	s_waitcnt lgkmcnt(0)
	v_bfe_u32 v12, v11, 16, 1
	v_lshrrev_b32_e32 v10, 16, v10
	v_add3_u32 v11, v11, v12, s73
	v_and_or_b32 v10, v11, s72, v10
	ds_read_b32 v11, v5 offset:792
	ds_read_b32 v12, v5 offset:924
	s_waitcnt lgkmcnt(1)
	v_bfe_u32 v13, v11, 16, 1
	v_add3_u32 v11, v11, v13, s73
	s_waitcnt lgkmcnt(0)
	v_bfe_u32 v13, v12, 16, 1
	v_lshrrev_b32_e32 v11, 16, v11
	v_add3_u32 v12, v12, v13, s73
	v_and_or_b32 v11, v12, s72, v11
	v_lshl_add_u64 v[12:13], v[0:1], 0, v[184:185]
	flat_store_dwordx4 v[12:13], v[8:11] nt
	ds_read_b32 v7, v5 offset:32
	ds_read_b32 v8, v5 offset:164
	v_lshlrev_b32_e32 v184, 9, v6
	s_waitcnt lgkmcnt(0)
	v_bfe_u32 v9, v7, 16, 1
	v_add3_u32 v7, v7, v9, s73
	v_bfe_u32 v9, v8, 16, 1
	v_lshrrev_b32_e32 v7, 16, v7
	v_add3_u32 v8, v8, v9, s73
	v_and_or_b32 v8, v8, s72, v7
	ds_read_b32 v7, v5 offset:296
	ds_read_b32 v9, v5 offset:428
	s_waitcnt lgkmcnt(0)
	v_bfe_u32 v10, v7, 16, 1
	v_add3_u32 v7, v7, v10, s73
	v_bfe_u32 v10, v9, 16, 1
	v_lshrrev_b32_e32 v7, 16, v7
	v_add3_u32 v9, v9, v10, s73
	v_and_or_b32 v9, v9, s72, v7
	ds_read_b32 v7, v5 offset:560
	ds_read_b32 v10, v5 offset:692
	s_waitcnt lgkmcnt(0)
	v_bfe_u32 v11, v7, 16, 1
	v_add3_u32 v7, v7, v11, s73
	v_bfe_u32 v11, v10, 16, 1
	v_lshrrev_b32_e32 v7, 16, v7
	v_add3_u32 v10, v10, v11, s73
	v_and_or_b32 v10, v10, s72, v7
	ds_read_b32 v7, v5 offset:824
	ds_read_b32 v11, v5 offset:956
	s_waitcnt lgkmcnt(0)
	v_bfe_u32 v12, v7, 16, 1
	v_add3_u32 v7, v7, v12, s73
	v_bfe_u32 v12, v11, 16, 1
	v_lshrrev_b32_e32 v7, 16, v7
	v_add3_u32 v11, v11, v12, s73
	v_and_or_b32 v11, v11, s72, v7
	v_lshl_add_u64 v[6:7], v[0:1], 0, v[184:185]
	flat_store_dwordx4 v[6:7], v[8:11] nt
	ds_read_b32 v6, v5 offset:64
	ds_read_b32 v7, v5 offset:196
	v_lshlrev_b32_e32 v184, 9, v4
	s_waitcnt lgkmcnt(0)
	v_bfe_u32 v8, v6, 16, 1
	v_add3_u32 v6, v6, v8, s73
	v_bfe_u32 v8, v7, 16, 1
	v_lshrrev_b32_e32 v6, 16, v6
	v_add3_u32 v7, v7, v8, s73
	v_and_or_b32 v6, v7, s72, v6
	ds_read_b32 v7, v5 offset:328
	ds_read_b32 v8, v5 offset:460
	s_waitcnt lgkmcnt(0)
	v_bfe_u32 v9, v7, 16, 1
	v_add3_u32 v7, v7, v9, s73
	v_bfe_u32 v9, v8, 16, 1
	v_lshrrev_b32_e32 v7, 16, v7
	v_add3_u32 v8, v8, v9, s73
	v_and_or_b32 v7, v8, s72, v7
	ds_read_b32 v8, v5 offset:592
	ds_read_b32 v9, v5 offset:724
	s_waitcnt lgkmcnt(0)
	v_bfe_u32 v10, v8, 16, 1
	v_add3_u32 v8, v8, v10, s73
	v_bfe_u32 v10, v9, 16, 1
	v_lshrrev_b32_e32 v8, 16, v8
	v_add3_u32 v9, v9, v10, s73
	v_and_or_b32 v8, v9, s72, v8
	ds_read_b32 v9, v5 offset:856
	ds_read_b32 v10, v5 offset:988
	s_waitcnt lgkmcnt(0)
	v_bfe_u32 v11, v9, 16, 1
	v_add3_u32 v9, v9, v11, s73
	v_bfe_u32 v11, v10, 16, 1
	v_lshrrev_b32_e32 v9, 16, v9
	v_add3_u32 v10, v10, v11, s73
	v_and_or_b32 v9, v10, s72, v9
	v_lshl_add_u64 v[10:11], v[0:1], 0, v[184:185]
	flat_store_dwordx4 v[10:11], v[6:9] nt
	ds_read_b32 v4, v5 offset:96
	ds_read_b32 v6, v5 offset:228
	v_lshlrev_b32_e32 v184, 9, v2
	v_lshl_add_u64 v[0:1], v[0:1], 0, v[184:185]
	s_waitcnt lgkmcnt(0)
	v_bfe_u32 v7, v4, 16, 1
	v_add3_u32 v4, v4, v7, s73
	v_bfe_u32 v7, v6, 16, 1
	v_lshrrev_b32_e32 v4, 16, v4
	v_add3_u32 v6, v6, v7, s73
	v_and_or_b32 v6, v6, s72, v4
	ds_read_b32 v4, v5 offset:360
	ds_read_b32 v7, v5 offset:492
	s_waitcnt lgkmcnt(0)
	v_bfe_u32 v8, v4, 16, 1
	v_add3_u32 v4, v4, v8, s73
	v_bfe_u32 v8, v7, 16, 1
	v_lshrrev_b32_e32 v4, 16, v4
	v_add3_u32 v7, v7, v8, s73
	v_and_or_b32 v7, v7, s72, v4
	ds_read_b32 v4, v5 offset:624
	ds_read_b32 v8, v5 offset:756
	s_waitcnt lgkmcnt(0)
	v_bfe_u32 v9, v4, 16, 1
	v_add3_u32 v4, v4, v9, s73
	v_bfe_u32 v9, v8, 16, 1
	v_lshrrev_b32_e32 v4, 16, v4
	v_add3_u32 v8, v8, v9, s73
	v_and_or_b32 v8, v8, s72, v4
	ds_read_b32 v4, v5 offset:888
	ds_read_b32 v5, v5 offset:1020
	s_waitcnt lgkmcnt(0)
	v_bfe_u32 v9, v4, 16, 1
	v_add3_u32 v4, v4, v9, s73
	v_bfe_u32 v9, v5, 16, 1
	v_lshrrev_b32_e32 v4, 16, v4
	v_add3_u32 v5, v5, v9, s73
	v_and_or_b32 v9, v5, s72, v4
	flat_store_dwordx4 v[0:1], v[6:9] nt
	s_waitcnt lgkmcnt(0)

; #define LAS __attribute__((address_space(3)))
; __device__ __forceinline__ void atomic_addq(i64* p, float v, float scale) { (void)__hip_atomic_fetch_add((unsigned long long*)p, (unsigned long long)(i64)__builtin_rintf(v * scale), __ATOMIC_RELAXED, __HIP_MEMORY_SCOPE_AGENT); }
; #define F_LANE() (tid_of(F.wave) & 63)
; #define LDS_WAIT() asm volatile("s_waitcnt lgkmcnt(0)" ::: "memory")
; template <class Map>
; __device__ __forceinline__ void conv_item(const Frame& F, int it, const float* W, int K, int N, bf16_t* WT, const float* gk, int gmask, float gmul, const float* bk, i64* cs, i64* bw, Map map) {
;     LAS float* scr = (LAS float*)(F.lds + F.wave * 16384);
;     const int lane = F_LANE(), nblk = N / 32;
;     {
;         const int kb = it / nblk, nb = it % nblk, k0 = 64 * kb, n0 = 32 * nb, v0 = map(n0);
; #pragma unroll
;         for (int i = 0; i < 8; ++i) { const int kk = 8 * i + (lane >> 3), c4 = (lane & 7) * 4;
;             const f32x4 w4 = __builtin_nontemporal_load((const f32x4*)(W + (size_t)(k0 + kk) * N + n0 + c4)); LAS float* d = scr + kk * 33 + c4; d[0] = w4[0]; d[1] = w4[1]; d[2] = w4[2]; d[3] = w4[3]; }
;         LDS_WAIT(); asm volatile("" ::: "memory");
;         if (bk) {
;             const int n = lane & 31, kh = lane >> 5; float sb = 0.f, sc = 0.f;
; #pragma unroll 8
;             for (int j = 0; j < 32; ++j) { const int kk = kh * 32 + j; const float w = scr[kk * 33 + n]; sb += bk[k0 + kk] * w; sc += bf_round(gk[(k0 + kk) & gmask] * gmul * w); }
;             { auto r = __builtin_amdgcn_permlane32_swap(__float_as_uint(sb), __float_as_uint(sb), false, false); sb = __uint_as_float(r[0]) + __uint_as_float(r[1]); }
;             { auto r = __builtin_amdgcn_permlane32_swap(__float_as_uint(sc), __float_as_uint(sc), false, false); sc = __uint_as_float(r[0]) + __uint_as_float(r[1]); }
;             if (lane < 32) { atomic_addq(bw + v0 + n, sb, FX_COL); atomic_addq(cs + v0 + n, sc, FX_COL); }
;         }
;         const int c = lane & 7; float gl[8];
; #pragma unroll
;         for (int i = 0; i < 8; ++i) gl[i] = gk ? gk[(k0 + 8 * c + i) & gmask] * gmul : 1.0f;
; __device__ BG_ATTR void bg_item(const Frame& F, unsigned char* ws, const int L, int id) {
;     ...
;     if (id < NI_G) { conv_item(F, id, INP(17) + (size_t)L * DM * DM, DM, DM, Wg, g2, DM - 1, 1.f, b2, csFq + 22528, csFq + 24576, MapIdent()); return; } id -= NI_G;
.LBB0_1430:
	s_andn2_saveexec_b64 s[56:57], s[56:57]
	s_cbranch_execz .LBB0_1436
	v_readlane_b32 s48, v252, 14
	v_readlane_b32 s49, v252, 15
	s_mov_b64 s[12:13], s[48:49]
	s_load_dwordx2 s[12:13], s[12:13], 0x88
	v_readlane_b32 s16, v255, 58
	v_readlane_b32 s84, v252, 12
	v_readlane_b32 s17, v255, 59
	v_readlane_b32 s85, v252, 13
	s_waitcnt lgkmcnt(0)
	s_add_u32 s16, s12, s16
	s_mov_b32 s21, s58
	s_addc_u32 s17, s13, s17
	s_mov_b64 s[58:59], s[84:85]
	s_mov_b64 s[12:13], s[48:49]
	s_mov_b32 vcc_lo, s79
	s_load_dwordx2 s[78:79], s[12:13], 0x68
	v_readlane_b32 s12, v255, 56
	v_readlane_b32 s13, v255, 57
	s_lshl_b64 s[12:13], s[12:13], 2
	v_add_u32_e32 v10, 0xbe00, v0
	s_waitcnt lgkmcnt(0)
	s_add_u32 s12, s78, s12
	s_addc_u32 s13, s79, s13
	s_add_u32 s86, s12, 0x2000
	s_addc_u32 s87, s13, 0
	s_mov_b64 s[12:13], s[48:49]
	v_lshlrev_b32_e32 v0, 5, v0
	s_load_dwordx2 s[96:97], s[12:13], 0x70
	s_mov_b64 s[12:13], s[84:85]
	s_mov_b64 s[48:49], s[84:85]
	v_mov_b32_e32 v24, v220
	v_and_b32_e32 v8, 0x7e0, v0
	v_lshlrev_b32_e32 v184, 2, v8
	v_lshlrev_b32_e32 v2, 4, v24
	v_and_b32_e32 v23, 0xffc0, v10
	v_bfe_u32 v22, v24, 3, 3
	v_lshl_add_u64 v[0:1], s[16:17], 0, v[184:185]
	v_and_b32_e32 v184, 0x70, v2
	v_lshl_add_u64 v[4:5], v[0:1], 0, v[184:185]
	v_or_b32_e32 v0, v22, v23
	v_lshlrev_b32_e32 v6, 13, v0
	v_mov_b32_e32 v7, v185
	v_lshl_add_u64 v[0:1], v[4:5], 0, v[6:7]
	global_load_dwordx4 v[132:135], v[0:1], off nt
	v_mul_u32_u24_e32 v7, 0x84, v22
	v_add3_u32 v7, vcc_lo, v184, v7
	v_or_b32_e32 v13, 8, v22
	v_add_u32_e32 v9, 0x420, v7
	v_or_b32_e32 v12, 16, v22
	v_add_u32_e32 v11, 0xc60, v7
	v_readlane_b32 s84, v255, 25
	s_add_u32 s16, s78, s84
	s_movk_i32 s78, 0x7c0
	v_readlane_b32 s85, v255, 26
	s_addc_u32 s17, s79, s85
	v_and_b32_e32 v26, 31, v24
	v_and_or_b32 v27, v24, 32, v23
	v_and_b32_e32 v25, 63, v24
	v_or_b32_e32 v0, v13, v23
	v_lshlrev_b32_e32 v184, 13, v0
	v_lshl_add_u64 v[0:1], v[4:5], 0, v[184:185]
	global_load_dwordx4 v[136:139], v[0:1], off nt
	v_add_u32_e32 v0, 0x428, v7
	v_or_b32_e32 v0, v12, v23
	v_lshlrev_b32_e32 v184, 13, v0
	v_lshl_add_u64 v[0:1], v[4:5], 0, v[184:185]
	global_load_dwordx4 v[140:143], v[0:1], off nt
	v_add_u32_e32 v9, 0x840, v7
	v_add_u32_e32 v0, 0x848, v7
	v_or_b32_e32 v9, 24, v22
	v_or_b32_e32 v0, v9, v23
	v_lshlrev_b32_e32 v184, 13, v0
	v_lshl_add_u64 v[0:1], v[4:5], 0, v[184:185]
	global_load_dwordx4 v[144:147], v[0:1], off nt
	v_or_b32_e32 v184, 0x40000, v6
	v_add_u32_e32 v0, 0xc68, v7
	v_lshl_add_u64 v[0:1], v[4:5], 0, v[184:185]
	global_load_dwordx4 v[148:151], v[0:1], off nt
	v_add_u32_e32 v11, 0x1080, v7
	v_or_b32_e32 v184, 0x50000, v6
	v_add_u32_e32 v0, 0x1088, v7
	v_lshl_add_u64 v[0:1], v[4:5], 0, v[184:185]
	global_load_dwordx4 v[152:155], v[0:1], off nt
	v_add_u32_e32 v11, 0x14a0, v7
	v_or_b32_e32 v184, 0x60000, v6
	v_add_u32_e32 v0, 0x14a8, v7
	v_lshl_add_u64 v[0:1], v[4:5], 0, v[184:185]
	global_load_dwordx4 v[156:159], v[0:1], off nt
	v_add_u32_e32 v11, 0x18c0, v7
	v_or_b32_e32 v184, 0x70000, v6
	v_add_u32_e32 v0, 0x18c8, v7
	v_lshl_add_u64 v[0:1], v[4:5], 0, v[184:185]
	global_load_dwordx4 v[160:163], v[0:1], off nt
	v_add_u32_e32 v4, 0x1ce0, v7
	v_add_u32_e32 v0, 0x1ce8, v7
	s_waitcnt vmcnt(0)
	v_add_u32_e32 v164, 0x0, v7
	ds_write2_b32 v164, v132, v133 offset1:1
	ds_write2_b32 v164, v134, v135 offset0:2 offset1:3
	v_add_u32_e32 v164, 0x420, v7
	ds_write2_b32 v164, v136, v137 offset1:1
	ds_write2_b32 v164, v138, v139 offset0:2 offset1:3
	v_add_u32_e32 v164, 0x840, v7
	ds_write2_b32 v164, v140, v141 offset1:1
	ds_write2_b32 v164, v142, v143 offset0:2 offset1:3
	v_add_u32_e32 v164, 0xc60, v7
	ds_write2_b32 v164, v144, v145 offset1:1
	ds_write2_b32 v164, v146, v147 offset0:2 offset1:3
	v_add_u32_e32 v164, 0x1080, v7
	ds_write2_b32 v164, v148, v149 offset1:1
	ds_write2_b32 v164, v150, v151 offset0:2 offset1:3
	v_add_u32_e32 v164, 0x14a0, v7
	ds_write2_b32 v164, v152, v153 offset1:1
	ds_write2_b32 v164, v154, v155 offset0:2 offset1:3
	v_add_u32_e32 v164, 0x18c0, v7
	ds_write2_b32 v164, v156, v157 offset1:1
	ds_write2_b32 v164, v158, v159 offset0:2 offset1:3
	v_add_u32_e32 v164, 0x1ce0, v7
	ds_write2_b32 v164, v160, v161 offset1:1
	ds_write2_b32 v164, v162, v163 offset0:2 offset1:3
	v_lshrrev_b32_e32 v0, 5, v24
	v_and_b32_e32 v0, 1, v0
	v_lshlrev_b16_e32 v0, 5, v0
	v_bitop3_b16 v0, v10, v0, s78 bitop3:0xec
	s_waitcnt lgkmcnt(0)
	v_lshlrev_b32_sdwa v184, v227, v0 dst_sel:DWORD dst_unused:UNUSED_PAD src0_sel:DWORD src1_sel:WORD_0
	v_bfe_u32 v0, v24, 5, 1
	v_lshl_add_u64 v[4:5], s[16:17], 0, v[184:185]
	s_waitcnt lgkmcnt(0)
	s_add_u32 s16, s96, s84
	v_mul_u32_u24_e32 v0, 0x1080, v0
	s_addc_u32 s17, s97, s85
	v_lshlrev_b32_e32 v184, 2, v27
	v_lshl_or_b32 v0, v26, 2, v0
	v_mov_b32_e32 v10, 0
	v_lshl_add_u64 v[6:7], s[16:17], 0, v[184:185]
	v_add_u32_e32 v28, vcc_lo, v0
	s_mov_b64 s[96:97], 0
	v_mov_b32_e32 v11, v10
	s_movk_i32 s16, 0x2000
	s_mov_b64 s[78:79], 0x2000

; #define LAS __attribute__((address_space(3)))
; #define F_LANE() (tid_of(F.wave) & 63)
; #define LDS_WAIT() asm volatile("s_waitcnt lgkmcnt(0)" ::: "memory")
; template <class Map>
; __device__ __forceinline__ void conv_item(const Frame& F, int it, const float* W, int K, int N, bf16_t* WT, const float* gk, int gmask, float gmul, const float* bk, i64* cs, i64* bw, Map map) {
;     LAS float* scr = (LAS float*)(F.lds + F.wave * 16384);
;     const int lane = F_LANE(), nblk = N / 32;
;     {
;         const int kb = it / nblk, nb = it % nblk, k0 = 64 * kb, n0 = 32 * nb, v0 = map(n0);
; #pragma unroll
;         for (int i = 0; i < 8; ++i) { const int kk = 8 * i + (lane >> 3), c4 = (lane & 7) * 4;
;             const f32x4 w4 = __builtin_nontemporal_load((const f32x4*)(W + (size_t)(k0 + kk) * N + n0 + c4)); LAS float* d = scr + kk * 33 + c4; d[0] = w4[0]; d[1] = w4[1]; d[2] = w4[2]; d[3] = w4[3]; }
;         LDS_WAIT(); asm volatile("" ::: "memory");
;         if (bk) {
;             const int n = lane & 31, kh = lane >> 5; float sb = 0.f, sc = 0.f;
; #pragma unroll 8
;             for (int j = 0; j < 32; ++j) { const int kk = kh * 32 + j; const float w = scr[kk * 33 + n]; sb += bk[k0 + kk] * w; sc += bf_round(gk[(k0 + kk) & gmask] * gmul * w); }
;             { auto r = __builtin_amdgcn_permlane32_swap(__float_as_uint(sb), __float_as_uint(sb), false, false); sb = __uint_as_float(r[0]) + __uint_as_float(r[1]); }
;             { auto r = __builtin_amdgcn_permlane32_swap(__float_as_uint(sc), __float_as_uint(sc), false, false); sc = __uint_as_float(r[0]) + __uint_as_float(r[1]); }
;             if (lane < 32) { atomic_addq(bw + v0 + n, sb, FX_COL); atomic_addq(cs + v0 + n, sc, FX_COL); }
;         }
;         const int c = lane & 7; float gl[8];
; #pragma unroll
;         for (int i = 0; i < 8; ++i) gl[i] = gk ? gk[(k0 + 8 * c + i) & gmask] * gmul : 1.0f;
; #pragma unroll
;         for (int j = 0; j < 4; ++j) { const int n = (lane >> 3) + 8 * j; const LAS float* s = scr + (8 * c) * 33 + n;
;             u32x4 o; o.x = pk2(s[0 * 33] * gl[0], s[1 * 33] * gl[1]); o.y = pk2(s[2 * 33] * gl[2], s[3 * 33] * gl[3]); o.z = pk2(s[4 * 33] * gl[4], s[5 * 33] * gl[5]); o.w = pk2(s[6 * 33] * gl[6], s[7 * 33] * gl[7]);
;             __builtin_nontemporal_store(o, (u32x4*)(WT + (size_t)(v0 + n) * K + k0 + 8 * c)); }
.LBB0_1437:
	s_andn2_saveexec_b64 s[56:57], s[92:93]
	s_cbranch_execz .LBB0_1439
	v_readlane_b32 s12, v252, 14
	v_readlane_b32 s13, v252, 15
	s_load_dwordx2 s[12:13], s[12:13], 0x80
	s_mul_i32 s16, s20, 0x2c00000
	v_add_u32_e32 v1, 0xd400, v0
	v_lshlrev_b32_e32 v0, 5, v0
	v_mov_b32_e32 v22, v220
	s_waitcnt lgkmcnt(0)
	s_add_u32 s16, s12, s16
	s_mul_hi_i32 s12, s20, 0x2c00000
	s_addc_u32 s17, s13, s12
	v_readlane_b32 s12, v252, 12
	v_readlane_b32 s13, v252, 13
	v_and_b32_e32 v2, 0x7e0, v0
	v_and_b32_e32 v23, 0xffc0, v1
	v_bfe_u32 v7, v22, 3, 3
	v_lshlrev_b32_e32 v184, 2, v2
	v_lshlrev_b32_e32 v3, 4, v22
	v_lshl_add_u64 v[0:1], s[16:17], 0, v[184:185]
	v_and_b32_e32 v184, 0x70, v3
	v_or_b32_e32 v3, v7, v23
	v_lshl_add_u64 v[0:1], v[0:1], 0, v[184:185]
	v_lshlrev_b32_e32 v12, 13, v3
	v_mov_b32_e32 v13, v185
	v_lshl_add_u64 v[4:5], v[0:1], 0, v[12:13]
	global_load_dwordx4 v[132:135], v[4:5], off nt
	v_mul_u32_u24_e32 v3, 0x84, v7
	v_or_b32_e32 v6, 8, v7
	v_add3_u32 v13, s79, v184, v3
	v_or_b32_e32 v3, v6, v23
	v_lshlrev_b32_e32 v184, 13, v3
	v_lshl_add_u64 v[4:5], v[0:1], 0, v[184:185]
	v_add_u32_e32 v3, 0x420, v13
	s_add_u32 s12, s12, s58
	s_addc_u32 s13, s13, 0
	v_or_b32_e32 v6, v6, v2
	v_mul_u32_u24_e32 v6, 0x1600, v6
	global_load_dwordx4 v[136:139], v[4:5], off nt
	v_or_b32_e32 v4, 16, v7
	v_add_u32_e32 v3, 0x428, v13
	v_or_b32_e32 v3, v4, v23
	v_lshlrev_b32_e32 v184, 13, v3
	v_lshl_add_u64 v[8:9], v[0:1], 0, v[184:185]
	global_load_dwordx4 v[140:143], v[8:9], off nt
	v_add_u32_e32 v3, 0x840, v13
	v_or_b32_e32 v4, v4, v2
	v_mul_u32_u24_e32 v4, 0x1600, v4
	v_add_u32_e32 v3, 0x848, v13
	v_or_b32_e32 v3, 24, v7
	v_or_b32_e32 v5, v3, v23
	v_lshlrev_b32_e32 v184, 13, v5
	v_lshl_add_u64 v[8:9], v[0:1], 0, v[184:185]
	global_load_dwordx4 v[144:147], v[8:9], off nt
	v_add_u32_e32 v5, 0xc60, v13
	v_or_b32_e32 v184, 0x40000, v12
	v_add_u32_e32 v5, 0xc68, v13
	v_lshl_add_u64 v[8:9], v[0:1], 0, v[184:185]
	global_load_dwordx4 v[148:151], v[8:9], off nt
	v_add_u32_e32 v5, 0x1080, v13
	v_or_b32_e32 v184, 0x50000, v12
	v_add_u32_e32 v5, 0x1088, v13
	v_lshl_add_u64 v[8:9], v[0:1], 0, v[184:185]
	global_load_dwordx4 v[152:155], v[8:9], off nt
	v_add_u32_e32 v5, 0x14a0, v13
	v_or_b32_e32 v184, 0x60000, v12
	v_add_u32_e32 v5, 0x14a8, v13
	v_lshl_add_u64 v[8:9], v[0:1], 0, v[184:185]
	global_load_dwordx4 v[156:159], v[8:9], off nt
	v_add_u32_e32 v5, 0x18c0, v13
	v_or_b32_e32 v184, 0x70000, v12
	v_lshl_add_u64 v[0:1], v[0:1], 0, v[184:185]
	v_lshlrev_b32_e32 v184, 1, v23
	v_add_u32_e32 v5, 0x18c8, v13
	global_load_dwordx4 v[160:163], v[0:1], off nt
	v_add_u32_e32 v0, 0x1ce0, v13
	v_and_b32_e32 v5, 7, v22
	v_add_u32_e32 v0, 0x1ce8, v13
	s_waitcnt vmcnt(0)
	v_add_u32_e32 v164, 0x0, v13
	ds_write2_b32 v164, v132, v133 offset1:1
	ds_write2_b32 v164, v134, v135 offset0:2 offset1:3
	v_add_u32_e32 v164, 0x420, v13
	ds_write2_b32 v164, v136, v137 offset1:1
	ds_write2_b32 v164, v138, v139 offset0:2 offset1:3
	v_add_u32_e32 v164, 0x840, v13
	ds_write2_b32 v164, v140, v141 offset1:1
	ds_write2_b32 v164, v142, v143 offset0:2 offset1:3
	v_add_u32_e32 v164, 0xc60, v13
	ds_write2_b32 v164, v144, v145 offset1:1
	ds_write2_b32 v164, v146, v147 offset0:2 offset1:3
	v_add_u32_e32 v164, 0x1080, v13
	ds_write2_b32 v164, v148, v149 offset1:1
	ds_write2_b32 v164, v150, v151 offset0:2 offset1:3
	v_add_u32_e32 v164, 0x14a0, v13
	ds_write2_b32 v164, v152, v153 offset1:1
	ds_write2_b32 v164, v154, v155 offset0:2 offset1:3
	v_add_u32_e32 v164, 0x18c0, v13
	ds_write2_b32 v164, v156, v157 offset1:1
	ds_write2_b32 v164, v158, v159 offset0:2 offset1:3
	v_add_u32_e32 v164, 0x1ce0, v13
	ds_write2_b32 v164, v160, v161 offset1:1
	ds_write2_b32 v164, v162, v163 offset0:2 offset1:3
	s_waitcnt lgkmcnt(0)
	v_mul_u32_u24_e32 v8, 0x420, v5
	v_lshl_add_u64 v[0:1], s[12:13], 0, v[184:185]
	v_lshlrev_b32_e32 v184, 4, v5
	v_lshlrev_b32_e32 v5, 2, v7
	v_add3_u32 v5, s79, v8, v5
	ds_read_b32 v8, v5
	ds_read_b32 v9, v5 offset:132
	v_or_b32_e32 v7, v7, v2
	v_lshl_add_u64 v[0:1], v[0:1], 0, v[184:185]
	s_mov_b64 s[12:13], 0x5c00000
	s_waitcnt lgkmcnt(1)
	v_bfe_u32 v10, v8, 16, 1
	v_add3_u32 v8, v8, v10, s73
	s_waitcnt lgkmcnt(0)
	v_bfe_u32 v10, v9, 16, 1
	v_lshrrev_b32_e32 v8, 16, v8
	v_add3_u32 v9, v9, v10, s73
	v_and_or_b32 v8, v9, s72, v8
	ds_read_b32 v9, v5 offset:264
	ds_read_b32 v10, v5 offset:396
	v_mul_u32_u24_e32 v7, 0x1600, v7
	v_lshl_add_u64 v[0:1], v[0:1], 0, s[12:13]
	v_lshlrev_b32_e32 v184, 1, v7
	s_waitcnt lgkmcnt(1)
; #define LAS __attribute__((address_space(3)))
; #define LDS_WAIT() asm volatile("s_waitcnt lgkmcnt(0)" ::: "memory")
; __device__ __forceinline__ unsigned pk2(float lo, float hi) { return f2bf(lo) | (f2bf(hi) << 16); }
; template <class Map>
; __device__ __forceinline__ void conv_item(const Frame& F, int it, const float* W, int K, int N, bf16_t* WT, const float* gk, int gmask, float gmul, const float* bk, i64* cs, i64* bw, Map map) {
;     ...
;         const int c = lane & 7; float gl[8];
; #pragma unroll
;         for (int i = 0; i < 8; ++i) gl[i] = gk ? gk[(k0 + 8 * c + i) & gmask] * gmul : 1.0f;
; #pragma unroll
;         for (int j = 0; j < 4; ++j) { const int n = (lane >> 3) + 8 * j; const LAS float* s = scr + (8 * c) * 33 + n;
;             u32x4 o; o.x = pk2(s[0 * 33] * gl[0], s[1 * 33] * gl[1]); o.y = pk2(s[2 * 33] * gl[2], s[3 * 33] * gl[3]); o.z = pk2(s[4 * 33] * gl[4], s[5 * 33] * gl[5]); o.w = pk2(s[6 * 33] * gl[6], s[7 * 33] * gl[7]);
;             __builtin_nontemporal_store(o, (u32x4*)(WT + (size_t)(v0 + n) * K + k0 + 8 * c)); }
;         LDS_WAIT(); asm volatile("" ::: "memory");
	v_bfe_u32 v11, v9, 16, 1
	v_add3_u32 v9, v9, v11, s73
	s_waitcnt lgkmcnt(0)
	v_bfe_u32 v11, v10, 16, 1
	v_lshrrev_b32_e32 v9, 16, v9
	v_add3_u32 v10, v10, v11, s73
	v_and_or_b32 v9, v10, s72, v9
	ds_read_b32 v10, v5 offset:528
	ds_read_b32 v11, v5 offset:660
	v_or_b32_e32 v2, v3, v2
	v_mul_u32_u24_e32 v2, 0x1600, v2
	s_waitcnt lgkmcnt(1)
	v_bfe_u32 v12, v10, 16, 1
	v_add3_u32 v10, v10, v12, s73
	s_waitcnt lgkmcnt(0)
	v_bfe_u32 v12, v11, 16, 1
	v_lshrrev_b32_e32 v10, 16, v10
	v_add3_u32 v11, v11, v12, s73
	v_and_or_b32 v10, v11, s72, v10
	ds_read_b32 v11, v5 offset:792
	ds_read_b32 v12, v5 offset:924
	s_waitcnt lgkmcnt(1)
	v_bfe_u32 v13, v11, 16, 1
	v_add3_u32 v11, v11, v13, s73
	s_waitcnt lgkmcnt(0)
	v_bfe_u32 v13, v12, 16, 1
	v_lshrrev_b32_e32 v11, 16, v11
	v_add3_u32 v12, v12, v13, s73
	v_and_or_b32 v11, v12, s72, v11
	v_lshl_add_u64 v[12:13], v[0:1], 0, v[184:185]
	flat_store_dwordx4 v[12:13], v[8:11] nt
	ds_read_b32 v7, v5 offset:32
	ds_read_b32 v8, v5 offset:164
	v_lshlrev_b32_e32 v184, 1, v6
	s_waitcnt lgkmcnt(0)
	v_bfe_u32 v9, v7, 16, 1
	v_add3_u32 v7, v7, v9, s73
	v_bfe_u32 v9, v8, 16, 1
	v_lshrrev_b32_e32 v7, 16, v7
	v_add3_u32 v8, v8, v9, s73
	v_and_or_b32 v8, v8, s72, v7
	ds_read_b32 v7, v5 offset:296
	ds_read_b32 v9, v5 offset:428
	s_waitcnt lgkmcnt(0)
	v_bfe_u32 v10, v7, 16, 1
	v_add3_u32 v7, v7, v10, s73
	v_bfe_u32 v10, v9, 16, 1
	v_lshrrev_b32_e32 v7, 16, v7
	v_add3_u32 v9, v9, v10, s73
	v_and_or_b32 v9, v9, s72, v7
	ds_read_b32 v7, v5 offset:560
	ds_read_b32 v10, v5 offset:692
	s_waitcnt lgkmcnt(0)
	v_bfe_u32 v11, v7, 16, 1
	v_add3_u32 v7, v7, v11, s73
	v_bfe_u32 v11, v10, 16, 1
	v_lshrrev_b32_e32 v7, 16, v7
	v_add3_u32 v10, v10, v11, s73
	v_and_or_b32 v10, v10, s72, v7
	ds_read_b32 v7, v5 offset:824
	ds_read_b32 v11, v5 offset:956
	s_waitcnt lgkmcnt(0)
	v_bfe_u32 v12, v7, 16, 1
	v_add3_u32 v7, v7, v12, s73
	v_bfe_u32 v12, v11, 16, 1
	v_lshrrev_b32_e32 v7, 16, v7
	v_add3_u32 v11, v11, v12, s73
	v_and_or_b32 v11, v11, s72, v7
	v_lshl_add_u64 v[6:7], v[0:1], 0, v[184:185]
	flat_store_dwordx4 v[6:7], v[8:11] nt
	ds_read_b32 v6, v5 offset:64
	ds_read_b32 v7, v5 offset:196
	v_lshlrev_b32_e32 v184, 1, v4
	s_waitcnt lgkmcnt(0)
	v_bfe_u32 v8, v6, 16, 1
	v_add3_u32 v6, v6, v8, s73
	v_bfe_u32 v8, v7, 16, 1
	v_lshrrev_b32_e32 v6, 16, v6
	v_add3_u32 v7, v7, v8, s73
	v_and_or_b32 v6, v7, s72, v6
	ds_read_b32 v7, v5 offset:328
	ds_read_b32 v8, v5 offset:460
	s_waitcnt lgkmcnt(0)
	v_bfe_u32 v9, v7, 16, 1
	v_add3_u32 v7, v7, v9, s73
	v_bfe_u32 v9, v8, 16, 1
	v_lshrrev_b32_e32 v7, 16, v7
	v_add3_u32 v8, v8, v9, s73
	v_and_or_b32 v7, v8, s72, v7
	ds_read_b32 v8, v5 offset:592
	ds_read_b32 v9, v5 offset:724
	s_waitcnt lgkmcnt(0)
	v_bfe_u32 v10, v8, 16, 1
	v_add3_u32 v8, v8, v10, s73
	v_bfe_u32 v10, v9, 16, 1
	v_lshrrev_b32_e32 v8, 16, v8
	v_add3_u32 v9, v9, v10, s73
	v_and_or_b32 v8, v9, s72, v8
	ds_read_b32 v9, v5 offset:856
	ds_read_b32 v10, v5 offset:988
	s_waitcnt lgkmcnt(0)
	v_bfe_u32 v11, v9, 16, 1
	v_add3_u32 v9, v9, v11, s73
	v_bfe_u32 v11, v10, 16, 1
	v_lshrrev_b32_e32 v9, 16, v9
	v_add3_u32 v10, v10, v11, s73
	v_and_or_b32 v9, v10, s72, v9
	v_lshl_add_u64 v[10:11], v[0:1], 0, v[184:185]
	flat_store_dwordx4 v[10:11], v[6:9] nt
	ds_read_b32 v4, v5 offset:96
	ds_read_b32 v6, v5 offset:228
	v_lshlrev_b32_e32 v184, 1, v2
	v_lshl_add_u64 v[0:1], v[0:1], 0, v[184:185]
	s_waitcnt lgkmcnt(0)
	v_bfe_u32 v7, v4, 16, 1
	v_add3_u32 v4, v4, v7, s73
	v_bfe_u32 v7, v6, 16, 1
	v_lshrrev_b32_e32 v4, 16, v4
	v_add3_u32 v6, v6, v7, s73
	v_and_or_b32 v6, v6, s72, v4
	ds_read_b32 v4, v5 offset:360
	ds_read_b32 v7, v5 offset:492
	s_waitcnt lgkmcnt(0)
	v_bfe_u32 v8, v4, 16, 1
	v_add3_u32 v4, v4, v8, s73
	v_bfe_u32 v8, v7, 16, 1
	v_lshrrev_b32_e32 v4, 16, v4
	v_add3_u32 v7, v7, v8, s73
	v_and_or_b32 v7, v7, s72, v4
	ds_read_b32 v4, v5 offset:624
	ds_read_b32 v8, v5 offset:756
	s_waitcnt lgkmcnt(0)
	v_bfe_u32 v9, v4, 16, 1
	v_add3_u32 v4, v4, v9, s73
	v_bfe_u32 v9, v8, 16, 1
	v_lshrrev_b32_e32 v4, 16, v4
	v_add3_u32 v8, v8, v9, s73
	v_and_or_b32 v8, v8, s72, v4
	ds_read_b32 v4, v5 offset:888
	ds_read_b32 v5, v5 offset:1020
	s_waitcnt lgkmcnt(0)
	v_bfe_u32 v9, v4, 16, 1
	v_add3_u32 v4, v4, v9, s73
	v_bfe_u32 v9, v5, 16, 1
	v_lshrrev_b32_e32 v4, 16, v4
	v_add3_u32 v5, v5, v9, s73
	v_and_or_b32 v9, v5, s72, v4
	flat_store_dwordx4 v[0:1], v[6:9] nt
	s_waitcnt lgkmcnt(0)

; #define LAS __attribute__((address_space(3)))
; __device__ __forceinline__ void atomic_addq(i64* p, float v, float scale) { (void)__hip_atomic_fetch_add((unsigned long long*)p, (unsigned long long)(i64)__builtin_rintf(v * scale), __ATOMIC_RELAXED, __HIP_MEMORY_SCOPE_AGENT); }
; #define F_LANE() (tid_of(F.wave) & 63)
; #define LDS_WAIT() asm volatile("s_waitcnt lgkmcnt(0)" ::: "memory")
; template <class Map>
; __device__ __forceinline__ void conv_item(const Frame& F, int it, const float* W, int K, int N, bf16_t* WT, const float* gk, int gmask, float gmul, const float* bk, i64* cs, i64* bw, Map map) {
;     LAS float* scr = (LAS float*)(F.lds + F.wave * 16384);
;     const int lane = F_LANE(), nblk = N / 32;
;     {
;         const int kb = it / nblk, nb = it % nblk, k0 = 64 * kb, n0 = 32 * nb, v0 = map(n0);
; #pragma unroll
;         for (int i = 0; i < 8; ++i) { const int kk = 8 * i + (lane >> 3), c4 = (lane & 7) * 4;
;             const f32x4 w4 = __builtin_nontemporal_load((const f32x4*)(W + (size_t)(k0 + kk) * N + n0 + c4)); LAS float* d = scr + kk * 33 + c4; d[0] = w4[0]; d[1] = w4[1]; d[2] = w4[2]; d[3] = w4[3]; }
;         LDS_WAIT(); asm volatile("" ::: "memory");
;         if (bk) {
;             const int n = lane & 31, kh = lane >> 5; float sb = 0.f, sc = 0.f;
; #pragma unroll 8
;             for (int j = 0; j < 32; ++j) { const int kk = kh * 32 + j; const float w = scr[kk * 33 + n]; sb += bk[k0 + kk] * w; sc += bf_round(gk[(k0 + kk) & gmask] * gmul * w); }
;             { auto r = __builtin_amdgcn_permlane32_swap(__float_as_uint(sb), __float_as_uint(sb), false, false); sb = __uint_as_float(r[0]) + __uint_as_float(r[1]); }
;             { auto r = __builtin_amdgcn_permlane32_swap(__float_as_uint(sc), __float_as_uint(sc), false, false); sc = __uint_as_float(r[0]) + __uint_as_float(r[1]); }
;             if (lane < 32) { atomic_addq(bw + v0 + n, sb, FX_COL); atomic_addq(cs + v0 + n, sc, FX_COL); }
;         }
;         const int c = lane & 7; float gl[8];
; #pragma unroll
;         for (int i = 0; i < 8; ++i) gl[i] = gk ? gk[(k0 + 8 * c + i) & gmask] * gmul : 1.0f;
; __device__ BG_ATTR void bg_item(const Frame& F, unsigned char* ws, const int L, int id) {
;     ...
;     if (id < NI_F1) { conv_item(F, id, INP(15) + (size_t)L * DM * 2 * DFF, DM, 2 * DFF, Wf1, g1, DM - 1, 1.f, b1, csFq, csFq + 11264, MapSwiglu()); return; } id -= NI_F1;
.LBB0_1440:
	s_andn2_saveexec_b64 s[56:57], s[42:43]
	s_cbranch_execz .LBB0_1464
	v_readlane_b32 s42, v252, 14
	v_readlane_b32 s43, v252, 15
	s_mov_b64 s[12:13], s[42:43]
	s_load_dwordx2 s[12:13], s[12:13], 0x78
	s_mul_i32 s16, s20, 0x5800000
	v_readlane_b32 s96, v252, 12
	v_readlane_b32 s97, v252, 13
	s_mov_b64 s[84:85], s[96:97]
	s_waitcnt lgkmcnt(0)
	s_add_u32 s78, s12, s16
	s_mul_hi_i32 s12, s20, 0x5800000
	s_addc_u32 s79, s13, s12
	s_mov_b64 s[12:13], s[42:43]
	s_load_dwordx2 s[92:93], s[12:13], 0x68
	v_readlane_b32 s12, v255, 56
	s_mov_b32 s16, 0xba2f
	v_readlane_b32 s13, v255, 57
	v_mul_u32_u24_sdwa v1, v0, s16 dst_sel:DWORD dst_unused:UNUSED_PAD src0_sel:WORD_0 src1_sel:DWORD
	s_movk_i32 s16, 0x160
	s_lshl_b64 s[12:13], s[12:13], 2
	v_mul_lo_u16_sdwa v2, v1, s16 dst_sel:DWORD dst_unused:UNUSED_PAD src0_sel:BYTE_3 src1_sel:DWORD
	s_waitcnt lgkmcnt(0)
	s_add_u32 s86, s92, s12
	v_sub_u16_e32 v2, v0, v2
	v_mov_b32_e32 v4, 6
	s_movk_i32 s16, 0xaf
	s_addc_u32 s87, s93, s13
	s_mov_b64 s[12:13], s[42:43]
	v_lshlrev_b16_sdwa v26, v4, v1 dst_sel:DWORD dst_unused:UNUSED_PAD src0_sel:DWORD src1_sel:BYTE_3
	v_lshlrev_b16_e32 v1, 5, v2
	v_cmp_lt_u16_e32 vcc, s16, v2
	s_movk_i32 s16, 0xb0
	s_mov_b64 s[48:49], s[96:97]
	v_mov_b32_e32 v3, v220
	v_add_u16_e32 v4, 0xea00, v1
	v_cmp_gt_u16_e64 s[42:43], s16, v2
	s_load_dwordx2 s[12:13], s[12:13], 0x70
	v_lshlrev_b32_e32 v184, 2, v1
	v_cndmask_b32_e64 v2, v4, v1, s[42:43]
	v_mov_b32_e32 v4, 1
	v_bfe_u32 v25, v3, 3, 3
	v_lshlrev_b32_e32 v1, 4, v3
	v_lshlrev_b32_sdwa v10, v4, sext(v2) dst_sel:DWORD dst_unused:UNUSED_PAD src0_sel:DWORD src1_sel:WORD_0
	v_lshl_add_u64 v[4:5], s[78:79], 0, v[184:185]
	v_and_b32_e32 v184, 0x70, v1
	v_or_b32_e32 v1, v25, v26
	v_lshl_add_u64 v[8:9], v[4:5], 0, v[184:185]
	v_mul_u32_u24_e32 v4, 0xb000, v1
	v_mov_b32_e32 v5, v185
	v_lshl_add_u64 v[4:5], v[8:9], 0, v[4:5]
	global_load_dwordx4 v[132:135], v[4:5], off nt
	v_readlane_b32 s79, v255, 17
	v_mul_u32_u24_e32 v12, 0x84, v25
	v_or_b32_e32 v24, 8, v25
	v_add3_u32 v12, s79, v184, v12
	v_add_u32_e32 v13, 0x420, v12
	v_or_b32_e32 v23, 16, v25
	v_or_b32_e32 v22, 24, v25
	s_movk_i32 s16, 0x60
	v_cndmask_b32_e32 v11, 0, v228, vcc
	v_and_b32_sdwa v2, sext(v2), s16 dst_sel:DWORD dst_unused:UNUSED_PAD src0_sel:WORD_0 src1_sel:DWORD
	s_waitcnt lgkmcnt(0)
	s_cmp_eq_u64 s[12:13], 0
	v_or_b32_e32 v4, v24, v26
	v_mul_u32_u24_e32 v184, 0xb000, v4
	v_lshl_add_u64 v[4:5], v[8:9], 0, v[184:185]
	global_load_dwordx4 v[136:139], v[4:5], off nt
	v_add_u32_e32 v4, 0x428, v12
	v_or_b32_e32 v4, v23, v26
	v_mul_u32_u24_e32 v184, 0xb000, v4
	v_lshl_add_u64 v[4:5], v[8:9], 0, v[184:185]
	global_load_dwordx4 v[140:143], v[4:5], off nt
	v_add_u32_e32 v13, 0x840, v12
	v_add_u32_e32 v4, 0x848, v12
	v_or_b32_e32 v4, v22, v26
	v_mul_u32_u24_e32 v184, 0xb000, v4
	v_lshl_add_u64 v[4:5], v[8:9], 0, v[184:185]
	global_load_dwordx4 v[144:147], v[4:5], off nt
	v_add_u32_e32 v13, 0xc60, v12
	v_add_u32_e32 v4, 0xc68, v12
	v_or_b32_e32 v4, 32, v1
	v_mul_u32_u24_e32 v184, 0xb000, v4
	v_lshl_add_u64 v[4:5], v[8:9], 0, v[184:185]
	global_load_dwordx4 v[148:151], v[4:5], off nt
	v_add_u32_e32 v13, 0x1080, v12
	v_add_u32_e32 v4, 0x1088, v12
	v_or_b32_e32 v4, 40, v1
	v_mul_u32_u24_e32 v184, 0xb000, v4
	v_lshl_add_u64 v[4:5], v[8:9], 0, v[184:185]
	global_load_dwordx4 v[152:155], v[4:5], off nt
	v_add_u32_e32 v13, 0x14a0, v12
	v_add_u32_e32 v4, 0x14a8, v12
	v_or_b32_e32 v4, 48, v1
	v_mul_u32_u24_e32 v184, 0xb000, v4
	v_lshl_add_u64 v[4:5], v[8:9], 0, v[184:185]
	global_load_dwordx4 v[156:159], v[4:5], off nt
	v_add_u32_e32 v13, 0x18c0, v12
	v_or_b32_e32 v1, 56, v1
	v_mul_u32_u24_e32 v184, 0xb000, v1
	v_add_u32_e32 v1, 0x1ce0, v12
	v_add_u32_e32 v4, 0x18c8, v12
	v_lshl_add_u64 v[4:5], v[8:9], 0, v[184:185]
	global_load_dwordx4 v[160:163], v[4:5], off nt
	v_add_u32_e32 v1, 0x1ce8, v12
	s_waitcnt vmcnt(0)
	v_add_u32_e32 v164, 0x0, v12
	ds_write2_b32 v164, v132, v133 offset1:1
	ds_write2_b32 v164, v134, v135 offset0:2 offset1:3
	v_add_u32_e32 v164, 0x420, v12
	ds_write2_b32 v164, v136, v137 offset1:1
	ds_write2_b32 v164, v138, v139 offset0:2 offset1:3
	v_add_u32_e32 v164, 0x840, v12
	ds_write2_b32 v164, v140, v141 offset1:1
	ds_write2_b32 v164, v142, v143 offset0:2 offset1:3
	v_add_u32_e32 v164, 0xc60, v12
	ds_write2_b32 v164, v144, v145 offset1:1
	ds_write2_b32 v164, v146, v147 offset0:2 offset1:3
	v_add_u32_e32 v164, 0x1080, v12
	ds_write2_b32 v164, v148, v149 offset1:1
	ds_write2_b32 v164, v150, v151 offset0:2 offset1:3
	v_add_u32_e32 v164, 0x14a0, v12
	ds_write2_b32 v164, v152, v153 offset1:1
	ds_write2_b32 v164, v154, v155 offset0:2 offset1:3
	v_add_u32_e32 v164, 0x18c0, v12
	ds_write2_b32 v164, v156, v157 offset1:1
	ds_write2_b32 v164, v158, v159 offset0:2 offset1:3
	v_add_u32_e32 v164, 0x1ce0, v12
	ds_write2_b32 v164, v160, v161 offset1:1
	ds_write2_b32 v164, v162, v163 offset0:2 offset1:3
	s_waitcnt lgkmcnt(0)
	v_and_b32_e32 v1, 0xffffff00, v10
	v_or3_b32 v4, v2, v11, v1
	s_cbranch_scc1 .LBB0_1447
	v_and_b32_e32 v1, 32, v3
	v_readlane_b32 s42, v255, 25
	v_readlane_b32 s43, v255, 26
	s_add_u32 s12, s12, s42
	v_add_u32_e32 v28, v26, v1
	s_mov_b32 s16, 0xba2e8c
	v_lshrrev_b32_e32 v1, 5, v3
	v_bfe_u32 v2, v3, 5, 1
	s_addc_u32 s13, s13, s43
	v_lshlrev_b32_e32 v184, 2, v28
	v_mul_hi_u32_u24_sdwa v0, v0, s16 dst_sel:DWORD dst_unused:UNUSED_PAD src0_sel:WORD_0 src1_sel:DWORD
	v_lshlrev_b32_e32 v8, 7, v2
	v_and_b32_e32 v1, 1, v1
	v_lshl_add_u64 v[6:7], s[12:13], 0, v[184:185]
	v_lshl_or_b32 v184, v0, 8, v8
	v_lshlrev_b16_e32 v0, 6, v0
	v_lshlrev_b16_e32 v1, 5, v1
	v_or_b32_e32 v0, v0, v1
	v_and_b32_e32 v0, 0x7e0, v0
	v_and_b32_e32 v27, 31, v3
	v_lshl_add_u64 v[8:9], s[12:13], 0, v[184:185]
	v_lshlrev_b32_e32 v184, 2, v0
	v_mul_u32_u24_e32 v0, 0x1080, v2
	s_add_u32 s12, s92, s42
	v_lshl_or_b32 v0, v27, 2, v0
	s_addc_u32 s13, s93, s43
	v_add_u32_e32 v29, s79, v0
	v_mov_b32_e32 v0, 0
	v_and_b32_e32 v5, 63, v3
	v_lshl_add_u64 v[10:11], s[12:13], 0, v[184:185]
	s_mov_b64 s[12:13], 0
	v_mov_b32_e32 v1, v0

; #define LAS __attribute__((address_space(3)))
; __device__ __forceinline__ void atomic_addq(i64* p, float v, float scale) { (void)__hip_atomic_fetch_add((unsigned long long*)p, (unsigned long long)(i64)__builtin_rintf(v * scale), __ATOMIC_RELAXED, __HIP_MEMORY_SCOPE_AGENT); }
; #define F_LANE() (tid_of(F.wave) & 63)
; #define INP(i) (kargs()->in[i])
; template <class Map>
; __device__ __forceinline__ void conv_item(const Frame& F, int it, const float* W, int K, int N, bf16_t* WT, const float* gk, int gmask, float gmul, const float* bk, i64* cs, i64* bw, Map map) {
;     LAS float* scr = (LAS float*)(F.lds + F.wave * 16384);
;     const int lane = F_LANE(), nblk = N / 32;
;     {
;         const int kb = it / nblk, nb = it % nblk, k0 = 64 * kb, n0 = 32 * nb, v0 = map(n0);
; #pragma unroll
;         for (int i = 0; i < 8; ++i) { const int kk = 8 * i + (lane >> 3), c4 = (lane & 7) * 4;
;             const f32x4 w4 = __builtin_nontemporal_load((const f32x4*)(W + (size_t)(k0 + kk) * N + n0 + c4)); LAS float* d = scr + kk * 33 + c4; d[0] = w4[0]; d[1] = w4[1]; d[2] = w4[2]; d[3] = w4[3]; }
;         LDS_WAIT(); asm volatile("" ::: "memory");
;         if (bk) {
;             const int n = lane & 31, kh = lane >> 5; float sb = 0.f, sc = 0.f;
; #pragma unroll 8
;             for (int j = 0; j < 32; ++j) { const int kk = kh * 32 + j; const float w = scr[kk * 33 + n]; sb += bk[k0 + kk] * w; sc += bf_round(gk[(k0 + kk) & gmask] * gmul * w); }
;             { auto r = __builtin_amdgcn_permlane32_swap(__float_as_uint(sb), __float_as_uint(sb), false, false); sb = __uint_as_float(r[0]) + __uint_as_float(r[1]); }
;             { auto r = __builtin_amdgcn_permlane32_swap(__float_as_uint(sc), __float_as_uint(sc), false, false); sc = __uint_as_float(r[0]) + __uint_as_float(r[1]); }
;             if (lane < 32) { atomic_addq(bw + v0 + n, sb, FX_COL); atomic_addq(cs + v0 + n, sc, FX_COL); }
;         }
;         const int c = lane & 7; float gl[8];
; #pragma unroll
;         for (int i = 0; i < 8; ++i) gl[i] = gk ? gk[(k0 + 8 * c + i) & gmask] * gmul : 1.0f;
; __device__ BG_ATTR void bg_item(const Frame& F, unsigned char* ws, const int L, int id) {
;     ...
;         if (id < NI_UKV) { conv_item(F, id, INP(6) + (size_t)j * MLA_RANK * 4096, MLA_RANK, 4096, Wukv, INP(4) + j * MLA_RANK, MLA_RANK - 1, 1.f, nullptr, nullptr, nullptr, MapIdent()); return; } id -= NI_UKV;
.LBB0_1466:
	v_readlane_b32 s26, v252, 14
	v_readlane_b32 s27, v252, 15
	s_mov_b64 s[16:17], s[26:27]
	s_load_dwordx2 s[16:17], s[16:17], 0x30
	v_add_u32_e32 v0, 0xfffff8c0, v21
	v_readlane_b32 s24, v252, 12
	v_lshrrev_b32_e32 v1, 1, v0
	v_lshlrev_b32_e32 v0, 5, v0
	s_waitcnt lgkmcnt(0)
	s_add_u32 s16, s16, s90
	v_readlane_b32 s25, v252, 13
	v_mov_b32_e32 v22, v220
	v_and_b32_e32 v8, 0xfe0, v0
	s_addc_u32 s17, s17, s91
	s_load_dwordx2 s[40:41], s[26:27], 0x20
	v_lshlrev_b32_e32 v184, 2, v8
	v_lshlrev_b32_e32 v2, 4, v22
	v_and_b32_e32 v13, 0x7fc0, v1
	v_bfe_u32 v12, v22, 3, 3
	v_lshl_add_u64 v[0:1], s[16:17], 0, v[184:185]
	v_and_b32_e32 v184, 0x70, v2
	v_lshl_add_u64 v[4:5], v[0:1], 0, v[184:185]
	v_or_b32_e32 v0, v12, v13
	v_lshlrev_b32_e32 v6, 14, v0
	v_mov_b32_e32 v7, v185
	v_lshl_add_u64 v[0:1], v[4:5], 0, v[6:7]
	global_load_dwordx4 v[132:135], v[0:1], off nt
	v_mul_u32_u24_e32 v7, 0x84, v12
	v_add3_u32 v7, s79, v184, v7
	v_or_b32_e32 v11, 8, v12
	v_add_u32_e32 v9, 0x420, v7
	v_or_b32_e32 v10, 16, v12
	v_add_u32_e32 v23, 0xc60, v7
	s_lshl_b64 s[26:27], s[74:75], 2
	s_waitcnt lgkmcnt(0)
	s_add_u32 s26, s40, s26
	v_and_b32_e32 v22, 7, v22
	s_addc_u32 s27, s41, s27
	s_cmp_lg_u64 s[40:41], 0
	s_cselect_b64 s[48:49], -1, 0
	s_cmp_eq_u64 s[40:41], 0
	v_or_b32_e32 v0, v11, v13
	v_lshlrev_b32_e32 v184, 14, v0
	v_lshl_add_u64 v[0:1], v[4:5], 0, v[184:185]
	global_load_dwordx4 v[136:139], v[0:1], off nt
	v_add_u32_e32 v0, 0x428, v7
	v_or_b32_e32 v0, v10, v13
	v_lshlrev_b32_e32 v184, 14, v0
	v_lshl_add_u64 v[0:1], v[4:5], 0, v[184:185]
	global_load_dwordx4 v[140:143], v[0:1], off nt
	v_add_u32_e32 v9, 0x840, v7
	v_add_u32_e32 v0, 0x848, v7
	v_or_b32_e32 v9, 24, v12
	v_or_b32_e32 v0, v9, v13
	v_lshlrev_b32_e32 v184, 14, v0
	v_lshl_add_u64 v[0:1], v[4:5], 0, v[184:185]
	global_load_dwordx4 v[144:147], v[0:1], off nt
	v_or_b32_e32 v184, 0x80000, v6
	v_add_u32_e32 v0, 0xc68, v7
	v_lshl_add_u64 v[0:1], v[4:5], 0, v[184:185]
	global_load_dwordx4 v[148:151], v[0:1], off nt
	v_add_u32_e32 v23, 0x1080, v7
	v_or_b32_e32 v184, 0xa0000, v6
	v_add_u32_e32 v0, 0x1088, v7
	v_lshl_add_u64 v[0:1], v[4:5], 0, v[184:185]
	global_load_dwordx4 v[152:155], v[0:1], off nt
	v_add_u32_e32 v23, 0x14a0, v7
	v_or_b32_e32 v184, 0xc0000, v6
	v_add_u32_e32 v0, 0x14a8, v7
	v_lshl_add_u64 v[0:1], v[4:5], 0, v[184:185]
	global_load_dwordx4 v[156:159], v[0:1], off nt
	v_add_u32_e32 v23, 0x18c0, v7
	v_or_b32_e32 v184, 0xe0000, v6
	v_add_u32_e32 v0, 0x18c8, v7
	v_lshl_add_u64 v[0:1], v[4:5], 0, v[184:185]
	global_load_dwordx4 v[160:163], v[0:1], off nt
	v_add_u32_e32 v4, 0x1ce0, v7
	v_lshlrev_b32_e32 v23, 3, v22
	v_add_u32_e32 v0, 0x1ce8, v7
	s_waitcnt vmcnt(0)
	v_add_u32_e32 v164, 0x0, v7
	ds_write2_b32 v164, v132, v133 offset1:1
	ds_write2_b32 v164, v134, v135 offset0:2 offset1:3
	v_add_u32_e32 v164, 0x420, v7
	ds_write2_b32 v164, v136, v137 offset1:1
	ds_write2_b32 v164, v138, v139 offset0:2 offset1:3
	v_add_u32_e32 v164, 0x840, v7
	ds_write2_b32 v164, v140, v141 offset1:1
	ds_write2_b32 v164, v142, v143 offset0:2 offset1:3
	v_add_u32_e32 v164, 0xc60, v7
	ds_write2_b32 v164, v144, v145 offset1:1
	ds_write2_b32 v164, v146, v147 offset0:2 offset1:3
	v_add_u32_e32 v164, 0x1080, v7
	ds_write2_b32 v164, v148, v149 offset1:1
	ds_write2_b32 v164, v150, v151 offset0:2 offset1:3
	v_add_u32_e32 v164, 0x14a0, v7
	ds_write2_b32 v164, v152, v153 offset1:1
	ds_write2_b32 v164, v154, v155 offset0:2 offset1:3
	v_add_u32_e32 v164, 0x18c0, v7
	ds_write2_b32 v164, v156, v157 offset1:1
	ds_write2_b32 v164, v158, v159 offset0:2 offset1:3
	v_add_u32_e32 v164, 0x1ce0, v7
	ds_write2_b32 v164, v160, v161 offset1:1
	ds_write2_b32 v164, v162, v163 offset0:2 offset1:3
	s_waitcnt lgkmcnt(0)
	v_or_b32_e32 v1, v23, v13
	v_mov_b32_e32 v0, 1.0
	v_lshlrev_b32_e32 v24, 2, v1
	v_mov_b32_e32 v2, 1.0
	s_cbranch_scc1 .LBB0_1468
	global_load_dword v2, v24, s[26:27]

; #define LAS __attribute__((address_space(3)))
; __device__ __forceinline__ void atomic_addq(i64* p, float v, float scale) { (void)__hip_atomic_fetch_add((unsigned long long*)p, (unsigned long long)(i64)__builtin_rintf(v * scale), __ATOMIC_RELAXED, __HIP_MEMORY_SCOPE_AGENT); }
; #define F_LANE() (tid_of(F.wave) & 63)
; #define INP(i) (kargs()->in[i])
; template <class Map>
; __device__ __forceinline__ void conv_item(const Frame& F, int it, const float* W, int K, int N, bf16_t* WT, const float* gk, int gmask, float gmul, const float* bk, i64* cs, i64* bw, Map map) {
;     LAS float* scr = (LAS float*)(F.lds + F.wave * 16384);
;     const int lane = F_LANE(), nblk = N / 32;
;     {
;         const int kb = it / nblk, nb = it % nblk, k0 = 64 * kb, n0 = 32 * nb, v0 = map(n0);
; #pragma unroll
;         for (int i = 0; i < 8; ++i) { const int kk = 8 * i + (lane >> 3), c4 = (lane & 7) * 4;
;             const f32x4 w4 = __builtin_nontemporal_load((const f32x4*)(W + (size_t)(k0 + kk) * N + n0 + c4)); LAS float* d = scr + kk * 33 + c4; d[0] = w4[0]; d[1] = w4[1]; d[2] = w4[2]; d[3] = w4[3]; }
;         LDS_WAIT(); asm volatile("" ::: "memory");
;         if (bk) {
;             const int n = lane & 31, kh = lane >> 5; float sb = 0.f, sc = 0.f;
; #pragma unroll 8
;             for (int j = 0; j < 32; ++j) { const int kk = kh * 32 + j; const float w = scr[kk * 33 + n]; sb += bk[k0 + kk] * w; sc += bf_round(gk[(k0 + kk) & gmask] * gmul * w); }
;             { auto r = __builtin_amdgcn_permlane32_swap(__float_as_uint(sb), __float_as_uint(sb), false, false); sb = __uint_as_float(r[0]) + __uint_as_float(r[1]); }
;             { auto r = __builtin_amdgcn_permlane32_swap(__float_as_uint(sc), __float_as_uint(sc), false, false); sc = __uint_as_float(r[0]) + __uint_as_float(r[1]); }
;             if (lane < 32) { atomic_addq(bw + v0 + n, sb, FX_COL); atomic_addq(cs + v0 + n, sc, FX_COL); }
;         }
;         const int c = lane & 7; float gl[8];
; #pragma unroll
;         for (int i = 0; i < 8; ++i) gl[i] = gk ? gk[(k0 + 8 * c + i) & gmask] * gmul : 1.0f;
; __device__ BG_ATTR void bg_item(const Frame& F, unsigned char* ws, const int L, int id) {
;     ...
;         if (id < NI_UQ) { conv_item(F, id, INP(5) + (size_t)j * MLA_RANK * 3072, MLA_RANK, 3072, Wuq, INP(3) + j * MLA_RANK, MLA_RANK - 1, 1.f, nullptr, nullptr, nullptr, MapMlaUq()); return; } id -= NI_UQ;
.LBB0_1483:
	s_or_b64 exec, exec, s[12:13]
	s_and_saveexec_b64 s[12:13], s[18:19]
	s_xor_b64 s[12:13], exec, s[12:13]
	s_cbranch_execz .LBB0_1505
	v_add_u16_e32 v2, 0xfbc0, v21
	v_mul_u32_u24_e32 v1, 0xaaab, v2
	v_lshrrev_b32_e32 v1, 22, v1
	v_mul_lo_u16_e32 v3, 0x60, v1
	v_sub_u16_e32 v3, v2, v3
	v_lshlrev_b16_e32 v2, 5, v3
	v_mul_u32_u24_e32 v4, 0x2aab, v2
	v_lshrrev_b32_e32 v4, 21, v4
	v_readlane_b32 s24, v252, 14
	v_mul_lo_u16_e32 v4, 0xc0, v4
	v_readlane_b32 s25, v252, 15
	v_readlane_b32 s18, v252, 12
	v_mul_lo_u16_e32 v3, 0xab, v3
	v_sub_u16_e32 v4, v2, v4
	s_movk_i32 s26, 0x7f
	s_mov_b64 s[16:17], s[24:25]
	v_readlane_b32 s19, v252, 13
	v_mov_b32_e32 v0, v220
	v_lshrrev_b16_e32 v3, 10, v3
	v_cmp_lt_u16_e32 vcc, s26, v4
	s_and_saveexec_b64 s[26:27], vcc
	s_xor_b64 s[26:27], exec, s[26:27]
	v_lshlrev_b32_e32 v5, 6, v3
	v_and_b32_e32 v5, 0x700, v5
	v_lshlrev_b32_e32 v3, 5, v3
	v_lshl_add_u32 v4, v4, 2, v5
	v_and_b32_e32 v3, 0x60, v3
	s_movk_i32 s40, 0x600
	v_add3_u32 v8, v4, v3, s40
	s_or_saveexec_b64 s[40:41], s[26:27]
	s_load_dwordx2 s[16:17], s[16:17], 0x28
	s_nop 0
	s_load_dwordx2 s[26:27], s[24:25], 0x18
	s_xor_b64 exec, exec, s[40:41]
	v_lshl_or_b32 v8, v3, 7, v4
	s_or_b64 exec, exec, s[40:41]
	v_readlane_b32 s21, v255, 35
	s_waitcnt lgkmcnt(0)
	s_add_u32 s16, s16, s21
	v_readlane_b32 s21, v255, 20
	s_addc_u32 s17, s17, s21
	v_lshlrev_b16_e32 v13, 6, v1
	v_bfe_u32 v12, v0, 3, 3
	v_lshlrev_b32_e32 v184, 2, v2
	v_lshlrev_b32_e32 v1, 4, v0
	v_lshl_add_u64 v[2:3], s[16:17], 0, v[184:185]
	v_and_b32_e32 v184, 0x70, v1
	v_or_b32_e32 v1, v12, v13
	v_lshl_add_u64 v[6:7], v[2:3], 0, v[184:185]
	v_mul_u32_u24_e32 v2, 0x3000, v1
	v_mov_b32_e32 v3, v185
	v_lshl_add_u64 v[2:3], v[6:7], 0, v[2:3]
	global_load_dwordx4 v[132:135], v[2:3], off nt
	v_mul_u32_u24_e32 v9, 0x84, v12
	v_add3_u32 v22, s79, v184, v9
	v_or_b32_e32 v11, 8, v12
	v_add_u32_e32 v9, 0x420, v22
	v_or_b32_e32 v10, 16, v12
	v_add_u32_e32 v23, 0xc60, v22
	s_lshl_b64 s[24:25], s[74:75], 2
	s_add_u32 s24, s26, s24
	s_addc_u32 s25, s27, s25
	s_movk_i32 s16, 0x1c0
	s_cmp_lg_u64 s[26:27], 0
	s_cselect_b64 s[40:41], -1, 0
	s_cmp_eq_u64 s[26:27], 0
	v_or_b32_e32 v2, v11, v13
	v_mul_u32_u24_e32 v184, 0x3000, v2
	v_lshl_add_u64 v[2:3], v[6:7], 0, v[184:185]
	global_load_dwordx4 v[136:139], v[2:3], off nt
	v_add_u32_e32 v2, 0x428, v22
	v_or_b32_e32 v2, v10, v13
	v_mul_u32_u24_e32 v184, 0x3000, v2
	v_lshl_add_u64 v[2:3], v[6:7], 0, v[184:185]
	global_load_dwordx4 v[140:143], v[2:3], off nt
	v_add_u32_e32 v9, 0x840, v22
	v_add_u32_e32 v2, 0x848, v22
	v_or_b32_e32 v9, 24, v12
	v_or_b32_e32 v2, v9, v13
	v_mul_u32_u24_e32 v184, 0x3000, v2
	v_lshl_add_u64 v[2:3], v[6:7], 0, v[184:185]
	global_load_dwordx4 v[144:147], v[2:3], off nt
	v_add_u32_e32 v2, 0xc68, v22
	v_or_b32_e32 v2, 32, v1
	v_mul_u32_u24_e32 v184, 0x3000, v2
	v_lshl_add_u64 v[2:3], v[6:7], 0, v[184:185]
	global_load_dwordx4 v[148:151], v[2:3], off nt
	v_add_u32_e32 v23, 0x1080, v22
	v_add_u32_e32 v2, 0x1088, v22
	v_or_b32_e32 v2, 40, v1
	v_mul_u32_u24_e32 v184, 0x3000, v2
	v_lshl_add_u64 v[2:3], v[6:7], 0, v[184:185]
	global_load_dwordx4 v[152:155], v[2:3], off nt
	v_add_u32_e32 v23, 0x14a0, v22
	v_add_u32_e32 v2, 0x14a8, v22
	v_or_b32_e32 v2, 48, v1
	v_mul_u32_u24_e32 v184, 0x3000, v2
	v_lshl_add_u64 v[2:3], v[6:7], 0, v[184:185]
	global_load_dwordx4 v[156:159], v[2:3], off nt
	v_add_u32_e32 v23, 0x18c0, v22
	v_or_b32_e32 v1, 56, v1
	v_mul_u32_u24_e32 v184, 0x3000, v1
	v_add_u32_e32 v1, 0x1ce0, v22
	v_add_u32_e32 v2, 0x18c8, v22
	v_lshl_add_u64 v[2:3], v[6:7], 0, v[184:185]
	global_load_dwordx4 v[160:163], v[2:3], off nt
	v_add_u32_e32 v1, 0x1ce8, v22
	s_waitcnt vmcnt(0)
	v_add_u32_e32 v164, 0x0, v22
	ds_write2_b32 v164, v132, v133 offset1:1
	ds_write2_b32 v164, v134, v135 offset0:2 offset1:3
	v_add_u32_e32 v164, 0x420, v22
	ds_write2_b32 v164, v136, v137 offset1:1
	ds_write2_b32 v164, v138, v139 offset0:2 offset1:3
	v_add_u32_e32 v164, 0x840, v22
	ds_write2_b32 v164, v140, v141 offset1:1
	ds_write2_b32 v164, v142, v143 offset0:2 offset1:3
	v_add_u32_e32 v164, 0xc60, v22
	ds_write2_b32 v164, v144, v145 offset1:1
	ds_write2_b32 v164, v146, v147 offset0:2 offset1:3
	v_add_u32_e32 v164, 0x1080, v22
	ds_write2_b32 v164, v148, v149 offset1:1
	ds_write2_b32 v164, v150, v151 offset0:2 offset1:3
	v_add_u32_e32 v164, 0x14a0, v22
	ds_write2_b32 v164, v152, v153 offset1:1
	ds_write2_b32 v164, v154, v155 offset0:2 offset1:3
	v_add_u32_e32 v164, 0x18c0, v22
	ds_write2_b32 v164, v156, v157 offset1:1
	ds_write2_b32 v164, v158, v159 offset0:2 offset1:3
	v_add_u32_e32 v164, 0x1ce0, v22
	ds_write2_b32 v164, v160, v161 offset1:1
	ds_write2_b32 v164, v162, v163 offset0:2 offset1:3
	s_waitcnt lgkmcnt(0)
	v_and_b32_e32 v22, 7, v0
	v_lshlrev_b32_e32 v23, 3, v22
	v_and_or_b32 v1, v13, s16, v23
	v_mov_b32_e32 v0, 1.0
	v_lshlrev_b32_e32 v24, 2, v1
	v_mov_b32_e32 v2, 1.0
	s_cbranch_scc1 .LBB0_1490
	global_load_dword v2, v24, s[24:25]

; #define LAS __attribute__((address_space(3)))
; #define F_LANE() (tid_of(F.wave) & 63)
; #define LDS_WAIT() asm volatile("s_waitcnt lgkmcnt(0)" ::: "memory")
; template <class Map>
; __device__ __forceinline__ void conv_item(const Frame& F, int it, const float* W, int K, int N, bf16_t* WT, const float* gk, int gmask, float gmul, const float* bk, i64* cs, i64* bw, Map map) {
;     LAS float* scr = (LAS float*)(F.lds + F.wave * 16384);
;     const int lane = F_LANE(), nblk = N / 32;
;     {
;         const int kb = it / nblk, nb = it % nblk, k0 = 64 * kb, n0 = 32 * nb, v0 = map(n0);
; #pragma unroll
;         for (int i = 0; i < 8; ++i) { const int kk = 8 * i + (lane >> 3), c4 = (lane & 7) * 4;
;             const f32x4 w4 = __builtin_nontemporal_load((const f32x4*)(W + (size_t)(k0 + kk) * N + n0 + c4)); LAS float* d = scr + kk * 33 + c4; d[0] = w4[0]; d[1] = w4[1]; d[2] = w4[2]; d[3] = w4[3]; }
;         LDS_WAIT(); asm volatile("" ::: "memory");
;         if (bk) {
;             const int n = lane & 31, kh = lane >> 5; float sb = 0.f, sc = 0.f;
; #pragma unroll 8
;             for (int j = 0; j < 32; ++j) { const int kk = kh * 32 + j; const float w = scr[kk * 33 + n]; sb += bk[k0 + kk] * w; sc += bf_round(gk[(k0 + kk) & gmask] * gmul * w); }
;             { auto r = __builtin_amdgcn_permlane32_swap(__float_as_uint(sb), __float_as_uint(sb), false, false); sb = __uint_as_float(r[0]) + __uint_as_float(r[1]); }
;             { auto r = __builtin_amdgcn_permlane32_swap(__float_as_uint(sc), __float_as_uint(sc), false, false); sc = __uint_as_float(r[0]) + __uint_as_float(r[1]); }
;             if (lane < 32) { atomic_addq(bw + v0 + n, sb, FX_COL); atomic_addq(cs + v0 + n, sc, FX_COL); }
;         }
;         const int c = lane & 7; float gl[8];
; #pragma unroll
;         for (int i = 0; i < 8; ++i) gl[i] = gk ? gk[(k0 + 8 * c + i) & gmask] * gmul : 1.0f;
; #pragma unroll
;         for (int j = 0; j < 4; ++j) { const int n = (lane >> 3) + 8 * j; const LAS float* s = scr + (8 * c) * 33 + n;
;             u32x4 o; o.x = pk2(s[0 * 33] * gl[0], s[1 * 33] * gl[1]); o.y = pk2(s[2 * 33] * gl[2], s[3 * 33] * gl[3]); o.z = pk2(s[4 * 33] * gl[4], s[5 * 33] * gl[5]); o.w = pk2(s[6 * 33] * gl[6], s[7 * 33] * gl[7]);
;             __builtin_nontemporal_store(o, (u32x4*)(WT + (size_t)(v0 + n) * K + k0 + 8 * c)); }
.LBB0_1505:
	s_or_b64 exec, exec, s[12:13]
	s_and_saveexec_b64 s[18:19], s[6:7]
	s_cbranch_execz .LBB0_1507
	v_readlane_b32 s6, v252, 14
	v_readlane_b32 s7, v252, 15
	s_load_dwordx2 s[6:7], s[6:7], 0x10
	s_mov_b32 s16, 0xf0f1
	v_mul_u32_u24_sdwa v0, v21, s16 dst_sel:DWORD dst_unused:UNUSED_PAD src0_sel:WORD_0 src1_sel:DWORD
	v_lshrrev_b32_e32 v0, 21, v0
	v_mul_lo_u16_e32 v1, 34, v0
	s_waitcnt lgkmcnt(0)
	s_add_u32 s12, s6, s61
	v_readlane_b32 s6, v255, 41
	s_addc_u32 s13, s7, s6
	v_readlane_b32 s6, v252, 12
	v_sub_u16_e32 v21, v21, v1
	v_readlane_b32 s7, v252, 13
	v_mov_b32_e32 v6, v220
	v_lshlrev_b16_e32 v23, 5, v21
	v_lshlrev_b16_e32 v22, 6, v0
	v_bfe_u32 v7, v6, 3, 3
	v_lshlrev_b32_e32 v184, 2, v23
	v_lshlrev_b32_e32 v2, 4, v6
	v_lshl_add_u64 v[0:1], s[12:13], 0, v[184:185]
	v_and_b32_e32 v184, 0x70, v2
	v_or_b32_e32 v25, v7, v22
	v_lshl_add_u64 v[12:13], v[0:1], 0, v[184:185]
	v_mul_u32_u24_e32 v0, 0x1100, v25
	v_mov_b32_e32 v1, v185
	v_lshl_add_u64 v[0:1], v[12:13], 0, v[0:1]
	global_load_dwordx4 v[132:135], v[0:1], off nt
	v_mul_u32_u24_e32 v4, 0x84, v7
	v_add3_u32 v26, s79, v184, v4
	v_or_b32_e32 v5, 8, v7
	v_add_u32_e32 v4, 0x420, v26
	v_add_u32_e32 v8, 0x840, v26
	v_add_u32_e32 v24, 0x60, v23
	v_cmp_gt_u16_e32 vcc, 33, v21
	v_or_b32_e32 v0, v5, v22
	v_mul_u32_u24_e32 v184, 0x1100, v0
	v_lshl_add_u64 v[0:1], v[12:13], 0, v[184:185]
	global_load_dwordx4 v[136:139], v[0:1], off nt
	v_add_u32_e32 v0, 0x428, v26
	v_or_b32_e32 v4, 16, v7
	v_or_b32_e32 v0, v4, v22
	v_mul_u32_u24_e32 v184, 0x1100, v0
	v_lshl_add_u64 v[0:1], v[12:13], 0, v[184:185]
	global_load_dwordx4 v[140:143], v[0:1], off nt
	v_add_u32_e32 v0, 0x848, v26
	v_or_b32_e32 v2, 24, v7
	v_or_b32_e32 v0, v2, v22
	v_mul_u32_u24_e32 v184, 0x1100, v0
	v_lshl_add_u64 v[0:1], v[12:13], 0, v[184:185]
	global_load_dwordx4 v[144:147], v[0:1], off nt
	v_add_u32_e32 v0, 0xc60, v26
	v_cndmask_b32_e32 v3, v24, v23, vcc
	v_or_b32_e32 v5, v5, v3
	v_or_b32_e32 v4, v4, v3
	v_or_b32_e32 v2, v2, v3
	v_add_u32_e32 v0, 0xc68, v26
	v_or_b32_e32 v0, 32, v25
	v_mul_u32_u24_e32 v184, 0x1100, v0
	v_lshl_add_u64 v[0:1], v[12:13], 0, v[184:185]
	global_load_dwordx4 v[148:151], v[0:1], off nt
	v_add_u32_e32 v0, 0x1080, v26
	v_add_u32_e32 v0, 0x1088, v26
	v_or_b32_e32 v0, 40, v25
	v_mul_u32_u24_e32 v184, 0x1100, v0
	v_lshl_add_u64 v[0:1], v[12:13], 0, v[184:185]
	global_load_dwordx4 v[152:155], v[0:1], off nt
	v_add_u32_e32 v0, 0x14a0, v26
	v_add_u32_e32 v0, 0x14a8, v26
	v_or_b32_e32 v0, 48, v25
	v_mul_u32_u24_e32 v184, 0x1100, v0
	v_lshl_add_u64 v[0:1], v[12:13], 0, v[184:185]
	global_load_dwordx4 v[156:159], v[0:1], off nt
	v_add_u32_e32 v0, 0x18c0, v26
	v_add_u32_e32 v0, 0x18c8, v26
	v_or_b32_e32 v0, 56, v25
	v_mul_u32_u24_e32 v184, 0x1100, v0
	v_lshl_add_u64 v[0:1], v[12:13], 0, v[184:185]
	global_load_dwordx4 v[160:163], v[0:1], off nt
	v_add_u32_e32 v0, 0x1ce0, v26
	v_lshlrev_b32_e32 v184, 1, v22
	v_add_u32_e32 v0, 0x1ce8, v26
	s_waitcnt vmcnt(0)
	v_add_u32_e32 v164, 0x0, v26
	ds_write2_b32 v164, v132, v133 offset1:1
	ds_write2_b32 v164, v134, v135 offset0:2 offset1:3
	v_add_u32_e32 v164, 0x420, v26
	ds_write2_b32 v164, v136, v137 offset1:1
	ds_write2_b32 v164, v138, v139 offset0:2 offset1:3
	v_add_u32_e32 v164, 0x840, v26
	ds_write2_b32 v164, v140, v141 offset1:1
	ds_write2_b32 v164, v142, v143 offset0:2 offset1:3
	v_add_u32_e32 v164, 0xc60, v26
	ds_write2_b32 v164, v144, v145 offset1:1
	ds_write2_b32 v164, v146, v147 offset0:2 offset1:3
	v_add_u32_e32 v164, 0x1080, v26
	ds_write2_b32 v164, v148, v149 offset1:1
	ds_write2_b32 v164, v150, v151 offset0:2 offset1:3
	v_add_u32_e32 v164, 0x14a0, v26
	ds_write2_b32 v164, v152, v153 offset1:1
	ds_write2_b32 v164, v154, v155 offset0:2 offset1:3
	v_add_u32_e32 v164, 0x18c0, v26
	ds_write2_b32 v164, v156, v157 offset1:1
	ds_write2_b32 v164, v158, v159 offset0:2 offset1:3
	v_add_u32_e32 v164, 0x1ce0, v26
	ds_write2_b32 v164, v160, v161 offset1:1
	ds_write2_b32 v164, v162, v163 offset0:2 offset1:3
	v_lshlrev_b32_e32 v0, 3, v6
	v_and_b32_e32 v6, 56, v0
	s_waitcnt lgkmcnt(0)
	v_mul_u32_u24_e32 v8, 0x84, v6
	v_lshl_add_u64 v[0:1], s[6:7], 0, v[184:185]
	v_lshlrev_b32_e32 v184, 1, v6
	v_lshlrev_b32_e32 v6, 2, v7
	v_add3_u32 v6, s79, v8, v6
	ds_read_b32 v8, v6
	ds_read_b32 v9, v6 offset:132
	v_lshl_add_u64 v[0:1], v[0:1], 0, v[184:185]
	s_mov_b64 s[6:7], 0x800000
	v_or_b32_e32 v7, v7, v3
	s_waitcnt lgkmcnt(1)
	v_bfe_u32 v10, v8, 16, 1
	v_add3_u32 v8, v8, v10, s73
	s_waitcnt lgkmcnt(0)
; #define LAS __attribute__((address_space(3)))
; #define LDS_WAIT() asm volatile("s_waitcnt lgkmcnt(0)" ::: "memory")
; __device__ __forceinline__ unsigned pk2(float lo, float hi) { return f2bf(lo) | (f2bf(hi) << 16); }
; template <class Map>
; __device__ __forceinline__ void conv_item(const Frame& F, int it, const float* W, int K, int N, bf16_t* WT, const float* gk, int gmask, float gmul, const float* bk, i64* cs, i64* bw, Map map) {
;     ...
;         const int c = lane & 7; float gl[8];
; #pragma unroll
;         for (int i = 0; i < 8; ++i) gl[i] = gk ? gk[(k0 + 8 * c + i) & gmask] * gmul : 1.0f;
; #pragma unroll
;         for (int j = 0; j < 4; ++j) { const int n = (lane >> 3) + 8 * j; const LAS float* s = scr + (8 * c) * 33 + n;
;             u32x4 o; o.x = pk2(s[0 * 33] * gl[0], s[1 * 33] * gl[1]); o.y = pk2(s[2 * 33] * gl[2], s[3 * 33] * gl[3]); o.z = pk2(s[4 * 33] * gl[4], s[5 * 33] * gl[5]); o.w = pk2(s[6 * 33] * gl[6], s[7 * 33] * gl[7]);
;             __builtin_nontemporal_store(o, (u32x4*)(WT + (size_t)(v0 + n) * K + k0 + 8 * c)); }
;         LDS_WAIT(); asm volatile("" ::: "memory");
	v_bfe_u32 v10, v9, 16, 1
	v_lshrrev_b32_e32 v8, 16, v8
	v_add3_u32 v9, v9, v10, s73
	v_and_or_b32 v8, v9, s72, v8
	ds_read_b32 v9, v6 offset:264
	ds_read_b32 v10, v6 offset:396
	v_lshl_add_u64 v[0:1], v[0:1], 0, s[6:7]
	v_lshlrev_b32_e32 v184, 12, v7
	s_waitcnt lgkmcnt(1)
	v_bfe_u32 v11, v9, 16, 1
	v_add3_u32 v9, v9, v11, s73
	s_waitcnt lgkmcnt(0)
	v_bfe_u32 v11, v10, 16, 1
	v_lshrrev_b32_e32 v9, 16, v9
	v_add3_u32 v10, v10, v11, s73
	v_and_or_b32 v9, v10, s72, v9
	ds_read_b32 v10, v6 offset:528
	ds_read_b32 v11, v6 offset:660
	s_waitcnt lgkmcnt(1)
	v_bfe_u32 v12, v10, 16, 1
	v_add3_u32 v10, v10, v12, s73
	s_waitcnt lgkmcnt(0)
	v_bfe_u32 v12, v11, 16, 1
	v_lshrrev_b32_e32 v10, 16, v10
	v_add3_u32 v11, v11, v12, s73
	v_and_or_b32 v10, v11, s72, v10
	ds_read_b32 v11, v6 offset:792
	ds_read_b32 v12, v6 offset:924
	s_waitcnt lgkmcnt(1)
	v_bfe_u32 v13, v11, 16, 1
	v_add3_u32 v11, v11, v13, s73
	s_waitcnt lgkmcnt(0)
	v_bfe_u32 v13, v12, 16, 1
	v_lshrrev_b32_e32 v11, 16, v11
	v_add3_u32 v12, v12, v13, s73
	v_and_or_b32 v11, v12, s72, v11
	v_lshl_add_u64 v[12:13], v[0:1], 0, v[184:185]
	flat_store_dwordx4 v[12:13], v[8:11] nt
	ds_read_b32 v7, v6 offset:32
	ds_read_b32 v8, v6 offset:164
	v_lshlrev_b32_e32 v184, 12, v5
	s_waitcnt lgkmcnt(0)
	v_bfe_u32 v9, v7, 16, 1
	v_add3_u32 v7, v7, v9, s73
	v_bfe_u32 v9, v8, 16, 1
	v_lshrrev_b32_e32 v7, 16, v7
	v_add3_u32 v8, v8, v9, s73
	v_and_or_b32 v8, v8, s72, v7
	ds_read_b32 v7, v6 offset:296
	ds_read_b32 v9, v6 offset:428
	s_waitcnt lgkmcnt(0)
	v_bfe_u32 v10, v7, 16, 1
	v_add3_u32 v7, v7, v10, s73
	v_bfe_u32 v10, v9, 16, 1
	v_lshrrev_b32_e32 v7, 16, v7
	v_add3_u32 v9, v9, v10, s73
	v_and_or_b32 v9, v9, s72, v7
	ds_read_b32 v7, v6 offset:560
	ds_read_b32 v10, v6 offset:692
	s_waitcnt lgkmcnt(0)
	v_bfe_u32 v11, v7, 16, 1
	v_add3_u32 v7, v7, v11, s73
	v_bfe_u32 v11, v10, 16, 1
	v_lshrrev_b32_e32 v7, 16, v7
	v_add3_u32 v10, v10, v11, s73
	v_and_or_b32 v10, v10, s72, v7
	ds_read_b32 v7, v6 offset:824
	ds_read_b32 v11, v6 offset:956
	s_waitcnt lgkmcnt(0)
	v_bfe_u32 v12, v7, 16, 1
	v_add3_u32 v7, v7, v12, s73
	v_bfe_u32 v12, v11, 16, 1
	v_lshrrev_b32_e32 v7, 16, v7
	v_add3_u32 v11, v11, v12, s73
	v_and_or_b32 v11, v11, s72, v7
	v_lshl_add_u64 v[12:13], v[0:1], 0, v[184:185]
	flat_store_dwordx4 v[12:13], v[8:11] nt
	ds_read_b32 v5, v6 offset:64
	ds_read_b32 v7, v6 offset:196
	v_lshlrev_b32_e32 v184, 12, v4
	s_waitcnt lgkmcnt(0)
	v_bfe_u32 v8, v5, 16, 1
	v_add3_u32 v5, v5, v8, s73
	v_bfe_u32 v8, v7, 16, 1
	v_lshrrev_b32_e32 v5, 16, v5
	v_add3_u32 v7, v7, v8, s73
	v_and_or_b32 v8, v7, s72, v5
	ds_read_b32 v5, v6 offset:328
	ds_read_b32 v7, v6 offset:460
	s_waitcnt lgkmcnt(0)
	v_bfe_u32 v9, v5, 16, 1
	v_add3_u32 v5, v5, v9, s73
	v_bfe_u32 v9, v7, 16, 1
	v_lshrrev_b32_e32 v5, 16, v5
	v_add3_u32 v7, v7, v9, s73
	v_and_or_b32 v9, v7, s72, v5
	ds_read_b32 v5, v6 offset:592
	ds_read_b32 v7, v6 offset:724
	s_waitcnt lgkmcnt(0)
	v_bfe_u32 v10, v5, 16, 1
	v_add3_u32 v5, v5, v10, s73
	v_bfe_u32 v10, v7, 16, 1
	v_lshrrev_b32_e32 v5, 16, v5
	v_add3_u32 v7, v7, v10, s73
	v_and_or_b32 v10, v7, s72, v5
	ds_read_b32 v5, v6 offset:856
	ds_read_b32 v7, v6 offset:988
	s_waitcnt lgkmcnt(0)
	v_bfe_u32 v11, v5, 16, 1
	v_add3_u32 v5, v5, v11, s73
	v_bfe_u32 v11, v7, 16, 1
	v_lshrrev_b32_e32 v5, 16, v5
	v_add3_u32 v7, v7, v11, s73
	v_and_or_b32 v11, v7, s72, v5
	v_lshl_add_u64 v[4:5], v[0:1], 0, v[184:185]
	flat_store_dwordx4 v[4:5], v[8:11] nt
	ds_read_b32 v4, v6 offset:96
	ds_read_b32 v5, v6 offset:228
	v_lshlrev_b32_e32 v184, 12, v2
	v_lshl_add_u64 v[0:1], v[0:1], 0, v[184:185]
	s_waitcnt lgkmcnt(0)
	v_bfe_u32 v7, v4, 16, 1
	v_add3_u32 v4, v4, v7, s73
	v_bfe_u32 v7, v5, 16, 1
	v_lshrrev_b32_e32 v4, 16, v4
	v_add3_u32 v5, v5, v7, s73
	v_and_or_b32 v8, v5, s72, v4
	ds_read_b32 v4, v6 offset:360
	ds_read_b32 v5, v6 offset:492
	s_waitcnt lgkmcnt(0)
	v_bfe_u32 v7, v4, 16, 1
	v_add3_u32 v4, v4, v7, s73
	v_bfe_u32 v7, v5, 16, 1
	v_lshrrev_b32_e32 v4, 16, v4
	v_add3_u32 v5, v5, v7, s73
	v_and_or_b32 v9, v5, s72, v4
	ds_read_b32 v4, v6 offset:624
	ds_read_b32 v5, v6 offset:756
	s_waitcnt lgkmcnt(0)
	v_bfe_u32 v7, v4, 16, 1
	v_add3_u32 v4, v4, v7, s73
	v_bfe_u32 v7, v5, 16, 1
	v_lshrrev_b32_e32 v4, 16, v4
	v_add3_u32 v5, v5, v7, s73
	v_and_or_b32 v10, v5, s72, v4
	ds_read_b32 v4, v6 offset:888
	ds_read_b32 v5, v6 offset:1020
	s_waitcnt lgkmcnt(0)
	v_bfe_u32 v6, v4, 16, 1
	v_add3_u32 v4, v4, v6, s73
	v_bfe_u32 v6, v5, 16, 1
	v_lshrrev_b32_e32 v4, 16, v4
	v_add3_u32 v5, v5, v6, s73
	v_and_or_b32 v11, v5, s72, v4
	flat_store_dwordx4 v[0:1], v[8:11] nt
	s_waitcnt lgkmcnt(0)

; #define LAS __attribute__((address_space(3)))
; __device__ __forceinline__ void atomic_addq(i64* p, float v, float scale) { (void)__hip_atomic_fetch_add((unsigned long long*)p, (unsigned long long)(i64)__builtin_rintf(v * scale), __ATOMIC_RELAXED, __HIP_MEMORY_SCOPE_AGENT); }
; #define F_LANE() (tid_of(F.wave) & 63)
; #define INP(i) (kargs()->in[i])
; template <class Map>
; __device__ __forceinline__ void conv_item(const Frame& F, int it, const float* W, int K, int N, bf16_t* WT, const float* gk, int gmask, float gmul, const float* bk, i64* cs, i64* bw, Map map) {
;     LAS float* scr = (LAS float*)(F.lds + F.wave * 16384);
;     const int lane = F_LANE(), nblk = N / 32;
;     {
;         const int kb = it / nblk, nb = it % nblk, k0 = 64 * kb, n0 = 32 * nb, v0 = map(n0);
; #pragma unroll
;         for (int i = 0; i < 8; ++i) { const int kk = 8 * i + (lane >> 3), c4 = (lane & 7) * 4;
;             const f32x4 w4 = __builtin_nontemporal_load((const f32x4*)(W + (size_t)(k0 + kk) * N + n0 + c4)); LAS float* d = scr + kk * 33 + c4; d[0] = w4[0]; d[1] = w4[1]; d[2] = w4[2]; d[3] = w4[3]; }
;         LDS_WAIT(); asm volatile("" ::: "memory");
;         if (bk) {
;             const int n = lane & 31, kh = lane >> 5; float sb = 0.f, sc = 0.f;
; #pragma unroll 8
;             for (int j = 0; j < 32; ++j) { const int kk = kh * 32 + j; const float w = scr[kk * 33 + n]; sb += bk[k0 + kk] * w; sc += bf_round(gk[(k0 + kk) & gmask] * gmul * w); }
;             { auto r = __builtin_amdgcn_permlane32_swap(__float_as_uint(sb), __float_as_uint(sb), false, false); sb = __uint_as_float(r[0]) + __uint_as_float(r[1]); }
;             { auto r = __builtin_amdgcn_permlane32_swap(__float_as_uint(sc), __float_as_uint(sc), false, false); sc = __uint_as_float(r[0]) + __uint_as_float(r[1]); }
;             if (lane < 32) { atomic_addq(bw + v0 + n, sb, FX_COL); atomic_addq(cs + v0 + n, sc, FX_COL); }
;         }
;         const int c = lane & 7; float gl[8];
; #pragma unroll
;         for (int i = 0; i < 8; ++i) gl[i] = gk ? gk[(k0 + 8 * c + i) & gmask] * gmul : 1.0f;
; __device__ BG_ATTR void bg_item(const Frame& F, unsigned char* ws, const int L, int id) {
;     ...
;         if (id < NI_O) { conv_item(F, id, INP(11) + (size_t)j * DM * DM, DM, DM, Wo, INP(10) + j * 256, 255, (j ? 1.0f - LAM_INIT_1 : 1.0f - LAM_INIT_0), nullptr, nullptr, nullptr, MapIdent()); return; } id -= NI_O;
.LBB0_1613:
	s_or_b64 exec, exec, s[6:7]
	s_mov_b64 s[6:7], -1
	s_mov_b64 s[40:41], 0
	s_and_b64 vcc, exec, s[66:67]
	s_mov_b64 s[42:43], 0
	s_cbranch_vccz .LBB0_1637
	s_movk_i32 s6, 0x17ff
	v_cmp_lt_u32_e32 vcc, s6, v21
	s_and_saveexec_b64 s[6:7], vcc
	s_xor_b64 s[6:7], exec, s[6:7]
	s_cbranch_execz .LBB0_1634
	s_movk_i32 s12, 0x2000
	v_cmp_gt_u32_e32 vcc, s12, v21
	s_mov_b64 s[16:17], -1
	s_and_saveexec_b64 s[12:13], vcc
	s_cbranch_execz .LBB0_1633
	v_readlane_b32 s24, v252, 14
	v_readlane_b32 s25, v252, 15
	s_mov_b64 s[16:17], s[24:25]
	s_load_dwordx2 s[16:17], s[16:17], 0x58
	v_add_u32_e32 v0, 0xe800, v21
	v_readlane_b32 s18, v252, 12
	v_and_b32_e32 v13, 0xffc0, v0
	v_lshlrev_b32_e32 v0, 5, v21
	s_waitcnt lgkmcnt(0)
	s_add_u32 s16, s16, s54
	v_readlane_b32 s19, v252, 13
	v_mov_b32_e32 v22, v220
	v_and_b32_e32 v8, 0x7e0, v0
	s_addc_u32 s17, s17, s55
	s_load_dwordx2 s[26:27], s[24:25], 0x50
	v_lshlrev_b32_e32 v184, 2, v8
	v_lshlrev_b32_e32 v2, 4, v22
	v_bfe_u32 v12, v22, 3, 3
	v_lshl_add_u64 v[0:1], s[16:17], 0, v[184:185]
	v_and_b32_e32 v184, 0x70, v2
	v_lshl_add_u64 v[4:5], v[0:1], 0, v[184:185]
	v_or_b32_e32 v0, v12, v13
	v_lshlrev_b32_e32 v6, 13, v0
	v_mov_b32_e32 v7, v185
	v_lshl_add_u64 v[0:1], v[4:5], 0, v[6:7]
	global_load_dwordx4 v[132:135], v[0:1], off nt
	v_mul_u32_u24_e32 v7, 0x84, v12
	v_add3_u32 v7, s79, v184, v7
	v_or_b32_e32 v11, 8, v12
	v_add_u32_e32 v9, 0x420, v7
	v_or_b32_e32 v10, 16, v12
	v_add_u32_e32 v23, 0xc60, v7
	v_readlane_b32 s24, v255, 60
	v_and_b32_e32 v22, 7, v22
	v_readlane_b32 s25, v255, 61
	s_waitcnt lgkmcnt(0)
	s_add_u32 s24, s26, s24
	s_addc_u32 s25, s27, s25
	s_cmp_lg_u64 s[26:27], 0
	s_cselect_b64 s[48:49], -1, 0
	s_cmp_eq_u64 s[26:27], 0
	v_or_b32_e32 v0, v11, v13
	v_lshlrev_b32_e32 v184, 13, v0
	v_lshl_add_u64 v[0:1], v[4:5], 0, v[184:185]
	global_load_dwordx4 v[136:139], v[0:1], off nt
	v_add_u32_e32 v0, 0x428, v7
	v_or_b32_e32 v0, v10, v13
	v_lshlrev_b32_e32 v184, 13, v0
	v_lshl_add_u64 v[0:1], v[4:5], 0, v[184:185]
	global_load_dwordx4 v[140:143], v[0:1], off nt
	v_add_u32_e32 v9, 0x840, v7
	v_add_u32_e32 v0, 0x848, v7
	v_or_b32_e32 v9, 24, v12
	v_or_b32_e32 v0, v9, v13
	v_lshlrev_b32_e32 v184, 13, v0
	v_lshl_add_u64 v[0:1], v[4:5], 0, v[184:185]
	global_load_dwordx4 v[144:147], v[0:1], off nt
	v_or_b32_e32 v184, 0x40000, v6
	v_add_u32_e32 v0, 0xc68, v7
	v_lshl_add_u64 v[0:1], v[4:5], 0, v[184:185]
	global_load_dwordx4 v[148:151], v[0:1], off nt
	v_add_u32_e32 v23, 0x1080, v7
	v_or_b32_e32 v184, 0x50000, v6
	v_add_u32_e32 v0, 0x1088, v7
	v_lshl_add_u64 v[0:1], v[4:5], 0, v[184:185]
	global_load_dwordx4 v[152:155], v[0:1], off nt
	v_add_u32_e32 v23, 0x14a0, v7
	v_or_b32_e32 v184, 0x60000, v6
	v_add_u32_e32 v0, 0x14a8, v7
	v_lshl_add_u64 v[0:1], v[4:5], 0, v[184:185]
	global_load_dwordx4 v[156:159], v[0:1], off nt
	v_add_u32_e32 v23, 0x18c0, v7
	v_or_b32_e32 v184, 0x70000, v6
	v_add_u32_e32 v0, 0x18c8, v7
	v_lshl_add_u64 v[0:1], v[4:5], 0, v[184:185]
	global_load_dwordx4 v[160:163], v[0:1], off nt
	v_add_u32_e32 v4, 0x1ce0, v7
	v_lshlrev_b32_e32 v23, 3, v22
	v_add_u32_e32 v0, 0x1ce8, v7
	s_waitcnt vmcnt(0)
	v_add_u32_e32 v164, 0x0, v7
	ds_write2_b32 v164, v132, v133 offset1:1
	ds_write2_b32 v164, v134, v135 offset0:2 offset1:3
	v_add_u32_e32 v164, 0x420, v7
	ds_write2_b32 v164, v136, v137 offset1:1
	ds_write2_b32 v164, v138, v139 offset0:2 offset1:3
	v_add_u32_e32 v164, 0x840, v7
	ds_write2_b32 v164, v140, v141 offset1:1
	ds_write2_b32 v164, v142, v143 offset0:2 offset1:3
	v_add_u32_e32 v164, 0xc60, v7
	ds_write2_b32 v164, v144, v145 offset1:1
	ds_write2_b32 v164, v146, v147 offset0:2 offset1:3
	v_add_u32_e32 v164, 0x1080, v7
	ds_write2_b32 v164, v148, v149 offset1:1
	ds_write2_b32 v164, v150, v151 offset0:2 offset1:3
	v_add_u32_e32 v164, 0x14a0, v7
	ds_write2_b32 v164, v152, v153 offset1:1
	ds_write2_b32 v164, v154, v155 offset0:2 offset1:3
	v_add_u32_e32 v164, 0x18c0, v7
	ds_write2_b32 v164, v156, v157 offset1:1
	ds_write2_b32 v164, v158, v159 offset0:2 offset1:3
	v_add_u32_e32 v164, 0x1ce0, v7
	ds_write2_b32 v164, v160, v161 offset1:1
	ds_write2_b32 v164, v162, v163 offset0:2 offset1:3
	s_waitcnt lgkmcnt(0)
	v_or_b32_e32 v1, v23, v13
	v_and_b32_e32 v1, 0xf8, v1
	v_mov_b32_e32 v0, 1.0
	v_lshlrev_b32_e32 v24, 2, v1
	v_mov_b32_e32 v2, 1.0
	s_cbranch_scc1 .LBB0_1618
	global_load_dword v1, v24, s[24:25]
	s_waitcnt vmcnt(0)
	v_mul_f32_e32 v2, v15, v1

; #define LAS __attribute__((address_space(3)))
; #define F_LANE() (tid_of(F.wave) & 63)
; #define LDS_WAIT() asm volatile("s_waitcnt lgkmcnt(0)" ::: "memory")
; template <class Map>
; __device__ __forceinline__ void conv_item(const Frame& F, int it, const float* W, int K, int N, bf16_t* WT, const float* gk, int gmask, float gmul, const float* bk, i64* cs, i64* bw, Map map) {
;     LAS float* scr = (LAS float*)(F.lds + F.wave * 16384);
;     const int lane = F_LANE(), nblk = N / 32;
;     {
;         const int kb = it / nblk, nb = it % nblk, k0 = 64 * kb, n0 = 32 * nb, v0 = map(n0);
; #pragma unroll
;         for (int i = 0; i < 8; ++i) { const int kk = 8 * i + (lane >> 3), c4 = (lane & 7) * 4;
;             const f32x4 w4 = __builtin_nontemporal_load((const f32x4*)(W + (size_t)(k0 + kk) * N + n0 + c4)); LAS float* d = scr + kk * 33 + c4; d[0] = w4[0]; d[1] = w4[1]; d[2] = w4[2]; d[3] = w4[3]; }
;         LDS_WAIT(); asm volatile("" ::: "memory");
;         if (bk) {
;             const int n = lane & 31, kh = lane >> 5; float sb = 0.f, sc = 0.f;
; #pragma unroll 8
;             for (int j = 0; j < 32; ++j) { const int kk = kh * 32 + j; const float w = scr[kk * 33 + n]; sb += bk[k0 + kk] * w; sc += bf_round(gk[(k0 + kk) & gmask] * gmul * w); }
;             { auto r = __builtin_amdgcn_permlane32_swap(__float_as_uint(sb), __float_as_uint(sb), false, false); sb = __uint_as_float(r[0]) + __uint_as_float(r[1]); }
;             { auto r = __builtin_amdgcn_permlane32_swap(__float_as_uint(sc), __float_as_uint(sc), false, false); sc = __uint_as_float(r[0]) + __uint_as_float(r[1]); }
;             if (lane < 32) { atomic_addq(bw + v0 + n, sb, FX_COL); atomic_addq(cs + v0 + n, sc, FX_COL); }
;         }
;         const int c = lane & 7; float gl[8];
; #pragma unroll
;         for (int i = 0; i < 8; ++i) gl[i] = gk ? gk[(k0 + 8 * c + i) & gmask] * gmul : 1.0f;
; #pragma unroll
;         for (int j = 0; j < 4; ++j) { const int n = (lane >> 3) + 8 * j; const LAS float* s = scr + (8 * c) * 33 + n;
;             u32x4 o; o.x = pk2(s[0 * 33] * gl[0], s[1 * 33] * gl[1]); o.y = pk2(s[2 * 33] * gl[2], s[3 * 33] * gl[3]); o.z = pk2(s[4 * 33] * gl[4], s[5 * 33] * gl[5]); o.w = pk2(s[6 * 33] * gl[6], s[7 * 33] * gl[7]);
;             __builtin_nontemporal_store(o, (u32x4*)(WT + (size_t)(v0 + n) * K + k0 + 8 * c)); }
.LBB0_1634:
	s_andn2_saveexec_b64 s[6:7], s[6:7]
	s_cbranch_execz .LBB0_1636
	v_readlane_b32 s12, v252, 14
	v_readlane_b32 s13, v252, 15
	s_load_dwordx2 s[12:13], s[12:13], 0x40
	s_mov_b32 s18, 0xaaab
	v_readlane_b32 s16, v255, 43
	v_mul_u32_u24_sdwa v0, v21, s18 dst_sel:DWORD dst_unused:UNUSED_PAD src0_sel:WORD_0 src1_sel:DWORD
	v_lshrrev_b32_e32 v0, 23, v0
	s_waitcnt lgkmcnt(0)
	s_add_u32 s16, s12, s16
	v_readlane_b32 s12, v255, 49
	s_addc_u32 s17, s13, s12
	v_readlane_b32 s12, v252, 12
	v_mul_lo_u16_e32 v1, 0xc0, v0
	v_readlane_b32 s13, v252, 13
	v_mov_b32_e32 v6, v220
	v_sub_u16_e32 v1, v21, v1
	v_lshlrev_b16_e32 v12, 6, v0
	v_lshlrev_b16_e32 v2, 5, v1
	v_bfe_u32 v7, v6, 3, 3
	v_lshlrev_b32_e32 v184, 2, v2
	v_lshlrev_b32_e32 v3, 4, v6
	v_or_b32_e32 v13, v7, v12
	v_lshl_add_u64 v[0:1], s[16:17], 0, v[184:185]
	v_and_b32_e32 v184, 0x70, v3
	v_mul_u32_u24_e32 v3, 0x1800, v13
	v_lshl_add_u64 v[0:1], v[0:1], 0, v[184:185]
	v_lshlrev_b32_e32 v4, 2, v3
	v_mov_b32_e32 v5, v185
	v_lshl_add_u64 v[4:5], v[0:1], 0, v[4:5]
	global_load_dwordx4 v[132:135], v[4:5], off nt
	v_mul_u32_u24_e32 v3, 0x84, v7
	v_or_b32_e32 v5, 8, v7
	v_add3_u32 v22, s79, v184, v3
	v_or_b32_e32 v3, v5, v12
	v_mul_u32_u24_e32 v3, 0x1800, v3
	v_lshlrev_b32_e32 v184, 2, v3
	v_add_u32_e32 v3, 0x420, v22
	v_or_b32_e32 v4, 16, v7
	v_add_u32_e32 v23, 0xc60, v22
	v_and_b32_e32 v6, 7, v6
	v_or_b32_e32 v5, v5, v2
	v_lshl_add_u64 v[8:9], v[0:1], 0, v[184:185]
	global_load_dwordx4 v[136:139], v[8:9], off nt
	v_add_u32_e32 v3, 0x428, v22
	v_or_b32_e32 v3, v4, v12
	v_mul_u32_u24_e32 v3, 0x1800, v3
	v_lshlrev_b32_e32 v184, 2, v3
	v_lshl_add_u64 v[8:9], v[0:1], 0, v[184:185]
	global_load_dwordx4 v[140:143], v[8:9], off nt
	v_add_u32_e32 v3, 0x840, v22
	v_or_b32_e32 v4, v4, v2
	v_add_u32_e32 v3, 0x848, v22
	v_or_b32_e32 v3, 24, v7
	v_or_b32_e32 v8, v3, v12
	v_mul_u32_u24_e32 v8, 0x1800, v8
	v_lshlrev_b32_e32 v184, 2, v8
	v_lshl_add_u64 v[8:9], v[0:1], 0, v[184:185]
	global_load_dwordx4 v[144:147], v[8:9], off nt
	v_add_u32_e32 v8, 0xc68, v22
	v_or_b32_e32 v8, 32, v13
	v_mul_u32_u24_e32 v8, 0x1800, v8
	v_lshlrev_b32_e32 v184, 2, v8
	v_lshl_add_u64 v[8:9], v[0:1], 0, v[184:185]
	global_load_dwordx4 v[148:151], v[8:9], off nt
	v_add_u32_e32 v23, 0x1080, v22
	v_add_u32_e32 v8, 0x1088, v22
	v_or_b32_e32 v8, 40, v13
	v_mul_u32_u24_e32 v8, 0x1800, v8
	v_lshlrev_b32_e32 v184, 2, v8
	v_lshl_add_u64 v[8:9], v[0:1], 0, v[184:185]
	global_load_dwordx4 v[152:155], v[8:9], off nt
	v_add_u32_e32 v23, 0x14a0, v22
	v_add_u32_e32 v8, 0x14a8, v22
	v_or_b32_e32 v8, 48, v13
	v_mul_u32_u24_e32 v8, 0x1800, v8
	v_lshlrev_b32_e32 v184, 2, v8
	v_lshl_add_u64 v[8:9], v[0:1], 0, v[184:185]
	global_load_dwordx4 v[156:159], v[8:9], off nt
	v_add_u32_e32 v23, 0x18c0, v22
	v_add_u32_e32 v8, 0x18c8, v22
	v_or_b32_e32 v8, 56, v13
	v_mul_u32_u24_e32 v8, 0x1800, v8
	v_lshlrev_b32_e32 v184, 2, v8
	v_lshl_add_u64 v[0:1], v[0:1], 0, v[184:185]
	global_load_dwordx4 v[160:163], v[0:1], off nt
	v_add_u32_e32 v0, 0x1ce0, v22
	v_lshlrev_b32_e32 v184, 1, v12
	v_add_u32_e32 v0, 0x1ce8, v22
	s_waitcnt vmcnt(0)
	v_add_u32_e32 v164, 0x0, v22
	ds_write2_b32 v164, v132, v133 offset1:1
	ds_write2_b32 v164, v134, v135 offset0:2 offset1:3
	v_add_u32_e32 v164, 0x420, v22
	ds_write2_b32 v164, v136, v137 offset1:1
	ds_write2_b32 v164, v138, v139 offset0:2 offset1:3
	v_add_u32_e32 v164, 0x840, v22
	ds_write2_b32 v164, v140, v141 offset1:1
	ds_write2_b32 v164, v142, v143 offset0:2 offset1:3
	v_add_u32_e32 v164, 0xc60, v22
	ds_write2_b32 v164, v144, v145 offset1:1
	ds_write2_b32 v164, v146, v147 offset0:2 offset1:3
	v_add_u32_e32 v164, 0x1080, v22
	ds_write2_b32 v164, v148, v149 offset1:1
	ds_write2_b32 v164, v150, v151 offset0:2 offset1:3
	v_add_u32_e32 v164, 0x14a0, v22
	ds_write2_b32 v164, v152, v153 offset1:1
	ds_write2_b32 v164, v154, v155 offset0:2 offset1:3
	v_add_u32_e32 v164, 0x18c0, v22
	ds_write2_b32 v164, v156, v157 offset1:1
	ds_write2_b32 v164, v158, v159 offset0:2 offset1:3
	v_add_u32_e32 v164, 0x1ce0, v22
	ds_write2_b32 v164, v160, v161 offset1:1
	ds_write2_b32 v164, v162, v163 offset0:2 offset1:3
	s_waitcnt lgkmcnt(0)
	v_mul_u32_u24_e32 v8, 0x420, v6
	v_lshl_add_u64 v[0:1], s[12:13], 0, v[184:185]
	v_lshlrev_b32_e32 v184, 4, v6
	v_lshlrev_b32_e32 v6, 2, v7
	v_add3_u32 v6, s79, v8, v6
	ds_read_b32 v8, v6
	ds_read_b32 v9, v6 offset:132
	v_lshl_add_u64 v[0:1], v[0:1], 0, v[184:185]
	s_mov_b64 s[12:13], 0x39500000
	v_or_b32_e32 v7, v7, v2
	s_waitcnt lgkmcnt(1)
	v_bfe_u32 v10, v8, 16, 1
	v_add3_u32 v8, v8, v10, s73
	s_waitcnt lgkmcnt(0)
; #define LAS __attribute__((address_space(3)))
; #define LDS_WAIT() asm volatile("s_waitcnt lgkmcnt(0)" ::: "memory")
; __device__ __forceinline__ unsigned pk2(float lo, float hi) { return f2bf(lo) | (f2bf(hi) << 16); }
; template <class Map>
; __device__ __forceinline__ void conv_item(const Frame& F, int it, const float* W, int K, int N, bf16_t* WT, const float* gk, int gmask, float gmul, const float* bk, i64* cs, i64* bw, Map map) {
;     ...
;         const int c = lane & 7; float gl[8];
; #pragma unroll
;         for (int i = 0; i < 8; ++i) gl[i] = gk ? gk[(k0 + 8 * c + i) & gmask] * gmul : 1.0f;
; #pragma unroll
;         for (int j = 0; j < 4; ++j) { const int n = (lane >> 3) + 8 * j; const LAS float* s = scr + (8 * c) * 33 + n;
;             u32x4 o; o.x = pk2(s[0 * 33] * gl[0], s[1 * 33] * gl[1]); o.y = pk2(s[2 * 33] * gl[2], s[3 * 33] * gl[3]); o.z = pk2(s[4 * 33] * gl[4], s[5 * 33] * gl[5]); o.w = pk2(s[6 * 33] * gl[6], s[7 * 33] * gl[7]);
;             __builtin_nontemporal_store(o, (u32x4*)(WT + (size_t)(v0 + n) * K + k0 + 8 * c)); }
;         LDS_WAIT(); asm volatile("" ::: "memory");
	v_bfe_u32 v10, v9, 16, 1
	v_lshrrev_b32_e32 v8, 16, v8
	v_add3_u32 v9, v9, v10, s73
	v_and_or_b32 v8, v9, s72, v8
	ds_read_b32 v9, v6 offset:264
	ds_read_b32 v10, v6 offset:396
	v_lshl_add_u64 v[0:1], v[0:1], 0, s[12:13]
	v_lshlrev_b32_e32 v184, 12, v7
	v_or_b32_e32 v2, v3, v2
	s_waitcnt lgkmcnt(1)
	v_bfe_u32 v11, v9, 16, 1
	v_add3_u32 v9, v9, v11, s73
	s_waitcnt lgkmcnt(0)
	v_bfe_u32 v11, v10, 16, 1
	v_lshrrev_b32_e32 v9, 16, v9
	v_add3_u32 v10, v10, v11, s73
	v_and_or_b32 v9, v10, s72, v9
	ds_read_b32 v10, v6 offset:528
	ds_read_b32 v11, v6 offset:660
	s_waitcnt lgkmcnt(1)
	v_bfe_u32 v12, v10, 16, 1
	v_add3_u32 v10, v10, v12, s73
	s_waitcnt lgkmcnt(0)
	v_bfe_u32 v12, v11, 16, 1
	v_lshrrev_b32_e32 v10, 16, v10
	v_add3_u32 v11, v11, v12, s73
	v_and_or_b32 v10, v11, s72, v10
	ds_read_b32 v11, v6 offset:792
	ds_read_b32 v12, v6 offset:924
	s_waitcnt lgkmcnt(1)
	v_bfe_u32 v13, v11, 16, 1
	v_add3_u32 v11, v11, v13, s73
	s_waitcnt lgkmcnt(0)
	v_bfe_u32 v13, v12, 16, 1
	v_lshrrev_b32_e32 v11, 16, v11
	v_add3_u32 v12, v12, v13, s73
	v_and_or_b32 v11, v12, s72, v11
	v_lshl_add_u64 v[12:13], v[0:1], 0, v[184:185]
	flat_store_dwordx4 v[12:13], v[8:11] nt
	ds_read_b32 v7, v6 offset:32
	ds_read_b32 v8, v6 offset:164
	v_lshlrev_b32_e32 v184, 12, v5
	s_waitcnt lgkmcnt(0)
	v_bfe_u32 v9, v7, 16, 1
	v_add3_u32 v7, v7, v9, s73
	v_bfe_u32 v9, v8, 16, 1
	v_lshrrev_b32_e32 v7, 16, v7
	v_add3_u32 v8, v8, v9, s73
	v_and_or_b32 v8, v8, s72, v7
	ds_read_b32 v7, v6 offset:296
	ds_read_b32 v9, v6 offset:428
	s_waitcnt lgkmcnt(0)
	v_bfe_u32 v10, v7, 16, 1
	v_add3_u32 v7, v7, v10, s73
	v_bfe_u32 v10, v9, 16, 1
	v_lshrrev_b32_e32 v7, 16, v7
	v_add3_u32 v9, v9, v10, s73
	v_and_or_b32 v9, v9, s72, v7
	ds_read_b32 v7, v6 offset:560
	ds_read_b32 v10, v6 offset:692
	s_waitcnt lgkmcnt(0)
	v_bfe_u32 v11, v7, 16, 1
	v_add3_u32 v7, v7, v11, s73
	v_bfe_u32 v11, v10, 16, 1
	v_lshrrev_b32_e32 v7, 16, v7
	v_add3_u32 v10, v10, v11, s73
	v_and_or_b32 v10, v10, s72, v7
	ds_read_b32 v7, v6 offset:824
	ds_read_b32 v11, v6 offset:956
	s_waitcnt lgkmcnt(0)
	v_bfe_u32 v12, v7, 16, 1
	v_add3_u32 v7, v7, v12, s73
	v_bfe_u32 v12, v11, 16, 1
	v_lshrrev_b32_e32 v7, 16, v7
	v_add3_u32 v11, v11, v12, s73
	v_and_or_b32 v11, v11, s72, v7
	v_lshl_add_u64 v[12:13], v[0:1], 0, v[184:185]
	flat_store_dwordx4 v[12:13], v[8:11] nt
	ds_read_b32 v5, v6 offset:64
	ds_read_b32 v7, v6 offset:196
	v_lshlrev_b32_e32 v184, 12, v4
	s_waitcnt lgkmcnt(0)
	v_bfe_u32 v8, v5, 16, 1
	v_add3_u32 v5, v5, v8, s73
	v_bfe_u32 v8, v7, 16, 1
	v_lshrrev_b32_e32 v5, 16, v5
	v_add3_u32 v7, v7, v8, s73
	v_and_or_b32 v8, v7, s72, v5
	ds_read_b32 v5, v6 offset:328
	ds_read_b32 v7, v6 offset:460
	s_waitcnt lgkmcnt(0)
	v_bfe_u32 v9, v5, 16, 1
	v_add3_u32 v5, v5, v9, s73
	v_bfe_u32 v9, v7, 16, 1
	v_lshrrev_b32_e32 v5, 16, v5
	v_add3_u32 v7, v7, v9, s73
	v_and_or_b32 v9, v7, s72, v5
	ds_read_b32 v5, v6 offset:592
	ds_read_b32 v7, v6 offset:724
	s_waitcnt lgkmcnt(0)
	v_bfe_u32 v10, v5, 16, 1
	v_add3_u32 v5, v5, v10, s73
	v_bfe_u32 v10, v7, 16, 1
	v_lshrrev_b32_e32 v5, 16, v5
	v_add3_u32 v7, v7, v10, s73
	v_and_or_b32 v10, v7, s72, v5
	ds_read_b32 v5, v6 offset:856
	ds_read_b32 v7, v6 offset:988
	s_waitcnt lgkmcnt(0)
	v_bfe_u32 v11, v5, 16, 1
	v_add3_u32 v5, v5, v11, s73
	v_bfe_u32 v11, v7, 16, 1
	v_lshrrev_b32_e32 v5, 16, v5
	v_add3_u32 v7, v7, v11, s73
	v_and_or_b32 v11, v7, s72, v5
	v_lshl_add_u64 v[4:5], v[0:1], 0, v[184:185]
	flat_store_dwordx4 v[4:5], v[8:11] nt
	ds_read_b32 v4, v6 offset:96
	ds_read_b32 v5, v6 offset:228
	v_lshlrev_b32_e32 v184, 12, v2
	v_lshl_add_u64 v[0:1], v[0:1], 0, v[184:185]
	s_waitcnt lgkmcnt(0)
	v_bfe_u32 v7, v4, 16, 1
	v_add3_u32 v4, v4, v7, s73
	v_bfe_u32 v7, v5, 16, 1
	v_lshrrev_b32_e32 v4, 16, v4
	v_add3_u32 v5, v5, v7, s73
	v_and_or_b32 v8, v5, s72, v4
	ds_read_b32 v4, v6 offset:360
	ds_read_b32 v5, v6 offset:492
	s_waitcnt lgkmcnt(0)
	v_bfe_u32 v7, v4, 16, 1
	v_add3_u32 v4, v4, v7, s73
	v_bfe_u32 v7, v5, 16, 1
	v_lshrrev_b32_e32 v4, 16, v4
	v_add3_u32 v5, v5, v7, s73
	v_and_or_b32 v9, v5, s72, v4
	ds_read_b32 v4, v6 offset:624
	ds_read_b32 v5, v6 offset:756
	s_waitcnt lgkmcnt(0)
	v_bfe_u32 v7, v4, 16, 1
	v_add3_u32 v4, v4, v7, s73
	v_bfe_u32 v7, v5, 16, 1
	v_lshrrev_b32_e32 v4, 16, v4
	v_add3_u32 v5, v5, v7, s73
	v_and_or_b32 v10, v5, s72, v4
	ds_read_b32 v4, v6 offset:888
	ds_read_b32 v5, v6 offset:1020
	s_waitcnt lgkmcnt(0)
	v_bfe_u32 v6, v4, 16, 1
	v_add3_u32 v4, v4, v6, s73
	v_bfe_u32 v6, v5, 16, 1
	v_lshrrev_b32_e32 v4, 16, v4
	v_add3_u32 v5, v5, v6, s73
	v_and_or_b32 v11, v5, s72, v4
	flat_store_dwordx4 v[0:1], v[8:11] nt
	s_waitcnt lgkmcnt(0)

; #define LAS __attribute__((address_space(3)))
; #define F_LANE() (tid_of(F.wave) & 63)
; #define LDS_WAIT() asm volatile("s_waitcnt lgkmcnt(0)" ::: "memory")
; template <class Map>
; __device__ __forceinline__ void conv_item(const Frame& F, int it, const float* W, int K, int N, bf16_t* WT, const float* gk, int gmask, float gmul, const float* bk, i64* cs, i64* bw, Map map) {
;     LAS float* scr = (LAS float*)(F.lds + F.wave * 16384);
;     const int lane = F_LANE(), nblk = N / 32;
;     {
;         const int kb = it / nblk, nb = it % nblk, k0 = 64 * kb, n0 = 32 * nb, v0 = map(n0);
; #pragma unroll
;         for (int i = 0; i < 8; ++i) { const int kk = 8 * i + (lane >> 3), c4 = (lane & 7) * 4;
;             const f32x4 w4 = __builtin_nontemporal_load((const f32x4*)(W + (size_t)(k0 + kk) * N + n0 + c4)); LAS float* d = scr + kk * 33 + c4; d[0] = w4[0]; d[1] = w4[1]; d[2] = w4[2]; d[3] = w4[3]; }
;         LDS_WAIT(); asm volatile("" ::: "memory");
;         if (bk) {
;             const int n = lane & 31, kh = lane >> 5; float sb = 0.f, sc = 0.f;
; #pragma unroll 8
;             for (int j = 0; j < 32; ++j) { const int kk = kh * 32 + j; const float w = scr[kk * 33 + n]; sb += bk[k0 + kk] * w; sc += bf_round(gk[(k0 + kk) & gmask] * gmul * w); }
;             { auto r = __builtin_amdgcn_permlane32_swap(__float_as_uint(sb), __float_as_uint(sb), false, false); sb = __uint_as_float(r[0]) + __uint_as_float(r[1]); }
;             { auto r = __builtin_amdgcn_permlane32_swap(__float_as_uint(sc), __float_as_uint(sc), false, false); sc = __uint_as_float(r[0]) + __uint_as_float(r[1]); }
;             if (lane < 32) { atomic_addq(bw + v0 + n, sb, FX_COL); atomic_addq(cs + v0 + n, sc, FX_COL); }
;         }
;         const int c = lane & 7; float gl[8];
; #pragma unroll
;         for (int i = 0; i < 8; ++i) gl[i] = gk ? gk[(k0 + 8 * c + i) & gmask] * gmul : 1.0f;
; #pragma unroll
;         for (int j = 0; j < 4; ++j) { const int n = (lane >> 3) + 8 * j; const LAS float* s = scr + (8 * c) * 33 + n;
;             u32x4 o; o.x = pk2(s[0 * 33] * gl[0], s[1 * 33] * gl[1]); o.y = pk2(s[2 * 33] * gl[2], s[3 * 33] * gl[3]); o.z = pk2(s[4 * 33] * gl[4], s[5 * 33] * gl[5]); o.w = pk2(s[6 * 33] * gl[6], s[7 * 33] * gl[7]);
;             __builtin_nontemporal_store(o, (u32x4*)(WT + (size_t)(v0 + n) * K + k0 + 8 * c)); }
.LBB0_1653:
	s_andn2_saveexec_b64 s[86:87], s[12:13]
	s_cbranch_execz .LBB0_1655
	v_readlane_b32 s12, v252, 14
	v_readlane_b32 s13, v252, 15
	s_load_dwordx2 s[12:13], s[12:13], 0x90
	v_readlane_b32 s16, v255, 52
	v_readlane_b32 s17, v255, 53
	v_and_b32_e32 v23, 0xc0, v0
	v_lshlrev_b32_e32 v0, 5, v0
	s_waitcnt lgkmcnt(0)
	s_add_u32 s16, s12, s16
	s_addc_u32 s17, s13, s17
	v_readlane_b32 s12, v252, 12
	v_readlane_b32 s13, v252, 13
	v_mov_b32_e32 v22, v220
	v_and_b32_e32 v2, 0x7e0, v0
	v_lshlrev_b32_e32 v184, 2, v2
	v_bfe_u32 v7, v22, 3, 3
	v_lshlrev_b32_e32 v3, 4, v22
	v_lshl_add_u64 v[0:1], s[16:17], 0, v[184:185]
	v_and_b32_e32 v184, 0x70, v3
	v_or_b32_e32 v3, v7, v23
	v_lshl_add_u64 v[0:1], v[0:1], 0, v[184:185]
	v_lshlrev_b32_e32 v12, 13, v3
	v_mov_b32_e32 v13, v185
	v_lshl_add_u64 v[4:5], v[0:1], 0, v[12:13]
	global_load_dwordx4 v[132:135], v[4:5], off nt
	v_mul_u32_u24_e32 v3, 0x84, v7
	v_or_b32_e32 v6, 8, v7
	v_add3_u32 v13, s79, v184, v3
	v_or_b32_e32 v3, v6, v23
	v_lshlrev_b32_e32 v184, 13, v3
	v_lshl_add_u64 v[4:5], v[0:1], 0, v[184:185]
	v_add_u32_e32 v3, 0x420, v13
	s_add_u32 s12, s12, s61
	s_addc_u32 s13, s13, 0
	v_or_b32_e32 v6, v6, v2
	global_load_dwordx4 v[136:139], v[4:5], off nt
	v_or_b32_e32 v4, 16, v7
	v_add_u32_e32 v3, 0x428, v13
	v_or_b32_e32 v3, v4, v23
	v_lshlrev_b32_e32 v184, 13, v3
	v_lshl_add_u64 v[8:9], v[0:1], 0, v[184:185]
	global_load_dwordx4 v[140:143], v[8:9], off nt
	v_add_u32_e32 v3, 0x840, v13
	v_or_b32_e32 v4, v4, v2
	v_add_u32_e32 v3, 0x848, v13
	v_or_b32_e32 v3, 24, v7
	v_or_b32_e32 v5, v3, v23
	v_lshlrev_b32_e32 v184, 13, v5
	v_lshl_add_u64 v[8:9], v[0:1], 0, v[184:185]
	global_load_dwordx4 v[144:147], v[8:9], off nt
	v_add_u32_e32 v5, 0xc60, v13
	v_or_b32_e32 v184, 0x40000, v12
	v_add_u32_e32 v5, 0xc68, v13
	v_lshl_add_u64 v[8:9], v[0:1], 0, v[184:185]
	global_load_dwordx4 v[148:151], v[8:9], off nt
	v_add_u32_e32 v5, 0x1080, v13
	v_or_b32_e32 v184, 0x50000, v12
	v_add_u32_e32 v5, 0x1088, v13
	v_lshl_add_u64 v[8:9], v[0:1], 0, v[184:185]
	global_load_dwordx4 v[152:155], v[8:9], off nt
	v_add_u32_e32 v5, 0x14a0, v13
	v_or_b32_e32 v184, 0x60000, v12
	v_add_u32_e32 v5, 0x14a8, v13
	v_lshl_add_u64 v[8:9], v[0:1], 0, v[184:185]
	global_load_dwordx4 v[156:159], v[8:9], off nt
	v_add_u32_e32 v5, 0x18c0, v13
	v_or_b32_e32 v184, 0x70000, v12
	v_lshl_add_u64 v[0:1], v[0:1], 0, v[184:185]
	v_lshlrev_b32_e32 v184, 1, v23
	v_add_u32_e32 v5, 0x18c8, v13
	global_load_dwordx4 v[160:163], v[0:1], off nt
	v_add_u32_e32 v0, 0x1ce0, v13
	v_and_b32_e32 v5, 7, v22
	v_add_u32_e32 v0, 0x1ce8, v13
	s_waitcnt vmcnt(0)
	v_add_u32_e32 v164, 0x0, v13
	ds_write2_b32 v164, v132, v133 offset1:1
	ds_write2_b32 v164, v134, v135 offset0:2 offset1:3
	v_add_u32_e32 v164, 0x420, v13
	ds_write2_b32 v164, v136, v137 offset1:1
	ds_write2_b32 v164, v138, v139 offset0:2 offset1:3
	v_add_u32_e32 v164, 0x840, v13
	ds_write2_b32 v164, v140, v141 offset1:1
	ds_write2_b32 v164, v142, v143 offset0:2 offset1:3
	v_add_u32_e32 v164, 0xc60, v13
	ds_write2_b32 v164, v144, v145 offset1:1
	ds_write2_b32 v164, v146, v147 offset0:2 offset1:3
	v_add_u32_e32 v164, 0x1080, v13
	ds_write2_b32 v164, v148, v149 offset1:1
	ds_write2_b32 v164, v150, v151 offset0:2 offset1:3
	v_add_u32_e32 v164, 0x14a0, v13
	ds_write2_b32 v164, v152, v153 offset1:1
	ds_write2_b32 v164, v154, v155 offset0:2 offset1:3
	v_add_u32_e32 v164, 0x18c0, v13
	ds_write2_b32 v164, v156, v157 offset1:1
	ds_write2_b32 v164, v158, v159 offset0:2 offset1:3
	v_add_u32_e32 v164, 0x1ce0, v13
	ds_write2_b32 v164, v160, v161 offset1:1
	ds_write2_b32 v164, v162, v163 offset0:2 offset1:3
	s_waitcnt lgkmcnt(0)
	v_mul_u32_u24_e32 v8, 0x420, v5
	v_lshl_add_u64 v[0:1], s[12:13], 0, v[184:185]
	v_lshlrev_b32_e32 v184, 4, v5
	v_lshlrev_b32_e32 v5, 2, v7
	v_add3_u32 v5, s79, v8, v5
	ds_read_b32 v8, v5
	ds_read_b32 v9, v5 offset:132
	v_lshl_add_u64 v[0:1], v[0:1], 0, v[184:185]
	s_mov_b64 s[12:13], 0x7a00000
	v_or_b32_e32 v7, v7, v2
	s_waitcnt lgkmcnt(1)
	v_bfe_u32 v10, v8, 16, 1
	v_add3_u32 v8, v8, v10, s73
	s_waitcnt lgkmcnt(0)
	v_bfe_u32 v10, v9, 16, 1
	v_lshrrev_b32_e32 v8, 16, v8
	v_add3_u32 v9, v9, v10, s73
	v_and_or_b32 v8, v9, s72, v8
	ds_read_b32 v9, v5 offset:264
	ds_read_b32 v10, v5 offset:396
	v_lshl_add_u64 v[0:1], v[0:1], 0, s[12:13]
	v_lshlrev_b32_e32 v184, 9, v7
	v_or_b32_e32 v2, v3, v2
	s_waitcnt lgkmcnt(1)
; #define LAS __attribute__((address_space(3)))
; #define LDS_WAIT() asm volatile("s_waitcnt lgkmcnt(0)" ::: "memory")
; __device__ __forceinline__ unsigned f2bf(float f) { unsigned u = __builtin_bit_cast(unsigned, f); return (u + 0x7fffu + ((u >> 16) & 1u)) >> 16; }
; __device__ __forceinline__ float bf_round(float f) { return __uint_as_float(f2bf(f) << 16); }
; __device__ __forceinline__ unsigned pk2(float lo, float hi) { return f2bf(lo) | (f2bf(hi) << 16); }
; template <class Map>
; __device__ __forceinline__ void conv_item(const Frame& F, int it, const float* W, int K, int N, bf16_t* WT, const float* gk, int gmask, float gmul, const float* bk, i64* cs, i64* bw, Map map) {
;     ...
;         for (int j = 0; j < 4; ++j) { const int n = (lane >> 3) + 8 * j; const LAS float* s = scr + (8 * c) * 33 + n;
;             u32x4 o; o.x = pk2(s[0 * 33] * gl[0], s[1 * 33] * gl[1]); o.y = pk2(s[2 * 33] * gl[2], s[3 * 33] * gl[3]); o.z = pk2(s[4 * 33] * gl[4], s[5 * 33] * gl[5]); o.w = pk2(s[6 * 33] * gl[6], s[7 * 33] * gl[7]);
;             __builtin_nontemporal_store(o, (u32x4*)(WT + (size_t)(v0 + n) * K + k0 + 8 * c)); }
;         LDS_WAIT(); asm volatile("" ::: "memory");
	v_bfe_u32 v11, v9, 16, 1
	v_add3_u32 v9, v9, v11, s73
	s_waitcnt lgkmcnt(0)
	v_bfe_u32 v11, v10, 16, 1
	v_lshrrev_b32_e32 v9, 16, v9
	v_add3_u32 v10, v10, v11, s73
	v_and_or_b32 v9, v10, s72, v9
	ds_read_b32 v10, v5 offset:528
	ds_read_b32 v11, v5 offset:660
	s_waitcnt lgkmcnt(1)
	v_bfe_u32 v12, v10, 16, 1
	v_add3_u32 v10, v10, v12, s73
	s_waitcnt lgkmcnt(0)
	v_bfe_u32 v12, v11, 16, 1
	v_lshrrev_b32_e32 v10, 16, v10
	v_add3_u32 v11, v11, v12, s73
	v_and_or_b32 v10, v11, s72, v10
	ds_read_b32 v11, v5 offset:792
	ds_read_b32 v12, v5 offset:924
	s_waitcnt lgkmcnt(1)
	v_bfe_u32 v13, v11, 16, 1
	v_add3_u32 v11, v11, v13, s73
	s_waitcnt lgkmcnt(0)
	v_bfe_u32 v13, v12, 16, 1
	v_lshrrev_b32_e32 v11, 16, v11
	v_add3_u32 v12, v12, v13, s73
	v_and_or_b32 v11, v12, s72, v11
	v_lshl_add_u64 v[12:13], v[0:1], 0, v[184:185]
	flat_store_dwordx4 v[12:13], v[8:11] nt
	ds_read_b32 v7, v5 offset:32
	ds_read_b32 v8, v5 offset:164
	v_lshlrev_b32_e32 v184, 9, v6
	s_waitcnt lgkmcnt(0)
	v_bfe_u32 v9, v7, 16, 1
	v_add3_u32 v7, v7, v9, s73
	v_bfe_u32 v9, v8, 16, 1
	v_lshrrev_b32_e32 v7, 16, v7
	v_add3_u32 v8, v8, v9, s73
	v_and_or_b32 v8, v8, s72, v7
	ds_read_b32 v7, v5 offset:296
	ds_read_b32 v9, v5 offset:428
	s_waitcnt lgkmcnt(0)
	v_bfe_u32 v10, v7, 16, 1
	v_add3_u32 v7, v7, v10, s73
	v_bfe_u32 v10, v9, 16, 1
	v_lshrrev_b32_e32 v7, 16, v7
	v_add3_u32 v9, v9, v10, s73
	v_and_or_b32 v9, v9, s72, v7
	ds_read_b32 v7, v5 offset:560
	ds_read_b32 v10, v5 offset:692
	s_waitcnt lgkmcnt(0)
	v_bfe_u32 v11, v7, 16, 1
	v_add3_u32 v7, v7, v11, s73
	v_bfe_u32 v11, v10, 16, 1
	v_lshrrev_b32_e32 v7, 16, v7
	v_add3_u32 v10, v10, v11, s73
	v_and_or_b32 v10, v10, s72, v7
	ds_read_b32 v7, v5 offset:824
	ds_read_b32 v11, v5 offset:956
	s_waitcnt lgkmcnt(0)
	v_bfe_u32 v12, v7, 16, 1
	v_add3_u32 v7, v7, v12, s73
	v_bfe_u32 v12, v11, 16, 1
	v_lshrrev_b32_e32 v7, 16, v7
	v_add3_u32 v11, v11, v12, s73
	v_and_or_b32 v11, v11, s72, v7
	v_lshl_add_u64 v[6:7], v[0:1], 0, v[184:185]
	flat_store_dwordx4 v[6:7], v[8:11] nt
	ds_read_b32 v6, v5 offset:64
	ds_read_b32 v7, v5 offset:196
	v_lshlrev_b32_e32 v184, 9, v4
	s_waitcnt lgkmcnt(0)
	v_bfe_u32 v8, v6, 16, 1
	v_add3_u32 v6, v6, v8, s73
	v_bfe_u32 v8, v7, 16, 1
	v_lshrrev_b32_e32 v6, 16, v6
	v_add3_u32 v7, v7, v8, s73
	v_and_or_b32 v6, v7, s72, v6
	ds_read_b32 v7, v5 offset:328
	ds_read_b32 v8, v5 offset:460
	s_waitcnt lgkmcnt(0)
	v_bfe_u32 v9, v7, 16, 1
	v_add3_u32 v7, v7, v9, s73
	v_bfe_u32 v9, v8, 16, 1
	v_lshrrev_b32_e32 v7, 16, v7
	v_add3_u32 v8, v8, v9, s73
	v_and_or_b32 v7, v8, s72, v7
	ds_read_b32 v8, v5 offset:592
	ds_read_b32 v9, v5 offset:724
	s_waitcnt lgkmcnt(0)
	v_bfe_u32 v10, v8, 16, 1
	v_add3_u32 v8, v8, v10, s73
	v_bfe_u32 v10, v9, 16, 1
	v_lshrrev_b32_e32 v8, 16, v8
	v_add3_u32 v9, v9, v10, s73
	v_and_or_b32 v8, v9, s72, v8
	ds_read_b32 v9, v5 offset:856
	ds_read_b32 v10, v5 offset:988
	s_waitcnt lgkmcnt(0)
	v_bfe_u32 v11, v9, 16, 1
	v_add3_u32 v9, v9, v11, s73
	v_bfe_u32 v11, v10, 16, 1
	v_lshrrev_b32_e32 v9, 16, v9
	v_add3_u32 v10, v10, v11, s73
	v_and_or_b32 v9, v10, s72, v9
	v_lshl_add_u64 v[10:11], v[0:1], 0, v[184:185]
	flat_store_dwordx4 v[10:11], v[6:9] nt
	ds_read_b32 v4, v5 offset:96
	ds_read_b32 v6, v5 offset:228
	v_lshlrev_b32_e32 v184, 9, v2
	v_lshl_add_u64 v[0:1], v[0:1], 0, v[184:185]
	s_waitcnt lgkmcnt(0)
	v_bfe_u32 v7, v4, 16, 1
	v_add3_u32 v4, v4, v7, s73
	v_bfe_u32 v7, v6, 16, 1
	v_lshrrev_b32_e32 v4, 16, v4
	v_add3_u32 v6, v6, v7, s73
	v_and_or_b32 v6, v6, s72, v4
	ds_read_b32 v4, v5 offset:360
	ds_read_b32 v7, v5 offset:492
	s_waitcnt lgkmcnt(0)
	v_bfe_u32 v8, v4, 16, 1
	v_add3_u32 v4, v4, v8, s73
	v_bfe_u32 v8, v7, 16, 1
	v_lshrrev_b32_e32 v4, 16, v4
	v_add3_u32 v7, v7, v8, s73
	v_and_or_b32 v7, v7, s72, v4
	ds_read_b32 v4, v5 offset:624
	ds_read_b32 v8, v5 offset:756
	s_waitcnt lgkmcnt(0)
	v_bfe_u32 v9, v4, 16, 1
	v_add3_u32 v4, v4, v9, s73
	v_bfe_u32 v9, v8, 16, 1
	v_lshrrev_b32_e32 v4, 16, v4
	v_add3_u32 v8, v8, v9, s73
	v_and_or_b32 v8, v8, s72, v4
	ds_read_b32 v4, v5 offset:888
	ds_read_b32 v5, v5 offset:1020
	s_waitcnt lgkmcnt(0)
	v_bfe_u32 v9, v4, 16, 1
	v_add3_u32 v4, v4, v9, s73
	v_bfe_u32 v9, v5, 16, 1
	v_lshrrev_b32_e32 v4, 16, v4
	v_add3_u32 v5, v5, v9, s73
	v_and_or_b32 v9, v5, s72, v4
	flat_store_dwordx4 v[0:1], v[6:9] nt
	s_waitcnt lgkmcnt(0)

; #define LAS __attribute__((address_space(3)))
; #define F_LANE() (tid_of(F.wave) & 63)
; #define LDS_WAIT() asm volatile("s_waitcnt lgkmcnt(0)" ::: "memory")
; template <class Map>
; __device__ __forceinline__ void conv_item(const Frame& F, int it, const float* W, int K, int N, bf16_t* WT, const float* gk, int gmask, float gmul, const float* bk, i64* cs, i64* bw, Map map) {
;     ...
;     const int lane = F_LANE(), nblk = N / 32;
;     {
;         const int kb = it / nblk, nb = it % nblk, k0 = 64 * kb, n0 = 32 * nb, v0 = map(n0);
; #pragma unroll
;         for (int i = 0; i < 8; ++i) { const int kk = 8 * i + (lane >> 3), c4 = (lane & 7) * 4;
;             const f32x4 w4 = __builtin_nontemporal_load((const f32x4*)(W + (size_t)(k0 + kk) * N + n0 + c4)); LAS float* d = scr + kk * 33 + c4; d[0] = w4[0]; d[1] = w4[1]; d[2] = w4[2]; d[3] = w4[3]; }
;         LDS_WAIT(); asm volatile("" ::: "memory");
;         if (bk) {
;             const int n = lane & 31, kh = lane >> 5; float sb = 0.f, sc = 0.f;
.LBB0_1656:
	s_andn2_saveexec_b64 s[84:85], s[84:85]
	s_cbranch_execz .LBB0_1662
	v_readlane_b32 s48, v252, 14
	v_readlane_b32 s49, v252, 15
	s_mov_b64 s[12:13], s[48:49]
	s_load_dwordx2 s[12:13], s[12:13], 0x88
	v_readlane_b32 s16, v255, 54
	v_readlane_b32 s86, v252, 12
	v_readlane_b32 s17, v255, 55
	v_readlane_b32 s87, v252, 13
	s_waitcnt lgkmcnt(0)
	s_add_u32 s16, s12, s16
	s_addc_u32 s17, s13, s17
	s_mov_b64 s[62:63], s[86:87]
	s_mov_b64 s[12:13], s[48:49]
	s_mov_b32 s21, s79
	s_load_dwordx2 s[78:79], s[12:13], 0x68
	v_readlane_b32 s12, v255, 47
	v_readlane_b32 s13, v255, 48
	s_lshl_b64 s[12:13], s[12:13], 2
	v_add_u32_e32 v10, 0xbe00, v0
	s_waitcnt lgkmcnt(0)
	s_add_u32 s12, s78, s12
	s_addc_u32 s13, s79, s13
	s_add_u32 s96, s12, 0x2000
	s_addc_u32 s97, s13, 0
	s_mov_b64 s[12:13], s[48:49]
	v_lshlrev_b32_e32 v0, 5, v0
	s_load_dwordx2 vcc, s[12:13], 0x70
	s_mov_b64 s[12:13], s[86:87]
	s_mov_b64 s[48:49], s[86:87]
	v_mov_b32_e32 v24, v220
	v_and_b32_e32 v8, 0x7e0, v0
	v_lshlrev_b32_e32 v184, 2, v8
	v_lshlrev_b32_e32 v2, 4, v24
	v_and_b32_e32 v23, 0xffc0, v10
	v_bfe_u32 v22, v24, 3, 3
	v_lshl_add_u64 v[0:1], s[16:17], 0, v[184:185]
	v_and_b32_e32 v184, 0x70, v2
	v_lshl_add_u64 v[4:5], v[0:1], 0, v[184:185]
	v_or_b32_e32 v0, v22, v23
	v_lshlrev_b32_e32 v6, 13, v0
	v_mov_b32_e32 v7, v185
	v_lshl_add_u64 v[0:1], v[4:5], 0, v[6:7]
	global_load_dwordx4 v[132:135], v[0:1], off nt
	v_mul_u32_u24_e32 v7, 0x84, v22
	v_add3_u32 v7, s21, v184, v7
	v_or_b32_e32 v13, 8, v22
	v_add_u32_e32 v9, 0x420, v7
	v_or_b32_e32 v12, 16, v22
	v_add_u32_e32 v11, 0xc60, v7
	v_readlane_b32 s86, v255, 25
	s_add_u32 s16, s78, s86
	s_movk_i32 s78, 0x7c0
	v_readlane_b32 s87, v255, 26
	s_addc_u32 s17, s79, s87
	v_and_b32_e32 v26, 31, v24
	v_and_or_b32 v27, v24, 32, v23
	v_and_b32_e32 v25, 63, v24
	v_or_b32_e32 v0, v13, v23
	v_lshlrev_b32_e32 v184, 13, v0
	v_lshl_add_u64 v[0:1], v[4:5], 0, v[184:185]
	global_load_dwordx4 v[136:139], v[0:1], off nt
	v_add_u32_e32 v0, 0x428, v7
	v_or_b32_e32 v0, v12, v23
	v_lshlrev_b32_e32 v184, 13, v0
	v_lshl_add_u64 v[0:1], v[4:5], 0, v[184:185]
	global_load_dwordx4 v[140:143], v[0:1], off nt
	v_add_u32_e32 v9, 0x840, v7
	v_add_u32_e32 v0, 0x848, v7
	v_or_b32_e32 v9, 24, v22
	v_or_b32_e32 v0, v9, v23
	v_lshlrev_b32_e32 v184, 13, v0
	v_lshl_add_u64 v[0:1], v[4:5], 0, v[184:185]
	global_load_dwordx4 v[144:147], v[0:1], off nt
	v_or_b32_e32 v184, 0x40000, v6
	v_add_u32_e32 v0, 0xc68, v7
	v_lshl_add_u64 v[0:1], v[4:5], 0, v[184:185]
	global_load_dwordx4 v[148:151], v[0:1], off nt
	v_add_u32_e32 v11, 0x1080, v7
	v_or_b32_e32 v184, 0x50000, v6
	v_add_u32_e32 v0, 0x1088, v7
	v_lshl_add_u64 v[0:1], v[4:5], 0, v[184:185]
	global_load_dwordx4 v[152:155], v[0:1], off nt
	v_add_u32_e32 v11, 0x14a0, v7
	v_or_b32_e32 v184, 0x60000, v6
	v_add_u32_e32 v0, 0x14a8, v7
	v_lshl_add_u64 v[0:1], v[4:5], 0, v[184:185]
	global_load_dwordx4 v[156:159], v[0:1], off nt
	v_add_u32_e32 v11, 0x18c0, v7
	v_or_b32_e32 v184, 0x70000, v6
	v_add_u32_e32 v0, 0x18c8, v7
	v_lshl_add_u64 v[0:1], v[4:5], 0, v[184:185]
	global_load_dwordx4 v[160:163], v[0:1], off nt
	v_add_u32_e32 v4, 0x1ce0, v7
	v_add_u32_e32 v0, 0x1ce8, v7
	s_waitcnt vmcnt(0)
	v_add_u32_e32 v164, 0x0, v7
	ds_write2_b32 v164, v132, v133 offset1:1
	ds_write2_b32 v164, v134, v135 offset0:2 offset1:3
	v_add_u32_e32 v164, 0x420, v7
	ds_write2_b32 v164, v136, v137 offset1:1
	ds_write2_b32 v164, v138, v139 offset0:2 offset1:3
	v_add_u32_e32 v164, 0x840, v7
	ds_write2_b32 v164, v140, v141 offset1:1
	ds_write2_b32 v164, v142, v143 offset0:2 offset1:3
	v_add_u32_e32 v164, 0xc60, v7
	ds_write2_b32 v164, v144, v145 offset1:1
	ds_write2_b32 v164, v146, v147 offset0:2 offset1:3
	v_add_u32_e32 v164, 0x1080, v7
	ds_write2_b32 v164, v148, v149 offset1:1
	ds_write2_b32 v164, v150, v151 offset0:2 offset1:3
	v_add_u32_e32 v164, 0x14a0, v7
	ds_write2_b32 v164, v152, v153 offset1:1
	ds_write2_b32 v164, v154, v155 offset0:2 offset1:3
	v_add_u32_e32 v164, 0x18c0, v7
	ds_write2_b32 v164, v156, v157 offset1:1
	ds_write2_b32 v164, v158, v159 offset0:2 offset1:3
	v_add_u32_e32 v164, 0x1ce0, v7
	ds_write2_b32 v164, v160, v161 offset1:1
	ds_write2_b32 v164, v162, v163 offset0:2 offset1:3
	v_lshrrev_b32_e32 v0, 5, v24
	v_and_b32_e32 v0, 1, v0
	v_lshlrev_b16_e32 v0, 5, v0
	v_bitop3_b16 v0, v10, v0, s78 bitop3:0xec
	s_waitcnt lgkmcnt(0)
	v_lshlrev_b32_sdwa v184, v227, v0 dst_sel:DWORD dst_unused:UNUSED_PAD src0_sel:DWORD src1_sel:WORD_0
	v_bfe_u32 v0, v24, 5, 1
	v_lshl_add_u64 v[4:5], s[16:17], 0, v[184:185]
	s_waitcnt lgkmcnt(0)
	s_add_u32 s16, vcc_lo, s86
	v_mul_u32_u24_e32 v0, 0x1080, v0
	s_addc_u32 s17, vcc_hi, s87
	v_lshlrev_b32_e32 v184, 2, v27
	v_lshl_or_b32 v0, v26, 2, v0
	v_mov_b32_e32 v10, 0
	v_lshl_add_u64 v[6:7], s[16:17], 0, v[184:185]
	v_add_u32_e32 v28, s21, v0
	s_mov_b64 s[78:79], 0
	v_mov_b32_e32 v11, v10
	s_movk_i32 s16, 0x2000
	s_mov_b64 s[86:87], 0x2000

; #define LAS __attribute__((address_space(3)))
; #define F_LANE() (tid_of(F.wave) & 63)
; #define LDS_WAIT() asm volatile("s_waitcnt lgkmcnt(0)" ::: "memory")
; template <class Map>
; __device__ __forceinline__ void conv_item(const Frame& F, int it, const float* W, int K, int N, bf16_t* WT, const float* gk, int gmask, float gmul, const float* bk, i64* cs, i64* bw, Map map) {
;     ...
;     const int lane = F_LANE(), nblk = N / 32;
;     {
;         const int kb = it / nblk, nb = it % nblk, k0 = 64 * kb, n0 = 32 * nb, v0 = map(n0);
; #pragma unroll
;         for (int i = 0; i < 8; ++i) { const int kk = 8 * i + (lane >> 3), c4 = (lane & 7) * 4;
;             const f32x4 w4 = __builtin_nontemporal_load((const f32x4*)(W + (size_t)(k0 + kk) * N + n0 + c4)); LAS float* d = scr + kk * 33 + c4; d[0] = w4[0]; d[1] = w4[1]; d[2] = w4[2]; d[3] = w4[3]; }
;         LDS_WAIT(); asm volatile("" ::: "memory");
.LBB0_1663:
	s_andn2_saveexec_b64 s[84:85], s[92:93]
	s_cbranch_execz .LBB0_1665
	v_readlane_b32 s12, v252, 14
	v_readlane_b32 s13, v252, 15
	s_load_dwordx2 s[12:13], s[12:13], 0x80
	s_mul_i32 s16, s20, 0x2c00000
	v_add_u32_e32 v1, 0xd400, v0
	v_lshlrev_b32_e32 v0, 5, v0
	v_mov_b32_e32 v22, v220
	s_waitcnt lgkmcnt(0)
	s_add_u32 s16, s12, s16
	s_mul_hi_i32 s12, s20, 0x2c00000
	s_addc_u32 s17, s13, s12
	v_readlane_b32 s12, v252, 12
	v_readlane_b32 s13, v252, 13
	v_and_b32_e32 v2, 0x7e0, v0
	v_and_b32_e32 v23, 0xffc0, v1
	v_bfe_u32 v7, v22, 3, 3
	v_lshlrev_b32_e32 v184, 2, v2
	v_lshlrev_b32_e32 v3, 4, v22
	v_lshl_add_u64 v[0:1], s[16:17], 0, v[184:185]
	v_and_b32_e32 v184, 0x70, v3
	v_or_b32_e32 v3, v7, v23
	v_lshl_add_u64 v[0:1], v[0:1], 0, v[184:185]
	v_lshlrev_b32_e32 v12, 13, v3
	v_mov_b32_e32 v13, v185
	v_lshl_add_u64 v[4:5], v[0:1], 0, v[12:13]
	global_load_dwordx4 v[132:135], v[4:5], off nt
	v_mul_u32_u24_e32 v3, 0x84, v7
	v_or_b32_e32 v6, 8, v7
	v_add3_u32 v13, s79, v184, v3
	v_or_b32_e32 v3, v6, v23
	v_lshlrev_b32_e32 v184, 13, v3
	v_lshl_add_u64 v[4:5], v[0:1], 0, v[184:185]
	v_add_u32_e32 v3, 0x420, v13
	s_add_u32 s12, s12, s61
	s_addc_u32 s13, s13, 0
	v_or_b32_e32 v6, v6, v2
	v_mul_u32_u24_e32 v6, 0x1600, v6
	global_load_dwordx4 v[136:139], v[4:5], off nt
	v_or_b32_e32 v4, 16, v7
	v_add_u32_e32 v3, 0x428, v13
	v_or_b32_e32 v3, v4, v23
	v_lshlrev_b32_e32 v184, 13, v3
	v_lshl_add_u64 v[8:9], v[0:1], 0, v[184:185]
	global_load_dwordx4 v[140:143], v[8:9], off nt
	v_add_u32_e32 v3, 0x840, v13
	v_or_b32_e32 v4, v4, v2
	v_mul_u32_u24_e32 v4, 0x1600, v4
	v_add_u32_e32 v3, 0x848, v13
	v_or_b32_e32 v3, 24, v7
	v_or_b32_e32 v5, v3, v23
	v_lshlrev_b32_e32 v184, 13, v5
	v_lshl_add_u64 v[8:9], v[0:1], 0, v[184:185]
	global_load_dwordx4 v[144:147], v[8:9], off nt
	v_add_u32_e32 v5, 0xc60, v13
	v_or_b32_e32 v184, 0x40000, v12
	v_add_u32_e32 v5, 0xc68, v13
	v_lshl_add_u64 v[8:9], v[0:1], 0, v[184:185]
	global_load_dwordx4 v[148:151], v[8:9], off nt
	v_add_u32_e32 v5, 0x1080, v13
	v_or_b32_e32 v184, 0x50000, v12
	v_add_u32_e32 v5, 0x1088, v13
	v_lshl_add_u64 v[8:9], v[0:1], 0, v[184:185]
	global_load_dwordx4 v[152:155], v[8:9], off nt
	v_add_u32_e32 v5, 0x14a0, v13
	v_or_b32_e32 v184, 0x60000, v12
	v_add_u32_e32 v5, 0x14a8, v13
	v_lshl_add_u64 v[8:9], v[0:1], 0, v[184:185]
	global_load_dwordx4 v[156:159], v[8:9], off nt
	v_add_u32_e32 v5, 0x18c0, v13
	v_or_b32_e32 v184, 0x70000, v12
	v_lshl_add_u64 v[0:1], v[0:1], 0, v[184:185]
	v_lshlrev_b32_e32 v184, 1, v23
	v_add_u32_e32 v5, 0x18c8, v13
	global_load_dwordx4 v[160:163], v[0:1], off nt
	v_add_u32_e32 v0, 0x1ce0, v13
	v_and_b32_e32 v5, 7, v22
	v_add_u32_e32 v0, 0x1ce8, v13
	s_waitcnt vmcnt(0)
	v_add_u32_e32 v164, 0x0, v13
	ds_write2_b32 v164, v132, v133 offset1:1
	ds_write2_b32 v164, v134, v135 offset0:2 offset1:3
	v_add_u32_e32 v164, 0x420, v13
	ds_write2_b32 v164, v136, v137 offset1:1
	ds_write2_b32 v164, v138, v139 offset0:2 offset1:3
	v_add_u32_e32 v164, 0x840, v13
	ds_write2_b32 v164, v140, v141 offset1:1
	ds_write2_b32 v164, v142, v143 offset0:2 offset1:3
	v_add_u32_e32 v164, 0xc60, v13
	ds_write2_b32 v164, v144, v145 offset1:1
	ds_write2_b32 v164, v146, v147 offset0:2 offset1:3
	v_add_u32_e32 v164, 0x1080, v13
	ds_write2_b32 v164, v148, v149 offset1:1
	ds_write2_b32 v164, v150, v151 offset0:2 offset1:3
	v_add_u32_e32 v164, 0x14a0, v13
	ds_write2_b32 v164, v152, v153 offset1:1
	ds_write2_b32 v164, v154, v155 offset0:2 offset1:3
	v_add_u32_e32 v164, 0x18c0, v13
	ds_write2_b32 v164, v156, v157 offset1:1
	ds_write2_b32 v164, v158, v159 offset0:2 offset1:3
	v_add_u32_e32 v164, 0x1ce0, v13
	ds_write2_b32 v164, v160, v161 offset1:1
	ds_write2_b32 v164, v162, v163 offset0:2 offset1:3
	s_waitcnt lgkmcnt(0)
	v_mul_u32_u24_e32 v8, 0x420, v5
	v_lshl_add_u64 v[0:1], s[12:13], 0, v[184:185]
	v_lshlrev_b32_e32 v184, 4, v5
	v_lshlrev_b32_e32 v5, 2, v7
	v_add3_u32 v5, s79, v8, v5
	ds_read_b32 v8, v5
	ds_read_b32 v9, v5 offset:132
	v_or_b32_e32 v7, v7, v2
	v_lshl_add_u64 v[0:1], v[0:1], 0, v[184:185]
	s_mov_b64 s[12:13], 0x5c00000
	s_waitcnt lgkmcnt(1)
	v_bfe_u32 v10, v8, 16, 1
	v_add3_u32 v8, v8, v10, s73
	s_waitcnt lgkmcnt(0)
	v_bfe_u32 v10, v9, 16, 1
	v_lshrrev_b32_e32 v8, 16, v8
	v_add3_u32 v9, v9, v10, s73
	v_and_or_b32 v8, v9, s72, v8
	ds_read_b32 v9, v5 offset:264
	ds_read_b32 v10, v5 offset:396
	v_mul_u32_u24_e32 v7, 0x1600, v7
	v_lshl_add_u64 v[0:1], v[0:1], 0, s[12:13]
	v_lshlrev_b32_e32 v184, 1, v7
	s_waitcnt lgkmcnt(1)
; #define LAS __attribute__((address_space(3)))
; #define LDS_WAIT() asm volatile("s_waitcnt lgkmcnt(0)" ::: "memory")
; __device__ __forceinline__ unsigned f2bf(float f) { unsigned u = __builtin_bit_cast(unsigned, f); return (u + 0x7fffu + ((u >> 16) & 1u)) >> 16; }
; __device__ __forceinline__ float bf_round(float f) { return __uint_as_float(f2bf(f) << 16); }
; __device__ __forceinline__ unsigned pk2(float lo, float hi) { return f2bf(lo) | (f2bf(hi) << 16); }
; template <class Map>
; __device__ __forceinline__ void conv_item(const Frame& F, int it, const float* W, int K, int N, bf16_t* WT, const float* gk, int gmask, float gmul, const float* bk, i64* cs, i64* bw, Map map) {
;     ...
;         for (int j = 0; j < 4; ++j) { const int n = (lane >> 3) + 8 * j; const LAS float* s = scr + (8 * c) * 33 + n;
;             u32x4 o; o.x = pk2(s[0 * 33] * gl[0], s[1 * 33] * gl[1]); o.y = pk2(s[2 * 33] * gl[2], s[3 * 33] * gl[3]); o.z = pk2(s[4 * 33] * gl[4], s[5 * 33] * gl[5]); o.w = pk2(s[6 * 33] * gl[6], s[7 * 33] * gl[7]);
;             __builtin_nontemporal_store(o, (u32x4*)(WT + (size_t)(v0 + n) * K + k0 + 8 * c)); }
;         LDS_WAIT(); asm volatile("" ::: "memory");
	v_bfe_u32 v11, v9, 16, 1
	v_add3_u32 v9, v9, v11, s73
	s_waitcnt lgkmcnt(0)
	v_bfe_u32 v11, v10, 16, 1
	v_lshrrev_b32_e32 v9, 16, v9
	v_add3_u32 v10, v10, v11, s73
	v_and_or_b32 v9, v10, s72, v9
	ds_read_b32 v10, v5 offset:528
	ds_read_b32 v11, v5 offset:660
	v_or_b32_e32 v2, v3, v2
	v_mul_u32_u24_e32 v2, 0x1600, v2
	s_waitcnt lgkmcnt(1)
	v_bfe_u32 v12, v10, 16, 1
	v_add3_u32 v10, v10, v12, s73
	s_waitcnt lgkmcnt(0)
	v_bfe_u32 v12, v11, 16, 1
	v_lshrrev_b32_e32 v10, 16, v10
	v_add3_u32 v11, v11, v12, s73
	v_and_or_b32 v10, v11, s72, v10
	ds_read_b32 v11, v5 offset:792
	ds_read_b32 v12, v5 offset:924
	s_waitcnt lgkmcnt(1)
	v_bfe_u32 v13, v11, 16, 1
	v_add3_u32 v11, v11, v13, s73
	s_waitcnt lgkmcnt(0)
	v_bfe_u32 v13, v12, 16, 1
	v_lshrrev_b32_e32 v11, 16, v11
	v_add3_u32 v12, v12, v13, s73
	v_and_or_b32 v11, v12, s72, v11
	v_lshl_add_u64 v[12:13], v[0:1], 0, v[184:185]
	flat_store_dwordx4 v[12:13], v[8:11] nt
	ds_read_b32 v7, v5 offset:32
	ds_read_b32 v8, v5 offset:164
	v_lshlrev_b32_e32 v184, 1, v6
	s_waitcnt lgkmcnt(0)
	v_bfe_u32 v9, v7, 16, 1
	v_add3_u32 v7, v7, v9, s73
	v_bfe_u32 v9, v8, 16, 1
	v_lshrrev_b32_e32 v7, 16, v7
	v_add3_u32 v8, v8, v9, s73
	v_and_or_b32 v8, v8, s72, v7
	ds_read_b32 v7, v5 offset:296
	ds_read_b32 v9, v5 offset:428
	s_waitcnt lgkmcnt(0)
	v_bfe_u32 v10, v7, 16, 1
	v_add3_u32 v7, v7, v10, s73
	v_bfe_u32 v10, v9, 16, 1
	v_lshrrev_b32_e32 v7, 16, v7
	v_add3_u32 v9, v9, v10, s73
	v_and_or_b32 v9, v9, s72, v7
	ds_read_b32 v7, v5 offset:560
	ds_read_b32 v10, v5 offset:692
	s_waitcnt lgkmcnt(0)
	v_bfe_u32 v11, v7, 16, 1
	v_add3_u32 v7, v7, v11, s73
	v_bfe_u32 v11, v10, 16, 1
	v_lshrrev_b32_e32 v7, 16, v7
	v_add3_u32 v10, v10, v11, s73
	v_and_or_b32 v10, v10, s72, v7
	ds_read_b32 v7, v5 offset:824
	ds_read_b32 v11, v5 offset:956
	s_waitcnt lgkmcnt(0)
	v_bfe_u32 v12, v7, 16, 1
	v_add3_u32 v7, v7, v12, s73
	v_bfe_u32 v12, v11, 16, 1
	v_lshrrev_b32_e32 v7, 16, v7
	v_add3_u32 v11, v11, v12, s73
	v_and_or_b32 v11, v11, s72, v7
	v_lshl_add_u64 v[6:7], v[0:1], 0, v[184:185]
	flat_store_dwordx4 v[6:7], v[8:11] nt
	ds_read_b32 v6, v5 offset:64
	ds_read_b32 v7, v5 offset:196
	v_lshlrev_b32_e32 v184, 1, v4
	s_waitcnt lgkmcnt(0)
	v_bfe_u32 v8, v6, 16, 1
	v_add3_u32 v6, v6, v8, s73
	v_bfe_u32 v8, v7, 16, 1
	v_lshrrev_b32_e32 v6, 16, v6
	v_add3_u32 v7, v7, v8, s73
	v_and_or_b32 v6, v7, s72, v6
	ds_read_b32 v7, v5 offset:328
	ds_read_b32 v8, v5 offset:460
	s_waitcnt lgkmcnt(0)
	v_bfe_u32 v9, v7, 16, 1
	v_add3_u32 v7, v7, v9, s73
	v_bfe_u32 v9, v8, 16, 1
	v_lshrrev_b32_e32 v7, 16, v7
	v_add3_u32 v8, v8, v9, s73
	v_and_or_b32 v7, v8, s72, v7
	ds_read_b32 v8, v5 offset:592
	ds_read_b32 v9, v5 offset:724
	s_waitcnt lgkmcnt(0)
	v_bfe_u32 v10, v8, 16, 1
	v_add3_u32 v8, v8, v10, s73
	v_bfe_u32 v10, v9, 16, 1
	v_lshrrev_b32_e32 v8, 16, v8
	v_add3_u32 v9, v9, v10, s73
	v_and_or_b32 v8, v9, s72, v8
	ds_read_b32 v9, v5 offset:856
	ds_read_b32 v10, v5 offset:988
	s_waitcnt lgkmcnt(0)
	v_bfe_u32 v11, v9, 16, 1
	v_add3_u32 v9, v9, v11, s73
	v_bfe_u32 v11, v10, 16, 1
	v_lshrrev_b32_e32 v9, 16, v9
	v_add3_u32 v10, v10, v11, s73
	v_and_or_b32 v9, v10, s72, v9
	v_lshl_add_u64 v[10:11], v[0:1], 0, v[184:185]
	flat_store_dwordx4 v[10:11], v[6:9] nt
	ds_read_b32 v4, v5 offset:96
	ds_read_b32 v6, v5 offset:228
	v_lshlrev_b32_e32 v184, 1, v2
	v_lshl_add_u64 v[0:1], v[0:1], 0, v[184:185]
	s_waitcnt lgkmcnt(0)
	v_bfe_u32 v7, v4, 16, 1
	v_add3_u32 v4, v4, v7, s73
	v_bfe_u32 v7, v6, 16, 1
	v_lshrrev_b32_e32 v4, 16, v4
	v_add3_u32 v6, v6, v7, s73
	v_and_or_b32 v6, v6, s72, v4
	ds_read_b32 v4, v5 offset:360
	ds_read_b32 v7, v5 offset:492
	s_waitcnt lgkmcnt(0)
	v_bfe_u32 v8, v4, 16, 1
	v_add3_u32 v4, v4, v8, s73
	v_bfe_u32 v8, v7, 16, 1
	v_lshrrev_b32_e32 v4, 16, v4
	v_add3_u32 v7, v7, v8, s73
	v_and_or_b32 v7, v7, s72, v4
	ds_read_b32 v4, v5 offset:624
	ds_read_b32 v8, v5 offset:756
	s_waitcnt lgkmcnt(0)
	v_bfe_u32 v9, v4, 16, 1
	v_add3_u32 v4, v4, v9, s73
	v_bfe_u32 v9, v8, 16, 1
	v_lshrrev_b32_e32 v4, 16, v4
	v_add3_u32 v8, v8, v9, s73
	v_and_or_b32 v8, v8, s72, v4
	ds_read_b32 v4, v5 offset:888
	ds_read_b32 v5, v5 offset:1020
	s_waitcnt lgkmcnt(0)
	v_bfe_u32 v9, v4, 16, 1
	v_add3_u32 v4, v4, v9, s73
	v_bfe_u32 v9, v5, 16, 1
	v_lshrrev_b32_e32 v4, 16, v4
	v_add3_u32 v5, v5, v9, s73
	v_and_or_b32 v9, v5, s72, v4
	flat_store_dwordx4 v[0:1], v[6:9] nt
	s_waitcnt lgkmcnt(0)

; #define LAS __attribute__((address_space(3)))
; #define F_LANE() (tid_of(F.wave) & 63)
; #define LDS_WAIT() asm volatile("s_waitcnt lgkmcnt(0)" ::: "memory")
; template <class Map>
; __device__ __forceinline__ void conv_item(const Frame& F, int it, const float* W, int K, int N, bf16_t* WT, const float* gk, int gmask, float gmul, const float* bk, i64* cs, i64* bw, Map map) {
;     LAS float* scr = (LAS float*)(F.lds + F.wave * 16384);
;     const int lane = F_LANE(), nblk = N / 32;
;     {
;         const int kb = it / nblk, nb = it % nblk, k0 = 64 * kb, n0 = 32 * nb, v0 = map(n0);
; #pragma unroll
;         for (int i = 0; i < 8; ++i) { const int kk = 8 * i + (lane >> 3), c4 = (lane & 7) * 4;
;             const f32x4 w4 = __builtin_nontemporal_load((const f32x4*)(W + (size_t)(k0 + kk) * N + n0 + c4)); LAS float* d = scr + kk * 33 + c4; d[0] = w4[0]; d[1] = w4[1]; d[2] = w4[2]; d[3] = w4[3]; }
;         LDS_WAIT(); asm volatile("" ::: "memory");
;         if (bk) {
;             const int n = lane & 31, kh = lane >> 5; float sb = 0.f, sc = 0.f;
.LBB0_1666:
	s_andn2_saveexec_b64 s[84:85], s[42:43]
	s_cbranch_execz .LBB0_1690
	v_readlane_b32 s42, v252, 14
	v_readlane_b32 s43, v252, 15
	s_mov_b64 s[12:13], s[42:43]
	s_load_dwordx2 s[12:13], s[12:13], 0x78
	s_mul_i32 s16, s20, 0x5800000
	v_readlane_b32 s48, v252, 12
	v_readlane_b32 s49, v252, 13
	s_mov_b64 s[86:87], s[48:49]
	s_waitcnt lgkmcnt(0)
	s_add_u32 s16, s12, s16
	s_mul_hi_i32 s12, s20, 0x5800000
	s_addc_u32 s17, s13, s12
	s_mov_b64 s[12:13], s[42:43]
	s_load_dwordx2 s[96:97], s[12:13], 0x68
	v_readlane_b32 s12, v255, 47
	v_readlane_b32 s13, v255, 48
	s_lshl_b64 s[12:13], s[12:13], 2
	v_mov_b32_e32 v4, 6
	s_waitcnt lgkmcnt(0)
	s_add_u32 s92, s96, s12
	s_addc_u32 s93, s97, s13
	s_mov_b64 s[12:13], s[42:43]
	s_mov_b32 s42, 0xba2f
	v_mul_u32_u24_sdwa v1, v0, s42 dst_sel:DWORD dst_unused:UNUSED_PAD src0_sel:WORD_0 src1_sel:DWORD
	s_movk_i32 s42, 0x160
	v_mul_lo_u16_sdwa v2, v1, s42 dst_sel:DWORD dst_unused:UNUSED_PAD src0_sel:BYTE_3 src1_sel:DWORD
	v_sub_u16_e32 v2, v0, v2
	s_movk_i32 s42, 0xaf
	v_lshlrev_b16_sdwa v26, v4, v1 dst_sel:DWORD dst_unused:UNUSED_PAD src0_sel:DWORD src1_sel:BYTE_3
	v_lshlrev_b16_e32 v1, 5, v2
	v_cmp_lt_u16_e32 vcc, s42, v2
	s_movk_i32 s42, 0xb0
	s_mov_b32 s21, s79
	s_load_dwordx2 s[78:79], s[12:13], 0x70
	s_mov_b64 s[12:13], s[48:49]
	v_mov_b32_e32 v3, v220
	v_add_u16_e32 v4, 0xea00, v1
	v_cmp_gt_u16_e64 s[42:43], s42, v2
	v_lshlrev_b32_e32 v184, 2, v1
	v_bfe_u32 v25, v3, 3, 3
	v_cndmask_b32_e64 v2, v4, v1, s[42:43]
	v_mov_b32_e32 v4, 1
	v_lshlrev_b32_e32 v1, 4, v3
	v_lshlrev_b32_sdwa v10, v4, sext(v2) dst_sel:DWORD dst_unused:UNUSED_PAD src0_sel:DWORD src1_sel:WORD_0
	v_lshl_add_u64 v[4:5], s[16:17], 0, v[184:185]
	v_and_b32_e32 v184, 0x70, v1
	v_or_b32_e32 v1, v25, v26
	v_lshl_add_u64 v[8:9], v[4:5], 0, v[184:185]
	v_mul_u32_u24_e32 v4, 0xb000, v1
	v_mov_b32_e32 v5, v185
	v_lshl_add_u64 v[4:5], v[8:9], 0, v[4:5]
	global_load_dwordx4 v[132:135], v[4:5], off nt
	v_mul_u32_u24_e32 v12, 0x84, v25
	v_add3_u32 v12, s21, v184, v12
	v_or_b32_e32 v24, 8, v25
	v_add_u32_e32 v13, 0x420, v12
	v_or_b32_e32 v23, 16, v25
	v_or_b32_e32 v22, 24, v25
	s_movk_i32 s42, 0x60
	v_cndmask_b32_e32 v11, 0, v228, vcc
	v_and_b32_sdwa v2, sext(v2), s42 dst_sel:DWORD dst_unused:UNUSED_PAD src0_sel:WORD_0 src1_sel:DWORD
	s_waitcnt lgkmcnt(0)
	s_cmp_eq_u64 s[78:79], 0
	v_or_b32_e32 v4, v24, v26
	v_mul_u32_u24_e32 v184, 0xb000, v4
	v_lshl_add_u64 v[4:5], v[8:9], 0, v[184:185]
	global_load_dwordx4 v[136:139], v[4:5], off nt
	v_add_u32_e32 v4, 0x428, v12
	v_or_b32_e32 v4, v23, v26
	v_mul_u32_u24_e32 v184, 0xb000, v4
	v_lshl_add_u64 v[4:5], v[8:9], 0, v[184:185]
	global_load_dwordx4 v[140:143], v[4:5], off nt
	v_add_u32_e32 v13, 0x840, v12
	v_add_u32_e32 v4, 0x848, v12
	v_or_b32_e32 v4, v22, v26
	v_mul_u32_u24_e32 v184, 0xb000, v4
	v_lshl_add_u64 v[4:5], v[8:9], 0, v[184:185]
	global_load_dwordx4 v[144:147], v[4:5], off nt
	v_add_u32_e32 v13, 0xc60, v12
	v_add_u32_e32 v4, 0xc68, v12
	v_or_b32_e32 v4, 32, v1
	v_mul_u32_u24_e32 v184, 0xb000, v4
	v_lshl_add_u64 v[4:5], v[8:9], 0, v[184:185]
	global_load_dwordx4 v[148:151], v[4:5], off nt
	v_add_u32_e32 v13, 0x1080, v12
	v_add_u32_e32 v4, 0x1088, v12
	v_or_b32_e32 v4, 40, v1
	v_mul_u32_u24_e32 v184, 0xb000, v4
	v_lshl_add_u64 v[4:5], v[8:9], 0, v[184:185]
	global_load_dwordx4 v[152:155], v[4:5], off nt
	v_add_u32_e32 v13, 0x14a0, v12
	v_add_u32_e32 v4, 0x14a8, v12
	v_or_b32_e32 v4, 48, v1
	v_mul_u32_u24_e32 v184, 0xb000, v4
	v_lshl_add_u64 v[4:5], v[8:9], 0, v[184:185]
	global_load_dwordx4 v[156:159], v[4:5], off nt
	v_add_u32_e32 v13, 0x18c0, v12
	v_or_b32_e32 v1, 56, v1
	v_mul_u32_u24_e32 v184, 0xb000, v1
	v_add_u32_e32 v1, 0x1ce0, v12
	v_add_u32_e32 v4, 0x18c8, v12
	v_lshl_add_u64 v[4:5], v[8:9], 0, v[184:185]
	global_load_dwordx4 v[160:163], v[4:5], off nt
	v_add_u32_e32 v1, 0x1ce8, v12
	s_waitcnt vmcnt(0)
	v_add_u32_e32 v164, 0x0, v12
	ds_write2_b32 v164, v132, v133 offset1:1
	ds_write2_b32 v164, v134, v135 offset0:2 offset1:3
	v_add_u32_e32 v164, 0x420, v12
	ds_write2_b32 v164, v136, v137 offset1:1
	ds_write2_b32 v164, v138, v139 offset0:2 offset1:3
	v_add_u32_e32 v164, 0x840, v12
	ds_write2_b32 v164, v140, v141 offset1:1
	ds_write2_b32 v164, v142, v143 offset0:2 offset1:3
	v_add_u32_e32 v164, 0xc60, v12
	ds_write2_b32 v164, v144, v145 offset1:1
	ds_write2_b32 v164, v146, v147 offset0:2 offset1:3
	v_add_u32_e32 v164, 0x1080, v12
	ds_write2_b32 v164, v148, v149 offset1:1
	ds_write2_b32 v164, v150, v151 offset0:2 offset1:3
	v_add_u32_e32 v164, 0x14a0, v12
	ds_write2_b32 v164, v152, v153 offset1:1
	ds_write2_b32 v164, v154, v155 offset0:2 offset1:3
	v_add_u32_e32 v164, 0x18c0, v12
	ds_write2_b32 v164, v156, v157 offset1:1
	ds_write2_b32 v164, v158, v159 offset0:2 offset1:3
	v_add_u32_e32 v164, 0x1ce0, v12
	ds_write2_b32 v164, v160, v161 offset1:1
	ds_write2_b32 v164, v162, v163 offset0:2 offset1:3
	s_waitcnt lgkmcnt(0)
	v_and_b32_e32 v1, 0xffffff00, v10
	v_or3_b32 v4, v2, v11, v1
	s_cbranch_scc1 .LBB0_1673
	v_and_b32_e32 v1, 32, v3
	v_readlane_b32 s42, v255, 25
	v_readlane_b32 s43, v255, 26
	s_add_u32 s16, s78, s42
	v_add_u32_e32 v28, v26, v1
	s_mov_b32 s21, 0xba2e8c
	v_lshrrev_b32_e32 v1, 5, v3
	v_bfe_u32 v2, v3, 5, 1
	s_addc_u32 s17, s79, s43
	v_lshlrev_b32_e32 v184, 2, v28
	v_mul_hi_u32_u24_sdwa v0, v0, s21 dst_sel:DWORD dst_unused:UNUSED_PAD src0_sel:WORD_0 src1_sel:DWORD
	v_lshlrev_b32_e32 v8, 7, v2
	v_and_b32_e32 v1, 1, v1
	v_lshl_add_u64 v[6:7], s[16:17], 0, v[184:185]
	v_lshl_or_b32 v184, v0, 8, v8
	v_lshlrev_b16_e32 v0, 6, v0
	v_lshlrev_b16_e32 v1, 5, v1
	v_or_b32_e32 v0, v0, v1
	v_lshl_add_u64 v[8:9], s[16:17], 0, v[184:185]
	s_add_u32 s16, s96, s42
	v_and_b32_e32 v0, 0x7e0, v0
	v_and_b32_e32 v27, 31, v3
	s_addc_u32 s17, s97, s43
	v_lshlrev_b32_e32 v184, 2, v0
	v_mul_u32_u24_e32 v0, 0x1080, v2
	v_lshl_add_u64 v[10:11], s[16:17], 0, v[184:185]
	v_lshl_or_b32 v0, v27, 2, v0
	v_readlane_b32 s16, v255, 17
	v_and_b32_e32 v5, 63, v3
	s_mov_b64 s[42:43], 0
	v_add_u32_e32 v29, s16, v0
	v_mov_b32_e32 v0, 0
	v_mov_b32_e32 v1, v0

; #define LAS __attribute__((address_space(3)))
; __device__ __forceinline__ void atomic_addq(i64* p, float v, float scale) { (void)__hip_atomic_fetch_add((unsigned long long*)p, (unsigned long long)(i64)__builtin_rintf(v * scale), __ATOMIC_RELAXED, __HIP_MEMORY_SCOPE_AGENT); }
; #define LDS_WAIT() asm volatile("s_waitcnt lgkmcnt(0)" ::: "memory")
; __device__ __forceinline__ float bf_round(float f) { return __uint_as_float(f2bf(f) << 16); }
; template <class Map>
; __device__ __forceinline__ void conv_item(const Frame& F, int it, const float* W, int K, int N, bf16_t* WT, const float* gk, int gmask, float gmul, const float* bk, i64* cs, i64* bw, Map map) {
;     ...
;         const int kb = it / nblk, nb = it % nblk, k0 = 64 * kb, n0 = 32 * nb, v0 = map(n0);
; #pragma unroll
;         for (int i = 0; i < 8; ++i) { const int kk = 8 * i + (lane >> 3), c4 = (lane & 7) * 4;
;             const f32x4 w4 = __builtin_nontemporal_load((const f32x4*)(W + (size_t)(k0 + kk) * N + n0 + c4)); LAS float* d = scr + kk * 33 + c4; d[0] = w4[0]; d[1] = w4[1]; d[2] = w4[2]; d[3] = w4[3]; }
;         LDS_WAIT(); asm volatile("" ::: "memory");
;         if (bk) {
;             const int n = lane & 31, kh = lane >> 5; float sb = 0.f, sc = 0.f;
; #pragma unroll 8
;             for (int j = 0; j < 32; ++j) { const int kk = kh * 32 + j; const float w = scr[kk * 33 + n]; sb += bk[k0 + kk] * w; sc += bf_round(gk[(k0 + kk) & gmask] * gmul * w); }
;             { auto r = __builtin_amdgcn_permlane32_swap(__float_as_uint(sb), __float_as_uint(sb), false, false); sb = __uint_as_float(r[0]) + __uint_as_float(r[1]); }
;             { auto r = __builtin_amdgcn_permlane32_swap(__float_as_uint(sc), __float_as_uint(sc), false, false); sc = __uint_as_float(r[0]) + __uint_as_float(r[1]); }
;             if (lane < 32) { atomic_addq(bw + v0 + n, sb, FX_COL); atomic_addq(cs + v0 + n, sc, FX_COL); }
;         }
;         const int c = lane & 7; float gl[8];
; #pragma unroll
;         for (int i = 0; i < 8; ++i) gl[i] = gk ? gk[(k0 + 8 * c + i) & gmask] * gmul : 1.0f;
.LBB0_1709:
	s_or_b64 exec, exec, s[12:13]
	s_and_saveexec_b64 s[12:13], s[18:19]
	s_xor_b64 s[12:13], exec, s[12:13]
	s_cbranch_execz .LBB0_1731
	v_add_u16_e32 v2, 0xfbc0, v21
	v_mul_u32_u24_e32 v1, 0xaaab, v2
	v_lshrrev_b32_e32 v1, 22, v1
	v_mul_lo_u16_e32 v3, 0x60, v1
	v_sub_u16_e32 v3, v2, v3
	v_lshlrev_b16_e32 v2, 5, v3
	v_mul_u32_u24_e32 v4, 0x2aab, v2
	v_lshrrev_b32_e32 v4, 21, v4
	v_readlane_b32 s24, v252, 14
	v_mul_lo_u16_e32 v4, 0xc0, v4
	v_readlane_b32 s25, v252, 15
	v_readlane_b32 s18, v252, 12
	v_mul_lo_u16_e32 v3, 0xab, v3
	v_sub_u16_e32 v4, v2, v4
	s_movk_i32 s21, 0x7f
	s_mov_b64 s[16:17], s[24:25]
	v_readlane_b32 s19, v252, 13
	v_mov_b32_e32 v0, v220
	v_lshrrev_b16_e32 v3, 10, v3
	v_cmp_lt_u16_e32 vcc, s21, v4
	s_and_saveexec_b64 s[26:27], vcc
	s_xor_b64 s[26:27], exec, s[26:27]
	v_lshlrev_b32_e32 v5, 6, v3
	v_and_b32_e32 v5, 0x700, v5
	v_lshlrev_b32_e32 v3, 5, v3
	v_lshl_add_u32 v4, v4, 2, v5
	v_and_b32_e32 v3, 0x60, v3
	s_movk_i32 s21, 0x600
	v_add3_u32 v8, v4, v3, s21
	s_or_saveexec_b64 s[40:41], s[26:27]
	s_load_dwordx2 s[16:17], s[16:17], 0x28
	s_nop 0
	s_load_dwordx2 s[26:27], s[24:25], 0x18
	s_xor_b64 exec, exec, s[40:41]
	v_lshl_or_b32 v8, v3, 7, v4
	s_or_b64 exec, exec, s[40:41]
	v_readlane_b32 s21, v255, 35
	s_waitcnt lgkmcnt(0)
	s_add_u32 s16, s16, s21
	v_readlane_b32 s21, v255, 29
	s_addc_u32 s17, s17, s21
	v_lshlrev_b16_e32 v13, 6, v1
	v_bfe_u32 v12, v0, 3, 3
	v_lshlrev_b32_e32 v184, 2, v2
	v_lshlrev_b32_e32 v1, 4, v0
	v_lshl_add_u64 v[2:3], s[16:17], 0, v[184:185]
	v_and_b32_e32 v184, 0x70, v1
	v_or_b32_e32 v1, v12, v13
	v_lshl_add_u64 v[6:7], v[2:3], 0, v[184:185]
	v_mul_u32_u24_e32 v2, 0x3000, v1
	v_mov_b32_e32 v3, v185
	v_lshl_add_u64 v[2:3], v[6:7], 0, v[2:3]
	global_load_dwordx4 v[132:135], v[2:3], off nt
	v_mul_u32_u24_e32 v9, 0x84, v12
	v_add3_u32 v22, s79, v184, v9
	v_or_b32_e32 v11, 8, v12
	v_add_u32_e32 v9, 0x420, v22
	v_or_b32_e32 v10, 16, v12
	v_add_u32_e32 v23, 0xc60, v22
	s_lshl_b64 s[24:25], s[74:75], 2
	s_add_u32 s24, s26, s24
	s_addc_u32 s25, s27, s25
	s_movk_i32 s16, 0x1c0
	s_cmp_lg_u64 s[26:27], 0
	s_cselect_b64 s[40:41], -1, 0
	s_cmp_eq_u64 s[26:27], 0
	v_or_b32_e32 v2, v11, v13
	v_mul_u32_u24_e32 v184, 0x3000, v2
	v_lshl_add_u64 v[2:3], v[6:7], 0, v[184:185]
	global_load_dwordx4 v[136:139], v[2:3], off nt
	v_add_u32_e32 v2, 0x428, v22
	v_or_b32_e32 v2, v10, v13
	v_mul_u32_u24_e32 v184, 0x3000, v2
	v_lshl_add_u64 v[2:3], v[6:7], 0, v[184:185]
	global_load_dwordx4 v[140:143], v[2:3], off nt
	v_add_u32_e32 v9, 0x840, v22
	v_add_u32_e32 v2, 0x848, v22
	v_or_b32_e32 v9, 24, v12
	v_or_b32_e32 v2, v9, v13
	v_mul_u32_u24_e32 v184, 0x3000, v2
	v_lshl_add_u64 v[2:3], v[6:7], 0, v[184:185]
	global_load_dwordx4 v[144:147], v[2:3], off nt
	v_add_u32_e32 v2, 0xc68, v22
	v_or_b32_e32 v2, 32, v1
	v_mul_u32_u24_e32 v184, 0x3000, v2
	v_lshl_add_u64 v[2:3], v[6:7], 0, v[184:185]
	global_load_dwordx4 v[148:151], v[2:3], off nt
	v_add_u32_e32 v23, 0x1080, v22
	v_add_u32_e32 v2, 0x1088, v22
	v_or_b32_e32 v2, 40, v1
	v_mul_u32_u24_e32 v184, 0x3000, v2
	v_lshl_add_u64 v[2:3], v[6:7], 0, v[184:185]
	global_load_dwordx4 v[152:155], v[2:3], off nt
	v_add_u32_e32 v23, 0x14a0, v22
	v_add_u32_e32 v2, 0x14a8, v22
	v_or_b32_e32 v2, 48, v1
	v_mul_u32_u24_e32 v184, 0x3000, v2
	v_lshl_add_u64 v[2:3], v[6:7], 0, v[184:185]
	global_load_dwordx4 v[156:159], v[2:3], off nt
	v_add_u32_e32 v23, 0x18c0, v22
	v_or_b32_e32 v1, 56, v1
	v_mul_u32_u24_e32 v184, 0x3000, v1
	v_add_u32_e32 v1, 0x1ce0, v22
	v_add_u32_e32 v2, 0x18c8, v22
	v_lshl_add_u64 v[2:3], v[6:7], 0, v[184:185]
	global_load_dwordx4 v[160:163], v[2:3], off nt
	v_add_u32_e32 v1, 0x1ce8, v22
	s_waitcnt vmcnt(0)
	v_add_u32_e32 v164, 0x0, v22
	ds_write2_b32 v164, v132, v133 offset1:1
	ds_write2_b32 v164, v134, v135 offset0:2 offset1:3
	v_add_u32_e32 v164, 0x420, v22
	ds_write2_b32 v164, v136, v137 offset1:1
	ds_write2_b32 v164, v138, v139 offset0:2 offset1:3
	v_add_u32_e32 v164, 0x840, v22
	ds_write2_b32 v164, v140, v141 offset1:1
	ds_write2_b32 v164, v142, v143 offset0:2 offset1:3
	v_add_u32_e32 v164, 0xc60, v22
	ds_write2_b32 v164, v144, v145 offset1:1
	ds_write2_b32 v164, v146, v147 offset0:2 offset1:3
	v_add_u32_e32 v164, 0x1080, v22
	ds_write2_b32 v164, v148, v149 offset1:1
	ds_write2_b32 v164, v150, v151 offset0:2 offset1:3
	v_add_u32_e32 v164, 0x14a0, v22
	ds_write2_b32 v164, v152, v153 offset1:1
	ds_write2_b32 v164, v154, v155 offset0:2 offset1:3
	v_add_u32_e32 v164, 0x18c0, v22
	ds_write2_b32 v164, v156, v157 offset1:1
	ds_write2_b32 v164, v158, v159 offset0:2 offset1:3
	v_add_u32_e32 v164, 0x1ce0, v22
	ds_write2_b32 v164, v160, v161 offset1:1
	ds_write2_b32 v164, v162, v163 offset0:2 offset1:3
	s_waitcnt lgkmcnt(0)
	v_and_b32_e32 v22, 7, v0
	v_lshlrev_b32_e32 v23, 3, v22
	v_and_or_b32 v1, v13, s16, v23
	v_mov_b32_e32 v0, 1.0
	v_lshlrev_b32_e32 v24, 2, v1
	v_mov_b32_e32 v2, 1.0
	s_cbranch_scc1 .LBB0_1716
	global_load_dword v2, v24, s[24:25]

; #define LAS __attribute__((address_space(3)))
; #define LDS_WAIT() asm volatile("s_waitcnt lgkmcnt(0)" ::: "memory")
; template <class Map>
; __device__ __forceinline__ void conv_item(const Frame& F, int it, const float* W, int K, int N, bf16_t* WT, const float* gk, int gmask, float gmul, const float* bk, i64* cs, i64* bw, Map map) {
;     ...
;         const int kb = it / nblk, nb = it % nblk, k0 = 64 * kb, n0 = 32 * nb, v0 = map(n0);
; #pragma unroll
;         for (int i = 0; i < 8; ++i) { const int kk = 8 * i + (lane >> 3), c4 = (lane & 7) * 4;
;             const f32x4 w4 = __builtin_nontemporal_load((const f32x4*)(W + (size_t)(k0 + kk) * N + n0 + c4)); LAS float* d = scr + kk * 33 + c4; d[0] = w4[0]; d[1] = w4[1]; d[2] = w4[2]; d[3] = w4[3]; }
;         LDS_WAIT(); asm volatile("" ::: "memory");
.LBB0_1731:
	s_or_b64 exec, exec, s[12:13]
	s_and_saveexec_b64 s[18:19], s[6:7]
	s_cbranch_execz .LBB0_1733
	v_readlane_b32 s6, v252, 14
	v_readlane_b32 s7, v252, 15
	s_load_dwordx2 s[6:7], s[6:7], 0x10
	s_mov_b32 s16, 0xf0f1
	v_mul_u32_u24_sdwa v0, v21, s16 dst_sel:DWORD dst_unused:UNUSED_PAD src0_sel:WORD_0 src1_sel:DWORD
	v_readlane_b32 s12, v255, 39
	v_lshrrev_b32_e32 v0, 21, v0
	s_waitcnt lgkmcnt(0)
	s_add_u32 s12, s6, s12
	v_readlane_b32 s6, v255, 41
	v_mul_lo_u16_e32 v1, 34, v0
	s_addc_u32 s13, s7, s6
	v_readlane_b32 s6, v252, 12
	v_sub_u16_e32 v21, v21, v1
	v_readlane_b32 s7, v252, 13
	v_mov_b32_e32 v6, v220
	v_lshlrev_b16_e32 v23, 5, v21
	v_lshlrev_b16_e32 v22, 6, v0
	v_bfe_u32 v7, v6, 3, 3
	v_lshlrev_b32_e32 v184, 2, v23
	v_lshlrev_b32_e32 v2, 4, v6
	v_lshl_add_u64 v[0:1], s[12:13], 0, v[184:185]
	v_and_b32_e32 v184, 0x70, v2
	v_or_b32_e32 v25, v7, v22
	v_lshl_add_u64 v[12:13], v[0:1], 0, v[184:185]
	v_mul_u32_u24_e32 v0, 0x1100, v25
	v_mov_b32_e32 v1, v185
	v_lshl_add_u64 v[0:1], v[12:13], 0, v[0:1]
	global_load_dwordx4 v[132:135], v[0:1], off nt
	v_mul_u32_u24_e32 v4, 0x84, v7
	v_add3_u32 v26, s79, v184, v4
	v_or_b32_e32 v5, 8, v7
	v_add_u32_e32 v4, 0x420, v26
	v_add_u32_e32 v8, 0x840, v26
	v_add_u32_e32 v24, 0x60, v23
	v_cmp_gt_u16_e32 vcc, 33, v21
	v_or_b32_e32 v0, v5, v22
	v_mul_u32_u24_e32 v184, 0x1100, v0
	v_lshl_add_u64 v[0:1], v[12:13], 0, v[184:185]
	global_load_dwordx4 v[136:139], v[0:1], off nt
	v_add_u32_e32 v0, 0x428, v26
	v_or_b32_e32 v4, 16, v7
	v_or_b32_e32 v0, v4, v22
	v_mul_u32_u24_e32 v184, 0x1100, v0
	v_lshl_add_u64 v[0:1], v[12:13], 0, v[184:185]
	global_load_dwordx4 v[140:143], v[0:1], off nt
	v_add_u32_e32 v0, 0x848, v26
	v_or_b32_e32 v2, 24, v7
	v_or_b32_e32 v0, v2, v22
	v_mul_u32_u24_e32 v184, 0x1100, v0
	v_lshl_add_u64 v[0:1], v[12:13], 0, v[184:185]
	global_load_dwordx4 v[144:147], v[0:1], off nt
	v_add_u32_e32 v0, 0xc60, v26
	v_cndmask_b32_e32 v3, v24, v23, vcc
	v_or_b32_e32 v5, v5, v3
	v_or_b32_e32 v4, v4, v3
	v_or_b32_e32 v2, v2, v3
	v_add_u32_e32 v0, 0xc68, v26
	v_or_b32_e32 v0, 32, v25
	v_mul_u32_u24_e32 v184, 0x1100, v0
	v_lshl_add_u64 v[0:1], v[12:13], 0, v[184:185]
	global_load_dwordx4 v[148:151], v[0:1], off nt
	v_add_u32_e32 v0, 0x1080, v26
	v_add_u32_e32 v0, 0x1088, v26
	v_or_b32_e32 v0, 40, v25
	v_mul_u32_u24_e32 v184, 0x1100, v0
	v_lshl_add_u64 v[0:1], v[12:13], 0, v[184:185]
	global_load_dwordx4 v[152:155], v[0:1], off nt
	v_add_u32_e32 v0, 0x14a0, v26
	v_add_u32_e32 v0, 0x14a8, v26
	v_or_b32_e32 v0, 48, v25
	v_mul_u32_u24_e32 v184, 0x1100, v0
	v_lshl_add_u64 v[0:1], v[12:13], 0, v[184:185]
	global_load_dwordx4 v[156:159], v[0:1], off nt
	v_add_u32_e32 v0, 0x18c0, v26
	v_add_u32_e32 v0, 0x18c8, v26
	v_or_b32_e32 v0, 56, v25
	v_mul_u32_u24_e32 v184, 0x1100, v0
	v_lshl_add_u64 v[0:1], v[12:13], 0, v[184:185]
	global_load_dwordx4 v[160:163], v[0:1], off nt
	v_add_u32_e32 v0, 0x1ce0, v26
	v_lshlrev_b32_e32 v184, 1, v22
	v_add_u32_e32 v0, 0x1ce8, v26
	s_waitcnt vmcnt(0)
	v_add_u32_e32 v164, 0x0, v26
	ds_write2_b32 v164, v132, v133 offset1:1
	ds_write2_b32 v164, v134, v135 offset0:2 offset1:3
	v_add_u32_e32 v164, 0x420, v26
	ds_write2_b32 v164, v136, v137 offset1:1
	ds_write2_b32 v164, v138, v139 offset0:2 offset1:3
	v_add_u32_e32 v164, 0x840, v26
	ds_write2_b32 v164, v140, v141 offset1:1
	ds_write2_b32 v164, v142, v143 offset0:2 offset1:3
	v_add_u32_e32 v164, 0xc60, v26
	ds_write2_b32 v164, v144, v145 offset1:1
	ds_write2_b32 v164, v146, v147 offset0:2 offset1:3
	v_add_u32_e32 v164, 0x1080, v26
	ds_write2_b32 v164, v148, v149 offset1:1
	ds_write2_b32 v164, v150, v151 offset0:2 offset1:3
	v_add_u32_e32 v164, 0x14a0, v26
	ds_write2_b32 v164, v152, v153 offset1:1
	ds_write2_b32 v164, v154, v155 offset0:2 offset1:3
	v_add_u32_e32 v164, 0x18c0, v26
	ds_write2_b32 v164, v156, v157 offset1:1
	ds_write2_b32 v164, v158, v159 offset0:2 offset1:3
	v_add_u32_e32 v164, 0x1ce0, v26
	ds_write2_b32 v164, v160, v161 offset1:1
	ds_write2_b32 v164, v162, v163 offset0:2 offset1:3
	v_lshlrev_b32_e32 v0, 3, v6
	v_and_b32_e32 v6, 56, v0
	s_waitcnt lgkmcnt(0)
	v_mul_u32_u24_e32 v8, 0x84, v6
	v_lshl_add_u64 v[0:1], s[6:7], 0, v[184:185]
	v_lshlrev_b32_e32 v184, 1, v6
	v_lshlrev_b32_e32 v6, 2, v7
	v_add3_u32 v6, s79, v8, v6
	ds_read_b32 v8, v6
	ds_read_b32 v9, v6 offset:132
	v_lshl_add_u64 v[0:1], v[0:1], 0, v[184:185]
	s_mov_b64 s[6:7], 0x800000
	v_or_b32_e32 v7, v7, v3
	s_waitcnt lgkmcnt(1)
	v_bfe_u32 v10, v8, 16, 1
	v_add3_u32 v8, v8, v10, s73
	s_waitcnt lgkmcnt(0)
; #define LAS __attribute__((address_space(3)))
; #define LDS_WAIT() asm volatile("s_waitcnt lgkmcnt(0)" ::: "memory")
; __device__ __forceinline__ unsigned f2bf(float f) { unsigned u = __builtin_bit_cast(unsigned, f); return (u + 0x7fffu + ((u >> 16) & 1u)) >> 16; }
; __device__ __forceinline__ float bf_round(float f) { return __uint_as_float(f2bf(f) << 16); }
; __device__ __forceinline__ unsigned pk2(float lo, float hi) { return f2bf(lo) | (f2bf(hi) << 16); }
; template <class Map>
; __device__ __forceinline__ void conv_item(const Frame& F, int it, const float* W, int K, int N, bf16_t* WT, const float* gk, int gmask, float gmul, const float* bk, i64* cs, i64* bw, Map map) {
;     ...
;         for (int j = 0; j < 4; ++j) { const int n = (lane >> 3) + 8 * j; const LAS float* s = scr + (8 * c) * 33 + n;
;             u32x4 o; o.x = pk2(s[0 * 33] * gl[0], s[1 * 33] * gl[1]); o.y = pk2(s[2 * 33] * gl[2], s[3 * 33] * gl[3]); o.z = pk2(s[4 * 33] * gl[4], s[5 * 33] * gl[5]); o.w = pk2(s[6 * 33] * gl[6], s[7 * 33] * gl[7]);
;             __builtin_nontemporal_store(o, (u32x4*)(WT + (size_t)(v0 + n) * K + k0 + 8 * c)); }
;         LDS_WAIT(); asm volatile("" ::: "memory");
	v_bfe_u32 v10, v9, 16, 1
	v_lshrrev_b32_e32 v8, 16, v8
	v_add3_u32 v9, v9, v10, s73
	v_and_or_b32 v8, v9, s72, v8
	ds_read_b32 v9, v6 offset:264
	ds_read_b32 v10, v6 offset:396
	v_lshl_add_u64 v[0:1], v[0:1], 0, s[6:7]
	v_lshlrev_b32_e32 v184, 12, v7
	s_waitcnt lgkmcnt(1)
	v_bfe_u32 v11, v9, 16, 1
	v_add3_u32 v9, v9, v11, s73
	s_waitcnt lgkmcnt(0)
	v_bfe_u32 v11, v10, 16, 1
	v_lshrrev_b32_e32 v9, 16, v9
	v_add3_u32 v10, v10, v11, s73
	v_and_or_b32 v9, v10, s72, v9
	ds_read_b32 v10, v6 offset:528
	ds_read_b32 v11, v6 offset:660
	s_waitcnt lgkmcnt(1)
	v_bfe_u32 v12, v10, 16, 1
	v_add3_u32 v10, v10, v12, s73
	s_waitcnt lgkmcnt(0)
	v_bfe_u32 v12, v11, 16, 1
	v_lshrrev_b32_e32 v10, 16, v10
	v_add3_u32 v11, v11, v12, s73
	v_and_or_b32 v10, v11, s72, v10
	ds_read_b32 v11, v6 offset:792
	ds_read_b32 v12, v6 offset:924
	s_waitcnt lgkmcnt(1)
	v_bfe_u32 v13, v11, 16, 1
	v_add3_u32 v11, v11, v13, s73
	s_waitcnt lgkmcnt(0)
	v_bfe_u32 v13, v12, 16, 1
	v_lshrrev_b32_e32 v11, 16, v11
	v_add3_u32 v12, v12, v13, s73
	v_and_or_b32 v11, v12, s72, v11
	v_lshl_add_u64 v[12:13], v[0:1], 0, v[184:185]
	flat_store_dwordx4 v[12:13], v[8:11] nt
	ds_read_b32 v7, v6 offset:32
	ds_read_b32 v8, v6 offset:164
	v_lshlrev_b32_e32 v184, 12, v5
	s_waitcnt lgkmcnt(0)
	v_bfe_u32 v9, v7, 16, 1
	v_add3_u32 v7, v7, v9, s73
	v_bfe_u32 v9, v8, 16, 1
	v_lshrrev_b32_e32 v7, 16, v7
	v_add3_u32 v8, v8, v9, s73
	v_and_or_b32 v8, v8, s72, v7
	ds_read_b32 v7, v6 offset:296
	ds_read_b32 v9, v6 offset:428
	s_waitcnt lgkmcnt(0)
	v_bfe_u32 v10, v7, 16, 1
	v_add3_u32 v7, v7, v10, s73
	v_bfe_u32 v10, v9, 16, 1
	v_lshrrev_b32_e32 v7, 16, v7
	v_add3_u32 v9, v9, v10, s73
	v_and_or_b32 v9, v9, s72, v7
	ds_read_b32 v7, v6 offset:560
	ds_read_b32 v10, v6 offset:692
	s_waitcnt lgkmcnt(0)
	v_bfe_u32 v11, v7, 16, 1
	v_add3_u32 v7, v7, v11, s73
	v_bfe_u32 v11, v10, 16, 1
	v_lshrrev_b32_e32 v7, 16, v7
	v_add3_u32 v10, v10, v11, s73
	v_and_or_b32 v10, v10, s72, v7
	ds_read_b32 v7, v6 offset:824
	ds_read_b32 v11, v6 offset:956
	s_waitcnt lgkmcnt(0)
	v_bfe_u32 v12, v7, 16, 1
	v_add3_u32 v7, v7, v12, s73
	v_bfe_u32 v12, v11, 16, 1
	v_lshrrev_b32_e32 v7, 16, v7
	v_add3_u32 v11, v11, v12, s73
	v_and_or_b32 v11, v11, s72, v7
	v_lshl_add_u64 v[12:13], v[0:1], 0, v[184:185]
	flat_store_dwordx4 v[12:13], v[8:11] nt
	ds_read_b32 v5, v6 offset:64
	ds_read_b32 v7, v6 offset:196
	v_lshlrev_b32_e32 v184, 12, v4
	s_waitcnt lgkmcnt(0)
	v_bfe_u32 v8, v5, 16, 1
	v_add3_u32 v5, v5, v8, s73
	v_bfe_u32 v8, v7, 16, 1
	v_lshrrev_b32_e32 v5, 16, v5
	v_add3_u32 v7, v7, v8, s73
	v_and_or_b32 v8, v7, s72, v5
	ds_read_b32 v5, v6 offset:328
	ds_read_b32 v7, v6 offset:460
	s_waitcnt lgkmcnt(0)
	v_bfe_u32 v9, v5, 16, 1
	v_add3_u32 v5, v5, v9, s73
	v_bfe_u32 v9, v7, 16, 1
	v_lshrrev_b32_e32 v5, 16, v5
	v_add3_u32 v7, v7, v9, s73
	v_and_or_b32 v9, v7, s72, v5
	ds_read_b32 v5, v6 offset:592
	ds_read_b32 v7, v6 offset:724
	s_waitcnt lgkmcnt(0)
	v_bfe_u32 v10, v5, 16, 1
	v_add3_u32 v5, v5, v10, s73
	v_bfe_u32 v10, v7, 16, 1
	v_lshrrev_b32_e32 v5, 16, v5
	v_add3_u32 v7, v7, v10, s73
	v_and_or_b32 v10, v7, s72, v5
	ds_read_b32 v5, v6 offset:856
	ds_read_b32 v7, v6 offset:988
	s_waitcnt lgkmcnt(0)
	v_bfe_u32 v11, v5, 16, 1
	v_add3_u32 v5, v5, v11, s73
	v_bfe_u32 v11, v7, 16, 1
	v_lshrrev_b32_e32 v5, 16, v5
	v_add3_u32 v7, v7, v11, s73
	v_and_or_b32 v11, v7, s72, v5
	v_lshl_add_u64 v[4:5], v[0:1], 0, v[184:185]
	flat_store_dwordx4 v[4:5], v[8:11] nt
	ds_read_b32 v4, v6 offset:96
	ds_read_b32 v5, v6 offset:228
	v_lshlrev_b32_e32 v184, 12, v2
	v_lshl_add_u64 v[0:1], v[0:1], 0, v[184:185]
	s_waitcnt lgkmcnt(0)
	v_bfe_u32 v7, v4, 16, 1
	v_add3_u32 v4, v4, v7, s73
	v_bfe_u32 v7, v5, 16, 1
	v_lshrrev_b32_e32 v4, 16, v4
	v_add3_u32 v5, v5, v7, s73
	v_and_or_b32 v8, v5, s72, v4
	ds_read_b32 v4, v6 offset:360
	ds_read_b32 v5, v6 offset:492
	s_waitcnt lgkmcnt(0)
	v_bfe_u32 v7, v4, 16, 1
	v_add3_u32 v4, v4, v7, s73
	v_bfe_u32 v7, v5, 16, 1
	v_lshrrev_b32_e32 v4, 16, v4
	v_add3_u32 v5, v5, v7, s73
	v_and_or_b32 v9, v5, s72, v4
	ds_read_b32 v4, v6 offset:624
	ds_read_b32 v5, v6 offset:756
	s_waitcnt lgkmcnt(0)
	v_bfe_u32 v7, v4, 16, 1
	v_add3_u32 v4, v4, v7, s73
	v_bfe_u32 v7, v5, 16, 1
	v_lshrrev_b32_e32 v4, 16, v4
	v_add3_u32 v5, v5, v7, s73
	v_and_or_b32 v10, v5, s72, v4
	ds_read_b32 v4, v6 offset:888
	ds_read_b32 v5, v6 offset:1020
	s_waitcnt lgkmcnt(0)
	v_bfe_u32 v6, v4, 16, 1
	v_add3_u32 v4, v4, v6, s73
	v_bfe_u32 v6, v5, 16, 1
	v_lshrrev_b32_e32 v4, 16, v4
	v_add3_u32 v5, v5, v6, s73
	v_and_or_b32 v11, v5, s72, v4
	flat_store_dwordx4 v[0:1], v[8:11] nt
	s_waitcnt lgkmcnt(0)

; #define LAS __attribute__((address_space(3)))
; __device__ __forceinline__ void atomic_addq(i64* p, float v, float scale) { (void)__hip_atomic_fetch_add((unsigned long long*)p, (unsigned long long)(i64)__builtin_rintf(v * scale), __ATOMIC_RELAXED, __HIP_MEMORY_SCOPE_AGENT); }
; #define F_LANE() (tid_of(F.wave) & 63)
; #define LDS_WAIT() asm volatile("s_waitcnt lgkmcnt(0)" ::: "memory")
; __device__ __forceinline__ float bf_round(float f) { return __uint_as_float(f2bf(f) << 16); }
; template <class Map>
; __device__ __forceinline__ void conv_item(const Frame& F, int it, const float* W, int K, int N, bf16_t* WT, const float* gk, int gmask, float gmul, const float* bk, i64* cs, i64* bw, Map map) {
;     ...
;     const int lane = F_LANE(), nblk = N / 32;
;     {
;         const int kb = it / nblk, nb = it % nblk, k0 = 64 * kb, n0 = 32 * nb, v0 = map(n0);
; #pragma unroll
;         for (int i = 0; i < 8; ++i) { const int kk = 8 * i + (lane >> 3), c4 = (lane & 7) * 4;
;             const f32x4 w4 = __builtin_nontemporal_load((const f32x4*)(W + (size_t)(k0 + kk) * N + n0 + c4)); LAS float* d = scr + kk * 33 + c4; d[0] = w4[0]; d[1] = w4[1]; d[2] = w4[2]; d[3] = w4[3]; }
;         LDS_WAIT(); asm volatile("" ::: "memory");
;         if (bk) {
;             const int n = lane & 31, kh = lane >> 5; float sb = 0.f, sc = 0.f;
; #pragma unroll 8
;             for (int j = 0; j < 32; ++j) { const int kk = kh * 32 + j; const float w = scr[kk * 33 + n]; sb += bk[k0 + kk] * w; sc += bf_round(gk[(k0 + kk) & gmask] * gmul * w); }
;             { auto r = __builtin_amdgcn_permlane32_swap(__float_as_uint(sb), __float_as_uint(sb), false, false); sb = __uint_as_float(r[0]) + __uint_as_float(r[1]); }
;             { auto r = __builtin_amdgcn_permlane32_swap(__float_as_uint(sc), __float_as_uint(sc), false, false); sc = __uint_as_float(r[0]) + __uint_as_float(r[1]); }
;             if (lane < 32) { atomic_addq(bw + v0 + n, sb, FX_COL); atomic_addq(cs + v0 + n, sc, FX_COL); }
;         }
;         const int c = lane & 7; float gl[8];
; #pragma unroll
;         for (int i = 0; i < 8; ++i) gl[i] = gk ? gk[(k0 + 8 * c + i) & gmask] * gmul : 1.0f;
; #pragma unroll
.LBB0_1927:
	s_or_b64 exec, exec, s[4:5]
	s_mov_b64 s[4:5], -1
	s_mov_b64 s[6:7], 0
	s_and_b64 vcc, exec, s[42:43]
	s_mov_b64 s[24:25], 0
	s_cbranch_vccz .LBB0_1951
	s_movk_i32 s4, 0x17ff
	v_cmp_lt_u32_e32 vcc, s4, v232
	s_and_saveexec_b64 s[4:5], vcc
	s_xor_b64 s[4:5], exec, s[4:5]
	s_cbranch_execz .LBB0_1948
	s_movk_i32 s8, 0x2000
	v_cmp_gt_u32_e32 vcc, s8, v232
	s_mov_b64 s[10:11], -1
	s_and_saveexec_b64 s[8:9], vcc
	s_cbranch_execz .LBB0_1947
	v_readlane_b32 s12, v252, 14
	v_readlane_b32 s13, v252, 15
	s_mov_b64 s[10:11], s[12:13]
	s_load_dwordx2 s[10:11], s[10:11], 0x58
	v_add_u32_e32 v0, 0xe800, v232
	v_and_b32_e32 v13, 0xffc0, v0
	v_lshlrev_b32_e32 v0, 5, v232
	v_mov_b32_e32 v16, v220
	s_waitcnt lgkmcnt(0)
	s_add_u32 s16, s10, s44
	s_addc_u32 s17, s11, s45
	v_readlane_b32 s10, v252, 12
	v_readlane_b32 s11, v252, 13
	v_and_b32_e32 v8, 0x7e0, v0
	s_load_dwordx2 s[18:19], s[12:13], 0x50
	v_lshlrev_b32_e32 v184, 2, v8
	v_lshlrev_b32_e32 v2, 4, v16
	v_bfe_u32 v12, v16, 3, 3
	v_lshl_add_u64 v[0:1], s[16:17], 0, v[184:185]
	v_and_b32_e32 v184, 0x70, v2
	v_lshl_add_u64 v[4:5], v[0:1], 0, v[184:185]
	v_or_b32_e32 v0, v12, v13
	v_lshlrev_b32_e32 v6, 13, v0
	v_mov_b32_e32 v7, v185
	v_lshl_add_u64 v[0:1], v[4:5], 0, v[6:7]
	global_load_dwordx4 v[132:135], v[0:1], off nt
	v_mul_u32_u24_e32 v7, 0x84, v12
	v_readlane_b32 s16, v255, 17
	v_or_b32_e32 v11, 8, v12
	v_or_b32_e32 v10, 16, v12
	v_add3_u32 v7, s16, v184, v7
	v_add_u32_e32 v9, 0x420, v7
	v_add_u32_e32 v17, 0xc60, v7
	v_and_b32_e32 v16, 7, v16
	s_waitcnt lgkmcnt(0)
	s_add_u32 s12, s18, s78
	s_addc_u32 s13, s19, s79
	s_cmp_lg_u64 s[18:19], 0
	s_cselect_b64 s[24:25], -1, 0
	s_cmp_eq_u64 s[18:19], 0
	v_or_b32_e32 v0, v11, v13
	v_lshlrev_b32_e32 v184, 13, v0
	v_lshl_add_u64 v[0:1], v[4:5], 0, v[184:185]
	global_load_dwordx4 v[136:139], v[0:1], off nt
	v_add_u32_e32 v0, 0x428, v7
	v_or_b32_e32 v0, v10, v13
	v_lshlrev_b32_e32 v184, 13, v0
	v_lshl_add_u64 v[0:1], v[4:5], 0, v[184:185]
	global_load_dwordx4 v[140:143], v[0:1], off nt
	v_add_u32_e32 v9, 0x840, v7
	v_add_u32_e32 v0, 0x848, v7
	v_or_b32_e32 v9, 24, v12
	v_or_b32_e32 v0, v9, v13
	v_lshlrev_b32_e32 v184, 13, v0
	v_lshl_add_u64 v[0:1], v[4:5], 0, v[184:185]
	global_load_dwordx4 v[144:147], v[0:1], off nt
	v_or_b32_e32 v184, 0x40000, v6
	v_add_u32_e32 v0, 0xc68, v7
	v_lshl_add_u64 v[0:1], v[4:5], 0, v[184:185]
	global_load_dwordx4 v[148:151], v[0:1], off nt
	v_add_u32_e32 v17, 0x1080, v7
	v_or_b32_e32 v184, 0x50000, v6
	v_add_u32_e32 v0, 0x1088, v7
	v_lshl_add_u64 v[0:1], v[4:5], 0, v[184:185]
	global_load_dwordx4 v[152:155], v[0:1], off nt
	v_add_u32_e32 v17, 0x14a0, v7
	v_or_b32_e32 v184, 0x60000, v6
	v_add_u32_e32 v0, 0x14a8, v7
	v_lshl_add_u64 v[0:1], v[4:5], 0, v[184:185]
	global_load_dwordx4 v[156:159], v[0:1], off nt
	v_add_u32_e32 v17, 0x18c0, v7
	v_or_b32_e32 v184, 0x70000, v6
	v_add_u32_e32 v0, 0x18c8, v7
	v_lshl_add_u64 v[0:1], v[4:5], 0, v[184:185]
	global_load_dwordx4 v[160:163], v[0:1], off nt
	v_add_u32_e32 v4, 0x1ce0, v7
	v_lshlrev_b32_e32 v17, 3, v16
	v_add_u32_e32 v0, 0x1ce8, v7
	s_waitcnt vmcnt(0)
	v_add_u32_e32 v164, 0x0, v7
	ds_write2_b32 v164, v132, v133 offset1:1
	ds_write2_b32 v164, v134, v135 offset0:2 offset1:3
	v_add_u32_e32 v164, 0x420, v7
	ds_write2_b32 v164, v136, v137 offset1:1
	ds_write2_b32 v164, v138, v139 offset0:2 offset1:3
	v_add_u32_e32 v164, 0x840, v7
	ds_write2_b32 v164, v140, v141 offset1:1
	ds_write2_b32 v164, v142, v143 offset0:2 offset1:3
	v_add_u32_e32 v164, 0xc60, v7
	ds_write2_b32 v164, v144, v145 offset1:1
	ds_write2_b32 v164, v146, v147 offset0:2 offset1:3
	v_add_u32_e32 v164, 0x1080, v7
	ds_write2_b32 v164, v148, v149 offset1:1
	ds_write2_b32 v164, v150, v151 offset0:2 offset1:3
	v_add_u32_e32 v164, 0x14a0, v7
	ds_write2_b32 v164, v152, v153 offset1:1
	ds_write2_b32 v164, v154, v155 offset0:2 offset1:3
	v_add_u32_e32 v164, 0x18c0, v7
	ds_write2_b32 v164, v156, v157 offset1:1
	ds_write2_b32 v164, v158, v159 offset0:2 offset1:3
	v_add_u32_e32 v164, 0x1ce0, v7
	ds_write2_b32 v164, v160, v161 offset1:1
	ds_write2_b32 v164, v162, v163 offset0:2 offset1:3
	s_waitcnt lgkmcnt(0)
	v_or_b32_e32 v1, v17, v13
	v_and_b32_e32 v1, 0xf8, v1
	v_mov_b32_e32 v0, 1.0
	v_lshlrev_b32_e32 v18, 2, v1
	v_mov_b32_e32 v2, 1.0
	s_cbranch_scc1 .LBB0_1932
	global_load_dword v1, v18, s[12:13]
	s_waitcnt vmcnt(0)
	v_mul_f32_e32 v2, v14, v1

; #define LAS __attribute__((address_space(3)))
; #define F_LANE() (tid_of(F.wave) & 63)
; #define LDS_WAIT() asm volatile("s_waitcnt lgkmcnt(0)" ::: "memory")
; template <class Map>
; __device__ __forceinline__ void conv_item(const Frame& F, int it, const float* W, int K, int N, bf16_t* WT, const float* gk, int gmask, float gmul, const float* bk, i64* cs, i64* bw, Map map) {
;     ...
;     const int lane = F_LANE(), nblk = N / 32;
;     {
;         const int kb = it / nblk, nb = it % nblk, k0 = 64 * kb, n0 = 32 * nb, v0 = map(n0);
; #pragma unroll
;         for (int i = 0; i < 8; ++i) { const int kk = 8 * i + (lane >> 3), c4 = (lane & 7) * 4;
;             const f32x4 w4 = __builtin_nontemporal_load((const f32x4*)(W + (size_t)(k0 + kk) * N + n0 + c4)); LAS float* d = scr + kk * 33 + c4; d[0] = w4[0]; d[1] = w4[1]; d[2] = w4[2]; d[3] = w4[3]; }
;         LDS_WAIT(); asm volatile("" ::: "memory");
.LBB0_1948:
	s_andn2_saveexec_b64 s[4:5], s[4:5]
	s_cbranch_execz .LBB0_1950
	v_readlane_b32 s8, v252, 14
	v_readlane_b32 s9, v252, 15
	s_load_dwordx2 s[8:9], s[8:9], 0x40
	s_mov_b32 s12, 0xaaab
	v_mul_u32_u24_sdwa v0, v232, s12 dst_sel:DWORD dst_unused:UNUSED_PAD src0_sel:WORD_0 src1_sel:DWORD
	v_lshrrev_b32_e32 v0, 23, v0
	v_mul_lo_u16_e32 v1, 0xc0, v0
	s_waitcnt lgkmcnt(0)
	s_add_u32 s10, s8, s85
	s_addc_u32 s11, s9, s84
	v_readlane_b32 s8, v252, 12
	v_readlane_b32 s9, v252, 13
	v_mov_b32_e32 v6, v220
	v_sub_u16_e32 v1, v232, v1
	v_lshlrev_b16_e32 v12, 6, v0
	v_lshlrev_b16_e32 v2, 5, v1
	v_bfe_u32 v7, v6, 3, 3
	v_lshlrev_b32_e32 v184, 2, v2
	v_lshlrev_b32_e32 v3, 4, v6
	v_or_b32_e32 v13, v7, v12
	v_lshl_add_u64 v[0:1], s[10:11], 0, v[184:185]
	v_and_b32_e32 v184, 0x70, v3
	v_mul_u32_u24_e32 v3, 0x1800, v13
	v_lshl_add_u64 v[0:1], v[0:1], 0, v[184:185]
	v_lshlrev_b32_e32 v4, 2, v3
	v_mov_b32_e32 v5, v185
	v_lshl_add_u64 v[4:5], v[0:1], 0, v[4:5]
	global_load_dwordx4 v[132:135], v[4:5], off nt
	v_mul_u32_u24_e32 v3, 0x84, v7
	v_readlane_b32 s10, v255, 17
	v_or_b32_e32 v5, 8, v7
	v_or_b32_e32 v4, 16, v7
	v_add3_u32 v16, s10, v184, v3
	v_or_b32_e32 v3, v5, v12
	v_mul_u32_u24_e32 v3, 0x1800, v3
	v_lshlrev_b32_e32 v184, 2, v3
	v_add_u32_e32 v3, 0x420, v16
	v_add_u32_e32 v17, 0xc60, v16
	v_and_b32_e32 v6, 7, v6
	v_or_b32_e32 v5, v5, v2
	v_lshl_add_u64 v[8:9], v[0:1], 0, v[184:185]
	global_load_dwordx4 v[136:139], v[8:9], off nt
	v_add_u32_e32 v3, 0x428, v16
	v_or_b32_e32 v3, v4, v12
	v_mul_u32_u24_e32 v3, 0x1800, v3
	v_lshlrev_b32_e32 v184, 2, v3
	v_lshl_add_u64 v[8:9], v[0:1], 0, v[184:185]
	global_load_dwordx4 v[140:143], v[8:9], off nt
	v_add_u32_e32 v3, 0x840, v16
	v_or_b32_e32 v4, v4, v2
	v_add_u32_e32 v3, 0x848, v16
	v_or_b32_e32 v3, 24, v7
	v_or_b32_e32 v8, v3, v12
	v_mul_u32_u24_e32 v8, 0x1800, v8
	v_lshlrev_b32_e32 v184, 2, v8
	v_lshl_add_u64 v[8:9], v[0:1], 0, v[184:185]
	global_load_dwordx4 v[144:147], v[8:9], off nt
	v_add_u32_e32 v8, 0xc68, v16
	v_or_b32_e32 v8, 32, v13
	v_mul_u32_u24_e32 v8, 0x1800, v8
	v_lshlrev_b32_e32 v184, 2, v8
	v_lshl_add_u64 v[8:9], v[0:1], 0, v[184:185]
	global_load_dwordx4 v[148:151], v[8:9], off nt
	v_add_u32_e32 v17, 0x1080, v16
	v_add_u32_e32 v8, 0x1088, v16
	v_or_b32_e32 v8, 40, v13
	v_mul_u32_u24_e32 v8, 0x1800, v8
	v_lshlrev_b32_e32 v184, 2, v8
	v_lshl_add_u64 v[8:9], v[0:1], 0, v[184:185]
	global_load_dwordx4 v[152:155], v[8:9], off nt
	v_add_u32_e32 v17, 0x14a0, v16
	v_add_u32_e32 v8, 0x14a8, v16
	v_or_b32_e32 v8, 48, v13
	v_mul_u32_u24_e32 v8, 0x1800, v8
	v_lshlrev_b32_e32 v184, 2, v8
	v_lshl_add_u64 v[8:9], v[0:1], 0, v[184:185]
	global_load_dwordx4 v[156:159], v[8:9], off nt
	v_add_u32_e32 v17, 0x18c0, v16
	v_add_u32_e32 v8, 0x18c8, v16
	v_or_b32_e32 v8, 56, v13
	v_mul_u32_u24_e32 v8, 0x1800, v8
	v_lshlrev_b32_e32 v184, 2, v8
	v_lshl_add_u64 v[0:1], v[0:1], 0, v[184:185]
	global_load_dwordx4 v[160:163], v[0:1], off nt
	v_add_u32_e32 v0, 0x1ce0, v16
	v_lshlrev_b32_e32 v184, 1, v12
	v_add_u32_e32 v0, 0x1ce8, v16
	s_waitcnt vmcnt(0)
	v_add_u32_e32 v164, 0x0, v16
	ds_write2_b32 v164, v132, v133 offset1:1
	ds_write2_b32 v164, v134, v135 offset0:2 offset1:3
	v_add_u32_e32 v164, 0x420, v16
	ds_write2_b32 v164, v136, v137 offset1:1
	ds_write2_b32 v164, v138, v139 offset0:2 offset1:3
	v_add_u32_e32 v164, 0x840, v16
	ds_write2_b32 v164, v140, v141 offset1:1
	ds_write2_b32 v164, v142, v143 offset0:2 offset1:3
	v_add_u32_e32 v164, 0xc60, v16
	ds_write2_b32 v164, v144, v145 offset1:1
	ds_write2_b32 v164, v146, v147 offset0:2 offset1:3
	v_add_u32_e32 v164, 0x1080, v16
	ds_write2_b32 v164, v148, v149 offset1:1
	ds_write2_b32 v164, v150, v151 offset0:2 offset1:3
	v_add_u32_e32 v164, 0x14a0, v16
	ds_write2_b32 v164, v152, v153 offset1:1
	ds_write2_b32 v164, v154, v155 offset0:2 offset1:3
	v_add_u32_e32 v164, 0x18c0, v16
	ds_write2_b32 v164, v156, v157 offset1:1
	ds_write2_b32 v164, v158, v159 offset0:2 offset1:3
	v_add_u32_e32 v164, 0x1ce0, v16
	ds_write2_b32 v164, v160, v161 offset1:1
	ds_write2_b32 v164, v162, v163 offset0:2 offset1:3
	s_waitcnt lgkmcnt(0)
	v_mul_u32_u24_e32 v8, 0x420, v6
	v_lshl_add_u64 v[0:1], s[8:9], 0, v[184:185]
	v_lshlrev_b32_e32 v184, 4, v6
	v_lshlrev_b32_e32 v6, 2, v7
	v_add3_u32 v6, s10, v8, v6
	ds_read_b32 v8, v6
	ds_read_b32 v9, v6 offset:132
	v_lshl_add_u64 v[0:1], v[0:1], 0, v[184:185]
	s_mov_b64 s[8:9], 0x39500000
	v_or_b32_e32 v7, v7, v2
	s_waitcnt lgkmcnt(1)
	v_bfe_u32 v10, v8, 16, 1
	v_add3_u32 v8, v8, v10, s73
	s_waitcnt lgkmcnt(0)
; #define LAS __attribute__((address_space(3)))
; #define LDS_WAIT() asm volatile("s_waitcnt lgkmcnt(0)" ::: "memory")
; __device__ __forceinline__ unsigned f2bf(float f) { unsigned u = __builtin_bit_cast(unsigned, f); return (u + 0x7fffu + ((u >> 16) & 1u)) >> 16; }
; __device__ __forceinline__ float bf_round(float f) { return __uint_as_float(f2bf(f) << 16); }
; __device__ __forceinline__ unsigned pk2(float lo, float hi) { return f2bf(lo) | (f2bf(hi) << 16); }
; template <class Map>
; __device__ __forceinline__ void conv_item(const Frame& F, int it, const float* W, int K, int N, bf16_t* WT, const float* gk, int gmask, float gmul, const float* bk, i64* cs, i64* bw, Map map) {
;     ...
;         for (int j = 0; j < 4; ++j) { const int n = (lane >> 3) + 8 * j; const LAS float* s = scr + (8 * c) * 33 + n;
;             u32x4 o; o.x = pk2(s[0 * 33] * gl[0], s[1 * 33] * gl[1]); o.y = pk2(s[2 * 33] * gl[2], s[3 * 33] * gl[3]); o.z = pk2(s[4 * 33] * gl[4], s[5 * 33] * gl[5]); o.w = pk2(s[6 * 33] * gl[6], s[7 * 33] * gl[7]);
;             __builtin_nontemporal_store(o, (u32x4*)(WT + (size_t)(v0 + n) * K + k0 + 8 * c)); }
;         LDS_WAIT(); asm volatile("" ::: "memory");
	v_bfe_u32 v10, v9, 16, 1
	v_lshrrev_b32_e32 v8, 16, v8
	v_add3_u32 v9, v9, v10, s73
	v_and_or_b32 v8, v9, s72, v8
	ds_read_b32 v9, v6 offset:264
	ds_read_b32 v10, v6 offset:396
	v_lshl_add_u64 v[0:1], v[0:1], 0, s[8:9]
	v_lshlrev_b32_e32 v184, 12, v7
	v_or_b32_e32 v2, v3, v2
	s_waitcnt lgkmcnt(1)
	v_bfe_u32 v11, v9, 16, 1
	v_add3_u32 v9, v9, v11, s73
	s_waitcnt lgkmcnt(0)
	v_bfe_u32 v11, v10, 16, 1
	v_lshrrev_b32_e32 v9, 16, v9
	v_add3_u32 v10, v10, v11, s73
	v_and_or_b32 v9, v10, s72, v9
	ds_read_b32 v10, v6 offset:528
	ds_read_b32 v11, v6 offset:660
	s_waitcnt lgkmcnt(1)
	v_bfe_u32 v12, v10, 16, 1
	v_add3_u32 v10, v10, v12, s73
	s_waitcnt lgkmcnt(0)
	v_bfe_u32 v12, v11, 16, 1
	v_lshrrev_b32_e32 v10, 16, v10
	v_add3_u32 v11, v11, v12, s73
	v_and_or_b32 v10, v11, s72, v10
	ds_read_b32 v11, v6 offset:792
	ds_read_b32 v12, v6 offset:924
	s_waitcnt lgkmcnt(1)
	v_bfe_u32 v13, v11, 16, 1
	v_add3_u32 v11, v11, v13, s73
	s_waitcnt lgkmcnt(0)
	v_bfe_u32 v13, v12, 16, 1
	v_lshrrev_b32_e32 v11, 16, v11
	v_add3_u32 v12, v12, v13, s73
	v_and_or_b32 v11, v12, s72, v11
	v_lshl_add_u64 v[12:13], v[0:1], 0, v[184:185]
	flat_store_dwordx4 v[12:13], v[8:11] nt
	ds_read_b32 v7, v6 offset:32
	ds_read_b32 v8, v6 offset:164
	v_lshlrev_b32_e32 v184, 12, v5
	s_waitcnt lgkmcnt(0)
	v_bfe_u32 v9, v7, 16, 1
	v_add3_u32 v7, v7, v9, s73
	v_bfe_u32 v9, v8, 16, 1
	v_lshrrev_b32_e32 v7, 16, v7
	v_add3_u32 v8, v8, v9, s73
	v_and_or_b32 v8, v8, s72, v7
	ds_read_b32 v7, v6 offset:296
	ds_read_b32 v9, v6 offset:428
	s_waitcnt lgkmcnt(0)
	v_bfe_u32 v10, v7, 16, 1
	v_add3_u32 v7, v7, v10, s73
	v_bfe_u32 v10, v9, 16, 1
	v_lshrrev_b32_e32 v7, 16, v7
	v_add3_u32 v9, v9, v10, s73
	v_and_or_b32 v9, v9, s72, v7
	ds_read_b32 v7, v6 offset:560
	ds_read_b32 v10, v6 offset:692
	s_waitcnt lgkmcnt(0)
	v_bfe_u32 v11, v7, 16, 1
	v_add3_u32 v7, v7, v11, s73
	v_bfe_u32 v11, v10, 16, 1
	v_lshrrev_b32_e32 v7, 16, v7
	v_add3_u32 v10, v10, v11, s73
	v_and_or_b32 v10, v10, s72, v7
	ds_read_b32 v7, v6 offset:824
	ds_read_b32 v11, v6 offset:956
	s_waitcnt lgkmcnt(0)
	v_bfe_u32 v12, v7, 16, 1
	v_add3_u32 v7, v7, v12, s73
	v_bfe_u32 v12, v11, 16, 1
	v_lshrrev_b32_e32 v7, 16, v7
	v_add3_u32 v11, v11, v12, s73
	v_and_or_b32 v11, v11, s72, v7
	v_lshl_add_u64 v[12:13], v[0:1], 0, v[184:185]
	flat_store_dwordx4 v[12:13], v[8:11] nt
	ds_read_b32 v5, v6 offset:64
	ds_read_b32 v7, v6 offset:196
	v_lshlrev_b32_e32 v184, 12, v4
	s_waitcnt lgkmcnt(0)
	v_bfe_u32 v8, v5, 16, 1
	v_add3_u32 v5, v5, v8, s73
	v_bfe_u32 v8, v7, 16, 1
	v_lshrrev_b32_e32 v5, 16, v5
	v_add3_u32 v7, v7, v8, s73
	v_and_or_b32 v8, v7, s72, v5
	ds_read_b32 v5, v6 offset:328
	ds_read_b32 v7, v6 offset:460
	s_waitcnt lgkmcnt(0)
	v_bfe_u32 v9, v5, 16, 1
	v_add3_u32 v5, v5, v9, s73
	v_bfe_u32 v9, v7, 16, 1
	v_lshrrev_b32_e32 v5, 16, v5
	v_add3_u32 v7, v7, v9, s73
	v_and_or_b32 v9, v7, s72, v5
	ds_read_b32 v5, v6 offset:592
	ds_read_b32 v7, v6 offset:724
	s_waitcnt lgkmcnt(0)
	v_bfe_u32 v10, v5, 16, 1
	v_add3_u32 v5, v5, v10, s73
	v_bfe_u32 v10, v7, 16, 1
	v_lshrrev_b32_e32 v5, 16, v5
	v_add3_u32 v7, v7, v10, s73
	v_and_or_b32 v10, v7, s72, v5
	ds_read_b32 v5, v6 offset:856
	ds_read_b32 v7, v6 offset:988
	s_waitcnt lgkmcnt(0)
	v_bfe_u32 v11, v5, 16, 1
	v_add3_u32 v5, v5, v11, s73
	v_bfe_u32 v11, v7, 16, 1
	v_lshrrev_b32_e32 v5, 16, v5
	v_add3_u32 v7, v7, v11, s73
	v_and_or_b32 v11, v7, s72, v5
	v_lshl_add_u64 v[4:5], v[0:1], 0, v[184:185]
	flat_store_dwordx4 v[4:5], v[8:11] nt
	ds_read_b32 v4, v6 offset:96
	ds_read_b32 v5, v6 offset:228
	v_lshlrev_b32_e32 v184, 12, v2
	v_lshl_add_u64 v[0:1], v[0:1], 0, v[184:185]
	s_waitcnt lgkmcnt(0)
	v_bfe_u32 v7, v4, 16, 1
	v_add3_u32 v4, v4, v7, s73
	v_bfe_u32 v7, v5, 16, 1
	v_lshrrev_b32_e32 v4, 16, v4
	v_add3_u32 v5, v5, v7, s73
	v_and_or_b32 v8, v5, s72, v4
	ds_read_b32 v4, v6 offset:360
	ds_read_b32 v5, v6 offset:492
	s_waitcnt lgkmcnt(0)
	v_bfe_u32 v7, v4, 16, 1
	v_add3_u32 v4, v4, v7, s73
	v_bfe_u32 v7, v5, 16, 1
	v_lshrrev_b32_e32 v4, 16, v4
	v_add3_u32 v5, v5, v7, s73
	v_and_or_b32 v9, v5, s72, v4
	ds_read_b32 v4, v6 offset:624
	ds_read_b32 v5, v6 offset:756
	s_waitcnt lgkmcnt(0)
	v_bfe_u32 v7, v4, 16, 1
	v_add3_u32 v4, v4, v7, s73
	v_bfe_u32 v7, v5, 16, 1
	v_lshrrev_b32_e32 v4, 16, v4
	v_add3_u32 v5, v5, v7, s73
	v_and_or_b32 v10, v5, s72, v4
	ds_read_b32 v4, v6 offset:888
	ds_read_b32 v5, v6 offset:1020
	s_waitcnt lgkmcnt(0)
	v_bfe_u32 v6, v4, 16, 1
	v_add3_u32 v4, v4, v6, s73
	v_bfe_u32 v6, v5, 16, 1
	v_lshrrev_b32_e32 v4, 16, v4
	v_add3_u32 v5, v5, v6, s73
	v_and_or_b32 v11, v5, s72, v4
	flat_store_dwordx4 v[0:1], v[8:11] nt
	s_waitcnt lgkmcnt(0)

; #define LAS __attribute__((address_space(3)))
; #define F_LANE() (tid_of(F.wave) & 63)
; #define LDS_WAIT() asm volatile("s_waitcnt lgkmcnt(0)" ::: "memory")
; template <class Map>
; __device__ __forceinline__ void conv_item(const Frame& F, int it, const float* W, int K, int N, bf16_t* WT, const float* gk, int gmask, float gmul, const float* bk, i64* cs, i64* bw, Map map) {
;     ...
;     const int lane = F_LANE(), nblk = N / 32;
;     {
;         const int kb = it / nblk, nb = it % nblk, k0 = 64 * kb, n0 = 32 * nb, v0 = map(n0);
; #pragma unroll
;         for (int i = 0; i < 8; ++i) { const int kk = 8 * i + (lane >> 3), c4 = (lane & 7) * 4;
;             const f32x4 w4 = __builtin_nontemporal_load((const f32x4*)(W + (size_t)(k0 + kk) * N + n0 + c4)); LAS float* d = scr + kk * 33 + c4; d[0] = w4[0]; d[1] = w4[1]; d[2] = w4[2]; d[3] = w4[3]; }
;         LDS_WAIT(); asm volatile("" ::: "memory");
.LBB0_1960:
	v_readlane_b32 s12, v252, 14
	v_readlane_b32 s13, v252, 15
	s_load_dwordx2 s[12:13], s[12:13], 0x38
	v_add_u32_e32 v0, 0xf4c0, v232
	v_and_b32_e32 v17, 0xffc0, v0
	v_lshlrev_b32_e32 v0, 5, v232
	v_mov_b32_e32 v16, v220
	s_waitcnt lgkmcnt(0)
	s_add_u32 s16, s12, s44
	s_addc_u32 s17, s13, s45
	v_readlane_b32 s12, v252, 12
	v_readlane_b32 s13, v252, 13
	v_and_b32_e32 v2, 0x7e0, v0
	v_lshlrev_b32_e32 v184, 2, v2
	v_bfe_u32 v7, v16, 3, 3
	v_lshlrev_b32_e32 v3, 4, v16
	v_lshl_add_u64 v[0:1], s[16:17], 0, v[184:185]
	v_and_b32_e32 v184, 0x70, v3
	v_or_b32_e32 v3, v7, v17
	v_lshl_add_u64 v[0:1], v[0:1], 0, v[184:185]
	v_lshlrev_b32_e32 v12, 13, v3
	v_mov_b32_e32 v13, v185
	v_lshl_add_u64 v[4:5], v[0:1], 0, v[12:13]
	global_load_dwordx4 v[132:135], v[4:5], off nt
	v_mul_u32_u24_e32 v3, 0x84, v7
	v_readlane_b32 s16, v255, 17
	v_or_b32_e32 v6, 8, v7
	s_nop 0
	v_add3_u32 v13, s16, v184, v3
	v_or_b32_e32 v3, v6, v17
	v_lshlrev_b32_e32 v184, 13, v3
	v_lshl_add_u64 v[4:5], v[0:1], 0, v[184:185]
	v_add_u32_e32 v3, 0x420, v13
	v_or_b32_e32 v6, v6, v2
	global_load_dwordx4 v[136:139], v[4:5], off nt
	v_or_b32_e32 v4, 16, v7
	v_add_u32_e32 v3, 0x428, v13
	v_or_b32_e32 v3, v4, v17
	v_lshlrev_b32_e32 v184, 13, v3
	v_lshl_add_u64 v[8:9], v[0:1], 0, v[184:185]
	global_load_dwordx4 v[140:143], v[8:9], off nt
	v_add_u32_e32 v3, 0x840, v13
	v_or_b32_e32 v4, v4, v2
	v_add_u32_e32 v3, 0x848, v13
	v_or_b32_e32 v3, 24, v7
	v_or_b32_e32 v5, v3, v17
	v_lshlrev_b32_e32 v184, 13, v5
	v_lshl_add_u64 v[8:9], v[0:1], 0, v[184:185]
	global_load_dwordx4 v[144:147], v[8:9], off nt
	v_add_u32_e32 v5, 0xc60, v13
	v_or_b32_e32 v184, 0x40000, v12
	v_add_u32_e32 v5, 0xc68, v13
	v_lshl_add_u64 v[8:9], v[0:1], 0, v[184:185]
	global_load_dwordx4 v[148:151], v[8:9], off nt
	v_add_u32_e32 v5, 0x1080, v13
	v_or_b32_e32 v184, 0x50000, v12
	v_add_u32_e32 v5, 0x1088, v13
	v_lshl_add_u64 v[8:9], v[0:1], 0, v[184:185]
	global_load_dwordx4 v[152:155], v[8:9], off nt
	v_add_u32_e32 v5, 0x14a0, v13
	v_or_b32_e32 v184, 0x60000, v12
	v_add_u32_e32 v5, 0x14a8, v13
	v_lshl_add_u64 v[8:9], v[0:1], 0, v[184:185]
	global_load_dwordx4 v[156:159], v[8:9], off nt
	v_add_u32_e32 v5, 0x18c0, v13
	v_or_b32_e32 v184, 0x70000, v12
	v_lshl_add_u64 v[0:1], v[0:1], 0, v[184:185]
	v_lshlrev_b32_e32 v184, 1, v17
	v_add_u32_e32 v5, 0x18c8, v13
	global_load_dwordx4 v[160:163], v[0:1], off nt
	v_add_u32_e32 v0, 0x1ce0, v13
	v_and_b32_e32 v5, 7, v16
	v_add_u32_e32 v0, 0x1ce8, v13
	s_waitcnt vmcnt(0)
	v_add_u32_e32 v164, 0x0, v13
	ds_write2_b32 v164, v132, v133 offset1:1
	ds_write2_b32 v164, v134, v135 offset0:2 offset1:3
	v_add_u32_e32 v164, 0x420, v13
	ds_write2_b32 v164, v136, v137 offset1:1
	ds_write2_b32 v164, v138, v139 offset0:2 offset1:3
	v_add_u32_e32 v164, 0x840, v13
	ds_write2_b32 v164, v140, v141 offset1:1
	ds_write2_b32 v164, v142, v143 offset0:2 offset1:3
	v_add_u32_e32 v164, 0xc60, v13
	ds_write2_b32 v164, v144, v145 offset1:1
	ds_write2_b32 v164, v146, v147 offset0:2 offset1:3
	v_add_u32_e32 v164, 0x1080, v13
	ds_write2_b32 v164, v148, v149 offset1:1
	ds_write2_b32 v164, v150, v151 offset0:2 offset1:3
	v_add_u32_e32 v164, 0x14a0, v13
	ds_write2_b32 v164, v152, v153 offset1:1
	ds_write2_b32 v164, v154, v155 offset0:2 offset1:3
	v_add_u32_e32 v164, 0x18c0, v13
	ds_write2_b32 v164, v156, v157 offset1:1
	ds_write2_b32 v164, v158, v159 offset0:2 offset1:3
	v_add_u32_e32 v164, 0x1ce0, v13
	ds_write2_b32 v164, v160, v161 offset1:1
	ds_write2_b32 v164, v162, v163 offset0:2 offset1:3
	s_waitcnt lgkmcnt(0)
	v_mul_u32_u24_e32 v8, 0x420, v5
	v_lshl_add_u64 v[0:1], s[12:13], 0, v[184:185]
	v_lshlrev_b32_e32 v184, 4, v5
	v_lshlrev_b32_e32 v5, 2, v7
	v_add3_u32 v5, s16, v8, v5
	ds_read_b32 v8, v5
	ds_read_b32 v9, v5 offset:132
	v_lshl_add_u64 v[0:1], v[0:1], 0, v[184:185]
	s_mov_b64 s[12:13], 0x2800000
	v_or_b32_e32 v7, v7, v2
	s_waitcnt lgkmcnt(1)
	v_bfe_u32 v10, v8, 16, 1
	v_add3_u32 v8, v8, v10, s73
	s_waitcnt lgkmcnt(0)
	v_bfe_u32 v10, v9, 16, 1
	v_lshrrev_b32_e32 v8, 16, v8
	v_add3_u32 v9, v9, v10, s73
	v_and_or_b32 v8, v9, s72, v8
	ds_read_b32 v9, v5 offset:264
	ds_read_b32 v10, v5 offset:396
	v_lshl_add_u64 v[0:1], v[0:1], 0, s[12:13]
	v_lshlrev_b32_e32 v184, 12, v7
	v_or_b32_e32 v2, v3, v2
	s_waitcnt lgkmcnt(1)
	v_bfe_u32 v11, v9, 16, 1
	v_add3_u32 v9, v9, v11, s73
	s_waitcnt lgkmcnt(0)
; #define LAS __attribute__((address_space(3)))
; #define LDS_WAIT() asm volatile("s_waitcnt lgkmcnt(0)" ::: "memory")
; __device__ __forceinline__ unsigned f2bf(float f) { unsigned u = __builtin_bit_cast(unsigned, f); return (u + 0x7fffu + ((u >> 16) & 1u)) >> 16; }
; __device__ __forceinline__ float bf_round(float f) { return __uint_as_float(f2bf(f) << 16); }
; __device__ __forceinline__ unsigned pk2(float lo, float hi) { return f2bf(lo) | (f2bf(hi) << 16); }
; template <class Map>
; __device__ __forceinline__ void conv_item(const Frame& F, int it, const float* W, int K, int N, bf16_t* WT, const float* gk, int gmask, float gmul, const float* bk, i64* cs, i64* bw, Map map) {
;     ...
;         for (int j = 0; j < 4; ++j) { const int n = (lane >> 3) + 8 * j; const LAS float* s = scr + (8 * c) * 33 + n;
;             u32x4 o; o.x = pk2(s[0 * 33] * gl[0], s[1 * 33] * gl[1]); o.y = pk2(s[2 * 33] * gl[2], s[3 * 33] * gl[3]); o.z = pk2(s[4 * 33] * gl[4], s[5 * 33] * gl[5]); o.w = pk2(s[6 * 33] * gl[6], s[7 * 33] * gl[7]);
;             __builtin_nontemporal_store(o, (u32x4*)(WT + (size_t)(v0 + n) * K + k0 + 8 * c)); }
;         LDS_WAIT(); asm volatile("" ::: "memory");
	v_bfe_u32 v11, v10, 16, 1
	v_lshrrev_b32_e32 v9, 16, v9
	v_add3_u32 v10, v10, v11, s73
	v_and_or_b32 v9, v10, s72, v9
	ds_read_b32 v10, v5 offset:528
	ds_read_b32 v11, v5 offset:660
	s_waitcnt lgkmcnt(1)
	v_bfe_u32 v12, v10, 16, 1
	v_add3_u32 v10, v10, v12, s73
	s_waitcnt lgkmcnt(0)
	v_bfe_u32 v12, v11, 16, 1
	v_lshrrev_b32_e32 v10, 16, v10
	v_add3_u32 v11, v11, v12, s73
	v_and_or_b32 v10, v11, s72, v10
	ds_read_b32 v11, v5 offset:792
	ds_read_b32 v12, v5 offset:924
	s_waitcnt lgkmcnt(1)
	v_bfe_u32 v13, v11, 16, 1
	v_add3_u32 v11, v11, v13, s73
	s_waitcnt lgkmcnt(0)
	v_bfe_u32 v13, v12, 16, 1
	v_lshrrev_b32_e32 v11, 16, v11
	v_add3_u32 v12, v12, v13, s73
	v_and_or_b32 v11, v12, s72, v11
	v_lshl_add_u64 v[12:13], v[0:1], 0, v[184:185]
	flat_store_dwordx4 v[12:13], v[8:11] nt
	ds_read_b32 v7, v5 offset:32
	ds_read_b32 v8, v5 offset:164
	v_lshlrev_b32_e32 v184, 12, v6
	s_waitcnt lgkmcnt(0)
	v_bfe_u32 v9, v7, 16, 1
	v_add3_u32 v7, v7, v9, s73
	v_bfe_u32 v9, v8, 16, 1
	v_lshrrev_b32_e32 v7, 16, v7
	v_add3_u32 v8, v8, v9, s73
	v_and_or_b32 v8, v8, s72, v7
	ds_read_b32 v7, v5 offset:296
	ds_read_b32 v9, v5 offset:428
	s_waitcnt lgkmcnt(0)
	v_bfe_u32 v10, v7, 16, 1
	v_add3_u32 v7, v7, v10, s73
	v_bfe_u32 v10, v9, 16, 1
	v_lshrrev_b32_e32 v7, 16, v7
	v_add3_u32 v9, v9, v10, s73
	v_and_or_b32 v9, v9, s72, v7
	ds_read_b32 v7, v5 offset:560
	ds_read_b32 v10, v5 offset:692
	s_waitcnt lgkmcnt(0)
	v_bfe_u32 v11, v7, 16, 1
	v_add3_u32 v7, v7, v11, s73
	v_bfe_u32 v11, v10, 16, 1
	v_lshrrev_b32_e32 v7, 16, v7
	v_add3_u32 v10, v10, v11, s73
	v_and_or_b32 v10, v10, s72, v7
	ds_read_b32 v7, v5 offset:824
	ds_read_b32 v11, v5 offset:956
	s_waitcnt lgkmcnt(0)
	v_bfe_u32 v12, v7, 16, 1
	v_add3_u32 v7, v7, v12, s73
	v_bfe_u32 v12, v11, 16, 1
	v_lshrrev_b32_e32 v7, 16, v7
	v_add3_u32 v11, v11, v12, s73
	v_and_or_b32 v11, v11, s72, v7
	v_lshl_add_u64 v[6:7], v[0:1], 0, v[184:185]
	flat_store_dwordx4 v[6:7], v[8:11] nt
	ds_read_b32 v6, v5 offset:64
	ds_read_b32 v7, v5 offset:196
	v_lshlrev_b32_e32 v184, 12, v4
	s_waitcnt lgkmcnt(0)
	v_bfe_u32 v8, v6, 16, 1
	v_add3_u32 v6, v6, v8, s73
	v_bfe_u32 v8, v7, 16, 1
	v_lshrrev_b32_e32 v6, 16, v6
	v_add3_u32 v7, v7, v8, s73
	v_and_or_b32 v6, v7, s72, v6
	ds_read_b32 v7, v5 offset:328
	ds_read_b32 v8, v5 offset:460
	s_waitcnt lgkmcnt(0)
	v_bfe_u32 v9, v7, 16, 1
	v_add3_u32 v7, v7, v9, s73
	v_bfe_u32 v9, v8, 16, 1
	v_lshrrev_b32_e32 v7, 16, v7
	v_add3_u32 v8, v8, v9, s73
	v_and_or_b32 v7, v8, s72, v7
	ds_read_b32 v8, v5 offset:592
	ds_read_b32 v9, v5 offset:724
	s_waitcnt lgkmcnt(0)
	v_bfe_u32 v10, v8, 16, 1
	v_add3_u32 v8, v8, v10, s73
	v_bfe_u32 v10, v9, 16, 1
	v_lshrrev_b32_e32 v8, 16, v8
	v_add3_u32 v9, v9, v10, s73
	v_and_or_b32 v8, v9, s72, v8
	ds_read_b32 v9, v5 offset:856
	ds_read_b32 v10, v5 offset:988
	s_waitcnt lgkmcnt(0)
	v_bfe_u32 v11, v9, 16, 1
	v_add3_u32 v9, v9, v11, s73
	v_bfe_u32 v11, v10, 16, 1
	v_lshrrev_b32_e32 v9, 16, v9
	v_add3_u32 v10, v10, v11, s73
	v_and_or_b32 v9, v10, s72, v9
	v_lshl_add_u64 v[10:11], v[0:1], 0, v[184:185]
	flat_store_dwordx4 v[10:11], v[6:9] nt
	ds_read_b32 v4, v5 offset:96
	ds_read_b32 v6, v5 offset:228
	v_lshlrev_b32_e32 v184, 12, v2
	v_lshl_add_u64 v[0:1], v[0:1], 0, v[184:185]
	s_waitcnt lgkmcnt(0)
	v_bfe_u32 v7, v4, 16, 1
	v_add3_u32 v4, v4, v7, s73
	v_bfe_u32 v7, v6, 16, 1
	v_lshrrev_b32_e32 v4, 16, v4
	v_add3_u32 v6, v6, v7, s73
	v_and_or_b32 v6, v6, s72, v4
	ds_read_b32 v4, v5 offset:360
	ds_read_b32 v7, v5 offset:492
	s_waitcnt lgkmcnt(0)
	v_bfe_u32 v8, v4, 16, 1
	v_add3_u32 v4, v4, v8, s73
	v_bfe_u32 v8, v7, 16, 1
	v_lshrrev_b32_e32 v4, 16, v4
	v_add3_u32 v7, v7, v8, s73
	v_and_or_b32 v7, v7, s72, v4
	ds_read_b32 v4, v5 offset:624
	ds_read_b32 v8, v5 offset:756
	s_waitcnt lgkmcnt(0)
	v_bfe_u32 v9, v4, 16, 1
	v_add3_u32 v4, v4, v9, s73
	v_bfe_u32 v9, v8, 16, 1
	v_lshrrev_b32_e32 v4, 16, v4
	v_add3_u32 v8, v8, v9, s73
	v_and_or_b32 v8, v8, s72, v4
	ds_read_b32 v4, v5 offset:888
	ds_read_b32 v5, v5 offset:1020
	s_waitcnt lgkmcnt(0)
	v_bfe_u32 v9, v4, 16, 1
	v_add3_u32 v4, v4, v9, s73
	v_bfe_u32 v9, v5, 16, 1
	v_lshrrev_b32_e32 v4, 16, v4
	v_add3_u32 v5, v5, v9, s73
	v_and_or_b32 v9, v5, s72, v4
	flat_store_dwordx4 v[0:1], v[6:9] nt
	s_waitcnt lgkmcnt(0)
	s_or_b64 exec, exec, s[6:7]
	s_and_saveexec_b64 s[6:7], s[10:11]
	s_cbranch_execz .LBB0_2023
	s_branch .LBB0_2006

; #define LAS __attribute__((address_space(3)))
; #define F_LANE() (tid_of(F.wave) & 63)
; #define LDS_WAIT() asm volatile("s_waitcnt lgkmcnt(0)" ::: "memory")
; template <class Map>
; __device__ __forceinline__ void conv_item(const Frame& F, int it, const float* W, int K, int N, bf16_t* WT, const float* gk, int gmask, float gmul, const float* bk, i64* cs, i64* bw, Map map) {
;     ...
;     const int lane = F_LANE(), nblk = N / 32;
;     {
;         const int kb = it / nblk, nb = it % nblk, k0 = 64 * kb, n0 = 32 * nb, v0 = map(n0);
; #pragma unroll
;         for (int i = 0; i < 8; ++i) { const int kk = 8 * i + (lane >> 3), c4 = (lane & 7) * 4;
;             const f32x4 w4 = __builtin_nontemporal_load((const f32x4*)(W + (size_t)(k0 + kk) * N + n0 + c4)); LAS float* d = scr + kk * 33 + c4; d[0] = w4[0]; d[1] = w4[1]; d[2] = w4[2]; d[3] = w4[3]; }
;         LDS_WAIT(); asm volatile("" ::: "memory");
.LBB0_1967:
	s_andn2_saveexec_b64 s[36:37], s[12:13]
	s_cbranch_execz .LBB0_1969
	v_readlane_b32 s12, v252, 14
	v_readlane_b32 s13, v252, 15
	s_load_dwordx2 s[12:13], s[12:13], 0x90
	v_and_b32_e32 v17, 0xc0, v0
	v_lshlrev_b32_e32 v0, 5, v0
	v_mov_b32_e32 v16, v220
	v_and_b32_e32 v2, 0x7e0, v0
	s_waitcnt lgkmcnt(0)
	s_add_u32 s16, s12, s54
	s_addc_u32 s17, s13, s55
	v_readlane_b32 s12, v252, 12
	v_readlane_b32 s13, v252, 13
	v_lshlrev_b32_e32 v184, 2, v2
	v_bfe_u32 v7, v16, 3, 3
	v_lshlrev_b32_e32 v3, 4, v16
	v_lshl_add_u64 v[0:1], s[16:17], 0, v[184:185]
	v_and_b32_e32 v184, 0x70, v3
	v_or_b32_e32 v3, v7, v17
	v_lshl_add_u64 v[0:1], v[0:1], 0, v[184:185]
	v_lshlrev_b32_e32 v12, 13, v3
	v_mov_b32_e32 v13, v185
	v_lshl_add_u64 v[4:5], v[0:1], 0, v[12:13]
	global_load_dwordx4 v[132:135], v[4:5], off nt
	v_mul_u32_u24_e32 v3, 0x84, v7
	v_readlane_b32 s16, v255, 17
	v_or_b32_e32 v6, 8, v7
	s_add_u32 s12, s12, s86
	v_add3_u32 v13, s16, v184, v3
	v_or_b32_e32 v3, v6, v17
	v_lshlrev_b32_e32 v184, 13, v3
	v_lshl_add_u64 v[4:5], v[0:1], 0, v[184:185]
	v_add_u32_e32 v3, 0x420, v13
	s_addc_u32 s13, s13, 0
	v_or_b32_e32 v6, v6, v2
	global_load_dwordx4 v[136:139], v[4:5], off nt
	v_or_b32_e32 v4, 16, v7
	v_add_u32_e32 v3, 0x428, v13
	v_or_b32_e32 v3, v4, v17
	v_lshlrev_b32_e32 v184, 13, v3
	v_lshl_add_u64 v[8:9], v[0:1], 0, v[184:185]
	global_load_dwordx4 v[140:143], v[8:9], off nt
	v_add_u32_e32 v3, 0x840, v13
	v_or_b32_e32 v4, v4, v2
	v_add_u32_e32 v3, 0x848, v13
	v_or_b32_e32 v3, 24, v7
	v_or_b32_e32 v5, v3, v17
	v_lshlrev_b32_e32 v184, 13, v5
	v_lshl_add_u64 v[8:9], v[0:1], 0, v[184:185]
	global_load_dwordx4 v[144:147], v[8:9], off nt
	v_add_u32_e32 v5, 0xc60, v13
	v_or_b32_e32 v184, 0x40000, v12
	v_add_u32_e32 v5, 0xc68, v13
	v_lshl_add_u64 v[8:9], v[0:1], 0, v[184:185]
	global_load_dwordx4 v[148:151], v[8:9], off nt
	v_add_u32_e32 v5, 0x1080, v13
	v_or_b32_e32 v184, 0x50000, v12
	v_add_u32_e32 v5, 0x1088, v13
	v_lshl_add_u64 v[8:9], v[0:1], 0, v[184:185]
	global_load_dwordx4 v[152:155], v[8:9], off nt
	v_add_u32_e32 v5, 0x14a0, v13
	v_or_b32_e32 v184, 0x60000, v12
	v_add_u32_e32 v5, 0x14a8, v13
	v_lshl_add_u64 v[8:9], v[0:1], 0, v[184:185]
	global_load_dwordx4 v[156:159], v[8:9], off nt
	v_add_u32_e32 v5, 0x18c0, v13
	v_or_b32_e32 v184, 0x70000, v12
	v_lshl_add_u64 v[0:1], v[0:1], 0, v[184:185]
	v_lshlrev_b32_e32 v184, 1, v17
	v_add_u32_e32 v5, 0x18c8, v13
	global_load_dwordx4 v[160:163], v[0:1], off nt
	v_add_u32_e32 v0, 0x1ce0, v13
	v_and_b32_e32 v5, 7, v16
	v_add_u32_e32 v0, 0x1ce8, v13
	s_waitcnt vmcnt(0)
	v_add_u32_e32 v164, 0x0, v13
	ds_write2_b32 v164, v132, v133 offset1:1
	ds_write2_b32 v164, v134, v135 offset0:2 offset1:3
	v_add_u32_e32 v164, 0x420, v13
	ds_write2_b32 v164, v136, v137 offset1:1
	ds_write2_b32 v164, v138, v139 offset0:2 offset1:3
	v_add_u32_e32 v164, 0x840, v13
	ds_write2_b32 v164, v140, v141 offset1:1
	ds_write2_b32 v164, v142, v143 offset0:2 offset1:3
	v_add_u32_e32 v164, 0xc60, v13
	ds_write2_b32 v164, v144, v145 offset1:1
	ds_write2_b32 v164, v146, v147 offset0:2 offset1:3
	v_add_u32_e32 v164, 0x1080, v13
	ds_write2_b32 v164, v148, v149 offset1:1
	ds_write2_b32 v164, v150, v151 offset0:2 offset1:3
	v_add_u32_e32 v164, 0x14a0, v13
	ds_write2_b32 v164, v152, v153 offset1:1
	ds_write2_b32 v164, v154, v155 offset0:2 offset1:3
	v_add_u32_e32 v164, 0x18c0, v13
	ds_write2_b32 v164, v156, v157 offset1:1
	ds_write2_b32 v164, v158, v159 offset0:2 offset1:3
	v_add_u32_e32 v164, 0x1ce0, v13
	ds_write2_b32 v164, v160, v161 offset1:1
	ds_write2_b32 v164, v162, v163 offset0:2 offset1:3
	s_waitcnt lgkmcnt(0)
	v_mul_u32_u24_e32 v8, 0x420, v5
	v_lshl_add_u64 v[0:1], s[12:13], 0, v[184:185]
	v_lshlrev_b32_e32 v184, 4, v5
	v_lshlrev_b32_e32 v5, 2, v7
	v_add3_u32 v5, s16, v8, v5
	ds_read_b32 v8, v5
	ds_read_b32 v9, v5 offset:132
	v_lshl_add_u64 v[0:1], v[0:1], 0, v[184:185]
	s_mov_b64 s[12:13], 0x7a00000
	v_or_b32_e32 v7, v7, v2
	s_waitcnt lgkmcnt(1)
	v_bfe_u32 v10, v8, 16, 1
	v_add3_u32 v8, v8, v10, s73
	s_waitcnt lgkmcnt(0)
	v_bfe_u32 v10, v9, 16, 1
	v_lshrrev_b32_e32 v8, 16, v8
	v_add3_u32 v9, v9, v10, s73
	v_and_or_b32 v8, v9, s72, v8
	ds_read_b32 v9, v5 offset:264
	ds_read_b32 v10, v5 offset:396
	v_lshl_add_u64 v[0:1], v[0:1], 0, s[12:13]
	v_lshlrev_b32_e32 v184, 9, v7
	v_or_b32_e32 v2, v3, v2
	s_waitcnt lgkmcnt(1)
; #define LAS __attribute__((address_space(3)))
; #define LDS_WAIT() asm volatile("s_waitcnt lgkmcnt(0)" ::: "memory")
; __device__ __forceinline__ unsigned f2bf(float f) { unsigned u = __builtin_bit_cast(unsigned, f); return (u + 0x7fffu + ((u >> 16) & 1u)) >> 16; }
; __device__ __forceinline__ float bf_round(float f) { return __uint_as_float(f2bf(f) << 16); }
; __device__ __forceinline__ unsigned pk2(float lo, float hi) { return f2bf(lo) | (f2bf(hi) << 16); }
; template <class Map>
; __device__ __forceinline__ void conv_item(const Frame& F, int it, const float* W, int K, int N, bf16_t* WT, const float* gk, int gmask, float gmul, const float* bk, i64* cs, i64* bw, Map map) {
;     ...
;         for (int j = 0; j < 4; ++j) { const int n = (lane >> 3) + 8 * j; const LAS float* s = scr + (8 * c) * 33 + n;
;             u32x4 o; o.x = pk2(s[0 * 33] * gl[0], s[1 * 33] * gl[1]); o.y = pk2(s[2 * 33] * gl[2], s[3 * 33] * gl[3]); o.z = pk2(s[4 * 33] * gl[4], s[5 * 33] * gl[5]); o.w = pk2(s[6 * 33] * gl[6], s[7 * 33] * gl[7]);
;             __builtin_nontemporal_store(o, (u32x4*)(WT + (size_t)(v0 + n) * K + k0 + 8 * c)); }
;         LDS_WAIT(); asm volatile("" ::: "memory");
	v_bfe_u32 v11, v9, 16, 1
	v_add3_u32 v9, v9, v11, s73
	s_waitcnt lgkmcnt(0)
	v_bfe_u32 v11, v10, 16, 1
	v_lshrrev_b32_e32 v9, 16, v9
	v_add3_u32 v10, v10, v11, s73
	v_and_or_b32 v9, v10, s72, v9
	ds_read_b32 v10, v5 offset:528
	ds_read_b32 v11, v5 offset:660
	s_waitcnt lgkmcnt(1)
	v_bfe_u32 v12, v10, 16, 1
	v_add3_u32 v10, v10, v12, s73
	s_waitcnt lgkmcnt(0)
	v_bfe_u32 v12, v11, 16, 1
	v_lshrrev_b32_e32 v10, 16, v10
	v_add3_u32 v11, v11, v12, s73
	v_and_or_b32 v10, v11, s72, v10
	ds_read_b32 v11, v5 offset:792
	ds_read_b32 v12, v5 offset:924
	s_waitcnt lgkmcnt(1)
	v_bfe_u32 v13, v11, 16, 1
	v_add3_u32 v11, v11, v13, s73
	s_waitcnt lgkmcnt(0)
	v_bfe_u32 v13, v12, 16, 1
	v_lshrrev_b32_e32 v11, 16, v11
	v_add3_u32 v12, v12, v13, s73
	v_and_or_b32 v11, v12, s72, v11
	v_lshl_add_u64 v[12:13], v[0:1], 0, v[184:185]
	flat_store_dwordx4 v[12:13], v[8:11] nt
	ds_read_b32 v7, v5 offset:32
	ds_read_b32 v8, v5 offset:164
	v_lshlrev_b32_e32 v184, 9, v6
	s_waitcnt lgkmcnt(0)
	v_bfe_u32 v9, v7, 16, 1
	v_add3_u32 v7, v7, v9, s73
	v_bfe_u32 v9, v8, 16, 1
	v_lshrrev_b32_e32 v7, 16, v7
	v_add3_u32 v8, v8, v9, s73
	v_and_or_b32 v8, v8, s72, v7
	ds_read_b32 v7, v5 offset:296
	ds_read_b32 v9, v5 offset:428
	s_waitcnt lgkmcnt(0)
	v_bfe_u32 v10, v7, 16, 1
	v_add3_u32 v7, v7, v10, s73
	v_bfe_u32 v10, v9, 16, 1
	v_lshrrev_b32_e32 v7, 16, v7
	v_add3_u32 v9, v9, v10, s73
	v_and_or_b32 v9, v9, s72, v7
	ds_read_b32 v7, v5 offset:560
	ds_read_b32 v10, v5 offset:692
	s_waitcnt lgkmcnt(0)
	v_bfe_u32 v11, v7, 16, 1
	v_add3_u32 v7, v7, v11, s73
	v_bfe_u32 v11, v10, 16, 1
	v_lshrrev_b32_e32 v7, 16, v7
	v_add3_u32 v10, v10, v11, s73
	v_and_or_b32 v10, v10, s72, v7
	ds_read_b32 v7, v5 offset:824
	ds_read_b32 v11, v5 offset:956
	s_waitcnt lgkmcnt(0)
	v_bfe_u32 v12, v7, 16, 1
	v_add3_u32 v7, v7, v12, s73
	v_bfe_u32 v12, v11, 16, 1
	v_lshrrev_b32_e32 v7, 16, v7
	v_add3_u32 v11, v11, v12, s73
	v_and_or_b32 v11, v11, s72, v7
	v_lshl_add_u64 v[6:7], v[0:1], 0, v[184:185]
	flat_store_dwordx4 v[6:7], v[8:11] nt
	ds_read_b32 v6, v5 offset:64
	ds_read_b32 v7, v5 offset:196
	v_lshlrev_b32_e32 v184, 9, v4
	s_waitcnt lgkmcnt(0)
	v_bfe_u32 v8, v6, 16, 1
	v_add3_u32 v6, v6, v8, s73
	v_bfe_u32 v8, v7, 16, 1
	v_lshrrev_b32_e32 v6, 16, v6
	v_add3_u32 v7, v7, v8, s73
	v_and_or_b32 v6, v7, s72, v6
	ds_read_b32 v7, v5 offset:328
	ds_read_b32 v8, v5 offset:460
	s_waitcnt lgkmcnt(0)
	v_bfe_u32 v9, v7, 16, 1
	v_add3_u32 v7, v7, v9, s73
	v_bfe_u32 v9, v8, 16, 1
	v_lshrrev_b32_e32 v7, 16, v7
	v_add3_u32 v8, v8, v9, s73
	v_and_or_b32 v7, v8, s72, v7
	ds_read_b32 v8, v5 offset:592
	ds_read_b32 v9, v5 offset:724
	s_waitcnt lgkmcnt(0)
	v_bfe_u32 v10, v8, 16, 1
	v_add3_u32 v8, v8, v10, s73
	v_bfe_u32 v10, v9, 16, 1
	v_lshrrev_b32_e32 v8, 16, v8
	v_add3_u32 v9, v9, v10, s73
	v_and_or_b32 v8, v9, s72, v8
	ds_read_b32 v9, v5 offset:856
	ds_read_b32 v10, v5 offset:988
	s_waitcnt lgkmcnt(0)
	v_bfe_u32 v11, v9, 16, 1
	v_add3_u32 v9, v9, v11, s73
	v_bfe_u32 v11, v10, 16, 1
	v_lshrrev_b32_e32 v9, 16, v9
	v_add3_u32 v10, v10, v11, s73
	v_and_or_b32 v9, v10, s72, v9
	v_lshl_add_u64 v[10:11], v[0:1], 0, v[184:185]
	flat_store_dwordx4 v[10:11], v[6:9] nt
	ds_read_b32 v4, v5 offset:96
	ds_read_b32 v6, v5 offset:228
	v_lshlrev_b32_e32 v184, 9, v2
	v_lshl_add_u64 v[0:1], v[0:1], 0, v[184:185]
	s_waitcnt lgkmcnt(0)
	v_bfe_u32 v7, v4, 16, 1
	v_add3_u32 v4, v4, v7, s73
	v_bfe_u32 v7, v6, 16, 1
	v_lshrrev_b32_e32 v4, 16, v4
	v_add3_u32 v6, v6, v7, s73
	v_and_or_b32 v6, v6, s72, v4
	ds_read_b32 v4, v5 offset:360
	ds_read_b32 v7, v5 offset:492
	s_waitcnt lgkmcnt(0)
	v_bfe_u32 v8, v4, 16, 1
	v_add3_u32 v4, v4, v8, s73
	v_bfe_u32 v8, v7, 16, 1
	v_lshrrev_b32_e32 v4, 16, v4
	v_add3_u32 v7, v7, v8, s73
	v_and_or_b32 v7, v7, s72, v4
	ds_read_b32 v4, v5 offset:624
	ds_read_b32 v8, v5 offset:756
	s_waitcnt lgkmcnt(0)
	v_bfe_u32 v9, v4, 16, 1
	v_add3_u32 v4, v4, v9, s73
	v_bfe_u32 v9, v8, 16, 1
	v_lshrrev_b32_e32 v4, 16, v4
	v_add3_u32 v8, v8, v9, s73
	v_and_or_b32 v8, v8, s72, v4
	ds_read_b32 v4, v5 offset:888
	ds_read_b32 v5, v5 offset:1020
	s_waitcnt lgkmcnt(0)
	v_bfe_u32 v9, v4, 16, 1
	v_add3_u32 v4, v4, v9, s73
	v_bfe_u32 v9, v5, 16, 1
	v_lshrrev_b32_e32 v4, 16, v4
	v_add3_u32 v5, v5, v9, s73
	v_and_or_b32 v9, v5, s72, v4
	flat_store_dwordx4 v[0:1], v[6:9] nt
	s_waitcnt lgkmcnt(0)

; #define LAS __attribute__((address_space(3)))
; #define F_LANE() (tid_of(F.wave) & 63)
; #define LDS_WAIT() asm volatile("s_waitcnt lgkmcnt(0)" ::: "memory")
; template <class Map>
; __device__ __forceinline__ void conv_item(const Frame& F, int it, const float* W, int K, int N, bf16_t* WT, const float* gk, int gmask, float gmul, const float* bk, i64* cs, i64* bw, Map map) {
;     ...
;     const int lane = F_LANE(), nblk = N / 32;
;     {
;         const int kb = it / nblk, nb = it % nblk, k0 = 64 * kb, n0 = 32 * nb, v0 = map(n0);
; #pragma unroll
;         for (int i = 0; i < 8; ++i) { const int kk = 8 * i + (lane >> 3), c4 = (lane & 7) * 4;
;             const f32x4 w4 = __builtin_nontemporal_load((const f32x4*)(W + (size_t)(k0 + kk) * N + n0 + c4)); LAS float* d = scr + kk * 33 + c4; d[0] = w4[0]; d[1] = w4[1]; d[2] = w4[2]; d[3] = w4[3]; }
;         LDS_WAIT(); asm volatile("" ::: "memory");
;         if (bk) {
;             const int n = lane & 31, kh = lane >> 5; float sb = 0.f, sc = 0.f;
.LBB0_1970:
	s_andn2_saveexec_b64 s[30:31], s[30:31]
	s_cbranch_execz .LBB0_1976
	v_readlane_b32 s48, v252, 14
	v_readlane_b32 s49, v252, 15
	s_mov_b64 s[12:13], s[48:49]
	s_load_dwordx2 s[12:13], s[12:13], 0x88
	v_readlane_b32 s36, v252, 12
	v_readlane_b32 s37, v252, 13
	s_mov_b64 s[46:47], s[36:37]
	s_waitcnt lgkmcnt(0)
	s_add_u32 s16, s12, s56
	s_addc_u32 s17, s13, s57
	s_mov_b64 s[12:13], s[48:49]
	s_load_dwordx2 s[70:71], s[12:13], 0x68
	s_lshl_b64 s[12:13], s[58:59], 2
	v_add_u32_e32 v10, 0xbe00, v0
	v_lshlrev_b32_e32 v0, 5, v0
	v_mov_b32_e32 v18, v220
	s_waitcnt lgkmcnt(0)
	s_add_u32 s12, s70, s12
	s_addc_u32 s13, s71, s13
	s_add_u32 s38, s12, 0x2000
	s_addc_u32 s39, s13, 0
	s_mov_b64 s[12:13], s[48:49]
	s_load_dwordx2 s[74:75], s[12:13], 0x70
	s_mov_b64 s[12:13], s[36:37]
	s_mov_b64 s[48:49], s[36:37]
	v_and_b32_e32 v8, 0x7e0, v0
	v_lshlrev_b32_e32 v184, 2, v8
	v_lshlrev_b32_e32 v2, 4, v18
	v_and_b32_e32 v17, 0xffc0, v10
	v_bfe_u32 v13, v18, 3, 3
	v_lshl_add_u64 v[0:1], s[16:17], 0, v[184:185]
	v_and_b32_e32 v184, 0x70, v2
	v_lshl_add_u64 v[4:5], v[0:1], 0, v[184:185]
	v_or_b32_e32 v0, v13, v17
	v_lshlrev_b32_e32 v6, 13, v0
	v_mov_b32_e32 v7, v185
	v_lshl_add_u64 v[0:1], v[4:5], 0, v[6:7]
	global_load_dwordx4 v[132:135], v[0:1], off nt
	v_mul_u32_u24_e32 v7, 0x84, v13
	v_readlane_b32 s36, v255, 17
	v_or_b32_e32 v12, 8, v13
	v_or_b32_e32 v16, 16, v13
	v_add3_u32 v7, s36, v184, v7
	v_add_u32_e32 v9, 0x420, v7
	v_add_u32_e32 v11, 0xc60, v7
	v_readlane_b32 vcc_lo, v255, 25
	s_movk_i32 s37, 0x7c0
	v_readlane_b32 vcc_hi, v255, 26
	s_add_u32 s16, s70, vcc_lo
	s_addc_u32 s17, s71, vcc_hi
	v_and_b32_e32 v20, 31, v18
	v_and_or_b32 v21, v18, 32, v17
	v_and_b32_e32 v19, 63, v18
	s_mov_b64 s[70:71], 0
	v_or_b32_e32 v0, v12, v17
	v_lshlrev_b32_e32 v184, 13, v0
	v_lshl_add_u64 v[0:1], v[4:5], 0, v[184:185]
	global_load_dwordx4 v[136:139], v[0:1], off nt
	v_add_u32_e32 v0, 0x428, v7
	v_or_b32_e32 v0, v16, v17
	v_lshlrev_b32_e32 v184, 13, v0
	v_lshl_add_u64 v[0:1], v[4:5], 0, v[184:185]
	global_load_dwordx4 v[140:143], v[0:1], off nt
	v_add_u32_e32 v9, 0x840, v7
	v_add_u32_e32 v0, 0x848, v7
	v_or_b32_e32 v9, 24, v13
	v_or_b32_e32 v0, v9, v17
	v_lshlrev_b32_e32 v184, 13, v0
	v_lshl_add_u64 v[0:1], v[4:5], 0, v[184:185]
	global_load_dwordx4 v[144:147], v[0:1], off nt
	v_or_b32_e32 v184, 0x40000, v6
	v_add_u32_e32 v0, 0xc68, v7
	v_lshl_add_u64 v[0:1], v[4:5], 0, v[184:185]
	global_load_dwordx4 v[148:151], v[0:1], off nt
	v_add_u32_e32 v11, 0x1080, v7
	v_or_b32_e32 v184, 0x50000, v6
	v_add_u32_e32 v0, 0x1088, v7
	v_lshl_add_u64 v[0:1], v[4:5], 0, v[184:185]
	global_load_dwordx4 v[152:155], v[0:1], off nt
	v_add_u32_e32 v11, 0x14a0, v7
	v_or_b32_e32 v184, 0x60000, v6
	v_add_u32_e32 v0, 0x14a8, v7
	v_lshl_add_u64 v[0:1], v[4:5], 0, v[184:185]
	global_load_dwordx4 v[156:159], v[0:1], off nt
	v_add_u32_e32 v11, 0x18c0, v7
	v_or_b32_e32 v184, 0x70000, v6
	v_add_u32_e32 v0, 0x18c8, v7
	v_lshl_add_u64 v[0:1], v[4:5], 0, v[184:185]
	global_load_dwordx4 v[160:163], v[0:1], off nt
	v_add_u32_e32 v4, 0x1ce0, v7
	v_add_u32_e32 v0, 0x1ce8, v7
	s_waitcnt vmcnt(0)
	v_add_u32_e32 v164, 0x0, v7
	ds_write2_b32 v164, v132, v133 offset1:1
	ds_write2_b32 v164, v134, v135 offset0:2 offset1:3
	v_add_u32_e32 v164, 0x420, v7
	ds_write2_b32 v164, v136, v137 offset1:1
	ds_write2_b32 v164, v138, v139 offset0:2 offset1:3
	v_add_u32_e32 v164, 0x840, v7
	ds_write2_b32 v164, v140, v141 offset1:1
	ds_write2_b32 v164, v142, v143 offset0:2 offset1:3
	v_add_u32_e32 v164, 0xc60, v7
	ds_write2_b32 v164, v144, v145 offset1:1
	ds_write2_b32 v164, v146, v147 offset0:2 offset1:3
	v_add_u32_e32 v164, 0x1080, v7
	ds_write2_b32 v164, v148, v149 offset1:1
	ds_write2_b32 v164, v150, v151 offset0:2 offset1:3
	v_add_u32_e32 v164, 0x14a0, v7
	ds_write2_b32 v164, v152, v153 offset1:1
	ds_write2_b32 v164, v154, v155 offset0:2 offset1:3
	v_add_u32_e32 v164, 0x18c0, v7
	ds_write2_b32 v164, v156, v157 offset1:1
	ds_write2_b32 v164, v158, v159 offset0:2 offset1:3
	v_add_u32_e32 v164, 0x1ce0, v7
	ds_write2_b32 v164, v160, v161 offset1:1
	ds_write2_b32 v164, v162, v163 offset0:2 offset1:3
	v_lshrrev_b32_e32 v0, 5, v18
	v_and_b32_e32 v0, 1, v0
	v_lshlrev_b16_e32 v0, 5, v0
	v_bitop3_b16 v0, v10, v0, s37 bitop3:0xec
	s_waitcnt lgkmcnt(0)
	v_lshlrev_b32_sdwa v184, v227, v0 dst_sel:DWORD dst_unused:UNUSED_PAD src0_sel:DWORD src1_sel:WORD_0
	v_bfe_u32 v0, v18, 5, 1
	v_lshl_add_u64 v[4:5], s[16:17], 0, v[184:185]
	s_waitcnt lgkmcnt(0)
	s_add_u32 s16, s74, vcc_lo
	v_mul_u32_u24_e32 v0, 0x1080, v0
	s_addc_u32 s17, s75, vcc_hi
	v_lshlrev_b32_e32 v184, 2, v21
	v_lshl_or_b32 v0, v20, 2, v0
	v_mov_b32_e32 v10, 0
	v_lshl_add_u64 v[6:7], s[16:17], 0, v[184:185]
	v_add_u32_e32 v22, s36, v0
	v_mov_b32_e32 v11, v10
	s_movk_i32 s16, 0x2000
	s_mov_b64 s[36:37], 0x2000

; #define LAS __attribute__((address_space(3)))
; #define F_LANE() (tid_of(F.wave) & 63)
; #define LDS_WAIT() asm volatile("s_waitcnt lgkmcnt(0)" ::: "memory")
; template <class Map>
; __device__ __forceinline__ void conv_item(const Frame& F, int it, const float* W, int K, int N, bf16_t* WT, const float* gk, int gmask, float gmul, const float* bk, i64* cs, i64* bw, Map map) {
;     ...
;     const int lane = F_LANE(), nblk = N / 32;
;     {
;         const int kb = it / nblk, nb = it % nblk, k0 = 64 * kb, n0 = 32 * nb, v0 = map(n0);
; #pragma unroll
;         for (int i = 0; i < 8; ++i) { const int kk = 8 * i + (lane >> 3), c4 = (lane & 7) * 4;
;             const f32x4 w4 = __builtin_nontemporal_load((const f32x4*)(W + (size_t)(k0 + kk) * N + n0 + c4)); LAS float* d = scr + kk * 33 + c4; d[0] = w4[0]; d[1] = w4[1]; d[2] = w4[2]; d[3] = w4[3]; }
;         LDS_WAIT(); asm volatile("" ::: "memory");
.LBB0_1977:
	s_andn2_saveexec_b64 s[26:27], s[26:27]
	s_cbranch_execz .LBB0_1979
	v_readlane_b32 s12, v252, 14
	v_readlane_b32 s13, v252, 15
	s_load_dwordx2 s[12:13], s[12:13], 0x80
	s_mul_i32 s16, s20, 0x2c00000
	v_add_u32_e32 v1, 0xd400, v0
	v_lshlrev_b32_e32 v0, 5, v0
	v_mov_b32_e32 v16, v220
	s_waitcnt lgkmcnt(0)
	s_add_u32 s16, s12, s16
	s_mul_hi_i32 s12, s20, 0x2c00000
	s_addc_u32 s17, s13, s12
	v_readlane_b32 s12, v252, 12
	v_readlane_b32 s13, v252, 13
	v_and_b32_e32 v2, 0x7e0, v0
	v_and_b32_e32 v17, 0xffc0, v1
	v_bfe_u32 v7, v16, 3, 3
	v_lshlrev_b32_e32 v184, 2, v2
	v_lshlrev_b32_e32 v3, 4, v16
	v_lshl_add_u64 v[0:1], s[16:17], 0, v[184:185]
	v_and_b32_e32 v184, 0x70, v3
	v_or_b32_e32 v3, v7, v17
	v_lshl_add_u64 v[0:1], v[0:1], 0, v[184:185]
	v_lshlrev_b32_e32 v12, 13, v3
	v_mov_b32_e32 v13, v185
	v_lshl_add_u64 v[4:5], v[0:1], 0, v[12:13]
	global_load_dwordx4 v[132:135], v[4:5], off nt
	v_mul_u32_u24_e32 v3, 0x84, v7
	v_readlane_b32 s16, v255, 17
	v_or_b32_e32 v6, 8, v7
	s_add_u32 s12, s12, s86
	v_add3_u32 v13, s16, v184, v3
	v_or_b32_e32 v3, v6, v17
	v_lshlrev_b32_e32 v184, 13, v3
	v_lshl_add_u64 v[4:5], v[0:1], 0, v[184:185]
	v_add_u32_e32 v3, 0x420, v13
	s_addc_u32 s13, s13, 0
	v_or_b32_e32 v6, v6, v2
	v_mul_u32_u24_e32 v6, 0x1600, v6
	global_load_dwordx4 v[136:139], v[4:5], off nt
	v_or_b32_e32 v4, 16, v7
	v_add_u32_e32 v3, 0x428, v13
	v_or_b32_e32 v3, v4, v17
	v_lshlrev_b32_e32 v184, 13, v3
	v_lshl_add_u64 v[8:9], v[0:1], 0, v[184:185]
	global_load_dwordx4 v[140:143], v[8:9], off nt
	v_add_u32_e32 v3, 0x840, v13
	v_or_b32_e32 v4, v4, v2
	v_mul_u32_u24_e32 v4, 0x1600, v4
	v_add_u32_e32 v3, 0x848, v13
	v_or_b32_e32 v3, 24, v7
	v_or_b32_e32 v5, v3, v17
	v_lshlrev_b32_e32 v184, 13, v5
	v_lshl_add_u64 v[8:9], v[0:1], 0, v[184:185]
	global_load_dwordx4 v[144:147], v[8:9], off nt
	v_add_u32_e32 v5, 0xc60, v13
	v_or_b32_e32 v184, 0x40000, v12
	v_add_u32_e32 v5, 0xc68, v13
	v_lshl_add_u64 v[8:9], v[0:1], 0, v[184:185]
	global_load_dwordx4 v[148:151], v[8:9], off nt
	v_add_u32_e32 v5, 0x1080, v13
	v_or_b32_e32 v184, 0x50000, v12
	v_add_u32_e32 v5, 0x1088, v13
	v_lshl_add_u64 v[8:9], v[0:1], 0, v[184:185]
	global_load_dwordx4 v[152:155], v[8:9], off nt
	v_add_u32_e32 v5, 0x14a0, v13
	v_or_b32_e32 v184, 0x60000, v12
	v_add_u32_e32 v5, 0x14a8, v13
	v_lshl_add_u64 v[8:9], v[0:1], 0, v[184:185]
	global_load_dwordx4 v[156:159], v[8:9], off nt
	v_add_u32_e32 v5, 0x18c0, v13
	v_or_b32_e32 v184, 0x70000, v12
	v_lshl_add_u64 v[0:1], v[0:1], 0, v[184:185]
	v_lshlrev_b32_e32 v184, 1, v17
	v_add_u32_e32 v5, 0x18c8, v13
	global_load_dwordx4 v[160:163], v[0:1], off nt
	v_add_u32_e32 v0, 0x1ce0, v13
	v_and_b32_e32 v5, 7, v16
	v_add_u32_e32 v0, 0x1ce8, v13
	s_waitcnt vmcnt(0)
	v_add_u32_e32 v164, 0x0, v13
	ds_write2_b32 v164, v132, v133 offset1:1
	ds_write2_b32 v164, v134, v135 offset0:2 offset1:3
	v_add_u32_e32 v164, 0x420, v13
	ds_write2_b32 v164, v136, v137 offset1:1
	ds_write2_b32 v164, v138, v139 offset0:2 offset1:3
	v_add_u32_e32 v164, 0x840, v13
	ds_write2_b32 v164, v140, v141 offset1:1
	ds_write2_b32 v164, v142, v143 offset0:2 offset1:3
	v_add_u32_e32 v164, 0xc60, v13
	ds_write2_b32 v164, v144, v145 offset1:1
	ds_write2_b32 v164, v146, v147 offset0:2 offset1:3
	v_add_u32_e32 v164, 0x1080, v13
	ds_write2_b32 v164, v148, v149 offset1:1
	ds_write2_b32 v164, v150, v151 offset0:2 offset1:3
	v_add_u32_e32 v164, 0x14a0, v13
	ds_write2_b32 v164, v152, v153 offset1:1
	ds_write2_b32 v164, v154, v155 offset0:2 offset1:3
	v_add_u32_e32 v164, 0x18c0, v13
	ds_write2_b32 v164, v156, v157 offset1:1
	ds_write2_b32 v164, v158, v159 offset0:2 offset1:3
	v_add_u32_e32 v164, 0x1ce0, v13
	ds_write2_b32 v164, v160, v161 offset1:1
	ds_write2_b32 v164, v162, v163 offset0:2 offset1:3
	s_waitcnt lgkmcnt(0)
	v_mul_u32_u24_e32 v8, 0x420, v5
	v_lshl_add_u64 v[0:1], s[12:13], 0, v[184:185]
	v_lshlrev_b32_e32 v184, 4, v5
	v_lshlrev_b32_e32 v5, 2, v7
	v_add3_u32 v5, s16, v8, v5
	ds_read_b32 v8, v5
	ds_read_b32 v9, v5 offset:132
	v_or_b32_e32 v7, v7, v2
	v_lshl_add_u64 v[0:1], v[0:1], 0, v[184:185]
	s_mov_b64 s[12:13], 0x5c00000
	s_waitcnt lgkmcnt(1)
	v_bfe_u32 v10, v8, 16, 1
	v_add3_u32 v8, v8, v10, s73
	s_waitcnt lgkmcnt(0)
	v_bfe_u32 v10, v9, 16, 1
	v_lshrrev_b32_e32 v8, 16, v8
	v_add3_u32 v9, v9, v10, s73
	v_and_or_b32 v8, v9, s72, v8
	ds_read_b32 v9, v5 offset:264
	ds_read_b32 v10, v5 offset:396
	v_mul_u32_u24_e32 v7, 0x1600, v7
	v_lshl_add_u64 v[0:1], v[0:1], 0, s[12:13]
	v_lshlrev_b32_e32 v184, 1, v7
	s_waitcnt lgkmcnt(1)
; #define LAS __attribute__((address_space(3)))
; #define LDS_WAIT() asm volatile("s_waitcnt lgkmcnt(0)" ::: "memory")
; __device__ __forceinline__ unsigned f2bf(float f) { unsigned u = __builtin_bit_cast(unsigned, f); return (u + 0x7fffu + ((u >> 16) & 1u)) >> 16; }
; __device__ __forceinline__ float bf_round(float f) { return __uint_as_float(f2bf(f) << 16); }
; __device__ __forceinline__ unsigned pk2(float lo, float hi) { return f2bf(lo) | (f2bf(hi) << 16); }
; template <class Map>
; __device__ __forceinline__ void conv_item(const Frame& F, int it, const float* W, int K, int N, bf16_t* WT, const float* gk, int gmask, float gmul, const float* bk, i64* cs, i64* bw, Map map) {
;     ...
;         for (int j = 0; j < 4; ++j) { const int n = (lane >> 3) + 8 * j; const LAS float* s = scr + (8 * c) * 33 + n;
;             u32x4 o; o.x = pk2(s[0 * 33] * gl[0], s[1 * 33] * gl[1]); o.y = pk2(s[2 * 33] * gl[2], s[3 * 33] * gl[3]); o.z = pk2(s[4 * 33] * gl[4], s[5 * 33] * gl[5]); o.w = pk2(s[6 * 33] * gl[6], s[7 * 33] * gl[7]);
;             __builtin_nontemporal_store(o, (u32x4*)(WT + (size_t)(v0 + n) * K + k0 + 8 * c)); }
;         LDS_WAIT(); asm volatile("" ::: "memory");
	v_bfe_u32 v11, v9, 16, 1
	v_add3_u32 v9, v9, v11, s73
	s_waitcnt lgkmcnt(0)
	v_bfe_u32 v11, v10, 16, 1
	v_lshrrev_b32_e32 v9, 16, v9
	v_add3_u32 v10, v10, v11, s73
	v_and_or_b32 v9, v10, s72, v9
	ds_read_b32 v10, v5 offset:528
	ds_read_b32 v11, v5 offset:660
	v_or_b32_e32 v2, v3, v2
	v_mul_u32_u24_e32 v2, 0x1600, v2
	s_waitcnt lgkmcnt(1)
	v_bfe_u32 v12, v10, 16, 1
	v_add3_u32 v10, v10, v12, s73
	s_waitcnt lgkmcnt(0)
	v_bfe_u32 v12, v11, 16, 1
	v_lshrrev_b32_e32 v10, 16, v10
	v_add3_u32 v11, v11, v12, s73
	v_and_or_b32 v10, v11, s72, v10
	ds_read_b32 v11, v5 offset:792
	ds_read_b32 v12, v5 offset:924
	s_waitcnt lgkmcnt(1)
	v_bfe_u32 v13, v11, 16, 1
	v_add3_u32 v11, v11, v13, s73
	s_waitcnt lgkmcnt(0)
	v_bfe_u32 v13, v12, 16, 1
	v_lshrrev_b32_e32 v11, 16, v11
	v_add3_u32 v12, v12, v13, s73
	v_and_or_b32 v11, v12, s72, v11
	v_lshl_add_u64 v[12:13], v[0:1], 0, v[184:185]
	flat_store_dwordx4 v[12:13], v[8:11] nt
	ds_read_b32 v7, v5 offset:32
	ds_read_b32 v8, v5 offset:164
	v_lshlrev_b32_e32 v184, 1, v6
	s_waitcnt lgkmcnt(0)
	v_bfe_u32 v9, v7, 16, 1
	v_add3_u32 v7, v7, v9, s73
	v_bfe_u32 v9, v8, 16, 1
	v_lshrrev_b32_e32 v7, 16, v7
	v_add3_u32 v8, v8, v9, s73
	v_and_or_b32 v8, v8, s72, v7
	ds_read_b32 v7, v5 offset:296
	ds_read_b32 v9, v5 offset:428
	s_waitcnt lgkmcnt(0)
	v_bfe_u32 v10, v7, 16, 1
	v_add3_u32 v7, v7, v10, s73
	v_bfe_u32 v10, v9, 16, 1
	v_lshrrev_b32_e32 v7, 16, v7
	v_add3_u32 v9, v9, v10, s73
	v_and_or_b32 v9, v9, s72, v7
	ds_read_b32 v7, v5 offset:560
	ds_read_b32 v10, v5 offset:692
	s_waitcnt lgkmcnt(0)
	v_bfe_u32 v11, v7, 16, 1
	v_add3_u32 v7, v7, v11, s73
	v_bfe_u32 v11, v10, 16, 1
	v_lshrrev_b32_e32 v7, 16, v7
	v_add3_u32 v10, v10, v11, s73
	v_and_or_b32 v10, v10, s72, v7
	ds_read_b32 v7, v5 offset:824
	ds_read_b32 v11, v5 offset:956
	s_waitcnt lgkmcnt(0)
	v_bfe_u32 v12, v7, 16, 1
	v_add3_u32 v7, v7, v12, s73
	v_bfe_u32 v12, v11, 16, 1
	v_lshrrev_b32_e32 v7, 16, v7
	v_add3_u32 v11, v11, v12, s73
	v_and_or_b32 v11, v11, s72, v7
	v_lshl_add_u64 v[6:7], v[0:1], 0, v[184:185]
	flat_store_dwordx4 v[6:7], v[8:11] nt
	ds_read_b32 v6, v5 offset:64
	ds_read_b32 v7, v5 offset:196
	v_lshlrev_b32_e32 v184, 1, v4
	s_waitcnt lgkmcnt(0)
	v_bfe_u32 v8, v6, 16, 1
	v_add3_u32 v6, v6, v8, s73
	v_bfe_u32 v8, v7, 16, 1
	v_lshrrev_b32_e32 v6, 16, v6
	v_add3_u32 v7, v7, v8, s73
	v_and_or_b32 v6, v7, s72, v6
	ds_read_b32 v7, v5 offset:328
	ds_read_b32 v8, v5 offset:460
	s_waitcnt lgkmcnt(0)
	v_bfe_u32 v9, v7, 16, 1
	v_add3_u32 v7, v7, v9, s73
	v_bfe_u32 v9, v8, 16, 1
	v_lshrrev_b32_e32 v7, 16, v7
	v_add3_u32 v8, v8, v9, s73
	v_and_or_b32 v7, v8, s72, v7
	ds_read_b32 v8, v5 offset:592
	ds_read_b32 v9, v5 offset:724
	s_waitcnt lgkmcnt(0)
	v_bfe_u32 v10, v8, 16, 1
	v_add3_u32 v8, v8, v10, s73
	v_bfe_u32 v10, v9, 16, 1
	v_lshrrev_b32_e32 v8, 16, v8
	v_add3_u32 v9, v9, v10, s73
	v_and_or_b32 v8, v9, s72, v8
	ds_read_b32 v9, v5 offset:856
	ds_read_b32 v10, v5 offset:988
	s_waitcnt lgkmcnt(0)
	v_bfe_u32 v11, v9, 16, 1
	v_add3_u32 v9, v9, v11, s73
	v_bfe_u32 v11, v10, 16, 1
	v_lshrrev_b32_e32 v9, 16, v9
	v_add3_u32 v10, v10, v11, s73
	v_and_or_b32 v9, v10, s72, v9
	v_lshl_add_u64 v[10:11], v[0:1], 0, v[184:185]
	flat_store_dwordx4 v[10:11], v[6:9] nt
	ds_read_b32 v4, v5 offset:96
	ds_read_b32 v6, v5 offset:228
	v_lshlrev_b32_e32 v184, 1, v2
	v_lshl_add_u64 v[0:1], v[0:1], 0, v[184:185]
	s_waitcnt lgkmcnt(0)
	v_bfe_u32 v7, v4, 16, 1
	v_add3_u32 v4, v4, v7, s73
	v_bfe_u32 v7, v6, 16, 1
	v_lshrrev_b32_e32 v4, 16, v4
	v_add3_u32 v6, v6, v7, s73
	v_and_or_b32 v6, v6, s72, v4
	ds_read_b32 v4, v5 offset:360
	ds_read_b32 v7, v5 offset:492
	s_waitcnt lgkmcnt(0)
	v_bfe_u32 v8, v4, 16, 1
	v_add3_u32 v4, v4, v8, s73
	v_bfe_u32 v8, v7, 16, 1
	v_lshrrev_b32_e32 v4, 16, v4
	v_add3_u32 v7, v7, v8, s73
	v_and_or_b32 v7, v7, s72, v4
	ds_read_b32 v4, v5 offset:624
	ds_read_b32 v8, v5 offset:756
	s_waitcnt lgkmcnt(0)
	v_bfe_u32 v9, v4, 16, 1
	v_add3_u32 v4, v4, v9, s73
	v_bfe_u32 v9, v8, 16, 1
	v_lshrrev_b32_e32 v4, 16, v4
	v_add3_u32 v8, v8, v9, s73
	v_and_or_b32 v8, v8, s72, v4
	ds_read_b32 v4, v5 offset:888
	ds_read_b32 v5, v5 offset:1020
	s_waitcnt lgkmcnt(0)
	v_bfe_u32 v9, v4, 16, 1
	v_add3_u32 v4, v4, v9, s73
	v_bfe_u32 v9, v5, 16, 1
	v_lshrrev_b32_e32 v4, 16, v4
	v_add3_u32 v5, v5, v9, s73
	v_and_or_b32 v9, v5, s72, v4
	flat_store_dwordx4 v[0:1], v[6:9] nt
	s_waitcnt lgkmcnt(0)

; #define LAS __attribute__((address_space(3)))
; #define F_LANE() (tid_of(F.wave) & 63)
; #define LDS_WAIT() asm volatile("s_waitcnt lgkmcnt(0)" ::: "memory")
; template <class Map>
; __device__ __forceinline__ void conv_item(const Frame& F, int it, const float* W, int K, int N, bf16_t* WT, const float* gk, int gmask, float gmul, const float* bk, i64* cs, i64* bw, Map map) {
;     LAS float* scr = (LAS float*)(F.lds + F.wave * 16384);
;     const int lane = F_LANE(), nblk = N / 32;
;     {
;         const int kb = it / nblk, nb = it % nblk, k0 = 64 * kb, n0 = 32 * nb, v0 = map(n0);
; #pragma unroll
;         for (int i = 0; i < 8; ++i) { const int kk = 8 * i + (lane >> 3), c4 = (lane & 7) * 4;
;             const f32x4 w4 = __builtin_nontemporal_load((const f32x4*)(W + (size_t)(k0 + kk) * N + n0 + c4)); LAS float* d = scr + kk * 33 + c4; d[0] = w4[0]; d[1] = w4[1]; d[2] = w4[2]; d[3] = w4[3]; }
;         LDS_WAIT(); asm volatile("" ::: "memory");
;         if (bk) {
;             const int n = lane & 31, kh = lane >> 5; float sb = 0.f, sc = 0.f;
.LBB0_1980:
	s_andn2_saveexec_b64 s[24:25], s[24:25]
	s_cbranch_execz .LBB0_2004
	v_readlane_b32 s38, v252, 14
	v_readlane_b32 s39, v252, 15
	s_mov_b64 s[12:13], s[38:39]
	s_load_dwordx2 s[12:13], s[12:13], 0x78
	s_mul_i32 s16, s20, 0x5800000
	v_readlane_b32 s48, v252, 12
	v_readlane_b32 s49, v252, 13
	s_mov_b64 s[26:27], s[48:49]
	s_waitcnt lgkmcnt(0)
	s_add_u32 s16, s12, s16
	s_mul_hi_i32 s12, s20, 0x5800000
	s_addc_u32 s17, s13, s12
	s_mov_b64 s[12:13], s[38:39]
	s_load_dwordx2 s[36:37], s[12:13], 0x68
	s_lshl_b64 s[12:13], s[58:59], 2
	v_mov_b32_e32 v4, 6
	v_mov_b32_e32 v3, v220
	s_waitcnt lgkmcnt(0)
	s_add_u32 s30, s36, s12
	s_addc_u32 s31, s37, s13
	s_mov_b64 s[12:13], s[38:39]
	s_mov_b32 s38, 0xba2f
	v_mul_u32_u24_sdwa v1, v0, s38 dst_sel:DWORD dst_unused:UNUSED_PAD src0_sel:WORD_0 src1_sel:DWORD
	s_movk_i32 s38, 0x160
	v_mul_lo_u16_sdwa v2, v1, s38 dst_sel:DWORD dst_unused:UNUSED_PAD src0_sel:BYTE_3 src1_sel:DWORD
	v_sub_u16_e32 v2, v0, v2
	s_movk_i32 s38, 0xaf
	v_lshlrev_b16_sdwa v20, v4, v1 dst_sel:DWORD dst_unused:UNUSED_PAD src0_sel:DWORD src1_sel:BYTE_3
	v_lshlrev_b16_e32 v1, 5, v2
	v_cmp_lt_u16_e32 vcc, s38, v2
	s_movk_i32 s38, 0xb0
	s_load_dwordx2 s[70:71], s[12:13], 0x70
	s_mov_b64 s[12:13], s[48:49]
	v_add_u16_e32 v4, 0xea00, v1
	v_cmp_gt_u16_e64 s[38:39], s38, v2
	v_lshlrev_b32_e32 v184, 2, v1
	v_bfe_u32 v19, v3, 3, 3
	v_cndmask_b32_e64 v2, v4, v1, s[38:39]
	v_mov_b32_e32 v4, 1
	v_lshlrev_b32_e32 v1, 4, v3
	v_lshlrev_b32_sdwa v10, v4, sext(v2) dst_sel:DWORD dst_unused:UNUSED_PAD src0_sel:DWORD src1_sel:WORD_0
	v_lshl_add_u64 v[4:5], s[16:17], 0, v[184:185]
	v_and_b32_e32 v184, 0x70, v1
	v_or_b32_e32 v1, v19, v20
	v_lshl_add_u64 v[8:9], v[4:5], 0, v[184:185]
	v_mul_u32_u24_e32 v4, 0xb000, v1
	v_mov_b32_e32 v5, v185
	v_lshl_add_u64 v[4:5], v[8:9], 0, v[4:5]
	global_load_dwordx4 v[132:135], v[4:5], off nt
	v_mul_u32_u24_e32 v12, 0x84, v19
	v_readlane_b32 s16, v255, 17
	v_or_b32_e32 v18, 8, v19
	v_or_b32_e32 v17, 16, v19
	v_add3_u32 v12, s16, v184, v12
	v_add_u32_e32 v13, 0x420, v12
	v_or_b32_e32 v16, 24, v19
	s_movk_i32 s38, 0x60
	v_cndmask_b32_e32 v11, 0, v228, vcc
	v_and_b32_sdwa v2, sext(v2), s38 dst_sel:DWORD dst_unused:UNUSED_PAD src0_sel:WORD_0 src1_sel:DWORD
	s_waitcnt lgkmcnt(0)
	s_cmp_eq_u64 s[70:71], 0
	v_or_b32_e32 v4, v18, v20
	v_mul_u32_u24_e32 v184, 0xb000, v4
	v_lshl_add_u64 v[4:5], v[8:9], 0, v[184:185]
	global_load_dwordx4 v[136:139], v[4:5], off nt
	v_add_u32_e32 v4, 0x428, v12
	v_or_b32_e32 v4, v17, v20
	v_mul_u32_u24_e32 v184, 0xb000, v4
	v_lshl_add_u64 v[4:5], v[8:9], 0, v[184:185]
	global_load_dwordx4 v[140:143], v[4:5], off nt
	v_add_u32_e32 v13, 0x840, v12
	v_add_u32_e32 v4, 0x848, v12
	v_or_b32_e32 v4, v16, v20
	v_mul_u32_u24_e32 v184, 0xb000, v4
	v_lshl_add_u64 v[4:5], v[8:9], 0, v[184:185]
	global_load_dwordx4 v[144:147], v[4:5], off nt
	v_add_u32_e32 v13, 0xc60, v12
	v_add_u32_e32 v4, 0xc68, v12
	v_or_b32_e32 v4, 32, v1
	v_mul_u32_u24_e32 v184, 0xb000, v4
	v_lshl_add_u64 v[4:5], v[8:9], 0, v[184:185]
	global_load_dwordx4 v[148:151], v[4:5], off nt
	v_add_u32_e32 v13, 0x1080, v12
	v_add_u32_e32 v4, 0x1088, v12
	v_or_b32_e32 v4, 40, v1
	v_mul_u32_u24_e32 v184, 0xb000, v4
	v_lshl_add_u64 v[4:5], v[8:9], 0, v[184:185]
	global_load_dwordx4 v[152:155], v[4:5], off nt
	v_add_u32_e32 v13, 0x14a0, v12
	v_add_u32_e32 v4, 0x14a8, v12
	v_or_b32_e32 v4, 48, v1
	v_mul_u32_u24_e32 v184, 0xb000, v4
	v_lshl_add_u64 v[4:5], v[8:9], 0, v[184:185]
	global_load_dwordx4 v[156:159], v[4:5], off nt
	v_add_u32_e32 v13, 0x18c0, v12
	v_or_b32_e32 v1, 56, v1
	v_mul_u32_u24_e32 v184, 0xb000, v1
	v_add_u32_e32 v1, 0x1ce0, v12
	v_add_u32_e32 v4, 0x18c8, v12
	v_lshl_add_u64 v[4:5], v[8:9], 0, v[184:185]
	global_load_dwordx4 v[160:163], v[4:5], off nt
	v_add_u32_e32 v1, 0x1ce8, v12
	s_waitcnt vmcnt(0)
	v_add_u32_e32 v164, 0x0, v12
	ds_write2_b32 v164, v132, v133 offset1:1
	ds_write2_b32 v164, v134, v135 offset0:2 offset1:3
	v_add_u32_e32 v164, 0x420, v12
	ds_write2_b32 v164, v136, v137 offset1:1
	ds_write2_b32 v164, v138, v139 offset0:2 offset1:3
	v_add_u32_e32 v164, 0x840, v12
	ds_write2_b32 v164, v140, v141 offset1:1
	ds_write2_b32 v164, v142, v143 offset0:2 offset1:3
	v_add_u32_e32 v164, 0xc60, v12
	ds_write2_b32 v164, v144, v145 offset1:1
	ds_write2_b32 v164, v146, v147 offset0:2 offset1:3
	v_add_u32_e32 v164, 0x1080, v12
	ds_write2_b32 v164, v148, v149 offset1:1
	ds_write2_b32 v164, v150, v151 offset0:2 offset1:3
	v_add_u32_e32 v164, 0x14a0, v12
	ds_write2_b32 v164, v152, v153 offset1:1
	ds_write2_b32 v164, v154, v155 offset0:2 offset1:3
	v_add_u32_e32 v164, 0x18c0, v12
	ds_write2_b32 v164, v156, v157 offset1:1
	ds_write2_b32 v164, v158, v159 offset0:2 offset1:3
	v_add_u32_e32 v164, 0x1ce0, v12
	ds_write2_b32 v164, v160, v161 offset1:1
	ds_write2_b32 v164, v162, v163 offset0:2 offset1:3
	s_waitcnt lgkmcnt(0)
	v_and_b32_e32 v1, 0xffffff00, v10
	v_or3_b32 v4, v2, v11, v1
	s_cbranch_scc1 .LBB0_1987
	v_and_b32_e32 v1, 32, v3
	v_readlane_b32 s46, v255, 25
	v_readlane_b32 s47, v255, 26
	s_add_u32 s16, s70, s46
	v_add_u32_e32 v22, v20, v1
	s_mov_b32 s38, 0xba2e8c
	v_lshrrev_b32_e32 v1, 5, v3
	v_bfe_u32 v2, v3, 5, 1
	s_addc_u32 s17, s71, s47
	v_lshlrev_b32_e32 v184, 2, v22
	v_mul_hi_u32_u24_sdwa v0, v0, s38 dst_sel:DWORD dst_unused:UNUSED_PAD src0_sel:WORD_0 src1_sel:DWORD
	v_lshlrev_b32_e32 v8, 7, v2
	v_and_b32_e32 v1, 1, v1
	v_lshl_add_u64 v[6:7], s[16:17], 0, v[184:185]
	v_lshl_or_b32 v184, v0, 8, v8
	v_lshlrev_b16_e32 v0, 6, v0
	v_lshlrev_b16_e32 v1, 5, v1
	v_or_b32_e32 v0, v0, v1
	v_lshl_add_u64 v[8:9], s[16:17], 0, v[184:185]
	s_add_u32 s16, s36, s46
	v_and_b32_e32 v0, 0x7e0, v0
	v_and_b32_e32 v21, 31, v3
	s_addc_u32 s17, s37, s47
	v_lshlrev_b32_e32 v184, 2, v0
	v_mul_u32_u24_e32 v0, 0x1080, v2
	v_lshl_add_u64 v[10:11], s[16:17], 0, v[184:185]
	v_lshl_or_b32 v0, v21, 2, v0
	v_readlane_b32 s16, v255, 17
	v_and_b32_e32 v5, 63, v3
	s_mov_b64 s[38:39], 0
	v_add_u32_e32 v23, s16, v0
	v_mov_b32_e32 v0, 0
	v_mov_b32_e32 v1, v0

; #define LAS __attribute__((address_space(3)))
; __device__ __forceinline__ void atomic_addq(i64* p, float v, float scale) { (void)__hip_atomic_fetch_add((unsigned long long*)p, (unsigned long long)(i64)__builtin_rintf(v * scale), __ATOMIC_RELAXED, __HIP_MEMORY_SCOPE_AGENT); }
; #define F_LANE() (tid_of(F.wave) & 63)
; #define LDS_WAIT() asm volatile("s_waitcnt lgkmcnt(0)" ::: "memory")
; __device__ __forceinline__ float bf_round(float f) { return __uint_as_float(f2bf(f) << 16); }
; template <class Map>
; __device__ __forceinline__ void conv_item(const Frame& F, int it, const float* W, int K, int N, bf16_t* WT, const float* gk, int gmask, float gmul, const float* bk, i64* cs, i64* bw, Map map) {
;     ...
;     const int lane = F_LANE(), nblk = N / 32;
;     {
;         const int kb = it / nblk, nb = it % nblk, k0 = 64 * kb, n0 = 32 * nb, v0 = map(n0);
; #pragma unroll
;         for (int i = 0; i < 8; ++i) { const int kk = 8 * i + (lane >> 3), c4 = (lane & 7) * 4;
;             const f32x4 w4 = __builtin_nontemporal_load((const f32x4*)(W + (size_t)(k0 + kk) * N + n0 + c4)); LAS float* d = scr + kk * 33 + c4; d[0] = w4[0]; d[1] = w4[1]; d[2] = w4[2]; d[3] = w4[3]; }
;         LDS_WAIT(); asm volatile("" ::: "memory");
;         if (bk) {
;             const int n = lane & 31, kh = lane >> 5; float sb = 0.f, sc = 0.f;
; #pragma unroll 8
;             for (int j = 0; j < 32; ++j) { const int kk = kh * 32 + j; const float w = scr[kk * 33 + n]; sb += bk[k0 + kk] * w; sc += bf_round(gk[(k0 + kk) & gmask] * gmul * w); }
;             { auto r = __builtin_amdgcn_permlane32_swap(__float_as_uint(sb), __float_as_uint(sb), false, false); sb = __uint_as_float(r[0]) + __uint_as_float(r[1]); }
;             { auto r = __builtin_amdgcn_permlane32_swap(__float_as_uint(sc), __float_as_uint(sc), false, false); sc = __uint_as_float(r[0]) + __uint_as_float(r[1]); }
;             if (lane < 32) { atomic_addq(bw + v0 + n, sb, FX_COL); atomic_addq(cs + v0 + n, sc, FX_COL); }
;         }
;         const int c = lane & 7; float gl[8];
; #pragma unroll
;         for (int i = 0; i < 8; ++i) gl[i] = gk ? gk[(k0 + 8 * c + i) & gmask] * gmul : 1.0f;
.LBB0_2006:
	v_readlane_b32 s12, v252, 14
	v_readlane_b32 s13, v252, 15
	s_mov_b64 s[10:11], s[12:13]
	s_load_dwordx2 s[10:11], s[10:11], 0x30
	v_add_u32_e32 v0, 0xfffff8c0, v232
	v_lshrrev_b32_e32 v1, 1, v0
	v_lshlrev_b32_e32 v0, 5, v0
	v_mov_b32_e32 v16, v220
	s_waitcnt lgkmcnt(0)
	s_add_u32 s16, s10, s62
	s_addc_u32 s17, s11, s63
	v_readlane_b32 s10, v252, 12
	v_readlane_b32 s11, v252, 13
	v_and_b32_e32 v8, 0xfe0, v0
	s_load_dwordx2 s[18:19], s[12:13], 0x20
	v_lshlrev_b32_e32 v184, 2, v8
	v_lshlrev_b32_e32 v2, 4, v16
	v_and_b32_e32 v13, 0x7fc0, v1
	v_bfe_u32 v12, v16, 3, 3
	v_lshl_add_u64 v[0:1], s[16:17], 0, v[184:185]
	v_and_b32_e32 v184, 0x70, v2
	v_lshl_add_u64 v[4:5], v[0:1], 0, v[184:185]
	v_or_b32_e32 v0, v12, v13
	v_lshlrev_b32_e32 v6, 14, v0
	v_mov_b32_e32 v7, v185
	v_lshl_add_u64 v[0:1], v[4:5], 0, v[6:7]
	global_load_dwordx4 v[132:135], v[0:1], off nt
	v_mul_u32_u24_e32 v7, 0x84, v12
	v_readlane_b32 s16, v255, 17
	v_or_b32_e32 v11, 8, v12
	v_or_b32_e32 v10, 16, v12
	v_add3_u32 v7, s16, v184, v7
	v_add_u32_e32 v9, 0x420, v7
	v_add_u32_e32 v17, 0xc60, v7
	s_lshl_b64 s[12:13], s[64:65], 2
	s_waitcnt lgkmcnt(0)
	s_add_u32 s12, s18, s12
	v_and_b32_e32 v16, 7, v16
	s_addc_u32 s13, s19, s13
	s_cmp_lg_u64 s[18:19], 0
	s_cselect_b64 s[24:25], -1, 0
	s_cmp_eq_u64 s[18:19], 0
	v_or_b32_e32 v0, v11, v13
	v_lshlrev_b32_e32 v184, 14, v0
	v_lshl_add_u64 v[0:1], v[4:5], 0, v[184:185]
	global_load_dwordx4 v[136:139], v[0:1], off nt
	v_add_u32_e32 v0, 0x428, v7
	v_or_b32_e32 v0, v10, v13
	v_lshlrev_b32_e32 v184, 14, v0
	v_lshl_add_u64 v[0:1], v[4:5], 0, v[184:185]
	global_load_dwordx4 v[140:143], v[0:1], off nt
	v_add_u32_e32 v9, 0x840, v7
	v_add_u32_e32 v0, 0x848, v7
	v_or_b32_e32 v9, 24, v12
	v_or_b32_e32 v0, v9, v13
	v_lshlrev_b32_e32 v184, 14, v0
	v_lshl_add_u64 v[0:1], v[4:5], 0, v[184:185]
	global_load_dwordx4 v[144:147], v[0:1], off nt
	v_or_b32_e32 v184, 0x80000, v6
	v_add_u32_e32 v0, 0xc68, v7
	v_lshl_add_u64 v[0:1], v[4:5], 0, v[184:185]
	global_load_dwordx4 v[148:151], v[0:1], off nt
	v_add_u32_e32 v17, 0x1080, v7
	v_or_b32_e32 v184, 0xa0000, v6
	v_add_u32_e32 v0, 0x1088, v7
	v_lshl_add_u64 v[0:1], v[4:5], 0, v[184:185]
	global_load_dwordx4 v[152:155], v[0:1], off nt
	v_add_u32_e32 v17, 0x14a0, v7
	v_or_b32_e32 v184, 0xc0000, v6
	v_add_u32_e32 v0, 0x14a8, v7
	v_lshl_add_u64 v[0:1], v[4:5], 0, v[184:185]
	global_load_dwordx4 v[156:159], v[0:1], off nt
	v_add_u32_e32 v17, 0x18c0, v7
	v_or_b32_e32 v184, 0xe0000, v6
	v_add_u32_e32 v0, 0x18c8, v7
	v_lshl_add_u64 v[0:1], v[4:5], 0, v[184:185]
	global_load_dwordx4 v[160:163], v[0:1], off nt
	v_add_u32_e32 v4, 0x1ce0, v7
	v_lshlrev_b32_e32 v17, 3, v16
	v_add_u32_e32 v0, 0x1ce8, v7
	s_waitcnt vmcnt(0)
	v_add_u32_e32 v164, 0x0, v7
	ds_write2_b32 v164, v132, v133 offset1:1
	ds_write2_b32 v164, v134, v135 offset0:2 offset1:3
	v_add_u32_e32 v164, 0x420, v7
	ds_write2_b32 v164, v136, v137 offset1:1
	ds_write2_b32 v164, v138, v139 offset0:2 offset1:3
	v_add_u32_e32 v164, 0x840, v7
	ds_write2_b32 v164, v140, v141 offset1:1
	ds_write2_b32 v164, v142, v143 offset0:2 offset1:3
	v_add_u32_e32 v164, 0xc60, v7
	ds_write2_b32 v164, v144, v145 offset1:1
	ds_write2_b32 v164, v146, v147 offset0:2 offset1:3
	v_add_u32_e32 v164, 0x1080, v7
	ds_write2_b32 v164, v148, v149 offset1:1
	ds_write2_b32 v164, v150, v151 offset0:2 offset1:3
	v_add_u32_e32 v164, 0x14a0, v7
	ds_write2_b32 v164, v152, v153 offset1:1
	ds_write2_b32 v164, v154, v155 offset0:2 offset1:3
	v_add_u32_e32 v164, 0x18c0, v7
	ds_write2_b32 v164, v156, v157 offset1:1
	ds_write2_b32 v164, v158, v159 offset0:2 offset1:3
	v_add_u32_e32 v164, 0x1ce0, v7
	ds_write2_b32 v164, v160, v161 offset1:1
	ds_write2_b32 v164, v162, v163 offset0:2 offset1:3
	s_waitcnt lgkmcnt(0)
	v_or_b32_e32 v1, v17, v13
	v_mov_b32_e32 v0, 1.0
	v_lshlrev_b32_e32 v18, 2, v1
	v_mov_b32_e32 v2, 1.0
	s_cbranch_scc1 .LBB0_2008
	global_load_dword v2, v18, s[12:13]

; #define LAS __attribute__((address_space(3)))
; __device__ __forceinline__ void atomic_addq(i64* p, float v, float scale) { (void)__hip_atomic_fetch_add((unsigned long long*)p, (unsigned long long)(i64)__builtin_rintf(v * scale), __ATOMIC_RELAXED, __HIP_MEMORY_SCOPE_AGENT); }
; #define LDS_WAIT() asm volatile("s_waitcnt lgkmcnt(0)" ::: "memory")
; __device__ __forceinline__ float bf_round(float f) { return __uint_as_float(f2bf(f) << 16); }
; template <class Map>
; __device__ __forceinline__ void conv_item(const Frame& F, int it, const float* W, int K, int N, bf16_t* WT, const float* gk, int gmask, float gmul, const float* bk, i64* cs, i64* bw, Map map) {
;     ...
;         const int kb = it / nblk, nb = it % nblk, k0 = 64 * kb, n0 = 32 * nb, v0 = map(n0);
; #pragma unroll
;         for (int i = 0; i < 8; ++i) { const int kk = 8 * i + (lane >> 3), c4 = (lane & 7) * 4;
;             const f32x4 w4 = __builtin_nontemporal_load((const f32x4*)(W + (size_t)(k0 + kk) * N + n0 + c4)); LAS float* d = scr + kk * 33 + c4; d[0] = w4[0]; d[1] = w4[1]; d[2] = w4[2]; d[3] = w4[3]; }
;         LDS_WAIT(); asm volatile("" ::: "memory");
;         if (bk) {
;             const int n = lane & 31, kh = lane >> 5; float sb = 0.f, sc = 0.f;
; #pragma unroll 8
;             for (int j = 0; j < 32; ++j) { const int kk = kh * 32 + j; const float w = scr[kk * 33 + n]; sb += bk[k0 + kk] * w; sc += bf_round(gk[(k0 + kk) & gmask] * gmul * w); }
;             { auto r = __builtin_amdgcn_permlane32_swap(__float_as_uint(sb), __float_as_uint(sb), false, false); sb = __uint_as_float(r[0]) + __uint_as_float(r[1]); }
;             { auto r = __builtin_amdgcn_permlane32_swap(__float_as_uint(sc), __float_as_uint(sc), false, false); sc = __uint_as_float(r[0]) + __uint_as_float(r[1]); }
;             if (lane < 32) { atomic_addq(bw + v0 + n, sb, FX_COL); atomic_addq(cs + v0 + n, sc, FX_COL); }
;         }
;         const int c = lane & 7; float gl[8];
; #pragma unroll
;         for (int i = 0; i < 8; ++i) gl[i] = gk ? gk[(k0 + 8 * c + i) & gmask] * gmul : 1.0f;
.LBB0_2023:
	s_or_b64 exec, exec, s[6:7]
	s_and_saveexec_b64 s[6:7], s[8:9]
	s_xor_b64 s[6:7], exec, s[6:7]
	s_cbranch_execz .LBB0_2045
	v_add_u16_e32 v2, 0xfbc0, v232
	v_mul_u32_u24_e32 v1, 0xaaab, v2
	v_lshrrev_b32_e32 v1, 22, v1
	v_mul_lo_u16_e32 v3, 0x60, v1
	v_sub_u16_e32 v3, v2, v3
	v_lshlrev_b16_e32 v2, 5, v3
	v_mul_u32_u24_e32 v4, 0x2aab, v2
	v_lshrrev_b32_e32 v4, 21, v4
	v_readlane_b32 s12, v252, 14
	v_mul_lo_u16_e32 v4, 0xc0, v4
	v_readlane_b32 s13, v252, 15
	v_readlane_b32 s8, v252, 12
	v_mul_lo_u16_e32 v3, 0xab, v3
	v_sub_u16_e32 v4, v2, v4
	s_movk_i32 s16, 0x7f
	s_mov_b64 s[10:11], s[12:13]
	v_readlane_b32 s9, v252, 13
	v_mov_b32_e32 v0, v220
	v_lshrrev_b16_e32 v3, 10, v3
	v_cmp_lt_u16_e32 vcc, s16, v4
	s_and_saveexec_b64 s[16:17], vcc
	s_xor_b64 s[16:17], exec, s[16:17]
	v_lshlrev_b32_e32 v5, 6, v3
	v_and_b32_e32 v5, 0x700, v5
	v_lshlrev_b32_e32 v3, 5, v3
	v_lshl_add_u32 v4, v4, 2, v5
	v_and_b32_e32 v3, 0x60, v3
	s_movk_i32 s18, 0x600
	v_add3_u32 v8, v4, v3, s18
	s_or_saveexec_b64 s[16:17], s[16:17]
	s_load_dwordx2 s[10:11], s[10:11], 0x28
	s_nop 0
	s_load_dwordx2 s[12:13], s[12:13], 0x18
	s_xor_b64 exec, exec, s[16:17]
	v_lshl_or_b32 v8, v3, 7, v4
	s_or_b64 exec, exec, s[16:17]
	s_waitcnt lgkmcnt(0)
	s_add_u32 s16, s10, s87
	s_addc_u32 s17, s11, s21
	v_lshlrev_b16_e32 v13, 6, v1
	v_bfe_u32 v12, v0, 3, 3
	v_lshlrev_b32_e32 v184, 2, v2
	v_lshlrev_b32_e32 v1, 4, v0
	v_lshl_add_u64 v[2:3], s[16:17], 0, v[184:185]
	v_and_b32_e32 v184, 0x70, v1
	v_or_b32_e32 v1, v12, v13
	v_lshl_add_u64 v[6:7], v[2:3], 0, v[184:185]
	v_mul_u32_u24_e32 v2, 0x3000, v1
	v_mov_b32_e32 v3, v185
	v_lshl_add_u64 v[2:3], v[6:7], 0, v[2:3]
	global_load_dwordx4 v[132:135], v[2:3], off nt
	v_mul_u32_u24_e32 v9, 0x84, v12
	v_readlane_b32 s16, v255, 17
	v_or_b32_e32 v11, 8, v12
	v_or_b32_e32 v10, 16, v12
	v_add3_u32 v16, s16, v184, v9
	v_add_u32_e32 v9, 0x420, v16
	v_add_u32_e32 v17, 0xc60, v16
	s_lshl_b64 s[10:11], s[64:65], 2
	s_add_u32 s10, s12, s10
	s_addc_u32 s11, s13, s11
	s_cmp_lg_u64 s[12:13], 0
	s_cselect_b64 s[18:19], -1, 0
	s_cmp_eq_u64 s[12:13], 0
	s_movk_i32 s12, 0x1c0
	v_or_b32_e32 v2, v11, v13
	v_mul_u32_u24_e32 v184, 0x3000, v2
	v_lshl_add_u64 v[2:3], v[6:7], 0, v[184:185]
	global_load_dwordx4 v[136:139], v[2:3], off nt
	v_add_u32_e32 v2, 0x428, v16
	v_or_b32_e32 v2, v10, v13
	v_mul_u32_u24_e32 v184, 0x3000, v2
	v_lshl_add_u64 v[2:3], v[6:7], 0, v[184:185]
	global_load_dwordx4 v[140:143], v[2:3], off nt
	v_add_u32_e32 v9, 0x840, v16
	v_add_u32_e32 v2, 0x848, v16
	v_or_b32_e32 v9, 24, v12
	v_or_b32_e32 v2, v9, v13
	v_mul_u32_u24_e32 v184, 0x3000, v2
	v_lshl_add_u64 v[2:3], v[6:7], 0, v[184:185]
	global_load_dwordx4 v[144:147], v[2:3], off nt
	v_add_u32_e32 v2, 0xc68, v16
	v_or_b32_e32 v2, 32, v1
	v_mul_u32_u24_e32 v184, 0x3000, v2
	v_lshl_add_u64 v[2:3], v[6:7], 0, v[184:185]
	global_load_dwordx4 v[148:151], v[2:3], off nt
	v_add_u32_e32 v17, 0x1080, v16
	v_add_u32_e32 v2, 0x1088, v16
	v_or_b32_e32 v2, 40, v1
	v_mul_u32_u24_e32 v184, 0x3000, v2
	v_lshl_add_u64 v[2:3], v[6:7], 0, v[184:185]
	global_load_dwordx4 v[152:155], v[2:3], off nt
	v_add_u32_e32 v17, 0x14a0, v16
	v_add_u32_e32 v2, 0x14a8, v16
	v_or_b32_e32 v2, 48, v1
	v_mul_u32_u24_e32 v184, 0x3000, v2
	v_lshl_add_u64 v[2:3], v[6:7], 0, v[184:185]
	global_load_dwordx4 v[156:159], v[2:3], off nt
	v_add_u32_e32 v17, 0x18c0, v16
	v_or_b32_e32 v1, 56, v1
	v_mul_u32_u24_e32 v184, 0x3000, v1
	v_add_u32_e32 v1, 0x1ce0, v16
	v_add_u32_e32 v2, 0x18c8, v16
	v_lshl_add_u64 v[2:3], v[6:7], 0, v[184:185]
	global_load_dwordx4 v[160:163], v[2:3], off nt
	v_add_u32_e32 v1, 0x1ce8, v16
	s_waitcnt vmcnt(0)
	v_add_u32_e32 v164, 0x0, v16
	ds_write2_b32 v164, v132, v133 offset1:1
	ds_write2_b32 v164, v134, v135 offset0:2 offset1:3
	v_add_u32_e32 v164, 0x420, v16
	ds_write2_b32 v164, v136, v137 offset1:1
	ds_write2_b32 v164, v138, v139 offset0:2 offset1:3
	v_add_u32_e32 v164, 0x840, v16
	ds_write2_b32 v164, v140, v141 offset1:1
	ds_write2_b32 v164, v142, v143 offset0:2 offset1:3
	v_add_u32_e32 v164, 0xc60, v16
	ds_write2_b32 v164, v144, v145 offset1:1
	ds_write2_b32 v164, v146, v147 offset0:2 offset1:3
	v_add_u32_e32 v164, 0x1080, v16
	ds_write2_b32 v164, v148, v149 offset1:1
	ds_write2_b32 v164, v150, v151 offset0:2 offset1:3
	v_add_u32_e32 v164, 0x14a0, v16
	ds_write2_b32 v164, v152, v153 offset1:1
	ds_write2_b32 v164, v154, v155 offset0:2 offset1:3
	v_add_u32_e32 v164, 0x18c0, v16
	ds_write2_b32 v164, v156, v157 offset1:1
	ds_write2_b32 v164, v158, v159 offset0:2 offset1:3
	v_add_u32_e32 v164, 0x1ce0, v16
	ds_write2_b32 v164, v160, v161 offset1:1
	ds_write2_b32 v164, v162, v163 offset0:2 offset1:3
	s_waitcnt lgkmcnt(0)
	v_and_b32_e32 v16, 7, v0
	v_lshlrev_b32_e32 v17, 3, v16
	v_and_or_b32 v1, v13, s12, v17
	v_mov_b32_e32 v0, 1.0
	v_lshlrev_b32_e32 v18, 2, v1
	v_mov_b32_e32 v2, 1.0
	s_cbranch_scc1 .LBB0_2030
	global_load_dword v2, v18, s[10:11]

; #define LAS __attribute__((address_space(3)))
; #define LDS_WAIT() asm volatile("s_waitcnt lgkmcnt(0)" ::: "memory")
; template <class Map>
; __device__ __forceinline__ void conv_item(const Frame& F, int it, const float* W, int K, int N, bf16_t* WT, const float* gk, int gmask, float gmul, const float* bk, i64* cs, i64* bw, Map map) {
;     ...
;         const int kb = it / nblk, nb = it % nblk, k0 = 64 * kb, n0 = 32 * nb, v0 = map(n0);
; #pragma unroll
;         for (int i = 0; i < 8; ++i) { const int kk = 8 * i + (lane >> 3), c4 = (lane & 7) * 4;
;             const f32x4 w4 = __builtin_nontemporal_load((const f32x4*)(W + (size_t)(k0 + kk) * N + n0 + c4)); LAS float* d = scr + kk * 33 + c4; d[0] = w4[0]; d[1] = w4[1]; d[2] = w4[2]; d[3] = w4[3]; }
;         LDS_WAIT(); asm volatile("" ::: "memory");
.LBB0_2045:
	s_or_b64 exec, exec, s[6:7]
	s_and_saveexec_b64 s[6:7], s[4:5]
	s_cbranch_execz .LBB0_1914
	v_readlane_b32 s4, v252, 14
	v_readlane_b32 s5, v252, 15
	s_load_dwordx2 s[4:5], s[4:5], 0x10
	s_mov_b32 s10, 0xf0f1
	v_mul_u32_u24_sdwa v0, v232, s10 dst_sel:DWORD dst_unused:UNUSED_PAD src0_sel:WORD_0 src1_sel:DWORD
	v_lshrrev_b32_e32 v0, 21, v0
	v_mul_lo_u16_e32 v1, 34, v0
	s_waitcnt lgkmcnt(0)
	s_add_u32 s8, s4, s91
	s_addc_u32 s9, s5, s90
	v_readlane_b32 s4, v252, 12
	v_sub_u16_e32 v16, v232, v1
	v_readlane_b32 s5, v252, 13
	v_mov_b32_e32 v6, v220
	v_lshlrev_b16_e32 v18, 5, v16
	v_lshlrev_b16_e32 v17, 6, v0
	v_bfe_u32 v7, v6, 3, 3
	v_lshlrev_b32_e32 v184, 2, v18
	v_lshlrev_b32_e32 v2, 4, v6
	v_lshl_add_u64 v[0:1], s[8:9], 0, v[184:185]
	v_and_b32_e32 v184, 0x70, v2
	v_or_b32_e32 v20, v7, v17
	v_lshl_add_u64 v[12:13], v[0:1], 0, v[184:185]
	v_mul_u32_u24_e32 v0, 0x1100, v20
	v_mov_b32_e32 v1, v185
	v_lshl_add_u64 v[0:1], v[12:13], 0, v[0:1]
	global_load_dwordx4 v[132:135], v[0:1], off nt
	v_mul_u32_u24_e32 v4, 0x84, v7
	v_readlane_b32 s8, v255, 17
	v_or_b32_e32 v5, 8, v7
	v_add_u32_e32 v19, 0x60, v18
	v_add3_u32 v21, s8, v184, v4
	v_add_u32_e32 v4, 0x420, v21
	v_add_u32_e32 v8, 0x840, v21
	v_cmp_gt_u16_e32 vcc, 33, v16
	v_or_b32_e32 v0, v5, v17
	v_mul_u32_u24_e32 v184, 0x1100, v0
	v_lshl_add_u64 v[0:1], v[12:13], 0, v[184:185]
	global_load_dwordx4 v[136:139], v[0:1], off nt
	v_add_u32_e32 v0, 0x428, v21
	v_or_b32_e32 v4, 16, v7
	v_or_b32_e32 v0, v4, v17
	v_mul_u32_u24_e32 v184, 0x1100, v0
	v_lshl_add_u64 v[0:1], v[12:13], 0, v[184:185]
	global_load_dwordx4 v[140:143], v[0:1], off nt
	v_add_u32_e32 v0, 0x848, v21
	v_or_b32_e32 v2, 24, v7
	v_or_b32_e32 v0, v2, v17
	v_mul_u32_u24_e32 v184, 0x1100, v0
	v_lshl_add_u64 v[0:1], v[12:13], 0, v[184:185]
	global_load_dwordx4 v[144:147], v[0:1], off nt
	v_add_u32_e32 v0, 0xc60, v21
	v_cndmask_b32_e32 v3, v19, v18, vcc
	v_or_b32_e32 v5, v5, v3
	v_or_b32_e32 v4, v4, v3
	v_or_b32_e32 v2, v2, v3
	v_add_u32_e32 v0, 0xc68, v21
	v_or_b32_e32 v0, 32, v20
	v_mul_u32_u24_e32 v184, 0x1100, v0
	v_lshl_add_u64 v[0:1], v[12:13], 0, v[184:185]
	global_load_dwordx4 v[148:151], v[0:1], off nt
	v_add_u32_e32 v0, 0x1080, v21
	v_add_u32_e32 v0, 0x1088, v21
	v_or_b32_e32 v0, 40, v20
	v_mul_u32_u24_e32 v184, 0x1100, v0
	v_lshl_add_u64 v[0:1], v[12:13], 0, v[184:185]
	global_load_dwordx4 v[152:155], v[0:1], off nt
	v_add_u32_e32 v0, 0x14a0, v21
	v_add_u32_e32 v0, 0x14a8, v21
	v_or_b32_e32 v0, 48, v20
	v_mul_u32_u24_e32 v184, 0x1100, v0
	v_lshl_add_u64 v[0:1], v[12:13], 0, v[184:185]
	global_load_dwordx4 v[156:159], v[0:1], off nt
	v_add_u32_e32 v0, 0x18c0, v21
	v_add_u32_e32 v0, 0x18c8, v21
	v_or_b32_e32 v0, 56, v20
	v_mul_u32_u24_e32 v184, 0x1100, v0
	v_lshl_add_u64 v[0:1], v[12:13], 0, v[184:185]
	global_load_dwordx4 v[160:163], v[0:1], off nt
	v_add_u32_e32 v0, 0x1ce0, v21
	v_lshlrev_b32_e32 v184, 1, v17
	v_add_u32_e32 v0, 0x1ce8, v21
	s_waitcnt vmcnt(0)
	v_add_u32_e32 v164, 0x0, v21
	ds_write2_b32 v164, v132, v133 offset1:1
	ds_write2_b32 v164, v134, v135 offset0:2 offset1:3
	v_add_u32_e32 v164, 0x420, v21
	ds_write2_b32 v164, v136, v137 offset1:1
	ds_write2_b32 v164, v138, v139 offset0:2 offset1:3
	v_add_u32_e32 v164, 0x840, v21
	ds_write2_b32 v164, v140, v141 offset1:1
	ds_write2_b32 v164, v142, v143 offset0:2 offset1:3
	v_add_u32_e32 v164, 0xc60, v21
	ds_write2_b32 v164, v144, v145 offset1:1
	ds_write2_b32 v164, v146, v147 offset0:2 offset1:3
	v_add_u32_e32 v164, 0x1080, v21
	ds_write2_b32 v164, v148, v149 offset1:1
	ds_write2_b32 v164, v150, v151 offset0:2 offset1:3
	v_add_u32_e32 v164, 0x14a0, v21
	ds_write2_b32 v164, v152, v153 offset1:1
	ds_write2_b32 v164, v154, v155 offset0:2 offset1:3
	v_add_u32_e32 v164, 0x18c0, v21
	ds_write2_b32 v164, v156, v157 offset1:1
	ds_write2_b32 v164, v158, v159 offset0:2 offset1:3
	v_add_u32_e32 v164, 0x1ce0, v21
	ds_write2_b32 v164, v160, v161 offset1:1
	ds_write2_b32 v164, v162, v163 offset0:2 offset1:3
	v_lshlrev_b32_e32 v0, 3, v6
	v_and_b32_e32 v6, 56, v0
	s_waitcnt lgkmcnt(0)
	v_mul_u32_u24_e32 v8, 0x84, v6
	v_lshl_add_u64 v[0:1], s[4:5], 0, v[184:185]
	v_lshlrev_b32_e32 v184, 1, v6
	v_lshlrev_b32_e32 v6, 2, v7
	v_add3_u32 v6, s8, v8, v6
	ds_read_b32 v8, v6
	ds_read_b32 v9, v6 offset:132
	v_lshl_add_u64 v[0:1], v[0:1], 0, v[184:185]
	s_mov_b64 s[4:5], 0x800000
	v_or_b32_e32 v7, v7, v3
	s_waitcnt lgkmcnt(1)
	v_bfe_u32 v10, v8, 16, 1
	v_add3_u32 v8, v8, v10, s73
	s_waitcnt lgkmcnt(0)
; #define LAS __attribute__((address_space(3)))
; #define LDS_WAIT() asm volatile("s_waitcnt lgkmcnt(0)" ::: "memory")
; __device__ __forceinline__ unsigned f2bf(float f) { unsigned u = __builtin_bit_cast(unsigned, f); return (u + 0x7fffu + ((u >> 16) & 1u)) >> 16; }
; __device__ __forceinline__ float bf_round(float f) { return __uint_as_float(f2bf(f) << 16); }
; __device__ __forceinline__ unsigned pk2(float lo, float hi) { return f2bf(lo) | (f2bf(hi) << 16); }
; template <class Map>
; __device__ __forceinline__ void conv_item(const Frame& F, int it, const float* W, int K, int N, bf16_t* WT, const float* gk, int gmask, float gmul, const float* bk, i64* cs, i64* bw, Map map) {
;     ...
;         for (int j = 0; j < 4; ++j) { const int n = (lane >> 3) + 8 * j; const LAS float* s = scr + (8 * c) * 33 + n;
;             u32x4 o; o.x = pk2(s[0 * 33] * gl[0], s[1 * 33] * gl[1]); o.y = pk2(s[2 * 33] * gl[2], s[3 * 33] * gl[3]); o.z = pk2(s[4 * 33] * gl[4], s[5 * 33] * gl[5]); o.w = pk2(s[6 * 33] * gl[6], s[7 * 33] * gl[7]);
;             __builtin_nontemporal_store(o, (u32x4*)(WT + (size_t)(v0 + n) * K + k0 + 8 * c)); }
;         LDS_WAIT(); asm volatile("" ::: "memory");
	v_bfe_u32 v10, v9, 16, 1
	v_lshrrev_b32_e32 v8, 16, v8
	v_add3_u32 v9, v9, v10, s73
	v_and_or_b32 v8, v9, s72, v8
	ds_read_b32 v9, v6 offset:264
	ds_read_b32 v10, v6 offset:396
	v_lshl_add_u64 v[0:1], v[0:1], 0, s[4:5]
	v_lshlrev_b32_e32 v184, 12, v7
	s_waitcnt lgkmcnt(1)
	v_bfe_u32 v11, v9, 16, 1
	v_add3_u32 v9, v9, v11, s73
	s_waitcnt lgkmcnt(0)
	v_bfe_u32 v11, v10, 16, 1
	v_lshrrev_b32_e32 v9, 16, v9
	v_add3_u32 v10, v10, v11, s73
	v_and_or_b32 v9, v10, s72, v9
	ds_read_b32 v10, v6 offset:528
	ds_read_b32 v11, v6 offset:660
	s_waitcnt lgkmcnt(1)
	v_bfe_u32 v12, v10, 16, 1
	v_add3_u32 v10, v10, v12, s73
	s_waitcnt lgkmcnt(0)
	v_bfe_u32 v12, v11, 16, 1
	v_lshrrev_b32_e32 v10, 16, v10
	v_add3_u32 v11, v11, v12, s73
	v_and_or_b32 v10, v11, s72, v10
	ds_read_b32 v11, v6 offset:792
	ds_read_b32 v12, v6 offset:924
	s_waitcnt lgkmcnt(1)
	v_bfe_u32 v13, v11, 16, 1
	v_add3_u32 v11, v11, v13, s73
	s_waitcnt lgkmcnt(0)
	v_bfe_u32 v13, v12, 16, 1
	v_lshrrev_b32_e32 v11, 16, v11
	v_add3_u32 v12, v12, v13, s73
	v_and_or_b32 v11, v12, s72, v11
	v_lshl_add_u64 v[12:13], v[0:1], 0, v[184:185]
	flat_store_dwordx4 v[12:13], v[8:11] nt
	ds_read_b32 v7, v6 offset:32
	ds_read_b32 v8, v6 offset:164
	v_lshlrev_b32_e32 v184, 12, v5
	s_waitcnt lgkmcnt(0)
	v_bfe_u32 v9, v7, 16, 1
	v_add3_u32 v7, v7, v9, s73
	v_bfe_u32 v9, v8, 16, 1
	v_lshrrev_b32_e32 v7, 16, v7
	v_add3_u32 v8, v8, v9, s73
	v_and_or_b32 v8, v8, s72, v7
	ds_read_b32 v7, v6 offset:296
	ds_read_b32 v9, v6 offset:428
	s_waitcnt lgkmcnt(0)
	v_bfe_u32 v10, v7, 16, 1
	v_add3_u32 v7, v7, v10, s73
	v_bfe_u32 v10, v9, 16, 1
	v_lshrrev_b32_e32 v7, 16, v7
	v_add3_u32 v9, v9, v10, s73
	v_and_or_b32 v9, v9, s72, v7
	ds_read_b32 v7, v6 offset:560
	ds_read_b32 v10, v6 offset:692
	s_waitcnt lgkmcnt(0)
	v_bfe_u32 v11, v7, 16, 1
	v_add3_u32 v7, v7, v11, s73
	v_bfe_u32 v11, v10, 16, 1
	v_lshrrev_b32_e32 v7, 16, v7
	v_add3_u32 v10, v10, v11, s73
	v_and_or_b32 v10, v10, s72, v7
	ds_read_b32 v7, v6 offset:824
	ds_read_b32 v11, v6 offset:956
	s_waitcnt lgkmcnt(0)
	v_bfe_u32 v12, v7, 16, 1
	v_add3_u32 v7, v7, v12, s73
	v_bfe_u32 v12, v11, 16, 1
	v_lshrrev_b32_e32 v7, 16, v7
	v_add3_u32 v11, v11, v12, s73
	v_and_or_b32 v11, v11, s72, v7
	v_lshl_add_u64 v[12:13], v[0:1], 0, v[184:185]
	flat_store_dwordx4 v[12:13], v[8:11] nt
	ds_read_b32 v5, v6 offset:64
	ds_read_b32 v7, v6 offset:196
	v_lshlrev_b32_e32 v184, 12, v4
	s_waitcnt lgkmcnt(0)
	v_bfe_u32 v8, v5, 16, 1
	v_add3_u32 v5, v5, v8, s73
	v_bfe_u32 v8, v7, 16, 1
	v_lshrrev_b32_e32 v5, 16, v5
	v_add3_u32 v7, v7, v8, s73
	v_and_or_b32 v8, v7, s72, v5
	ds_read_b32 v5, v6 offset:328
	ds_read_b32 v7, v6 offset:460
	s_waitcnt lgkmcnt(0)
	v_bfe_u32 v9, v5, 16, 1
	v_add3_u32 v5, v5, v9, s73
	v_bfe_u32 v9, v7, 16, 1
	v_lshrrev_b32_e32 v5, 16, v5
	v_add3_u32 v7, v7, v9, s73
	v_and_or_b32 v9, v7, s72, v5
	ds_read_b32 v5, v6 offset:592
	ds_read_b32 v7, v6 offset:724
	s_waitcnt lgkmcnt(0)
	v_bfe_u32 v10, v5, 16, 1
	v_add3_u32 v5, v5, v10, s73
	v_bfe_u32 v10, v7, 16, 1
	v_lshrrev_b32_e32 v5, 16, v5
	v_add3_u32 v7, v7, v10, s73
	v_and_or_b32 v10, v7, s72, v5
	ds_read_b32 v5, v6 offset:856
	ds_read_b32 v7, v6 offset:988
	s_waitcnt lgkmcnt(0)
	v_bfe_u32 v11, v5, 16, 1
	v_add3_u32 v5, v5, v11, s73
	v_bfe_u32 v11, v7, 16, 1
	v_lshrrev_b32_e32 v5, 16, v5
	v_add3_u32 v7, v7, v11, s73
	v_and_or_b32 v11, v7, s72, v5
	v_lshl_add_u64 v[4:5], v[0:1], 0, v[184:185]
	flat_store_dwordx4 v[4:5], v[8:11] nt
	ds_read_b32 v4, v6 offset:96
	ds_read_b32 v5, v6 offset:228
	v_lshlrev_b32_e32 v184, 12, v2
	v_lshl_add_u64 v[0:1], v[0:1], 0, v[184:185]
	s_waitcnt lgkmcnt(0)
	v_bfe_u32 v7, v4, 16, 1
	v_add3_u32 v4, v4, v7, s73
	v_bfe_u32 v7, v5, 16, 1
	v_lshrrev_b32_e32 v4, 16, v4
	v_add3_u32 v5, v5, v7, s73
	v_and_or_b32 v8, v5, s72, v4
	ds_read_b32 v4, v6 offset:360
	ds_read_b32 v5, v6 offset:492
	s_waitcnt lgkmcnt(0)
	v_bfe_u32 v7, v4, 16, 1
	v_add3_u32 v4, v4, v7, s73
	v_bfe_u32 v7, v5, 16, 1
	v_lshrrev_b32_e32 v4, 16, v4
	v_add3_u32 v5, v5, v7, s73
	v_and_or_b32 v9, v5, s72, v4
	ds_read_b32 v4, v6 offset:624
	ds_read_b32 v5, v6 offset:756
	s_waitcnt lgkmcnt(0)
	v_bfe_u32 v7, v4, 16, 1
	v_add3_u32 v4, v4, v7, s73
	v_bfe_u32 v7, v5, 16, 1
	v_lshrrev_b32_e32 v4, 16, v4
	v_add3_u32 v5, v5, v7, s73
	v_and_or_b32 v10, v5, s72, v4
	ds_read_b32 v4, v6 offset:888
	ds_read_b32 v5, v6 offset:1020
	s_waitcnt lgkmcnt(0)
	v_bfe_u32 v6, v4, 16, 1
	v_add3_u32 v4, v4, v6, s73
	v_bfe_u32 v6, v5, 16, 1
	v_lshrrev_b32_e32 v4, 16, v4
	v_add3_u32 v5, v5, v6, s73
	v_and_or_b32 v11, v5, s72, v4
	flat_store_dwordx4 v[0:1], v[8:11] nt
	s_waitcnt lgkmcnt(0)
	s_branch .LBB0_1914
